# PEER stage C rewritten by hand: 8 tokens per wave, u-table sweep (dots+coefs to LDS) then v-table sweep, chunked lists of 4 partitions, 5-deep ring
# speedup vs baseline: 1.0142x; 1.0023x over previous
; __device__ __forceinline__ unsigned f2key(float f) { const unsigned u = __float_as_uint(f); return (u & 0x80000000u) ? ~u : (u | 0x80000000u); }
; __device__ __forceinline__ void peer_tile(const Args& A, LAS unsigned char* lds, int tile) {
;     ...
;         const int tg = w & 3, hg = w >> 2, tl = 16 * tg + l15;
;         const size_t m = (size_t)tile * 64 + tl;
;         unsigned LA[4][2][16];
; #pragma unroll
;         for (int hh = 0; hh < 4; ++hh) {
;             const int h = 4 * hg + hh;
; #pragma unroll
;             for (int p = 0; p < 2; ++p) {
;                 const int hp = 2 * h + p;
;                 unsigned k0[16], k1[16];
;                 { const bf16_t* sp = QRY + m * 2048 + hp * 128 + 32 * g;
;                   const u32x4 s0 = *(const u32x4*)sp, s1 = *(const u32x4*)(sp + 8), s2 = *(const u32x4*)(sp + 16), s3 = *(const u32x4*)(sp + 24);
;                   const unsigned sw[16] = {s0.x, s0.y, s0.z, s0.w, s1.x, s1.y, s1.z, s1.w, s2.x, s2.y, s2.z, s2.w, s3.x, s3.y, s3.z, s3.w};
; #pragma unroll
;                   for (int i = 0; i < 16; ++i) {
;                       const float lo = (float)__builtin_bit_cast(_Float16, (unsigned short)(sw[i] & 0xffffu)), hi = (float)__builtin_bit_cast(_Float16, (unsigned short)(sw[i] >> 16));
;                       const unsigned klo = (f2key(lo) & ~127u) | (unsigned)(127 - (32 * g + 2 * i)), khi = (f2key(hi) & ~127u) | (unsigned)(127 - (32 * g + 2 * i + 1));
;                       if (i < 8) { k0[2 * i] = klo; k0[2 * i + 1] = khi; } else { k1[2 * (i - 8)] = klo; k1[2 * (i - 8) + 1] = khi; } } }
.LBB0_699:
	v_mov_b32_e32 v19, v214
	s_ashr_i32 s3, s2, 31
	v_ashrrev_i32_e32 v7, 6, v19
	v_and_b32_e32 v0, 15, v19
	v_lshlrev_b32_e32 v1, 4, v7
	v_and_or_b32 v13, v1, 48, v0
	s_lshl_b64 s[28:29], s[2:3], 6
	v_or_b32_e32 v0, s28, v13
	v_mov_b32_e32 v1, s29
	v_bfe_u32 v221, v19, 4, 2
	v_ashrrev_i32_e32 v11, 8, v19
	v_lshlrev_b64 v[0:1], 12, v[0:1]
	v_lshlrev_b32_e32 v2, 10, v11
	v_lshl_add_u64 v[0:1], s[54:55], 0, v[0:1]
	v_lshlrev_b32_e32 v112, 6, v221
	v_lshl_add_u64 v[0:1], v[0:1], 0, v[112:113]
	v_ashrrev_i32_e32 v3, 31, v2
	v_lshl_add_u64 v[4:5], v[2:3], 1, v[0:1]
	global_load_dwordx4 v[20:23], v[4:5], off
	global_load_dwordx4 v[24:27], v[4:5], off offset:16
	global_load_dwordx4 v[0:3], v[4:5], off offset:48
	global_load_dwordx4 v[28:31], v[4:5], off offset:32
	v_lshlrev_b32_e32 v15, 5, v221
	v_or_b32_e32 v8, 8, v15
	v_or_b32_e32 v14, 2, v15
	v_or_b32_e32 v12, 4, v15
	v_or_b32_e32 v10, 6, v15
	v_and_b32_e32 v9, 63, v19
	v_cmp_gt_u32_e64 s[0:1], 16, v9
	v_cmp_gt_u32_e64 s[4:5], 32, v9
	v_mul_lo_u32 v6, v19, s17
	s_mov_b32 s3, 8
	s_waitcnt vmcnt(3)
	v_cvt_f32_f16_sdwa v17, v20 dst_sel:DWORD dst_unused:UNUSED_PAD src0_sel:WORD_1
	v_cvt_f32_f16_e32 v16, v20
	v_cvt_f32_f16_sdwa v20, v21 dst_sel:DWORD dst_unused:UNUSED_PAD src0_sel:WORD_1
	v_cvt_f32_f16_e32 v18, v21
	v_cvt_f32_f16_e32 v21, v22
	v_cvt_f32_f16_sdwa v22, v22 dst_sel:DWORD dst_unused:UNUSED_PAD src0_sel:WORD_1
	v_not_b32_e32 v34, v17
	v_or_b32_e32 v35, 0x80000000, v17
	v_cmp_gt_i32_e32 vcc, 0, v17
	v_not_b32_e32 v36, v16
	v_or_b32_e32 v37, 0x80000000, v16
	v_cndmask_b32_e32 v17, v35, v34, vcc
	v_cmp_gt_i32_e32 vcc, 0, v16
	v_cvt_f32_f16_e32 v32, v23
	v_cvt_f32_f16_sdwa v23, v23 dst_sel:DWORD dst_unused:UNUSED_PAD src0_sel:WORD_1
	v_not_b32_e32 v38, v20
	v_or_b32_e32 v39, 0x80000000, v20
	v_cndmask_b32_e32 v16, v37, v36, vcc
	v_cmp_gt_i32_e32 vcc, 0, v20
	v_not_b32_e32 v40, v18
	v_or_b32_e32 v41, 0x80000000, v18
	v_cndmask_b32_e32 v20, v39, v38, vcc
	v_cmp_gt_i32_e32 vcc, 0, v18
	s_waitcnt vmcnt(2)
	v_cvt_f32_f16_e32 v33, v24
	v_cvt_f32_f16_sdwa v24, v24 dst_sel:DWORD dst_unused:UNUSED_PAD src0_sel:WORD_1
	v_not_b32_e32 v42, v22
	v_or_b32_e32 v43, 0x80000000, v22
	v_cndmask_b32_e32 v18, v41, v40, vcc
	v_cmp_gt_i32_e32 vcc, 0, v22
	v_not_b32_e32 v44, v21
	v_or_b32_e32 v45, 0x80000000, v21
	v_cndmask_b32_e32 v22, v43, v42, vcc
	v_cmp_gt_i32_e32 vcc, 0, v21
	v_not_b32_e32 v46, v23
	v_or_b32_e32 v47, 0x80000000, v23
	v_cndmask_b32_e32 v21, v45, v44, vcc
	v_cmp_gt_i32_e32 vcc, 0, v23
	v_not_b32_e32 v48, v32
	v_or_b32_e32 v49, 0x80000000, v32
	v_cndmask_b32_e32 v23, v47, v46, vcc
	v_cmp_gt_i32_e32 vcc, 0, v32
	v_and_b32_e32 v16, 0xffffff80, v16
	v_not_b32_e32 v50, v24
	v_or_b32_e32 v51, 0x80000000, v24
	v_cndmask_b32_e32 v32, v49, v48, vcc
	v_sub_u32_e32 v16, v16, v15
	v_cmp_gt_i32_e32 vcc, 0, v24
	v_add_u32_e32 v35, 0x7f, v16
	v_and_b32_e32 v17, 0xffffff80, v17
	v_cndmask_b32_e32 v16, v51, v50, vcc
	v_and_b32_e32 v16, 0xffffff80, v16
	v_sub_u32_e32 v17, v17, v15
	v_sub_u32_e32 v16, v16, v8
	v_add_u32_e32 v34, 0x7e, v17
	v_add_u32_e32 v41, 0x7e, v16
	v_not_b32_e32 v16, v33
	v_or_b32_e32 v17, 0x80000000, v33
	v_cmp_gt_i32_e32 vcc, 0, v33
	v_and_b32_e32 v20, 0xffffff80, v20
	v_and_b32_e32 v18, 0xffffff80, v18
	v_cndmask_b32_e32 v16, v17, v16, vcc
	v_cvt_f32_f16_sdwa v17, v25 dst_sel:DWORD dst_unused:UNUSED_PAD src0_sel:WORD_1
	v_and_b32_e32 v21, 0xffffff80, v21
	v_sub_u32_e32 v20, v20, v14
	v_sub_u32_e32 v18, v18, v14
	v_sub_u32_e32 v21, v21, v12
	v_add_u32_e32 v36, 0x7e, v20
	v_add_u32_e32 v37, 0x7f, v18
	v_add_u32_e32 v39, 0x7f, v21
	v_and_b32_e32 v16, 0xffffff80, v16
	v_cvt_f32_f16_e32 v18, v25
	v_not_b32_e32 v20, v17
	v_or_b32_e32 v21, 0x80000000, v17
	v_cmp_gt_i32_e32 vcc, 0, v17
	v_sub_u32_e32 v16, v16, v8
	v_add_u32_e32 v33, 0x7f, v16
	v_cndmask_b32_e32 v17, v21, v20, vcc
	v_or_b32_e32 v16, 10, v15
	v_and_b32_e32 v17, 0xffffff80, v17
	v_sub_u32_e32 v17, v17, v16
	v_add_u32_e32 v42, 0x7e, v17
	v_not_b32_e32 v17, v18
	v_or_b32_e32 v20, 0x80000000, v18
	v_cmp_gt_i32_e32 vcc, 0, v18
	v_cvt_f32_f16_sdwa v18, v26 dst_sel:DWORD dst_unused:UNUSED_PAD src0_sel:WORD_1
	v_and_b32_e32 v22, 0xffffff80, v22
	v_sub_u32_e32 v22, v22, v12
	v_cndmask_b32_e32 v17, v20, v17, vcc
	v_add_u32_e32 v38, 0x7e, v22
	v_and_b32_e32 v17, 0xffffff80, v17
	v_cvt_f32_f16_e32 v20, v26
	v_not_b32_e32 v21, v18
	v_or_b32_e32 v22, 0x80000000, v18
	v_cmp_gt_i32_e32 vcc, 0, v18
	v_sub_u32_e32 v17, v17, v16
	v_add_u32_e32 v43, 0x7f, v17
	v_cndmask_b32_e32 v18, v22, v21, vcc
	v_or_b32_e32 v17, 12, v15
	v_and_b32_e32 v18, 0xffffff80, v18
	v_sub_u32_e32 v18, v18, v17
	v_add_u32_e32 v44, 0x7e, v18
	v_not_b32_e32 v18, v20
	v_or_b32_e32 v21, 0x80000000, v20
	v_cmp_gt_i32_e32 vcc, 0, v20
	v_cvt_f32_f16_sdwa v20, v27 dst_sel:DWORD dst_unused:UNUSED_PAD src0_sel:WORD_1
	v_and_b32_e32 v23, 0xffffff80, v23
	v_sub_u32_e32 v23, v23, v10
	v_cndmask_b32_e32 v18, v21, v18, vcc
	v_add_u32_e32 v40, 0x7e, v23
	v_and_b32_e32 v18, 0xffffff80, v18
	v_cvt_f32_f16_e32 v21, v27
	v_not_b32_e32 v22, v20
	v_or_b32_e32 v23, 0x80000000, v20
	v_cmp_gt_i32_e32 vcc, 0, v20
	v_sub_u32_e32 v18, v18, v17
	v_add_u32_e32 v45, 0x7f, v18
	v_cndmask_b32_e32 v20, v23, v22, vcc
	v_or_b32_e32 v18, 14, v15
	v_and_b32_e32 v20, 0xffffff80, v20
	v_sub_u32_e32 v20, v20, v18
	v_add_u32_e32 v27, 0x7e, v20
	v_not_b32_e32 v20, v21
	v_or_b32_e32 v22, 0x80000000, v21
	v_cmp_gt_i32_e32 vcc, 0, v21
	s_waitcnt vmcnt(0)
; __device__ __forceinline__ unsigned f2key(float f) { const unsigned u = __float_as_uint(f); return (u & 0x80000000u) ? ~u : (u | 0x80000000u); }
; #define CE_DESC(a, b) do { const unsigned _mx = (a) > (b) ? (a) : (b), _mn = (a) > (b) ? (b) : (a); (a) = _mx; (b) = _mn; } while (0)
; __device__ __forceinline__ void sort16_desc(unsigned (&k)[16]) {
; #pragma unroll
;     for (int size = 2; size <= 16; size <<= 1)
; #pragma unroll
;         for (int stride = size >> 1; stride > 0; stride >>= 1)
; #pragma unroll
;             for (int i = 0; i < 16; ++i) { const int j = i ^ stride;
;                 if (j > i) { if ((i & size) == 0) CE_DESC(k[i], k[j]); else CE_DESC(k[j], k[i]); } }
; }
; __device__ __forceinline__ void peer_tile(const Args& A, LAS unsigned char* lds, int tile) {
;     ...
;                   for (int i = 0; i < 16; ++i) {
;                       const float lo = (float)__builtin_bit_cast(_Float16, (unsigned short)(sw[i] & 0xffffu)), hi = (float)__builtin_bit_cast(_Float16, (unsigned short)(sw[i] >> 16));
;                       const unsigned klo = (f2key(lo) & ~127u) | (unsigned)(127 - (32 * g + 2 * i)), khi = (f2key(hi) & ~127u) | (unsigned)(127 - (32 * g + 2 * i + 1));
;                       if (i < 8) { k0[2 * i] = klo; k0[2 * i + 1] = khi; } else { k1[2 * (i - 8)] = klo; k1[2 * (i - 8) + 1] = khi; } } }
;                 sort16_desc(k0); sort16_desc(k1); merge16(k0, k1);
	v_cvt_f32_f16_sdwa v21, v28 dst_sel:DWORD dst_unused:UNUSED_PAD src0_sel:WORD_1
	v_and_b32_e32 v32, 0xffffff80, v32
	v_cndmask_b32_e32 v20, v22, v20, vcc
	v_and_b32_e32 v20, 0xffffff80, v20
	v_cvt_f32_f16_e32 v22, v28
	v_not_b32_e32 v23, v21
	v_or_b32_e32 v24, 0x80000000, v21
	v_cmp_gt_i32_e32 vcc, 0, v21
	v_sub_u32_e32 v20, v20, v18
	v_add_u32_e32 v46, 0x7f, v20
	v_cndmask_b32_e32 v21, v24, v23, vcc
	v_or_b32_e32 v20, 16, v15
	v_and_b32_e32 v21, 0xffffff80, v21
	v_sub_u32_e32 v21, v21, v20
	v_add_u32_e32 v47, 0x7e, v21
	v_not_b32_e32 v21, v22
	v_or_b32_e32 v23, 0x80000000, v22
	v_cmp_gt_i32_e32 vcc, 0, v22
	v_cvt_f32_f16_sdwa v22, v29 dst_sel:DWORD dst_unused:UNUSED_PAD src0_sel:WORD_1
	v_sub_u32_e32 v32, v32, v10
	v_cndmask_b32_e32 v21, v23, v21, vcc
	v_and_b32_e32 v21, 0xffffff80, v21
	v_cvt_f32_f16_e32 v23, v29
	v_not_b32_e32 v24, v22
	v_or_b32_e32 v25, 0x80000000, v22
	v_cmp_gt_i32_e32 vcc, 0, v22
	v_sub_u32_e32 v21, v21, v20
	v_add_u32_e32 v48, 0x7f, v21
	v_cndmask_b32_e32 v22, v25, v24, vcc
	v_or_b32_e32 v21, 18, v15
	v_and_b32_e32 v22, 0xffffff80, v22
	v_sub_u32_e32 v22, v22, v21
	v_add_u32_e32 v29, 0x7e, v22
	v_not_b32_e32 v22, v23
	v_or_b32_e32 v24, 0x80000000, v23
	v_cmp_gt_i32_e32 vcc, 0, v23
	v_cvt_f32_f16_sdwa v23, v30 dst_sel:DWORD dst_unused:UNUSED_PAD src0_sel:WORD_1
	v_add_u32_e32 v32, 0x7f, v32
	v_cndmask_b32_e32 v22, v24, v22, vcc
	v_and_b32_e32 v22, 0xffffff80, v22
	v_cvt_f32_f16_e32 v24, v30
	v_not_b32_e32 v25, v23
	v_or_b32_e32 v26, 0x80000000, v23
	v_cmp_gt_i32_e32 vcc, 0, v23
	v_sub_u32_e32 v22, v22, v21
	v_add_u32_e32 v49, 0x7f, v22
	v_cndmask_b32_e32 v23, v26, v25, vcc
	v_or_b32_e32 v22, 20, v15
	v_and_b32_e32 v23, 0xffffff80, v23
	v_sub_u32_e32 v23, v23, v22
	v_add_u32_e32 v30, 0x7e, v23
	v_not_b32_e32 v23, v24
	v_or_b32_e32 v25, 0x80000000, v24
	v_cmp_gt_i32_e32 vcc, 0, v24
	v_cvt_f32_f16_sdwa v24, v31 dst_sel:DWORD dst_unused:UNUSED_PAD src0_sel:WORD_1
	v_max_u32_e32 v64, v48, v47
	v_cndmask_b32_e32 v23, v25, v23, vcc
	v_and_b32_e32 v23, 0xffffff80, v23
	v_cvt_f32_f16_e32 v25, v31
	v_not_b32_e32 v26, v24
	v_or_b32_e32 v28, 0x80000000, v24
	v_cmp_gt_i32_e32 vcc, 0, v24
	v_sub_u32_e32 v23, v23, v22
	v_add_u32_e32 v50, 0x7f, v23
	v_cndmask_b32_e32 v24, v28, v26, vcc
	v_or_b32_e32 v23, 22, v15
	v_and_b32_e32 v24, 0xffffff80, v24
	v_sub_u32_e32 v24, v24, v23
	v_add_u32_e32 v31, 0x7e, v24
	v_not_b32_e32 v24, v25
	v_or_b32_e32 v26, 0x80000000, v25
	v_cmp_gt_i32_e32 vcc, 0, v25
	v_cvt_f32_f16_sdwa v25, v0 dst_sel:DWORD dst_unused:UNUSED_PAD src0_sel:WORD_1
	v_cvt_f32_f16_e32 v0, v0
	v_cndmask_b32_e32 v24, v26, v24, vcc
	v_and_b32_e32 v24, 0xffffff80, v24
	v_not_b32_e32 v26, v25
	v_or_b32_e32 v28, 0x80000000, v25
	v_cmp_gt_i32_e32 vcc, 0, v25
	v_sub_u32_e32 v24, v24, v23
	v_add_u32_e32 v51, 0x7f, v24
	v_cndmask_b32_e32 v25, v28, v26, vcc
	v_or_b32_e32 v24, 24, v15
	v_and_b32_e32 v25, 0xffffff80, v25
	v_sub_u32_e32 v25, v25, v24
	v_add_u32_e32 v52, 0x7e, v25
	v_not_b32_e32 v25, v0
	v_or_b32_e32 v26, 0x80000000, v0
	v_cmp_gt_i32_e32 vcc, 0, v0
	v_min_u32_e32 v47, v48, v47
	v_max_u32_e32 v48, v29, v49
	v_cndmask_b32_e32 v0, v26, v25, vcc
	v_cvt_f32_f16_sdwa v26, v1 dst_sel:DWORD dst_unused:UNUSED_PAD src0_sel:WORD_1
	v_cvt_f32_f16_e32 v1, v1
	v_or_b32_e32 v25, 26, v15
	v_and_b32_e32 v0, 0xffffff80, v0
	v_not_b32_e32 v28, v26
	v_or_b32_e32 v53, 0x80000000, v26
	v_cmp_gt_i32_e32 vcc, 0, v26
	v_sub_u32_e32 v0, v0, v24
	v_add_u32_e32 v0, 0x7f, v0
	v_cndmask_b32_e32 v26, v53, v28, vcc
	v_and_b32_e32 v26, 0xffffff80, v26
	v_sub_u32_e32 v26, v26, v25
	v_add_u32_e32 v53, 0x7e, v26
	v_not_b32_e32 v26, v1
	v_or_b32_e32 v28, 0x80000000, v1
	v_cmp_gt_i32_e32 vcc, 0, v1
	v_min_u32_e32 v29, v29, v49
	v_max_u32_e32 v49, v50, v30
	v_cndmask_b32_e32 v1, v28, v26, vcc
	v_cvt_f32_f16_sdwa v28, v2 dst_sel:DWORD dst_unused:UNUSED_PAD src0_sel:WORD_1
	v_cvt_f32_f16_e32 v2, v2
	v_or_b32_e32 v26, 28, v15
	v_and_b32_e32 v1, 0xffffff80, v1
	v_not_b32_e32 v54, v28
	v_or_b32_e32 v55, 0x80000000, v28
	v_cmp_gt_i32_e32 vcc, 0, v28
	v_sub_u32_e32 v1, v1, v25
	v_add_u32_e32 v1, 0x7f, v1
	v_cndmask_b32_e32 v28, v55, v54, vcc
	v_and_b32_e32 v28, 0xffffff80, v28
	v_sub_u32_e32 v28, v28, v26
	v_add_u32_e32 v54, 0x7e, v28
	v_not_b32_e32 v28, v2
	v_or_b32_e32 v55, 0x80000000, v2
	v_cmp_gt_i32_e32 vcc, 0, v2
	v_min_u32_e32 v30, v50, v30
	v_max_u32_e32 v50, v31, v51
	v_cndmask_b32_e32 v2, v55, v28, vcc
	v_cvt_f32_f16_e32 v55, v3
	v_cvt_f32_f16_sdwa v3, v3 dst_sel:DWORD dst_unused:UNUSED_PAD src0_sel:WORD_1
	v_and_b32_e32 v2, 0xffffff80, v2
	v_or_b32_e32 v28, 30, v15
	v_not_b32_e32 v56, v55
	v_or_b32_e32 v57, 0x80000000, v55
	v_cmp_gt_i32_e32 vcc, 0, v55
	v_sub_u32_e32 v2, v2, v26
	v_add_u32_e32 v2, 0x7f, v2
	v_cndmask_b32_e32 v55, v57, v56, vcc
	v_not_b32_e32 v56, v3
	v_or_b32_e32 v57, 0x80000000, v3
	v_cmp_gt_i32_e32 vcc, 0, v3
	v_and_b32_e32 v55, 0xffffff80, v55
	v_sub_u32_e32 v55, v55, v28
	v_cndmask_b32_e32 v3, v57, v56, vcc
	v_and_b32_e32 v3, 0xffffff80, v3
	v_sub_u32_e32 v3, v3, v28
	v_add_u32_e32 v55, 0x7f, v55
	v_add_u32_e32 v3, 0x7e, v3
	v_max_u32_e32 v56, v35, v34
	v_min_u32_e32 v34, v35, v34
	v_max_u32_e32 v35, v36, v37
	v_min_u32_e32 v36, v36, v37
	v_max_u32_e32 v37, v39, v38
	v_min_u32_e32 v38, v39, v38
	v_max_u32_e32 v39, v40, v32
	v_min_u32_e32 v32, v40, v32
	v_max_u32_e32 v40, v33, v41
	v_min_u32_e32 v33, v33, v41
	v_max_u32_e32 v41, v42, v43
	v_min_u32_e32 v42, v42, v43
	v_max_u32_e32 v43, v45, v44
	v_min_u32_e32 v44, v45, v44
	v_max_u32_e32 v45, v27, v46
	v_min_u32_e32 v27, v27, v46
	v_min_u32_e32 v31, v31, v51
	v_max_u32_e32 v51, v0, v52
	v_min_u32_e32 v0, v0, v52
	v_max_u32_e32 v52, v53, v1
	v_min_u32_e32 v1, v53, v1
	v_max_u32_e32 v53, v2, v54
; #define CE_DESC(a, b) do { const unsigned _mx = (a) > (b) ? (a) : (b), _mn = (a) > (b) ? (b) : (a); (a) = _mx; (b) = _mn; } while (0)
; __device__ __forceinline__ void sort16_desc(unsigned (&k)[16]) {
; #pragma unroll
;     for (int size = 2; size <= 16; size <<= 1)
; #pragma unroll
;         for (int stride = size >> 1; stride > 0; stride >>= 1)
; #pragma unroll
;             for (int i = 0; i < 16; ++i) { const int j = i ^ stride;
;                 if (j > i) { if ((i & size) == 0) CE_DESC(k[i], k[j]); else CE_DESC(k[j], k[i]); } }
; }
	v_min_u32_e32 v2, v2, v54
	v_max_u32_e32 v54, v3, v55
	v_min_u32_e32 v3, v3, v55
	v_max_u32_e32 v46, v56, v36
	v_min_u32_e32 v36, v56, v36
	v_max_u32_e32 v56, v34, v35
	v_min_u32_e32 v34, v34, v35
	v_max_u32_e32 v35, v32, v37
	v_min_u32_e32 v32, v32, v37
	v_max_u32_e32 v37, v39, v38
	v_min_u32_e32 v38, v39, v38
	v_max_u32_e32 v39, v40, v42
	v_min_u32_e32 v40, v40, v42
	v_max_u32_e32 v42, v33, v41
	v_min_u32_e32 v33, v33, v41
	v_max_u32_e32 v41, v27, v43
	v_min_u32_e32 v27, v27, v43
	v_max_u32_e32 v43, v45, v44
	v_min_u32_e32 v44, v45, v44
	v_max_u32_e32 v55, v64, v29
	v_min_u32_e32 v29, v64, v29
	v_max_u32_e32 v64, v47, v48
	v_min_u32_e32 v47, v47, v48
	v_max_u32_e32 v48, v31, v49
	v_min_u32_e32 v31, v31, v49
	v_max_u32_e32 v49, v50, v30
	v_min_u32_e32 v30, v50, v30
	v_max_u32_e32 v50, v51, v1
	v_min_u32_e32 v1, v51, v1
	v_max_u32_e32 v51, v0, v52
	v_min_u32_e32 v0, v0, v52
	v_max_u32_e32 v52, v3, v53
	v_min_u32_e32 v3, v3, v53
	v_max_u32_e32 v53, v54, v2
	v_min_u32_e32 v2, v54, v2
	v_max_u32_e32 v45, v46, v56
	v_min_u32_e32 v46, v46, v56
	v_max_u32_e32 v56, v36, v34
	v_min_u32_e32 v34, v36, v34
	v_max_u32_e32 v36, v38, v32
	v_min_u32_e32 v32, v38, v32
	v_max_u32_e32 v38, v37, v35
	v_min_u32_e32 v35, v37, v35
	v_max_u32_e32 v37, v39, v42
	v_min_u32_e32 v39, v39, v42
	v_max_u32_e32 v42, v40, v33
	v_min_u32_e32 v33, v40, v33
	v_max_u32_e32 v40, v44, v27
	v_min_u32_e32 v27, v44, v27
	v_max_u32_e32 v44, v43, v41
	v_min_u32_e32 v41, v43, v41
	v_max_u32_e32 v54, v55, v64
	v_min_u32_e32 v55, v55, v64
	v_max_u32_e32 v64, v29, v47
	v_min_u32_e32 v29, v29, v47
	v_max_u32_e32 v47, v30, v31
	v_min_u32_e32 v30, v30, v31
	v_max_u32_e32 v31, v49, v48
	v_min_u32_e32 v48, v49, v48
	v_max_u32_e32 v49, v50, v51
	v_min_u32_e32 v50, v50, v51
	v_max_u32_e32 v51, v1, v0
	v_min_u32_e32 v0, v1, v0
	v_max_u32_e32 v1, v2, v3
	v_min_u32_e32 v2, v2, v3
	v_max_u32_e32 v3, v53, v52
	v_min_u32_e32 v52, v53, v52
	v_max_u32_e32 v43, v45, v32
	v_min_u32_e32 v32, v45, v32
	v_max_u32_e32 v45, v46, v36
	v_min_u32_e32 v36, v46, v36
	v_max_u32_e32 v46, v56, v35
	v_min_u32_e32 v35, v56, v35
	v_max_u32_e32 v56, v34, v38
	v_min_u32_e32 v34, v34, v38
	v_max_u32_e32 v38, v27, v37
	v_min_u32_e32 v27, v27, v37
	v_max_u32_e32 v37, v40, v39
	v_min_u32_e32 v39, v40, v39
	v_max_u32_e32 v40, v41, v42
	v_min_u32_e32 v41, v41, v42
	v_max_u32_e32 v42, v44, v33
	v_min_u32_e32 v33, v44, v33
	v_max_u32_e32 v53, v54, v30
	v_min_u32_e32 v30, v54, v30
	v_max_u32_e32 v54, v55, v47
	v_min_u32_e32 v47, v55, v47
	v_max_u32_e32 v55, v64, v48
	v_min_u32_e32 v48, v64, v48
	v_max_u32_e32 v64, v29, v31
	v_min_u32_e32 v29, v29, v31
	v_max_u32_e32 v31, v2, v49
	v_min_u32_e32 v2, v2, v49
	v_max_u32_e32 v49, v1, v50
	v_min_u32_e32 v1, v1, v50
	v_max_u32_e32 v50, v52, v51
	v_min_u32_e32 v51, v52, v51
	v_max_u32_e32 v52, v3, v0
	v_min_u32_e32 v0, v3, v0
	v_max_u32_e32 v44, v43, v46
	v_min_u32_e32 v43, v43, v46
	v_max_u32_e32 v46, v45, v56
	v_min_u32_e32 v45, v45, v56
	v_max_u32_e32 v56, v32, v35
	v_min_u32_e32 v32, v32, v35
	v_max_u32_e32 v35, v36, v34
	v_min_u32_e32 v34, v36, v34
	v_max_u32_e32 v36, v41, v27
	v_min_u32_e32 v27, v41, v27
	v_max_u32_e32 v41, v33, v39
	v_min_u32_e32 v33, v33, v39
	v_max_u32_e32 v39, v40, v38
	v_min_u32_e32 v38, v40, v38
	v_max_u32_e32 v40, v42, v37
	v_min_u32_e32 v37, v42, v37
	v_max_u32_e32 v3, v53, v55
	v_min_u32_e32 v53, v53, v55
	v_max_u32_e32 v55, v54, v64
	v_min_u32_e32 v54, v54, v64
	v_max_u32_e32 v64, v30, v48
	v_min_u32_e32 v30, v30, v48
	v_max_u32_e32 v48, v47, v29
	v_min_u32_e32 v29, v47, v29
	v_max_u32_e32 v47, v51, v2
	v_min_u32_e32 v2, v51, v2
	v_max_u32_e32 v51, v0, v1
	v_min_u32_e32 v0, v0, v1
	v_max_u32_e32 v1, v50, v31
	v_min_u32_e32 v31, v50, v31
	v_max_u32_e32 v50, v52, v49
	v_min_u32_e32 v49, v52, v49
	v_max_u32_e32 v42, v44, v46
	v_min_u32_e32 v44, v44, v46
	v_max_u32_e32 v46, v43, v45
	v_min_u32_e32 v43, v43, v45
	v_max_u32_e32 v45, v56, v35
	v_min_u32_e32 v35, v56, v35
	v_max_u32_e32 v56, v32, v34
	v_min_u32_e32 v32, v32, v34
	v_max_u32_e32 v34, v33, v27
	v_min_u32_e32 v27, v33, v27
	v_max_u32_e32 v33, v41, v36
	v_min_u32_e32 v36, v41, v36
	v_max_u32_e32 v41, v37, v38
	v_min_u32_e32 v37, v37, v38
	v_max_u32_e32 v38, v40, v39
	v_min_u32_e32 v39, v40, v39
	v_max_u32_e32 v52, v3, v55
	v_min_u32_e32 v3, v3, v55
	v_max_u32_e32 v55, v53, v54
	v_min_u32_e32 v53, v53, v54
	v_max_u32_e32 v54, v64, v48
	v_min_u32_e32 v48, v64, v48
	v_max_u32_e32 v64, v30, v29
	v_min_u32_e32 v29, v30, v29
	v_max_u32_e32 v30, v0, v2
	v_min_u32_e32 v0, v0, v2
	v_max_u32_e32 v2, v51, v47
	v_min_u32_e32 v47, v51, v47
	v_max_u32_e32 v51, v49, v31
	v_min_u32_e32 v31, v49, v31
	v_max_u32_e32 v49, v50, v1
	v_min_u32_e32 v1, v50, v1
	v_max_u32_e32 v40, v42, v27
	v_min_u32_e32 v27, v42, v27
	v_max_u32_e32 v42, v44, v34
	v_min_u32_e32 v34, v44, v34
	v_max_u32_e32 v44, v46, v36
	v_min_u32_e32 v36, v46, v36
	v_max_u32_e32 v46, v43, v33
	v_min_u32_e32 v33, v43, v33
	v_max_u32_e32 v43, v45, v37
	v_min_u32_e32 v37, v45, v37
	v_max_u32_e32 v45, v35, v41
	v_min_u32_e32 v35, v35, v41
	v_max_u32_e32 v41, v56, v39
	v_min_u32_e32 v39, v56, v39
	v_max_u32_e32 v56, v32, v38
	v_min_u32_e32 v32, v32, v38
	v_max_u32_e32 v50, v52, v0
	v_min_u32_e32 v0, v52, v0
	v_max_u32_e32 v52, v3, v30
	v_min_u32_e32 v3, v3, v30
	v_max_u32_e32 v30, v55, v47
	v_min_u32_e32 v47, v55, v47
	v_max_u32_e32 v55, v53, v2
	v_min_u32_e32 v2, v53, v2
	v_max_u32_e32 v53, v54, v31
	v_min_u32_e32 v31, v54, v31
	v_max_u32_e32 v54, v48, v51
	v_min_u32_e32 v48, v48, v51
	v_max_u32_e32 v51, v64, v1
	v_min_u32_e32 v1, v64, v1
	v_max_u32_e32 v64, v29, v49
	v_min_u32_e32 v29, v29, v49
	v_max_u32_e32 v38, v40, v43
	v_min_u32_e32 v40, v40, v43
; #define CE_DESC(a, b) do { const unsigned _mx = (a) > (b) ? (a) : (b), _mn = (a) > (b) ? (b) : (a); (a) = _mx; (b) = _mn; } while (0)
; __device__ __forceinline__ void merge16(unsigned (&a)[16], const unsigned (&b)[16]) {
; #pragma unroll
;     for (int i = 0; i < 16; ++i) a[i] = a[i] > b[15 - i] ? a[i] : b[15 - i];
; #pragma unroll
;     for (int stride = 8; stride > 0; stride >>= 1)
; #pragma unroll
;         for (int i = 0; i < 16; ++i) { const int j = i ^ stride; if (j > i) CE_DESC(a[i], a[j]); }
; }
; __device__ __forceinline__ void peer_tile(const Args& A, LAS unsigned char* lds, int tile) {
;     ...
;                 for (int msk = 16; msk <= 32; msk <<= 1) {
; #pragma unroll
;                     for (int i = 0; i < 16; ++i) k1[i] = (unsigned)__shfl_xor((int)k0[i], msk);
;                     merge16(k0, k1); }
	v_max_u32_e32 v43, v42, v45
	v_min_u32_e32 v42, v42, v45
	v_max_u32_e32 v45, v44, v41
	v_min_u32_e32 v41, v44, v41
	v_max_u32_e32 v44, v46, v56
	v_min_u32_e32 v46, v46, v56
	v_max_u32_e32 v56, v27, v37
	v_min_u32_e32 v27, v27, v37
	v_max_u32_e32 v37, v34, v35
	v_min_u32_e32 v34, v34, v35
	v_max_u32_e32 v35, v36, v39
	v_min_u32_e32 v36, v36, v39
	v_max_u32_e32 v39, v33, v32
	v_min_u32_e32 v32, v33, v32
	v_max_u32_e32 v49, v50, v53
	v_min_u32_e32 v50, v50, v53
	v_max_u32_e32 v53, v52, v54
	v_min_u32_e32 v52, v52, v54
	v_max_u32_e32 v54, v30, v51
	v_min_u32_e32 v30, v30, v51
	v_max_u32_e32 v51, v55, v64
	v_min_u32_e32 v55, v55, v64
	v_max_u32_e32 v64, v0, v31
	v_min_u32_e32 v0, v0, v31
	v_max_u32_e32 v31, v3, v48
	v_min_u32_e32 v3, v3, v48
	v_max_u32_e32 v48, v47, v1
	v_min_u32_e32 v1, v47, v1
	v_max_u32_e32 v47, v2, v29
	v_min_u32_e32 v2, v2, v29
	v_max_u32_e32 v33, v38, v45
	v_min_u32_e32 v38, v38, v45
	v_max_u32_e32 v45, v43, v44
	v_min_u32_e32 v43, v43, v44
	v_max_u32_e32 v44, v40, v41
	v_min_u32_e32 v40, v40, v41
	v_max_u32_e32 v41, v42, v46
	v_min_u32_e32 v42, v42, v46
	v_max_u32_e32 v46, v56, v35
	v_min_u32_e32 v35, v56, v35
	v_max_u32_e32 v56, v37, v39
	v_min_u32_e32 v37, v37, v39
	v_max_u32_e32 v39, v27, v36
	v_min_u32_e32 v27, v27, v36
	v_max_u32_e32 v36, v34, v32
	v_min_u32_e32 v32, v34, v32
	v_max_u32_e32 v29, v49, v54
	v_min_u32_e32 v49, v49, v54
	v_max_u32_e32 v54, v53, v51
	v_min_u32_e32 v51, v53, v51
	v_max_u32_e32 v53, v50, v30
	v_min_u32_e32 v30, v50, v30
	v_max_u32_e32 v50, v52, v55
	v_min_u32_e32 v52, v52, v55
	v_max_u32_e32 v55, v64, v48
	v_min_u32_e32 v48, v64, v48
	v_max_u32_e32 v64, v31, v47
	v_min_u32_e32 v31, v31, v47
	v_max_u32_e32 v47, v0, v1
	v_min_u32_e32 v0, v0, v1
	v_max_u32_e32 v1, v3, v2
	v_min_u32_e32 v2, v3, v2
	v_min_u32_e32 v34, v33, v45
	v_min_u32_e32 v57, v38, v43
	v_min_u32_e32 v58, v44, v41
	v_min_u32_e32 v59, v40, v42
	v_min_u32_e32 v60, v46, v56
	v_min_u32_e32 v61, v35, v37
	v_min_u32_e32 v62, v39, v36
	v_min_u32_e32 v63, v27, v32
	v_min_u32_e32 v3, v29, v54
	v_min_u32_e32 v65, v49, v51
	v_min_u32_e32 v66, v53, v50
	v_min_u32_e32 v67, v30, v52
	v_min_u32_e32 v68, v55, v64
	v_min_u32_e32 v69, v48, v31
	v_min_u32_e32 v70, v47, v1
	v_min_u32_e32 v71, v0, v2
	v_max3_u32 v33, v33, v45, v71
	v_max3_u32 v0, v34, v0, v2
	v_max3_u32 v2, v38, v43, v70
	v_max3_u32 v1, v57, v47, v1
	v_max3_u32 v34, v44, v41, v69
	v_max3_u32 v31, v58, v48, v31
	v_max3_u32 v38, v40, v42, v68
	v_max3_u32 v40, v59, v55, v64
	v_max3_u32 v41, v46, v56, v67
	v_max3_u32 v30, v60, v30, v52
	v_max3_u32 v35, v35, v37, v66
	v_max3_u32 v37, v61, v53, v50
	v_max3_u32 v36, v39, v36, v65
	v_max3_u32 v39, v62, v49, v51
	v_max3_u32 v3, v27, v32, v3
	v_max3_u32 v27, v63, v29, v54
	v_max_u32_e32 v29, v33, v41
	v_min_u32_e32 v32, v33, v41
	v_max_u32_e32 v33, v0, v30
	v_min_u32_e32 v0, v0, v30
	v_max_u32_e32 v30, v2, v35
	v_min_u32_e32 v2, v2, v35
	v_max_u32_e32 v35, v1, v37
	v_min_u32_e32 v1, v1, v37
	v_max_u32_e32 v37, v34, v36
	v_min_u32_e32 v34, v34, v36
	v_max_u32_e32 v36, v31, v39
	v_min_u32_e32 v31, v31, v39
	v_max_u32_e32 v39, v38, v3
	v_min_u32_e32 v3, v38, v3
	v_max_u32_e32 v38, v40, v27
	v_min_u32_e32 v27, v40, v27
	v_max_u32_e32 v40, v29, v37
	v_min_u32_e32 v29, v29, v37
	v_max_u32_e32 v37, v33, v36
	v_min_u32_e32 v33, v33, v36
	v_max_u32_e32 v36, v30, v39
	v_min_u32_e32 v30, v30, v39
	v_max_u32_e32 v39, v35, v38
	v_min_u32_e32 v35, v35, v38
	v_max_u32_e32 v38, v32, v34
	v_min_u32_e32 v32, v32, v34
	v_max_u32_e32 v34, v0, v31
	v_min_u32_e32 v0, v0, v31
	v_max_u32_e32 v31, v2, v3
	v_min_u32_e32 v2, v2, v3
	v_max_u32_e32 v3, v1, v27
	v_min_u32_e32 v1, v1, v27
	v_max_u32_e32 v27, v40, v36
	v_min_u32_e32 v36, v40, v36
	v_max_u32_e32 v40, v37, v39
	v_min_u32_e32 v37, v37, v39
	v_max_u32_e32 v39, v29, v30
	v_min_u32_e32 v29, v29, v30
	v_max_u32_e32 v30, v33, v35
	v_min_u32_e32 v33, v33, v35
	v_max_u32_e32 v35, v38, v31
	v_min_u32_e32 v31, v38, v31
	v_max_u32_e32 v38, v34, v3
	v_min_u32_e32 v3, v34, v3
	v_max_u32_e32 v34, v32, v2
	v_min_u32_e32 v2, v32, v2
	v_max_u32_e32 v32, v0, v1
	v_min_u32_e32 v0, v0, v1
	v_cmp_lt_i32_e32 vcc, v217, v216
	v_max_u32_e32 v41, v36, v37
	v_min_u32_e32 v36, v36, v37
	v_max_u32_e32 v37, v39, v30
	v_min_u32_e32 v30, v39, v30
	v_max_u32_e32 v39, v29, v33
	v_min_u32_e32 v29, v29, v33
	v_max_u32_e32 v33, v35, v38
	v_min_u32_e32 v35, v35, v38
	v_max_u32_e32 v38, v31, v3
	v_min_u32_e32 v3, v31, v3
	v_max_u32_e32 v31, v34, v32
	v_min_u32_e32 v32, v34, v32
	v_max_u32_e32 v34, v2, v0
	v_min_u32_e32 v0, v2, v0
	v_cndmask_b32_e32 v2, v215, v217, vcc
	v_max_u32_e32 v1, v27, v40
	v_min_u32_e32 v40, v27, v40
	v_lshlrev_b32_e32 v27, 2, v2
	ds_bpermute_b32 v2, v27, v1
	ds_bpermute_b32 v42, v27, v40
	ds_bpermute_b32 v43, v27, v41
	ds_bpermute_b32 v44, v27, v36
	ds_bpermute_b32 v45, v27, v37
	ds_bpermute_b32 v46, v27, v30
	ds_bpermute_b32 v47, v27, v39
	ds_bpermute_b32 v48, v27, v29
	ds_bpermute_b32 v49, v27, v33
	ds_bpermute_b32 v50, v27, v35
	ds_bpermute_b32 v51, v27, v38
	ds_bpermute_b32 v52, v27, v0
	ds_bpermute_b32 v53, v27, v34
	ds_bpermute_b32 v54, v27, v32
	ds_bpermute_b32 v55, v27, v31
	ds_bpermute_b32 v56, v27, v3
	s_waitcnt lgkmcnt(4)
	v_max_u32_e32 v1, v1, v52
	s_waitcnt lgkmcnt(3)
	v_max_u32_e32 v40, v40, v53
	s_waitcnt lgkmcnt(2)
	v_max_u32_e32 v41, v41, v54
	s_waitcnt lgkmcnt(1)
	v_max_u32_e32 v36, v36, v55
	s_waitcnt lgkmcnt(0)
; __device__ __forceinline__ void peer_tile(const Args& A, LAS unsigned char* lds, int tile) {
;     ...
;                 { const bf16_t* sp = QRY + m * 2048 + hp * 128 + 32 * g;
;                   const u32x4 s0 = *(const u32x4*)sp, s1 = *(const u32x4*)(sp + 8), s2 = *(const u32x4*)(sp + 16), s3 = *(const u32x4*)(sp + 24);
;     ...
;                 for (int msk = 16; msk <= 32; msk <<= 1) {
; #pragma unroll
;                     for (int i = 0; i < 16; ++i) k1[i] = (unsigned)__shfl_xor((int)k0[i], msk);
;                     merge16(k0, k1); }
; #pragma unroll
;                 for (int i = 0; i < 16; ++i) LA[hh][p][i] = k0[i];
	v_max_u32_e32 v37, v37, v56
	v_max_u32_e32 v30, v30, v51
	v_max_u32_e32 v39, v39, v50
	v_max_u32_e32 v29, v29, v49
	v_max_u32_e32 v33, v33, v48
	v_max_u32_e32 v35, v35, v47
	v_max_u32_e32 v38, v38, v46
	v_max_u32_e32 v3, v3, v45
	v_max_u32_e32 v31, v31, v44
	v_max_u32_e32 v32, v32, v43
	v_max_u32_e32 v34, v34, v42
	v_max_u32_e32 v0, v0, v2
	v_max_u32_e32 v2, v1, v33
	v_min_u32_e32 v1, v1, v33
	v_max_u32_e32 v33, v40, v35
	v_min_u32_e32 v35, v40, v35
	v_max_u32_e32 v40, v41, v38
	v_min_u32_e32 v38, v41, v38
	v_max_u32_e32 v41, v36, v3
	v_min_u32_e32 v3, v36, v3
	v_max_u32_e32 v36, v37, v31
	v_min_u32_e32 v31, v37, v31
	v_max_u32_e32 v37, v30, v32
	v_min_u32_e32 v30, v30, v32
	v_max_u32_e32 v32, v39, v34
	v_min_u32_e32 v34, v39, v34
	v_max_u32_e32 v39, v29, v0
	v_min_u32_e32 v0, v29, v0
	v_max_u32_e32 v29, v2, v36
	v_min_u32_e32 v2, v2, v36
	v_max_u32_e32 v36, v33, v37
	v_min_u32_e32 v33, v33, v37
	v_max_u32_e32 v37, v40, v32
	v_min_u32_e32 v32, v40, v32
	v_max_u32_e32 v40, v41, v39
	v_min_u32_e32 v39, v41, v39
	v_max_u32_e32 v41, v1, v31
	v_min_u32_e32 v1, v1, v31
	v_max_u32_e32 v31, v35, v30
	v_min_u32_e32 v30, v35, v30
	v_max_u32_e32 v35, v38, v34
	v_min_u32_e32 v34, v38, v34
	v_max_u32_e32 v38, v3, v0
	v_min_u32_e32 v0, v3, v0
	v_max_u32_e32 v3, v29, v37
	v_min_u32_e32 v29, v29, v37
	v_max_u32_e32 v37, v36, v40
	v_min_u32_e32 v36, v36, v40
	v_max_u32_e32 v40, v2, v32
	v_min_u32_e32 v2, v2, v32
	v_max_u32_e32 v32, v33, v39
	v_min_u32_e32 v33, v33, v39
	v_max_u32_e32 v39, v41, v35
	v_min_u32_e32 v35, v41, v35
	v_max_u32_e32 v41, v31, v38
	v_min_u32_e32 v31, v31, v38
	v_max_u32_e32 v38, v1, v34
	v_min_u32_e32 v1, v1, v34
	v_max_u32_e32 v34, v30, v0
	v_min_u32_e32 v0, v30, v0
	v_cmp_lt_i32_e32 vcc, v218, v216
	v_max_u32_e32 v42, v40, v32
	v_min_u32_e32 v32, v40, v32
	v_max_u32_e32 v40, v2, v33
	v_min_u32_e32 v2, v2, v33
	v_max_u32_e32 v33, v39, v41
	v_min_u32_e32 v39, v39, v41
	v_max_u32_e32 v41, v35, v31
	v_min_u32_e32 v31, v35, v31
	v_max_u32_e32 v35, v38, v34
	v_min_u32_e32 v34, v38, v34
	v_max_u32_e32 v38, v1, v0
	v_min_u32_e32 v0, v1, v0
	v_cndmask_b32_e32 v1, v215, v218, vcc
	v_max_u32_e32 v30, v3, v37
	v_min_u32_e32 v3, v3, v37
	v_max_u32_e32 v37, v29, v36
	v_min_u32_e32 v36, v29, v36
	v_lshlrev_b32_e32 v29, 2, v1
	ds_bpermute_b32 v46, v29, v0
	ds_bpermute_b32 v1, v29, v30
	ds_bpermute_b32 v43, v29, v3
	ds_bpermute_b32 v44, v29, v37
	ds_bpermute_b32 v45, v29, v36
	s_waitcnt lgkmcnt(4)
	v_max_u32_e32 v30, v30, v46
	global_load_dwordx4 v[46:49], v[4:5], off offset:272
	global_load_dwordx4 v[50:53], v[4:5], off offset:256
	ds_bpermute_b32 v54, v29, v42
	ds_bpermute_b32 v55, v29, v32
	ds_bpermute_b32 v56, v29, v40
	ds_bpermute_b32 v57, v29, v2
	ds_bpermute_b32 v58, v29, v33
	ds_bpermute_b32 v59, v29, v39
	ds_bpermute_b32 v60, v29, v41
	ds_bpermute_b32 v61, v29, v31
	ds_bpermute_b32 v62, v29, v35
	ds_bpermute_b32 v63, v29, v38
	ds_bpermute_b32 v64, v29, v34
	s_waitcnt lgkmcnt(4)
	v_max_u32_e32 v32, v32, v60
	s_waitcnt lgkmcnt(3)
	v_max_u32_e32 v42, v42, v61
	s_waitcnt lgkmcnt(2)
	v_max_u32_e32 v36, v36, v62
	s_waitcnt lgkmcnt(1)
	v_max_u32_e32 v3, v3, v63
	s_waitcnt lgkmcnt(0)
	v_max_u32_e32 v37, v37, v64
	v_max_u32_e32 v40, v40, v59
	v_max_u32_e32 v2, v2, v58
	v_max_u32_e32 v33, v33, v57
	v_max_u32_e32 v39, v39, v56
	v_max_u32_e32 v41, v41, v55
	v_max_u32_e32 v31, v31, v54
	v_max_u32_e32 v35, v35, v45
	v_max_u32_e32 v34, v34, v44
	v_max_u32_e32 v38, v38, v43
	v_max_u32_e32 v0, v0, v1
	v_max_u32_e32 v1, v30, v33
	v_min_u32_e32 v30, v30, v33
	v_max_u32_e32 v33, v3, v39
	v_min_u32_e32 v3, v3, v39
	v_max_u32_e32 v39, v37, v41
	v_min_u32_e32 v37, v37, v41
	v_max_u32_e32 v41, v36, v31
	v_min_u32_e32 v31, v36, v31
	v_max_u32_e32 v36, v42, v35
	v_min_u32_e32 v35, v42, v35
	v_max_u32_e32 v42, v32, v34
	v_min_u32_e32 v32, v32, v34
	v_max_u32_e32 v34, v40, v38
	v_min_u32_e32 v38, v40, v38
	v_max_u32_e32 v40, v2, v0
	v_min_u32_e32 v0, v2, v0
	v_max_u32_e32 v2, v1, v36
	v_min_u32_e32 v1, v1, v36
	v_max_u32_e32 v36, v33, v42
	v_min_u32_e32 v33, v33, v42
	v_max_u32_e32 v42, v39, v34
	v_min_u32_e32 v34, v39, v34
	v_max_u32_e32 v39, v41, v40
	v_min_u32_e32 v40, v41, v40
	v_max_u32_e32 v41, v30, v35
	v_min_u32_e32 v30, v30, v35
	v_max_u32_e32 v35, v3, v32
	v_min_u32_e32 v3, v3, v32
	v_max_u32_e32 v32, v37, v38
	v_min_u32_e32 v37, v37, v38
	v_max_u32_e32 v38, v31, v0
	v_min_u32_e32 v0, v31, v0
	v_max_u32_e32 v31, v2, v42
	v_min_u32_e32 v2, v2, v42
	v_max_u32_e32 v42, v36, v39
	v_min_u32_e32 v36, v36, v39
	v_max_u32_e32 v39, v1, v34
	v_min_u32_e32 v1, v1, v34
	v_max_u32_e32 v34, v33, v40
	v_min_u32_e32 v33, v33, v40
	v_max_u32_e32 v54, v41, v32
	v_min_u32_e32 v32, v41, v32
	v_max_u32_e32 v55, v35, v38
	v_min_u32_e32 v56, v35, v38
	v_max_u32_e32 v57, v30, v37
	v_min_u32_e32 v30, v30, v37
	v_max_u32_e32 v58, v3, v0
	v_min_u32_e32 v0, v3, v0
	v_max_u32_e32 v45, v31, v42
	v_min_u32_e32 v44, v31, v42
	v_max_u32_e32 v43, v2, v36
	v_min_u32_e32 v42, v2, v36
	v_max_u32_e32 v41, v39, v34
	v_min_u32_e32 v40, v39, v34
	v_max_u32_e32 v39, v1, v33
	v_min_u32_e32 v38, v1, v33
	v_max_u32_e32 v37, v54, v55
	v_min_u32_e32 v36, v54, v55
	v_max_u32_e32 v35, v32, v56
	v_min_u32_e32 v34, v32, v56
	v_max_u32_e32 v33, v57, v58
	v_min_u32_e32 v32, v57, v58
	v_max_u32_e32 v31, v30, v0
	v_min_u32_e32 v30, v30, v0
	global_load_dwordx4 v[0:3], v[4:5], off offset:304
	global_load_dwordx4 v[54:57], v[4:5], off offset:288
	s_waitcnt vmcnt(2)
; __device__ __forceinline__ unsigned f2key(float f) { const unsigned u = __float_as_uint(f); return (u & 0x80000000u) ? ~u : (u | 0x80000000u); }
; __device__ __forceinline__ void peer_tile(const Args& A, LAS unsigned char* lds, int tile) {
;     ...
;                   for (int i = 0; i < 16; ++i) {
;                       const float lo = (float)__builtin_bit_cast(_Float16, (unsigned short)(sw[i] & 0xffffu)), hi = (float)__builtin_bit_cast(_Float16, (unsigned short)(sw[i] >> 16));
;                       const unsigned klo = (f2key(lo) & ~127u) | (unsigned)(127 - (32 * g + 2 * i)), khi = (f2key(hi) & ~127u) | (unsigned)(127 - (32 * g + 2 * i + 1));
;                       if (i < 8) { k0[2 * i] = klo; k0[2 * i + 1] = khi; } else { k1[2 * (i - 8)] = klo; k1[2 * (i - 8) + 1] = khi; } } }
	v_cvt_f32_f16_sdwa v58, v50 dst_sel:DWORD dst_unused:UNUSED_PAD src0_sel:WORD_1
	v_cvt_f32_f16_e32 v50, v50
	v_not_b32_e32 v59, v58
	v_or_b32_e32 v60, 0x80000000, v58
	v_cmp_gt_i32_e32 vcc, 0, v58
	s_nop 1
	v_cndmask_b32_e32 v58, v60, v59, vcc
	v_not_b32_e32 v59, v50
	v_or_b32_e32 v60, 0x80000000, v50
	v_cmp_gt_i32_e32 vcc, 0, v50
	v_and_b32_e32 v58, 0xffffff80, v58
	v_sub_u32_e32 v58, v58, v15
	v_cndmask_b32_e32 v50, v60, v59, vcc
	v_cvt_f32_f16_sdwa v59, v51 dst_sel:DWORD dst_unused:UNUSED_PAD src0_sel:WORD_1
	v_cvt_f32_f16_e32 v51, v51
	v_and_b32_e32 v50, 0xffffff80, v50
	v_sub_u32_e32 v50, v50, v15
	v_not_b32_e32 v60, v59
	v_or_b32_e32 v61, 0x80000000, v59
	v_cmp_gt_i32_e32 vcc, 0, v59
	v_add_u32_e32 v58, 0x7e, v58
	v_add_u32_e32 v50, 0x7f, v50
	v_cndmask_b32_e32 v59, v61, v60, vcc
	v_not_b32_e32 v60, v51
	v_or_b32_e32 v61, 0x80000000, v51
	v_cmp_gt_i32_e32 vcc, 0, v51
	v_and_b32_e32 v59, 0xffffff80, v59
	v_sub_u32_e32 v59, v59, v14
	v_cndmask_b32_e32 v51, v61, v60, vcc
	v_cvt_f32_f16_sdwa v60, v52 dst_sel:DWORD dst_unused:UNUSED_PAD src0_sel:WORD_1
	v_cvt_f32_f16_e32 v52, v52
	v_and_b32_e32 v51, 0xffffff80, v51
	v_sub_u32_e32 v51, v51, v14
	v_not_b32_e32 v61, v60
	v_or_b32_e32 v62, 0x80000000, v60
	v_cmp_gt_i32_e32 vcc, 0, v60
	v_add_u32_e32 v59, 0x7e, v59
	v_add_u32_e32 v51, 0x7f, v51
	v_cndmask_b32_e32 v60, v62, v61, vcc
	v_not_b32_e32 v61, v52
	v_or_b32_e32 v62, 0x80000000, v52
	v_cmp_gt_i32_e32 vcc, 0, v52
	v_and_b32_e32 v60, 0xffffff80, v60
	v_sub_u32_e32 v60, v60, v12
	v_cndmask_b32_e32 v52, v62, v61, vcc
	v_cvt_f32_f16_sdwa v61, v53 dst_sel:DWORD dst_unused:UNUSED_PAD src0_sel:WORD_1
	v_cvt_f32_f16_e32 v53, v53
	v_and_b32_e32 v52, 0xffffff80, v52
	v_sub_u32_e32 v52, v52, v12
	v_not_b32_e32 v62, v61
	v_or_b32_e32 v63, 0x80000000, v61
	v_cmp_gt_i32_e32 vcc, 0, v61
	v_add_u32_e32 v60, 0x7e, v60
	v_add_u32_e32 v52, 0x7f, v52
	v_cndmask_b32_e32 v61, v63, v62, vcc
	v_not_b32_e32 v62, v53
	v_or_b32_e32 v63, 0x80000000, v53
	v_cmp_gt_i32_e32 vcc, 0, v53
	v_and_b32_e32 v61, 0xffffff80, v61
	v_sub_u32_e32 v61, v61, v10
	v_cndmask_b32_e32 v53, v63, v62, vcc
	v_cvt_f32_f16_sdwa v62, v46 dst_sel:DWORD dst_unused:UNUSED_PAD src0_sel:WORD_1
	v_cvt_f32_f16_e32 v46, v46
	v_and_b32_e32 v53, 0xffffff80, v53
	v_sub_u32_e32 v53, v53, v10
	v_not_b32_e32 v63, v62
	v_or_b32_e32 v64, 0x80000000, v62
	v_cmp_gt_i32_e32 vcc, 0, v62
	v_add_u32_e32 v61, 0x7e, v61
	v_add_u32_e32 v53, 0x7f, v53
	v_cndmask_b32_e32 v62, v64, v63, vcc
	v_not_b32_e32 v63, v46
	v_or_b32_e32 v64, 0x80000000, v46
	v_cmp_gt_i32_e32 vcc, 0, v46
	v_and_b32_e32 v62, 0xffffff80, v62
	v_sub_u32_e32 v62, v62, v8
	v_cndmask_b32_e32 v46, v64, v63, vcc
	v_cvt_f32_f16_sdwa v63, v47 dst_sel:DWORD dst_unused:UNUSED_PAD src0_sel:WORD_1
	v_cvt_f32_f16_e32 v47, v47
	v_and_b32_e32 v46, 0xffffff80, v46
	v_sub_u32_e32 v46, v46, v8
	v_not_b32_e32 v64, v63
	v_or_b32_e32 v65, 0x80000000, v63
	v_cmp_gt_i32_e32 vcc, 0, v63
	v_add_u32_e32 v62, 0x7e, v62
	v_add_u32_e32 v46, 0x7f, v46
	v_cndmask_b32_e32 v63, v65, v64, vcc
	v_not_b32_e32 v64, v47
	v_or_b32_e32 v65, 0x80000000, v47
	v_cmp_gt_i32_e32 vcc, 0, v47
	v_and_b32_e32 v63, 0xffffff80, v63
	v_sub_u32_e32 v63, v63, v16
	v_cndmask_b32_e32 v47, v65, v64, vcc
	v_cvt_f32_f16_sdwa v64, v48 dst_sel:DWORD dst_unused:UNUSED_PAD src0_sel:WORD_1
	v_cvt_f32_f16_e32 v48, v48
	v_and_b32_e32 v47, 0xffffff80, v47
	v_sub_u32_e32 v47, v47, v16
	v_not_b32_e32 v65, v64
	v_or_b32_e32 v66, 0x80000000, v64
	v_cmp_gt_i32_e32 vcc, 0, v64
	v_add_u32_e32 v63, 0x7e, v63
	v_add_u32_e32 v47, 0x7f, v47
	v_cndmask_b32_e32 v64, v66, v65, vcc
	v_not_b32_e32 v65, v48
	v_or_b32_e32 v66, 0x80000000, v48
	v_cmp_gt_i32_e32 vcc, 0, v48
	v_and_b32_e32 v64, 0xffffff80, v64
	v_sub_u32_e32 v64, v64, v17
	v_cndmask_b32_e32 v48, v66, v65, vcc
	v_cvt_f32_f16_sdwa v65, v49 dst_sel:DWORD dst_unused:UNUSED_PAD src0_sel:WORD_1
	v_cvt_f32_f16_e32 v49, v49
	v_and_b32_e32 v48, 0xffffff80, v48
	v_sub_u32_e32 v48, v48, v17
	v_not_b32_e32 v66, v65
	v_or_b32_e32 v67, 0x80000000, v65
	v_cmp_gt_i32_e32 vcc, 0, v65
	v_add_u32_e32 v64, 0x7e, v64
	v_add_u32_e32 v48, 0x7f, v48
	v_cndmask_b32_e32 v65, v67, v66, vcc
	v_not_b32_e32 v66, v49
	v_or_b32_e32 v67, 0x80000000, v49
	v_cmp_gt_i32_e32 vcc, 0, v49
	v_and_b32_e32 v65, 0xffffff80, v65
	v_sub_u32_e32 v65, v65, v18
	v_cndmask_b32_e32 v49, v67, v66, vcc
	s_waitcnt vmcnt(0)
; __device__ __forceinline__ unsigned f2key(float f) { const unsigned u = __float_as_uint(f); return (u & 0x80000000u) ? ~u : (u | 0x80000000u); }
; #define CE_DESC(a, b) do { const unsigned _mx = (a) > (b) ? (a) : (b), _mn = (a) > (b) ? (b) : (a); (a) = _mx; (b) = _mn; } while (0)
; __device__ __forceinline__ void sort16_desc(unsigned (&k)[16]) {
; #pragma unroll
;     for (int size = 2; size <= 16; size <<= 1)
; #pragma unroll
;         for (int stride = size >> 1; stride > 0; stride >>= 1)
; #pragma unroll
;             for (int i = 0; i < 16; ++i) { const int j = i ^ stride;
;                 if (j > i) { if ((i & size) == 0) CE_DESC(k[i], k[j]); else CE_DESC(k[j], k[i]); } }
; }
; __device__ __forceinline__ void peer_tile(const Args& A, LAS unsigned char* lds, int tile) {
;     ...
;                   for (int i = 0; i < 16; ++i) {
;                       const float lo = (float)__builtin_bit_cast(_Float16, (unsigned short)(sw[i] & 0xffffu)), hi = (float)__builtin_bit_cast(_Float16, (unsigned short)(sw[i] >> 16));
;                       const unsigned klo = (f2key(lo) & ~127u) | (unsigned)(127 - (32 * g + 2 * i)), khi = (f2key(hi) & ~127u) | (unsigned)(127 - (32 * g + 2 * i + 1));
;                       if (i < 8) { k0[2 * i] = klo; k0[2 * i + 1] = khi; } else { k1[2 * (i - 8)] = klo; k1[2 * (i - 8) + 1] = khi; } } }
;                 sort16_desc(k0); sort16_desc(k1); merge16(k0, k1);
	v_cvt_f32_f16_sdwa v66, v54 dst_sel:DWORD dst_unused:UNUSED_PAD src0_sel:WORD_1
	v_cvt_f32_f16_e32 v54, v54
	v_and_b32_e32 v49, 0xffffff80, v49
	v_sub_u32_e32 v49, v49, v18
	v_not_b32_e32 v67, v66
	v_or_b32_e32 v68, 0x80000000, v66
	v_cmp_gt_i32_e32 vcc, 0, v66
	v_add_u32_e32 v65, 0x7e, v65
	v_add_u32_e32 v49, 0x7f, v49
	v_cndmask_b32_e32 v66, v68, v67, vcc
	v_not_b32_e32 v67, v54
	v_or_b32_e32 v68, 0x80000000, v54
	v_cmp_gt_i32_e32 vcc, 0, v54
	v_and_b32_e32 v66, 0xffffff80, v66
	v_sub_u32_e32 v66, v66, v20
	v_cndmask_b32_e32 v54, v68, v67, vcc
	v_cvt_f32_f16_sdwa v67, v55 dst_sel:DWORD dst_unused:UNUSED_PAD src0_sel:WORD_1
	v_cvt_f32_f16_e32 v55, v55
	v_and_b32_e32 v54, 0xffffff80, v54
	v_sub_u32_e32 v54, v54, v20
	v_not_b32_e32 v68, v67
	v_or_b32_e32 v69, 0x80000000, v67
	v_cmp_gt_i32_e32 vcc, 0, v67
	v_add_u32_e32 v66, 0x7e, v66
	v_add_u32_e32 v54, 0x7f, v54
	v_cndmask_b32_e32 v67, v69, v68, vcc
	v_not_b32_e32 v68, v55
	v_or_b32_e32 v69, 0x80000000, v55
	v_cmp_gt_i32_e32 vcc, 0, v55
	v_and_b32_e32 v67, 0xffffff80, v67
	v_sub_u32_e32 v67, v67, v21
	v_cndmask_b32_e32 v55, v69, v68, vcc
	v_cvt_f32_f16_sdwa v68, v56 dst_sel:DWORD dst_unused:UNUSED_PAD src0_sel:WORD_1
	v_cvt_f32_f16_e32 v56, v56
	v_and_b32_e32 v55, 0xffffff80, v55
	v_sub_u32_e32 v55, v55, v21
	v_not_b32_e32 v69, v68
	v_or_b32_e32 v70, 0x80000000, v68
	v_cmp_gt_i32_e32 vcc, 0, v68
	v_add_u32_e32 v67, 0x7e, v67
	v_add_u32_e32 v55, 0x7f, v55
	v_cndmask_b32_e32 v68, v70, v69, vcc
	v_not_b32_e32 v69, v56
	v_or_b32_e32 v70, 0x80000000, v56
	v_cmp_gt_i32_e32 vcc, 0, v56
	v_and_b32_e32 v68, 0xffffff80, v68
	v_sub_u32_e32 v68, v68, v22
	v_cndmask_b32_e32 v56, v70, v69, vcc
	v_cvt_f32_f16_sdwa v69, v57 dst_sel:DWORD dst_unused:UNUSED_PAD src0_sel:WORD_1
	v_cvt_f32_f16_e32 v57, v57
	v_and_b32_e32 v56, 0xffffff80, v56
	v_sub_u32_e32 v56, v56, v22
	v_not_b32_e32 v70, v69
	v_or_b32_e32 v71, 0x80000000, v69
	v_cmp_gt_i32_e32 vcc, 0, v69
	v_add_u32_e32 v68, 0x7e, v68
	v_add_u32_e32 v56, 0x7f, v56
	v_cndmask_b32_e32 v69, v71, v70, vcc
	v_not_b32_e32 v70, v57
	v_or_b32_e32 v71, 0x80000000, v57
	v_cmp_gt_i32_e32 vcc, 0, v57
	v_and_b32_e32 v69, 0xffffff80, v69
	v_sub_u32_e32 v69, v69, v23
	v_cndmask_b32_e32 v57, v71, v70, vcc
	v_cvt_f32_f16_sdwa v70, v0 dst_sel:DWORD dst_unused:UNUSED_PAD src0_sel:WORD_1
	v_cvt_f32_f16_e32 v0, v0
	v_and_b32_e32 v57, 0xffffff80, v57
	v_sub_u32_e32 v57, v57, v23
	v_not_b32_e32 v71, v70
	v_or_b32_e32 v72, 0x80000000, v70
	v_cmp_gt_i32_e32 vcc, 0, v70
	v_add_u32_e32 v69, 0x7e, v69
	v_add_u32_e32 v57, 0x7f, v57
	v_cndmask_b32_e32 v70, v72, v71, vcc
	v_not_b32_e32 v71, v0
	v_or_b32_e32 v72, 0x80000000, v0
	v_cmp_gt_i32_e32 vcc, 0, v0
	v_and_b32_e32 v70, 0xffffff80, v70
	v_sub_u32_e32 v70, v70, v24
	v_cndmask_b32_e32 v0, v72, v71, vcc
	v_cvt_f32_f16_sdwa v71, v1 dst_sel:DWORD dst_unused:UNUSED_PAD src0_sel:WORD_1
	v_cvt_f32_f16_e32 v1, v1
	v_and_b32_e32 v0, 0xffffff80, v0
	v_sub_u32_e32 v0, v0, v24
	v_not_b32_e32 v72, v71
	v_or_b32_e32 v73, 0x80000000, v71
	v_cmp_gt_i32_e32 vcc, 0, v71
	v_add_u32_e32 v70, 0x7e, v70
	v_add_u32_e32 v0, 0x7f, v0
	v_cndmask_b32_e32 v71, v73, v72, vcc
	v_not_b32_e32 v72, v1
	v_or_b32_e32 v73, 0x80000000, v1
	v_cmp_gt_i32_e32 vcc, 0, v1
	v_and_b32_e32 v71, 0xffffff80, v71
	v_sub_u32_e32 v71, v71, v25
	v_cndmask_b32_e32 v1, v73, v72, vcc
	v_cvt_f32_f16_sdwa v72, v2 dst_sel:DWORD dst_unused:UNUSED_PAD src0_sel:WORD_1
	v_cvt_f32_f16_e32 v2, v2
	v_and_b32_e32 v1, 0xffffff80, v1
	v_sub_u32_e32 v1, v1, v25
	v_not_b32_e32 v73, v72
	v_or_b32_e32 v74, 0x80000000, v72
	v_cmp_gt_i32_e32 vcc, 0, v72
	v_add_u32_e32 v71, 0x7e, v71
	v_add_u32_e32 v1, 0x7f, v1
	v_cndmask_b32_e32 v72, v74, v73, vcc
	v_not_b32_e32 v73, v2
	v_or_b32_e32 v74, 0x80000000, v2
	v_cmp_gt_i32_e32 vcc, 0, v2
	v_and_b32_e32 v72, 0xffffff80, v72
	v_sub_u32_e32 v72, v72, v26
	v_cndmask_b32_e32 v2, v74, v73, vcc
	v_cvt_f32_f16_sdwa v73, v3 dst_sel:DWORD dst_unused:UNUSED_PAD src0_sel:WORD_1
	v_cvt_f32_f16_e32 v3, v3
	v_and_b32_e32 v2, 0xffffff80, v2
	v_sub_u32_e32 v2, v2, v26
	v_not_b32_e32 v74, v73
	v_or_b32_e32 v75, 0x80000000, v73
	v_cmp_gt_i32_e32 vcc, 0, v73
	v_add_u32_e32 v72, 0x7e, v72
	v_add_u32_e32 v2, 0x7f, v2
	v_cndmask_b32_e32 v73, v75, v74, vcc
	v_not_b32_e32 v74, v3
	v_or_b32_e32 v75, 0x80000000, v3
	v_cmp_gt_i32_e32 vcc, 0, v3
	v_and_b32_e32 v73, 0xffffff80, v73
	v_sub_u32_e32 v73, v73, v28
	v_cndmask_b32_e32 v3, v75, v74, vcc
	v_and_b32_e32 v3, 0xffffff80, v3
	v_sub_u32_e32 v3, v3, v28
	v_add_u32_e32 v73, 0x7e, v73
	v_add_u32_e32 v3, 0x7f, v3
	v_max_u32_e32 v74, v50, v58
	v_min_u32_e32 v50, v50, v58
	v_max_u32_e32 v58, v59, v51
	v_min_u32_e32 v51, v59, v51
	v_max_u32_e32 v59, v52, v60
	v_min_u32_e32 v52, v52, v60
	v_max_u32_e32 v60, v61, v53
	v_min_u32_e32 v53, v61, v53
	v_max_u32_e32 v61, v46, v62
	v_min_u32_e32 v46, v46, v62
	v_max_u32_e32 v62, v63, v47
	v_min_u32_e32 v47, v63, v47
	v_max_u32_e32 v63, v48, v64
	v_min_u32_e32 v48, v48, v64
	v_max_u32_e32 v64, v65, v49
	v_min_u32_e32 v49, v65, v49
	v_max_u32_e32 v82, v54, v66
	v_min_u32_e32 v54, v54, v66
	v_max_u32_e32 v66, v67, v55
	v_min_u32_e32 v55, v67, v55
	v_max_u32_e32 v67, v56, v68
	v_min_u32_e32 v56, v56, v68
	v_max_u32_e32 v68, v69, v57
	v_min_u32_e32 v57, v69, v57
	v_max_u32_e32 v69, v0, v70
	v_min_u32_e32 v0, v0, v70
	v_max_u32_e32 v70, v71, v1
	v_min_u32_e32 v1, v71, v1
	v_max_u32_e32 v71, v2, v72
	v_min_u32_e32 v2, v2, v72
	v_max_u32_e32 v72, v73, v3
	v_min_u32_e32 v3, v73, v3
	v_max_u32_e32 v65, v74, v51
	v_min_u32_e32 v51, v74, v51
	v_max_u32_e32 v74, v50, v58
	v_min_u32_e32 v50, v50, v58
	v_max_u32_e32 v58, v53, v59
	v_min_u32_e32 v53, v53, v59
	v_max_u32_e32 v59, v60, v52
	v_min_u32_e32 v52, v60, v52
; #define CE_DESC(a, b) do { const unsigned _mx = (a) > (b) ? (a) : (b), _mn = (a) > (b) ? (b) : (a); (a) = _mx; (b) = _mn; } while (0)
; __device__ __forceinline__ void sort16_desc(unsigned (&k)[16]) {
; #pragma unroll
;     for (int size = 2; size <= 16; size <<= 1)
; #pragma unroll
;         for (int stride = size >> 1; stride > 0; stride >>= 1)
; #pragma unroll
;             for (int i = 0; i < 16; ++i) { const int j = i ^ stride;
;                 if (j > i) { if ((i & size) == 0) CE_DESC(k[i], k[j]); else CE_DESC(k[j], k[i]); } }
; }
	v_max_u32_e32 v60, v61, v47
	v_min_u32_e32 v47, v61, v47
	v_max_u32_e32 v61, v46, v62
	v_min_u32_e32 v46, v46, v62
	v_max_u32_e32 v62, v49, v63
	v_min_u32_e32 v49, v49, v63
	v_max_u32_e32 v63, v64, v48
	v_min_u32_e32 v48, v64, v48
	v_max_u32_e32 v73, v82, v55
	v_min_u32_e32 v55, v82, v55
	v_max_u32_e32 v82, v54, v66
	v_min_u32_e32 v54, v54, v66
	v_max_u32_e32 v66, v57, v67
	v_min_u32_e32 v57, v57, v67
	v_max_u32_e32 v67, v68, v56
	v_min_u32_e32 v56, v68, v56
	v_max_u32_e32 v68, v69, v1
	v_min_u32_e32 v1, v69, v1
	v_max_u32_e32 v69, v0, v70
	v_min_u32_e32 v0, v0, v70
	v_max_u32_e32 v70, v3, v71
	v_min_u32_e32 v3, v3, v71
	v_max_u32_e32 v71, v72, v2
	v_min_u32_e32 v2, v72, v2
	v_max_u32_e32 v64, v65, v74
	v_min_u32_e32 v65, v65, v74
	v_max_u32_e32 v74, v51, v50
	v_min_u32_e32 v50, v51, v50
	v_max_u32_e32 v51, v52, v53
	v_min_u32_e32 v52, v52, v53
	v_max_u32_e32 v53, v59, v58
	v_min_u32_e32 v58, v59, v58
	v_max_u32_e32 v59, v60, v61
	v_min_u32_e32 v60, v60, v61
	v_max_u32_e32 v61, v47, v46
	v_min_u32_e32 v46, v47, v46
	v_max_u32_e32 v47, v48, v49
	v_min_u32_e32 v48, v48, v49
	v_max_u32_e32 v49, v63, v62
	v_min_u32_e32 v62, v63, v62
	v_max_u32_e32 v72, v73, v82
	v_min_u32_e32 v73, v73, v82
	v_max_u32_e32 v82, v55, v54
	v_min_u32_e32 v54, v55, v54
	v_max_u32_e32 v55, v56, v57
	v_min_u32_e32 v56, v56, v57
	v_max_u32_e32 v57, v67, v66
	v_min_u32_e32 v66, v67, v66
	v_max_u32_e32 v67, v68, v69
	v_min_u32_e32 v68, v68, v69
	v_max_u32_e32 v69, v1, v0
	v_min_u32_e32 v0, v1, v0
	v_max_u32_e32 v1, v2, v3
	v_min_u32_e32 v2, v2, v3
	v_max_u32_e32 v3, v71, v70
	v_min_u32_e32 v70, v71, v70
	v_max_u32_e32 v63, v64, v52
	v_min_u32_e32 v52, v64, v52
	v_max_u32_e32 v64, v65, v51
	v_min_u32_e32 v51, v65, v51
	v_max_u32_e32 v65, v74, v58
	v_min_u32_e32 v58, v74, v58
	v_max_u32_e32 v74, v50, v53
	v_min_u32_e32 v50, v50, v53
	v_max_u32_e32 v53, v48, v59
	v_min_u32_e32 v48, v48, v59
	v_max_u32_e32 v59, v47, v60
	v_min_u32_e32 v47, v47, v60
	v_max_u32_e32 v60, v62, v61
	v_min_u32_e32 v61, v62, v61
	v_max_u32_e32 v62, v49, v46
	v_min_u32_e32 v46, v49, v46
	v_max_u32_e32 v71, v72, v56
	v_min_u32_e32 v56, v72, v56
	v_max_u32_e32 v72, v73, v55
	v_min_u32_e32 v55, v73, v55
	v_max_u32_e32 v73, v82, v66
	v_min_u32_e32 v66, v82, v66
	v_max_u32_e32 v82, v54, v57
	v_min_u32_e32 v54, v54, v57
	v_max_u32_e32 v57, v2, v67
	v_min_u32_e32 v2, v2, v67
	v_max_u32_e32 v67, v1, v68
	v_min_u32_e32 v1, v1, v68
	v_max_u32_e32 v68, v70, v69
	v_min_u32_e32 v69, v70, v69
	v_max_u32_e32 v70, v3, v0
	v_min_u32_e32 v0, v3, v0
	v_max_u32_e32 v49, v63, v65
	v_min_u32_e32 v63, v63, v65
	v_max_u32_e32 v65, v64, v74
	v_min_u32_e32 v64, v64, v74
	v_max_u32_e32 v74, v52, v58
	v_min_u32_e32 v52, v52, v58
	v_max_u32_e32 v58, v51, v50
	v_min_u32_e32 v50, v51, v50
	v_max_u32_e32 v51, v61, v48
	v_min_u32_e32 v48, v61, v48
	v_max_u32_e32 v61, v46, v47
	v_min_u32_e32 v46, v46, v47
	v_max_u32_e32 v47, v60, v53
	v_min_u32_e32 v53, v60, v53
	v_max_u32_e32 v60, v62, v59
	v_min_u32_e32 v59, v62, v59
	v_max_u32_e32 v3, v71, v73
	v_min_u32_e32 v71, v71, v73
	v_max_u32_e32 v73, v72, v82
	v_min_u32_e32 v72, v72, v82
	v_max_u32_e32 v82, v56, v66
	v_min_u32_e32 v56, v56, v66
	v_max_u32_e32 v66, v55, v54
	v_min_u32_e32 v54, v55, v54
	v_max_u32_e32 v55, v69, v2
	v_min_u32_e32 v2, v69, v2
	v_max_u32_e32 v69, v0, v1
	v_min_u32_e32 v0, v0, v1
	v_max_u32_e32 v1, v68, v57
	v_min_u32_e32 v57, v68, v57
	v_max_u32_e32 v68, v70, v67
	v_min_u32_e32 v67, v70, v67
	v_max_u32_e32 v62, v49, v65
	v_min_u32_e32 v49, v49, v65
	v_max_u32_e32 v65, v63, v64
	v_min_u32_e32 v63, v63, v64
	v_max_u32_e32 v64, v74, v58
	v_min_u32_e32 v58, v74, v58
	v_max_u32_e32 v74, v52, v50
	v_min_u32_e32 v50, v52, v50
	v_max_u32_e32 v52, v46, v48
	v_min_u32_e32 v46, v46, v48
	v_max_u32_e32 v48, v61, v51
	v_min_u32_e32 v51, v61, v51
	v_max_u32_e32 v61, v59, v53
	v_min_u32_e32 v53, v59, v53
	v_max_u32_e32 v59, v60, v47
	v_min_u32_e32 v47, v60, v47
	v_max_u32_e32 v70, v3, v73
	v_min_u32_e32 v3, v3, v73
	v_max_u32_e32 v73, v71, v72
	v_min_u32_e32 v71, v71, v72
	v_max_u32_e32 v72, v82, v66
	v_min_u32_e32 v66, v82, v66
	v_max_u32_e32 v82, v56, v54
	v_min_u32_e32 v54, v56, v54
	v_max_u32_e32 v56, v0, v2
	v_min_u32_e32 v0, v0, v2
	v_max_u32_e32 v2, v69, v55
	v_min_u32_e32 v55, v69, v55
	v_max_u32_e32 v69, v67, v57
	v_min_u32_e32 v57, v67, v57
	v_max_u32_e32 v67, v68, v1
	v_min_u32_e32 v1, v68, v1
	v_max_u32_e32 v60, v62, v46
	v_min_u32_e32 v46, v62, v46
	v_max_u32_e32 v62, v49, v52
	v_min_u32_e32 v49, v49, v52
	v_max_u32_e32 v52, v65, v51
	v_min_u32_e32 v51, v65, v51
	v_max_u32_e32 v65, v63, v48
	v_min_u32_e32 v48, v63, v48
	v_max_u32_e32 v63, v64, v53
	v_min_u32_e32 v53, v64, v53
	v_max_u32_e32 v64, v58, v61
	v_min_u32_e32 v58, v58, v61
	v_max_u32_e32 v61, v74, v47
	v_min_u32_e32 v47, v74, v47
	v_max_u32_e32 v74, v50, v59
	v_min_u32_e32 v50, v50, v59
	v_max_u32_e32 v68, v70, v0
	v_min_u32_e32 v0, v70, v0
	v_max_u32_e32 v70, v3, v56
	v_min_u32_e32 v3, v3, v56
	v_max_u32_e32 v56, v73, v55
	v_min_u32_e32 v55, v73, v55
	v_max_u32_e32 v73, v71, v2
	v_min_u32_e32 v2, v71, v2
	v_max_u32_e32 v71, v72, v57
	v_min_u32_e32 v57, v72, v57
	v_max_u32_e32 v72, v66, v69
	v_min_u32_e32 v66, v66, v69
	v_max_u32_e32 v69, v82, v1
	v_min_u32_e32 v1, v82, v1
	v_max_u32_e32 v82, v54, v67
	v_min_u32_e32 v54, v54, v67
	v_max_u32_e32 v59, v60, v63
	v_min_u32_e32 v60, v60, v63
	v_max_u32_e32 v63, v62, v64
	v_min_u32_e32 v62, v62, v64
	v_max_u32_e32 v64, v52, v61
	v_min_u32_e32 v52, v52, v61
	v_max_u32_e32 v61, v65, v74
	v_min_u32_e32 v65, v65, v74
	v_max_u32_e32 v74, v46, v53
	v_min_u32_e32 v46, v46, v53
	v_max_u32_e32 v53, v49, v58
	v_min_u32_e32 v49, v49, v58
	v_max_u32_e32 v58, v51, v47
; #define CE_DESC(a, b) do { const unsigned _mx = (a) > (b) ? (a) : (b), _mn = (a) > (b) ? (b) : (a); (a) = _mx; (b) = _mn; } while (0)
; __device__ __forceinline__ void sort16_desc(unsigned (&k)[16]) {
; #pragma unroll
;     for (int size = 2; size <= 16; size <<= 1)
; #pragma unroll
;         for (int stride = size >> 1; stride > 0; stride >>= 1)
; #pragma unroll
;             for (int i = 0; i < 16; ++i) { const int j = i ^ stride;
;                 if (j > i) { if ((i & size) == 0) CE_DESC(k[i], k[j]); else CE_DESC(k[j], k[i]); } }
; }
; __device__ __forceinline__ void merge16(unsigned (&a)[16], const unsigned (&b)[16]) {
; #pragma unroll
;     for (int i = 0; i < 16; ++i) a[i] = a[i] > b[15 - i] ? a[i] : b[15 - i];
; #pragma unroll
;     for (int stride = 8; stride > 0; stride >>= 1)
; #pragma unroll
;         for (int i = 0; i < 16; ++i) { const int j = i ^ stride; if (j > i) CE_DESC(a[i], a[j]); }
; }
; __device__ __forceinline__ void peer_tile(const Args& A, LAS unsigned char* lds, int tile) {
;     ...
;                 sort16_desc(k0); sort16_desc(k1); merge16(k0, k1);
; #pragma unroll
;                 for (int msk = 16; msk <= 32; msk <<= 1) {
; #pragma unroll
;                     for (int i = 0; i < 16; ++i) k1[i] = (unsigned)__shfl_xor((int)k0[i], msk);
;                     merge16(k0, k1); }
	v_min_u32_e32 v47, v51, v47
	v_max_u32_e32 v51, v48, v50
	v_min_u32_e32 v48, v48, v50
	v_max_u32_e32 v67, v68, v71
	v_min_u32_e32 v68, v68, v71
	v_max_u32_e32 v71, v70, v72
	v_min_u32_e32 v70, v70, v72
	v_max_u32_e32 v72, v56, v69
	v_min_u32_e32 v56, v56, v69
	v_max_u32_e32 v69, v73, v82
	v_min_u32_e32 v73, v73, v82
	v_max_u32_e32 v82, v0, v57
	v_min_u32_e32 v0, v0, v57
	v_max_u32_e32 v57, v3, v66
	v_min_u32_e32 v3, v3, v66
	v_max_u32_e32 v66, v55, v1
	v_min_u32_e32 v1, v55, v1
	v_max_u32_e32 v55, v2, v54
	v_min_u32_e32 v2, v2, v54
	v_max_u32_e32 v50, v59, v64
	v_min_u32_e32 v59, v59, v64
	v_max_u32_e32 v64, v63, v61
	v_min_u32_e32 v61, v63, v61
	v_max_u32_e32 v63, v60, v52
	v_min_u32_e32 v52, v60, v52
	v_max_u32_e32 v60, v62, v65
	v_min_u32_e32 v62, v62, v65
	v_max_u32_e32 v65, v74, v58
	v_min_u32_e32 v58, v74, v58
	v_max_u32_e32 v74, v53, v51
	v_min_u32_e32 v51, v53, v51
	v_max_u32_e32 v53, v46, v47
	v_min_u32_e32 v46, v46, v47
	v_max_u32_e32 v47, v49, v48
	v_min_u32_e32 v48, v49, v48
	v_max_u32_e32 v54, v67, v72
	v_min_u32_e32 v67, v67, v72
	v_max_u32_e32 v72, v71, v69
	v_min_u32_e32 v69, v71, v69
	v_max_u32_e32 v71, v68, v56
	v_min_u32_e32 v56, v68, v56
	v_max_u32_e32 v68, v70, v73
	v_min_u32_e32 v70, v70, v73
	v_max_u32_e32 v73, v82, v66
	v_min_u32_e32 v66, v82, v66
	v_max_u32_e32 v82, v57, v55
	v_min_u32_e32 v55, v57, v55
	v_max_u32_e32 v57, v0, v1
	v_min_u32_e32 v0, v0, v1
	v_max_u32_e32 v1, v3, v2
	v_min_u32_e32 v2, v3, v2
	v_min_u32_e32 v49, v50, v64
	v_min_u32_e32 v75, v59, v61
	v_min_u32_e32 v76, v63, v60
	v_min_u32_e32 v77, v52, v62
	v_min_u32_e32 v78, v65, v74
	v_min_u32_e32 v79, v58, v51
	v_min_u32_e32 v80, v53, v47
	v_min_u32_e32 v81, v46, v48
	v_min_u32_e32 v3, v54, v72
	v_min_u32_e32 v83, v67, v69
	v_min_u32_e32 v84, v71, v68
	v_min_u32_e32 v85, v56, v70
	v_min_u32_e32 v86, v73, v82
	v_min_u32_e32 v87, v66, v55
	v_min_u32_e32 v88, v57, v1
	v_min_u32_e32 v89, v0, v2
	v_max3_u32 v50, v50, v64, v89
	v_max3_u32 v0, v49, v0, v2
	v_max3_u32 v2, v59, v61, v88
	v_max3_u32 v1, v75, v57, v1
	v_max3_u32 v49, v63, v60, v87
	v_max3_u32 v55, v76, v66, v55
	v_max3_u32 v52, v52, v62, v86
	v_max3_u32 v57, v77, v73, v82
	v_max3_u32 v59, v65, v74, v85
	v_max3_u32 v56, v78, v56, v70
	v_max3_u32 v51, v58, v51, v84
	v_max3_u32 v58, v79, v71, v68
	v_max3_u32 v47, v53, v47, v83
	v_max3_u32 v53, v80, v67, v69
	v_max3_u32 v3, v46, v48, v3
	v_max3_u32 v46, v81, v54, v72
	v_max_u32_e32 v48, v50, v59
	v_min_u32_e32 v50, v50, v59
	v_max_u32_e32 v54, v0, v56
	v_min_u32_e32 v0, v0, v56
	v_max_u32_e32 v56, v2, v51
	v_min_u32_e32 v2, v2, v51
	v_max_u32_e32 v51, v1, v58
	v_min_u32_e32 v1, v1, v58
	v_max_u32_e32 v58, v49, v47
	v_min_u32_e32 v47, v49, v47
	v_max_u32_e32 v49, v55, v53
	v_min_u32_e32 v53, v55, v53
	v_max_u32_e32 v55, v52, v3
	v_min_u32_e32 v3, v52, v3
	v_max_u32_e32 v52, v57, v46
	v_min_u32_e32 v46, v57, v46
	v_max_u32_e32 v57, v48, v58
	v_min_u32_e32 v48, v48, v58
	v_max_u32_e32 v58, v54, v49
	v_min_u32_e32 v49, v54, v49
	v_max_u32_e32 v54, v56, v55
	v_min_u32_e32 v55, v56, v55
	v_max_u32_e32 v56, v51, v52
	v_min_u32_e32 v51, v51, v52
	v_max_u32_e32 v52, v50, v47
	v_min_u32_e32 v47, v50, v47
	v_max_u32_e32 v50, v0, v53
	v_min_u32_e32 v0, v0, v53
	v_max_u32_e32 v53, v2, v3
	v_min_u32_e32 v2, v2, v3
	v_max_u32_e32 v3, v1, v46
	v_min_u32_e32 v1, v1, v46
	v_max_u32_e32 v46, v57, v54
	v_min_u32_e32 v54, v57, v54
	v_max_u32_e32 v57, v58, v56
	v_min_u32_e32 v56, v58, v56
	v_max_u32_e32 v58, v48, v55
	v_min_u32_e32 v48, v48, v55
	v_max_u32_e32 v55, v49, v51
	v_min_u32_e32 v49, v49, v51
	v_max_u32_e32 v51, v52, v53
	v_min_u32_e32 v52, v52, v53
	v_max_u32_e32 v53, v50, v3
	v_min_u32_e32 v3, v50, v3
	v_max_u32_e32 v50, v47, v2
	v_min_u32_e32 v2, v47, v2
	v_max_u32_e32 v47, v0, v1
	v_min_u32_e32 v0, v0, v1
	v_max_u32_e32 v1, v46, v57
	v_min_u32_e32 v46, v46, v57
	v_max_u32_e32 v57, v54, v56
	v_min_u32_e32 v54, v54, v56
	v_max_u32_e32 v56, v58, v55
	v_min_u32_e32 v55, v58, v55
	v_max_u32_e32 v58, v48, v49
	v_min_u32_e32 v48, v48, v49
	v_max_u32_e32 v49, v51, v53
	v_min_u32_e32 v51, v51, v53
	v_max_u32_e32 v53, v52, v3
	v_min_u32_e32 v3, v52, v3
	v_max_u32_e32 v52, v50, v47
	v_min_u32_e32 v47, v50, v47
	v_max_u32_e32 v50, v2, v0
	v_min_u32_e32 v0, v2, v0
	ds_bpermute_b32 v2, v27, v1
	ds_bpermute_b32 v59, v27, v46
	ds_bpermute_b32 v60, v27, v57
	ds_bpermute_b32 v61, v27, v54
	ds_bpermute_b32 v62, v27, v56
	ds_bpermute_b32 v63, v27, v55
	ds_bpermute_b32 v64, v27, v58
	ds_bpermute_b32 v65, v27, v48
	ds_bpermute_b32 v66, v27, v49
	ds_bpermute_b32 v67, v27, v51
	ds_bpermute_b32 v68, v27, v53
	ds_bpermute_b32 v69, v27, v0
	ds_bpermute_b32 v70, v27, v50
	ds_bpermute_b32 v71, v27, v47
	ds_bpermute_b32 v72, v27, v52
	ds_bpermute_b32 v73, v27, v3
	s_waitcnt lgkmcnt(4)
	v_max_u32_e32 v1, v1, v69
	s_waitcnt lgkmcnt(3)
	v_max_u32_e32 v46, v46, v70
	s_waitcnt lgkmcnt(2)
	v_max_u32_e32 v57, v57, v71
	s_waitcnt lgkmcnt(1)
	v_max_u32_e32 v54, v54, v72
	s_waitcnt lgkmcnt(0)
; __device__ __forceinline__ void peer_tile(const Args& A, LAS unsigned char* lds, int tile) {
;     ...
;                 { const bf16_t* sp = QRY + m * 2048 + hp * 128 + 32 * g;
;                   const u32x4 s0 = *(const u32x4*)sp, s1 = *(const u32x4*)(sp + 8), s2 = *(const u32x4*)(sp + 16), s3 = *(const u32x4*)(sp + 24);
;     ...
;                 for (int msk = 16; msk <= 32; msk <<= 1) {
; #pragma unroll
;                     for (int i = 0; i < 16; ++i) k1[i] = (unsigned)__shfl_xor((int)k0[i], msk);
;                     merge16(k0, k1); }
; #pragma unroll
;                 for (int i = 0; i < 16; ++i) LA[hh][p][i] = k0[i];
	v_max_u32_e32 v56, v56, v73
	v_max_u32_e32 v55, v55, v68
	v_max_u32_e32 v58, v58, v67
	v_max_u32_e32 v48, v48, v66
	v_max_u32_e32 v49, v49, v65
	v_max_u32_e32 v51, v51, v64
	v_max_u32_e32 v53, v53, v63
	v_max_u32_e32 v3, v3, v62
	v_max_u32_e32 v52, v52, v61
	v_max_u32_e32 v47, v47, v60
	v_max_u32_e32 v50, v50, v59
	v_max_u32_e32 v0, v0, v2
	v_max_u32_e32 v2, v1, v49
	v_min_u32_e32 v1, v1, v49
	v_max_u32_e32 v49, v46, v51
	v_min_u32_e32 v46, v46, v51
	v_max_u32_e32 v51, v57, v53
	v_min_u32_e32 v53, v57, v53
	v_max_u32_e32 v57, v54, v3
	v_min_u32_e32 v3, v54, v3
	v_max_u32_e32 v54, v56, v52
	v_min_u32_e32 v52, v56, v52
	v_max_u32_e32 v56, v55, v47
	v_min_u32_e32 v47, v55, v47
	v_max_u32_e32 v55, v58, v50
	v_min_u32_e32 v50, v58, v50
	v_max_u32_e32 v58, v48, v0
	v_min_u32_e32 v0, v48, v0
	v_max_u32_e32 v48, v2, v54
	v_min_u32_e32 v2, v2, v54
	v_max_u32_e32 v54, v49, v56
	v_min_u32_e32 v49, v49, v56
	v_max_u32_e32 v56, v51, v55
	v_min_u32_e32 v51, v51, v55
	v_max_u32_e32 v55, v57, v58
	v_min_u32_e32 v57, v57, v58
	v_max_u32_e32 v58, v1, v52
	v_min_u32_e32 v1, v1, v52
	v_max_u32_e32 v52, v46, v47
	v_min_u32_e32 v46, v46, v47
	v_max_u32_e32 v47, v53, v50
	v_min_u32_e32 v50, v53, v50
	v_max_u32_e32 v53, v3, v0
	v_min_u32_e32 v0, v3, v0
	v_max_u32_e32 v3, v48, v56
	v_min_u32_e32 v48, v48, v56
	v_max_u32_e32 v56, v54, v55
	v_min_u32_e32 v54, v54, v55
	v_max_u32_e32 v55, v2, v51
	v_min_u32_e32 v2, v2, v51
	v_max_u32_e32 v51, v49, v57
	v_min_u32_e32 v49, v49, v57
	v_max_u32_e32 v57, v58, v47
	v_min_u32_e32 v47, v58, v47
	v_max_u32_e32 v58, v52, v53
	v_min_u32_e32 v52, v52, v53
	v_max_u32_e32 v53, v1, v50
	v_min_u32_e32 v1, v1, v50
	v_max_u32_e32 v50, v46, v0
	v_min_u32_e32 v0, v46, v0
	v_max_u32_e32 v46, v3, v56
	v_min_u32_e32 v3, v3, v56
	v_max_u32_e32 v56, v48, v54
	v_min_u32_e32 v48, v48, v54
	v_max_u32_e32 v54, v55, v51
	v_min_u32_e32 v51, v55, v51
	v_max_u32_e32 v55, v2, v49
	v_min_u32_e32 v2, v2, v49
	v_max_u32_e32 v49, v57, v58
	v_min_u32_e32 v57, v57, v58
	v_max_u32_e32 v58, v47, v52
	v_min_u32_e32 v47, v47, v52
	v_max_u32_e32 v52, v53, v50
	v_min_u32_e32 v50, v53, v50
	v_max_u32_e32 v53, v1, v0
	v_min_u32_e32 v0, v1, v0
	ds_bpermute_b32 v62, v29, v0
	ds_bpermute_b32 v1, v29, v46
	ds_bpermute_b32 v59, v29, v3
	ds_bpermute_b32 v60, v29, v56
	ds_bpermute_b32 v61, v29, v48
	s_waitcnt lgkmcnt(4)
	v_max_u32_e32 v46, v46, v62
	global_load_dwordx4 v[62:65], v[4:5], off offset:528
	global_load_dwordx4 v[66:69], v[4:5], off offset:512
	ds_bpermute_b32 v70, v29, v54
	ds_bpermute_b32 v71, v29, v51
	ds_bpermute_b32 v72, v29, v55
	ds_bpermute_b32 v73, v29, v2
	ds_bpermute_b32 v74, v29, v49
	ds_bpermute_b32 v75, v29, v57
	ds_bpermute_b32 v76, v29, v58
	ds_bpermute_b32 v77, v29, v47
	ds_bpermute_b32 v78, v29, v52
	ds_bpermute_b32 v79, v29, v53
	ds_bpermute_b32 v80, v29, v50
	s_waitcnt lgkmcnt(4)
	v_max_u32_e32 v51, v51, v76
	s_waitcnt lgkmcnt(3)
	v_max_u32_e32 v54, v54, v77
	s_waitcnt lgkmcnt(2)
	v_max_u32_e32 v48, v48, v78
	s_waitcnt lgkmcnt(1)
	v_max_u32_e32 v3, v3, v79
	s_waitcnt lgkmcnt(0)
	v_max_u32_e32 v56, v56, v80
	v_max_u32_e32 v55, v55, v75
	v_max_u32_e32 v2, v2, v74
	v_max_u32_e32 v49, v49, v73
	v_max_u32_e32 v57, v57, v72
	v_max_u32_e32 v58, v58, v71
	v_max_u32_e32 v47, v47, v70
	v_max_u32_e32 v52, v52, v61
	v_max_u32_e32 v50, v50, v60
	v_max_u32_e32 v53, v53, v59
	v_max_u32_e32 v0, v0, v1
	v_max_u32_e32 v1, v46, v49
	v_min_u32_e32 v46, v46, v49
	v_max_u32_e32 v49, v3, v57
	v_min_u32_e32 v3, v3, v57
	v_max_u32_e32 v57, v56, v58
	v_min_u32_e32 v56, v56, v58
	v_max_u32_e32 v58, v48, v47
	v_min_u32_e32 v47, v48, v47
	v_max_u32_e32 v48, v54, v52
	v_min_u32_e32 v52, v54, v52
	v_max_u32_e32 v54, v51, v50
	v_min_u32_e32 v50, v51, v50
	v_max_u32_e32 v51, v55, v53
	v_min_u32_e32 v53, v55, v53
	v_max_u32_e32 v55, v2, v0
	v_min_u32_e32 v0, v2, v0
	v_max_u32_e32 v2, v1, v48
	v_min_u32_e32 v1, v1, v48
	v_max_u32_e32 v48, v49, v54
	v_min_u32_e32 v49, v49, v54
	v_max_u32_e32 v54, v57, v51
	v_min_u32_e32 v51, v57, v51
	v_max_u32_e32 v57, v58, v55
	v_min_u32_e32 v55, v58, v55
	v_max_u32_e32 v58, v46, v52
	v_min_u32_e32 v46, v46, v52
	v_max_u32_e32 v52, v3, v50
	v_min_u32_e32 v3, v3, v50
	v_max_u32_e32 v50, v56, v53
	v_min_u32_e32 v53, v56, v53
	v_max_u32_e32 v56, v47, v0
	v_min_u32_e32 v0, v47, v0
	v_max_u32_e32 v47, v2, v54
	v_min_u32_e32 v2, v2, v54
	v_max_u32_e32 v54, v48, v57
	v_min_u32_e32 v48, v48, v57
	v_max_u32_e32 v70, v1, v51
	v_min_u32_e32 v1, v1, v51
	v_max_u32_e32 v51, v49, v55
	v_min_u32_e32 v49, v49, v55
	v_max_u32_e32 v71, v58, v50
	v_min_u32_e32 v50, v58, v50
	v_max_u32_e32 v72, v52, v56
	v_min_u32_e32 v73, v52, v56
	v_max_u32_e32 v74, v46, v53
	v_min_u32_e32 v46, v46, v53
	v_max_u32_e32 v75, v3, v0
	v_min_u32_e32 v0, v3, v0
	v_max_u32_e32 v61, v47, v54
	v_min_u32_e32 v60, v47, v54
	v_max_u32_e32 v59, v2, v48
	v_min_u32_e32 v58, v2, v48
	v_max_u32_e32 v57, v70, v51
	v_min_u32_e32 v56, v70, v51
	v_max_u32_e32 v55, v1, v49
	v_min_u32_e32 v54, v1, v49
	v_max_u32_e32 v53, v71, v72
	v_min_u32_e32 v52, v71, v72
	v_max_u32_e32 v51, v50, v73
	v_min_u32_e32 v50, v50, v73
	v_max_u32_e32 v47, v46, v0
	v_min_u32_e32 v46, v46, v0
	global_load_dwordx4 v[0:3], v[4:5], off offset:560
	global_load_dwordx4 v[70:73], v[4:5], off offset:544
	v_max_u32_e32 v49, v74, v75
	v_min_u32_e32 v48, v74, v75
	s_waitcnt vmcnt(2)
; __device__ __forceinline__ unsigned f2key(float f) { const unsigned u = __float_as_uint(f); return (u & 0x80000000u) ? ~u : (u | 0x80000000u); }
; __device__ __forceinline__ void peer_tile(const Args& A, LAS unsigned char* lds, int tile) {
;     ...
;                   for (int i = 0; i < 16; ++i) {
;                       const float lo = (float)__builtin_bit_cast(_Float16, (unsigned short)(sw[i] & 0xffffu)), hi = (float)__builtin_bit_cast(_Float16, (unsigned short)(sw[i] >> 16));
;                       const unsigned klo = (f2key(lo) & ~127u) | (unsigned)(127 - (32 * g + 2 * i)), khi = (f2key(hi) & ~127u) | (unsigned)(127 - (32 * g + 2 * i + 1));
;                       if (i < 8) { k0[2 * i] = klo; k0[2 * i + 1] = khi; } else { k1[2 * (i - 8)] = klo; k1[2 * (i - 8) + 1] = khi; } } }
	v_cvt_f32_f16_sdwa v74, v66 dst_sel:DWORD dst_unused:UNUSED_PAD src0_sel:WORD_1
	v_cvt_f32_f16_e32 v66, v66
	v_not_b32_e32 v75, v74
	v_or_b32_e32 v76, 0x80000000, v74
	v_cmp_gt_i32_e32 vcc, 0, v74
	s_nop 1
	v_cndmask_b32_e32 v74, v76, v75, vcc
	v_not_b32_e32 v75, v66
	v_or_b32_e32 v76, 0x80000000, v66
	v_cmp_gt_i32_e32 vcc, 0, v66
	v_and_b32_e32 v74, 0xffffff80, v74
	v_sub_u32_e32 v74, v74, v15
	v_cndmask_b32_e32 v66, v76, v75, vcc
	v_cvt_f32_f16_sdwa v75, v67 dst_sel:DWORD dst_unused:UNUSED_PAD src0_sel:WORD_1
	v_cvt_f32_f16_e32 v67, v67
	v_and_b32_e32 v66, 0xffffff80, v66
	v_sub_u32_e32 v66, v66, v15
	v_not_b32_e32 v76, v75
	v_or_b32_e32 v77, 0x80000000, v75
	v_cmp_gt_i32_e32 vcc, 0, v75
	v_add_u32_e32 v74, 0x7e, v74
	v_add_u32_e32 v66, 0x7f, v66
	v_cndmask_b32_e32 v75, v77, v76, vcc
	v_not_b32_e32 v76, v67
	v_or_b32_e32 v77, 0x80000000, v67
	v_cmp_gt_i32_e32 vcc, 0, v67
	v_and_b32_e32 v75, 0xffffff80, v75
	v_sub_u32_e32 v75, v75, v14
	v_cndmask_b32_e32 v67, v77, v76, vcc
	v_cvt_f32_f16_sdwa v76, v68 dst_sel:DWORD dst_unused:UNUSED_PAD src0_sel:WORD_1
	v_cvt_f32_f16_e32 v68, v68
	v_and_b32_e32 v67, 0xffffff80, v67
	v_sub_u32_e32 v67, v67, v14
	v_not_b32_e32 v77, v76
	v_or_b32_e32 v78, 0x80000000, v76
	v_cmp_gt_i32_e32 vcc, 0, v76
	v_add_u32_e32 v75, 0x7e, v75
	v_add_u32_e32 v67, 0x7f, v67
	v_cndmask_b32_e32 v76, v78, v77, vcc
	v_not_b32_e32 v77, v68
	v_or_b32_e32 v78, 0x80000000, v68
	v_cmp_gt_i32_e32 vcc, 0, v68
	v_and_b32_e32 v76, 0xffffff80, v76
	v_sub_u32_e32 v76, v76, v12
	v_cndmask_b32_e32 v68, v78, v77, vcc
	v_cvt_f32_f16_sdwa v77, v69 dst_sel:DWORD dst_unused:UNUSED_PAD src0_sel:WORD_1
	v_cvt_f32_f16_e32 v69, v69
	v_and_b32_e32 v68, 0xffffff80, v68
	v_sub_u32_e32 v68, v68, v12
	v_not_b32_e32 v78, v77
	v_or_b32_e32 v79, 0x80000000, v77
	v_cmp_gt_i32_e32 vcc, 0, v77
	v_add_u32_e32 v76, 0x7e, v76
	v_add_u32_e32 v68, 0x7f, v68
	v_cndmask_b32_e32 v77, v79, v78, vcc
	v_not_b32_e32 v78, v69
	v_or_b32_e32 v79, 0x80000000, v69
	v_cmp_gt_i32_e32 vcc, 0, v69
	v_and_b32_e32 v77, 0xffffff80, v77
	v_sub_u32_e32 v77, v77, v10
	v_cndmask_b32_e32 v69, v79, v78, vcc
	v_cvt_f32_f16_sdwa v78, v62 dst_sel:DWORD dst_unused:UNUSED_PAD src0_sel:WORD_1
	v_cvt_f32_f16_e32 v62, v62
	v_and_b32_e32 v69, 0xffffff80, v69
	v_sub_u32_e32 v69, v69, v10
	v_not_b32_e32 v79, v78
	v_or_b32_e32 v80, 0x80000000, v78
	v_cmp_gt_i32_e32 vcc, 0, v78
	v_add_u32_e32 v77, 0x7e, v77
	v_add_u32_e32 v69, 0x7f, v69
	v_cndmask_b32_e32 v78, v80, v79, vcc
	v_not_b32_e32 v79, v62
	v_or_b32_e32 v80, 0x80000000, v62
	v_cmp_gt_i32_e32 vcc, 0, v62
	v_and_b32_e32 v78, 0xffffff80, v78
	v_sub_u32_e32 v78, v78, v8
	v_cndmask_b32_e32 v62, v80, v79, vcc
	v_cvt_f32_f16_sdwa v79, v63 dst_sel:DWORD dst_unused:UNUSED_PAD src0_sel:WORD_1
	v_cvt_f32_f16_e32 v63, v63
	v_and_b32_e32 v62, 0xffffff80, v62
	v_sub_u32_e32 v62, v62, v8
	v_not_b32_e32 v80, v79
	v_or_b32_e32 v81, 0x80000000, v79
	v_cmp_gt_i32_e32 vcc, 0, v79
	v_add_u32_e32 v78, 0x7e, v78
	v_add_u32_e32 v62, 0x7f, v62
	v_cndmask_b32_e32 v79, v81, v80, vcc
	v_not_b32_e32 v80, v63
	v_or_b32_e32 v81, 0x80000000, v63
	v_cmp_gt_i32_e32 vcc, 0, v63
	v_and_b32_e32 v79, 0xffffff80, v79
	v_sub_u32_e32 v79, v79, v16
	v_cndmask_b32_e32 v63, v81, v80, vcc
	v_cvt_f32_f16_sdwa v80, v64 dst_sel:DWORD dst_unused:UNUSED_PAD src0_sel:WORD_1
	v_cvt_f32_f16_e32 v64, v64
	v_and_b32_e32 v63, 0xffffff80, v63
	v_sub_u32_e32 v63, v63, v16
	v_not_b32_e32 v81, v80
	v_or_b32_e32 v82, 0x80000000, v80
	v_cmp_gt_i32_e32 vcc, 0, v80
	v_add_u32_e32 v79, 0x7e, v79
	v_add_u32_e32 v63, 0x7f, v63
	v_cndmask_b32_e32 v80, v82, v81, vcc
	v_not_b32_e32 v81, v64
	v_or_b32_e32 v82, 0x80000000, v64
	v_cmp_gt_i32_e32 vcc, 0, v64
	v_and_b32_e32 v80, 0xffffff80, v80
	v_sub_u32_e32 v80, v80, v17
	v_cndmask_b32_e32 v64, v82, v81, vcc
	v_cvt_f32_f16_sdwa v81, v65 dst_sel:DWORD dst_unused:UNUSED_PAD src0_sel:WORD_1
	v_cvt_f32_f16_e32 v65, v65
	v_and_b32_e32 v64, 0xffffff80, v64
	v_sub_u32_e32 v64, v64, v17
	v_not_b32_e32 v82, v81
	v_or_b32_e32 v83, 0x80000000, v81
	v_cmp_gt_i32_e32 vcc, 0, v81
	v_add_u32_e32 v80, 0x7e, v80
	v_add_u32_e32 v64, 0x7f, v64
	v_cndmask_b32_e32 v81, v83, v82, vcc
	v_not_b32_e32 v82, v65
	v_or_b32_e32 v83, 0x80000000, v65
	v_cmp_gt_i32_e32 vcc, 0, v65
	v_and_b32_e32 v81, 0xffffff80, v81
	v_sub_u32_e32 v81, v81, v18
	v_cndmask_b32_e32 v65, v83, v82, vcc
	s_waitcnt vmcnt(0)
; __device__ __forceinline__ unsigned f2key(float f) { const unsigned u = __float_as_uint(f); return (u & 0x80000000u) ? ~u : (u | 0x80000000u); }
; #define CE_DESC(a, b) do { const unsigned _mx = (a) > (b) ? (a) : (b), _mn = (a) > (b) ? (b) : (a); (a) = _mx; (b) = _mn; } while (0)
; __device__ __forceinline__ void sort16_desc(unsigned (&k)[16]) {
; #pragma unroll
;     for (int size = 2; size <= 16; size <<= 1)
; #pragma unroll
;         for (int stride = size >> 1; stride > 0; stride >>= 1)
; #pragma unroll
;             for (int i = 0; i < 16; ++i) { const int j = i ^ stride;
;                 if (j > i) { if ((i & size) == 0) CE_DESC(k[i], k[j]); else CE_DESC(k[j], k[i]); } }
; }
; __device__ __forceinline__ void peer_tile(const Args& A, LAS unsigned char* lds, int tile) {
;     ...
;                   for (int i = 0; i < 16; ++i) {
;                       const float lo = (float)__builtin_bit_cast(_Float16, (unsigned short)(sw[i] & 0xffffu)), hi = (float)__builtin_bit_cast(_Float16, (unsigned short)(sw[i] >> 16));
;                       const unsigned klo = (f2key(lo) & ~127u) | (unsigned)(127 - (32 * g + 2 * i)), khi = (f2key(hi) & ~127u) | (unsigned)(127 - (32 * g + 2 * i + 1));
;                       if (i < 8) { k0[2 * i] = klo; k0[2 * i + 1] = khi; } else { k1[2 * (i - 8)] = klo; k1[2 * (i - 8) + 1] = khi; } } }
;                 sort16_desc(k0); sort16_desc(k1); merge16(k0, k1);
	v_cvt_f32_f16_sdwa v82, v70 dst_sel:DWORD dst_unused:UNUSED_PAD src0_sel:WORD_1
	v_cvt_f32_f16_e32 v70, v70
	v_and_b32_e32 v65, 0xffffff80, v65
	v_sub_u32_e32 v65, v65, v18
	v_not_b32_e32 v83, v82
	v_or_b32_e32 v84, 0x80000000, v82
	v_cmp_gt_i32_e32 vcc, 0, v82
	v_add_u32_e32 v81, 0x7e, v81
	v_add_u32_e32 v65, 0x7f, v65
	v_cndmask_b32_e32 v82, v84, v83, vcc
	v_not_b32_e32 v83, v70
	v_or_b32_e32 v84, 0x80000000, v70
	v_cmp_gt_i32_e32 vcc, 0, v70
	v_and_b32_e32 v82, 0xffffff80, v82
	v_sub_u32_e32 v82, v82, v20
	v_cndmask_b32_e32 v70, v84, v83, vcc
	v_cvt_f32_f16_sdwa v83, v71 dst_sel:DWORD dst_unused:UNUSED_PAD src0_sel:WORD_1
	v_cvt_f32_f16_e32 v71, v71
	v_and_b32_e32 v70, 0xffffff80, v70
	v_sub_u32_e32 v70, v70, v20
	v_not_b32_e32 v84, v83
	v_or_b32_e32 v85, 0x80000000, v83
	v_cmp_gt_i32_e32 vcc, 0, v83
	v_add_u32_e32 v82, 0x7e, v82
	v_add_u32_e32 v70, 0x7f, v70
	v_cndmask_b32_e32 v83, v85, v84, vcc
	v_not_b32_e32 v84, v71
	v_or_b32_e32 v85, 0x80000000, v71
	v_cmp_gt_i32_e32 vcc, 0, v71
	v_and_b32_e32 v83, 0xffffff80, v83
	v_sub_u32_e32 v83, v83, v21
	v_cndmask_b32_e32 v71, v85, v84, vcc
	v_cvt_f32_f16_sdwa v84, v72 dst_sel:DWORD dst_unused:UNUSED_PAD src0_sel:WORD_1
	v_cvt_f32_f16_e32 v72, v72
	v_and_b32_e32 v71, 0xffffff80, v71
	v_sub_u32_e32 v71, v71, v21
	v_not_b32_e32 v85, v84
	v_or_b32_e32 v86, 0x80000000, v84
	v_cmp_gt_i32_e32 vcc, 0, v84
	v_add_u32_e32 v83, 0x7e, v83
	v_add_u32_e32 v71, 0x7f, v71
	v_cndmask_b32_e32 v84, v86, v85, vcc
	v_not_b32_e32 v85, v72
	v_or_b32_e32 v86, 0x80000000, v72
	v_cmp_gt_i32_e32 vcc, 0, v72
	v_and_b32_e32 v84, 0xffffff80, v84
	v_sub_u32_e32 v84, v84, v22
	v_cndmask_b32_e32 v72, v86, v85, vcc
	v_cvt_f32_f16_sdwa v85, v73 dst_sel:DWORD dst_unused:UNUSED_PAD src0_sel:WORD_1
	v_cvt_f32_f16_e32 v73, v73
	v_and_b32_e32 v72, 0xffffff80, v72
	v_sub_u32_e32 v72, v72, v22
	v_not_b32_e32 v86, v85
	v_or_b32_e32 v87, 0x80000000, v85
	v_cmp_gt_i32_e32 vcc, 0, v85
	v_add_u32_e32 v84, 0x7e, v84
	v_add_u32_e32 v72, 0x7f, v72
	v_cndmask_b32_e32 v85, v87, v86, vcc
	v_not_b32_e32 v86, v73
	v_or_b32_e32 v87, 0x80000000, v73
	v_cmp_gt_i32_e32 vcc, 0, v73
	v_and_b32_e32 v85, 0xffffff80, v85
	v_sub_u32_e32 v85, v85, v23
	v_cndmask_b32_e32 v73, v87, v86, vcc
	v_cvt_f32_f16_sdwa v86, v0 dst_sel:DWORD dst_unused:UNUSED_PAD src0_sel:WORD_1
	v_cvt_f32_f16_e32 v0, v0
	v_and_b32_e32 v73, 0xffffff80, v73
	v_sub_u32_e32 v73, v73, v23
	v_not_b32_e32 v87, v86
	v_or_b32_e32 v88, 0x80000000, v86
	v_cmp_gt_i32_e32 vcc, 0, v86
	v_add_u32_e32 v85, 0x7e, v85
	v_add_u32_e32 v73, 0x7f, v73
	v_cndmask_b32_e32 v86, v88, v87, vcc
	v_not_b32_e32 v87, v0
	v_or_b32_e32 v88, 0x80000000, v0
	v_cmp_gt_i32_e32 vcc, 0, v0
	v_and_b32_e32 v86, 0xffffff80, v86
	v_sub_u32_e32 v86, v86, v24
	v_cndmask_b32_e32 v0, v88, v87, vcc
	v_cvt_f32_f16_sdwa v87, v1 dst_sel:DWORD dst_unused:UNUSED_PAD src0_sel:WORD_1
	v_cvt_f32_f16_e32 v1, v1
	v_and_b32_e32 v0, 0xffffff80, v0
	v_sub_u32_e32 v0, v0, v24
	v_not_b32_e32 v88, v87
	v_or_b32_e32 v89, 0x80000000, v87
	v_cmp_gt_i32_e32 vcc, 0, v87
	v_add_u32_e32 v86, 0x7e, v86
	v_add_u32_e32 v0, 0x7f, v0
	v_cndmask_b32_e32 v87, v89, v88, vcc
	v_not_b32_e32 v88, v1
	v_or_b32_e32 v89, 0x80000000, v1
	v_cmp_gt_i32_e32 vcc, 0, v1
	v_and_b32_e32 v87, 0xffffff80, v87
	v_sub_u32_e32 v87, v87, v25
	v_cndmask_b32_e32 v1, v89, v88, vcc
	v_cvt_f32_f16_sdwa v88, v2 dst_sel:DWORD dst_unused:UNUSED_PAD src0_sel:WORD_1
	v_cvt_f32_f16_e32 v2, v2
	v_and_b32_e32 v1, 0xffffff80, v1
	v_sub_u32_e32 v1, v1, v25
	v_not_b32_e32 v89, v88
	v_or_b32_e32 v90, 0x80000000, v88
	v_cmp_gt_i32_e32 vcc, 0, v88
	v_add_u32_e32 v87, 0x7e, v87
	v_add_u32_e32 v1, 0x7f, v1
	v_cndmask_b32_e32 v88, v90, v89, vcc
	v_not_b32_e32 v89, v2
	v_or_b32_e32 v90, 0x80000000, v2
	v_cmp_gt_i32_e32 vcc, 0, v2
	v_and_b32_e32 v88, 0xffffff80, v88
	v_sub_u32_e32 v88, v88, v26
	v_cndmask_b32_e32 v2, v90, v89, vcc
	v_cvt_f32_f16_sdwa v89, v3 dst_sel:DWORD dst_unused:UNUSED_PAD src0_sel:WORD_1
	v_cvt_f32_f16_e32 v3, v3
	v_and_b32_e32 v2, 0xffffff80, v2
	v_sub_u32_e32 v2, v2, v26
	v_not_b32_e32 v90, v89
	v_or_b32_e32 v91, 0x80000000, v89
	v_cmp_gt_i32_e32 vcc, 0, v89
	v_add_u32_e32 v88, 0x7e, v88
	v_add_u32_e32 v2, 0x7f, v2
	v_cndmask_b32_e32 v89, v91, v90, vcc
	v_not_b32_e32 v90, v3
	v_or_b32_e32 v91, 0x80000000, v3
	v_cmp_gt_i32_e32 vcc, 0, v3
	v_and_b32_e32 v89, 0xffffff80, v89
	v_sub_u32_e32 v89, v89, v28
	v_cndmask_b32_e32 v3, v91, v90, vcc
	v_and_b32_e32 v3, 0xffffff80, v3
	v_sub_u32_e32 v3, v3, v28
	v_add_u32_e32 v89, 0x7e, v89
	v_add_u32_e32 v3, 0x7f, v3
	v_max_u32_e32 v90, v66, v74
	v_min_u32_e32 v66, v66, v74
	v_max_u32_e32 v74, v75, v67
	v_min_u32_e32 v67, v75, v67
	v_max_u32_e32 v75, v68, v76
	v_min_u32_e32 v68, v68, v76
	v_max_u32_e32 v76, v77, v69
	v_min_u32_e32 v69, v77, v69
	v_max_u32_e32 v77, v62, v78
	v_min_u32_e32 v62, v62, v78
	v_max_u32_e32 v78, v79, v63
	v_min_u32_e32 v63, v79, v63
	v_max_u32_e32 v79, v64, v80
	v_min_u32_e32 v64, v64, v80
	v_max_u32_e32 v80, v81, v65
	v_min_u32_e32 v65, v81, v65
	v_max_u32_e32 v98, v70, v82
	v_min_u32_e32 v70, v70, v82
	v_max_u32_e32 v82, v83, v71
	v_min_u32_e32 v71, v83, v71
	v_max_u32_e32 v83, v72, v84
	v_min_u32_e32 v72, v72, v84
	v_max_u32_e32 v84, v85, v73
	v_min_u32_e32 v73, v85, v73
	v_max_u32_e32 v85, v0, v86
	v_min_u32_e32 v0, v0, v86
	v_max_u32_e32 v86, v87, v1
	v_min_u32_e32 v1, v87, v1
	v_max_u32_e32 v87, v2, v88
	v_min_u32_e32 v2, v2, v88
	v_max_u32_e32 v88, v89, v3
	v_min_u32_e32 v3, v89, v3
	v_max_u32_e32 v81, v90, v67
	v_min_u32_e32 v67, v90, v67
	v_max_u32_e32 v90, v66, v74
	v_min_u32_e32 v66, v66, v74
	v_max_u32_e32 v74, v69, v75
	v_min_u32_e32 v69, v69, v75
	v_max_u32_e32 v75, v76, v68
	v_min_u32_e32 v68, v76, v68
; #define CE_DESC(a, b) do { const unsigned _mx = (a) > (b) ? (a) : (b), _mn = (a) > (b) ? (b) : (a); (a) = _mx; (b) = _mn; } while (0)
; __device__ __forceinline__ void sort16_desc(unsigned (&k)[16]) {
; #pragma unroll
;     for (int size = 2; size <= 16; size <<= 1)
; #pragma unroll
;         for (int stride = size >> 1; stride > 0; stride >>= 1)
; #pragma unroll
;             for (int i = 0; i < 16; ++i) { const int j = i ^ stride;
;                 if (j > i) { if ((i & size) == 0) CE_DESC(k[i], k[j]); else CE_DESC(k[j], k[i]); } }
; }
	v_max_u32_e32 v76, v77, v63
	v_min_u32_e32 v63, v77, v63
	v_max_u32_e32 v77, v62, v78
	v_min_u32_e32 v62, v62, v78
	v_max_u32_e32 v78, v65, v79
	v_min_u32_e32 v65, v65, v79
	v_max_u32_e32 v79, v80, v64
	v_min_u32_e32 v64, v80, v64
	v_max_u32_e32 v89, v98, v71
	v_min_u32_e32 v71, v98, v71
	v_max_u32_e32 v98, v70, v82
	v_min_u32_e32 v70, v70, v82
	v_max_u32_e32 v82, v73, v83
	v_min_u32_e32 v73, v73, v83
	v_max_u32_e32 v83, v84, v72
	v_min_u32_e32 v72, v84, v72
	v_max_u32_e32 v84, v85, v1
	v_min_u32_e32 v1, v85, v1
	v_max_u32_e32 v85, v0, v86
	v_min_u32_e32 v0, v0, v86
	v_max_u32_e32 v86, v3, v87
	v_min_u32_e32 v3, v3, v87
	v_max_u32_e32 v87, v88, v2
	v_min_u32_e32 v2, v88, v2
	v_max_u32_e32 v80, v81, v90
	v_min_u32_e32 v81, v81, v90
	v_max_u32_e32 v90, v67, v66
	v_min_u32_e32 v66, v67, v66
	v_max_u32_e32 v67, v68, v69
	v_min_u32_e32 v68, v68, v69
	v_max_u32_e32 v69, v75, v74
	v_min_u32_e32 v74, v75, v74
	v_max_u32_e32 v75, v76, v77
	v_min_u32_e32 v76, v76, v77
	v_max_u32_e32 v77, v63, v62
	v_min_u32_e32 v62, v63, v62
	v_max_u32_e32 v63, v64, v65
	v_min_u32_e32 v64, v64, v65
	v_max_u32_e32 v65, v79, v78
	v_min_u32_e32 v78, v79, v78
	v_max_u32_e32 v88, v89, v98
	v_min_u32_e32 v89, v89, v98
	v_max_u32_e32 v98, v71, v70
	v_min_u32_e32 v70, v71, v70
	v_max_u32_e32 v71, v72, v73
	v_min_u32_e32 v72, v72, v73
	v_max_u32_e32 v73, v83, v82
	v_min_u32_e32 v82, v83, v82
	v_max_u32_e32 v83, v84, v85
	v_min_u32_e32 v84, v84, v85
	v_max_u32_e32 v85, v1, v0
	v_min_u32_e32 v0, v1, v0
	v_max_u32_e32 v1, v2, v3
	v_min_u32_e32 v2, v2, v3
	v_max_u32_e32 v3, v87, v86
	v_min_u32_e32 v86, v87, v86
	v_max_u32_e32 v79, v80, v68
	v_min_u32_e32 v68, v80, v68
	v_max_u32_e32 v80, v81, v67
	v_min_u32_e32 v67, v81, v67
	v_max_u32_e32 v81, v90, v74
	v_min_u32_e32 v74, v90, v74
	v_max_u32_e32 v90, v66, v69
	v_min_u32_e32 v66, v66, v69
	v_max_u32_e32 v69, v64, v75
	v_min_u32_e32 v64, v64, v75
	v_max_u32_e32 v75, v63, v76
	v_min_u32_e32 v63, v63, v76
	v_max_u32_e32 v76, v78, v77
	v_min_u32_e32 v77, v78, v77
	v_max_u32_e32 v78, v65, v62
	v_min_u32_e32 v62, v65, v62
	v_max_u32_e32 v87, v88, v72
	v_min_u32_e32 v72, v88, v72
	v_max_u32_e32 v88, v89, v71
	v_min_u32_e32 v71, v89, v71
	v_max_u32_e32 v89, v98, v82
	v_min_u32_e32 v82, v98, v82
	v_max_u32_e32 v98, v70, v73
	v_min_u32_e32 v70, v70, v73
	v_max_u32_e32 v73, v2, v83
	v_min_u32_e32 v2, v2, v83
	v_max_u32_e32 v83, v1, v84
	v_min_u32_e32 v1, v1, v84
	v_max_u32_e32 v84, v86, v85
	v_min_u32_e32 v85, v86, v85
	v_max_u32_e32 v86, v3, v0
	v_min_u32_e32 v0, v3, v0
	v_max_u32_e32 v65, v79, v81
	v_min_u32_e32 v79, v79, v81
	v_max_u32_e32 v81, v80, v90
	v_min_u32_e32 v80, v80, v90
	v_max_u32_e32 v90, v68, v74
	v_min_u32_e32 v68, v68, v74
	v_max_u32_e32 v74, v67, v66
	v_min_u32_e32 v66, v67, v66
	v_max_u32_e32 v67, v77, v64
	v_min_u32_e32 v64, v77, v64
	v_max_u32_e32 v77, v62, v63
	v_min_u32_e32 v62, v62, v63
	v_max_u32_e32 v63, v76, v69
	v_min_u32_e32 v69, v76, v69
	v_max_u32_e32 v76, v78, v75
	v_min_u32_e32 v75, v78, v75
	v_max_u32_e32 v3, v87, v89
	v_min_u32_e32 v87, v87, v89
	v_max_u32_e32 v89, v88, v98
	v_min_u32_e32 v88, v88, v98
	v_max_u32_e32 v98, v72, v82
	v_min_u32_e32 v72, v72, v82
	v_max_u32_e32 v82, v71, v70
	v_min_u32_e32 v70, v71, v70
	v_max_u32_e32 v71, v85, v2
	v_min_u32_e32 v2, v85, v2
	v_max_u32_e32 v85, v0, v1
	v_min_u32_e32 v0, v0, v1
	v_max_u32_e32 v1, v84, v73
	v_min_u32_e32 v73, v84, v73
	v_max_u32_e32 v84, v86, v83
	v_min_u32_e32 v83, v86, v83
	v_max_u32_e32 v78, v65, v81
	v_min_u32_e32 v65, v65, v81
	v_max_u32_e32 v81, v79, v80
	v_min_u32_e32 v79, v79, v80
	v_max_u32_e32 v80, v90, v74
	v_min_u32_e32 v74, v90, v74
	v_max_u32_e32 v90, v68, v66
	v_min_u32_e32 v66, v68, v66
	v_max_u32_e32 v68, v62, v64
	v_min_u32_e32 v62, v62, v64
	v_max_u32_e32 v64, v77, v67
	v_min_u32_e32 v67, v77, v67
	v_max_u32_e32 v77, v75, v69
	v_min_u32_e32 v69, v75, v69
	v_max_u32_e32 v75, v76, v63
	v_min_u32_e32 v63, v76, v63
	v_max_u32_e32 v86, v3, v89
	v_min_u32_e32 v3, v3, v89
	v_max_u32_e32 v89, v87, v88
	v_min_u32_e32 v87, v87, v88
	v_max_u32_e32 v88, v98, v82
	v_min_u32_e32 v82, v98, v82
	v_max_u32_e32 v98, v72, v70
	v_min_u32_e32 v70, v72, v70
	v_max_u32_e32 v72, v0, v2
	v_min_u32_e32 v0, v0, v2
	v_max_u32_e32 v2, v85, v71
	v_min_u32_e32 v71, v85, v71
	v_max_u32_e32 v85, v83, v73
	v_min_u32_e32 v73, v83, v73
	v_max_u32_e32 v83, v84, v1
	v_min_u32_e32 v1, v84, v1
	v_max_u32_e32 v76, v78, v62
	v_min_u32_e32 v62, v78, v62
	v_max_u32_e32 v78, v65, v68
	v_min_u32_e32 v65, v65, v68
	v_max_u32_e32 v68, v81, v67
	v_min_u32_e32 v67, v81, v67
	v_max_u32_e32 v81, v79, v64
	v_min_u32_e32 v64, v79, v64
	v_max_u32_e32 v79, v80, v69
	v_min_u32_e32 v69, v80, v69
	v_max_u32_e32 v80, v74, v77
	v_min_u32_e32 v74, v74, v77
	v_max_u32_e32 v77, v90, v63
	v_min_u32_e32 v63, v90, v63
	v_max_u32_e32 v90, v66, v75
	v_min_u32_e32 v66, v66, v75
	v_max_u32_e32 v84, v86, v0
	v_min_u32_e32 v0, v86, v0
	v_max_u32_e32 v86, v3, v72
	v_min_u32_e32 v3, v3, v72
	v_max_u32_e32 v72, v89, v71
	v_min_u32_e32 v71, v89, v71
	v_max_u32_e32 v89, v87, v2
	v_min_u32_e32 v2, v87, v2
	v_max_u32_e32 v87, v88, v73
	v_min_u32_e32 v73, v88, v73
	v_max_u32_e32 v88, v82, v85
	v_min_u32_e32 v82, v82, v85
	v_max_u32_e32 v85, v98, v1
	v_min_u32_e32 v1, v98, v1
	v_max_u32_e32 v98, v70, v83
	v_min_u32_e32 v70, v70, v83
	v_max_u32_e32 v75, v76, v79
	v_min_u32_e32 v76, v76, v79
	v_max_u32_e32 v79, v78, v80
	v_min_u32_e32 v78, v78, v80
	v_max_u32_e32 v80, v68, v77
	v_min_u32_e32 v68, v68, v77
	v_max_u32_e32 v77, v81, v90
	v_min_u32_e32 v81, v81, v90
	v_max_u32_e32 v90, v62, v69
	v_min_u32_e32 v62, v62, v69
	v_max_u32_e32 v69, v65, v74
	v_min_u32_e32 v65, v65, v74
	v_max_u32_e32 v74, v67, v63
; #define CE_DESC(a, b) do { const unsigned _mx = (a) > (b) ? (a) : (b), _mn = (a) > (b) ? (b) : (a); (a) = _mx; (b) = _mn; } while (0)
; __device__ __forceinline__ void sort16_desc(unsigned (&k)[16]) {
; #pragma unroll
;     for (int size = 2; size <= 16; size <<= 1)
; #pragma unroll
;         for (int stride = size >> 1; stride > 0; stride >>= 1)
; #pragma unroll
;             for (int i = 0; i < 16; ++i) { const int j = i ^ stride;
;                 if (j > i) { if ((i & size) == 0) CE_DESC(k[i], k[j]); else CE_DESC(k[j], k[i]); } }
; }
; __device__ __forceinline__ void merge16(unsigned (&a)[16], const unsigned (&b)[16]) {
; #pragma unroll
;     for (int i = 0; i < 16; ++i) a[i] = a[i] > b[15 - i] ? a[i] : b[15 - i];
; #pragma unroll
;     for (int stride = 8; stride > 0; stride >>= 1)
; #pragma unroll
;         for (int i = 0; i < 16; ++i) { const int j = i ^ stride; if (j > i) CE_DESC(a[i], a[j]); }
; }
; __device__ __forceinline__ void peer_tile(const Args& A, LAS unsigned char* lds, int tile) {
;     ...
;                 sort16_desc(k0); sort16_desc(k1); merge16(k0, k1);
; #pragma unroll
;                 for (int msk = 16; msk <= 32; msk <<= 1) {
; #pragma unroll
;                     for (int i = 0; i < 16; ++i) k1[i] = (unsigned)__shfl_xor((int)k0[i], msk);
;                     merge16(k0, k1); }
	v_min_u32_e32 v63, v67, v63
	v_max_u32_e32 v67, v64, v66
	v_min_u32_e32 v64, v64, v66
	v_max_u32_e32 v83, v84, v87
	v_min_u32_e32 v84, v84, v87
	v_max_u32_e32 v87, v86, v88
	v_min_u32_e32 v86, v86, v88
	v_max_u32_e32 v88, v72, v85
	v_min_u32_e32 v72, v72, v85
	v_max_u32_e32 v85, v89, v98
	v_min_u32_e32 v89, v89, v98
	v_max_u32_e32 v98, v0, v73
	v_min_u32_e32 v0, v0, v73
	v_max_u32_e32 v73, v3, v82
	v_min_u32_e32 v3, v3, v82
	v_max_u32_e32 v82, v71, v1
	v_min_u32_e32 v1, v71, v1
	v_max_u32_e32 v71, v2, v70
	v_min_u32_e32 v2, v2, v70
	v_max_u32_e32 v66, v75, v80
	v_min_u32_e32 v75, v75, v80
	v_max_u32_e32 v80, v79, v77
	v_min_u32_e32 v77, v79, v77
	v_max_u32_e32 v79, v76, v68
	v_min_u32_e32 v68, v76, v68
	v_max_u32_e32 v76, v78, v81
	v_min_u32_e32 v78, v78, v81
	v_max_u32_e32 v81, v90, v74
	v_min_u32_e32 v74, v90, v74
	v_max_u32_e32 v90, v69, v67
	v_min_u32_e32 v67, v69, v67
	v_max_u32_e32 v69, v62, v63
	v_min_u32_e32 v62, v62, v63
	v_max_u32_e32 v63, v65, v64
	v_min_u32_e32 v64, v65, v64
	v_max_u32_e32 v70, v83, v88
	v_min_u32_e32 v83, v83, v88
	v_max_u32_e32 v88, v87, v85
	v_min_u32_e32 v85, v87, v85
	v_max_u32_e32 v87, v84, v72
	v_min_u32_e32 v72, v84, v72
	v_max_u32_e32 v84, v86, v89
	v_min_u32_e32 v86, v86, v89
	v_max_u32_e32 v89, v98, v82
	v_min_u32_e32 v82, v98, v82
	v_max_u32_e32 v98, v73, v71
	v_min_u32_e32 v71, v73, v71
	v_max_u32_e32 v73, v0, v1
	v_min_u32_e32 v0, v0, v1
	v_max_u32_e32 v1, v3, v2
	v_min_u32_e32 v2, v3, v2
	v_min_u32_e32 v65, v66, v80
	v_min_u32_e32 v91, v75, v77
	v_min_u32_e32 v92, v79, v76
	v_min_u32_e32 v93, v68, v78
	v_min_u32_e32 v94, v81, v90
	v_min_u32_e32 v95, v74, v67
	v_min_u32_e32 v96, v69, v63
	v_min_u32_e32 v97, v62, v64
	v_min_u32_e32 v3, v70, v88
	v_min_u32_e32 v99, v83, v85
	v_min_u32_e32 v100, v87, v84
	v_min_u32_e32 v101, v72, v86
	v_min_u32_e32 v102, v89, v98
	v_min_u32_e32 v103, v82, v71
	v_min_u32_e32 v104, v73, v1
	v_min_u32_e32 v105, v0, v2
	v_max3_u32 v66, v66, v80, v105
	v_max3_u32 v0, v65, v0, v2
	v_max3_u32 v2, v75, v77, v104
	v_max3_u32 v1, v91, v73, v1
	v_max3_u32 v65, v79, v76, v103
	v_max3_u32 v71, v92, v82, v71
	v_max3_u32 v68, v68, v78, v102
	v_max3_u32 v73, v93, v89, v98
	v_max3_u32 v75, v81, v90, v101
	v_max3_u32 v72, v94, v72, v86
	v_max3_u32 v67, v74, v67, v100
	v_max3_u32 v74, v95, v87, v84
	v_max3_u32 v63, v69, v63, v99
	v_max3_u32 v69, v96, v83, v85
	v_max3_u32 v3, v62, v64, v3
	v_max3_u32 v62, v97, v70, v88
	v_max_u32_e32 v64, v66, v75
	v_min_u32_e32 v66, v66, v75
	v_max_u32_e32 v70, v0, v72
	v_min_u32_e32 v0, v0, v72
	v_max_u32_e32 v72, v2, v67
	v_min_u32_e32 v2, v2, v67
	v_max_u32_e32 v67, v1, v74
	v_min_u32_e32 v1, v1, v74
	v_max_u32_e32 v74, v65, v63
	v_min_u32_e32 v63, v65, v63
	v_max_u32_e32 v65, v71, v69
	v_min_u32_e32 v69, v71, v69
	v_max_u32_e32 v71, v68, v3
	v_min_u32_e32 v3, v68, v3
	v_max_u32_e32 v68, v73, v62
	v_min_u32_e32 v62, v73, v62
	v_max_u32_e32 v73, v64, v74
	v_min_u32_e32 v64, v64, v74
	v_max_u32_e32 v74, v70, v65
	v_min_u32_e32 v65, v70, v65
	v_max_u32_e32 v70, v72, v71
	v_min_u32_e32 v71, v72, v71
	v_max_u32_e32 v72, v67, v68
	v_min_u32_e32 v67, v67, v68
	v_max_u32_e32 v68, v66, v63
	v_min_u32_e32 v63, v66, v63
	v_max_u32_e32 v66, v0, v69
	v_min_u32_e32 v0, v0, v69
	v_max_u32_e32 v69, v2, v3
	v_min_u32_e32 v2, v2, v3
	v_max_u32_e32 v3, v1, v62
	v_min_u32_e32 v1, v1, v62
	v_max_u32_e32 v62, v73, v70
	v_min_u32_e32 v70, v73, v70
	v_max_u32_e32 v73, v74, v72
	v_min_u32_e32 v72, v74, v72
	v_max_u32_e32 v74, v64, v71
	v_min_u32_e32 v64, v64, v71
	v_max_u32_e32 v71, v65, v67
	v_min_u32_e32 v65, v65, v67
	v_max_u32_e32 v67, v68, v69
	v_min_u32_e32 v68, v68, v69
	v_max_u32_e32 v69, v66, v3
	v_min_u32_e32 v3, v66, v3
	v_max_u32_e32 v66, v63, v2
	v_min_u32_e32 v2, v63, v2
	v_max_u32_e32 v63, v0, v1
	v_min_u32_e32 v0, v0, v1
	v_max_u32_e32 v1, v62, v73
	v_min_u32_e32 v62, v62, v73
	v_max_u32_e32 v73, v70, v72
	v_min_u32_e32 v70, v70, v72
	v_max_u32_e32 v72, v74, v71
	v_min_u32_e32 v71, v74, v71
	v_max_u32_e32 v74, v64, v65
	v_min_u32_e32 v64, v64, v65
	v_max_u32_e32 v65, v67, v69
	v_min_u32_e32 v67, v67, v69
	v_max_u32_e32 v69, v68, v3
	v_min_u32_e32 v3, v68, v3
	v_max_u32_e32 v68, v66, v63
	v_min_u32_e32 v63, v66, v63
	v_max_u32_e32 v66, v2, v0
	v_min_u32_e32 v0, v2, v0
	ds_bpermute_b32 v2, v27, v1
	ds_bpermute_b32 v75, v27, v62
	ds_bpermute_b32 v76, v27, v73
	ds_bpermute_b32 v77, v27, v70
	ds_bpermute_b32 v78, v27, v72
	ds_bpermute_b32 v79, v27, v71
	ds_bpermute_b32 v80, v27, v74
	ds_bpermute_b32 v81, v27, v64
	ds_bpermute_b32 v82, v27, v65
	ds_bpermute_b32 v83, v27, v67
	ds_bpermute_b32 v84, v27, v69
	ds_bpermute_b32 v85, v27, v0
	ds_bpermute_b32 v86, v27, v66
	ds_bpermute_b32 v87, v27, v63
	ds_bpermute_b32 v88, v27, v68
	ds_bpermute_b32 v89, v27, v3
	s_waitcnt lgkmcnt(4)
	v_max_u32_e32 v1, v1, v85
	s_waitcnt lgkmcnt(3)
	v_max_u32_e32 v62, v62, v86
	s_waitcnt lgkmcnt(2)
	v_max_u32_e32 v73, v73, v87
	s_waitcnt lgkmcnt(1)
	v_max_u32_e32 v70, v70, v88
	s_waitcnt lgkmcnt(0)
; __device__ __forceinline__ void peer_tile(const Args& A, LAS unsigned char* lds, int tile) {
;     ...
;                 { const bf16_t* sp = QRY + m * 2048 + hp * 128 + 32 * g;
;                   const u32x4 s0 = *(const u32x4*)sp, s1 = *(const u32x4*)(sp + 8), s2 = *(const u32x4*)(sp + 16), s3 = *(const u32x4*)(sp + 24);
;     ...
;                 for (int msk = 16; msk <= 32; msk <<= 1) {
; #pragma unroll
;                     for (int i = 0; i < 16; ++i) k1[i] = (unsigned)__shfl_xor((int)k0[i], msk);
;                     merge16(k0, k1); }
; #pragma unroll
;                 for (int i = 0; i < 16; ++i) LA[hh][p][i] = k0[i];
	v_max_u32_e32 v72, v72, v89
	v_max_u32_e32 v71, v71, v84
	v_max_u32_e32 v74, v74, v83
	v_max_u32_e32 v64, v64, v82
	v_max_u32_e32 v65, v65, v81
	v_max_u32_e32 v67, v67, v80
	v_max_u32_e32 v69, v69, v79
	v_max_u32_e32 v3, v3, v78
	v_max_u32_e32 v68, v68, v77
	v_max_u32_e32 v63, v63, v76
	v_max_u32_e32 v66, v66, v75
	v_max_u32_e32 v0, v0, v2
	v_max_u32_e32 v2, v1, v65
	v_min_u32_e32 v1, v1, v65
	v_max_u32_e32 v65, v62, v67
	v_min_u32_e32 v62, v62, v67
	v_max_u32_e32 v67, v73, v69
	v_min_u32_e32 v69, v73, v69
	v_max_u32_e32 v73, v70, v3
	v_min_u32_e32 v3, v70, v3
	v_max_u32_e32 v70, v72, v68
	v_min_u32_e32 v68, v72, v68
	v_max_u32_e32 v72, v71, v63
	v_min_u32_e32 v63, v71, v63
	v_max_u32_e32 v71, v74, v66
	v_min_u32_e32 v66, v74, v66
	v_max_u32_e32 v74, v64, v0
	v_min_u32_e32 v0, v64, v0
	v_max_u32_e32 v64, v2, v70
	v_min_u32_e32 v2, v2, v70
	v_max_u32_e32 v70, v65, v72
	v_min_u32_e32 v65, v65, v72
	v_max_u32_e32 v72, v67, v71
	v_min_u32_e32 v67, v67, v71
	v_max_u32_e32 v71, v73, v74
	v_min_u32_e32 v73, v73, v74
	v_max_u32_e32 v74, v1, v68
	v_min_u32_e32 v1, v1, v68
	v_max_u32_e32 v68, v62, v63
	v_min_u32_e32 v62, v62, v63
	v_max_u32_e32 v63, v69, v66
	v_min_u32_e32 v66, v69, v66
	v_max_u32_e32 v69, v3, v0
	v_min_u32_e32 v0, v3, v0
	v_max_u32_e32 v3, v64, v72
	v_min_u32_e32 v64, v64, v72
	v_max_u32_e32 v72, v70, v71
	v_min_u32_e32 v70, v70, v71
	v_max_u32_e32 v71, v2, v67
	v_min_u32_e32 v2, v2, v67
	v_max_u32_e32 v67, v65, v73
	v_min_u32_e32 v65, v65, v73
	v_max_u32_e32 v73, v74, v63
	v_min_u32_e32 v63, v74, v63
	v_max_u32_e32 v74, v68, v69
	v_min_u32_e32 v68, v68, v69
	v_max_u32_e32 v69, v1, v66
	v_min_u32_e32 v1, v1, v66
	v_max_u32_e32 v66, v62, v0
	v_min_u32_e32 v0, v62, v0
	v_max_u32_e32 v62, v3, v72
	v_min_u32_e32 v3, v3, v72
	v_max_u32_e32 v72, v64, v70
	v_min_u32_e32 v64, v64, v70
	v_max_u32_e32 v70, v71, v67
	v_min_u32_e32 v67, v71, v67
	v_max_u32_e32 v71, v2, v65
	v_min_u32_e32 v2, v2, v65
	v_max_u32_e32 v65, v73, v74
	v_min_u32_e32 v73, v73, v74
	v_max_u32_e32 v74, v63, v68
	v_min_u32_e32 v63, v63, v68
	v_max_u32_e32 v68, v69, v66
	v_min_u32_e32 v66, v69, v66
	v_max_u32_e32 v69, v1, v0
	v_min_u32_e32 v0, v1, v0
	ds_bpermute_b32 v78, v29, v0
	ds_bpermute_b32 v1, v29, v62
	ds_bpermute_b32 v75, v29, v3
	ds_bpermute_b32 v76, v29, v72
	ds_bpermute_b32 v77, v29, v64
	s_waitcnt lgkmcnt(4)
	v_max_u32_e32 v62, v62, v78
	global_load_dwordx4 v[78:81], v[4:5], off offset:784
	global_load_dwordx4 v[82:85], v[4:5], off offset:768
	ds_bpermute_b32 v86, v29, v70
	ds_bpermute_b32 v87, v29, v67
	ds_bpermute_b32 v88, v29, v71
	ds_bpermute_b32 v89, v29, v2
	ds_bpermute_b32 v90, v29, v65
	ds_bpermute_b32 v91, v29, v73
	ds_bpermute_b32 v92, v29, v74
	ds_bpermute_b32 v93, v29, v63
	ds_bpermute_b32 v94, v29, v68
	ds_bpermute_b32 v95, v29, v69
	ds_bpermute_b32 v96, v29, v66
	s_waitcnt lgkmcnt(4)
	v_max_u32_e32 v67, v67, v92
	s_waitcnt lgkmcnt(3)
	v_max_u32_e32 v70, v70, v93
	s_waitcnt lgkmcnt(2)
	v_max_u32_e32 v64, v64, v94
	s_waitcnt lgkmcnt(1)
	v_max_u32_e32 v3, v3, v95
	s_waitcnt lgkmcnt(0)
	v_max_u32_e32 v72, v72, v96
	v_max_u32_e32 v71, v71, v91
	v_max_u32_e32 v2, v2, v90
	v_max_u32_e32 v65, v65, v89
	v_max_u32_e32 v73, v73, v88
	v_max_u32_e32 v74, v74, v87
	v_max_u32_e32 v63, v63, v86
	v_max_u32_e32 v68, v68, v77
	v_max_u32_e32 v66, v66, v76
	v_max_u32_e32 v69, v69, v75
	v_max_u32_e32 v0, v0, v1
	v_max_u32_e32 v1, v62, v65
	v_min_u32_e32 v62, v62, v65
	v_max_u32_e32 v65, v3, v73
	v_min_u32_e32 v3, v3, v73
	v_max_u32_e32 v73, v72, v74
	v_min_u32_e32 v72, v72, v74
	v_max_u32_e32 v74, v64, v63
	v_min_u32_e32 v63, v64, v63
	v_max_u32_e32 v64, v70, v68
	v_min_u32_e32 v68, v70, v68
	v_max_u32_e32 v70, v67, v66
	v_min_u32_e32 v66, v67, v66
	v_max_u32_e32 v67, v71, v69
	v_min_u32_e32 v69, v71, v69
	v_max_u32_e32 v71, v2, v0
	v_min_u32_e32 v0, v2, v0
	v_max_u32_e32 v2, v1, v64
	v_min_u32_e32 v1, v1, v64
	v_max_u32_e32 v64, v65, v70
	v_min_u32_e32 v65, v65, v70
	v_max_u32_e32 v70, v73, v67
	v_min_u32_e32 v67, v73, v67
	v_max_u32_e32 v73, v74, v71
	v_min_u32_e32 v71, v74, v71
	v_max_u32_e32 v74, v62, v68
	v_min_u32_e32 v62, v62, v68
	v_max_u32_e32 v68, v3, v66
	v_min_u32_e32 v3, v3, v66
	v_max_u32_e32 v66, v72, v69
	v_min_u32_e32 v69, v72, v69
	v_max_u32_e32 v72, v63, v0
	v_min_u32_e32 v0, v63, v0
	v_max_u32_e32 v63, v2, v70
	v_min_u32_e32 v2, v2, v70
	v_max_u32_e32 v70, v64, v73
	v_min_u32_e32 v64, v64, v73
	v_max_u32_e32 v86, v1, v67
	v_min_u32_e32 v1, v1, v67
	v_max_u32_e32 v67, v65, v71
	v_min_u32_e32 v65, v65, v71
	v_max_u32_e32 v87, v74, v66
	v_min_u32_e32 v66, v74, v66
	v_max_u32_e32 v88, v68, v72
	v_min_u32_e32 v89, v68, v72
	v_max_u32_e32 v90, v62, v69
	v_min_u32_e32 v62, v62, v69
	v_max_u32_e32 v91, v3, v0
	v_min_u32_e32 v0, v3, v0
	v_max_u32_e32 v77, v63, v70
	v_min_u32_e32 v76, v63, v70
	v_max_u32_e32 v75, v2, v64
	v_min_u32_e32 v74, v2, v64
	v_max_u32_e32 v73, v86, v67
	v_min_u32_e32 v72, v86, v67
	v_max_u32_e32 v71, v1, v65
	v_min_u32_e32 v70, v1, v65
	v_max_u32_e32 v69, v87, v88
	v_min_u32_e32 v68, v87, v88
	v_max_u32_e32 v67, v66, v89
	v_min_u32_e32 v66, v66, v89
	v_max_u32_e32 v63, v62, v0
	v_min_u32_e32 v62, v62, v0
	global_load_dwordx4 v[0:3], v[4:5], off offset:816
	global_load_dwordx4 v[86:89], v[4:5], off offset:800
	v_max_u32_e32 v65, v90, v91
	v_min_u32_e32 v64, v90, v91
	s_waitcnt vmcnt(2)
; __device__ __forceinline__ unsigned f2key(float f) { const unsigned u = __float_as_uint(f); return (u & 0x80000000u) ? ~u : (u | 0x80000000u); }
; __device__ __forceinline__ void peer_tile(const Args& A, LAS unsigned char* lds, int tile) {
;     ...
;                   for (int i = 0; i < 16; ++i) {
;                       const float lo = (float)__builtin_bit_cast(_Float16, (unsigned short)(sw[i] & 0xffffu)), hi = (float)__builtin_bit_cast(_Float16, (unsigned short)(sw[i] >> 16));
;                       const unsigned klo = (f2key(lo) & ~127u) | (unsigned)(127 - (32 * g + 2 * i)), khi = (f2key(hi) & ~127u) | (unsigned)(127 - (32 * g + 2 * i + 1));
;                       if (i < 8) { k0[2 * i] = klo; k0[2 * i + 1] = khi; } else { k1[2 * (i - 8)] = klo; k1[2 * (i - 8) + 1] = khi; } } }
;     ...
;                 for (int i = 0; i < 16; ++i) L2[p][i] = (g & 2) ? ((g & 1) ? LA[3][p][i] : LA[2][p][i]) : ((g & 1) ? LA[1][p][i] : LA[0][p][i]);
	v_cvt_f32_f16_sdwa v90, v82 dst_sel:DWORD dst_unused:UNUSED_PAD src0_sel:WORD_1
	v_cvt_f32_f16_e32 v82, v82
	v_cndmask_b32_e64 v38, v70, v38, s[0:1]
	v_cndmask_b32_e64 v37, v69, v37, s[0:1]
	v_not_b32_e32 v91, v90
	v_or_b32_e32 v92, 0x80000000, v90
	v_cmp_gt_i32_e32 vcc, 0, v90
	v_cndmask_b32_e64 v36, v68, v36, s[0:1]
	v_cndmask_b32_e64 v35, v67, v35, s[0:1]
	v_cndmask_b32_e32 v90, v92, v91, vcc
	v_not_b32_e32 v91, v82
	v_or_b32_e32 v92, 0x80000000, v82
	v_cmp_gt_i32_e32 vcc, 0, v82
	v_and_b32_e32 v90, 0xffffff80, v90
	v_sub_u32_e32 v90, v90, v15
	v_cndmask_b32_e32 v82, v92, v91, vcc
	v_cvt_f32_f16_sdwa v91, v83 dst_sel:DWORD dst_unused:UNUSED_PAD src0_sel:WORD_1
	v_cvt_f32_f16_e32 v83, v83
	v_and_b32_e32 v82, 0xffffff80, v82
	v_sub_u32_e32 v82, v82, v15
	v_not_b32_e32 v92, v91
	v_or_b32_e32 v93, 0x80000000, v91
	v_cmp_gt_i32_e32 vcc, 0, v91
	v_add_u32_e32 v90, 0x7e, v90
	v_add_u32_e32 v82, 0x7f, v82
	v_cndmask_b32_e32 v91, v93, v92, vcc
	v_not_b32_e32 v92, v83
	v_or_b32_e32 v93, 0x80000000, v83
	v_cmp_gt_i32_e32 vcc, 0, v83
	v_and_b32_e32 v91, 0xffffff80, v91
	v_sub_u32_e32 v91, v91, v14
	v_cndmask_b32_e32 v83, v93, v92, vcc
	v_cvt_f32_f16_sdwa v92, v84 dst_sel:DWORD dst_unused:UNUSED_PAD src0_sel:WORD_1
	v_cvt_f32_f16_e32 v84, v84
	v_and_b32_e32 v83, 0xffffff80, v83
	v_sub_u32_e32 v83, v83, v14
	v_not_b32_e32 v93, v92
	v_or_b32_e32 v94, 0x80000000, v92
	v_cmp_gt_i32_e32 vcc, 0, v92
	v_add_u32_e32 v91, 0x7e, v91
	v_add_u32_e32 v83, 0x7f, v83
	v_cndmask_b32_e32 v92, v94, v93, vcc
	v_not_b32_e32 v93, v84
	v_or_b32_e32 v94, 0x80000000, v84
	v_cmp_gt_i32_e32 vcc, 0, v84
	v_and_b32_e32 v92, 0xffffff80, v92
	v_sub_u32_e32 v92, v92, v12
	v_cndmask_b32_e32 v84, v94, v93, vcc
	v_cvt_f32_f16_sdwa v93, v85 dst_sel:DWORD dst_unused:UNUSED_PAD src0_sel:WORD_1
	v_cvt_f32_f16_e32 v85, v85
	v_and_b32_e32 v84, 0xffffff80, v84
	v_sub_u32_e32 v84, v84, v12
	v_not_b32_e32 v94, v93
	v_or_b32_e32 v95, 0x80000000, v93
	v_cmp_gt_i32_e32 vcc, 0, v93
	v_add_u32_e32 v92, 0x7e, v92
	v_add_u32_e32 v84, 0x7f, v84
	v_cndmask_b32_e32 v93, v95, v94, vcc
	v_not_b32_e32 v94, v85
	v_or_b32_e32 v95, 0x80000000, v85
	v_cmp_gt_i32_e32 vcc, 0, v85
	v_and_b32_e32 v93, 0xffffff80, v93
	v_sub_u32_e32 v93, v93, v10
	v_cndmask_b32_e32 v85, v95, v94, vcc
	v_cvt_f32_f16_sdwa v94, v78 dst_sel:DWORD dst_unused:UNUSED_PAD src0_sel:WORD_1
	v_cvt_f32_f16_e32 v78, v78
	v_and_b32_e32 v85, 0xffffff80, v85
	v_sub_u32_e32 v85, v85, v10
	v_not_b32_e32 v95, v94
	v_or_b32_e32 v96, 0x80000000, v94
	v_cmp_gt_i32_e32 vcc, 0, v94
	v_add_u32_e32 v93, 0x7e, v93
	v_add_u32_e32 v85, 0x7f, v85
	v_cndmask_b32_e32 v94, v96, v95, vcc
	v_not_b32_e32 v95, v78
	v_or_b32_e32 v96, 0x80000000, v78
	v_cmp_gt_i32_e32 vcc, 0, v78
	v_and_b32_e32 v94, 0xffffff80, v94
	v_sub_u32_e32 v94, v94, v8
	v_cndmask_b32_e32 v78, v96, v95, vcc
	v_cvt_f32_f16_sdwa v95, v79 dst_sel:DWORD dst_unused:UNUSED_PAD src0_sel:WORD_1
	v_cvt_f32_f16_e32 v79, v79
	v_and_b32_e32 v78, 0xffffff80, v78
	v_sub_u32_e32 v78, v78, v8
	v_not_b32_e32 v96, v95
	v_or_b32_e32 v97, 0x80000000, v95
	v_cmp_gt_i32_e32 vcc, 0, v95
	v_add_u32_e32 v94, 0x7e, v94
	v_add_u32_e32 v78, 0x7f, v78
	v_cndmask_b32_e32 v95, v97, v96, vcc
	v_not_b32_e32 v96, v79
	v_or_b32_e32 v97, 0x80000000, v79
	v_cmp_gt_i32_e32 vcc, 0, v79
	v_and_b32_e32 v95, 0xffffff80, v95
	v_sub_u32_e32 v95, v95, v16
	v_cndmask_b32_e32 v79, v97, v96, vcc
	v_cvt_f32_f16_sdwa v96, v80 dst_sel:DWORD dst_unused:UNUSED_PAD src0_sel:WORD_1
	v_cvt_f32_f16_e32 v80, v80
	v_and_b32_e32 v79, 0xffffff80, v79
	v_sub_u32_e32 v79, v79, v16
	v_not_b32_e32 v97, v96
	v_or_b32_e32 v98, 0x80000000, v96
	v_cmp_gt_i32_e32 vcc, 0, v96
	v_add_u32_e32 v95, 0x7e, v95
	v_add_u32_e32 v79, 0x7f, v79
	v_cndmask_b32_e32 v96, v98, v97, vcc
	v_not_b32_e32 v97, v80
	v_or_b32_e32 v98, 0x80000000, v80
	v_cmp_gt_i32_e32 vcc, 0, v80
	v_and_b32_e32 v96, 0xffffff80, v96
	v_sub_u32_e32 v96, v96, v17
	v_cndmask_b32_e32 v80, v98, v97, vcc
	v_cvt_f32_f16_sdwa v97, v81 dst_sel:DWORD dst_unused:UNUSED_PAD src0_sel:WORD_1
	v_cvt_f32_f16_e32 v81, v81
	v_and_b32_e32 v80, 0xffffff80, v80
	v_sub_u32_e32 v80, v80, v17
	v_not_b32_e32 v98, v97
	v_or_b32_e32 v99, 0x80000000, v97
	v_cmp_gt_i32_e32 vcc, 0, v97
	v_add_u32_e32 v96, 0x7e, v96
	v_add_u32_e32 v80, 0x7f, v80
	v_cndmask_b32_e32 v97, v99, v98, vcc
	v_not_b32_e32 v98, v81
	v_or_b32_e32 v99, 0x80000000, v81
	v_cmp_gt_i32_e32 vcc, 0, v81
	v_and_b32_e32 v97, 0xffffff80, v97
	v_sub_u32_e32 v97, v97, v18
	v_cndmask_b32_e32 v81, v99, v98, vcc
	s_waitcnt vmcnt(0)
; __device__ __forceinline__ unsigned f2key(float f) { const unsigned u = __float_as_uint(f); return (u & 0x80000000u) ? ~u : (u | 0x80000000u); }
; #define CE_DESC(a, b) do { const unsigned _mx = (a) > (b) ? (a) : (b), _mn = (a) > (b) ? (b) : (a); (a) = _mx; (b) = _mn; } while (0)
; __device__ __forceinline__ void sort16_desc(unsigned (&k)[16]) {
; #pragma unroll
;     for (int size = 2; size <= 16; size <<= 1)
; #pragma unroll
;         for (int stride = size >> 1; stride > 0; stride >>= 1)
; #pragma unroll
;             for (int i = 0; i < 16; ++i) { const int j = i ^ stride;
;                 if (j > i) { if ((i & size) == 0) CE_DESC(k[i], k[j]); else CE_DESC(k[j], k[i]); } }
; }
; __device__ __forceinline__ void peer_tile(const Args& A, LAS unsigned char* lds, int tile) {
;     ...
;                   for (int i = 0; i < 16; ++i) {
;                       const float lo = (float)__builtin_bit_cast(_Float16, (unsigned short)(sw[i] & 0xffffu)), hi = (float)__builtin_bit_cast(_Float16, (unsigned short)(sw[i] >> 16));
;                       const unsigned klo = (f2key(lo) & ~127u) | (unsigned)(127 - (32 * g + 2 * i)), khi = (f2key(hi) & ~127u) | (unsigned)(127 - (32 * g + 2 * i + 1));
;                       if (i < 8) { k0[2 * i] = klo; k0[2 * i + 1] = khi; } else { k1[2 * (i - 8)] = klo; k1[2 * (i - 8) + 1] = khi; } } }
;                 sort16_desc(k0); sort16_desc(k1); merge16(k0, k1);
	v_cvt_f32_f16_sdwa v98, v86 dst_sel:DWORD dst_unused:UNUSED_PAD src0_sel:WORD_1
	v_cvt_f32_f16_e32 v86, v86
	v_and_b32_e32 v81, 0xffffff80, v81
	v_sub_u32_e32 v81, v81, v18
	v_not_b32_e32 v99, v98
	v_or_b32_e32 v100, 0x80000000, v98
	v_cmp_gt_i32_e32 vcc, 0, v98
	v_add_u32_e32 v97, 0x7e, v97
	v_add_u32_e32 v81, 0x7f, v81
	v_cndmask_b32_e32 v98, v100, v99, vcc
	v_not_b32_e32 v99, v86
	v_or_b32_e32 v100, 0x80000000, v86
	v_cmp_gt_i32_e32 vcc, 0, v86
	v_and_b32_e32 v98, 0xffffff80, v98
	v_sub_u32_e32 v98, v98, v20
	v_cndmask_b32_e32 v86, v100, v99, vcc
	v_cvt_f32_f16_sdwa v99, v87 dst_sel:DWORD dst_unused:UNUSED_PAD src0_sel:WORD_1
	v_cvt_f32_f16_e32 v87, v87
	v_and_b32_e32 v86, 0xffffff80, v86
	v_sub_u32_e32 v86, v86, v20
	v_not_b32_e32 v100, v99
	v_or_b32_e32 v101, 0x80000000, v99
	v_cmp_gt_i32_e32 vcc, 0, v99
	v_add_u32_e32 v98, 0x7e, v98
	v_add_u32_e32 v86, 0x7f, v86
	v_cndmask_b32_e32 v99, v101, v100, vcc
	v_not_b32_e32 v100, v87
	v_or_b32_e32 v101, 0x80000000, v87
	v_cmp_gt_i32_e32 vcc, 0, v87
	v_and_b32_e32 v99, 0xffffff80, v99
	v_sub_u32_e32 v99, v99, v21
	v_cndmask_b32_e32 v87, v101, v100, vcc
	v_cvt_f32_f16_sdwa v100, v88 dst_sel:DWORD dst_unused:UNUSED_PAD src0_sel:WORD_1
	v_cvt_f32_f16_e32 v88, v88
	v_and_b32_e32 v87, 0xffffff80, v87
	v_sub_u32_e32 v87, v87, v21
	v_not_b32_e32 v101, v100
	v_or_b32_e32 v102, 0x80000000, v100
	v_cmp_gt_i32_e32 vcc, 0, v100
	v_add_u32_e32 v99, 0x7e, v99
	v_add_u32_e32 v87, 0x7f, v87
	v_cndmask_b32_e32 v100, v102, v101, vcc
	v_not_b32_e32 v101, v88
	v_or_b32_e32 v102, 0x80000000, v88
	v_cmp_gt_i32_e32 vcc, 0, v88
	v_and_b32_e32 v100, 0xffffff80, v100
	v_sub_u32_e32 v100, v100, v22
	v_cndmask_b32_e32 v88, v102, v101, vcc
	v_cvt_f32_f16_sdwa v101, v89 dst_sel:DWORD dst_unused:UNUSED_PAD src0_sel:WORD_1
	v_cvt_f32_f16_e32 v89, v89
	v_and_b32_e32 v88, 0xffffff80, v88
	v_sub_u32_e32 v88, v88, v22
	v_not_b32_e32 v102, v101
	v_or_b32_e32 v103, 0x80000000, v101
	v_cmp_gt_i32_e32 vcc, 0, v101
	v_add_u32_e32 v100, 0x7e, v100
	v_add_u32_e32 v88, 0x7f, v88
	v_cndmask_b32_e32 v101, v103, v102, vcc
	v_not_b32_e32 v102, v89
	v_or_b32_e32 v103, 0x80000000, v89
	v_cmp_gt_i32_e32 vcc, 0, v89
	v_and_b32_e32 v101, 0xffffff80, v101
	v_sub_u32_e32 v101, v101, v23
	v_cndmask_b32_e32 v89, v103, v102, vcc
	v_cvt_f32_f16_sdwa v102, v0 dst_sel:DWORD dst_unused:UNUSED_PAD src0_sel:WORD_1
	v_cvt_f32_f16_e32 v0, v0
	v_and_b32_e32 v89, 0xffffff80, v89
	v_sub_u32_e32 v89, v89, v23
	v_not_b32_e32 v103, v102
	v_or_b32_e32 v104, 0x80000000, v102
	v_cmp_gt_i32_e32 vcc, 0, v102
	v_add_u32_e32 v101, 0x7e, v101
	v_add_u32_e32 v89, 0x7f, v89
	v_cndmask_b32_e32 v102, v104, v103, vcc
	v_not_b32_e32 v103, v0
	v_or_b32_e32 v104, 0x80000000, v0
	v_cmp_gt_i32_e32 vcc, 0, v0
	v_and_b32_e32 v102, 0xffffff80, v102
	v_sub_u32_e32 v102, v102, v24
	v_cndmask_b32_e32 v0, v104, v103, vcc
	v_cvt_f32_f16_sdwa v103, v1 dst_sel:DWORD dst_unused:UNUSED_PAD src0_sel:WORD_1
	v_cvt_f32_f16_e32 v1, v1
	v_and_b32_e32 v0, 0xffffff80, v0
	v_sub_u32_e32 v0, v0, v24
	v_not_b32_e32 v104, v103
	v_or_b32_e32 v105, 0x80000000, v103
	v_cmp_gt_i32_e32 vcc, 0, v103
	v_add_u32_e32 v102, 0x7e, v102
	v_add_u32_e32 v0, 0x7f, v0
	v_cndmask_b32_e32 v103, v105, v104, vcc
	v_not_b32_e32 v104, v1
	v_or_b32_e32 v105, 0x80000000, v1
	v_cmp_gt_i32_e32 vcc, 0, v1
	v_and_b32_e32 v103, 0xffffff80, v103
	v_sub_u32_e32 v103, v103, v25
	v_cndmask_b32_e32 v1, v105, v104, vcc
	v_cvt_f32_f16_sdwa v104, v2 dst_sel:DWORD dst_unused:UNUSED_PAD src0_sel:WORD_1
	v_cvt_f32_f16_e32 v2, v2
	v_and_b32_e32 v1, 0xffffff80, v1
	v_sub_u32_e32 v1, v1, v25
	v_not_b32_e32 v105, v104
	v_or_b32_e32 v106, 0x80000000, v104
	v_cmp_gt_i32_e32 vcc, 0, v104
	v_add_u32_e32 v103, 0x7e, v103
	v_add_u32_e32 v1, 0x7f, v1
	v_cndmask_b32_e32 v104, v106, v105, vcc
	v_not_b32_e32 v105, v2
	v_or_b32_e32 v106, 0x80000000, v2
	v_cmp_gt_i32_e32 vcc, 0, v2
	v_and_b32_e32 v104, 0xffffff80, v104
	v_sub_u32_e32 v104, v104, v26
	v_cndmask_b32_e32 v2, v106, v105, vcc
	v_cvt_f32_f16_sdwa v105, v3 dst_sel:DWORD dst_unused:UNUSED_PAD src0_sel:WORD_1
	v_cvt_f32_f16_e32 v3, v3
	v_and_b32_e32 v2, 0xffffff80, v2
	v_sub_u32_e32 v2, v2, v26
	v_not_b32_e32 v106, v105
	v_or_b32_e32 v107, 0x80000000, v105
	v_cmp_gt_i32_e32 vcc, 0, v105
	v_add_u32_e32 v104, 0x7e, v104
	v_add_u32_e32 v2, 0x7f, v2
	v_cndmask_b32_e32 v105, v107, v106, vcc
	v_not_b32_e32 v106, v3
	v_or_b32_e32 v107, 0x80000000, v3
	v_cmp_gt_i32_e32 vcc, 0, v3
	v_and_b32_e32 v105, 0xffffff80, v105
	v_sub_u32_e32 v105, v105, v28
	v_cndmask_b32_e32 v3, v107, v106, vcc
	v_and_b32_e32 v3, 0xffffff80, v3
	v_sub_u32_e32 v3, v3, v28
	v_add_u32_e32 v105, 0x7e, v105
	v_add_u32_e32 v3, 0x7f, v3
	v_max_u32_e32 v106, v82, v90
	v_min_u32_e32 v82, v82, v90
	v_max_u32_e32 v90, v91, v83
	v_min_u32_e32 v83, v91, v83
	v_max_u32_e32 v91, v84, v92
	v_min_u32_e32 v84, v84, v92
	v_max_u32_e32 v92, v93, v85
	v_min_u32_e32 v85, v93, v85
	v_max_u32_e32 v93, v78, v94
	v_min_u32_e32 v78, v78, v94
	v_max_u32_e32 v94, v95, v79
	v_min_u32_e32 v79, v95, v79
	v_max_u32_e32 v95, v80, v96
	v_min_u32_e32 v80, v80, v96
	v_max_u32_e32 v96, v97, v81
	v_min_u32_e32 v81, v97, v81
	v_max_u32_e32 v115, v86, v98
	v_min_u32_e32 v86, v86, v98
	v_max_u32_e32 v98, v99, v87
	v_min_u32_e32 v87, v99, v87
	v_max_u32_e32 v99, v88, v100
	v_min_u32_e32 v88, v88, v100
	v_max_u32_e32 v100, v101, v89
	v_min_u32_e32 v89, v101, v89
	v_max_u32_e32 v101, v0, v102
	v_min_u32_e32 v0, v0, v102
	v_max_u32_e32 v102, v103, v1
	v_min_u32_e32 v1, v103, v1
	v_max_u32_e32 v103, v2, v104
	v_min_u32_e32 v2, v2, v104
	v_max_u32_e32 v104, v105, v3
	v_min_u32_e32 v3, v105, v3
	v_max_u32_e32 v97, v106, v83
	v_min_u32_e32 v83, v106, v83
	v_max_u32_e32 v106, v82, v90
; #define CE_DESC(a, b) do { const unsigned _mx = (a) > (b) ? (a) : (b), _mn = (a) > (b) ? (b) : (a); (a) = _mx; (b) = _mn; } while (0)
; __device__ __forceinline__ void sort16_desc(unsigned (&k)[16]) {
; #pragma unroll
;     for (int size = 2; size <= 16; size <<= 1)
; #pragma unroll
;         for (int stride = size >> 1; stride > 0; stride >>= 1)
; #pragma unroll
;             for (int i = 0; i < 16; ++i) { const int j = i ^ stride;
;                 if (j > i) { if ((i & size) == 0) CE_DESC(k[i], k[j]); else CE_DESC(k[j], k[i]); } }
; }
	v_min_u32_e32 v82, v82, v90
	v_max_u32_e32 v90, v85, v91
	v_min_u32_e32 v85, v85, v91
	v_max_u32_e32 v91, v92, v84
	v_min_u32_e32 v84, v92, v84
	v_max_u32_e32 v92, v93, v79
	v_min_u32_e32 v79, v93, v79
	v_max_u32_e32 v93, v78, v94
	v_min_u32_e32 v78, v78, v94
	v_max_u32_e32 v94, v81, v95
	v_min_u32_e32 v81, v81, v95
	v_max_u32_e32 v95, v96, v80
	v_min_u32_e32 v80, v96, v80
	v_max_u32_e32 v105, v115, v87
	v_min_u32_e32 v87, v115, v87
	v_max_u32_e32 v115, v86, v98
	v_min_u32_e32 v86, v86, v98
	v_max_u32_e32 v98, v89, v99
	v_min_u32_e32 v89, v89, v99
	v_max_u32_e32 v99, v100, v88
	v_min_u32_e32 v88, v100, v88
	v_max_u32_e32 v100, v101, v1
	v_min_u32_e32 v1, v101, v1
	v_max_u32_e32 v101, v0, v102
	v_min_u32_e32 v0, v0, v102
	v_max_u32_e32 v102, v3, v103
	v_min_u32_e32 v3, v3, v103
	v_max_u32_e32 v103, v104, v2
	v_min_u32_e32 v2, v104, v2
	v_max_u32_e32 v96, v97, v106
	v_min_u32_e32 v97, v97, v106
	v_max_u32_e32 v106, v83, v82
	v_min_u32_e32 v82, v83, v82
	v_max_u32_e32 v83, v84, v85
	v_min_u32_e32 v84, v84, v85
	v_max_u32_e32 v85, v91, v90
	v_min_u32_e32 v90, v91, v90
	v_max_u32_e32 v91, v92, v93
	v_min_u32_e32 v92, v92, v93
	v_max_u32_e32 v93, v79, v78
	v_min_u32_e32 v78, v79, v78
	v_max_u32_e32 v79, v80, v81
	v_min_u32_e32 v80, v80, v81
	v_max_u32_e32 v81, v95, v94
	v_min_u32_e32 v94, v95, v94
	v_max_u32_e32 v104, v105, v115
	v_min_u32_e32 v105, v105, v115
	v_max_u32_e32 v115, v87, v86
	v_min_u32_e32 v86, v87, v86
	v_max_u32_e32 v87, v88, v89
	v_min_u32_e32 v88, v88, v89
	v_max_u32_e32 v89, v99, v98
	v_min_u32_e32 v98, v99, v98
	v_max_u32_e32 v99, v100, v101
	v_min_u32_e32 v100, v100, v101
	v_max_u32_e32 v101, v1, v0
	v_min_u32_e32 v0, v1, v0
	v_max_u32_e32 v1, v2, v3
	v_min_u32_e32 v2, v2, v3
	v_max_u32_e32 v3, v103, v102
	v_min_u32_e32 v102, v103, v102
	v_max_u32_e32 v95, v96, v84
	v_min_u32_e32 v84, v96, v84
	v_max_u32_e32 v96, v97, v83
	v_min_u32_e32 v83, v97, v83
	v_max_u32_e32 v97, v106, v90
	v_min_u32_e32 v90, v106, v90
	v_max_u32_e32 v106, v82, v85
	v_min_u32_e32 v82, v82, v85
	v_max_u32_e32 v85, v80, v91
	v_min_u32_e32 v80, v80, v91
	v_max_u32_e32 v91, v79, v92
	v_min_u32_e32 v79, v79, v92
	v_max_u32_e32 v92, v94, v93
	v_min_u32_e32 v93, v94, v93
	v_max_u32_e32 v94, v81, v78
	v_min_u32_e32 v78, v81, v78
	v_max_u32_e32 v103, v104, v88
	v_min_u32_e32 v88, v104, v88
	v_max_u32_e32 v104, v105, v87
	v_min_u32_e32 v87, v105, v87
	v_max_u32_e32 v105, v115, v98
	v_min_u32_e32 v98, v115, v98
	v_max_u32_e32 v115, v86, v89
	v_min_u32_e32 v86, v86, v89
	v_max_u32_e32 v89, v2, v99
	v_min_u32_e32 v2, v2, v99
	v_max_u32_e32 v99, v1, v100
	v_min_u32_e32 v1, v1, v100
	v_max_u32_e32 v100, v102, v101
	v_min_u32_e32 v101, v102, v101
	v_max_u32_e32 v102, v3, v0
	v_min_u32_e32 v0, v3, v0
	v_max_u32_e32 v81, v95, v97
	v_min_u32_e32 v95, v95, v97
	v_max_u32_e32 v97, v96, v106
	v_min_u32_e32 v96, v96, v106
	v_max_u32_e32 v106, v84, v90
	v_min_u32_e32 v84, v84, v90
	v_max_u32_e32 v90, v83, v82
	v_min_u32_e32 v82, v83, v82
	v_max_u32_e32 v83, v93, v80
	v_min_u32_e32 v80, v93, v80
	v_max_u32_e32 v93, v78, v79
	v_min_u32_e32 v78, v78, v79
	v_max_u32_e32 v79, v92, v85
	v_min_u32_e32 v85, v92, v85
	v_max_u32_e32 v92, v94, v91
	v_min_u32_e32 v91, v94, v91
	v_max_u32_e32 v3, v103, v105
	v_min_u32_e32 v103, v103, v105
	v_max_u32_e32 v105, v104, v115
	v_min_u32_e32 v104, v104, v115
	v_max_u32_e32 v115, v88, v98
	v_min_u32_e32 v88, v88, v98
	v_max_u32_e32 v98, v87, v86
	v_min_u32_e32 v86, v87, v86
	v_max_u32_e32 v87, v101, v2
	v_min_u32_e32 v2, v101, v2
	v_max_u32_e32 v101, v0, v1
	v_min_u32_e32 v0, v0, v1
	v_max_u32_e32 v1, v100, v89
	v_min_u32_e32 v89, v100, v89
	v_max_u32_e32 v100, v102, v99
	v_min_u32_e32 v99, v102, v99
	v_max_u32_e32 v94, v81, v97
	v_min_u32_e32 v81, v81, v97
	v_max_u32_e32 v97, v95, v96
	v_min_u32_e32 v95, v95, v96
	v_max_u32_e32 v96, v106, v90
	v_min_u32_e32 v90, v106, v90
	v_max_u32_e32 v106, v84, v82
	v_min_u32_e32 v82, v84, v82
	v_max_u32_e32 v84, v78, v80
	v_min_u32_e32 v78, v78, v80
	v_max_u32_e32 v80, v93, v83
	v_min_u32_e32 v83, v93, v83
	v_max_u32_e32 v93, v91, v85
	v_min_u32_e32 v85, v91, v85
	v_max_u32_e32 v91, v92, v79
	v_min_u32_e32 v79, v92, v79
	v_max_u32_e32 v102, v3, v105
	v_min_u32_e32 v3, v3, v105
	v_max_u32_e32 v105, v103, v104
	v_min_u32_e32 v103, v103, v104
	v_max_u32_e32 v104, v115, v98
	v_min_u32_e32 v98, v115, v98
	v_max_u32_e32 v115, v88, v86
	v_min_u32_e32 v86, v88, v86
	v_max_u32_e32 v88, v0, v2
	v_min_u32_e32 v0, v0, v2
	v_max_u32_e32 v2, v101, v87
	v_min_u32_e32 v87, v101, v87
	v_max_u32_e32 v101, v99, v89
	v_min_u32_e32 v89, v99, v89
	v_max_u32_e32 v99, v100, v1
	v_min_u32_e32 v1, v100, v1
	v_max_u32_e32 v92, v94, v78
	v_min_u32_e32 v78, v94, v78
	v_max_u32_e32 v94, v81, v84
	v_min_u32_e32 v81, v81, v84
	v_max_u32_e32 v84, v97, v83
	v_min_u32_e32 v83, v97, v83
	v_max_u32_e32 v97, v95, v80
	v_min_u32_e32 v80, v95, v80
	v_max_u32_e32 v95, v96, v85
	v_min_u32_e32 v85, v96, v85
	v_max_u32_e32 v96, v90, v93
	v_min_u32_e32 v90, v90, v93
	v_max_u32_e32 v93, v106, v79
	v_min_u32_e32 v79, v106, v79
	v_max_u32_e32 v106, v82, v91
	v_min_u32_e32 v82, v82, v91
	v_max_u32_e32 v100, v102, v0
	v_min_u32_e32 v0, v102, v0
	v_max_u32_e32 v102, v3, v88
	v_min_u32_e32 v3, v3, v88
	v_max_u32_e32 v88, v105, v87
	v_min_u32_e32 v87, v105, v87
	v_max_u32_e32 v105, v103, v2
	v_min_u32_e32 v2, v103, v2
	v_max_u32_e32 v103, v104, v89
	v_min_u32_e32 v89, v104, v89
	v_max_u32_e32 v104, v98, v101
	v_min_u32_e32 v98, v98, v101
	v_max_u32_e32 v101, v115, v1
	v_min_u32_e32 v1, v115, v1
	v_max_u32_e32 v115, v86, v99
	v_min_u32_e32 v86, v86, v99
	v_max_u32_e32 v91, v92, v95
	v_min_u32_e32 v92, v92, v95
	v_max_u32_e32 v95, v94, v96
; #define CE_DESC(a, b) do { const unsigned _mx = (a) > (b) ? (a) : (b), _mn = (a) > (b) ? (b) : (a); (a) = _mx; (b) = _mn; } while (0)
; __device__ __forceinline__ void sort16_desc(unsigned (&k)[16]) {
; #pragma unroll
;     for (int size = 2; size <= 16; size <<= 1)
; #pragma unroll
;         for (int stride = size >> 1; stride > 0; stride >>= 1)
; #pragma unroll
;             for (int i = 0; i < 16; ++i) { const int j = i ^ stride;
;                 if (j > i) { if ((i & size) == 0) CE_DESC(k[i], k[j]); else CE_DESC(k[j], k[i]); } }
; }
; __device__ __forceinline__ void merge16(unsigned (&a)[16], const unsigned (&b)[16]) {
; #pragma unroll
;     for (int i = 0; i < 16; ++i) a[i] = a[i] > b[15 - i] ? a[i] : b[15 - i];
; #pragma unroll
;     for (int stride = 8; stride > 0; stride >>= 1)
; #pragma unroll
;         for (int i = 0; i < 16; ++i) { const int j = i ^ stride; if (j > i) CE_DESC(a[i], a[j]); }
; }
; __device__ __forceinline__ void peer_tile(const Args& A, LAS unsigned char* lds, int tile) {
;     ...
;                 sort16_desc(k0); sort16_desc(k1); merge16(k0, k1);
; #pragma unroll
;                 for (int msk = 16; msk <= 32; msk <<= 1) {
; #pragma unroll
;                     for (int i = 0; i < 16; ++i) k1[i] = (unsigned)__shfl_xor((int)k0[i], msk);
;                     merge16(k0, k1); }
	v_min_u32_e32 v94, v94, v96
	v_max_u32_e32 v96, v84, v93
	v_min_u32_e32 v84, v84, v93
	v_max_u32_e32 v93, v97, v106
	v_min_u32_e32 v97, v97, v106
	v_max_u32_e32 v106, v78, v85
	v_min_u32_e32 v78, v78, v85
	v_max_u32_e32 v85, v81, v90
	v_min_u32_e32 v81, v81, v90
	v_max_u32_e32 v90, v83, v79
	v_min_u32_e32 v79, v83, v79
	v_max_u32_e32 v83, v80, v82
	v_min_u32_e32 v80, v80, v82
	v_max_u32_e32 v99, v100, v103
	v_min_u32_e32 v100, v100, v103
	v_max_u32_e32 v103, v102, v104
	v_min_u32_e32 v102, v102, v104
	v_max_u32_e32 v104, v88, v101
	v_min_u32_e32 v88, v88, v101
	v_max_u32_e32 v101, v105, v115
	v_min_u32_e32 v105, v105, v115
	v_max_u32_e32 v115, v0, v89
	v_min_u32_e32 v0, v0, v89
	v_max_u32_e32 v89, v3, v98
	v_min_u32_e32 v3, v3, v98
	v_max_u32_e32 v98, v87, v1
	v_min_u32_e32 v1, v87, v1
	v_max_u32_e32 v87, v2, v86
	v_min_u32_e32 v2, v2, v86
	v_max_u32_e32 v82, v91, v96
	v_min_u32_e32 v91, v91, v96
	v_max_u32_e32 v96, v95, v93
	v_min_u32_e32 v93, v95, v93
	v_max_u32_e32 v95, v92, v84
	v_min_u32_e32 v84, v92, v84
	v_max_u32_e32 v92, v94, v97
	v_min_u32_e32 v94, v94, v97
	v_max_u32_e32 v97, v106, v90
	v_min_u32_e32 v90, v106, v90
	v_max_u32_e32 v106, v85, v83
	v_min_u32_e32 v83, v85, v83
	v_max_u32_e32 v85, v78, v79
	v_min_u32_e32 v78, v78, v79
	v_max_u32_e32 v79, v81, v80
	v_min_u32_e32 v80, v81, v80
	v_max_u32_e32 v86, v99, v104
	v_min_u32_e32 v99, v99, v104
	v_max_u32_e32 v104, v103, v101
	v_min_u32_e32 v101, v103, v101
	v_max_u32_e32 v103, v100, v88
	v_min_u32_e32 v88, v100, v88
	v_max_u32_e32 v100, v102, v105
	v_min_u32_e32 v102, v102, v105
	v_max_u32_e32 v105, v115, v98
	v_min_u32_e32 v98, v115, v98
	v_max_u32_e32 v115, v89, v87
	v_min_u32_e32 v87, v89, v87
	v_max_u32_e32 v89, v0, v1
	v_min_u32_e32 v0, v0, v1
	v_max_u32_e32 v1, v3, v2
	v_min_u32_e32 v2, v3, v2
	v_min_u32_e32 v81, v82, v96
	v_min_u32_e32 v107, v91, v93
	v_min_u32_e32 v108, v95, v92
	v_min_u32_e32 v109, v84, v94
	v_min_u32_e32 v110, v97, v106
	v_min_u32_e32 v111, v90, v83
	v_min_u32_e32 v112, v85, v79
	v_min_u32_e32 v114, v78, v80
	v_min_u32_e32 v3, v86, v104
	v_min_u32_e32 v116, v99, v101
	v_min_u32_e32 v117, v103, v100
	v_min_u32_e32 v118, v88, v102
	v_min_u32_e32 v119, v105, v115
	v_min_u32_e32 v120, v98, v87
	v_min_u32_e32 v121, v89, v1
	v_min_u32_e32 v122, v0, v2
	v_max3_u32 v82, v82, v96, v122
	v_max3_u32 v0, v81, v0, v2
	v_max3_u32 v2, v91, v93, v121
	v_max3_u32 v1, v107, v89, v1
	v_max3_u32 v81, v95, v92, v120
	v_max3_u32 v87, v108, v98, v87
	v_max3_u32 v84, v84, v94, v119
	v_max3_u32 v89, v109, v105, v115
	v_max3_u32 v91, v97, v106, v118
	v_max3_u32 v88, v110, v88, v102
	v_max3_u32 v83, v90, v83, v117
	v_max3_u32 v90, v111, v103, v100
	v_max3_u32 v79, v85, v79, v116
	v_max3_u32 v85, v112, v99, v101
	v_max3_u32 v3, v78, v80, v3
	v_max3_u32 v78, v114, v86, v104
	v_max_u32_e32 v80, v82, v91
	v_min_u32_e32 v82, v82, v91
	v_max_u32_e32 v86, v0, v88
	v_min_u32_e32 v0, v0, v88
	v_max_u32_e32 v88, v2, v83
	v_min_u32_e32 v2, v2, v83
	v_max_u32_e32 v83, v1, v90
	v_min_u32_e32 v1, v1, v90
	v_max_u32_e32 v90, v81, v79
	v_min_u32_e32 v79, v81, v79
	v_max_u32_e32 v81, v87, v85
	v_min_u32_e32 v85, v87, v85
	v_max_u32_e32 v87, v84, v3
	v_min_u32_e32 v3, v84, v3
	v_max_u32_e32 v84, v89, v78
	v_min_u32_e32 v78, v89, v78
	v_max_u32_e32 v89, v80, v90
	v_min_u32_e32 v80, v80, v90
	v_max_u32_e32 v90, v86, v81
	v_min_u32_e32 v81, v86, v81
	v_max_u32_e32 v86, v88, v87
	v_min_u32_e32 v87, v88, v87
	v_max_u32_e32 v88, v83, v84
	v_min_u32_e32 v83, v83, v84
	v_max_u32_e32 v84, v82, v79
	v_min_u32_e32 v79, v82, v79
	v_max_u32_e32 v82, v0, v85
	v_min_u32_e32 v0, v0, v85
	v_max_u32_e32 v85, v2, v3
	v_min_u32_e32 v2, v2, v3
	v_max_u32_e32 v3, v1, v78
	v_min_u32_e32 v1, v1, v78
	v_max_u32_e32 v78, v89, v86
	v_min_u32_e32 v86, v89, v86
	v_max_u32_e32 v89, v90, v88
	v_min_u32_e32 v88, v90, v88
	v_max_u32_e32 v90, v80, v87
	v_min_u32_e32 v80, v80, v87
	v_max_u32_e32 v87, v81, v83
	v_min_u32_e32 v81, v81, v83
	v_max_u32_e32 v83, v84, v85
	v_min_u32_e32 v84, v84, v85
	v_max_u32_e32 v85, v82, v3
	v_min_u32_e32 v3, v82, v3
	v_max_u32_e32 v82, v79, v2
	v_min_u32_e32 v2, v79, v2
	v_max_u32_e32 v79, v0, v1
	v_min_u32_e32 v0, v0, v1
	v_max_u32_e32 v1, v78, v89
	v_min_u32_e32 v78, v78, v89
	v_max_u32_e32 v89, v86, v88
	v_min_u32_e32 v86, v86, v88
	v_max_u32_e32 v88, v90, v87
	v_min_u32_e32 v87, v90, v87
	v_max_u32_e32 v90, v80, v81
	v_min_u32_e32 v80, v80, v81
	v_max_u32_e32 v81, v83, v85
	v_min_u32_e32 v83, v83, v85
	v_max_u32_e32 v85, v84, v3
	v_min_u32_e32 v3, v84, v3
	v_max_u32_e32 v84, v82, v79
	v_min_u32_e32 v79, v82, v79
	v_max_u32_e32 v82, v2, v0
	v_min_u32_e32 v0, v2, v0
	ds_bpermute_b32 v2, v27, v1
	ds_bpermute_b32 v91, v27, v78
	ds_bpermute_b32 v92, v27, v89
	ds_bpermute_b32 v93, v27, v86
	ds_bpermute_b32 v94, v27, v88
	ds_bpermute_b32 v95, v27, v87
	ds_bpermute_b32 v96, v27, v90
	ds_bpermute_b32 v97, v27, v80
	ds_bpermute_b32 v98, v27, v81
	ds_bpermute_b32 v99, v27, v83
	ds_bpermute_b32 v100, v27, v85
	ds_bpermute_b32 v101, v27, v0
	ds_bpermute_b32 v102, v27, v82
	ds_bpermute_b32 v103, v27, v79
	ds_bpermute_b32 v104, v27, v84
	ds_bpermute_b32 v105, v27, v3
	s_waitcnt lgkmcnt(4)
	v_max_u32_e32 v1, v1, v101
	s_waitcnt lgkmcnt(3)
	v_max_u32_e32 v78, v78, v102
	s_waitcnt lgkmcnt(2)
	v_max_u32_e32 v89, v89, v103
	s_waitcnt lgkmcnt(1)
	v_max_u32_e32 v86, v86, v104
	s_waitcnt lgkmcnt(0)
; __device__ __forceinline__ void peer_tile(const Args& A, LAS unsigned char* lds, int tile) {
;     ...
;                 { const bf16_t* sp = QRY + m * 2048 + hp * 128 + 32 * g;
;                   const u32x4 s0 = *(const u32x4*)sp, s1 = *(const u32x4*)(sp + 8), s2 = *(const u32x4*)(sp + 16), s3 = *(const u32x4*)(sp + 24);
;     ...
;                 for (int msk = 16; msk <= 32; msk <<= 1) {
; #pragma unroll
;                     for (int i = 0; i < 16; ++i) k1[i] = (unsigned)__shfl_xor((int)k0[i], msk);
;                     merge16(k0, k1); }
; #pragma unroll
;                 for (int i = 0; i < 16; ++i) LA[hh][p][i] = k0[i];
	v_max_u32_e32 v88, v88, v105
	v_max_u32_e32 v87, v87, v100
	v_max_u32_e32 v90, v90, v99
	v_max_u32_e32 v80, v80, v98
	v_max_u32_e32 v81, v81, v97
	v_max_u32_e32 v83, v83, v96
	v_max_u32_e32 v85, v85, v95
	v_max_u32_e32 v3, v3, v94
	v_max_u32_e32 v84, v84, v93
	v_max_u32_e32 v79, v79, v92
	v_max_u32_e32 v82, v82, v91
	v_max_u32_e32 v0, v0, v2
	v_max_u32_e32 v2, v1, v81
	v_min_u32_e32 v1, v1, v81
	v_max_u32_e32 v81, v78, v83
	v_min_u32_e32 v78, v78, v83
	v_max_u32_e32 v83, v89, v85
	v_min_u32_e32 v85, v89, v85
	v_max_u32_e32 v89, v86, v3
	v_min_u32_e32 v3, v86, v3
	v_max_u32_e32 v86, v88, v84
	v_min_u32_e32 v84, v88, v84
	v_max_u32_e32 v88, v87, v79
	v_min_u32_e32 v79, v87, v79
	v_max_u32_e32 v87, v90, v82
	v_min_u32_e32 v82, v90, v82
	v_max_u32_e32 v90, v80, v0
	v_min_u32_e32 v0, v80, v0
	v_max_u32_e32 v80, v2, v86
	v_min_u32_e32 v2, v2, v86
	v_max_u32_e32 v86, v81, v88
	v_min_u32_e32 v81, v81, v88
	v_max_u32_e32 v88, v83, v87
	v_min_u32_e32 v83, v83, v87
	v_max_u32_e32 v87, v89, v90
	v_min_u32_e32 v89, v89, v90
	v_max_u32_e32 v90, v1, v84
	v_min_u32_e32 v1, v1, v84
	v_max_u32_e32 v84, v78, v79
	v_min_u32_e32 v78, v78, v79
	v_max_u32_e32 v79, v85, v82
	v_min_u32_e32 v82, v85, v82
	v_max_u32_e32 v85, v3, v0
	v_min_u32_e32 v0, v3, v0
	v_max_u32_e32 v3, v80, v88
	v_min_u32_e32 v80, v80, v88
	v_max_u32_e32 v88, v86, v87
	v_min_u32_e32 v86, v86, v87
	v_max_u32_e32 v87, v2, v83
	v_min_u32_e32 v2, v2, v83
	v_max_u32_e32 v83, v81, v89
	v_min_u32_e32 v81, v81, v89
	v_max_u32_e32 v89, v90, v79
	v_min_u32_e32 v79, v90, v79
	v_max_u32_e32 v90, v84, v85
	v_min_u32_e32 v84, v84, v85
	v_max_u32_e32 v85, v1, v82
	v_min_u32_e32 v1, v1, v82
	v_max_u32_e32 v82, v78, v0
	v_min_u32_e32 v0, v78, v0
	v_max_u32_e32 v78, v3, v88
	v_min_u32_e32 v3, v3, v88
	v_max_u32_e32 v88, v80, v86
	v_min_u32_e32 v80, v80, v86
	v_max_u32_e32 v86, v87, v83
	v_min_u32_e32 v83, v87, v83
	v_max_u32_e32 v87, v2, v81
	v_min_u32_e32 v2, v2, v81
	v_max_u32_e32 v81, v89, v90
	v_min_u32_e32 v89, v89, v90
	v_max_u32_e32 v90, v79, v84
	v_min_u32_e32 v79, v79, v84
	v_max_u32_e32 v84, v85, v82
	v_min_u32_e32 v82, v85, v82
	v_max_u32_e32 v85, v1, v0
	v_min_u32_e32 v0, v1, v0
	ds_bpermute_b32 v94, v29, v0
	ds_bpermute_b32 v1, v29, v78
	ds_bpermute_b32 v91, v29, v3
	ds_bpermute_b32 v92, v29, v88
	ds_bpermute_b32 v93, v29, v80
	s_waitcnt lgkmcnt(4)
	v_max_u32_e32 v78, v78, v94
	global_load_dwordx4 v[94:97], v[4:5], off offset:1040
	global_load_dwordx4 v[98:101], v[4:5], off offset:1024
	ds_bpermute_b32 v102, v29, v86
	ds_bpermute_b32 v103, v29, v83
	ds_bpermute_b32 v104, v29, v87
	ds_bpermute_b32 v105, v29, v2
	ds_bpermute_b32 v106, v29, v81
	ds_bpermute_b32 v107, v29, v89
	ds_bpermute_b32 v108, v29, v90
	ds_bpermute_b32 v109, v29, v79
	ds_bpermute_b32 v110, v29, v84
	ds_bpermute_b32 v111, v29, v85
	ds_bpermute_b32 v112, v29, v82
	s_waitcnt lgkmcnt(4)
	v_max_u32_e32 v83, v83, v108
	s_waitcnt lgkmcnt(3)
	v_max_u32_e32 v86, v86, v109
	s_waitcnt lgkmcnt(2)
	v_max_u32_e32 v80, v80, v110
	s_waitcnt lgkmcnt(1)
	v_max_u32_e32 v3, v3, v111
	s_waitcnt lgkmcnt(0)
	v_max_u32_e32 v88, v88, v112
	v_max_u32_e32 v87, v87, v107
	v_max_u32_e32 v2, v2, v106
	v_max_u32_e32 v81, v81, v105
	v_max_u32_e32 v89, v89, v104
	v_max_u32_e32 v90, v90, v103
	v_max_u32_e32 v79, v79, v102
	v_max_u32_e32 v84, v84, v93
	v_max_u32_e32 v82, v82, v92
	v_max_u32_e32 v85, v85, v91
	v_max_u32_e32 v0, v0, v1
	v_max_u32_e32 v1, v78, v81
	v_min_u32_e32 v78, v78, v81
	v_max_u32_e32 v81, v3, v89
	v_min_u32_e32 v3, v3, v89
	v_max_u32_e32 v89, v88, v90
	v_min_u32_e32 v88, v88, v90
	v_max_u32_e32 v90, v80, v79
	v_min_u32_e32 v79, v80, v79
	v_max_u32_e32 v80, v86, v84
	v_min_u32_e32 v84, v86, v84
	v_max_u32_e32 v86, v83, v82
	v_min_u32_e32 v82, v83, v82
	v_max_u32_e32 v83, v87, v85
	v_min_u32_e32 v85, v87, v85
	v_max_u32_e32 v87, v2, v0
	v_min_u32_e32 v0, v2, v0
	v_max_u32_e32 v2, v1, v80
	v_min_u32_e32 v1, v1, v80
	v_max_u32_e32 v80, v81, v86
	v_min_u32_e32 v81, v81, v86
	v_max_u32_e32 v86, v89, v83
	v_min_u32_e32 v83, v89, v83
	v_max_u32_e32 v89, v90, v87
	v_min_u32_e32 v87, v90, v87
	v_max_u32_e32 v90, v78, v84
	v_min_u32_e32 v78, v78, v84
	v_max_u32_e32 v84, v3, v82
	v_min_u32_e32 v3, v3, v82
	v_max_u32_e32 v82, v88, v85
	v_min_u32_e32 v85, v88, v85
	v_max_u32_e32 v88, v79, v0
	v_min_u32_e32 v0, v79, v0
	v_max_u32_e32 v79, v2, v86
	v_min_u32_e32 v2, v2, v86
	v_max_u32_e32 v86, v80, v89
	v_min_u32_e32 v80, v80, v89
	v_max_u32_e32 v102, v1, v83
	v_min_u32_e32 v1, v1, v83
	v_max_u32_e32 v83, v81, v87
	v_min_u32_e32 v81, v81, v87
	v_max_u32_e32 v103, v90, v82
	v_min_u32_e32 v82, v90, v82
	v_max_u32_e32 v104, v84, v88
	v_min_u32_e32 v105, v84, v88
	v_max_u32_e32 v106, v78, v85
	v_min_u32_e32 v78, v78, v85
	v_max_u32_e32 v107, v3, v0
	v_min_u32_e32 v0, v3, v0
	v_max_u32_e32 v93, v79, v86
	v_min_u32_e32 v92, v79, v86
	v_max_u32_e32 v91, v2, v80
	v_min_u32_e32 v90, v2, v80
	v_max_u32_e32 v89, v102, v83
	v_min_u32_e32 v88, v102, v83
	v_max_u32_e32 v87, v1, v81
	v_min_u32_e32 v86, v1, v81
	v_max_u32_e32 v85, v103, v104
	v_min_u32_e32 v84, v103, v104
	v_max_u32_e32 v83, v82, v105
	v_min_u32_e32 v82, v82, v105
	v_max_u32_e32 v79, v78, v0
	v_min_u32_e32 v78, v78, v0
	global_load_dwordx4 v[0:3], v[4:5], off offset:1072
	global_load_dwordx4 v[102:105], v[4:5], off offset:1056
	v_max_u32_e32 v81, v106, v107
	v_min_u32_e32 v80, v106, v107
	s_waitcnt vmcnt(2)
; __device__ __forceinline__ unsigned f2key(float f) { const unsigned u = __float_as_uint(f); return (u & 0x80000000u) ? ~u : (u | 0x80000000u); }
; __device__ __forceinline__ void peer_tile(const Args& A, LAS unsigned char* lds, int tile) {
;     ...
;                   for (int i = 0; i < 16; ++i) {
;                       const float lo = (float)__builtin_bit_cast(_Float16, (unsigned short)(sw[i] & 0xffffu)), hi = (float)__builtin_bit_cast(_Float16, (unsigned short)(sw[i] >> 16));
;                       const unsigned klo = (f2key(lo) & ~127u) | (unsigned)(127 - (32 * g + 2 * i)), khi = (f2key(hi) & ~127u) | (unsigned)(127 - (32 * g + 2 * i + 1));
;                       if (i < 8) { k0[2 * i] = klo; k0[2 * i + 1] = khi; } else { k1[2 * (i - 8)] = klo; k1[2 * (i - 8) + 1] = khi; } } }
;     ...
;                 for (int i = 0; i < 16; ++i) L2[p][i] = (g & 2) ? ((g & 1) ? LA[3][p][i] : LA[2][p][i]) : ((g & 1) ? LA[1][p][i] : LA[0][p][i]);
	v_cvt_f32_f16_sdwa v106, v98 dst_sel:DWORD dst_unused:UNUSED_PAD src0_sel:WORD_1
	v_cvt_f32_f16_e32 v98, v98
	v_cndmask_b32_e64 v34, v66, v34, s[0:1]
	v_cndmask_b32_e64 v33, v65, v33, s[0:1]
	v_not_b32_e32 v107, v106
	v_or_b32_e32 v108, 0x80000000, v106
	v_cmp_gt_i32_e32 vcc, 0, v106
	v_cndmask_b32_e64 v32, v64, v32, s[0:1]
	v_cndmask_b32_e64 v31, v63, v31, s[0:1]
	v_cndmask_b32_e32 v106, v108, v107, vcc
	v_not_b32_e32 v107, v98
	v_or_b32_e32 v108, 0x80000000, v98
	v_cmp_gt_i32_e32 vcc, 0, v98
	v_and_b32_e32 v106, 0xffffff80, v106
	v_sub_u32_e32 v106, v106, v15
	v_cndmask_b32_e32 v98, v108, v107, vcc
	v_cvt_f32_f16_sdwa v107, v99 dst_sel:DWORD dst_unused:UNUSED_PAD src0_sel:WORD_1
	v_cvt_f32_f16_e32 v99, v99
	v_and_b32_e32 v98, 0xffffff80, v98
	v_sub_u32_e32 v98, v98, v15
	v_not_b32_e32 v108, v107
	v_or_b32_e32 v109, 0x80000000, v107
	v_cmp_gt_i32_e32 vcc, 0, v107
	v_add_u32_e32 v106, 0x7e, v106
	v_add_u32_e32 v98, 0x7f, v98
	v_cndmask_b32_e32 v107, v109, v108, vcc
	v_not_b32_e32 v108, v99
	v_or_b32_e32 v109, 0x80000000, v99
	v_cmp_gt_i32_e32 vcc, 0, v99
	v_and_b32_e32 v107, 0xffffff80, v107
	v_sub_u32_e32 v107, v107, v14
	v_cndmask_b32_e32 v99, v109, v108, vcc
	v_cvt_f32_f16_sdwa v108, v100 dst_sel:DWORD dst_unused:UNUSED_PAD src0_sel:WORD_1
	v_cvt_f32_f16_e32 v100, v100
	v_and_b32_e32 v99, 0xffffff80, v99
	v_sub_u32_e32 v99, v99, v14
	v_not_b32_e32 v109, v108
	v_or_b32_e32 v110, 0x80000000, v108
	v_cmp_gt_i32_e32 vcc, 0, v108
	v_add_u32_e32 v107, 0x7e, v107
	v_add_u32_e32 v99, 0x7f, v99
	v_cndmask_b32_e32 v108, v110, v109, vcc
	v_not_b32_e32 v109, v100
	v_or_b32_e32 v110, 0x80000000, v100
	v_cmp_gt_i32_e32 vcc, 0, v100
	v_and_b32_e32 v108, 0xffffff80, v108
	v_sub_u32_e32 v108, v108, v12
	v_cndmask_b32_e32 v100, v110, v109, vcc
	v_cvt_f32_f16_sdwa v109, v101 dst_sel:DWORD dst_unused:UNUSED_PAD src0_sel:WORD_1
	v_cvt_f32_f16_e32 v101, v101
	v_and_b32_e32 v100, 0xffffff80, v100
	v_sub_u32_e32 v100, v100, v12
	v_not_b32_e32 v110, v109
	v_or_b32_e32 v111, 0x80000000, v109
	v_cmp_gt_i32_e32 vcc, 0, v109
	v_add_u32_e32 v108, 0x7e, v108
	v_add_u32_e32 v100, 0x7f, v100
	v_cndmask_b32_e32 v109, v111, v110, vcc
	v_not_b32_e32 v110, v101
	v_or_b32_e32 v111, 0x80000000, v101
	v_cmp_gt_i32_e32 vcc, 0, v101
	v_and_b32_e32 v109, 0xffffff80, v109
	v_sub_u32_e32 v109, v109, v10
	v_cndmask_b32_e32 v101, v111, v110, vcc
	v_cvt_f32_f16_sdwa v110, v94 dst_sel:DWORD dst_unused:UNUSED_PAD src0_sel:WORD_1
	v_cvt_f32_f16_e32 v94, v94
	v_and_b32_e32 v101, 0xffffff80, v101
	v_sub_u32_e32 v101, v101, v10
	v_not_b32_e32 v111, v110
	v_or_b32_e32 v112, 0x80000000, v110
	v_cmp_gt_i32_e32 vcc, 0, v110
	v_add_u32_e32 v109, 0x7e, v109
	v_add_u32_e32 v101, 0x7f, v101
	v_cndmask_b32_e32 v110, v112, v111, vcc
	v_not_b32_e32 v111, v94
	v_or_b32_e32 v112, 0x80000000, v94
	v_cmp_gt_i32_e32 vcc, 0, v94
	v_and_b32_e32 v110, 0xffffff80, v110
	v_sub_u32_e32 v110, v110, v8
	v_cndmask_b32_e32 v94, v112, v111, vcc
	v_cvt_f32_f16_sdwa v111, v95 dst_sel:DWORD dst_unused:UNUSED_PAD src0_sel:WORD_1
	v_cvt_f32_f16_e32 v95, v95
	v_and_b32_e32 v94, 0xffffff80, v94
	v_sub_u32_e32 v94, v94, v8
	v_not_b32_e32 v112, v111
	v_or_b32_e32 v114, 0x80000000, v111
	v_cmp_gt_i32_e32 vcc, 0, v111
	v_add_u32_e32 v110, 0x7e, v110
	v_add_u32_e32 v94, 0x7f, v94
	v_cndmask_b32_e32 v111, v114, v112, vcc
	v_not_b32_e32 v112, v95
	v_or_b32_e32 v114, 0x80000000, v95
	v_cmp_gt_i32_e32 vcc, 0, v95
	v_and_b32_e32 v111, 0xffffff80, v111
	v_sub_u32_e32 v111, v111, v16
	v_cndmask_b32_e32 v95, v114, v112, vcc
	v_cvt_f32_f16_sdwa v112, v96 dst_sel:DWORD dst_unused:UNUSED_PAD src0_sel:WORD_1
	v_cvt_f32_f16_e32 v96, v96
	v_and_b32_e32 v95, 0xffffff80, v95
	v_sub_u32_e32 v95, v95, v16
	v_not_b32_e32 v114, v112
	v_or_b32_e32 v115, 0x80000000, v112
	v_cmp_gt_i32_e32 vcc, 0, v112
	v_add_u32_e32 v111, 0x7e, v111
	v_add_u32_e32 v95, 0x7f, v95
	v_cndmask_b32_e32 v112, v115, v114, vcc
	v_not_b32_e32 v114, v96
	v_or_b32_e32 v115, 0x80000000, v96
	v_cmp_gt_i32_e32 vcc, 0, v96
	v_and_b32_e32 v112, 0xffffff80, v112
	v_sub_u32_e32 v112, v112, v17
	v_cndmask_b32_e32 v96, v115, v114, vcc
	v_cvt_f32_f16_sdwa v114, v97 dst_sel:DWORD dst_unused:UNUSED_PAD src0_sel:WORD_1
	v_cvt_f32_f16_e32 v97, v97
	v_and_b32_e32 v96, 0xffffff80, v96
	v_sub_u32_e32 v96, v96, v17
	v_not_b32_e32 v115, v114
	v_or_b32_e32 v116, 0x80000000, v114
	v_cmp_gt_i32_e32 vcc, 0, v114
	v_add_u32_e32 v112, 0x7e, v112
	v_add_u32_e32 v96, 0x7f, v96
	v_cndmask_b32_e32 v114, v116, v115, vcc
	v_not_b32_e32 v115, v97
	v_or_b32_e32 v116, 0x80000000, v97
	v_cmp_gt_i32_e32 vcc, 0, v97
	v_and_b32_e32 v114, 0xffffff80, v114
	v_sub_u32_e32 v114, v114, v18
	v_cndmask_b32_e32 v97, v116, v115, vcc
	s_waitcnt vmcnt(0)
; __device__ __forceinline__ unsigned f2key(float f) { const unsigned u = __float_as_uint(f); return (u & 0x80000000u) ? ~u : (u | 0x80000000u); }
; #define CE_DESC(a, b) do { const unsigned _mx = (a) > (b) ? (a) : (b), _mn = (a) > (b) ? (b) : (a); (a) = _mx; (b) = _mn; } while (0)
; __device__ __forceinline__ void sort16_desc(unsigned (&k)[16]) {
; #pragma unroll
;     for (int size = 2; size <= 16; size <<= 1)
; #pragma unroll
;         for (int stride = size >> 1; stride > 0; stride >>= 1)
; #pragma unroll
;             for (int i = 0; i < 16; ++i) { const int j = i ^ stride;
;                 if (j > i) { if ((i & size) == 0) CE_DESC(k[i], k[j]); else CE_DESC(k[j], k[i]); } }
; }
; __device__ __forceinline__ void peer_tile(const Args& A, LAS unsigned char* lds, int tile) {
;     ...
;                   for (int i = 0; i < 16; ++i) {
;                       const float lo = (float)__builtin_bit_cast(_Float16, (unsigned short)(sw[i] & 0xffffu)), hi = (float)__builtin_bit_cast(_Float16, (unsigned short)(sw[i] >> 16));
;                       const unsigned klo = (f2key(lo) & ~127u) | (unsigned)(127 - (32 * g + 2 * i)), khi = (f2key(hi) & ~127u) | (unsigned)(127 - (32 * g + 2 * i + 1));
;                       if (i < 8) { k0[2 * i] = klo; k0[2 * i + 1] = khi; } else { k1[2 * (i - 8)] = klo; k1[2 * (i - 8) + 1] = khi; } } }
;                 sort16_desc(k0); sort16_desc(k1); merge16(k0, k1);
	v_cvt_f32_f16_sdwa v115, v102 dst_sel:DWORD dst_unused:UNUSED_PAD src0_sel:WORD_1
	v_cvt_f32_f16_e32 v102, v102
	v_and_b32_e32 v97, 0xffffff80, v97
	v_sub_u32_e32 v97, v97, v18
	v_not_b32_e32 v116, v115
	v_or_b32_e32 v117, 0x80000000, v115
	v_cmp_gt_i32_e32 vcc, 0, v115
	v_add_u32_e32 v114, 0x7e, v114
	v_add_u32_e32 v97, 0x7f, v97
	v_cndmask_b32_e32 v115, v117, v116, vcc
	v_not_b32_e32 v116, v102
	v_or_b32_e32 v117, 0x80000000, v102
	v_cmp_gt_i32_e32 vcc, 0, v102
	v_and_b32_e32 v115, 0xffffff80, v115
	v_sub_u32_e32 v115, v115, v20
	v_cndmask_b32_e32 v102, v117, v116, vcc
	v_cvt_f32_f16_sdwa v116, v103 dst_sel:DWORD dst_unused:UNUSED_PAD src0_sel:WORD_1
	v_cvt_f32_f16_e32 v103, v103
	v_and_b32_e32 v102, 0xffffff80, v102
	v_sub_u32_e32 v102, v102, v20
	v_not_b32_e32 v117, v116
	v_or_b32_e32 v118, 0x80000000, v116
	v_cmp_gt_i32_e32 vcc, 0, v116
	v_add_u32_e32 v115, 0x7e, v115
	v_add_u32_e32 v102, 0x7f, v102
	v_cndmask_b32_e32 v116, v118, v117, vcc
	v_not_b32_e32 v117, v103
	v_or_b32_e32 v118, 0x80000000, v103
	v_cmp_gt_i32_e32 vcc, 0, v103
	v_and_b32_e32 v116, 0xffffff80, v116
	v_sub_u32_e32 v116, v116, v21
	v_cndmask_b32_e32 v103, v118, v117, vcc
	v_cvt_f32_f16_sdwa v117, v104 dst_sel:DWORD dst_unused:UNUSED_PAD src0_sel:WORD_1
	v_cvt_f32_f16_e32 v104, v104
	v_and_b32_e32 v103, 0xffffff80, v103
	v_sub_u32_e32 v103, v103, v21
	v_not_b32_e32 v118, v117
	v_or_b32_e32 v119, 0x80000000, v117
	v_cmp_gt_i32_e32 vcc, 0, v117
	v_add_u32_e32 v116, 0x7e, v116
	v_add_u32_e32 v103, 0x7f, v103
	v_cndmask_b32_e32 v117, v119, v118, vcc
	v_not_b32_e32 v118, v104
	v_or_b32_e32 v119, 0x80000000, v104
	v_cmp_gt_i32_e32 vcc, 0, v104
	v_and_b32_e32 v117, 0xffffff80, v117
	v_sub_u32_e32 v117, v117, v22
	v_cndmask_b32_e32 v104, v119, v118, vcc
	v_cvt_f32_f16_sdwa v118, v105 dst_sel:DWORD dst_unused:UNUSED_PAD src0_sel:WORD_1
	v_cvt_f32_f16_e32 v105, v105
	v_and_b32_e32 v104, 0xffffff80, v104
	v_sub_u32_e32 v104, v104, v22
	v_not_b32_e32 v119, v118
	v_or_b32_e32 v120, 0x80000000, v118
	v_cmp_gt_i32_e32 vcc, 0, v118
	v_add_u32_e32 v117, 0x7e, v117
	v_add_u32_e32 v104, 0x7f, v104
	v_cndmask_b32_e32 v118, v120, v119, vcc
	v_not_b32_e32 v119, v105
	v_or_b32_e32 v120, 0x80000000, v105
	v_cmp_gt_i32_e32 vcc, 0, v105
	v_and_b32_e32 v118, 0xffffff80, v118
	v_sub_u32_e32 v118, v118, v23
	v_cndmask_b32_e32 v105, v120, v119, vcc
	v_cvt_f32_f16_sdwa v119, v0 dst_sel:DWORD dst_unused:UNUSED_PAD src0_sel:WORD_1
	v_cvt_f32_f16_e32 v0, v0
	v_and_b32_e32 v105, 0xffffff80, v105
	v_sub_u32_e32 v105, v105, v23
	v_not_b32_e32 v120, v119
	v_or_b32_e32 v121, 0x80000000, v119
	v_cmp_gt_i32_e32 vcc, 0, v119
	v_add_u32_e32 v118, 0x7e, v118
	v_add_u32_e32 v105, 0x7f, v105
	v_cndmask_b32_e32 v119, v121, v120, vcc
	v_not_b32_e32 v120, v0
	v_or_b32_e32 v121, 0x80000000, v0
	v_cmp_gt_i32_e32 vcc, 0, v0
	v_and_b32_e32 v119, 0xffffff80, v119
	v_sub_u32_e32 v119, v119, v24
	v_cndmask_b32_e32 v0, v121, v120, vcc
	v_cvt_f32_f16_sdwa v120, v1 dst_sel:DWORD dst_unused:UNUSED_PAD src0_sel:WORD_1
	v_cvt_f32_f16_e32 v1, v1
	v_and_b32_e32 v0, 0xffffff80, v0
	v_sub_u32_e32 v0, v0, v24
	v_not_b32_e32 v121, v120
	v_or_b32_e32 v122, 0x80000000, v120
	v_cmp_gt_i32_e32 vcc, 0, v120
	v_add_u32_e32 v119, 0x7e, v119
	v_add_u32_e32 v0, 0x7f, v0
	v_cndmask_b32_e32 v120, v122, v121, vcc
	v_not_b32_e32 v121, v1
	v_or_b32_e32 v122, 0x80000000, v1
	v_cmp_gt_i32_e32 vcc, 0, v1
	v_and_b32_e32 v120, 0xffffff80, v120
	v_sub_u32_e32 v120, v120, v25
	v_cndmask_b32_e32 v1, v122, v121, vcc
	v_cvt_f32_f16_sdwa v121, v2 dst_sel:DWORD dst_unused:UNUSED_PAD src0_sel:WORD_1
	v_cvt_f32_f16_e32 v2, v2
	v_and_b32_e32 v1, 0xffffff80, v1
	v_sub_u32_e32 v1, v1, v25
	v_not_b32_e32 v122, v121
	v_or_b32_e32 v123, 0x80000000, v121
	v_cmp_gt_i32_e32 vcc, 0, v121
	v_add_u32_e32 v120, 0x7e, v120
	v_add_u32_e32 v1, 0x7f, v1
	v_cndmask_b32_e32 v121, v123, v122, vcc
	v_not_b32_e32 v122, v2
	v_or_b32_e32 v123, 0x80000000, v2
	v_cmp_gt_i32_e32 vcc, 0, v2
	v_and_b32_e32 v121, 0xffffff80, v121
	v_sub_u32_e32 v121, v121, v26
	v_cndmask_b32_e32 v2, v123, v122, vcc
	v_cvt_f32_f16_sdwa v122, v3 dst_sel:DWORD dst_unused:UNUSED_PAD src0_sel:WORD_1
	v_cvt_f32_f16_e32 v3, v3
	v_and_b32_e32 v2, 0xffffff80, v2
	v_sub_u32_e32 v2, v2, v26
	v_not_b32_e32 v123, v122
	v_or_b32_e32 v124, 0x80000000, v122
	v_cmp_gt_i32_e32 vcc, 0, v122
	v_add_u32_e32 v121, 0x7e, v121
	v_add_u32_e32 v2, 0x7f, v2
	v_cndmask_b32_e32 v122, v124, v123, vcc
	v_not_b32_e32 v123, v3
	v_or_b32_e32 v124, 0x80000000, v3
	v_cmp_gt_i32_e32 vcc, 0, v3
	v_and_b32_e32 v122, 0xffffff80, v122
	v_sub_u32_e32 v122, v122, v28
	v_cndmask_b32_e32 v3, v124, v123, vcc
	v_and_b32_e32 v3, 0xffffff80, v3
	v_sub_u32_e32 v3, v3, v28
	v_add_u32_e32 v122, 0x7e, v122
	v_add_u32_e32 v3, 0x7f, v3
	v_max_u32_e32 v123, v98, v106
	v_min_u32_e32 v98, v98, v106
	v_max_u32_e32 v106, v107, v99
	v_min_u32_e32 v99, v107, v99
	v_max_u32_e32 v107, v100, v108
	v_min_u32_e32 v100, v100, v108
	v_max_u32_e32 v108, v109, v101
	v_min_u32_e32 v101, v109, v101
	v_max_u32_e32 v109, v94, v110
	v_min_u32_e32 v94, v94, v110
	v_max_u32_e32 v110, v111, v95
	v_min_u32_e32 v95, v111, v95
	v_max_u32_e32 v111, v96, v112
	v_min_u32_e32 v96, v96, v112
	v_max_u32_e32 v112, v114, v97
	v_min_u32_e32 v97, v114, v97
	v_max_u32_e32 v131, v102, v115
	v_min_u32_e32 v102, v102, v115
	v_max_u32_e32 v115, v116, v103
	v_min_u32_e32 v103, v116, v103
	v_max_u32_e32 v116, v104, v117
	v_min_u32_e32 v104, v104, v117
	v_max_u32_e32 v117, v118, v105
	v_min_u32_e32 v105, v118, v105
	v_max_u32_e32 v118, v0, v119
	v_min_u32_e32 v0, v0, v119
	v_max_u32_e32 v119, v120, v1
	v_min_u32_e32 v1, v120, v1
	v_max_u32_e32 v120, v2, v121
	v_min_u32_e32 v2, v2, v121
; #define CE_DESC(a, b) do { const unsigned _mx = (a) > (b) ? (a) : (b), _mn = (a) > (b) ? (b) : (a); (a) = _mx; (b) = _mn; } while (0)
; __device__ __forceinline__ void sort16_desc(unsigned (&k)[16]) {
; #pragma unroll
;     for (int size = 2; size <= 16; size <<= 1)
; #pragma unroll
;         for (int stride = size >> 1; stride > 0; stride >>= 1)
; #pragma unroll
;             for (int i = 0; i < 16; ++i) { const int j = i ^ stride;
;                 if (j > i) { if ((i & size) == 0) CE_DESC(k[i], k[j]); else CE_DESC(k[j], k[i]); } }
; }
	v_max_u32_e32 v121, v122, v3
	v_min_u32_e32 v3, v122, v3
	v_max_u32_e32 v114, v123, v99
	v_min_u32_e32 v99, v123, v99
	v_max_u32_e32 v123, v98, v106
	v_min_u32_e32 v98, v98, v106
	v_max_u32_e32 v106, v101, v107
	v_min_u32_e32 v101, v101, v107
	v_max_u32_e32 v107, v108, v100
	v_min_u32_e32 v100, v108, v100
	v_max_u32_e32 v108, v109, v95
	v_min_u32_e32 v95, v109, v95
	v_max_u32_e32 v109, v94, v110
	v_min_u32_e32 v94, v94, v110
	v_max_u32_e32 v110, v97, v111
	v_min_u32_e32 v97, v97, v111
	v_max_u32_e32 v111, v112, v96
	v_min_u32_e32 v96, v112, v96
	v_max_u32_e32 v122, v131, v103
	v_min_u32_e32 v103, v131, v103
	v_max_u32_e32 v131, v102, v115
	v_min_u32_e32 v102, v102, v115
	v_max_u32_e32 v115, v105, v116
	v_min_u32_e32 v105, v105, v116
	v_max_u32_e32 v116, v117, v104
	v_min_u32_e32 v104, v117, v104
	v_max_u32_e32 v117, v118, v1
	v_min_u32_e32 v1, v118, v1
	v_max_u32_e32 v118, v0, v119
	v_min_u32_e32 v0, v0, v119
	v_max_u32_e32 v119, v3, v120
	v_min_u32_e32 v3, v3, v120
	v_max_u32_e32 v120, v121, v2
	v_min_u32_e32 v2, v121, v2
	v_max_u32_e32 v112, v114, v123
	v_min_u32_e32 v114, v114, v123
	v_max_u32_e32 v123, v99, v98
	v_min_u32_e32 v98, v99, v98
	v_max_u32_e32 v99, v100, v101
	v_min_u32_e32 v100, v100, v101
	v_max_u32_e32 v101, v107, v106
	v_min_u32_e32 v106, v107, v106
	v_max_u32_e32 v107, v108, v109
	v_min_u32_e32 v108, v108, v109
	v_max_u32_e32 v109, v95, v94
	v_min_u32_e32 v94, v95, v94
	v_max_u32_e32 v95, v96, v97
	v_min_u32_e32 v96, v96, v97
	v_max_u32_e32 v97, v111, v110
	v_min_u32_e32 v110, v111, v110
	v_max_u32_e32 v121, v122, v131
	v_min_u32_e32 v122, v122, v131
	v_max_u32_e32 v131, v103, v102
	v_min_u32_e32 v102, v103, v102
	v_max_u32_e32 v103, v104, v105
	v_min_u32_e32 v104, v104, v105
	v_max_u32_e32 v105, v116, v115
	v_min_u32_e32 v115, v116, v115
	v_max_u32_e32 v116, v117, v118
	v_min_u32_e32 v117, v117, v118
	v_max_u32_e32 v118, v1, v0
	v_min_u32_e32 v0, v1, v0
	v_max_u32_e32 v1, v2, v3
	v_min_u32_e32 v2, v2, v3
	v_max_u32_e32 v3, v120, v119
	v_min_u32_e32 v119, v120, v119
	v_max_u32_e32 v111, v112, v100
	v_min_u32_e32 v100, v112, v100
	v_max_u32_e32 v112, v114, v99
	v_min_u32_e32 v99, v114, v99
	v_max_u32_e32 v114, v123, v106
	v_min_u32_e32 v106, v123, v106
	v_max_u32_e32 v123, v98, v101
	v_min_u32_e32 v98, v98, v101
	v_max_u32_e32 v101, v96, v107
	v_min_u32_e32 v96, v96, v107
	v_max_u32_e32 v107, v95, v108
	v_min_u32_e32 v95, v95, v108
	v_max_u32_e32 v108, v110, v109
	v_min_u32_e32 v109, v110, v109
	v_max_u32_e32 v110, v97, v94
	v_min_u32_e32 v94, v97, v94
	v_max_u32_e32 v120, v121, v104
	v_min_u32_e32 v104, v121, v104
	v_max_u32_e32 v121, v122, v103
	v_min_u32_e32 v103, v122, v103
	v_max_u32_e32 v122, v131, v115
	v_min_u32_e32 v115, v131, v115
	v_max_u32_e32 v131, v102, v105
	v_min_u32_e32 v102, v102, v105
	v_max_u32_e32 v105, v2, v116
	v_min_u32_e32 v2, v2, v116
	v_max_u32_e32 v116, v1, v117
	v_min_u32_e32 v1, v1, v117
	v_max_u32_e32 v117, v119, v118
	v_min_u32_e32 v118, v119, v118
	v_max_u32_e32 v119, v3, v0
	v_min_u32_e32 v0, v3, v0
	v_max_u32_e32 v97, v111, v114
	v_min_u32_e32 v111, v111, v114
	v_max_u32_e32 v114, v112, v123
	v_min_u32_e32 v112, v112, v123
	v_max_u32_e32 v123, v100, v106
	v_min_u32_e32 v100, v100, v106
	v_max_u32_e32 v106, v99, v98
	v_min_u32_e32 v98, v99, v98
	v_max_u32_e32 v99, v109, v96
	v_min_u32_e32 v96, v109, v96
	v_max_u32_e32 v109, v94, v95
	v_min_u32_e32 v94, v94, v95
	v_max_u32_e32 v95, v108, v101
	v_min_u32_e32 v101, v108, v101
	v_max_u32_e32 v108, v110, v107
	v_min_u32_e32 v107, v110, v107
	v_max_u32_e32 v3, v120, v122
	v_min_u32_e32 v120, v120, v122
	v_max_u32_e32 v122, v121, v131
	v_min_u32_e32 v121, v121, v131
	v_max_u32_e32 v131, v104, v115
	v_min_u32_e32 v104, v104, v115
	v_max_u32_e32 v115, v103, v102
	v_min_u32_e32 v102, v103, v102
	v_max_u32_e32 v103, v118, v2
	v_min_u32_e32 v2, v118, v2
	v_max_u32_e32 v118, v0, v1
	v_min_u32_e32 v0, v0, v1
	v_max_u32_e32 v1, v117, v105
	v_min_u32_e32 v105, v117, v105
	v_max_u32_e32 v117, v119, v116
	v_min_u32_e32 v116, v119, v116
	v_max_u32_e32 v110, v97, v114
	v_min_u32_e32 v97, v97, v114
	v_max_u32_e32 v114, v111, v112
	v_min_u32_e32 v111, v111, v112
	v_max_u32_e32 v112, v123, v106
	v_min_u32_e32 v106, v123, v106
	v_max_u32_e32 v123, v100, v98
	v_min_u32_e32 v98, v100, v98
	v_max_u32_e32 v100, v94, v96
	v_min_u32_e32 v94, v94, v96
	v_max_u32_e32 v96, v109, v99
	v_min_u32_e32 v99, v109, v99
	v_max_u32_e32 v109, v107, v101
	v_min_u32_e32 v101, v107, v101
	v_max_u32_e32 v107, v108, v95
	v_min_u32_e32 v95, v108, v95
	v_max_u32_e32 v119, v3, v122
	v_min_u32_e32 v3, v3, v122
	v_max_u32_e32 v122, v120, v121
	v_min_u32_e32 v120, v120, v121
	v_max_u32_e32 v121, v131, v115
	v_min_u32_e32 v115, v131, v115
	v_max_u32_e32 v131, v104, v102
	v_min_u32_e32 v102, v104, v102
	v_max_u32_e32 v104, v0, v2
	v_min_u32_e32 v0, v0, v2
	v_max_u32_e32 v2, v118, v103
	v_min_u32_e32 v103, v118, v103
	v_max_u32_e32 v118, v116, v105
	v_min_u32_e32 v105, v116, v105
	v_max_u32_e32 v116, v117, v1
	v_min_u32_e32 v1, v117, v1
	v_max_u32_e32 v108, v110, v94
	v_min_u32_e32 v94, v110, v94
	v_max_u32_e32 v110, v97, v100
	v_min_u32_e32 v97, v97, v100
	v_max_u32_e32 v100, v114, v99
	v_min_u32_e32 v99, v114, v99
	v_max_u32_e32 v114, v111, v96
	v_min_u32_e32 v96, v111, v96
	v_max_u32_e32 v111, v112, v101
	v_min_u32_e32 v101, v112, v101
	v_max_u32_e32 v112, v106, v109
	v_min_u32_e32 v106, v106, v109
	v_max_u32_e32 v109, v123, v95
	v_min_u32_e32 v95, v123, v95
	v_max_u32_e32 v123, v98, v107
	v_min_u32_e32 v98, v98, v107
	v_max_u32_e32 v117, v119, v0
	v_min_u32_e32 v0, v119, v0
	v_max_u32_e32 v119, v3, v104
	v_min_u32_e32 v3, v3, v104
	v_max_u32_e32 v104, v122, v103
	v_min_u32_e32 v103, v122, v103
; #define CE_DESC(a, b) do { const unsigned _mx = (a) > (b) ? (a) : (b), _mn = (a) > (b) ? (b) : (a); (a) = _mx; (b) = _mn; } while (0)
; __device__ __forceinline__ void sort16_desc(unsigned (&k)[16]) {
; #pragma unroll
;     for (int size = 2; size <= 16; size <<= 1)
; #pragma unroll
;         for (int stride = size >> 1; stride > 0; stride >>= 1)
; #pragma unroll
;             for (int i = 0; i < 16; ++i) { const int j = i ^ stride;
;                 if (j > i) { if ((i & size) == 0) CE_DESC(k[i], k[j]); else CE_DESC(k[j], k[i]); } }
; }
; __device__ __forceinline__ void merge16(unsigned (&a)[16], const unsigned (&b)[16]) {
; #pragma unroll
;     for (int i = 0; i < 16; ++i) a[i] = a[i] > b[15 - i] ? a[i] : b[15 - i];
; #pragma unroll
;     for (int stride = 8; stride > 0; stride >>= 1)
; #pragma unroll
;         for (int i = 0; i < 16; ++i) { const int j = i ^ stride; if (j > i) CE_DESC(a[i], a[j]); }
; }
; __device__ __forceinline__ void peer_tile(const Args& A, LAS unsigned char* lds, int tile) {
;     ...
;                 sort16_desc(k0); sort16_desc(k1); merge16(k0, k1);
; #pragma unroll
;                 for (int msk = 16; msk <= 32; msk <<= 1) {
; #pragma unroll
;                     for (int i = 0; i < 16; ++i) k1[i] = (unsigned)__shfl_xor((int)k0[i], msk);
;                     merge16(k0, k1); }
	v_max_u32_e32 v122, v120, v2
	v_min_u32_e32 v2, v120, v2
	v_max_u32_e32 v120, v121, v105
	v_min_u32_e32 v105, v121, v105
	v_max_u32_e32 v121, v115, v118
	v_min_u32_e32 v115, v115, v118
	v_max_u32_e32 v118, v131, v1
	v_min_u32_e32 v1, v131, v1
	v_max_u32_e32 v131, v102, v116
	v_min_u32_e32 v102, v102, v116
	v_max_u32_e32 v107, v108, v111
	v_min_u32_e32 v108, v108, v111
	v_max_u32_e32 v111, v110, v112
	v_min_u32_e32 v110, v110, v112
	v_max_u32_e32 v112, v100, v109
	v_min_u32_e32 v100, v100, v109
	v_max_u32_e32 v109, v114, v123
	v_min_u32_e32 v114, v114, v123
	v_max_u32_e32 v123, v94, v101
	v_min_u32_e32 v94, v94, v101
	v_max_u32_e32 v101, v97, v106
	v_min_u32_e32 v97, v97, v106
	v_max_u32_e32 v106, v99, v95
	v_min_u32_e32 v95, v99, v95
	v_max_u32_e32 v99, v96, v98
	v_min_u32_e32 v96, v96, v98
	v_max_u32_e32 v116, v117, v120
	v_min_u32_e32 v117, v117, v120
	v_max_u32_e32 v120, v119, v121
	v_min_u32_e32 v119, v119, v121
	v_max_u32_e32 v121, v104, v118
	v_min_u32_e32 v104, v104, v118
	v_max_u32_e32 v118, v122, v131
	v_min_u32_e32 v122, v122, v131
	v_max_u32_e32 v131, v0, v105
	v_min_u32_e32 v0, v0, v105
	v_max_u32_e32 v105, v3, v115
	v_min_u32_e32 v3, v3, v115
	v_max_u32_e32 v115, v103, v1
	v_min_u32_e32 v1, v103, v1
	v_max_u32_e32 v103, v2, v102
	v_min_u32_e32 v2, v2, v102
	v_max_u32_e32 v98, v107, v112
	v_min_u32_e32 v107, v107, v112
	v_max_u32_e32 v112, v111, v109
	v_min_u32_e32 v109, v111, v109
	v_max_u32_e32 v111, v108, v100
	v_min_u32_e32 v100, v108, v100
	v_max_u32_e32 v108, v110, v114
	v_min_u32_e32 v110, v110, v114
	v_max_u32_e32 v114, v123, v106
	v_min_u32_e32 v106, v123, v106
	v_max_u32_e32 v123, v101, v99
	v_min_u32_e32 v99, v101, v99
	v_max_u32_e32 v101, v94, v95
	v_min_u32_e32 v94, v94, v95
	v_max_u32_e32 v95, v97, v96
	v_min_u32_e32 v96, v97, v96
	v_max_u32_e32 v102, v116, v121
	v_min_u32_e32 v116, v116, v121
	v_max_u32_e32 v121, v120, v118
	v_min_u32_e32 v118, v120, v118
	v_max_u32_e32 v120, v117, v104
	v_min_u32_e32 v104, v117, v104
	v_max_u32_e32 v117, v119, v122
	v_min_u32_e32 v119, v119, v122
	v_max_u32_e32 v122, v131, v115
	v_min_u32_e32 v115, v131, v115
	v_max_u32_e32 v131, v105, v103
	v_min_u32_e32 v103, v105, v103
	v_max_u32_e32 v105, v0, v1
	v_min_u32_e32 v0, v0, v1
	v_max_u32_e32 v1, v3, v2
	v_min_u32_e32 v2, v3, v2
	v_min_u32_e32 v97, v98, v112
	v_min_u32_e32 v124, v107, v109
	v_min_u32_e32 v125, v111, v108
	v_min_u32_e32 v126, v100, v110
	v_min_u32_e32 v127, v114, v123
	v_min_u32_e32 v128, v106, v99
	v_min_u32_e32 v129, v101, v95
	v_min_u32_e32 v130, v94, v96
	v_min_u32_e32 v3, v102, v121
	v_min_u32_e32 v132, v116, v118
	v_min_u32_e32 v133, v120, v117
	v_min_u32_e32 v134, v104, v119
	v_min_u32_e32 v135, v122, v131
	v_min_u32_e32 v136, v115, v103
	v_min_u32_e32 v137, v105, v1
	v_min_u32_e32 v138, v0, v2
	v_max3_u32 v98, v98, v112, v138
	v_max3_u32 v0, v97, v0, v2
	v_max3_u32 v2, v107, v109, v137
	v_max3_u32 v1, v124, v105, v1
	v_max3_u32 v97, v111, v108, v136
	v_max3_u32 v103, v125, v115, v103
	v_max3_u32 v100, v100, v110, v135
	v_max3_u32 v105, v126, v122, v131
	v_max3_u32 v107, v114, v123, v134
	v_max3_u32 v104, v127, v104, v119
	v_max3_u32 v99, v106, v99, v133
	v_max3_u32 v106, v128, v120, v117
	v_max3_u32 v95, v101, v95, v132
	v_max3_u32 v101, v129, v116, v118
	v_max3_u32 v3, v94, v96, v3
	v_max3_u32 v94, v130, v102, v121
	v_max_u32_e32 v96, v98, v107
	v_min_u32_e32 v98, v98, v107
	v_max_u32_e32 v102, v0, v104
	v_min_u32_e32 v0, v0, v104
	v_max_u32_e32 v104, v2, v99
	v_min_u32_e32 v2, v2, v99
	v_max_u32_e32 v99, v1, v106
	v_min_u32_e32 v1, v1, v106
	v_max_u32_e32 v106, v97, v95
	v_min_u32_e32 v95, v97, v95
	v_max_u32_e32 v97, v103, v101
	v_min_u32_e32 v101, v103, v101
	v_max_u32_e32 v103, v100, v3
	v_min_u32_e32 v3, v100, v3
	v_max_u32_e32 v100, v105, v94
	v_min_u32_e32 v94, v105, v94
	v_max_u32_e32 v105, v96, v106
	v_min_u32_e32 v96, v96, v106
	v_max_u32_e32 v106, v102, v97
	v_min_u32_e32 v97, v102, v97
	v_max_u32_e32 v102, v104, v103
	v_min_u32_e32 v103, v104, v103
	v_max_u32_e32 v104, v99, v100
	v_min_u32_e32 v99, v99, v100
	v_max_u32_e32 v100, v98, v95
	v_min_u32_e32 v95, v98, v95
	v_max_u32_e32 v98, v0, v101
	v_min_u32_e32 v0, v0, v101
	v_max_u32_e32 v101, v2, v3
	v_min_u32_e32 v2, v2, v3
	v_max_u32_e32 v3, v1, v94
	v_min_u32_e32 v1, v1, v94
	v_max_u32_e32 v94, v105, v102
	v_min_u32_e32 v102, v105, v102
	v_max_u32_e32 v105, v106, v104
	v_min_u32_e32 v104, v106, v104
	v_max_u32_e32 v106, v96, v103
	v_min_u32_e32 v96, v96, v103
	v_max_u32_e32 v103, v97, v99
	v_min_u32_e32 v97, v97, v99
	v_max_u32_e32 v99, v100, v101
	v_min_u32_e32 v100, v100, v101
	v_max_u32_e32 v101, v98, v3
	v_min_u32_e32 v3, v98, v3
	v_max_u32_e32 v98, v95, v2
	v_min_u32_e32 v2, v95, v2
	v_max_u32_e32 v95, v0, v1
	v_min_u32_e32 v0, v0, v1
	v_max_u32_e32 v1, v94, v105
	v_min_u32_e32 v94, v94, v105
	v_max_u32_e32 v105, v102, v104
	v_min_u32_e32 v102, v102, v104
	v_max_u32_e32 v104, v106, v103
	v_min_u32_e32 v103, v106, v103
	v_max_u32_e32 v106, v96, v97
	v_min_u32_e32 v96, v96, v97
	v_max_u32_e32 v97, v99, v101
	v_min_u32_e32 v99, v99, v101
	v_max_u32_e32 v101, v100, v3
	v_min_u32_e32 v3, v100, v3
	v_max_u32_e32 v100, v98, v95
	v_min_u32_e32 v95, v98, v95
	v_max_u32_e32 v98, v2, v0
	v_min_u32_e32 v0, v2, v0
	ds_bpermute_b32 v2, v27, v1
	ds_bpermute_b32 v107, v27, v94
	ds_bpermute_b32 v108, v27, v105
	ds_bpermute_b32 v109, v27, v102
	ds_bpermute_b32 v110, v27, v104
	ds_bpermute_b32 v111, v27, v103
	ds_bpermute_b32 v112, v27, v106
	ds_bpermute_b32 v114, v27, v96
	ds_bpermute_b32 v115, v27, v97
	ds_bpermute_b32 v116, v27, v99
	ds_bpermute_b32 v117, v27, v101
	ds_bpermute_b32 v118, v27, v0
	ds_bpermute_b32 v119, v27, v98
	ds_bpermute_b32 v120, v27, v95
	ds_bpermute_b32 v121, v27, v100
	ds_bpermute_b32 v122, v27, v3
	s_waitcnt lgkmcnt(4)
; __device__ __forceinline__ void peer_tile(const Args& A, LAS unsigned char* lds, int tile) {
;     ...
;                 { const bf16_t* sp = QRY + m * 2048 + hp * 128 + 32 * g;
;                   const u32x4 s0 = *(const u32x4*)sp, s1 = *(const u32x4*)(sp + 8), s2 = *(const u32x4*)(sp + 16), s3 = *(const u32x4*)(sp + 24);
;     ...
;                 for (int msk = 16; msk <= 32; msk <<= 1) {
; #pragma unroll
;                     for (int i = 0; i < 16; ++i) k1[i] = (unsigned)__shfl_xor((int)k0[i], msk);
;                     merge16(k0, k1); }
; #pragma unroll
;                 for (int i = 0; i < 16; ++i) LA[hh][p][i] = k0[i];
	v_max_u32_e32 v1, v1, v118
	s_waitcnt lgkmcnt(3)
	v_max_u32_e32 v94, v94, v119
	s_waitcnt lgkmcnt(2)
	v_max_u32_e32 v105, v105, v120
	s_waitcnt lgkmcnt(1)
	v_max_u32_e32 v102, v102, v121
	s_waitcnt lgkmcnt(0)
	v_max_u32_e32 v104, v104, v122
	v_max_u32_e32 v103, v103, v117
	v_max_u32_e32 v106, v106, v116
	v_max_u32_e32 v96, v96, v115
	v_max_u32_e32 v97, v97, v114
	v_max_u32_e32 v99, v99, v112
	v_max_u32_e32 v101, v101, v111
	v_max_u32_e32 v3, v3, v110
	v_max_u32_e32 v100, v100, v109
	v_max_u32_e32 v95, v95, v108
	v_max_u32_e32 v98, v98, v107
	v_max_u32_e32 v0, v0, v2
	v_max_u32_e32 v2, v1, v97
	v_min_u32_e32 v1, v1, v97
	v_max_u32_e32 v97, v94, v99
	v_min_u32_e32 v94, v94, v99
	v_max_u32_e32 v99, v105, v101
	v_min_u32_e32 v101, v105, v101
	v_max_u32_e32 v105, v102, v3
	v_min_u32_e32 v3, v102, v3
	v_max_u32_e32 v102, v104, v100
	v_min_u32_e32 v100, v104, v100
	v_max_u32_e32 v104, v103, v95
	v_min_u32_e32 v95, v103, v95
	v_max_u32_e32 v103, v106, v98
	v_min_u32_e32 v98, v106, v98
	v_max_u32_e32 v106, v96, v0
	v_min_u32_e32 v0, v96, v0
	v_max_u32_e32 v96, v2, v102
	v_min_u32_e32 v2, v2, v102
	v_max_u32_e32 v102, v97, v104
	v_min_u32_e32 v97, v97, v104
	v_max_u32_e32 v104, v99, v103
	v_min_u32_e32 v99, v99, v103
	v_max_u32_e32 v103, v105, v106
	v_min_u32_e32 v105, v105, v106
	v_max_u32_e32 v106, v1, v100
	v_min_u32_e32 v1, v1, v100
	v_max_u32_e32 v100, v94, v95
	v_min_u32_e32 v94, v94, v95
	v_max_u32_e32 v95, v101, v98
	v_min_u32_e32 v98, v101, v98
	v_max_u32_e32 v101, v3, v0
	v_min_u32_e32 v0, v3, v0
	v_max_u32_e32 v3, v96, v104
	v_min_u32_e32 v96, v96, v104
	v_max_u32_e32 v104, v102, v103
	v_min_u32_e32 v102, v102, v103
	v_max_u32_e32 v103, v2, v99
	v_min_u32_e32 v2, v2, v99
	v_max_u32_e32 v99, v97, v105
	v_min_u32_e32 v97, v97, v105
	v_max_u32_e32 v105, v106, v95
	v_min_u32_e32 v95, v106, v95
	v_max_u32_e32 v106, v100, v101
	v_min_u32_e32 v100, v100, v101
	v_max_u32_e32 v101, v1, v98
	v_min_u32_e32 v1, v1, v98
	v_max_u32_e32 v98, v94, v0
	v_min_u32_e32 v0, v94, v0
	v_max_u32_e32 v94, v3, v104
	v_min_u32_e32 v3, v3, v104
	v_max_u32_e32 v104, v96, v102
	v_min_u32_e32 v96, v96, v102
	v_max_u32_e32 v102, v103, v99
	v_min_u32_e32 v99, v103, v99
	v_max_u32_e32 v103, v2, v97
	v_min_u32_e32 v2, v2, v97
	v_max_u32_e32 v97, v105, v106
	v_min_u32_e32 v105, v105, v106
	v_max_u32_e32 v106, v95, v100
	v_min_u32_e32 v95, v95, v100
	v_max_u32_e32 v100, v101, v98
	v_min_u32_e32 v98, v101, v98
	v_max_u32_e32 v101, v1, v0
	v_min_u32_e32 v0, v1, v0
	ds_bpermute_b32 v114, v29, v0
	ds_bpermute_b32 v1, v29, v94
	ds_bpermute_b32 v107, v29, v3
	ds_bpermute_b32 v108, v29, v104
	ds_bpermute_b32 v109, v29, v96
	s_waitcnt lgkmcnt(4)
	v_max_u32_e32 v94, v94, v114
	global_load_dwordx4 v[114:117], v[4:5], off offset:1296
	global_load_dwordx4 v[118:121], v[4:5], off offset:1280
	ds_bpermute_b32 v110, v29, v102
	ds_bpermute_b32 v111, v29, v99
	ds_bpermute_b32 v112, v29, v103
	ds_bpermute_b32 v122, v29, v2
	ds_bpermute_b32 v123, v29, v97
	ds_bpermute_b32 v124, v29, v105
	ds_bpermute_b32 v125, v29, v106
	ds_bpermute_b32 v126, v29, v95
	ds_bpermute_b32 v127, v29, v100
	ds_bpermute_b32 v128, v29, v101
	ds_bpermute_b32 v129, v29, v98
	s_waitcnt lgkmcnt(4)
	v_max_u32_e32 v99, v99, v125
	s_waitcnt lgkmcnt(3)
	v_max_u32_e32 v102, v102, v126
	s_waitcnt lgkmcnt(2)
	v_max_u32_e32 v96, v96, v127
	s_waitcnt lgkmcnt(1)
	v_max_u32_e32 v3, v3, v128
	s_waitcnt lgkmcnt(0)
	v_max_u32_e32 v104, v104, v129
	v_max_u32_e32 v103, v103, v124
	v_max_u32_e32 v2, v2, v123
	v_max_u32_e32 v97, v97, v122
	v_max_u32_e32 v105, v105, v112
	v_max_u32_e32 v106, v106, v111
	v_max_u32_e32 v95, v95, v110
	v_max_u32_e32 v100, v100, v109
	v_max_u32_e32 v98, v98, v108
	v_max_u32_e32 v101, v101, v107
	v_max_u32_e32 v0, v0, v1
	v_max_u32_e32 v1, v94, v97
	v_min_u32_e32 v94, v94, v97
	v_max_u32_e32 v97, v3, v105
	v_min_u32_e32 v3, v3, v105
	v_max_u32_e32 v105, v104, v106
	v_min_u32_e32 v104, v104, v106
	v_max_u32_e32 v106, v96, v95
	v_min_u32_e32 v95, v96, v95
	v_max_u32_e32 v96, v102, v100
	v_min_u32_e32 v100, v102, v100
	v_max_u32_e32 v102, v99, v98
	v_min_u32_e32 v98, v99, v98
	v_max_u32_e32 v99, v103, v101
	v_min_u32_e32 v101, v103, v101
	v_max_u32_e32 v103, v2, v0
	v_min_u32_e32 v0, v2, v0
	v_max_u32_e32 v2, v1, v96
	v_min_u32_e32 v1, v1, v96
	v_max_u32_e32 v96, v97, v102
	v_min_u32_e32 v97, v97, v102
	v_max_u32_e32 v102, v105, v99
	v_min_u32_e32 v99, v105, v99
	v_max_u32_e32 v105, v106, v103
	v_min_u32_e32 v103, v106, v103
	v_max_u32_e32 v106, v94, v100
	v_min_u32_e32 v94, v94, v100
	v_max_u32_e32 v100, v3, v98
	v_min_u32_e32 v3, v3, v98
	v_max_u32_e32 v98, v104, v101
	v_min_u32_e32 v101, v104, v101
	v_max_u32_e32 v104, v95, v0
	v_min_u32_e32 v0, v95, v0
	v_max_u32_e32 v95, v2, v102
	v_min_u32_e32 v2, v2, v102
	v_max_u32_e32 v102, v96, v105
	v_min_u32_e32 v96, v96, v105
	v_max_u32_e32 v110, v1, v99
	v_min_u32_e32 v1, v1, v99
	v_max_u32_e32 v99, v97, v103
	v_min_u32_e32 v97, v97, v103
	v_max_u32_e32 v111, v106, v98
	v_min_u32_e32 v98, v106, v98
	v_min_u32_e32 v122, v100, v104
	v_max_u32_e32 v123, v94, v101
	v_min_u32_e32 v94, v94, v101
	v_max_u32_e32 v124, v3, v0
	v_min_u32_e32 v0, v3, v0
	v_max_u32_e32 v112, v100, v104
	v_max_u32_e32 v109, v95, v102
	v_min_u32_e32 v108, v95, v102
	v_max_u32_e32 v107, v2, v96
	v_min_u32_e32 v106, v2, v96
	v_max_u32_e32 v105, v110, v99
	v_min_u32_e32 v104, v110, v99
	v_max_u32_e32 v103, v1, v97
	v_min_u32_e32 v102, v1, v97
	v_max_u32_e32 v99, v98, v122
	v_min_u32_e32 v98, v98, v122
	v_max_u32_e32 v97, v123, v124
	v_min_u32_e32 v96, v123, v124
	v_max_u32_e32 v95, v94, v0
	v_min_u32_e32 v94, v94, v0
	global_load_dwordx4 v[0:3], v[4:5], off offset:1328
	global_load_dwordx4 v[122:125], v[4:5], off offset:1312
	s_waitcnt vmcnt(2)
; __device__ __forceinline__ unsigned f2key(float f) { const unsigned u = __float_as_uint(f); return (u & 0x80000000u) ? ~u : (u | 0x80000000u); }
; __device__ __forceinline__ void peer_tile(const Args& A, LAS unsigned char* lds, int tile) {
;     ...
;                   for (int i = 0; i < 16; ++i) {
;                       const float lo = (float)__builtin_bit_cast(_Float16, (unsigned short)(sw[i] & 0xffffu)), hi = (float)__builtin_bit_cast(_Float16, (unsigned short)(sw[i] >> 16));
;                       const unsigned klo = (f2key(lo) & ~127u) | (unsigned)(127 - (32 * g + 2 * i)), khi = (f2key(hi) & ~127u) | (unsigned)(127 - (32 * g + 2 * i + 1));
;                       if (i < 8) { k0[2 * i] = klo; k0[2 * i + 1] = khi; } else { k1[2 * (i - 8)] = klo; k1[2 * (i - 8) + 1] = khi; } } }
;     ...
;                 for (int i = 0; i < 16; ++i) L2[p][i] = (g & 2) ? ((g & 1) ? LA[3][p][i] : LA[2][p][i]) : ((g & 1) ? LA[1][p][i] : LA[0][p][i]);
	v_cvt_f32_f16_sdwa v110, v118 dst_sel:DWORD dst_unused:UNUSED_PAD src0_sel:WORD_1
	v_max_u32_e32 v101, v111, v112
	v_min_u32_e32 v100, v111, v112
	v_cvt_f32_f16_e32 v111, v118
	v_not_b32_e32 v112, v110
	v_or_b32_e32 v118, 0x80000000, v110
	v_cmp_gt_i32_e32 vcc, 0, v110
	v_cndmask_b32_e64 v30, v62, v30, s[0:1]
	s_nop 0
	v_cndmask_b32_e32 v110, v118, v112, vcc
	v_not_b32_e32 v112, v111
	v_or_b32_e32 v118, 0x80000000, v111
	v_cmp_gt_i32_e32 vcc, 0, v111
	v_and_b32_e32 v110, 0xffffff80, v110
	v_sub_u32_e32 v110, v110, v15
	v_cndmask_b32_e32 v111, v118, v112, vcc
	v_cvt_f32_f16_sdwa v112, v119 dst_sel:DWORD dst_unused:UNUSED_PAD src0_sel:WORD_1
	v_cvt_f32_f16_e32 v118, v119
	v_and_b32_e32 v111, 0xffffff80, v111
	v_sub_u32_e32 v111, v111, v15
	v_not_b32_e32 v119, v112
	v_or_b32_e32 v126, 0x80000000, v112
	v_cmp_gt_i32_e32 vcc, 0, v112
	v_add_u32_e32 v110, 0x7e, v110
	v_add_u32_e32 v111, 0x7f, v111
	v_cndmask_b32_e32 v112, v126, v119, vcc
	v_not_b32_e32 v119, v118
	v_or_b32_e32 v126, 0x80000000, v118
	v_cmp_gt_i32_e32 vcc, 0, v118
	v_and_b32_e32 v112, 0xffffff80, v112
	v_sub_u32_e32 v112, v112, v14
	v_cndmask_b32_e32 v118, v126, v119, vcc
	v_cvt_f32_f16_sdwa v119, v120 dst_sel:DWORD dst_unused:UNUSED_PAD src0_sel:WORD_1
	v_cvt_f32_f16_e32 v120, v120
	v_and_b32_e32 v118, 0xffffff80, v118
	v_sub_u32_e32 v118, v118, v14
	v_not_b32_e32 v126, v119
	v_or_b32_e32 v127, 0x80000000, v119
	v_cmp_gt_i32_e32 vcc, 0, v119
	v_add_u32_e32 v112, 0x7e, v112
	v_add_u32_e32 v118, 0x7f, v118
	v_cndmask_b32_e32 v119, v127, v126, vcc
	v_not_b32_e32 v126, v120
	v_or_b32_e32 v127, 0x80000000, v120
	v_cmp_gt_i32_e32 vcc, 0, v120
	v_and_b32_e32 v119, 0xffffff80, v119
	v_sub_u32_e32 v119, v119, v12
	v_cndmask_b32_e32 v120, v127, v126, vcc
	v_cvt_f32_f16_sdwa v126, v121 dst_sel:DWORD dst_unused:UNUSED_PAD src0_sel:WORD_1
	v_cvt_f32_f16_e32 v121, v121
	v_and_b32_e32 v120, 0xffffff80, v120
	v_sub_u32_e32 v120, v120, v12
	v_not_b32_e32 v127, v126
	v_or_b32_e32 v128, 0x80000000, v126
	v_cmp_gt_i32_e32 vcc, 0, v126
	v_add_u32_e32 v119, 0x7e, v119
	v_add_u32_e32 v120, 0x7f, v120
	v_cndmask_b32_e32 v126, v128, v127, vcc
	v_not_b32_e32 v127, v121
	v_or_b32_e32 v128, 0x80000000, v121
	v_cmp_gt_i32_e32 vcc, 0, v121
	v_and_b32_e32 v126, 0xffffff80, v126
	v_sub_u32_e32 v126, v126, v10
	v_cndmask_b32_e32 v121, v128, v127, vcc
	v_cvt_f32_f16_sdwa v127, v114 dst_sel:DWORD dst_unused:UNUSED_PAD src0_sel:WORD_1
	v_cvt_f32_f16_e32 v114, v114
	v_and_b32_e32 v121, 0xffffff80, v121
	v_sub_u32_e32 v121, v121, v10
	v_not_b32_e32 v128, v127
	v_or_b32_e32 v129, 0x80000000, v127
	v_cmp_gt_i32_e32 vcc, 0, v127
	v_add_u32_e32 v126, 0x7e, v126
	v_add_u32_e32 v121, 0x7f, v121
	v_cndmask_b32_e32 v127, v129, v128, vcc
	v_not_b32_e32 v128, v114
	v_or_b32_e32 v129, 0x80000000, v114
	v_cmp_gt_i32_e32 vcc, 0, v114
	v_and_b32_e32 v127, 0xffffff80, v127
	v_sub_u32_e32 v127, v127, v8
	v_cndmask_b32_e32 v114, v129, v128, vcc
	v_cvt_f32_f16_sdwa v128, v115 dst_sel:DWORD dst_unused:UNUSED_PAD src0_sel:WORD_1
	v_cvt_f32_f16_e32 v115, v115
	v_and_b32_e32 v114, 0xffffff80, v114
	v_sub_u32_e32 v114, v114, v8
	v_not_b32_e32 v129, v128
	v_or_b32_e32 v130, 0x80000000, v128
	v_cmp_gt_i32_e32 vcc, 0, v128
	v_add_u32_e32 v127, 0x7e, v127
	v_add_u32_e32 v114, 0x7f, v114
	v_cndmask_b32_e32 v128, v130, v129, vcc
	v_not_b32_e32 v129, v115
	v_or_b32_e32 v130, 0x80000000, v115
	v_cmp_gt_i32_e32 vcc, 0, v115
	v_and_b32_e32 v128, 0xffffff80, v128
	v_sub_u32_e32 v128, v128, v16
	v_cndmask_b32_e32 v115, v130, v129, vcc
	v_cvt_f32_f16_sdwa v129, v116 dst_sel:DWORD dst_unused:UNUSED_PAD src0_sel:WORD_1
	v_cvt_f32_f16_e32 v116, v116
	v_and_b32_e32 v115, 0xffffff80, v115
	v_sub_u32_e32 v115, v115, v16
	v_not_b32_e32 v130, v129
	v_or_b32_e32 v131, 0x80000000, v129
	v_cmp_gt_i32_e32 vcc, 0, v129
	v_add_u32_e32 v128, 0x7e, v128
	v_add_u32_e32 v115, 0x7f, v115
	v_cndmask_b32_e32 v129, v131, v130, vcc
	v_not_b32_e32 v130, v116
	v_or_b32_e32 v131, 0x80000000, v116
	v_cmp_gt_i32_e32 vcc, 0, v116
	v_and_b32_e32 v129, 0xffffff80, v129
	v_sub_u32_e32 v129, v129, v17
	v_cndmask_b32_e32 v116, v131, v130, vcc
	v_cvt_f32_f16_sdwa v130, v117 dst_sel:DWORD dst_unused:UNUSED_PAD src0_sel:WORD_1
	v_cvt_f32_f16_e32 v117, v117
	v_and_b32_e32 v116, 0xffffff80, v116
	v_sub_u32_e32 v116, v116, v17
	v_not_b32_e32 v131, v130
	v_or_b32_e32 v132, 0x80000000, v130
	v_cmp_gt_i32_e32 vcc, 0, v130
	v_add_u32_e32 v129, 0x7e, v129
	v_add_u32_e32 v116, 0x7f, v116
	v_cndmask_b32_e32 v130, v132, v131, vcc
	v_not_b32_e32 v131, v117
	v_or_b32_e32 v132, 0x80000000, v117
	v_cmp_gt_i32_e32 vcc, 0, v117
	v_and_b32_e32 v130, 0xffffff80, v130
	v_sub_u32_e32 v130, v130, v18
	v_cndmask_b32_e32 v117, v132, v131, vcc
	s_waitcnt vmcnt(0)
; __device__ __forceinline__ unsigned f2key(float f) { const unsigned u = __float_as_uint(f); return (u & 0x80000000u) ? ~u : (u | 0x80000000u); }
; #define CE_DESC(a, b) do { const unsigned _mx = (a) > (b) ? (a) : (b), _mn = (a) > (b) ? (b) : (a); (a) = _mx; (b) = _mn; } while (0)
; __device__ __forceinline__ void sort16_desc(unsigned (&k)[16]) {
; #pragma unroll
;     for (int size = 2; size <= 16; size <<= 1)
; #pragma unroll
;         for (int stride = size >> 1; stride > 0; stride >>= 1)
; #pragma unroll
;             for (int i = 0; i < 16; ++i) { const int j = i ^ stride;
;                 if (j > i) { if ((i & size) == 0) CE_DESC(k[i], k[j]); else CE_DESC(k[j], k[i]); } }
; }
; __device__ __forceinline__ void peer_tile(const Args& A, LAS unsigned char* lds, int tile) {
;     ...
;                   for (int i = 0; i < 16; ++i) {
;                       const float lo = (float)__builtin_bit_cast(_Float16, (unsigned short)(sw[i] & 0xffffu)), hi = (float)__builtin_bit_cast(_Float16, (unsigned short)(sw[i] >> 16));
;                       const unsigned klo = (f2key(lo) & ~127u) | (unsigned)(127 - (32 * g + 2 * i)), khi = (f2key(hi) & ~127u) | (unsigned)(127 - (32 * g + 2 * i + 1));
;                       if (i < 8) { k0[2 * i] = klo; k0[2 * i + 1] = khi; } else { k1[2 * (i - 8)] = klo; k1[2 * (i - 8) + 1] = khi; } } }
;                 sort16_desc(k0); sort16_desc(k1); merge16(k0, k1);
	v_cvt_f32_f16_sdwa v131, v122 dst_sel:DWORD dst_unused:UNUSED_PAD src0_sel:WORD_1
	v_cvt_f32_f16_e32 v122, v122
	v_and_b32_e32 v117, 0xffffff80, v117
	v_sub_u32_e32 v117, v117, v18
	v_not_b32_e32 v132, v131
	v_or_b32_e32 v133, 0x80000000, v131
	v_cmp_gt_i32_e32 vcc, 0, v131
	v_add_u32_e32 v130, 0x7e, v130
	v_add_u32_e32 v117, 0x7f, v117
	v_cndmask_b32_e32 v131, v133, v132, vcc
	v_not_b32_e32 v132, v122
	v_or_b32_e32 v133, 0x80000000, v122
	v_cmp_gt_i32_e32 vcc, 0, v122
	v_and_b32_e32 v131, 0xffffff80, v131
	v_sub_u32_e32 v131, v131, v20
	v_cndmask_b32_e32 v122, v133, v132, vcc
	v_cvt_f32_f16_sdwa v132, v123 dst_sel:DWORD dst_unused:UNUSED_PAD src0_sel:WORD_1
	v_cvt_f32_f16_e32 v123, v123
	v_and_b32_e32 v122, 0xffffff80, v122
	v_sub_u32_e32 v122, v122, v20
	v_not_b32_e32 v133, v132
	v_or_b32_e32 v134, 0x80000000, v132
	v_cmp_gt_i32_e32 vcc, 0, v132
	v_add_u32_e32 v131, 0x7e, v131
	v_add_u32_e32 v122, 0x7f, v122
	v_cndmask_b32_e32 v132, v134, v133, vcc
	v_not_b32_e32 v133, v123
	v_or_b32_e32 v134, 0x80000000, v123
	v_cmp_gt_i32_e32 vcc, 0, v123
	v_and_b32_e32 v132, 0xffffff80, v132
	v_sub_u32_e32 v132, v132, v21
	v_cndmask_b32_e32 v123, v134, v133, vcc
	v_cvt_f32_f16_sdwa v133, v124 dst_sel:DWORD dst_unused:UNUSED_PAD src0_sel:WORD_1
	v_cvt_f32_f16_e32 v124, v124
	v_and_b32_e32 v123, 0xffffff80, v123
	v_sub_u32_e32 v123, v123, v21
	v_not_b32_e32 v134, v133
	v_or_b32_e32 v135, 0x80000000, v133
	v_cmp_gt_i32_e32 vcc, 0, v133
	v_add_u32_e32 v132, 0x7e, v132
	v_add_u32_e32 v123, 0x7f, v123
	v_cndmask_b32_e32 v133, v135, v134, vcc
	v_not_b32_e32 v134, v124
	v_or_b32_e32 v135, 0x80000000, v124
	v_cmp_gt_i32_e32 vcc, 0, v124
	v_and_b32_e32 v133, 0xffffff80, v133
	v_sub_u32_e32 v133, v133, v22
	v_cndmask_b32_e32 v124, v135, v134, vcc
	v_cvt_f32_f16_sdwa v134, v125 dst_sel:DWORD dst_unused:UNUSED_PAD src0_sel:WORD_1
	v_cvt_f32_f16_e32 v125, v125
	v_and_b32_e32 v124, 0xffffff80, v124
	v_sub_u32_e32 v124, v124, v22
	v_not_b32_e32 v135, v134
	v_or_b32_e32 v136, 0x80000000, v134
	v_cmp_gt_i32_e32 vcc, 0, v134
	v_add_u32_e32 v133, 0x7e, v133
	v_add_u32_e32 v124, 0x7f, v124
	v_cndmask_b32_e32 v134, v136, v135, vcc
	v_not_b32_e32 v135, v125
	v_or_b32_e32 v136, 0x80000000, v125
	v_cmp_gt_i32_e32 vcc, 0, v125
	v_and_b32_e32 v134, 0xffffff80, v134
	v_sub_u32_e32 v134, v134, v23
	v_cndmask_b32_e32 v125, v136, v135, vcc
	v_cvt_f32_f16_sdwa v135, v0 dst_sel:DWORD dst_unused:UNUSED_PAD src0_sel:WORD_1
	v_cvt_f32_f16_e32 v0, v0
	v_and_b32_e32 v125, 0xffffff80, v125
	v_sub_u32_e32 v125, v125, v23
	v_not_b32_e32 v136, v135
	v_or_b32_e32 v137, 0x80000000, v135
	v_cmp_gt_i32_e32 vcc, 0, v135
	v_add_u32_e32 v134, 0x7e, v134
	v_add_u32_e32 v125, 0x7f, v125
	v_cndmask_b32_e32 v135, v137, v136, vcc
	v_not_b32_e32 v136, v0
	v_or_b32_e32 v137, 0x80000000, v0
	v_cmp_gt_i32_e32 vcc, 0, v0
	v_and_b32_e32 v135, 0xffffff80, v135
	v_sub_u32_e32 v135, v135, v24
	v_cndmask_b32_e32 v0, v137, v136, vcc
	v_cvt_f32_f16_sdwa v136, v1 dst_sel:DWORD dst_unused:UNUSED_PAD src0_sel:WORD_1
	v_cvt_f32_f16_e32 v1, v1
	v_and_b32_e32 v0, 0xffffff80, v0
	v_sub_u32_e32 v0, v0, v24
	v_not_b32_e32 v137, v136
	v_or_b32_e32 v138, 0x80000000, v136
	v_cmp_gt_i32_e32 vcc, 0, v136
	v_add_u32_e32 v135, 0x7e, v135
	v_add_u32_e32 v0, 0x7f, v0
	v_cndmask_b32_e32 v136, v138, v137, vcc
	v_not_b32_e32 v137, v1
	v_or_b32_e32 v138, 0x80000000, v1
	v_cmp_gt_i32_e32 vcc, 0, v1
	v_and_b32_e32 v136, 0xffffff80, v136
	v_sub_u32_e32 v136, v136, v25
	v_cndmask_b32_e32 v1, v138, v137, vcc
	v_cvt_f32_f16_sdwa v137, v2 dst_sel:DWORD dst_unused:UNUSED_PAD src0_sel:WORD_1
	v_cvt_f32_f16_e32 v2, v2
	v_and_b32_e32 v1, 0xffffff80, v1
	v_sub_u32_e32 v1, v1, v25
	v_not_b32_e32 v138, v137
	v_or_b32_e32 v139, 0x80000000, v137
	v_cmp_gt_i32_e32 vcc, 0, v137
	v_add_u32_e32 v136, 0x7e, v136
	v_add_u32_e32 v1, 0x7f, v1
	v_cndmask_b32_e32 v137, v139, v138, vcc
	v_not_b32_e32 v138, v2
	v_or_b32_e32 v139, 0x80000000, v2
	v_cmp_gt_i32_e32 vcc, 0, v2
	v_and_b32_e32 v137, 0xffffff80, v137
	v_sub_u32_e32 v137, v137, v26
	v_cndmask_b32_e32 v2, v139, v138, vcc
	v_cvt_f32_f16_sdwa v138, v3 dst_sel:DWORD dst_unused:UNUSED_PAD src0_sel:WORD_1
	v_cvt_f32_f16_e32 v3, v3
	v_and_b32_e32 v2, 0xffffff80, v2
	v_sub_u32_e32 v2, v2, v26
	v_not_b32_e32 v139, v138
	v_or_b32_e32 v140, 0x80000000, v138
	v_cmp_gt_i32_e32 vcc, 0, v138
	v_add_u32_e32 v137, 0x7e, v137
	v_add_u32_e32 v2, 0x7f, v2
	v_cndmask_b32_e32 v138, v140, v139, vcc
	v_not_b32_e32 v139, v3
	v_or_b32_e32 v140, 0x80000000, v3
	v_cmp_gt_i32_e32 vcc, 0, v3
	v_and_b32_e32 v138, 0xffffff80, v138
	v_sub_u32_e32 v138, v138, v28
	v_cndmask_b32_e32 v3, v140, v139, vcc
	v_and_b32_e32 v3, 0xffffff80, v3
	v_sub_u32_e32 v3, v3, v28
	v_add_u32_e32 v138, 0x7e, v138
	v_add_u32_e32 v3, 0x7f, v3
	v_max_u32_e32 v139, v111, v110
	v_min_u32_e32 v110, v111, v110
	v_max_u32_e32 v111, v112, v118
	v_min_u32_e32 v112, v112, v118
	v_max_u32_e32 v118, v120, v119
	v_min_u32_e32 v119, v120, v119
	v_max_u32_e32 v120, v126, v121
	v_min_u32_e32 v121, v126, v121
	v_max_u32_e32 v126, v114, v127
	v_min_u32_e32 v114, v114, v127
	v_max_u32_e32 v127, v128, v115
	v_min_u32_e32 v115, v128, v115
	v_max_u32_e32 v128, v116, v129
	v_min_u32_e32 v116, v116, v129
	v_max_u32_e32 v129, v130, v117
	v_min_u32_e32 v117, v130, v117
	v_max_u32_e32 v147, v122, v131
	v_min_u32_e32 v122, v122, v131
	v_max_u32_e32 v131, v132, v123
	v_min_u32_e32 v123, v132, v123
	v_max_u32_e32 v132, v124, v133
	v_min_u32_e32 v124, v124, v133
	v_max_u32_e32 v133, v134, v125
	v_min_u32_e32 v125, v134, v125
	v_max_u32_e32 v134, v0, v135
	v_min_u32_e32 v0, v0, v135
	v_max_u32_e32 v135, v136, v1
	v_min_u32_e32 v1, v136, v1
	v_max_u32_e32 v136, v2, v137
	v_min_u32_e32 v2, v2, v137
; #define CE_DESC(a, b) do { const unsigned _mx = (a) > (b) ? (a) : (b), _mn = (a) > (b) ? (b) : (a); (a) = _mx; (b) = _mn; } while (0)
; __device__ __forceinline__ void sort16_desc(unsigned (&k)[16]) {
; #pragma unroll
;     for (int size = 2; size <= 16; size <<= 1)
; #pragma unroll
;         for (int stride = size >> 1; stride > 0; stride >>= 1)
; #pragma unroll
;             for (int i = 0; i < 16; ++i) { const int j = i ^ stride;
;                 if (j > i) { if ((i & size) == 0) CE_DESC(k[i], k[j]); else CE_DESC(k[j], k[i]); } }
; }
; __device__ __forceinline__ void merge16(unsigned (&a)[16], const unsigned (&b)[16]) {
; #pragma unroll
;     for (int i = 0; i < 16; ++i) a[i] = a[i] > b[15 - i] ? a[i] : b[15 - i];
; #pragma unroll
;     for (int stride = 8; stride > 0; stride >>= 1)
; #pragma unroll
;         for (int i = 0; i < 16; ++i) { const int j = i ^ stride; if (j > i) CE_DESC(a[i], a[j]); }
; }
; __device__ __forceinline__ void peer_tile(const Args& A, LAS unsigned char* lds, int tile) {
;     ...
;                 sort16_desc(k0); sort16_desc(k1); merge16(k0, k1);
; #pragma unroll
;                 for (int msk = 16; msk <= 32; msk <<= 1) {
; #pragma unroll
;                     for (int i = 0; i < 16; ++i) k1[i] = (unsigned)__shfl_xor((int)k0[i], msk);
;                     merge16(k0, k1); }
	v_max_u32_e32 v137, v138, v3
	v_min_u32_e32 v3, v138, v3
	v_max_u32_e32 v130, v139, v112
	v_min_u32_e32 v112, v139, v112
	v_max_u32_e32 v139, v110, v111
	v_min_u32_e32 v110, v110, v111
	v_max_u32_e32 v111, v121, v118
	v_min_u32_e32 v118, v121, v118
	v_max_u32_e32 v121, v120, v119
	v_min_u32_e32 v119, v120, v119
	v_max_u32_e32 v120, v126, v115
	v_min_u32_e32 v115, v126, v115
	v_max_u32_e32 v126, v114, v127
	v_min_u32_e32 v114, v114, v127
	v_max_u32_e32 v127, v117, v128
	v_min_u32_e32 v117, v117, v128
	v_max_u32_e32 v128, v129, v116
	v_min_u32_e32 v116, v129, v116
	v_max_u32_e32 v138, v147, v123
	v_min_u32_e32 v123, v147, v123
	v_max_u32_e32 v147, v122, v131
	v_min_u32_e32 v122, v122, v131
	v_max_u32_e32 v131, v125, v132
	v_min_u32_e32 v125, v125, v132
	v_max_u32_e32 v132, v133, v124
	v_min_u32_e32 v124, v133, v124
	v_max_u32_e32 v133, v134, v1
	v_min_u32_e32 v1, v134, v1
	v_max_u32_e32 v134, v0, v135
	v_min_u32_e32 v0, v0, v135
	v_max_u32_e32 v135, v3, v136
	v_min_u32_e32 v3, v3, v136
	v_max_u32_e32 v136, v137, v2
	v_min_u32_e32 v2, v137, v2
	v_max_u32_e32 v129, v130, v139
	v_min_u32_e32 v130, v130, v139
	v_max_u32_e32 v139, v112, v110
	v_min_u32_e32 v110, v112, v110
	v_max_u32_e32 v112, v119, v118
	v_min_u32_e32 v118, v119, v118
	v_max_u32_e32 v119, v121, v111
	v_min_u32_e32 v111, v121, v111
	v_max_u32_e32 v121, v120, v126
	v_min_u32_e32 v120, v120, v126
	v_max_u32_e32 v126, v115, v114
	v_min_u32_e32 v114, v115, v114
	v_max_u32_e32 v115, v116, v117
	v_min_u32_e32 v116, v116, v117
	v_max_u32_e32 v117, v128, v127
	v_min_u32_e32 v127, v128, v127
	v_max_u32_e32 v137, v138, v147
	v_min_u32_e32 v138, v138, v147
	v_max_u32_e32 v147, v123, v122
	v_min_u32_e32 v122, v123, v122
	v_max_u32_e32 v123, v124, v125
	v_min_u32_e32 v124, v124, v125
	v_max_u32_e32 v125, v132, v131
	v_min_u32_e32 v131, v132, v131
	v_max_u32_e32 v132, v133, v134
	v_min_u32_e32 v133, v133, v134
	v_max_u32_e32 v134, v1, v0
	v_min_u32_e32 v0, v1, v0
	v_max_u32_e32 v1, v2, v3
	v_min_u32_e32 v2, v2, v3
	v_max_u32_e32 v3, v136, v135
	v_min_u32_e32 v135, v136, v135
	v_max_u32_e32 v128, v129, v118
	v_min_u32_e32 v118, v129, v118
	v_max_u32_e32 v129, v130, v112
	v_min_u32_e32 v112, v130, v112
	v_max_u32_e32 v130, v139, v111
	v_min_u32_e32 v111, v139, v111
	v_max_u32_e32 v139, v110, v119
	v_min_u32_e32 v110, v110, v119
	v_max_u32_e32 v119, v116, v121
	v_min_u32_e32 v116, v116, v121
	v_max_u32_e32 v121, v115, v120
	v_min_u32_e32 v115, v115, v120
	v_max_u32_e32 v120, v127, v126
	v_min_u32_e32 v126, v127, v126
	v_max_u32_e32 v127, v117, v114
	v_min_u32_e32 v114, v117, v114
	v_max_u32_e32 v136, v137, v124
	v_min_u32_e32 v124, v137, v124
	v_max_u32_e32 v137, v138, v123
	v_min_u32_e32 v123, v138, v123
	v_max_u32_e32 v138, v147, v131
	v_min_u32_e32 v131, v147, v131
	v_max_u32_e32 v147, v122, v125
	v_min_u32_e32 v122, v122, v125
	v_max_u32_e32 v125, v2, v132
	v_min_u32_e32 v2, v2, v132
	v_max_u32_e32 v132, v1, v133
	v_min_u32_e32 v1, v1, v133
	v_max_u32_e32 v133, v135, v134
	v_min_u32_e32 v134, v135, v134
	v_max_u32_e32 v135, v3, v0
	v_min_u32_e32 v0, v3, v0
	v_max_u32_e32 v117, v128, v130
	v_min_u32_e32 v128, v128, v130
	v_max_u32_e32 v130, v129, v139
	v_min_u32_e32 v129, v129, v139
	v_max_u32_e32 v139, v118, v111
	v_min_u32_e32 v111, v118, v111
	v_max_u32_e32 v118, v112, v110
	v_min_u32_e32 v110, v112, v110
	v_max_u32_e32 v112, v126, v116
	v_min_u32_e32 v116, v126, v116
	v_max_u32_e32 v126, v114, v115
	v_min_u32_e32 v114, v114, v115
	v_max_u32_e32 v115, v120, v119
	v_min_u32_e32 v119, v120, v119
	v_max_u32_e32 v120, v127, v121
	v_min_u32_e32 v121, v127, v121
	v_max_u32_e32 v3, v136, v138
	v_min_u32_e32 v136, v136, v138
	v_max_u32_e32 v138, v137, v147
	v_min_u32_e32 v137, v137, v147
	v_max_u32_e32 v147, v124, v131
	v_min_u32_e32 v124, v124, v131
	v_max_u32_e32 v131, v123, v122
	v_min_u32_e32 v122, v123, v122
	v_max_u32_e32 v123, v134, v2
	v_min_u32_e32 v2, v134, v2
	v_max_u32_e32 v134, v0, v1
	v_min_u32_e32 v0, v0, v1
	v_max_u32_e32 v1, v133, v125
	v_min_u32_e32 v125, v133, v125
	v_max_u32_e32 v133, v135, v132
	v_min_u32_e32 v132, v135, v132
	v_max_u32_e32 v127, v117, v130
	v_min_u32_e32 v117, v117, v130
	v_max_u32_e32 v130, v128, v129
	v_min_u32_e32 v128, v128, v129
	v_max_u32_e32 v129, v139, v118
	v_min_u32_e32 v118, v139, v118
	v_max_u32_e32 v139, v111, v110
	v_min_u32_e32 v110, v111, v110
	v_max_u32_e32 v111, v114, v116
	v_min_u32_e32 v114, v114, v116
	v_max_u32_e32 v116, v126, v112
	v_min_u32_e32 v112, v126, v112
	v_max_u32_e32 v126, v121, v119
	v_min_u32_e32 v119, v121, v119
	v_max_u32_e32 v121, v120, v115
	v_min_u32_e32 v115, v120, v115
	v_max_u32_e32 v135, v3, v138
	v_min_u32_e32 v3, v3, v138
	v_max_u32_e32 v138, v136, v137
	v_min_u32_e32 v136, v136, v137
	v_max_u32_e32 v137, v147, v131
	v_min_u32_e32 v131, v147, v131
	v_max_u32_e32 v147, v124, v122
	v_min_u32_e32 v122, v124, v122
	v_max_u32_e32 v124, v0, v2
	v_min_u32_e32 v0, v0, v2
	v_max_u32_e32 v2, v134, v123
	v_min_u32_e32 v123, v134, v123
	v_max_u32_e32 v134, v132, v125
	v_min_u32_e32 v125, v132, v125
	v_max_u32_e32 v132, v133, v1
	v_min_u32_e32 v1, v133, v1
	v_max_u32_e32 v120, v127, v114
	v_min_u32_e32 v114, v127, v114
	v_max_u32_e32 v127, v117, v111
	v_min_u32_e32 v111, v117, v111
	v_max_u32_e32 v117, v130, v112
	v_min_u32_e32 v112, v130, v112
	v_max_u32_e32 v130, v128, v116
	v_min_u32_e32 v116, v128, v116
	v_max_u32_e32 v128, v129, v119
	v_min_u32_e32 v119, v129, v119
	v_max_u32_e32 v129, v118, v126
	v_min_u32_e32 v118, v118, v126
	v_max_u32_e32 v126, v139, v115
	v_min_u32_e32 v115, v139, v115
	v_max_u32_e32 v139, v110, v121
	v_min_u32_e32 v110, v110, v121
	v_max_u32_e32 v133, v135, v0
	v_min_u32_e32 v0, v135, v0
; #define CE_DESC(a, b) do { const unsigned _mx = (a) > (b) ? (a) : (b), _mn = (a) > (b) ? (b) : (a); (a) = _mx; (b) = _mn; } while (0)
; __device__ __forceinline__ void sort16_desc(unsigned (&k)[16]) {
; #pragma unroll
;     for (int size = 2; size <= 16; size <<= 1)
; #pragma unroll
;         for (int stride = size >> 1; stride > 0; stride >>= 1)
; #pragma unroll
;             for (int i = 0; i < 16; ++i) { const int j = i ^ stride;
;                 if (j > i) { if ((i & size) == 0) CE_DESC(k[i], k[j]); else CE_DESC(k[j], k[i]); } }
; }
; __device__ __forceinline__ void merge16(unsigned (&a)[16], const unsigned (&b)[16]) {
; #pragma unroll
;     for (int i = 0; i < 16; ++i) a[i] = a[i] > b[15 - i] ? a[i] : b[15 - i];
; #pragma unroll
;     for (int stride = 8; stride > 0; stride >>= 1)
; #pragma unroll
;         for (int i = 0; i < 16; ++i) { const int j = i ^ stride; if (j > i) CE_DESC(a[i], a[j]); }
; }
; __device__ __forceinline__ void peer_tile(const Args& A, LAS unsigned char* lds, int tile) {
;     ...
;                 sort16_desc(k0); sort16_desc(k1); merge16(k0, k1);
; #pragma unroll
;                 for (int msk = 16; msk <= 32; msk <<= 1) {
; #pragma unroll
;                     for (int i = 0; i < 16; ++i) k1[i] = (unsigned)__shfl_xor((int)k0[i], msk);
;                     merge16(k0, k1); }
	v_max_u32_e32 v135, v3, v124
	v_min_u32_e32 v3, v3, v124
	v_max_u32_e32 v124, v138, v123
	v_min_u32_e32 v123, v138, v123
	v_max_u32_e32 v138, v136, v2
	v_min_u32_e32 v2, v136, v2
	v_max_u32_e32 v136, v137, v125
	v_min_u32_e32 v125, v137, v125
	v_max_u32_e32 v137, v131, v134
	v_min_u32_e32 v131, v131, v134
	v_max_u32_e32 v134, v147, v1
	v_min_u32_e32 v1, v147, v1
	v_max_u32_e32 v147, v122, v132
	v_min_u32_e32 v122, v122, v132
	v_max_u32_e32 v121, v120, v128
	v_min_u32_e32 v120, v120, v128
	v_max_u32_e32 v128, v127, v129
	v_min_u32_e32 v127, v127, v129
	v_max_u32_e32 v129, v117, v126
	v_min_u32_e32 v117, v117, v126
	v_max_u32_e32 v126, v130, v139
	v_min_u32_e32 v130, v130, v139
	v_max_u32_e32 v139, v114, v119
	v_min_u32_e32 v114, v114, v119
	v_max_u32_e32 v119, v111, v118
	v_min_u32_e32 v111, v111, v118
	v_max_u32_e32 v118, v112, v115
	v_min_u32_e32 v112, v112, v115
	v_max_u32_e32 v115, v116, v110
	v_min_u32_e32 v110, v116, v110
	v_max_u32_e32 v132, v133, v136
	v_min_u32_e32 v133, v133, v136
	v_max_u32_e32 v136, v135, v137
	v_min_u32_e32 v135, v135, v137
	v_max_u32_e32 v137, v124, v134
	v_min_u32_e32 v124, v124, v134
	v_max_u32_e32 v134, v138, v147
	v_min_u32_e32 v138, v138, v147
	v_max_u32_e32 v147, v0, v125
	v_min_u32_e32 v0, v0, v125
	v_max_u32_e32 v125, v3, v131
	v_min_u32_e32 v3, v3, v131
	v_max_u32_e32 v131, v123, v1
	v_min_u32_e32 v1, v123, v1
	v_max_u32_e32 v123, v2, v122
	v_min_u32_e32 v2, v2, v122
	v_max_u32_e32 v116, v121, v129
	v_min_u32_e32 v121, v121, v129
	v_max_u32_e32 v129, v128, v126
	v_min_u32_e32 v126, v128, v126
	v_max_u32_e32 v128, v120, v117
	v_min_u32_e32 v117, v120, v117
	v_max_u32_e32 v120, v127, v130
	v_min_u32_e32 v127, v127, v130
	v_max_u32_e32 v130, v139, v118
	v_min_u32_e32 v118, v139, v118
	v_max_u32_e32 v139, v119, v115
	v_min_u32_e32 v115, v119, v115
	v_max_u32_e32 v119, v114, v112
	v_min_u32_e32 v112, v114, v112
	v_max_u32_e32 v114, v111, v110
	v_min_u32_e32 v110, v111, v110
	v_max_u32_e32 v122, v132, v137
	v_min_u32_e32 v132, v132, v137
	v_max_u32_e32 v137, v136, v134
	v_min_u32_e32 v134, v136, v134
	v_max_u32_e32 v136, v133, v124
	v_min_u32_e32 v124, v133, v124
	v_max_u32_e32 v133, v135, v138
	v_min_u32_e32 v135, v135, v138
	v_max_u32_e32 v138, v147, v131
	v_min_u32_e32 v131, v147, v131
	v_max_u32_e32 v147, v125, v123
	v_min_u32_e32 v123, v125, v123
	v_max_u32_e32 v125, v0, v1
	v_min_u32_e32 v0, v0, v1
	v_max_u32_e32 v1, v3, v2
	v_min_u32_e32 v2, v3, v2
	v_min_u32_e32 v111, v116, v129
	v_min_u32_e32 v140, v121, v126
	v_min_u32_e32 v141, v128, v120
	v_min_u32_e32 v142, v117, v127
	v_min_u32_e32 v143, v130, v139
	v_min_u32_e32 v144, v118, v115
	v_min_u32_e32 v145, v119, v114
	v_min_u32_e32 v146, v112, v110
	v_min_u32_e32 v3, v122, v137
	v_min_u32_e32 v148, v132, v134
	v_min_u32_e32 v149, v136, v133
	v_min_u32_e32 v150, v124, v135
	v_min_u32_e32 v151, v138, v147
	v_min_u32_e32 v152, v131, v123
	v_min_u32_e32 v153, v125, v1
	v_min_u32_e32 v154, v0, v2
	v_max3_u32 v116, v116, v129, v154
	v_max3_u32 v0, v111, v0, v2
	v_max3_u32 v2, v121, v126, v153
	v_max3_u32 v1, v140, v125, v1
	v_max3_u32 v111, v128, v120, v152
	v_max3_u32 v120, v141, v131, v123
	v_max3_u32 v117, v117, v127, v151
	v_max3_u32 v121, v142, v138, v147
	v_max3_u32 v123, v130, v139, v150
	v_max3_u32 v124, v143, v124, v135
	v_max3_u32 v115, v118, v115, v149
	v_max3_u32 v118, v144, v136, v133
	v_max3_u32 v114, v119, v114, v148
	v_max3_u32 v119, v145, v132, v134
	v_max3_u32 v3, v112, v110, v3
	v_max3_u32 v110, v146, v122, v137
	v_max_u32_e32 v112, v116, v123
	v_min_u32_e32 v116, v116, v123
	v_max_u32_e32 v122, v0, v124
	v_min_u32_e32 v0, v0, v124
	v_max_u32_e32 v123, v2, v115
	v_min_u32_e32 v2, v2, v115
	v_max_u32_e32 v115, v1, v118
	v_min_u32_e32 v1, v1, v118
	v_max_u32_e32 v118, v111, v114
	v_min_u32_e32 v111, v111, v114
	v_max_u32_e32 v114, v120, v119
	v_min_u32_e32 v119, v120, v119
	v_max_u32_e32 v120, v117, v3
	v_min_u32_e32 v3, v117, v3
	v_max_u32_e32 v117, v121, v110
	v_min_u32_e32 v110, v121, v110
	v_max_u32_e32 v121, v112, v118
	v_min_u32_e32 v112, v112, v118
	v_max_u32_e32 v118, v122, v114
	v_min_u32_e32 v114, v122, v114
	v_max_u32_e32 v122, v123, v120
	v_min_u32_e32 v120, v123, v120
	v_max_u32_e32 v123, v115, v117
	v_min_u32_e32 v115, v115, v117
	v_max_u32_e32 v117, v116, v111
	v_min_u32_e32 v111, v116, v111
	v_max_u32_e32 v116, v0, v119
	v_min_u32_e32 v0, v0, v119
	v_max_u32_e32 v119, v2, v3
	v_min_u32_e32 v2, v2, v3
	v_max_u32_e32 v3, v1, v110
	v_min_u32_e32 v1, v1, v110
	v_max_u32_e32 v110, v121, v122
	v_min_u32_e32 v121, v121, v122
	v_max_u32_e32 v122, v118, v123
	v_min_u32_e32 v118, v118, v123
	v_max_u32_e32 v123, v112, v120
	v_min_u32_e32 v112, v112, v120
	v_max_u32_e32 v120, v114, v115
	v_min_u32_e32 v114, v114, v115
	v_max_u32_e32 v115, v117, v119
	v_min_u32_e32 v117, v117, v119
	v_max_u32_e32 v119, v116, v3
	v_min_u32_e32 v3, v116, v3
	v_max_u32_e32 v116, v111, v2
	v_min_u32_e32 v2, v111, v2
	v_max_u32_e32 v111, v0, v1
	v_min_u32_e32 v0, v0, v1
	v_max_u32_e32 v1, v110, v122
	v_min_u32_e32 v110, v110, v122
	v_max_u32_e32 v122, v121, v118
	v_min_u32_e32 v118, v121, v118
	v_max_u32_e32 v121, v123, v120
	v_min_u32_e32 v120, v123, v120
	v_max_u32_e32 v123, v112, v114
	v_min_u32_e32 v112, v112, v114
	v_max_u32_e32 v114, v115, v119
	v_min_u32_e32 v115, v115, v119
	v_max_u32_e32 v119, v117, v3
	v_min_u32_e32 v3, v117, v3
	v_max_u32_e32 v117, v116, v111
	v_min_u32_e32 v111, v116, v111
	v_max_u32_e32 v116, v2, v0
	v_min_u32_e32 v0, v2, v0
	ds_bpermute_b32 v2, v27, v1
	ds_bpermute_b32 v124, v27, v110
	ds_bpermute_b32 v125, v27, v122
	ds_bpermute_b32 v126, v27, v118
	ds_bpermute_b32 v127, v27, v121
	ds_bpermute_b32 v128, v27, v120
	ds_bpermute_b32 v129, v27, v123
	ds_bpermute_b32 v130, v27, v112
	ds_bpermute_b32 v131, v27, v114
	ds_bpermute_b32 v132, v27, v115
	ds_bpermute_b32 v133, v27, v119
	ds_bpermute_b32 v134, v27, v0
	ds_bpermute_b32 v135, v27, v116
	ds_bpermute_b32 v136, v27, v111
	ds_bpermute_b32 v137, v27, v117
	ds_bpermute_b32 v138, v27, v3
	s_waitcnt lgkmcnt(4)
; __device__ __forceinline__ void peer_tile(const Args& A, LAS unsigned char* lds, int tile) {
;     ...
;                 { const bf16_t* sp = QRY + m * 2048 + hp * 128 + 32 * g;
;                   const u32x4 s0 = *(const u32x4*)sp, s1 = *(const u32x4*)(sp + 8), s2 = *(const u32x4*)(sp + 16), s3 = *(const u32x4*)(sp + 24);
;     ...
;                 sort16_desc(k0); sort16_desc(k1); merge16(k0, k1);
; #pragma unroll
;                 for (int msk = 16; msk <= 32; msk <<= 1) {
; #pragma unroll
;                     for (int i = 0; i < 16; ++i) k1[i] = (unsigned)__shfl_xor((int)k0[i], msk);
;                     merge16(k0, k1); }
	v_max_u32_e32 v1, v1, v134
	s_waitcnt lgkmcnt(3)
	v_max_u32_e32 v110, v110, v135
	s_waitcnt lgkmcnt(2)
	v_max_u32_e32 v122, v122, v136
	s_waitcnt lgkmcnt(1)
	v_max_u32_e32 v118, v118, v137
	s_waitcnt lgkmcnt(0)
	v_max_u32_e32 v121, v121, v138
	v_max_u32_e32 v120, v120, v133
	v_max_u32_e32 v123, v123, v132
	v_max_u32_e32 v112, v112, v131
	v_max_u32_e32 v114, v114, v130
	v_max_u32_e32 v115, v115, v129
	v_max_u32_e32 v119, v119, v128
	v_max_u32_e32 v3, v3, v127
	v_max_u32_e32 v117, v117, v126
	v_max_u32_e32 v111, v111, v125
	v_max_u32_e32 v116, v116, v124
	v_max_u32_e32 v0, v0, v2
	v_max_u32_e32 v2, v1, v114
	v_min_u32_e32 v1, v1, v114
	v_max_u32_e32 v114, v110, v115
	v_min_u32_e32 v110, v110, v115
	v_max_u32_e32 v115, v122, v119
	v_min_u32_e32 v119, v122, v119
	v_max_u32_e32 v122, v118, v3
	v_min_u32_e32 v3, v118, v3
	v_max_u32_e32 v118, v121, v117
	v_min_u32_e32 v117, v121, v117
	v_max_u32_e32 v121, v120, v111
	v_min_u32_e32 v111, v120, v111
	v_max_u32_e32 v120, v123, v116
	v_min_u32_e32 v116, v123, v116
	v_max_u32_e32 v123, v112, v0
	v_min_u32_e32 v0, v112, v0
	v_max_u32_e32 v112, v2, v118
	v_min_u32_e32 v2, v2, v118
	v_max_u32_e32 v118, v114, v121
	v_min_u32_e32 v114, v114, v121
	v_max_u32_e32 v121, v115, v120
	v_min_u32_e32 v115, v115, v120
	v_max_u32_e32 v120, v122, v123
	v_min_u32_e32 v122, v122, v123
	v_max_u32_e32 v123, v1, v117
	v_min_u32_e32 v1, v1, v117
	v_max_u32_e32 v117, v110, v111
	v_min_u32_e32 v110, v110, v111
	v_max_u32_e32 v111, v119, v116
	v_min_u32_e32 v116, v119, v116
	v_max_u32_e32 v119, v3, v0
	v_min_u32_e32 v0, v3, v0
	v_max_u32_e32 v3, v112, v121
	v_min_u32_e32 v112, v112, v121
	v_max_u32_e32 v121, v118, v120
	v_min_u32_e32 v118, v118, v120
	v_max_u32_e32 v120, v2, v115
	v_min_u32_e32 v2, v2, v115
	v_max_u32_e32 v115, v114, v122
	v_min_u32_e32 v114, v114, v122
	v_max_u32_e32 v122, v123, v111
	v_min_u32_e32 v111, v123, v111
	v_max_u32_e32 v123, v117, v119
	v_min_u32_e32 v117, v117, v119
	v_max_u32_e32 v119, v1, v116
	v_min_u32_e32 v1, v1, v116
	v_max_u32_e32 v116, v110, v0
	v_min_u32_e32 v0, v110, v0
	v_max_u32_e32 v110, v3, v121
	v_min_u32_e32 v3, v3, v121
	v_max_u32_e32 v121, v112, v118
	v_min_u32_e32 v112, v112, v118
	v_max_u32_e32 v118, v120, v115
	v_min_u32_e32 v115, v120, v115
	v_max_u32_e32 v120, v2, v114
	v_min_u32_e32 v2, v2, v114
	v_max_u32_e32 v114, v122, v123
	v_min_u32_e32 v122, v122, v123
	v_max_u32_e32 v123, v111, v117
	v_min_u32_e32 v111, v111, v117
	v_max_u32_e32 v117, v119, v116
	v_min_u32_e32 v116, v119, v116
	v_max_u32_e32 v119, v1, v0
	v_min_u32_e32 v0, v1, v0
	ds_bpermute_b32 v128, v29, v0
	ds_bpermute_b32 v1, v29, v110
	ds_bpermute_b32 v124, v29, v3
	ds_bpermute_b32 v125, v29, v121
	ds_bpermute_b32 v126, v29, v112
	s_waitcnt lgkmcnt(4)
	v_max_u32_e32 v110, v110, v128
	global_load_dwordx4 v[128:131], v[4:5], off offset:1552
	global_load_dwordx4 v[132:135], v[4:5], off offset:1536
	ds_bpermute_b32 v127, v29, v118
	ds_bpermute_b32 v136, v29, v115
	ds_bpermute_b32 v137, v29, v120
	ds_bpermute_b32 v138, v29, v2
	ds_bpermute_b32 v139, v29, v114
	ds_bpermute_b32 v140, v29, v122
	ds_bpermute_b32 v141, v29, v123
	ds_bpermute_b32 v142, v29, v111
	ds_bpermute_b32 v143, v29, v117
	ds_bpermute_b32 v144, v29, v119
	ds_bpermute_b32 v145, v29, v116
	s_waitcnt lgkmcnt(4)
	v_max_u32_e32 v115, v115, v141
	s_waitcnt lgkmcnt(3)
	v_max_u32_e32 v118, v118, v142
	s_waitcnt lgkmcnt(2)
	v_max_u32_e32 v112, v112, v143
	s_waitcnt lgkmcnt(1)
	v_max_u32_e32 v3, v3, v144
	s_waitcnt lgkmcnt(0)
	v_max_u32_e32 v121, v121, v145
	v_max_u32_e32 v120, v120, v140
	v_max_u32_e32 v2, v2, v139
	v_max_u32_e32 v114, v114, v138
	v_max_u32_e32 v122, v122, v137
	v_max_u32_e32 v123, v123, v136
	v_max_u32_e32 v111, v111, v127
	v_max_u32_e32 v117, v117, v126
	v_max_u32_e32 v116, v116, v125
	v_max_u32_e32 v119, v119, v124
	v_max_u32_e32 v0, v0, v1
	v_max_u32_e32 v1, v110, v114
	v_min_u32_e32 v110, v110, v114
	v_max_u32_e32 v114, v3, v122
	v_min_u32_e32 v3, v3, v122
	v_max_u32_e32 v122, v121, v123
	v_min_u32_e32 v121, v121, v123
	v_max_u32_e32 v123, v112, v111
	v_min_u32_e32 v111, v112, v111
	v_max_u32_e32 v112, v118, v117
	v_min_u32_e32 v117, v118, v117
	v_max_u32_e32 v118, v115, v116
	v_min_u32_e32 v115, v115, v116
	v_max_u32_e32 v116, v120, v119
	v_min_u32_e32 v119, v120, v119
	v_max_u32_e32 v120, v2, v0
	v_min_u32_e32 v0, v2, v0
	v_max_u32_e32 v2, v1, v112
	v_min_u32_e32 v1, v1, v112
	v_max_u32_e32 v112, v114, v118
	v_min_u32_e32 v114, v114, v118
	v_max_u32_e32 v118, v122, v116
	v_min_u32_e32 v116, v122, v116
	v_max_u32_e32 v122, v123, v120
	v_min_u32_e32 v120, v123, v120
	v_max_u32_e32 v123, v110, v117
	v_min_u32_e32 v110, v110, v117
	v_max_u32_e32 v117, v3, v115
	v_min_u32_e32 v3, v3, v115
	v_max_u32_e32 v115, v121, v119
	v_min_u32_e32 v119, v121, v119
	v_max_u32_e32 v121, v111, v0
	v_min_u32_e32 v0, v111, v0
	v_max_u32_e32 v111, v2, v118
	v_min_u32_e32 v2, v2, v118
	v_max_u32_e32 v118, v112, v122
	v_min_u32_e32 v112, v112, v122
	v_max_u32_e32 v127, v1, v116
	v_min_u32_e32 v1, v1, v116
	v_max_u32_e32 v116, v114, v120
	v_min_u32_e32 v114, v114, v120
	v_max_u32_e32 v136, v123, v115
	v_min_u32_e32 v115, v123, v115
	v_max_u32_e32 v137, v117, v121
	v_min_u32_e32 v138, v117, v121
	v_max_u32_e32 v139, v110, v119
	v_min_u32_e32 v110, v110, v119
	v_max_u32_e32 v140, v3, v0
	v_min_u32_e32 v0, v3, v0
	v_max_u32_e32 v126, v111, v118
	v_min_u32_e32 v125, v111, v118
	v_max_u32_e32 v124, v2, v112
	v_min_u32_e32 v123, v2, v112
	v_max_u32_e32 v122, v127, v116
	v_min_u32_e32 v121, v127, v116
	v_max_u32_e32 v120, v1, v114
	v_min_u32_e32 v119, v1, v114
	v_max_u32_e32 v118, v136, v137
	v_min_u32_e32 v117, v136, v137
	v_max_u32_e32 v116, v115, v138
	v_min_u32_e32 v115, v115, v138
	v_max_u32_e32 v114, v139, v140
	v_min_u32_e32 v112, v139, v140
	v_max_u32_e32 v111, v110, v0
	v_min_u32_e32 v110, v110, v0
	global_load_dwordx4 v[0:3], v[4:5], off offset:1584
	global_load_dwordx4 v[136:139], v[4:5], off offset:1568
	s_waitcnt vmcnt(2)
; __device__ __forceinline__ unsigned f2key(float f) { const unsigned u = __float_as_uint(f); return (u & 0x80000000u) ? ~u : (u | 0x80000000u); }
; __device__ __forceinline__ void peer_tile(const Args& A, LAS unsigned char* lds, int tile) {
;     ...
;                 { const bf16_t* sp = QRY + m * 2048 + hp * 128 + 32 * g;
;                   const u32x4 s0 = *(const u32x4*)sp, s1 = *(const u32x4*)(sp + 8), s2 = *(const u32x4*)(sp + 16), s3 = *(const u32x4*)(sp + 24);
;                   const unsigned sw[16] = {s0.x, s0.y, s0.z, s0.w, s1.x, s1.y, s1.z, s1.w, s2.x, s2.y, s2.z, s2.w, s3.x, s3.y, s3.z, s3.w};
; #pragma unroll
;                   for (int i = 0; i < 16; ++i) {
;                       const float lo = (float)__builtin_bit_cast(_Float16, (unsigned short)(sw[i] & 0xffffu)), hi = (float)__builtin_bit_cast(_Float16, (unsigned short)(sw[i] >> 16));
;                       const unsigned klo = (f2key(lo) & ~127u) | (unsigned)(127 - (32 * g + 2 * i)), khi = (f2key(hi) & ~127u) | (unsigned)(127 - (32 * g + 2 * i + 1));
;                       if (i < 8) { k0[2 * i] = klo; k0[2 * i + 1] = khi; } else { k1[2 * (i - 8)] = klo; k1[2 * (i - 8) + 1] = khi; } } }
	v_cvt_f32_f16_sdwa v127, v132 dst_sel:DWORD dst_unused:UNUSED_PAD src0_sel:WORD_1
	v_cvt_f32_f16_e32 v132, v132
	v_not_b32_e32 v140, v127
	v_or_b32_e32 v141, 0x80000000, v127
	v_cmp_gt_i32_e32 vcc, 0, v127
	s_nop 1
	v_cndmask_b32_e32 v127, v141, v140, vcc
	v_not_b32_e32 v140, v132
	v_or_b32_e32 v141, 0x80000000, v132
	v_cmp_gt_i32_e32 vcc, 0, v132
	v_and_b32_e32 v127, 0xffffff80, v127
	v_sub_u32_e32 v127, v127, v15
	v_cndmask_b32_e32 v132, v141, v140, vcc
	v_cvt_f32_f16_sdwa v140, v133 dst_sel:DWORD dst_unused:UNUSED_PAD src0_sel:WORD_1
	v_cvt_f32_f16_e32 v133, v133
	v_and_b32_e32 v132, 0xffffff80, v132
	v_sub_u32_e32 v132, v132, v15
	v_not_b32_e32 v141, v140
	v_or_b32_e32 v142, 0x80000000, v140
	v_cmp_gt_i32_e32 vcc, 0, v140
	v_add_u32_e32 v127, 0x7e, v127
	v_add_u32_e32 v132, 0x7f, v132
	v_cndmask_b32_e32 v140, v142, v141, vcc
	v_not_b32_e32 v141, v133
	v_or_b32_e32 v142, 0x80000000, v133
	v_cmp_gt_i32_e32 vcc, 0, v133
	v_and_b32_e32 v140, 0xffffff80, v140
	v_sub_u32_e32 v140, v140, v14
	v_cndmask_b32_e32 v133, v142, v141, vcc
	v_cvt_f32_f16_sdwa v141, v134 dst_sel:DWORD dst_unused:UNUSED_PAD src0_sel:WORD_1
	v_cvt_f32_f16_e32 v134, v134
	v_and_b32_e32 v133, 0xffffff80, v133
	v_sub_u32_e32 v133, v133, v14
	v_not_b32_e32 v142, v141
	v_or_b32_e32 v143, 0x80000000, v141
	v_cmp_gt_i32_e32 vcc, 0, v141
	v_add_u32_e32 v140, 0x7e, v140
	v_add_u32_e32 v133, 0x7f, v133
	v_cndmask_b32_e32 v141, v143, v142, vcc
	v_not_b32_e32 v142, v134
	v_or_b32_e32 v143, 0x80000000, v134
	v_cmp_gt_i32_e32 vcc, 0, v134
	v_and_b32_e32 v141, 0xffffff80, v141
	v_sub_u32_e32 v141, v141, v12
	v_cndmask_b32_e32 v134, v143, v142, vcc
	v_cvt_f32_f16_sdwa v142, v135 dst_sel:DWORD dst_unused:UNUSED_PAD src0_sel:WORD_1
	v_cvt_f32_f16_e32 v135, v135
	v_and_b32_e32 v134, 0xffffff80, v134
	v_sub_u32_e32 v134, v134, v12
	v_not_b32_e32 v143, v142
	v_or_b32_e32 v144, 0x80000000, v142
	v_cmp_gt_i32_e32 vcc, 0, v142
	v_add_u32_e32 v141, 0x7e, v141
	v_add_u32_e32 v134, 0x7f, v134
	v_cndmask_b32_e32 v142, v144, v143, vcc
	v_not_b32_e32 v143, v135
	v_or_b32_e32 v144, 0x80000000, v135
	v_cmp_gt_i32_e32 vcc, 0, v135
	v_and_b32_e32 v142, 0xffffff80, v142
	v_sub_u32_e32 v142, v142, v10
	v_cndmask_b32_e32 v135, v144, v143, vcc
	v_cvt_f32_f16_sdwa v143, v128 dst_sel:DWORD dst_unused:UNUSED_PAD src0_sel:WORD_1
	v_cvt_f32_f16_e32 v128, v128
	v_and_b32_e32 v135, 0xffffff80, v135
	v_sub_u32_e32 v135, v135, v10
	v_not_b32_e32 v144, v143
	v_or_b32_e32 v145, 0x80000000, v143
	v_cmp_gt_i32_e32 vcc, 0, v143
	v_add_u32_e32 v142, 0x7e, v142
	v_add_u32_e32 v135, 0x7f, v135
	v_cndmask_b32_e32 v143, v145, v144, vcc
	v_not_b32_e32 v144, v128
	v_or_b32_e32 v145, 0x80000000, v128
	v_cmp_gt_i32_e32 vcc, 0, v128
	v_and_b32_e32 v143, 0xffffff80, v143
	v_sub_u32_e32 v143, v143, v8
	v_cndmask_b32_e32 v128, v145, v144, vcc
	v_cvt_f32_f16_sdwa v144, v129 dst_sel:DWORD dst_unused:UNUSED_PAD src0_sel:WORD_1
	v_cvt_f32_f16_e32 v129, v129
	v_and_b32_e32 v128, 0xffffff80, v128
	v_sub_u32_e32 v128, v128, v8
	v_not_b32_e32 v145, v144
	v_or_b32_e32 v146, 0x80000000, v144
	v_cmp_gt_i32_e32 vcc, 0, v144
	v_add_u32_e32 v143, 0x7e, v143
	v_add_u32_e32 v128, 0x7f, v128
	v_cndmask_b32_e32 v144, v146, v145, vcc
	v_not_b32_e32 v145, v129
	v_or_b32_e32 v146, 0x80000000, v129
	v_cmp_gt_i32_e32 vcc, 0, v129
	v_and_b32_e32 v144, 0xffffff80, v144
	v_sub_u32_e32 v144, v144, v16
	v_cndmask_b32_e32 v129, v146, v145, vcc
	v_cvt_f32_f16_sdwa v145, v130 dst_sel:DWORD dst_unused:UNUSED_PAD src0_sel:WORD_1
	v_cvt_f32_f16_e32 v130, v130
	v_and_b32_e32 v129, 0xffffff80, v129
	v_sub_u32_e32 v129, v129, v16
	v_not_b32_e32 v146, v145
	v_or_b32_e32 v147, 0x80000000, v145
	v_cmp_gt_i32_e32 vcc, 0, v145
	v_add_u32_e32 v144, 0x7e, v144
	v_add_u32_e32 v129, 0x7f, v129
	v_cndmask_b32_e32 v145, v147, v146, vcc
	v_not_b32_e32 v146, v130
	v_or_b32_e32 v147, 0x80000000, v130
	v_cmp_gt_i32_e32 vcc, 0, v130
	v_and_b32_e32 v145, 0xffffff80, v145
	v_sub_u32_e32 v145, v145, v17
	v_cndmask_b32_e32 v130, v147, v146, vcc
	v_cvt_f32_f16_sdwa v146, v131 dst_sel:DWORD dst_unused:UNUSED_PAD src0_sel:WORD_1
	v_cvt_f32_f16_e32 v131, v131
	v_and_b32_e32 v130, 0xffffff80, v130
	v_sub_u32_e32 v130, v130, v17
	v_not_b32_e32 v147, v146
	v_or_b32_e32 v148, 0x80000000, v146
	v_cmp_gt_i32_e32 vcc, 0, v146
	v_add_u32_e32 v145, 0x7e, v145
	v_add_u32_e32 v130, 0x7f, v130
	v_cndmask_b32_e32 v146, v148, v147, vcc
	v_not_b32_e32 v147, v131
	v_or_b32_e32 v148, 0x80000000, v131
	v_cmp_gt_i32_e32 vcc, 0, v131
	v_and_b32_e32 v146, 0xffffff80, v146
	v_sub_u32_e32 v146, v146, v18
	v_cndmask_b32_e32 v131, v148, v147, vcc
	s_waitcnt vmcnt(0)
; __device__ __forceinline__ unsigned f2key(float f) { const unsigned u = __float_as_uint(f); return (u & 0x80000000u) ? ~u : (u | 0x80000000u); }
; __device__ __forceinline__ void peer_tile(const Args& A, LAS unsigned char* lds, int tile) {
;     ...
;                 { const bf16_t* sp = QRY + m * 2048 + hp * 128 + 32 * g;
;                   const u32x4 s0 = *(const u32x4*)sp, s1 = *(const u32x4*)(sp + 8), s2 = *(const u32x4*)(sp + 16), s3 = *(const u32x4*)(sp + 24);
;                   const unsigned sw[16] = {s0.x, s0.y, s0.z, s0.w, s1.x, s1.y, s1.z, s1.w, s2.x, s2.y, s2.z, s2.w, s3.x, s3.y, s3.z, s3.w};
; #pragma unroll
;                   for (int i = 0; i < 16; ++i) {
;                       const float lo = (float)__builtin_bit_cast(_Float16, (unsigned short)(sw[i] & 0xffffu)), hi = (float)__builtin_bit_cast(_Float16, (unsigned short)(sw[i] >> 16));
;                       const unsigned klo = (f2key(lo) & ~127u) | (unsigned)(127 - (32 * g + 2 * i)), khi = (f2key(hi) & ~127u) | (unsigned)(127 - (32 * g + 2 * i + 1));
;                       if (i < 8) { k0[2 * i] = klo; k0[2 * i + 1] = khi; } else { k1[2 * (i - 8)] = klo; k1[2 * (i - 8) + 1] = khi; } } }
;                 sort16_desc(k0); sort16_desc(k1); merge16(k0, k1);
	v_cvt_f32_f16_sdwa v147, v136 dst_sel:DWORD dst_unused:UNUSED_PAD src0_sel:WORD_1
	v_cvt_f32_f16_e32 v136, v136
	v_and_b32_e32 v131, 0xffffff80, v131
	v_sub_u32_e32 v131, v131, v18
	v_not_b32_e32 v148, v147
	v_or_b32_e32 v149, 0x80000000, v147
	v_cmp_gt_i32_e32 vcc, 0, v147
	v_add_u32_e32 v146, 0x7e, v146
	v_add_u32_e32 v131, 0x7f, v131
	v_cndmask_b32_e32 v147, v149, v148, vcc
	v_not_b32_e32 v148, v136
	v_or_b32_e32 v149, 0x80000000, v136
	v_cmp_gt_i32_e32 vcc, 0, v136
	v_and_b32_e32 v147, 0xffffff80, v147
	v_sub_u32_e32 v147, v147, v20
	v_cndmask_b32_e32 v136, v149, v148, vcc
	v_cvt_f32_f16_sdwa v148, v137 dst_sel:DWORD dst_unused:UNUSED_PAD src0_sel:WORD_1
	v_cvt_f32_f16_e32 v137, v137
	v_and_b32_e32 v136, 0xffffff80, v136
	v_sub_u32_e32 v136, v136, v20
	v_not_b32_e32 v149, v148
	v_or_b32_e32 v150, 0x80000000, v148
	v_cmp_gt_i32_e32 vcc, 0, v148
	v_add_u32_e32 v147, 0x7e, v147
	v_add_u32_e32 v136, 0x7f, v136
	v_cndmask_b32_e32 v148, v150, v149, vcc
	v_not_b32_e32 v149, v137
	v_or_b32_e32 v150, 0x80000000, v137
	v_cmp_gt_i32_e32 vcc, 0, v137
	v_and_b32_e32 v148, 0xffffff80, v148
	v_sub_u32_e32 v148, v148, v21
	v_cndmask_b32_e32 v137, v150, v149, vcc
	v_cvt_f32_f16_sdwa v149, v138 dst_sel:DWORD dst_unused:UNUSED_PAD src0_sel:WORD_1
	v_cvt_f32_f16_e32 v138, v138
	v_and_b32_e32 v137, 0xffffff80, v137
	v_sub_u32_e32 v137, v137, v21
	v_not_b32_e32 v150, v149
	v_or_b32_e32 v151, 0x80000000, v149
	v_cmp_gt_i32_e32 vcc, 0, v149
	v_add_u32_e32 v148, 0x7e, v148
	v_add_u32_e32 v137, 0x7f, v137
	v_cndmask_b32_e32 v149, v151, v150, vcc
	v_not_b32_e32 v150, v138
	v_or_b32_e32 v151, 0x80000000, v138
	v_cmp_gt_i32_e32 vcc, 0, v138
	v_and_b32_e32 v149, 0xffffff80, v149
	v_sub_u32_e32 v149, v149, v22
	v_cndmask_b32_e32 v138, v151, v150, vcc
	v_cvt_f32_f16_sdwa v150, v139 dst_sel:DWORD dst_unused:UNUSED_PAD src0_sel:WORD_1
	v_cvt_f32_f16_e32 v139, v139
	v_and_b32_e32 v138, 0xffffff80, v138
	v_sub_u32_e32 v138, v138, v22
	v_not_b32_e32 v151, v150
	v_or_b32_e32 v152, 0x80000000, v150
	v_cmp_gt_i32_e32 vcc, 0, v150
	v_add_u32_e32 v149, 0x7e, v149
	v_add_u32_e32 v138, 0x7f, v138
	v_cndmask_b32_e32 v150, v152, v151, vcc
	v_not_b32_e32 v151, v139
	v_or_b32_e32 v152, 0x80000000, v139
	v_cmp_gt_i32_e32 vcc, 0, v139
	v_and_b32_e32 v150, 0xffffff80, v150
	v_sub_u32_e32 v150, v150, v23
	v_cndmask_b32_e32 v139, v152, v151, vcc
	v_cvt_f32_f16_sdwa v151, v0 dst_sel:DWORD dst_unused:UNUSED_PAD src0_sel:WORD_1
	v_cvt_f32_f16_e32 v0, v0
	v_and_b32_e32 v139, 0xffffff80, v139
	v_sub_u32_e32 v139, v139, v23
	v_not_b32_e32 v152, v151
	v_or_b32_e32 v153, 0x80000000, v151
	v_cmp_gt_i32_e32 vcc, 0, v151
	v_add_u32_e32 v150, 0x7e, v150
	v_add_u32_e32 v139, 0x7f, v139
	v_cndmask_b32_e32 v151, v153, v152, vcc
	v_not_b32_e32 v152, v0
	v_or_b32_e32 v153, 0x80000000, v0
	v_cmp_gt_i32_e32 vcc, 0, v0
	v_and_b32_e32 v151, 0xffffff80, v151
	v_sub_u32_e32 v151, v151, v24
	v_cndmask_b32_e32 v0, v153, v152, vcc
	v_cvt_f32_f16_sdwa v152, v1 dst_sel:DWORD dst_unused:UNUSED_PAD src0_sel:WORD_1
	v_cvt_f32_f16_e32 v1, v1
	v_and_b32_e32 v0, 0xffffff80, v0
	v_sub_u32_e32 v0, v0, v24
	v_not_b32_e32 v153, v152
	v_or_b32_e32 v154, 0x80000000, v152
	v_cmp_gt_i32_e32 vcc, 0, v152
	v_add_u32_e32 v151, 0x7e, v151
	v_add_u32_e32 v0, 0x7f, v0
	v_cndmask_b32_e32 v152, v154, v153, vcc
	v_not_b32_e32 v153, v1
	v_or_b32_e32 v154, 0x80000000, v1
	v_cmp_gt_i32_e32 vcc, 0, v1
	v_and_b32_e32 v152, 0xffffff80, v152
	v_sub_u32_e32 v152, v152, v25
	v_cndmask_b32_e32 v1, v154, v153, vcc
	v_cvt_f32_f16_sdwa v153, v2 dst_sel:DWORD dst_unused:UNUSED_PAD src0_sel:WORD_1
	v_cvt_f32_f16_e32 v2, v2
	v_and_b32_e32 v1, 0xffffff80, v1
	v_sub_u32_e32 v1, v1, v25
	v_not_b32_e32 v154, v153
	v_or_b32_e32 v155, 0x80000000, v153
	v_cmp_gt_i32_e32 vcc, 0, v153
	v_add_u32_e32 v152, 0x7e, v152
	v_add_u32_e32 v1, 0x7f, v1
	v_cndmask_b32_e32 v153, v155, v154, vcc
	v_not_b32_e32 v154, v2
	v_or_b32_e32 v155, 0x80000000, v2
	v_cmp_gt_i32_e32 vcc, 0, v2
	v_and_b32_e32 v153, 0xffffff80, v153
	v_sub_u32_e32 v153, v153, v26
	v_cndmask_b32_e32 v2, v155, v154, vcc
	v_cvt_f32_f16_sdwa v154, v3 dst_sel:DWORD dst_unused:UNUSED_PAD src0_sel:WORD_1
	v_cvt_f32_f16_e32 v3, v3
	v_and_b32_e32 v2, 0xffffff80, v2
	v_sub_u32_e32 v2, v2, v26
	v_not_b32_e32 v155, v154
	v_or_b32_e32 v156, 0x80000000, v154
	v_cmp_gt_i32_e32 vcc, 0, v154
	v_add_u32_e32 v153, 0x7e, v153
	v_add_u32_e32 v2, 0x7f, v2
	v_cndmask_b32_e32 v154, v156, v155, vcc
	v_not_b32_e32 v155, v3
	v_or_b32_e32 v156, 0x80000000, v3
	v_cmp_gt_i32_e32 vcc, 0, v3
	v_and_b32_e32 v154, 0xffffff80, v154
	v_sub_u32_e32 v154, v154, v28
	v_cndmask_b32_e32 v3, v156, v155, vcc
	v_and_b32_e32 v3, 0xffffff80, v3
	v_sub_u32_e32 v3, v3, v28
	v_add_u32_e32 v154, 0x7e, v154
	v_add_u32_e32 v3, 0x7f, v3
	v_max_u32_e32 v155, v132, v127
	v_min_u32_e32 v127, v132, v127
	v_max_u32_e32 v132, v140, v133
	v_min_u32_e32 v133, v140, v133
	v_max_u32_e32 v140, v134, v141
	v_min_u32_e32 v134, v134, v141
	v_max_u32_e32 v141, v142, v135
	v_min_u32_e32 v135, v142, v135
	v_max_u32_e32 v142, v128, v143
	v_min_u32_e32 v128, v128, v143
	v_max_u32_e32 v143, v144, v129
	v_min_u32_e32 v129, v144, v129
	v_max_u32_e32 v144, v130, v145
	v_min_u32_e32 v130, v130, v145
	v_max_u32_e32 v145, v146, v131
	v_min_u32_e32 v131, v146, v131
	v_max_u32_e32 v163, v136, v147
	v_min_u32_e32 v136, v136, v147
	v_max_u32_e32 v147, v148, v137
	v_min_u32_e32 v137, v148, v137
	v_max_u32_e32 v148, v138, v149
	v_min_u32_e32 v138, v138, v149
	v_max_u32_e32 v149, v150, v139
	v_min_u32_e32 v139, v150, v139
	v_max_u32_e32 v150, v0, v151
	v_min_u32_e32 v0, v0, v151
	v_max_u32_e32 v151, v152, v1
	v_min_u32_e32 v1, v152, v1
	v_max_u32_e32 v152, v2, v153
	v_min_u32_e32 v2, v2, v153
; #define CE_DESC(a, b) do { const unsigned _mx = (a) > (b) ? (a) : (b), _mn = (a) > (b) ? (b) : (a); (a) = _mx; (b) = _mn; } while (0)
; __device__ __forceinline__ void sort16_desc(unsigned (&k)[16]) {
; #pragma unroll
;     for (int size = 2; size <= 16; size <<= 1)
; #pragma unroll
;         for (int stride = size >> 1; stride > 0; stride >>= 1)
; #pragma unroll
;             for (int i = 0; i < 16; ++i) { const int j = i ^ stride;
;                 if (j > i) { if ((i & size) == 0) CE_DESC(k[i], k[j]); else CE_DESC(k[j], k[i]); } }
; }
	v_max_u32_e32 v153, v154, v3
	v_min_u32_e32 v3, v154, v3
	v_max_u32_e32 v146, v155, v133
	v_min_u32_e32 v133, v155, v133
	v_max_u32_e32 v155, v127, v132
	v_min_u32_e32 v127, v127, v132
	v_max_u32_e32 v132, v135, v140
	v_min_u32_e32 v135, v135, v140
	v_max_u32_e32 v140, v141, v134
	v_min_u32_e32 v134, v141, v134
	v_max_u32_e32 v141, v142, v129
	v_min_u32_e32 v129, v142, v129
	v_max_u32_e32 v142, v128, v143
	v_min_u32_e32 v128, v128, v143
	v_max_u32_e32 v143, v131, v144
	v_min_u32_e32 v131, v131, v144
	v_max_u32_e32 v144, v145, v130
	v_min_u32_e32 v130, v145, v130
	v_max_u32_e32 v154, v163, v137
	v_min_u32_e32 v137, v163, v137
	v_max_u32_e32 v163, v136, v147
	v_min_u32_e32 v136, v136, v147
	v_max_u32_e32 v147, v139, v148
	v_min_u32_e32 v139, v139, v148
	v_max_u32_e32 v148, v149, v138
	v_min_u32_e32 v138, v149, v138
	v_max_u32_e32 v149, v150, v1
	v_min_u32_e32 v1, v150, v1
	v_max_u32_e32 v150, v0, v151
	v_min_u32_e32 v0, v0, v151
	v_max_u32_e32 v151, v3, v152
	v_min_u32_e32 v3, v3, v152
	v_max_u32_e32 v152, v153, v2
	v_min_u32_e32 v2, v153, v2
	v_max_u32_e32 v145, v146, v155
	v_min_u32_e32 v146, v146, v155
	v_max_u32_e32 v155, v133, v127
	v_min_u32_e32 v127, v133, v127
	v_max_u32_e32 v133, v134, v135
	v_min_u32_e32 v134, v134, v135
	v_max_u32_e32 v135, v140, v132
	v_min_u32_e32 v132, v140, v132
	v_max_u32_e32 v140, v141, v142
	v_min_u32_e32 v141, v141, v142
	v_max_u32_e32 v142, v129, v128
	v_min_u32_e32 v128, v129, v128
	v_max_u32_e32 v129, v130, v131
	v_min_u32_e32 v130, v130, v131
	v_max_u32_e32 v131, v144, v143
	v_min_u32_e32 v143, v144, v143
	v_max_u32_e32 v153, v154, v163
	v_min_u32_e32 v154, v154, v163
	v_max_u32_e32 v163, v137, v136
	v_min_u32_e32 v136, v137, v136
	v_max_u32_e32 v137, v138, v139
	v_min_u32_e32 v138, v138, v139
	v_max_u32_e32 v139, v148, v147
	v_min_u32_e32 v147, v148, v147
	v_max_u32_e32 v148, v149, v150
	v_min_u32_e32 v149, v149, v150
	v_max_u32_e32 v150, v1, v0
	v_min_u32_e32 v0, v1, v0
	v_max_u32_e32 v1, v2, v3
	v_min_u32_e32 v2, v2, v3
	v_max_u32_e32 v3, v152, v151
	v_min_u32_e32 v151, v152, v151
	v_max_u32_e32 v144, v145, v134
	v_min_u32_e32 v134, v145, v134
	v_max_u32_e32 v145, v146, v133
	v_min_u32_e32 v133, v146, v133
	v_max_u32_e32 v146, v155, v132
	v_min_u32_e32 v132, v155, v132
	v_max_u32_e32 v155, v127, v135
	v_min_u32_e32 v127, v127, v135
	v_max_u32_e32 v135, v130, v140
	v_min_u32_e32 v130, v130, v140
	v_max_u32_e32 v140, v129, v141
	v_min_u32_e32 v129, v129, v141
	v_max_u32_e32 v141, v143, v142
	v_min_u32_e32 v142, v143, v142
	v_max_u32_e32 v143, v131, v128
	v_min_u32_e32 v128, v131, v128
	v_max_u32_e32 v152, v153, v138
	v_min_u32_e32 v138, v153, v138
	v_max_u32_e32 v153, v154, v137
	v_min_u32_e32 v137, v154, v137
	v_max_u32_e32 v154, v163, v147
	v_min_u32_e32 v147, v163, v147
	v_max_u32_e32 v163, v136, v139
	v_min_u32_e32 v136, v136, v139
	v_max_u32_e32 v139, v2, v148
	v_min_u32_e32 v2, v2, v148
	v_max_u32_e32 v148, v1, v149
	v_min_u32_e32 v1, v1, v149
	v_max_u32_e32 v149, v151, v150
	v_min_u32_e32 v150, v151, v150
	v_max_u32_e32 v151, v3, v0
	v_min_u32_e32 v0, v3, v0
	v_max_u32_e32 v131, v144, v146
	v_min_u32_e32 v144, v144, v146
	v_max_u32_e32 v146, v145, v155
	v_min_u32_e32 v145, v145, v155
	v_max_u32_e32 v155, v134, v132
	v_min_u32_e32 v132, v134, v132
	v_max_u32_e32 v134, v133, v127
	v_min_u32_e32 v127, v133, v127
	v_max_u32_e32 v133, v142, v130
	v_min_u32_e32 v130, v142, v130
	v_max_u32_e32 v142, v128, v129
	v_min_u32_e32 v128, v128, v129
	v_max_u32_e32 v129, v141, v135
	v_min_u32_e32 v135, v141, v135
	v_max_u32_e32 v141, v143, v140
	v_min_u32_e32 v140, v143, v140
	v_max_u32_e32 v3, v152, v154
	v_min_u32_e32 v152, v152, v154
	v_max_u32_e32 v154, v153, v163
	v_min_u32_e32 v153, v153, v163
	v_max_u32_e32 v163, v138, v147
	v_min_u32_e32 v138, v138, v147
	v_max_u32_e32 v147, v137, v136
	v_min_u32_e32 v136, v137, v136
	v_max_u32_e32 v137, v150, v2
	v_min_u32_e32 v2, v150, v2
	v_max_u32_e32 v150, v0, v1
	v_min_u32_e32 v0, v0, v1
	v_max_u32_e32 v1, v149, v139
	v_min_u32_e32 v139, v149, v139
	v_max_u32_e32 v149, v151, v148
	v_min_u32_e32 v148, v151, v148
	v_max_u32_e32 v143, v131, v146
	v_min_u32_e32 v131, v131, v146
	v_max_u32_e32 v146, v144, v145
	v_min_u32_e32 v144, v144, v145
	v_max_u32_e32 v145, v155, v134
	v_min_u32_e32 v134, v155, v134
	v_max_u32_e32 v155, v132, v127
	v_min_u32_e32 v127, v132, v127
	v_max_u32_e32 v132, v128, v130
	v_min_u32_e32 v128, v128, v130
	v_max_u32_e32 v130, v142, v133
	v_min_u32_e32 v133, v142, v133
	v_max_u32_e32 v142, v140, v135
	v_min_u32_e32 v135, v140, v135
	v_max_u32_e32 v140, v141, v129
	v_min_u32_e32 v129, v141, v129
	v_max_u32_e32 v151, v3, v154
	v_min_u32_e32 v3, v3, v154
	v_max_u32_e32 v154, v152, v153
	v_min_u32_e32 v152, v152, v153
	v_max_u32_e32 v153, v163, v147
	v_min_u32_e32 v147, v163, v147
	v_max_u32_e32 v163, v138, v136
	v_min_u32_e32 v136, v138, v136
	v_max_u32_e32 v138, v0, v2
	v_min_u32_e32 v0, v0, v2
	v_max_u32_e32 v2, v150, v137
	v_min_u32_e32 v137, v150, v137
	v_max_u32_e32 v150, v148, v139
	v_min_u32_e32 v139, v148, v139
	v_max_u32_e32 v148, v149, v1
	v_min_u32_e32 v1, v149, v1
	v_max_u32_e32 v141, v143, v128
	v_min_u32_e32 v128, v143, v128
	v_max_u32_e32 v143, v131, v132
	v_min_u32_e32 v131, v131, v132
	v_max_u32_e32 v132, v146, v133
	v_min_u32_e32 v133, v146, v133
	v_max_u32_e32 v146, v144, v130
	v_min_u32_e32 v130, v144, v130
	v_max_u32_e32 v144, v145, v135
	v_min_u32_e32 v135, v145, v135
	v_max_u32_e32 v145, v134, v142
	v_min_u32_e32 v134, v134, v142
	v_max_u32_e32 v142, v155, v129
	v_min_u32_e32 v129, v155, v129
	v_max_u32_e32 v155, v127, v140
	v_min_u32_e32 v127, v127, v140
	v_max_u32_e32 v149, v151, v0
	v_min_u32_e32 v0, v151, v0
; #define CE_DESC(a, b) do { const unsigned _mx = (a) > (b) ? (a) : (b), _mn = (a) > (b) ? (b) : (a); (a) = _mx; (b) = _mn; } while (0)
; __device__ __forceinline__ void sort16_desc(unsigned (&k)[16]) {
; #pragma unroll
;     for (int size = 2; size <= 16; size <<= 1)
; #pragma unroll
;         for (int stride = size >> 1; stride > 0; stride >>= 1)
; #pragma unroll
;             for (int i = 0; i < 16; ++i) { const int j = i ^ stride;
;                 if (j > i) { if ((i & size) == 0) CE_DESC(k[i], k[j]); else CE_DESC(k[j], k[i]); } }
; }
; __device__ __forceinline__ void merge16(unsigned (&a)[16], const unsigned (&b)[16]) {
; #pragma unroll
;     for (int i = 0; i < 16; ++i) a[i] = a[i] > b[15 - i] ? a[i] : b[15 - i];
; #pragma unroll
;     for (int stride = 8; stride > 0; stride >>= 1)
; #pragma unroll
;         for (int i = 0; i < 16; ++i) { const int j = i ^ stride; if (j > i) CE_DESC(a[i], a[j]); }
; }
; __device__ __forceinline__ void peer_tile(const Args& A, LAS unsigned char* lds, int tile) {
;     ...
;                 for (int msk = 16; msk <= 32; msk <<= 1) {
; #pragma unroll
;                     for (int i = 0; i < 16; ++i) k1[i] = (unsigned)__shfl_xor((int)k0[i], msk);
;                     merge16(k0, k1); }
	v_max_u32_e32 v151, v3, v138
	v_min_u32_e32 v3, v3, v138
	v_max_u32_e32 v138, v154, v137
	v_min_u32_e32 v137, v154, v137
	v_max_u32_e32 v154, v152, v2
	v_min_u32_e32 v2, v152, v2
	v_max_u32_e32 v152, v153, v139
	v_min_u32_e32 v139, v153, v139
	v_max_u32_e32 v153, v147, v150
	v_min_u32_e32 v147, v147, v150
	v_max_u32_e32 v150, v163, v1
	v_min_u32_e32 v1, v163, v1
	v_max_u32_e32 v163, v136, v148
	v_min_u32_e32 v136, v136, v148
	v_max_u32_e32 v140, v141, v144
	v_min_u32_e32 v141, v141, v144
	v_max_u32_e32 v144, v143, v145
	v_min_u32_e32 v143, v143, v145
	v_max_u32_e32 v145, v132, v142
	v_min_u32_e32 v132, v132, v142
	v_max_u32_e32 v142, v146, v155
	v_min_u32_e32 v146, v146, v155
	v_max_u32_e32 v155, v128, v135
	v_min_u32_e32 v128, v128, v135
	v_max_u32_e32 v135, v131, v134
	v_min_u32_e32 v131, v131, v134
	v_max_u32_e32 v134, v133, v129
	v_min_u32_e32 v129, v133, v129
	v_max_u32_e32 v133, v130, v127
	v_min_u32_e32 v127, v130, v127
	v_max_u32_e32 v148, v149, v152
	v_min_u32_e32 v149, v149, v152
	v_max_u32_e32 v152, v151, v153
	v_min_u32_e32 v151, v151, v153
	v_max_u32_e32 v153, v138, v150
	v_min_u32_e32 v138, v138, v150
	v_max_u32_e32 v150, v154, v163
	v_min_u32_e32 v154, v154, v163
	v_max_u32_e32 v163, v0, v139
	v_min_u32_e32 v0, v0, v139
	v_max_u32_e32 v139, v3, v147
	v_min_u32_e32 v3, v3, v147
	v_max_u32_e32 v147, v137, v1
	v_min_u32_e32 v1, v137, v1
	v_max_u32_e32 v137, v2, v136
	v_min_u32_e32 v2, v2, v136
	v_max_u32_e32 v130, v140, v145
	v_min_u32_e32 v140, v140, v145
	v_max_u32_e32 v145, v144, v142
	v_min_u32_e32 v142, v144, v142
	v_max_u32_e32 v144, v141, v132
	v_min_u32_e32 v132, v141, v132
	v_max_u32_e32 v141, v143, v146
	v_min_u32_e32 v143, v143, v146
	v_max_u32_e32 v146, v155, v134
	v_min_u32_e32 v134, v155, v134
	v_max_u32_e32 v155, v135, v133
	v_min_u32_e32 v133, v135, v133
	v_max_u32_e32 v135, v128, v129
	v_min_u32_e32 v128, v128, v129
	v_max_u32_e32 v129, v131, v127
	v_min_u32_e32 v127, v131, v127
	v_max_u32_e32 v136, v148, v153
	v_min_u32_e32 v148, v148, v153
	v_max_u32_e32 v153, v152, v150
	v_min_u32_e32 v150, v152, v150
	v_max_u32_e32 v152, v149, v138
	v_min_u32_e32 v138, v149, v138
	v_max_u32_e32 v149, v151, v154
	v_min_u32_e32 v151, v151, v154
	v_max_u32_e32 v154, v163, v147
	v_min_u32_e32 v147, v163, v147
	v_max_u32_e32 v163, v139, v137
	v_min_u32_e32 v137, v139, v137
	v_max_u32_e32 v139, v0, v1
	v_min_u32_e32 v0, v0, v1
	v_max_u32_e32 v1, v3, v2
	v_min_u32_e32 v2, v3, v2
	v_min_u32_e32 v131, v130, v145
	v_min_u32_e32 v156, v140, v142
	v_min_u32_e32 v157, v144, v141
	v_min_u32_e32 v158, v132, v143
	v_min_u32_e32 v159, v146, v155
	v_min_u32_e32 v160, v134, v133
	v_min_u32_e32 v161, v135, v129
	v_min_u32_e32 v162, v128, v127
	v_min_u32_e32 v3, v136, v153
	v_min_u32_e32 v164, v148, v150
	v_min_u32_e32 v165, v152, v149
	v_min_u32_e32 v166, v138, v151
	v_min_u32_e32 v167, v154, v163
	v_min_u32_e32 v168, v147, v137
	v_min_u32_e32 v169, v139, v1
	v_min_u32_e32 v170, v0, v2
	v_max3_u32 v130, v130, v145, v170
	v_max3_u32 v0, v131, v0, v2
	v_max3_u32 v2, v140, v142, v169
	v_max3_u32 v1, v156, v139, v1
	v_max3_u32 v131, v144, v141, v168
	v_max3_u32 v137, v157, v147, v137
	v_max3_u32 v132, v132, v143, v167
	v_max3_u32 v139, v158, v154, v163
	v_max3_u32 v140, v146, v155, v166
	v_max3_u32 v138, v159, v138, v151
	v_max3_u32 v133, v134, v133, v165
	v_max3_u32 v134, v160, v152, v149
	v_max3_u32 v129, v135, v129, v164
	v_max3_u32 v135, v161, v148, v150
	v_max3_u32 v3, v128, v127, v3
	v_max3_u32 v127, v162, v136, v153
	v_max_u32_e32 v128, v130, v140
	v_min_u32_e32 v130, v130, v140
	v_max_u32_e32 v136, v0, v138
	v_min_u32_e32 v0, v0, v138
	v_max_u32_e32 v138, v2, v133
	v_min_u32_e32 v2, v2, v133
	v_max_u32_e32 v133, v1, v134
	v_min_u32_e32 v1, v1, v134
	v_max_u32_e32 v134, v131, v129
	v_min_u32_e32 v129, v131, v129
	v_max_u32_e32 v131, v137, v135
	v_min_u32_e32 v135, v137, v135
	v_max_u32_e32 v137, v132, v3
	v_min_u32_e32 v3, v132, v3
	v_max_u32_e32 v132, v139, v127
	v_min_u32_e32 v127, v139, v127
	v_max_u32_e32 v139, v128, v134
	v_min_u32_e32 v128, v128, v134
	v_max_u32_e32 v134, v136, v131
	v_min_u32_e32 v131, v136, v131
	v_max_u32_e32 v136, v138, v137
	v_min_u32_e32 v137, v138, v137
	v_max_u32_e32 v138, v133, v132
	v_min_u32_e32 v132, v133, v132
	v_max_u32_e32 v133, v130, v129
	v_min_u32_e32 v129, v130, v129
	v_max_u32_e32 v130, v0, v135
	v_min_u32_e32 v0, v0, v135
	v_max_u32_e32 v135, v2, v3
	v_min_u32_e32 v2, v2, v3
	v_max_u32_e32 v3, v1, v127
	v_min_u32_e32 v1, v1, v127
	v_max_u32_e32 v127, v139, v136
	v_min_u32_e32 v136, v139, v136
	v_max_u32_e32 v139, v134, v138
	v_min_u32_e32 v134, v134, v138
	v_max_u32_e32 v138, v128, v137
	v_min_u32_e32 v128, v128, v137
	v_max_u32_e32 v137, v131, v132
	v_min_u32_e32 v131, v131, v132
	v_max_u32_e32 v132, v133, v135
	v_min_u32_e32 v133, v133, v135
	v_max_u32_e32 v135, v130, v3
	v_min_u32_e32 v3, v130, v3
	v_max_u32_e32 v130, v129, v2
	v_min_u32_e32 v2, v129, v2
	v_max_u32_e32 v129, v0, v1
	v_min_u32_e32 v0, v0, v1
	v_max_u32_e32 v1, v127, v139
	v_min_u32_e32 v127, v127, v139
	v_max_u32_e32 v139, v136, v134
	v_min_u32_e32 v134, v136, v134
	v_max_u32_e32 v136, v138, v137
	v_min_u32_e32 v137, v138, v137
	v_max_u32_e32 v138, v128, v131
	v_min_u32_e32 v128, v128, v131
	v_max_u32_e32 v131, v132, v135
	v_min_u32_e32 v132, v132, v135
	v_max_u32_e32 v135, v133, v3
	v_min_u32_e32 v3, v133, v3
	v_max_u32_e32 v133, v130, v129
	v_min_u32_e32 v129, v130, v129
	v_max_u32_e32 v130, v2, v0
	v_min_u32_e32 v0, v2, v0
	ds_bpermute_b32 v2, v27, v1
	ds_bpermute_b32 v140, v27, v127
	ds_bpermute_b32 v141, v27, v139
	ds_bpermute_b32 v142, v27, v134
	ds_bpermute_b32 v143, v27, v136
	ds_bpermute_b32 v144, v27, v137
	ds_bpermute_b32 v145, v27, v138
	ds_bpermute_b32 v146, v27, v128
	ds_bpermute_b32 v147, v27, v131
	ds_bpermute_b32 v148, v27, v132
	ds_bpermute_b32 v149, v27, v135
	ds_bpermute_b32 v150, v27, v0
	ds_bpermute_b32 v151, v27, v130
	ds_bpermute_b32 v152, v27, v129
	ds_bpermute_b32 v153, v27, v133
	ds_bpermute_b32 v154, v27, v3
	s_waitcnt lgkmcnt(4)
; __device__ __forceinline__ void peer_tile(const Args& A, LAS unsigned char* lds, int tile) {
;     ...
;                 { const bf16_t* sp = QRY + m * 2048 + hp * 128 + 32 * g;
;                   const u32x4 s0 = *(const u32x4*)sp, s1 = *(const u32x4*)(sp + 8), s2 = *(const u32x4*)(sp + 16), s3 = *(const u32x4*)(sp + 24);
;     ...
;                 for (int msk = 16; msk <= 32; msk <<= 1) {
; #pragma unroll
;                     for (int i = 0; i < 16; ++i) k1[i] = (unsigned)__shfl_xor((int)k0[i], msk);
;                     merge16(k0, k1); }
	v_max_u32_e32 v1, v1, v150
	s_waitcnt lgkmcnt(3)
	v_max_u32_e32 v127, v127, v151
	s_waitcnt lgkmcnt(2)
	v_max_u32_e32 v139, v139, v152
	s_waitcnt lgkmcnt(1)
	v_max_u32_e32 v134, v134, v153
	s_waitcnt lgkmcnt(0)
	v_max_u32_e32 v136, v136, v154
	v_max_u32_e32 v137, v137, v149
	v_max_u32_e32 v138, v138, v148
	v_max_u32_e32 v128, v128, v147
	v_max_u32_e32 v131, v131, v146
	v_max_u32_e32 v132, v132, v145
	v_max_u32_e32 v135, v135, v144
	v_max_u32_e32 v3, v3, v143
	v_max_u32_e32 v133, v133, v142
	v_max_u32_e32 v129, v129, v141
	v_max_u32_e32 v130, v130, v140
	v_max_u32_e32 v0, v0, v2
	v_max_u32_e32 v2, v1, v131
	v_min_u32_e32 v1, v1, v131
	v_max_u32_e32 v131, v127, v132
	v_min_u32_e32 v127, v127, v132
	v_max_u32_e32 v132, v139, v135
	v_min_u32_e32 v135, v139, v135
	v_max_u32_e32 v139, v134, v3
	v_min_u32_e32 v3, v134, v3
	v_max_u32_e32 v134, v136, v133
	v_min_u32_e32 v133, v136, v133
	v_max_u32_e32 v136, v137, v129
	v_min_u32_e32 v129, v137, v129
	v_max_u32_e32 v137, v138, v130
	v_min_u32_e32 v130, v138, v130
	v_max_u32_e32 v138, v128, v0
	v_min_u32_e32 v0, v128, v0
	v_max_u32_e32 v128, v2, v134
	v_min_u32_e32 v2, v2, v134
	v_max_u32_e32 v134, v131, v136
	v_min_u32_e32 v131, v131, v136
	v_max_u32_e32 v136, v132, v137
	v_min_u32_e32 v132, v132, v137
	v_max_u32_e32 v137, v139, v138
	v_min_u32_e32 v138, v139, v138
	v_max_u32_e32 v139, v1, v133
	v_min_u32_e32 v1, v1, v133
	v_max_u32_e32 v133, v127, v129
	v_min_u32_e32 v127, v127, v129
	v_max_u32_e32 v129, v135, v130
	v_min_u32_e32 v130, v135, v130
	v_max_u32_e32 v135, v3, v0
	v_min_u32_e32 v0, v3, v0
	v_max_u32_e32 v3, v128, v136
	v_min_u32_e32 v128, v128, v136
	v_max_u32_e32 v136, v134, v137
	v_min_u32_e32 v134, v134, v137
	v_max_u32_e32 v137, v2, v132
	v_min_u32_e32 v2, v2, v132
	v_max_u32_e32 v132, v131, v138
	v_min_u32_e32 v131, v131, v138
	v_max_u32_e32 v138, v139, v129
	v_min_u32_e32 v129, v139, v129
	v_max_u32_e32 v139, v133, v135
	v_min_u32_e32 v133, v133, v135
	v_max_u32_e32 v135, v1, v130
	v_min_u32_e32 v1, v1, v130
	v_max_u32_e32 v130, v127, v0
	v_min_u32_e32 v0, v127, v0
	v_max_u32_e32 v127, v3, v136
	v_min_u32_e32 v3, v3, v136
	v_max_u32_e32 v136, v128, v134
	v_min_u32_e32 v128, v128, v134
	v_max_u32_e32 v134, v137, v132
	v_min_u32_e32 v132, v137, v132
	v_max_u32_e32 v137, v2, v131
	v_min_u32_e32 v2, v2, v131
	v_max_u32_e32 v131, v138, v139
	v_min_u32_e32 v138, v138, v139
	v_max_u32_e32 v139, v129, v133
	v_min_u32_e32 v129, v129, v133
	v_max_u32_e32 v133, v135, v130
	v_min_u32_e32 v130, v135, v130
	v_max_u32_e32 v135, v1, v0
	v_min_u32_e32 v0, v1, v0
	ds_bpermute_b32 v144, v29, v0
	ds_bpermute_b32 v1, v29, v127
	ds_bpermute_b32 v140, v29, v3
	ds_bpermute_b32 v141, v29, v136
	ds_bpermute_b32 v142, v29, v128
	s_waitcnt lgkmcnt(4)
	v_max_u32_e32 v127, v127, v144
	global_load_dwordx4 v[144:147], v[4:5], off offset:1808
	global_load_dwordx4 v[148:151], v[4:5], off offset:1792
	ds_bpermute_b32 v143, v29, v134
	ds_bpermute_b32 v152, v29, v132
	ds_bpermute_b32 v153, v29, v137
	ds_bpermute_b32 v154, v29, v2
	ds_bpermute_b32 v155, v29, v131
	ds_bpermute_b32 v156, v29, v138
	ds_bpermute_b32 v157, v29, v139
	ds_bpermute_b32 v158, v29, v129
	ds_bpermute_b32 v159, v29, v133
	ds_bpermute_b32 v160, v29, v135
	ds_bpermute_b32 v161, v29, v130
	s_waitcnt lgkmcnt(4)
	v_max_u32_e32 v132, v132, v157
	s_waitcnt lgkmcnt(3)
	v_max_u32_e32 v134, v134, v158
	s_waitcnt lgkmcnt(2)
	v_max_u32_e32 v128, v128, v159
	s_waitcnt lgkmcnt(1)
	v_max_u32_e32 v3, v3, v160
	s_waitcnt lgkmcnt(0)
	v_max_u32_e32 v136, v136, v161
	v_max_u32_e32 v137, v137, v156
	v_max_u32_e32 v2, v2, v155
	v_max_u32_e32 v131, v131, v154
	v_max_u32_e32 v138, v138, v153
	v_max_u32_e32 v139, v139, v152
	v_max_u32_e32 v129, v129, v143
	v_max_u32_e32 v133, v133, v142
	v_max_u32_e32 v130, v130, v141
	v_max_u32_e32 v135, v135, v140
	v_max_u32_e32 v0, v0, v1
	v_max_u32_e32 v1, v127, v131
	v_min_u32_e32 v127, v127, v131
	v_max_u32_e32 v131, v3, v138
	v_min_u32_e32 v3, v3, v138
	v_max_u32_e32 v138, v136, v139
	v_min_u32_e32 v136, v136, v139
	v_max_u32_e32 v139, v128, v129
	v_min_u32_e32 v128, v128, v129
	v_max_u32_e32 v129, v134, v133
	v_min_u32_e32 v133, v134, v133
	v_max_u32_e32 v134, v132, v130
	v_min_u32_e32 v130, v132, v130
	v_max_u32_e32 v132, v137, v135
	v_min_u32_e32 v135, v137, v135
	v_max_u32_e32 v137, v2, v0
	v_min_u32_e32 v0, v2, v0
	v_max_u32_e32 v2, v1, v129
	v_min_u32_e32 v1, v1, v129
	v_max_u32_e32 v129, v131, v134
	v_min_u32_e32 v131, v131, v134
	v_max_u32_e32 v134, v138, v132
	v_min_u32_e32 v132, v138, v132
	v_max_u32_e32 v138, v139, v137
	v_min_u32_e32 v137, v139, v137
	v_max_u32_e32 v139, v127, v133
	v_min_u32_e32 v127, v127, v133
	v_max_u32_e32 v133, v3, v130
	v_min_u32_e32 v3, v3, v130
	v_max_u32_e32 v130, v136, v135
	v_min_u32_e32 v135, v136, v135
	v_max_u32_e32 v136, v128, v0
	v_min_u32_e32 v0, v128, v0
	v_max_u32_e32 v128, v2, v134
	v_min_u32_e32 v2, v2, v134
	v_max_u32_e32 v134, v129, v138
	v_min_u32_e32 v129, v129, v138
	v_max_u32_e32 v143, v1, v132
	v_min_u32_e32 v1, v1, v132
	v_max_u32_e32 v132, v131, v137
	v_min_u32_e32 v131, v131, v137
	v_max_u32_e32 v152, v139, v130
	v_min_u32_e32 v130, v139, v130
	v_max_u32_e32 v153, v133, v136
	v_min_u32_e32 v154, v133, v136
	v_max_u32_e32 v155, v127, v135
	v_min_u32_e32 v127, v127, v135
	v_max_u32_e32 v156, v3, v0
	v_min_u32_e32 v0, v3, v0
	v_max_u32_e32 v142, v128, v134
	v_min_u32_e32 v141, v128, v134
	v_max_u32_e32 v140, v2, v129
	v_min_u32_e32 v139, v2, v129
	v_max_u32_e32 v138, v143, v132
	v_min_u32_e32 v137, v143, v132
	v_max_u32_e32 v136, v1, v131
	v_min_u32_e32 v135, v1, v131
	v_max_u32_e32 v134, v152, v153
	v_min_u32_e32 v133, v152, v153
	v_max_u32_e32 v132, v130, v154
	v_min_u32_e32 v131, v130, v154
	v_max_u32_e32 v130, v155, v156
	v_min_u32_e32 v129, v155, v156
	v_max_u32_e32 v128, v127, v0
	v_min_u32_e32 v127, v127, v0
	global_load_dwordx4 v[0:3], v[4:5], off offset:1840
	global_load_dwordx4 v[152:155], v[4:5], off offset:1824
	s_waitcnt vmcnt(2)
; __device__ __forceinline__ unsigned f2key(float f) { const unsigned u = __float_as_uint(f); return (u & 0x80000000u) ? ~u : (u | 0x80000000u); }
; __device__ __forceinline__ void peer_tile(const Args& A, LAS unsigned char* lds, int tile) {
;     ...
;                 { const bf16_t* sp = QRY + m * 2048 + hp * 128 + 32 * g;
;                   const u32x4 s0 = *(const u32x4*)sp, s1 = *(const u32x4*)(sp + 8), s2 = *(const u32x4*)(sp + 16), s3 = *(const u32x4*)(sp + 24);
;                   const unsigned sw[16] = {s0.x, s0.y, s0.z, s0.w, s1.x, s1.y, s1.z, s1.w, s2.x, s2.y, s2.z, s2.w, s3.x, s3.y, s3.z, s3.w};
; #pragma unroll
;                   for (int i = 0; i < 16; ++i) {
;                       const float lo = (float)__builtin_bit_cast(_Float16, (unsigned short)(sw[i] & 0xffffu)), hi = (float)__builtin_bit_cast(_Float16, (unsigned short)(sw[i] >> 16));
;                       const unsigned klo = (f2key(lo) & ~127u) | (unsigned)(127 - (32 * g + 2 * i)), khi = (f2key(hi) & ~127u) | (unsigned)(127 - (32 * g + 2 * i + 1));
;                       if (i < 8) { k0[2 * i] = klo; k0[2 * i + 1] = khi; } else { k1[2 * (i - 8)] = klo; k1[2 * (i - 8) + 1] = khi; } } }
	v_cvt_f32_f16_sdwa v143, v148 dst_sel:DWORD dst_unused:UNUSED_PAD src0_sel:WORD_1
	v_cvt_f32_f16_e32 v4, v148
	v_not_b32_e32 v5, v143
	v_or_b32_e32 v148, 0x80000000, v143
	v_cmp_gt_i32_e32 vcc, 0, v143
	v_not_b32_e32 v143, v4
	s_nop 0
	v_cndmask_b32_e32 v5, v148, v5, vcc
	v_or_b32_e32 v148, 0x80000000, v4
	v_cmp_gt_i32_e32 vcc, 0, v4
	v_and_b32_e32 v5, 0xffffff80, v5
	v_sub_u32_e32 v5, v5, v15
	v_cndmask_b32_e32 v4, v148, v143, vcc
	v_and_b32_e32 v4, 0xffffff80, v4
	v_cvt_f32_f16_sdwa v143, v149 dst_sel:DWORD dst_unused:UNUSED_PAD src0_sel:WORD_1
	v_sub_u32_e32 v4, v4, v15
	v_cvt_f32_f16_e32 v15, v149
	v_add_u32_e32 v5, 0x7e, v5
	v_not_b32_e32 v148, v143
	v_or_b32_e32 v149, 0x80000000, v143
	v_cmp_gt_i32_e32 vcc, 0, v143
	v_add_u32_e32 v4, 0x7f, v4
	s_nop 0
	v_cndmask_b32_e32 v143, v149, v148, vcc
	v_not_b32_e32 v148, v15
	v_or_b32_e32 v149, 0x80000000, v15
	v_cmp_gt_i32_e32 vcc, 0, v15
	v_and_b32_e32 v143, 0xffffff80, v143
	v_sub_u32_e32 v143, v143, v14
	v_cndmask_b32_e32 v15, v149, v148, vcc
	v_and_b32_e32 v15, 0xffffff80, v15
	v_cvt_f32_f16_sdwa v148, v150 dst_sel:DWORD dst_unused:UNUSED_PAD src0_sel:WORD_1
	v_sub_u32_e32 v14, v15, v14
	v_cvt_f32_f16_e32 v15, v150
	v_add_u32_e32 v143, 0x7e, v143
	v_not_b32_e32 v149, v148
	v_or_b32_e32 v150, 0x80000000, v148
	v_cmp_gt_i32_e32 vcc, 0, v148
	v_add_u32_e32 v14, 0x7f, v14
	s_nop 0
	v_cndmask_b32_e32 v148, v150, v149, vcc
	v_not_b32_e32 v149, v15
	v_or_b32_e32 v150, 0x80000000, v15
	v_cmp_gt_i32_e32 vcc, 0, v15
	v_and_b32_e32 v148, 0xffffff80, v148
	v_sub_u32_e32 v148, v148, v12
	v_cndmask_b32_e32 v15, v150, v149, vcc
	v_and_b32_e32 v15, 0xffffff80, v15
	v_cvt_f32_f16_sdwa v149, v151 dst_sel:DWORD dst_unused:UNUSED_PAD src0_sel:WORD_1
	v_sub_u32_e32 v12, v15, v12
	v_cvt_f32_f16_e32 v15, v151
	v_add_u32_e32 v148, 0x7e, v148
	v_not_b32_e32 v150, v149
	v_or_b32_e32 v151, 0x80000000, v149
	v_cmp_gt_i32_e32 vcc, 0, v149
	v_add_u32_e32 v12, 0x7f, v12
	s_nop 0
	v_cndmask_b32_e32 v149, v151, v150, vcc
	v_not_b32_e32 v150, v15
	v_or_b32_e32 v151, 0x80000000, v15
	v_cmp_gt_i32_e32 vcc, 0, v15
	v_and_b32_e32 v149, 0xffffff80, v149
	v_sub_u32_e32 v149, v149, v10
	v_cndmask_b32_e32 v15, v151, v150, vcc
	v_and_b32_e32 v15, 0xffffff80, v15
	v_cvt_f32_f16_sdwa v150, v144 dst_sel:DWORD dst_unused:UNUSED_PAD src0_sel:WORD_1
	v_sub_u32_e32 v10, v15, v10
	v_cvt_f32_f16_e32 v15, v144
	v_add_u32_e32 v149, 0x7e, v149
	v_not_b32_e32 v144, v150
	v_or_b32_e32 v151, 0x80000000, v150
	v_cmp_gt_i32_e32 vcc, 0, v150
	v_not_b32_e32 v150, v15
	v_add_u32_e32 v10, 0x7f, v10
	v_cndmask_b32_e32 v144, v151, v144, vcc
	v_or_b32_e32 v151, 0x80000000, v15
	v_cmp_gt_i32_e32 vcc, 0, v15
	v_and_b32_e32 v144, 0xffffff80, v144
	v_sub_u32_e32 v144, v144, v8
	v_cndmask_b32_e32 v15, v151, v150, vcc
	v_and_b32_e32 v15, 0xffffff80, v15
	v_cvt_f32_f16_sdwa v150, v145 dst_sel:DWORD dst_unused:UNUSED_PAD src0_sel:WORD_1
	v_sub_u32_e32 v8, v15, v8
	v_cvt_f32_f16_e32 v15, v145
	v_add_u32_e32 v144, 0x7e, v144
	v_not_b32_e32 v145, v150
	v_or_b32_e32 v151, 0x80000000, v150
	v_cmp_gt_i32_e32 vcc, 0, v150
	v_not_b32_e32 v150, v15
	v_add_u32_e32 v8, 0x7f, v8
	v_cndmask_b32_e32 v145, v151, v145, vcc
	v_or_b32_e32 v151, 0x80000000, v15
	v_cmp_gt_i32_e32 vcc, 0, v15
	v_and_b32_e32 v145, 0xffffff80, v145
	v_sub_u32_e32 v145, v145, v16
	v_cndmask_b32_e32 v15, v151, v150, vcc
	v_and_b32_e32 v15, 0xffffff80, v15
	v_cvt_f32_f16_sdwa v150, v146 dst_sel:DWORD dst_unused:UNUSED_PAD src0_sel:WORD_1
	v_sub_u32_e32 v15, v15, v16
	v_cvt_f32_f16_e32 v16, v146
	v_add_u32_e32 v145, 0x7e, v145
	v_not_b32_e32 v146, v150
	v_or_b32_e32 v151, 0x80000000, v150
	v_cmp_gt_i32_e32 vcc, 0, v150
	v_not_b32_e32 v150, v16
	v_add_u32_e32 v15, 0x7f, v15
	v_cndmask_b32_e32 v146, v151, v146, vcc
	v_or_b32_e32 v151, 0x80000000, v16
	v_cmp_gt_i32_e32 vcc, 0, v16
	v_and_b32_e32 v146, 0xffffff80, v146
	v_sub_u32_e32 v146, v146, v17
	v_cndmask_b32_e32 v16, v151, v150, vcc
	v_and_b32_e32 v16, 0xffffff80, v16
	v_cvt_f32_f16_sdwa v150, v147 dst_sel:DWORD dst_unused:UNUSED_PAD src0_sel:WORD_1
	v_sub_u32_e32 v16, v16, v17
	v_cvt_f32_f16_e32 v17, v147
	v_add_u32_e32 v146, 0x7e, v146
	v_not_b32_e32 v147, v150
	v_or_b32_e32 v151, 0x80000000, v150
	v_cmp_gt_i32_e32 vcc, 0, v150
	v_not_b32_e32 v150, v17
	v_add_u32_e32 v16, 0x7f, v16
	v_cndmask_b32_e32 v147, v151, v147, vcc
	v_or_b32_e32 v151, 0x80000000, v17
	v_cmp_gt_i32_e32 vcc, 0, v17
	v_and_b32_e32 v147, 0xffffff80, v147
	v_sub_u32_e32 v147, v147, v18
	v_cndmask_b32_e32 v17, v151, v150, vcc
	v_and_b32_e32 v17, 0xffffff80, v17
	s_waitcnt vmcnt(0)
; __device__ __forceinline__ unsigned f2key(float f) { const unsigned u = __float_as_uint(f); return (u & 0x80000000u) ? ~u : (u | 0x80000000u); }
; __device__ __forceinline__ void peer_tile(const Args& A, LAS unsigned char* lds, int tile) {
;     ...
;                 { const bf16_t* sp = QRY + m * 2048 + hp * 128 + 32 * g;
;                   const u32x4 s0 = *(const u32x4*)sp, s1 = *(const u32x4*)(sp + 8), s2 = *(const u32x4*)(sp + 16), s3 = *(const u32x4*)(sp + 24);
;                   const unsigned sw[16] = {s0.x, s0.y, s0.z, s0.w, s1.x, s1.y, s1.z, s1.w, s2.x, s2.y, s2.z, s2.w, s3.x, s3.y, s3.z, s3.w};
; #pragma unroll
;                   for (int i = 0; i < 16; ++i) {
;                       const float lo = (float)__builtin_bit_cast(_Float16, (unsigned short)(sw[i] & 0xffffu)), hi = (float)__builtin_bit_cast(_Float16, (unsigned short)(sw[i] >> 16));
;                       const unsigned klo = (f2key(lo) & ~127u) | (unsigned)(127 - (32 * g + 2 * i)), khi = (f2key(hi) & ~127u) | (unsigned)(127 - (32 * g + 2 * i + 1));
;                       if (i < 8) { k0[2 * i] = klo; k0[2 * i + 1] = khi; } else { k1[2 * (i - 8)] = klo; k1[2 * (i - 8) + 1] = khi; } } }
;                 sort16_desc(k0); sort16_desc(k1); merge16(k0, k1);
	v_cvt_f32_f16_sdwa v150, v152 dst_sel:DWORD dst_unused:UNUSED_PAD src0_sel:WORD_1
	v_sub_u32_e32 v17, v17, v18
	v_cvt_f32_f16_e32 v18, v152
	v_add_u32_e32 v147, 0x7e, v147
	v_not_b32_e32 v151, v150
	v_or_b32_e32 v152, 0x80000000, v150
	v_cmp_gt_i32_e32 vcc, 0, v150
	v_add_u32_e32 v17, 0x7f, v17
	s_nop 0
	v_cndmask_b32_e32 v150, v152, v151, vcc
	v_not_b32_e32 v151, v18
	v_or_b32_e32 v152, 0x80000000, v18
	v_cmp_gt_i32_e32 vcc, 0, v18
	v_and_b32_e32 v150, 0xffffff80, v150
	v_sub_u32_e32 v150, v150, v20
	v_cndmask_b32_e32 v18, v152, v151, vcc
	v_and_b32_e32 v18, 0xffffff80, v18
	v_cvt_f32_f16_sdwa v151, v153 dst_sel:DWORD dst_unused:UNUSED_PAD src0_sel:WORD_1
	v_sub_u32_e32 v18, v18, v20
	v_cvt_f32_f16_e32 v20, v153
	v_add_u32_e32 v150, 0x7e, v150
	v_not_b32_e32 v152, v151
	v_or_b32_e32 v153, 0x80000000, v151
	v_cmp_gt_i32_e32 vcc, 0, v151
	v_add_u32_e32 v18, 0x7f, v18
	v_max_u32_e32 v161, v18, v150
	v_cndmask_b32_e32 v151, v153, v152, vcc
	v_not_b32_e32 v152, v20
	v_or_b32_e32 v153, 0x80000000, v20
	v_cmp_gt_i32_e32 vcc, 0, v20
	v_and_b32_e32 v151, 0xffffff80, v151
	v_sub_u32_e32 v151, v151, v21
	v_cndmask_b32_e32 v20, v153, v152, vcc
	v_and_b32_e32 v20, 0xffffff80, v20
	v_cvt_f32_f16_sdwa v152, v154 dst_sel:DWORD dst_unused:UNUSED_PAD src0_sel:WORD_1
	v_sub_u32_e32 v20, v20, v21
	v_cvt_f32_f16_e32 v21, v154
	v_add_u32_e32 v151, 0x7e, v151
	v_not_b32_e32 v153, v152
	v_or_b32_e32 v154, 0x80000000, v152
	v_cmp_gt_i32_e32 vcc, 0, v152
	v_add_u32_e32 v20, 0x7f, v20
	v_min_u32_e32 v18, v18, v150
	v_cndmask_b32_e32 v152, v154, v153, vcc
	v_not_b32_e32 v153, v21
	v_or_b32_e32 v154, 0x80000000, v21
	v_cmp_gt_i32_e32 vcc, 0, v21
	v_and_b32_e32 v152, 0xffffff80, v152
	v_sub_u32_e32 v152, v152, v22
	v_cndmask_b32_e32 v21, v154, v153, vcc
	v_and_b32_e32 v21, 0xffffff80, v21
	v_cvt_f32_f16_sdwa v153, v155 dst_sel:DWORD dst_unused:UNUSED_PAD src0_sel:WORD_1
	v_sub_u32_e32 v21, v21, v22
	v_cvt_f32_f16_e32 v22, v155
	v_add_u32_e32 v152, 0x7e, v152
	v_not_b32_e32 v154, v153
	v_or_b32_e32 v155, 0x80000000, v153
	v_cmp_gt_i32_e32 vcc, 0, v153
	v_add_u32_e32 v21, 0x7f, v21
	v_max_u32_e32 v150, v151, v20
	v_cndmask_b32_e32 v153, v155, v154, vcc
	v_not_b32_e32 v154, v22
	v_or_b32_e32 v155, 0x80000000, v22
	v_cmp_gt_i32_e32 vcc, 0, v22
	v_and_b32_e32 v153, 0xffffff80, v153
	v_sub_u32_e32 v153, v153, v23
	v_cndmask_b32_e32 v22, v155, v154, vcc
	v_cvt_f32_f16_sdwa v154, v0 dst_sel:DWORD dst_unused:UNUSED_PAD src0_sel:WORD_1
	v_cvt_f32_f16_e32 v0, v0
	v_and_b32_e32 v22, 0xffffff80, v22
	v_sub_u32_e32 v22, v22, v23
	v_not_b32_e32 v23, v154
	v_or_b32_e32 v155, 0x80000000, v154
	v_cmp_gt_i32_e32 vcc, 0, v154
	v_not_b32_e32 v154, v0
	v_add_u32_e32 v153, 0x7e, v153
	v_cndmask_b32_e32 v23, v155, v23, vcc
	v_or_b32_e32 v155, 0x80000000, v0
	v_cmp_gt_i32_e32 vcc, 0, v0
	v_and_b32_e32 v23, 0xffffff80, v23
	v_sub_u32_e32 v23, v23, v24
	v_cndmask_b32_e32 v0, v155, v154, vcc
	v_cvt_f32_f16_sdwa v154, v1 dst_sel:DWORD dst_unused:UNUSED_PAD src0_sel:WORD_1
	v_cvt_f32_f16_e32 v1, v1
	v_and_b32_e32 v0, 0xffffff80, v0
	v_sub_u32_e32 v0, v0, v24
	v_not_b32_e32 v24, v154
	v_or_b32_e32 v155, 0x80000000, v154
	v_cmp_gt_i32_e32 vcc, 0, v154
	v_not_b32_e32 v154, v1
	v_add_u32_e32 v22, 0x7f, v22
	v_cndmask_b32_e32 v24, v155, v24, vcc
	v_or_b32_e32 v155, 0x80000000, v1
	v_cmp_gt_i32_e32 vcc, 0, v1
	v_and_b32_e32 v24, 0xffffff80, v24
	v_sub_u32_e32 v24, v24, v25
	v_cndmask_b32_e32 v1, v155, v154, vcc
	v_cvt_f32_f16_sdwa v154, v2 dst_sel:DWORD dst_unused:UNUSED_PAD src0_sel:WORD_1
	v_cvt_f32_f16_e32 v2, v2
	v_and_b32_e32 v1, 0xffffff80, v1
	v_sub_u32_e32 v1, v1, v25
	v_not_b32_e32 v25, v154
	v_or_b32_e32 v155, 0x80000000, v154
	v_cmp_gt_i32_e32 vcc, 0, v154
	v_not_b32_e32 v154, v2
	v_add_u32_e32 v23, 0x7e, v23
	v_cndmask_b32_e32 v25, v155, v25, vcc
	v_or_b32_e32 v155, 0x80000000, v2
	v_cmp_gt_i32_e32 vcc, 0, v2
	v_and_b32_e32 v25, 0xffffff80, v25
	v_sub_u32_e32 v25, v25, v26
	v_cndmask_b32_e32 v2, v155, v154, vcc
	v_cvt_f32_f16_sdwa v154, v3 dst_sel:DWORD dst_unused:UNUSED_PAD src0_sel:WORD_1
	v_cvt_f32_f16_e32 v3, v3
	v_and_b32_e32 v2, 0xffffff80, v2
	v_sub_u32_e32 v2, v2, v26
	v_not_b32_e32 v26, v154
	v_or_b32_e32 v155, 0x80000000, v154
	v_cmp_gt_i32_e32 vcc, 0, v154
	v_not_b32_e32 v154, v3
	v_add_u32_e32 v0, 0x7f, v0
	v_cndmask_b32_e32 v26, v155, v26, vcc
	v_or_b32_e32 v155, 0x80000000, v3
	v_cmp_gt_i32_e32 vcc, 0, v3
	v_and_b32_e32 v26, 0xffffff80, v26
	v_sub_u32_e32 v26, v26, v28
	v_cndmask_b32_e32 v3, v155, v154, vcc
	v_and_b32_e32 v3, 0xffffff80, v3
	v_sub_u32_e32 v3, v3, v28
	v_add_u32_e32 v24, 0x7e, v24
	v_add_u32_e32 v1, 0x7f, v1
	v_add_u32_e32 v25, 0x7e, v25
	v_add_u32_e32 v2, 0x7f, v2
	v_add_u32_e32 v26, 0x7e, v26
	v_add_u32_e32 v3, 0x7f, v3
	v_max_u32_e32 v28, v4, v5
	v_min_u32_e32 v4, v4, v5
	v_max_u32_e32 v5, v143, v14
	v_min_u32_e32 v14, v143, v14
	v_max_u32_e32 v143, v12, v148
	v_min_u32_e32 v12, v12, v148
	v_max_u32_e32 v148, v149, v10
	v_min_u32_e32 v10, v149, v10
	v_max_u32_e32 v149, v8, v144
	v_min_u32_e32 v8, v8, v144
	v_max_u32_e32 v144, v145, v15
	v_min_u32_e32 v15, v145, v15
	v_max_u32_e32 v145, v16, v146
	v_min_u32_e32 v16, v16, v146
	v_max_u32_e32 v146, v147, v17
	v_min_u32_e32 v17, v147, v17
	v_min_u32_e32 v20, v151, v20
	v_max_u32_e32 v151, v21, v152
	v_min_u32_e32 v21, v21, v152
	v_max_u32_e32 v152, v153, v22
	v_min_u32_e32 v22, v153, v22
	v_max_u32_e32 v153, v0, v23
	v_min_u32_e32 v0, v0, v23
	v_max_u32_e32 v23, v24, v1
	v_min_u32_e32 v1, v24, v1
	v_max_u32_e32 v24, v2, v25
	v_min_u32_e32 v2, v2, v25
	v_max_u32_e32 v25, v26, v3
	v_min_u32_e32 v3, v26, v3
	v_max_u32_e32 v147, v28, v14
	v_min_u32_e32 v14, v28, v14
	v_max_u32_e32 v28, v4, v5
	v_min_u32_e32 v4, v4, v5
; #define CE_DESC(a, b) do { const unsigned _mx = (a) > (b) ? (a) : (b), _mn = (a) > (b) ? (b) : (a); (a) = _mx; (b) = _mn; } while (0)
; __device__ __forceinline__ void sort16_desc(unsigned (&k)[16]) {
; #pragma unroll
;     for (int size = 2; size <= 16; size <<= 1)
; #pragma unroll
;         for (int stride = size >> 1; stride > 0; stride >>= 1)
; #pragma unroll
;             for (int i = 0; i < 16; ++i) { const int j = i ^ stride;
;                 if (j > i) { if ((i & size) == 0) CE_DESC(k[i], k[j]); else CE_DESC(k[j], k[i]); } }
; }
	v_max_u32_e32 v5, v10, v143
	v_min_u32_e32 v10, v10, v143
	v_max_u32_e32 v143, v148, v12
	v_min_u32_e32 v12, v148, v12
	v_max_u32_e32 v148, v149, v15
	v_min_u32_e32 v15, v149, v15
	v_max_u32_e32 v149, v8, v144
	v_min_u32_e32 v8, v8, v144
	v_max_u32_e32 v144, v17, v145
	v_min_u32_e32 v17, v17, v145
	v_max_u32_e32 v145, v146, v16
	v_min_u32_e32 v16, v146, v16
	v_max_u32_e32 v26, v161, v20
	v_min_u32_e32 v20, v161, v20
	v_max_u32_e32 v161, v18, v150
	v_min_u32_e32 v18, v18, v150
	v_max_u32_e32 v150, v22, v151
	v_min_u32_e32 v22, v22, v151
	v_max_u32_e32 v151, v152, v21
	v_min_u32_e32 v21, v152, v21
	v_max_u32_e32 v152, v153, v1
	v_min_u32_e32 v1, v153, v1
	v_max_u32_e32 v153, v0, v23
	v_min_u32_e32 v0, v0, v23
	v_max_u32_e32 v23, v3, v24
	v_min_u32_e32 v3, v3, v24
	v_max_u32_e32 v24, v25, v2
	v_min_u32_e32 v2, v25, v2
	v_max_u32_e32 v146, v147, v28
	v_min_u32_e32 v28, v147, v28
	v_max_u32_e32 v147, v14, v4
	v_min_u32_e32 v4, v14, v4
	v_max_u32_e32 v14, v12, v10
	v_min_u32_e32 v10, v12, v10
	v_max_u32_e32 v12, v143, v5
	v_min_u32_e32 v5, v143, v5
	v_max_u32_e32 v143, v148, v149
	v_min_u32_e32 v148, v148, v149
	v_max_u32_e32 v149, v15, v8
	v_min_u32_e32 v8, v15, v8
	v_max_u32_e32 v15, v16, v17
	v_min_u32_e32 v16, v16, v17
	v_max_u32_e32 v17, v145, v144
	v_min_u32_e32 v144, v145, v144
	v_max_u32_e32 v25, v26, v161
	v_min_u32_e32 v26, v26, v161
	v_max_u32_e32 v161, v20, v18
	v_min_u32_e32 v18, v20, v18
	v_max_u32_e32 v20, v21, v22
	v_min_u32_e32 v21, v21, v22
	v_max_u32_e32 v22, v151, v150
	v_min_u32_e32 v150, v151, v150
	v_max_u32_e32 v151, v152, v153
	v_min_u32_e32 v152, v152, v153
	v_max_u32_e32 v153, v1, v0
	v_min_u32_e32 v0, v1, v0
	v_max_u32_e32 v1, v2, v3
	v_min_u32_e32 v2, v2, v3
	v_max_u32_e32 v3, v24, v23
	v_min_u32_e32 v23, v24, v23
	v_max_u32_e32 v145, v146, v10
	v_min_u32_e32 v10, v146, v10
	v_max_u32_e32 v146, v28, v14
	v_min_u32_e32 v14, v28, v14
	v_max_u32_e32 v28, v147, v5
	v_min_u32_e32 v5, v147, v5
	v_max_u32_e32 v147, v4, v12
	v_min_u32_e32 v4, v4, v12
	v_max_u32_e32 v12, v16, v143
	v_min_u32_e32 v16, v16, v143
	v_max_u32_e32 v143, v15, v148
	v_min_u32_e32 v15, v15, v148
	v_max_u32_e32 v148, v144, v149
	v_min_u32_e32 v144, v144, v149
	v_max_u32_e32 v149, v17, v8
	v_min_u32_e32 v8, v17, v8
	v_max_u32_e32 v24, v25, v21
	v_min_u32_e32 v21, v25, v21
	v_max_u32_e32 v25, v26, v20
	v_min_u32_e32 v20, v26, v20
	v_max_u32_e32 v26, v161, v150
	v_min_u32_e32 v150, v161, v150
	v_max_u32_e32 v161, v18, v22
	v_min_u32_e32 v18, v18, v22
	v_max_u32_e32 v22, v2, v151
	v_min_u32_e32 v2, v2, v151
	v_max_u32_e32 v151, v1, v152
	v_min_u32_e32 v1, v1, v152
	v_max_u32_e32 v152, v23, v153
	v_min_u32_e32 v23, v23, v153
	v_max_u32_e32 v153, v3, v0
	v_min_u32_e32 v0, v3, v0
	v_max_u32_e32 v17, v145, v28
	v_min_u32_e32 v28, v145, v28
	v_max_u32_e32 v145, v146, v147
	v_min_u32_e32 v146, v146, v147
	v_max_u32_e32 v147, v10, v5
	v_min_u32_e32 v5, v10, v5
	v_max_u32_e32 v10, v14, v4
	v_min_u32_e32 v4, v14, v4
	v_max_u32_e32 v14, v144, v16
	v_min_u32_e32 v16, v144, v16
	v_max_u32_e32 v144, v8, v15
	v_min_u32_e32 v8, v8, v15
	v_max_u32_e32 v15, v148, v12
	v_min_u32_e32 v12, v148, v12
	v_max_u32_e32 v148, v149, v143
	v_min_u32_e32 v143, v149, v143
	v_max_u32_e32 v3, v24, v26
	v_min_u32_e32 v24, v24, v26
	v_max_u32_e32 v26, v25, v161
	v_min_u32_e32 v25, v25, v161
	v_max_u32_e32 v161, v21, v150
	v_min_u32_e32 v21, v21, v150
	v_max_u32_e32 v150, v20, v18
	v_min_u32_e32 v18, v20, v18
	v_max_u32_e32 v20, v23, v2
	v_min_u32_e32 v2, v23, v2
	v_max_u32_e32 v23, v0, v1
	v_min_u32_e32 v0, v0, v1
	v_max_u32_e32 v1, v152, v22
	v_min_u32_e32 v22, v152, v22
	v_max_u32_e32 v152, v153, v151
	v_min_u32_e32 v151, v153, v151
	v_max_u32_e32 v149, v17, v145
	v_min_u32_e32 v17, v17, v145
	v_max_u32_e32 v145, v28, v146
	v_min_u32_e32 v28, v28, v146
	v_max_u32_e32 v146, v147, v10
	v_min_u32_e32 v10, v147, v10
	v_max_u32_e32 v147, v5, v4
	v_min_u32_e32 v4, v5, v4
	v_max_u32_e32 v5, v8, v16
	v_min_u32_e32 v8, v8, v16
	v_max_u32_e32 v16, v144, v14
	v_min_u32_e32 v14, v144, v14
	v_max_u32_e32 v144, v143, v12
	v_min_u32_e32 v12, v143, v12
	v_max_u32_e32 v143, v148, v15
	v_min_u32_e32 v15, v148, v15
	v_max_u32_e32 v153, v3, v26
	v_min_u32_e32 v3, v3, v26
	v_max_u32_e32 v26, v24, v25
	v_min_u32_e32 v24, v24, v25
	v_max_u32_e32 v25, v161, v150
	v_min_u32_e32 v150, v161, v150
	v_max_u32_e32 v161, v21, v18
	v_min_u32_e32 v18, v21, v18
	v_max_u32_e32 v21, v0, v2
	v_min_u32_e32 v0, v0, v2
	v_max_u32_e32 v2, v23, v20
	v_min_u32_e32 v20, v23, v20
	v_max_u32_e32 v23, v151, v22
	v_min_u32_e32 v22, v151, v22
	v_max_u32_e32 v151, v152, v1
	v_min_u32_e32 v1, v152, v1
	v_max_u32_e32 v148, v149, v8
	v_min_u32_e32 v8, v149, v8
	v_max_u32_e32 v149, v17, v5
	v_min_u32_e32 v5, v17, v5
	v_max_u32_e32 v17, v145, v14
	v_min_u32_e32 v14, v145, v14
	v_max_u32_e32 v145, v28, v16
	v_min_u32_e32 v16, v28, v16
	v_max_u32_e32 v28, v146, v12
	v_min_u32_e32 v12, v146, v12
	v_max_u32_e32 v146, v10, v144
	v_min_u32_e32 v10, v10, v144
	v_max_u32_e32 v144, v147, v15
	v_min_u32_e32 v15, v147, v15
	v_max_u32_e32 v147, v4, v143
	v_min_u32_e32 v4, v4, v143
	v_max_u32_e32 v152, v153, v0
	v_min_u32_e32 v0, v153, v0
	v_max_u32_e32 v153, v3, v21
	v_min_u32_e32 v3, v3, v21
	v_max_u32_e32 v21, v26, v20
	v_min_u32_e32 v20, v26, v20
	v_max_u32_e32 v26, v24, v2
	v_min_u32_e32 v2, v24, v2
	v_max_u32_e32 v24, v25, v22
	v_min_u32_e32 v22, v25, v22
	v_max_u32_e32 v25, v150, v23
	v_min_u32_e32 v23, v150, v23
	v_max_u32_e32 v150, v161, v1
	v_min_u32_e32 v1, v161, v1
	v_max_u32_e32 v161, v18, v151
	v_min_u32_e32 v18, v18, v151
	v_max_u32_e32 v143, v148, v28
	v_min_u32_e32 v28, v148, v28
	v_max_u32_e32 v148, v149, v146
	v_min_u32_e32 v146, v149, v146
; #define CE_DESC(a, b) do { const unsigned _mx = (a) > (b) ? (a) : (b), _mn = (a) > (b) ? (b) : (a); (a) = _mx; (b) = _mn; } while (0)
; __device__ __forceinline__ void sort16_desc(unsigned (&k)[16]) {
; #pragma unroll
;     for (int size = 2; size <= 16; size <<= 1)
; #pragma unroll
;         for (int stride = size >> 1; stride > 0; stride >>= 1)
; #pragma unroll
;             for (int i = 0; i < 16; ++i) { const int j = i ^ stride;
;                 if (j > i) { if ((i & size) == 0) CE_DESC(k[i], k[j]); else CE_DESC(k[j], k[i]); } }
; }
; __device__ __forceinline__ void merge16(unsigned (&a)[16], const unsigned (&b)[16]) {
; #pragma unroll
;     for (int i = 0; i < 16; ++i) a[i] = a[i] > b[15 - i] ? a[i] : b[15 - i];
; #pragma unroll
;     for (int stride = 8; stride > 0; stride >>= 1)
; #pragma unroll
;         for (int i = 0; i < 16; ++i) { const int j = i ^ stride; if (j > i) CE_DESC(a[i], a[j]); }
; }
; __device__ __forceinline__ void peer_tile(const Args& A, LAS unsigned char* lds, int tile) {
;     ...
;                 for (int msk = 16; msk <= 32; msk <<= 1) {
; #pragma unroll
;                     for (int i = 0; i < 16; ++i) k1[i] = (unsigned)__shfl_xor((int)k0[i], msk);
;                     merge16(k0, k1); }
	v_max_u32_e32 v149, v17, v144
	v_min_u32_e32 v17, v17, v144
	v_max_u32_e32 v144, v145, v147
	v_min_u32_e32 v145, v145, v147
	v_max_u32_e32 v147, v8, v12
	v_min_u32_e32 v8, v8, v12
	v_max_u32_e32 v12, v5, v10
	v_min_u32_e32 v5, v5, v10
	v_max_u32_e32 v10, v14, v15
	v_min_u32_e32 v14, v14, v15
	v_max_u32_e32 v15, v16, v4
	v_min_u32_e32 v4, v16, v4
	v_max_u32_e32 v151, v152, v24
	v_min_u32_e32 v24, v152, v24
	v_max_u32_e32 v152, v153, v25
	v_min_u32_e32 v25, v153, v25
	v_max_u32_e32 v153, v21, v150
	v_min_u32_e32 v21, v21, v150
	v_max_u32_e32 v150, v26, v161
	v_min_u32_e32 v26, v26, v161
	v_max_u32_e32 v161, v0, v22
	v_min_u32_e32 v0, v0, v22
	v_max_u32_e32 v22, v3, v23
	v_min_u32_e32 v3, v3, v23
	v_max_u32_e32 v23, v20, v1
	v_min_u32_e32 v1, v20, v1
	v_max_u32_e32 v20, v2, v18
	v_min_u32_e32 v2, v2, v18
	v_max_u32_e32 v16, v143, v149
	v_min_u32_e32 v143, v143, v149
	v_max_u32_e32 v149, v148, v144
	v_min_u32_e32 v144, v148, v144
	v_max_u32_e32 v148, v28, v17
	v_min_u32_e32 v17, v28, v17
	v_max_u32_e32 v28, v146, v145
	v_min_u32_e32 v145, v146, v145
	v_max_u32_e32 v146, v147, v10
	v_min_u32_e32 v10, v147, v10
	v_max_u32_e32 v147, v12, v15
	v_min_u32_e32 v12, v12, v15
	v_max_u32_e32 v15, v8, v14
	v_min_u32_e32 v8, v8, v14
	v_max_u32_e32 v14, v5, v4
	v_min_u32_e32 v4, v5, v4
	v_max_u32_e32 v18, v151, v153
	v_min_u32_e32 v151, v151, v153
	v_max_u32_e32 v153, v152, v150
	v_min_u32_e32 v150, v152, v150
	v_max_u32_e32 v152, v24, v21
	v_min_u32_e32 v21, v24, v21
	v_max_u32_e32 v24, v25, v26
	v_min_u32_e32 v25, v25, v26
	v_max_u32_e32 v26, v161, v23
	v_min_u32_e32 v23, v161, v23
	v_max_u32_e32 v161, v22, v20
	v_min_u32_e32 v20, v22, v20
	v_max_u32_e32 v22, v0, v1
	v_min_u32_e32 v0, v0, v1
	v_max_u32_e32 v1, v3, v2
	v_min_u32_e32 v2, v3, v2
	v_min_u32_e32 v5, v16, v149
	v_min_u32_e32 v154, v143, v144
	v_min_u32_e32 v155, v148, v28
	v_min_u32_e32 v156, v17, v145
	v_min_u32_e32 v157, v146, v147
	v_min_u32_e32 v158, v10, v12
	v_min_u32_e32 v159, v15, v14
	v_min_u32_e32 v160, v8, v4
	v_min_u32_e32 v3, v18, v153
	v_min_u32_e32 v162, v151, v150
	v_min_u32_e32 v163, v152, v24
	v_min_u32_e32 v164, v21, v25
	v_min_u32_e32 v165, v26, v161
	v_min_u32_e32 v166, v23, v20
	v_min_u32_e32 v167, v22, v1
	v_min_u32_e32 v168, v0, v2
	v_max3_u32 v16, v16, v149, v168
	v_max3_u32 v0, v5, v0, v2
	v_max3_u32 v2, v143, v144, v167
	v_max3_u32 v1, v154, v22, v1
	v_max3_u32 v5, v148, v28, v166
	v_max3_u32 v20, v155, v23, v20
	v_max3_u32 v17, v17, v145, v165
	v_max3_u32 v22, v156, v26, v161
	v_max3_u32 v23, v146, v147, v164
	v_max3_u32 v21, v157, v21, v25
	v_max3_u32 v10, v10, v12, v163
	v_max3_u32 v12, v158, v152, v24
	v_max3_u32 v14, v15, v14, v162
	v_max3_u32 v15, v159, v151, v150
	v_max3_u32 v3, v8, v4, v3
	v_max3_u32 v4, v160, v18, v153
	v_max_u32_e32 v8, v16, v23
	v_min_u32_e32 v16, v16, v23
	v_max_u32_e32 v18, v0, v21
	v_min_u32_e32 v0, v0, v21
	v_max_u32_e32 v21, v2, v10
	v_min_u32_e32 v2, v2, v10
	v_max_u32_e32 v10, v1, v12
	v_min_u32_e32 v1, v1, v12
	v_max_u32_e32 v12, v5, v14
	v_min_u32_e32 v5, v5, v14
	v_max_u32_e32 v14, v20, v15
	v_min_u32_e32 v15, v20, v15
	v_max_u32_e32 v20, v17, v3
	v_min_u32_e32 v3, v17, v3
	v_max_u32_e32 v17, v22, v4
	v_min_u32_e32 v4, v22, v4
	v_max_u32_e32 v22, v8, v12
	v_min_u32_e32 v8, v8, v12
	v_max_u32_e32 v12, v18, v14
	v_min_u32_e32 v14, v18, v14
	v_max_u32_e32 v18, v21, v20
	v_min_u32_e32 v20, v21, v20
	v_max_u32_e32 v21, v10, v17
	v_min_u32_e32 v10, v10, v17
	v_max_u32_e32 v17, v16, v5
	v_min_u32_e32 v5, v16, v5
	v_max_u32_e32 v16, v0, v15
	v_min_u32_e32 v0, v0, v15
	v_max_u32_e32 v15, v2, v3
	v_min_u32_e32 v2, v2, v3
	v_max_u32_e32 v3, v1, v4
	v_min_u32_e32 v1, v1, v4
	v_max_u32_e32 v4, v22, v18
	v_min_u32_e32 v18, v22, v18
	v_max_u32_e32 v22, v12, v21
	v_min_u32_e32 v12, v12, v21
	v_max_u32_e32 v21, v8, v20
	v_min_u32_e32 v8, v8, v20
	v_max_u32_e32 v20, v14, v10
	v_min_u32_e32 v10, v14, v10
	v_max_u32_e32 v14, v17, v15
	v_min_u32_e32 v15, v17, v15
	v_max_u32_e32 v17, v16, v3
	v_min_u32_e32 v3, v16, v3
	v_max_u32_e32 v16, v5, v2
	v_min_u32_e32 v2, v5, v2
	v_max_u32_e32 v5, v0, v1
	v_min_u32_e32 v0, v0, v1
	v_max_u32_e32 v1, v4, v22
	v_min_u32_e32 v4, v4, v22
	v_max_u32_e32 v22, v18, v12
	v_min_u32_e32 v12, v18, v12
	v_max_u32_e32 v18, v21, v20
	v_min_u32_e32 v20, v21, v20
	v_max_u32_e32 v21, v8, v10
	v_min_u32_e32 v8, v8, v10
	v_max_u32_e32 v10, v14, v17
	v_min_u32_e32 v14, v14, v17
	v_max_u32_e32 v17, v15, v3
	v_min_u32_e32 v3, v15, v3
	v_max_u32_e32 v15, v16, v5
	v_min_u32_e32 v5, v16, v5
	v_max_u32_e32 v16, v2, v0
	v_min_u32_e32 v0, v2, v0
	ds_bpermute_b32 v2, v27, v1
	ds_bpermute_b32 v23, v27, v4
	ds_bpermute_b32 v24, v27, v22
	ds_bpermute_b32 v25, v27, v12
	ds_bpermute_b32 v26, v27, v18
	ds_bpermute_b32 v28, v27, v20
	ds_bpermute_b32 v143, v27, v21
	ds_bpermute_b32 v144, v27, v8
	ds_bpermute_b32 v145, v27, v10
	ds_bpermute_b32 v146, v27, v14
	ds_bpermute_b32 v147, v27, v17
	ds_bpermute_b32 v148, v27, v0
	ds_bpermute_b32 v149, v27, v16
	ds_bpermute_b32 v150, v27, v5
	ds_bpermute_b32 v151, v27, v15
	ds_bpermute_b32 v27, v27, v3
	s_waitcnt lgkmcnt(4)
	v_max_u32_e32 v1, v1, v148
	s_waitcnt lgkmcnt(3)
	v_max_u32_e32 v4, v4, v149
	s_waitcnt lgkmcnt(2)
	v_max_u32_e32 v22, v22, v150
	s_waitcnt lgkmcnt(1)
	v_max_u32_e32 v12, v12, v151
	s_waitcnt lgkmcnt(0)
; __device__ __forceinline__ void peer_tile(const Args& A, LAS unsigned char* lds, int tile) {
;     ...
;                 for (int msk = 16; msk <= 32; msk <<= 1) {
; #pragma unroll
;                     for (int i = 0; i < 16; ++i) k1[i] = (unsigned)__shfl_xor((int)k0[i], msk);
;                     merge16(k0, k1); }
; #pragma unroll
;                 for (int i = 0; i < 16; ++i) LA[hh][p][i] = k0[i];
;             }
;         }
;         {
;             const int h = 4 * hg + g;
;             unsigned L2[2][16];
; #pragma unroll
;             for (int p = 0; p < 2; ++p)
; #pragma unroll
;                 for (int i = 0; i < 16; ++i) L2[p][i] = (g & 2) ? ((g & 1) ? LA[3][p][i] : LA[2][p][i]) : ((g & 1) ? LA[1][p][i] : LA[0][p][i]);
	v_max_u32_e32 v18, v18, v27
	v_max_u32_e32 v20, v20, v147
	v_max_u32_e32 v21, v21, v146
	v_max_u32_e32 v8, v8, v145
	v_max_u32_e32 v10, v10, v144
	v_max_u32_e32 v14, v14, v143
	v_max_u32_e32 v17, v17, v28
	v_max_u32_e32 v3, v3, v26
	v_max_u32_e32 v15, v15, v25
	v_max_u32_e32 v5, v5, v24
	v_max_u32_e32 v16, v16, v23
	v_max_u32_e32 v0, v0, v2
	v_max_u32_e32 v2, v1, v10
	v_min_u32_e32 v1, v1, v10
	v_max_u32_e32 v10, v4, v14
	v_min_u32_e32 v4, v4, v14
	v_max_u32_e32 v14, v22, v17
	v_min_u32_e32 v17, v22, v17
	v_max_u32_e32 v22, v12, v3
	v_min_u32_e32 v3, v12, v3
	v_max_u32_e32 v12, v18, v15
	v_min_u32_e32 v15, v18, v15
	v_max_u32_e32 v18, v20, v5
	v_min_u32_e32 v5, v20, v5
	v_max_u32_e32 v20, v21, v16
	v_min_u32_e32 v16, v21, v16
	v_max_u32_e32 v21, v8, v0
	v_min_u32_e32 v0, v8, v0
	v_max_u32_e32 v8, v2, v12
	v_min_u32_e32 v2, v2, v12
	v_max_u32_e32 v12, v10, v18
	v_min_u32_e32 v10, v10, v18
	v_max_u32_e32 v18, v14, v20
	v_min_u32_e32 v14, v14, v20
	v_max_u32_e32 v20, v22, v21
	v_min_u32_e32 v21, v22, v21
	v_max_u32_e32 v22, v1, v15
	v_min_u32_e32 v1, v1, v15
	v_max_u32_e32 v15, v4, v5
	v_min_u32_e32 v4, v4, v5
	v_max_u32_e32 v5, v17, v16
	v_min_u32_e32 v16, v17, v16
	v_max_u32_e32 v17, v3, v0
	v_min_u32_e32 v0, v3, v0
	v_max_u32_e32 v3, v8, v18
	v_min_u32_e32 v8, v8, v18
	v_max_u32_e32 v18, v12, v20
	v_min_u32_e32 v12, v12, v20
	v_max_u32_e32 v20, v2, v14
	v_min_u32_e32 v2, v2, v14
	v_max_u32_e32 v14, v10, v21
	v_min_u32_e32 v10, v10, v21
	v_max_u32_e32 v21, v22, v5
	v_min_u32_e32 v5, v22, v5
	v_max_u32_e32 v22, v15, v17
	v_min_u32_e32 v15, v15, v17
	v_max_u32_e32 v17, v1, v16
	v_min_u32_e32 v1, v1, v16
	v_max_u32_e32 v16, v4, v0
	v_min_u32_e32 v0, v4, v0
	v_max_u32_e32 v4, v3, v18
	v_min_u32_e32 v3, v3, v18
	v_max_u32_e32 v18, v8, v12
	v_min_u32_e32 v8, v8, v12
	v_max_u32_e32 v12, v20, v14
	v_min_u32_e32 v14, v20, v14
	v_max_u32_e32 v20, v2, v10
	v_min_u32_e32 v2, v2, v10
	v_max_u32_e32 v10, v21, v22
	v_min_u32_e32 v21, v21, v22
	v_max_u32_e32 v22, v5, v15
	v_min_u32_e32 v5, v5, v15
	v_max_u32_e32 v15, v17, v16
	v_min_u32_e32 v16, v17, v16
	v_max_u32_e32 v17, v1, v0
	v_min_u32_e32 v0, v1, v0
	ds_bpermute_b32 v1, v29, v4
	ds_bpermute_b32 v23, v29, v3
	ds_bpermute_b32 v24, v29, v18
	ds_bpermute_b32 v25, v29, v8
	ds_bpermute_b32 v26, v29, v12
	ds_bpermute_b32 v27, v29, v14
	ds_bpermute_b32 v28, v29, v20
	ds_bpermute_b32 v143, v29, v2
	ds_bpermute_b32 v144, v29, v10
	ds_bpermute_b32 v145, v29, v21
	ds_bpermute_b32 v146, v29, v22
	ds_bpermute_b32 v147, v29, v0
	ds_bpermute_b32 v148, v29, v17
	ds_bpermute_b32 v149, v29, v16
	ds_bpermute_b32 v150, v29, v15
	ds_bpermute_b32 v29, v29, v5
	s_waitcnt lgkmcnt(4)
	v_max_u32_e32 v4, v4, v147
	s_waitcnt lgkmcnt(3)
	v_max_u32_e32 v3, v3, v148
	s_waitcnt lgkmcnt(2)
	v_max_u32_e32 v18, v18, v149
	s_waitcnt lgkmcnt(1)
	v_max_u32_e32 v8, v8, v150
	s_waitcnt lgkmcnt(0)
	v_max_u32_e32 v12, v12, v29
	v_max_u32_e32 v14, v14, v146
	v_max_u32_e32 v20, v20, v145
	v_max_u32_e32 v2, v2, v144
	v_max_u32_e32 v10, v10, v143
	v_max_u32_e32 v21, v21, v28
	v_max_u32_e32 v22, v22, v27
	v_max_u32_e32 v5, v5, v26
	v_max_u32_e32 v15, v15, v25
	v_max_u32_e32 v16, v16, v24
	v_max_u32_e32 v17, v17, v23
	v_max_u32_e32 v0, v0, v1
	v_max_u32_e32 v1, v4, v10
	v_min_u32_e32 v4, v4, v10
	v_max_u32_e32 v10, v3, v21
	v_min_u32_e32 v3, v3, v21
	v_max_u32_e32 v21, v18, v22
	v_min_u32_e32 v18, v18, v22
	v_max_u32_e32 v22, v8, v5
	v_min_u32_e32 v5, v8, v5
	v_max_u32_e32 v8, v12, v15
	v_min_u32_e32 v12, v12, v15
	v_max_u32_e32 v15, v14, v16
	v_min_u32_e32 v14, v14, v16
	v_max_u32_e32 v16, v20, v17
	v_min_u32_e32 v17, v20, v17
	v_max_u32_e32 v20, v2, v0
	v_min_u32_e32 v0, v2, v0
	v_max_u32_e32 v2, v1, v8
	v_min_u32_e32 v1, v1, v8
	v_max_u32_e32 v8, v10, v15
	v_min_u32_e32 v10, v10, v15
	v_max_u32_e32 v15, v21, v16
	v_min_u32_e32 v16, v21, v16
	v_max_u32_e32 v21, v22, v20
	v_min_u32_e32 v20, v22, v20
	v_max_u32_e32 v22, v4, v12
	v_min_u32_e32 v4, v4, v12
	v_max_u32_e32 v12, v3, v14
	v_min_u32_e32 v3, v3, v14
	v_max_u32_e32 v14, v18, v17
	v_min_u32_e32 v17, v18, v17
	v_max_u32_e32 v18, v5, v0
	v_min_u32_e32 v0, v5, v0
	v_max_u32_e32 v5, v2, v15
	v_min_u32_e32 v2, v2, v15
	v_max_u32_e32 v15, v8, v21
	v_min_u32_e32 v8, v8, v21
	v_max_u32_e32 v21, v1, v16
	v_min_u32_e32 v1, v1, v16
	v_max_u32_e32 v16, v10, v20
	v_min_u32_e32 v10, v10, v20
	v_max_u32_e32 v20, v22, v14
	v_min_u32_e32 v14, v22, v14
	v_max_u32_e32 v22, v12, v18
	v_min_u32_e32 v12, v12, v18
	v_max_u32_e32 v18, v4, v17
	v_min_u32_e32 v4, v4, v17
	v_max_u32_e32 v17, v3, v0
	v_min_u32_e32 v0, v3, v0
	v_max_u32_e32 v3, v5, v15
	v_min_u32_e32 v5, v5, v15
	v_max_u32_e32 v15, v2, v8
	v_min_u32_e32 v2, v2, v8
	v_max_u32_e32 v8, v21, v16
	v_min_u32_e32 v16, v21, v16
	v_max_u32_e32 v21, v1, v10
	v_min_u32_e32 v1, v1, v10
	v_max_u32_e32 v10, v20, v22
	v_min_u32_e32 v20, v20, v22
	v_max_u32_e32 v22, v14, v12
	v_min_u32_e32 v12, v14, v12
	v_max_u32_e32 v14, v18, v17
	v_min_u32_e32 v17, v18, v17
	v_max_u32_e32 v18, v4, v0
	v_min_u32_e32 v0, v4, v0
	v_and_b32_e32 v4, 16, v19
	v_cmp_eq_u32_e32 vcc, 0, v4
	v_cndmask_b32_e64 v23, v77, v45, s[0:1]
	v_cndmask_b32_e64 v24, v76, v44, s[0:1]
	v_cndmask_b32_e32 v4, v142, v109, vcc
	v_cndmask_b32_e64 v4, v4, v23, s[4:5]
	v_cndmask_b32_e32 v23, v141, v108, vcc
	v_cndmask_b32_e64 v23, v23, v24, s[4:5]
	v_cndmask_b32_e32 v24, v140, v107, vcc
	v_cndmask_b32_e64 v25, v75, v43, s[0:1]
	v_cndmask_b32_e64 v24, v24, v25, s[4:5]
	v_cndmask_b32_e32 v25, v139, v106, vcc
	v_cndmask_b32_e64 v26, v74, v42, s[0:1]
	v_cndmask_b32_e64 v25, v25, v26, s[4:5]
	v_cndmask_b32_e32 v26, v138, v105, vcc
	v_cndmask_b32_e64 v27, v73, v41, s[0:1]
	v_cndmask_b32_e64 v26, v26, v27, s[4:5]
; __device__ __forceinline__ float key2f(unsigned k) { const unsigned u = (k & 0x80000000u) ? (k & 0x7fffffffu) : ~k; return __uint_as_float(u); }
; __device__ __forceinline__ void peer_tile(const Args& A, LAS unsigned char* lds, int tile) {
;     ...
;                 for (int i = 0; i < 16; ++i) L2[p][i] = (g & 2) ? ((g & 1) ? LA[3][p][i] : LA[2][p][i]) : ((g & 1) ? LA[1][p][i] : LA[0][p][i]);
;             float va[16], vb[16];
; #pragma unroll
;             for (int i = 0; i < 16; ++i) { va[i] = key2f(L2[0][i] & ~127u); vb[i] = key2f(L2[1][i] & ~127u); idx[i] = 127u - (L2[0][i] & 127u); idx[16 + i] = 127u - (L2[1][i] & 127u); }
	v_cndmask_b32_e32 v27, v137, v104, vcc
	v_cndmask_b32_e64 v28, v72, v40, s[0:1]
	v_cndmask_b32_e64 v27, v27, v28, s[4:5]
	v_cndmask_b32_e32 v28, v136, v103, vcc
	v_cndmask_b32_e64 v29, v71, v39, s[0:1]
	v_cndmask_b32_e64 v28, v28, v29, s[4:5]
	v_cndmask_b32_e32 v29, v135, v102, vcc
	v_cndmask_b32_e64 v29, v29, v38, s[4:5]
	v_cndmask_b32_e32 v38, v134, v101, vcc
	v_cndmask_b32_e64 v37, v38, v37, s[4:5]
	v_cndmask_b32_e32 v38, v133, v100, vcc
	v_cndmask_b32_e64 v36, v38, v36, s[4:5]
	v_cndmask_b32_e32 v38, v132, v99, vcc
	v_cndmask_b32_e64 v38, v38, v35, s[4:5]
	v_cndmask_b32_e32 v35, v131, v98, vcc
	v_cndmask_b32_e64 v39, v35, v34, s[4:5]
	v_cndmask_b32_e32 v34, v130, v97, vcc
	v_cndmask_b32_e64 v33, v34, v33, s[4:5]
	v_cndmask_b32_e32 v34, v129, v96, vcc
	v_cndmask_b32_e64 v40, v34, v32, s[4:5]
	v_cndmask_b32_e32 v32, v128, v95, vcc
	v_cndmask_b32_e64 v42, v32, v31, s[4:5]
	v_cndmask_b32_e32 v31, v127, v94, vcc
	v_cndmask_b32_e64 v43, v31, v30, s[4:5]
	v_cndmask_b32_e32 v3, v3, v126, vcc
	v_cndmask_b32_e64 v30, v93, v61, s[0:1]
	v_cndmask_b32_e64 v3, v3, v30, s[4:5]
	v_cndmask_b32_e32 v5, v5, v125, vcc
	v_cndmask_b32_e64 v30, v92, v60, s[0:1]
	v_cndmask_b32_e64 v30, v5, v30, s[4:5]
	v_cndmask_b32_e32 v5, v15, v124, vcc
	v_cndmask_b32_e64 v15, v91, v59, s[0:1]
	v_cndmask_b32_e64 v15, v5, v15, s[4:5]
	v_cndmask_b32_e32 v2, v2, v123, vcc
	v_cndmask_b32_e64 v5, v90, v58, s[0:1]
	v_cndmask_b32_e64 v31, v2, v5, s[4:5]
	v_cndmask_b32_e32 v2, v8, v122, vcc
	v_cndmask_b32_e64 v5, v89, v57, s[0:1]
	v_cndmask_b32_e64 v8, v2, v5, s[4:5]
	v_cndmask_b32_e32 v2, v16, v121, vcc
	v_cndmask_b32_e64 v5, v88, v56, s[0:1]
	v_cndmask_b32_e64 v32, v2, v5, s[4:5]
	v_cndmask_b32_e32 v2, v21, v120, vcc
	v_cndmask_b32_e64 v5, v87, v55, s[0:1]
	v_cndmask_b32_e64 v21, v2, v5, s[4:5]
	v_cndmask_b32_e32 v1, v1, v119, vcc
	v_cndmask_b32_e64 v2, v86, v54, s[0:1]
	v_cndmask_b32_e64 v34, v1, v2, s[4:5]
	v_cndmask_b32_e32 v1, v10, v118, vcc
	v_cndmask_b32_e64 v2, v85, v53, s[0:1]
	v_cndmask_b32_e64 v41, v1, v2, s[4:5]
	v_cndmask_b32_e32 v1, v20, v117, vcc
	v_cndmask_b32_e64 v2, v84, v52, s[0:1]
	v_cndmask_b32_e64 v44, v1, v2, s[4:5]
	v_cndmask_b32_e32 v1, v22, v116, vcc
	v_cndmask_b32_e64 v2, v83, v51, s[0:1]
	v_cndmask_b32_e64 v45, v1, v2, s[4:5]
	v_cndmask_b32_e32 v1, v12, v115, vcc
	v_cndmask_b32_e64 v2, v82, v50, s[0:1]
	v_cndmask_b32_e64 v50, v1, v2, s[4:5]
	v_cndmask_b32_e32 v1, v14, v114, vcc
	v_cndmask_b32_e64 v2, v81, v49, s[0:1]
	v_cndmask_b32_e64 v49, v1, v2, s[4:5]
	v_cndmask_b32_e32 v1, v17, v112, vcc
	v_cndmask_b32_e64 v2, v80, v48, s[0:1]
	v_cndmask_b32_e64 v48, v1, v2, s[4:5]
	v_cndmask_b32_e32 v1, v18, v111, vcc
	v_cndmask_b32_e64 v2, v79, v47, s[0:1]
	v_cndmask_b32_e64 v47, v1, v2, s[4:5]
	v_cndmask_b32_e32 v0, v0, v110, vcc
	v_cndmask_b32_e64 v1, v78, v46, s[0:1]
	v_cndmask_b32_e64 v46, v0, v1, s[4:5]
	v_and_b32_e32 v0, 0x7fffff80, v4
	v_bitop3_b32 v1, v4, s19, v4 bitop3:0xcf
	v_cmp_gt_i32_e32 vcc, 0, v4
	v_bitop3_b32 v2, v4, s19, v4 bitop3:0xc
	v_bitop3_b32 v4, v23, s19, v23 bitop3:0xcf
	v_cndmask_b32_e32 v20, v1, v0, vcc
	v_and_b32_e32 v0, 0x7fffff80, v3
	v_bitop3_b32 v1, v3, s19, v3 bitop3:0xcf
	v_cmp_gt_i32_e32 vcc, 0, v3
	v_add_u32_e32 v5, 0, v6
	v_bitop3_b32 v3, v3, s19, v3 bitop3:0xc
	v_cndmask_b32_e32 v1, v1, v0, vcc
	v_and_b32_e32 v0, 0x7fffff80, v23
	v_cmp_gt_i32_e32 vcc, 0, v23
	v_bitop3_b32 v14, v31, s19, v31 bitop3:0xcf
	v_bitop3_b32 v6, v24, s19, v24 bitop3:0xc
	v_cndmask_b32_e32 v18, v4, v0, vcc
	v_and_b32_e32 v0, 0x7fffff80, v30
	v_bitop3_b32 v4, v30, s19, v30 bitop3:0xcf
	v_cmp_gt_i32_e32 vcc, 0, v30
	v_bitop3_b32 v10, v15, s19, v15 bitop3:0xc
	v_bitop3_b32 v16, v32, s19, v32 bitop3:0xcf
	v_cndmask_b32_e32 v0, v4, v0, vcc
	v_bitop3_b32 v4, v23, s19, v23 bitop3:0xc
	ds_write2_b32 v5, v2, v4 offset1:1
	v_bitop3_b32 v2, v30, s19, v30 bitop3:0xc
	ds_write2_b32 v5, v3, v2 offset0:16 offset1:17
	v_and_b32_e32 v2, 0x7fffff80, v24
	v_bitop3_b32 v3, v24, s19, v24 bitop3:0xcf
	v_cmp_gt_i32_e32 vcc, 0, v24
	v_bitop3_b32 v4, v25, s19, v25 bitop3:0xcf
	v_bitop3_b32 v22, v29, s19, v29 bitop3:0xcf
	v_cndmask_b32_e32 v12, v3, v2, vcc
	v_and_b32_e32 v2, 0x7fffff80, v15
	v_bitop3_b32 v3, v15, s19, v15 bitop3:0xcf
	v_cmp_gt_i32_e32 vcc, 0, v15
	v_bitop3_b32 v15, v27, s19, v27 bitop3:0xcf
	v_bitop3_b32 v24, v34, s19, v34 bitop3:0xcf
	v_cndmask_b32_e32 v3, v3, v2, vcc
	v_and_b32_e32 v2, 0x7fffff80, v25
	v_cmp_gt_i32_e32 vcc, 0, v25
	s_nop 1
	v_cndmask_b32_e32 v4, v4, v2, vcc
	v_and_b32_e32 v2, 0x7fffff80, v31
	v_cmp_gt_i32_e32 vcc, 0, v31
	s_nop 1
	v_cndmask_b32_e32 v2, v14, v2, vcc
	v_bitop3_b32 v14, v25, s19, v25 bitop3:0xc
	ds_write2_b32 v5, v6, v14 offset0:2 offset1:3
	v_bitop3_b32 v6, v31, s19, v31 bitop3:0xc
	ds_write2_b32 v5, v10, v6 offset0:18 offset1:19
	v_and_b32_e32 v6, 0x7fffff80, v26
	v_bitop3_b32 v10, v26, s19, v26 bitop3:0xcf
	v_cmp_gt_i32_e32 vcc, 0, v26
	v_bitop3_b32 v25, v36, s19, v36 bitop3:0xcf
	s_nop 0
	v_cndmask_b32_e32 v14, v10, v6, vcc
	v_and_b32_e32 v6, 0x7fffff80, v8
	v_bitop3_b32 v10, v8, s19, v8 bitop3:0xcf
	v_cmp_gt_i32_e32 vcc, 0, v8
	v_bitop3_b32 v8, v8, s19, v8 bitop3:0xc
	s_nop 0
	v_cndmask_b32_e32 v17, v10, v6, vcc
	v_and_b32_e32 v10, 0x7fffff80, v27
	v_cmp_gt_i32_e32 vcc, 0, v27
	v_bitop3_b32 v6, v26, s19, v26 bitop3:0xc
	v_bitop3_b32 v26, v43, s19, v43 bitop3:0xcf
	v_cndmask_b32_e32 v10, v15, v10, vcc
	v_and_b32_e32 v15, 0x7fffff80, v32
	v_cmp_gt_i32_e32 vcc, 0, v32
	s_nop 1
	v_cndmask_b32_e32 v16, v16, v15, vcc
	v_bitop3_b32 v15, v27, s19, v27 bitop3:0xc
	ds_write2_b32 v5, v6, v15 offset0:4 offset1:5
	v_bitop3_b32 v6, v32, s19, v32 bitop3:0xc
	ds_write2_b32 v5, v8, v6 offset0:20 offset1:21
	v_and_b32_e32 v6, 0x7fffff80, v28
; __device__ __forceinline__ float key2f(unsigned k) { const unsigned u = (k & 0x80000000u) ? (k & 0x7fffffffu) : ~k; return __uint_as_float(u); }
; #define CK(i, j) ((f2key(va[i] + vb[j]) & ~255u) | (unsigned)(255 - (16 * (i) + (j))))
; __device__ __forceinline__ void peer_tile(const Args& A, LAS unsigned char* lds, int tile) {
;     ...
;             for (int i = 0; i < 16; ++i) { va[i] = key2f(L2[0][i] & ~127u); vb[i] = key2f(L2[1][i] & ~127u); idx[i] = 127u - (L2[0][i] & 127u); idx[16 + i] = 127u - (L2[1][i] & 127u); }
;     ...
;             unsigned Lf[16], Bt[16];
; #pragma unroll
;             for (int j = 0; j < 16; ++j) Lf[j] = CK(0, j);
; #pragma unroll
	v_bitop3_b32 v8, v28, s19, v28 bitop3:0xcf
	v_cmp_gt_i32_e32 vcc, 0, v28
	v_bitop3_b32 v15, v21, s19, v21 bitop3:0xcf
	s_nop 0
	v_cndmask_b32_e32 v8, v8, v6, vcc
	v_and_b32_e32 v6, 0x7fffff80, v21
	v_cmp_gt_i32_e32 vcc, 0, v21
	v_bitop3_b32 v21, v21, s19, v21 bitop3:0xc
	s_nop 0
	v_cndmask_b32_e32 v23, v15, v6, vcc
	v_and_b32_e32 v6, 0x7fffff80, v29
	v_cmp_gt_i32_e32 vcc, 0, v29
	v_bitop3_b32 v15, v28, s19, v28 bitop3:0xc
	s_nop 0
	v_cndmask_b32_e32 v6, v22, v6, vcc
	v_and_b32_e32 v22, 0x7fffff80, v34
	v_cmp_gt_i32_e32 vcc, 0, v34
	s_nop 1
	v_cndmask_b32_e32 v22, v24, v22, vcc
	v_bitop3_b32 v24, v29, s19, v29 bitop3:0xc
	ds_write2_b32 v5, v15, v24 offset0:6 offset1:7
	v_bitop3_b32 v15, v34, s19, v34 bitop3:0xc
	ds_write2_b32 v5, v21, v15 offset0:22 offset1:23
	v_and_b32_e32 v15, 0x7fffff80, v37
	v_bitop3_b32 v21, v37, s19, v37 bitop3:0xcf
	v_cmp_gt_i32_e32 vcc, 0, v37
	v_and_b32_e32 v24, 0x7fffff80, v36
	s_nop 0
	v_cndmask_b32_e32 v27, v21, v15, vcc
	v_and_b32_e32 v15, 0x7fffff80, v41
	v_bitop3_b32 v21, v41, s19, v41 bitop3:0xcf
	v_cmp_gt_i32_e32 vcc, 0, v41
	s_nop 1
	v_cndmask_b32_e32 v35, v21, v15, vcc
	v_cmp_gt_i32_e32 vcc, 0, v36
	v_bitop3_b32 v15, v37, s19, v37 bitop3:0xc
	v_bitop3_b32 v21, v41, s19, v41 bitop3:0xc
	v_cndmask_b32_e32 v28, v25, v24, vcc
	v_and_b32_e32 v24, 0x7fffff80, v44
	v_bitop3_b32 v25, v44, s19, v44 bitop3:0xcf
	v_cmp_gt_i32_e32 vcc, 0, v44
	s_nop 1
	v_cndmask_b32_e32 v34, v25, v24, vcc
	v_bitop3_b32 v24, v36, s19, v36 bitop3:0xc
	ds_write2_b32 v5, v15, v24 offset0:8 offset1:9
	v_bitop3_b32 v15, v44, s19, v44 bitop3:0xc
	ds_write2_b32 v5, v21, v15 offset0:24 offset1:25
	v_and_b32_e32 v15, 0x7fffff80, v38
	v_bitop3_b32 v21, v38, s19, v38 bitop3:0xcf
	v_cmp_gt_i32_e32 vcc, 0, v38
	v_and_b32_e32 v24, 0x7fffff80, v39
	v_bitop3_b32 v25, v39, s19, v39 bitop3:0xcf
	v_cndmask_b32_e32 v29, v21, v15, vcc
	v_and_b32_e32 v15, 0x7fffff80, v45
	v_bitop3_b32 v21, v45, s19, v45 bitop3:0xcf
	v_cmp_gt_i32_e32 vcc, 0, v45
	s_nop 1
	v_cndmask_b32_e32 v37, v21, v15, vcc
	v_cmp_gt_i32_e32 vcc, 0, v39
	v_bitop3_b32 v15, v38, s19, v38 bitop3:0xc
	v_bitop3_b32 v21, v45, s19, v45 bitop3:0xc
	v_cndmask_b32_e32 v30, v25, v24, vcc
	v_and_b32_e32 v24, 0x7fffff80, v50
	v_bitop3_b32 v25, v50, s19, v50 bitop3:0xcf
	v_cmp_gt_i32_e32 vcc, 0, v50
	s_nop 1
	v_cndmask_b32_e32 v36, v25, v24, vcc
	v_bitop3_b32 v24, v39, s19, v39 bitop3:0xc
	ds_write2_b32 v5, v15, v24 offset0:10 offset1:11
	v_bitop3_b32 v15, v50, s19, v50 bitop3:0xc
	ds_write2_b32 v5, v21, v15 offset0:26 offset1:27
	v_and_b32_e32 v15, 0x7fffff80, v33
	v_bitop3_b32 v21, v33, s19, v33 bitop3:0xcf
	v_cmp_gt_i32_e32 vcc, 0, v33
	v_and_b32_e32 v24, 0x7fffff80, v40
	v_bitop3_b32 v25, v40, s19, v40 bitop3:0xcf
	v_cndmask_b32_e32 v31, v21, v15, vcc
	v_and_b32_e32 v15, 0x7fffff80, v49
	v_bitop3_b32 v21, v49, s19, v49 bitop3:0xcf
	v_cmp_gt_i32_e32 vcc, 0, v49
	s_nop 1
	v_cndmask_b32_e32 v39, v21, v15, vcc
	v_cmp_gt_i32_e32 vcc, 0, v40
	v_bitop3_b32 v15, v33, s19, v33 bitop3:0xc
	v_bitop3_b32 v21, v49, s19, v49 bitop3:0xc
	v_cndmask_b32_e32 v32, v25, v24, vcc
	v_and_b32_e32 v24, 0x7fffff80, v48
	v_bitop3_b32 v25, v48, s19, v48 bitop3:0xcf
	v_cmp_gt_i32_e32 vcc, 0, v48
	v_bitop3_b32 v33, v46, s19, v46 bitop3:0xcf
	s_nop 0
	v_cndmask_b32_e32 v38, v25, v24, vcc
	v_bitop3_b32 v24, v40, s19, v40 bitop3:0xc
	ds_write2_b32 v5, v15, v24 offset0:12 offset1:13
	v_bitop3_b32 v15, v48, s19, v48 bitop3:0xc
	ds_write2_b32 v5, v21, v15 offset0:28 offset1:29
	v_and_b32_e32 v15, 0x7fffff80, v42
	v_bitop3_b32 v21, v42, s19, v42 bitop3:0xcf
	v_cmp_gt_i32_e32 vcc, 0, v42
	v_and_b32_e32 v24, 0x7fffff80, v43
	s_nop 0
	v_cndmask_b32_e32 v25, v21, v15, vcc
	v_and_b32_e32 v15, 0x7fffff80, v47
	v_bitop3_b32 v21, v47, s19, v47 bitop3:0xcf
	v_cmp_gt_i32_e32 vcc, 0, v47
	s_nop 1
	v_cndmask_b32_e32 v41, v21, v15, vcc
	v_cmp_gt_i32_e32 vcc, 0, v43
	v_bitop3_b32 v21, v47, s19, v47 bitop3:0xc
	v_bitop3_b32 v15, v42, s19, v42 bitop3:0xc
	v_cndmask_b32_e32 v26, v26, v24, vcc
	v_and_b32_e32 v24, 0x7fffff80, v46
	v_cmp_gt_i32_e32 vcc, 0, v46
	v_pk_add_f32 v[34:35], v[20:21], v[34:35] op_sel_hi:[0,1]
	s_nop 0
	v_cndmask_b32_e32 v40, v33, v24, vcc
	v_bitop3_b32 v24, v43, s19, v43 bitop3:0xc
	v_pk_add_f32 v[42:43], v[20:21], v[0:1] op_sel_hi:[0,1]
	ds_write2_b32 v5, v15, v24 offset0:14 offset1:15
	v_not_b32_e32 v15, v43
	v_or_b32_e32 v33, 0x80000000, v43
	v_cmp_gt_i32_e32 vcc, 0, v43
	v_or_b32_e32 v43, 0x80000000, v42
	v_bitop3_b32 v24, v46, s19, v46 bitop3:0xc
	v_cndmask_b32_e32 v15, v33, v15, vcc
	v_or_b32_e32 v33, 0xff, v15
	v_not_b32_e32 v15, v42
	v_cmp_gt_i32_e32 vcc, 0, v42
	ds_write2_b32 v5, v21, v24 offset0:30 offset1:31
	s_waitcnt lgkmcnt(0)
; #define CK(i, j) ((f2key(va[i] + vb[j]) & ~255u) | (unsigned)(255 - (16 * (i) + (j))))
; __device__ __forceinline__ void peer_tile(const Args& A, LAS unsigned char* lds, int tile) {
;     ...
;             unsigned Lf[16], Bt[16];
; #pragma unroll
;             for (int j = 0; j < 16; ++j) Lf[j] = CK(0, j);
; #pragma unroll
;             for (int j = 0; j < 8; ++j) Bt[j] = CK(1, j);
; #pragma unroll
;             for (int j = 0; j < 5; ++j) Bt[8 + j] = CK(2, j);
	s_nop 0
	v_cndmask_b32_e32 v15, v43, v15, vcc
	v_and_b32_e32 v15, 0xffffff00, v15
	v_pk_add_f32 v[42:43], v[20:21], v[2:3] op_sel_hi:[0,1]
	v_or_b32_e32 v44, 0xfe, v15
	v_not_b32_e32 v15, v43
	v_or_b32_e32 v45, 0x80000000, v43
	v_cmp_gt_i32_e32 vcc, 0, v43
	v_or_b32_e32 v43, 0x80000000, v42
	s_nop 0
	v_cndmask_b32_e32 v15, v45, v15, vcc
	v_and_b32_e32 v15, 0xffffff00, v15
	v_or_b32_e32 v45, 0xfd, v15
	v_not_b32_e32 v15, v42
	v_cmp_gt_i32_e32 vcc, 0, v42
	s_nop 1
	v_cndmask_b32_e32 v15, v43, v15, vcc
	v_and_b32_e32 v15, 0xffffff00, v15
	v_pk_add_f32 v[42:43], v[20:21], v[16:17] op_sel_hi:[0,1]
	v_or_b32_e32 v46, 0xfc, v15
	v_not_b32_e32 v15, v43
	v_or_b32_e32 v47, 0x80000000, v43
	v_cmp_gt_i32_e32 vcc, 0, v43
	v_or_b32_e32 v43, 0x80000000, v42
	s_nop 0
	v_cndmask_b32_e32 v15, v47, v15, vcc
	v_and_b32_e32 v15, 0xffffff00, v15
	v_or_b32_e32 v47, 0xfb, v15
	v_not_b32_e32 v15, v42
	v_cmp_gt_i32_e32 vcc, 0, v42
	s_nop 1
	v_cndmask_b32_e32 v15, v43, v15, vcc
	v_and_b32_e32 v15, 0xffffff00, v15
	v_pk_add_f32 v[42:43], v[20:21], v[22:23] op_sel_hi:[0,1]
	v_or_b32_e32 v48, 0xfa, v15
	v_not_b32_e32 v15, v43
	v_or_b32_e32 v49, 0x80000000, v43
	v_cmp_gt_i32_e32 vcc, 0, v43
	v_pk_add_f32 v[22:23], v[18:19], v[22:23] op_sel_hi:[0,1]
	s_nop 0
	v_cndmask_b32_e32 v15, v49, v15, vcc
	v_and_b32_e32 v15, 0xffffff00, v15
	v_or_b32_e32 v43, 0xf9, v15
	v_not_b32_e32 v15, v42
	v_or_b32_e32 v49, 0x80000000, v42
	v_cmp_gt_i32_e32 vcc, 0, v42
	s_nop 1
	v_cndmask_b32_e32 v15, v49, v15, vcc
	v_and_b32_e32 v15, 0xffffff00, v15
	v_or_b32_e32 v42, 0xf8, v15
	v_not_b32_e32 v15, v35
	v_or_b32_e32 v49, 0x80000000, v35
	v_cmp_gt_i32_e32 vcc, 0, v35
	v_or_b32_e32 v35, 0x80000000, v34
	s_nop 0
	v_cndmask_b32_e32 v15, v49, v15, vcc
	v_and_b32_e32 v15, 0xffffff00, v15
	v_or_b32_e32 v49, 0xf7, v15
	v_not_b32_e32 v15, v34
	v_cmp_gt_i32_e32 vcc, 0, v34
	s_nop 1
	v_cndmask_b32_e32 v15, v35, v15, vcc
	v_and_b32_e32 v15, 0xffffff00, v15
	v_pk_add_f32 v[34:35], v[20:21], v[36:37] op_sel_hi:[0,1]
	v_or_b32_e32 v50, 0xf6, v15
	v_not_b32_e32 v15, v35
	v_or_b32_e32 v36, 0x80000000, v35
	v_cmp_gt_i32_e32 vcc, 0, v35
	v_or_b32_e32 v35, 0x80000000, v34
	s_nop 0
	v_cndmask_b32_e32 v15, v36, v15, vcc
	v_and_b32_e32 v15, 0xffffff00, v15
	v_or_b32_e32 v36, 0xf5, v15
	v_not_b32_e32 v15, v34
	v_cmp_gt_i32_e32 vcc, 0, v34
	s_nop 1
	v_cndmask_b32_e32 v15, v35, v15, vcc
	v_and_b32_e32 v15, 0xffffff00, v15
	v_pk_add_f32 v[34:35], v[20:21], v[38:39] op_sel_hi:[0,1]
	v_or_b32_e32 v37, 0xf4, v15
	v_not_b32_e32 v15, v35
	v_or_b32_e32 v38, 0x80000000, v35
	v_cmp_gt_i32_e32 vcc, 0, v35
	v_or_b32_e32 v35, 0x80000000, v34
	s_nop 0
	v_cndmask_b32_e32 v15, v38, v15, vcc
	v_and_b32_e32 v15, 0xffffff00, v15
	v_or_b32_e32 v38, 0xf3, v15
	v_not_b32_e32 v15, v34
	v_cmp_gt_i32_e32 vcc, 0, v34
	s_nop 1
	v_cndmask_b32_e32 v15, v35, v15, vcc
	v_and_b32_e32 v15, 0xffffff00, v15
	v_pk_add_f32 v[34:35], v[20:21], v[40:41] op_sel_hi:[0,1]
	v_or_b32_e32 v39, 0xf2, v15
	v_not_b32_e32 v15, v35
	v_or_b32_e32 v20, 0x80000000, v35
	v_cmp_gt_i32_e32 vcc, 0, v35
	v_or_b32_e32 v35, 0x80000000, v34
	s_nop 0
	v_cndmask_b32_e32 v15, v20, v15, vcc
	v_and_b32_e32 v15, 0xffffff00, v15
	v_or_b32_e32 v20, 0xf1, v15
	v_not_b32_e32 v15, v34
	v_cmp_gt_i32_e32 vcc, 0, v34
	s_nop 1
	v_cndmask_b32_e32 v15, v35, v15, vcc
	v_and_b32_e32 v15, 0xffffff00, v15
	v_pk_add_f32 v[34:35], v[18:19], v[0:1] op_sel_hi:[0,1]
	v_or_b32_e32 v40, 0xf0, v15
	v_not_b32_e32 v15, v35
	v_or_b32_e32 v41, 0x80000000, v35
	v_cmp_gt_i32_e32 vcc, 0, v35
	v_or_b32_e32 v35, 0x80000000, v34
	s_nop 0
	v_cndmask_b32_e32 v15, v41, v15, vcc
	v_and_b32_e32 v15, 0xffffff00, v15
	v_or_b32_e32 v41, 0xef, v15
	v_not_b32_e32 v15, v34
	v_cmp_gt_i32_e32 vcc, 0, v34
	s_nop 1
	v_cndmask_b32_e32 v15, v35, v15, vcc
	v_and_b32_e32 v15, 0xffffff00, v15
	v_pk_add_f32 v[34:35], v[18:19], v[2:3] op_sel_hi:[0,1]
	v_or_b32_e32 v51, 0xee, v15
	v_not_b32_e32 v15, v35
	v_or_b32_e32 v52, 0x80000000, v35
	v_cmp_gt_i32_e32 vcc, 0, v35
	v_or_b32_e32 v35, 0x80000000, v34
	s_nop 0
	v_cndmask_b32_e32 v15, v52, v15, vcc
	v_and_b32_e32 v15, 0xffffff00, v15
	v_or_b32_e32 v52, 0xed, v15
	v_not_b32_e32 v15, v34
	v_cmp_gt_i32_e32 vcc, 0, v34
	s_nop 1
	v_cndmask_b32_e32 v15, v35, v15, vcc
	v_and_b32_e32 v15, 0xffffff00, v15
	v_pk_add_f32 v[34:35], v[18:19], v[16:17] op_sel_hi:[0,1]
	v_or_b32_e32 v53, 0xec, v15
	v_not_b32_e32 v15, v35
	v_or_b32_e32 v16, 0x80000000, v35
	v_cmp_gt_i32_e32 vcc, 0, v35
	s_nop 1
	v_cndmask_b32_e32 v15, v16, v15, vcc
	v_and_b32_e32 v15, 0xffffff00, v15
	v_or_b32_e32 v35, 0xeb, v15
	v_not_b32_e32 v15, v34
	v_or_b32_e32 v16, 0x80000000, v34
	v_cmp_gt_i32_e32 vcc, 0, v34
	s_nop 1
	v_cndmask_b32_e32 v15, v16, v15, vcc
	v_and_b32_e32 v15, 0xffffff00, v15
	v_or_b32_e32 v34, 0xea, v15
	v_not_b32_e32 v15, v23
	v_or_b32_e32 v16, 0x80000000, v23
	v_cmp_gt_i32_e32 vcc, 0, v23
	s_nop 1
	v_cndmask_b32_e32 v15, v16, v15, vcc
	v_and_b32_e32 v15, 0xffffff00, v15
	v_or_b32_e32 v18, 0xe9, v15
	v_not_b32_e32 v15, v22
	v_or_b32_e32 v16, 0x80000000, v22
	v_cmp_gt_i32_e32 vcc, 0, v22
	v_pk_add_f32 v[22:23], v[12:13], v[0:1] op_sel_hi:[0,1]
	s_nop 0
	v_cndmask_b32_e32 v15, v16, v15, vcc
	v_and_b32_e32 v15, 0xffffff00, v15
	v_or_b32_e32 v54, 0xe8, v15
	v_not_b32_e32 v15, v23
	v_or_b32_e32 v16, 0x80000000, v23
	v_cmp_gt_i32_e32 vcc, 0, v23
	s_nop 1
	v_cndmask_b32_e32 v15, v16, v15, vcc
	v_and_b32_e32 v15, 0xffffff00, v15
	v_or_b32_e32 v55, 0xdf, v15
	v_not_b32_e32 v15, v22
	v_or_b32_e32 v16, 0x80000000, v22
	v_cmp_gt_i32_e32 vcc, 0, v22
	v_pk_add_f32 v[22:23], v[12:13], v[2:3] op_sel_hi:[0,1]
	v_lshl_add_u32 v13, v13, 10, s35
	v_cndmask_b32_e32 v15, v16, v15, vcc
	v_and_b32_e32 v15, 0xffffff00, v15
; #define CK(i, j) ((f2key(va[i] + vb[j]) & ~255u) | (unsigned)(255 - (16 * (i) + (j))))
; __device__ __forceinline__ void peer_tile(const Args& A, LAS unsigned char* lds, int tile) {
;     ...
;             unsigned Lf[16], Bt[16];
; #pragma unroll
;             for (int j = 0; j < 16; ++j) Lf[j] = CK(0, j);
; #pragma unroll
;             for (int j = 0; j < 8; ++j) Bt[j] = CK(1, j);
; #pragma unroll
;             for (int j = 0; j < 5; ++j) Bt[8 + j] = CK(2, j);
; #pragma unroll
;             for (int j = 0; j < 3; ++j) Bt[13 + j] = CK(4, j);
;             sort16_desc(Bt); merge16(Lf, Bt);
	v_or_b32_e32 v56, 0xde, v15
	v_not_b32_e32 v15, v23
	v_or_b32_e32 v16, 0x80000000, v23
	v_cmp_gt_i32_e32 vcc, 0, v23
	s_nop 1
	v_cndmask_b32_e32 v15, v16, v15, vcc
	v_and_b32_e32 v15, 0xffffff00, v15
	v_or_b32_e32 v23, 0xdd, v15
	v_not_b32_e32 v15, v22
	v_or_b32_e32 v16, 0x80000000, v22
	v_cmp_gt_i32_e32 vcc, 0, v22
	s_nop 1
	v_cndmask_b32_e32 v15, v16, v15, vcc
	v_and_b32_e32 v15, 0xffffff00, v15
	v_or_b32_e32 v22, 0xdc, v15
	v_mov_b32_e32 v15, v12
	v_mov_b32_e32 v16, v1
	v_pk_add_f32 v[16:17], v[14:15], v[16:17]
	s_nop 0
	v_not_b32_e32 v12, v17
	v_or_b32_e32 v15, 0x80000000, v17
	v_cmp_gt_i32_e32 vcc, 0, v17
	v_or_b32_e32 v17, 0x80000000, v16
	s_nop 0
	v_cndmask_b32_e32 v12, v15, v12, vcc
	v_not_b32_e32 v15, v16
	v_cmp_gt_i32_e32 vcc, 0, v16
	v_mov_b32_e32 v16, v3
	v_and_b32_e32 v12, 0xffffff00, v12
	v_cndmask_b32_e32 v15, v17, v15, vcc
	v_and_b32_e32 v15, 0xffffff00, v15
	v_mov_b32_e32 v17, v0
	v_or_b32_e32 v57, 0xbf, v15
	v_pk_add_f32 v[14:15], v[14:15], v[16:17] op_sel_hi:[0,1]
	v_not_b32_e32 v16, v15
	v_or_b32_e32 v17, 0x80000000, v15
	v_cmp_gt_i32_e32 vcc, 0, v15
	v_or_b32_e32 v12, 0xdb, v12
	v_pk_add_f32 v[2:3], v[4:5], v[2:3] op_sel_hi:[0,1]
	v_cndmask_b32_e32 v15, v17, v16, vcc
	v_not_b32_e32 v16, v14
	v_or_b32_e32 v17, 0x80000000, v14
	v_cmp_gt_i32_e32 vcc, 0, v14
	v_and_b32_e32 v15, 0xffffff00, v15
	v_or_b32_e32 v15, 0xbe, v15
	v_cndmask_b32_e32 v14, v17, v16, vcc
	v_and_b32_e32 v14, 0xffffff00, v14
	v_or_b32_e32 v14, 0xbd, v14
	v_max_u32_e32 v16, v41, v51
	v_min_u32_e32 v17, v41, v51
	v_max_u32_e32 v41, v53, v52
	v_min_u32_e32 v51, v53, v52
	v_max_u32_e32 v52, v35, v34
	v_min_u32_e32 v34, v35, v34
	v_max_u32_e32 v35, v54, v18
	v_min_u32_e32 v18, v54, v18
	v_max_u32_e32 v53, v55, v56
	v_min_u32_e32 v54, v55, v56
	v_max_u32_e32 v55, v22, v23
	v_min_u32_e32 v22, v22, v23
	v_max_u32_e32 v23, v12, v57
	v_min_u32_e32 v12, v12, v57
	v_max_u32_e32 v56, v14, v15
	v_min_u32_e32 v14, v14, v15
	v_max_u32_e32 v15, v16, v51
	v_min_u32_e32 v16, v16, v51
	v_max_u32_e32 v51, v17, v41
	v_min_u32_e32 v17, v17, v41
	v_max_u32_e32 v41, v18, v52
	v_min_u32_e32 v18, v18, v52
	v_max_u32_e32 v52, v35, v34
	v_min_u32_e32 v34, v35, v34
	v_max_u32_e32 v35, v53, v22
	v_min_u32_e32 v22, v53, v22
	v_max_u32_e32 v53, v54, v55
	v_min_u32_e32 v54, v54, v55
	v_max_u32_e32 v55, v14, v23
	v_min_u32_e32 v14, v14, v23
	v_max_u32_e32 v23, v56, v12
	v_min_u32_e32 v12, v56, v12
	v_max_u32_e32 v56, v15, v51
	v_min_u32_e32 v15, v15, v51
	v_max_u32_e32 v51, v16, v17
	v_min_u32_e32 v16, v16, v17
	v_max_u32_e32 v17, v34, v18
	v_min_u32_e32 v18, v34, v18
	v_max_u32_e32 v34, v52, v41
	v_min_u32_e32 v41, v52, v41
	v_max_u32_e32 v52, v35, v53
	v_min_u32_e32 v35, v35, v53
	v_max_u32_e32 v53, v22, v54
	v_min_u32_e32 v22, v22, v54
	v_max_u32_e32 v54, v12, v14
	v_min_u32_e32 v12, v12, v14
	v_max_u32_e32 v14, v23, v55
	v_min_u32_e32 v23, v23, v55
	v_max_u32_e32 v55, v56, v18
	v_min_u32_e32 v18, v56, v18
	v_max_u32_e32 v56, v15, v17
	v_min_u32_e32 v15, v15, v17
	v_max_u32_e32 v17, v51, v41
	v_min_u32_e32 v41, v51, v41
	v_max_u32_e32 v51, v16, v34
	v_min_u32_e32 v16, v16, v34
	v_max_u32_e32 v34, v12, v52
	v_min_u32_e32 v12, v12, v52
	v_max_u32_e32 v52, v54, v35
	v_min_u32_e32 v35, v54, v35
	v_max_u32_e32 v54, v23, v53
	v_min_u32_e32 v23, v23, v53
	v_max_u32_e32 v53, v14, v22
	v_min_u32_e32 v14, v14, v22
	v_max_u32_e32 v22, v55, v17
	v_min_u32_e32 v17, v55, v17
	v_max_u32_e32 v55, v56, v51
	v_min_u32_e32 v51, v56, v51
	v_max_u32_e32 v56, v18, v41
	v_min_u32_e32 v18, v18, v41
	v_max_u32_e32 v41, v15, v16
	v_min_u32_e32 v15, v15, v16
	v_max_u32_e32 v16, v23, v12
	v_min_u32_e32 v12, v23, v12
	v_max_u32_e32 v23, v14, v35
	v_min_u32_e32 v14, v14, v35
	v_max_u32_e32 v35, v54, v34
	v_min_u32_e32 v34, v54, v34
	v_max_u32_e32 v54, v53, v52
	v_min_u32_e32 v52, v53, v52
	v_max_u32_e32 v53, v22, v55
	v_min_u32_e32 v22, v22, v55
	v_max_u32_e32 v55, v17, v51
	v_min_u32_e32 v17, v17, v51
	v_max_u32_e32 v51, v56, v41
	v_min_u32_e32 v41, v56, v41
	v_max_u32_e32 v56, v18, v15
	v_min_u32_e32 v15, v18, v15
	v_max_u32_e32 v18, v14, v12
	v_min_u32_e32 v12, v14, v12
	v_max_u32_e32 v14, v23, v16
	v_min_u32_e32 v16, v23, v16
	v_max_u32_e32 v23, v52, v34
	v_min_u32_e32 v34, v52, v34
	v_max_u32_e32 v52, v54, v35
	v_min_u32_e32 v35, v54, v35
	v_max_u32_e32 v54, v53, v12
	v_min_u32_e32 v12, v53, v12
	v_max_u32_e32 v53, v22, v18
	v_min_u32_e32 v18, v22, v18
	v_max_u32_e32 v22, v55, v16
	v_min_u32_e32 v16, v55, v16
	v_max_u32_e32 v55, v17, v14
	v_min_u32_e32 v14, v17, v14
	v_max_u32_e32 v17, v51, v34
	v_min_u32_e32 v34, v51, v34
	v_max_u32_e32 v51, v41, v23
	v_min_u32_e32 v23, v41, v23
	v_max_u32_e32 v41, v56, v35
	v_min_u32_e32 v35, v56, v35
	v_max_u32_e32 v56, v15, v52
	v_min_u32_e32 v15, v15, v52
	v_max_u32_e32 v52, v54, v17
	v_min_u32_e32 v17, v54, v17
	v_max_u32_e32 v54, v53, v51
	v_min_u32_e32 v51, v53, v51
	v_max_u32_e32 v53, v22, v41
	v_min_u32_e32 v22, v22, v41
	v_max_u32_e32 v41, v55, v56
	v_min_u32_e32 v55, v55, v56
	v_max_u32_e32 v56, v12, v34
	v_min_u32_e32 v12, v12, v34
	v_max_u32_e32 v34, v18, v23
	v_min_u32_e32 v18, v18, v23
	v_max_u32_e32 v23, v16, v35
	v_min_u32_e32 v16, v16, v35
	v_max_u32_e32 v35, v14, v15
	v_min_u32_e32 v14, v14, v15
	v_max_u32_e32 v15, v52, v53
	v_min_u32_e32 v52, v52, v53
	v_max_u32_e32 v53, v54, v41
	v_min_u32_e32 v41, v54, v41
	v_max_u32_e32 v54, v17, v22
	v_min_u32_e32 v17, v17, v22
	v_max_u32_e32 v22, v51, v55
	v_min_u32_e32 v51, v51, v55
	v_max_u32_e32 v55, v56, v23
	v_min_u32_e32 v23, v56, v23
	v_max_u32_e32 v56, v34, v35
	v_min_u32_e32 v34, v34, v35
	v_max_u32_e32 v35, v12, v16
	v_min_u32_e32 v12, v12, v16
	v_max_u32_e32 v16, v18, v14
	v_min_u32_e32 v14, v18, v14
; #define CK(i, j) ((f2key(va[i] + vb[j]) & ~255u) | (unsigned)(255 - (16 * (i) + (j))))
; __device__ __forceinline__ void peer_tile(const Args& A, LAS unsigned char* lds, int tile) {
;     ...
;             sort16_desc(Bt); merge16(Lf, Bt);
; #pragma unroll
;             for (int j = 0; j < 4; ++j) Bt[j] = CK(3, j);
;             Bt[4] = CK(5, 0); Bt[5] = CK(5, 1); Bt[6] = CK(6, 0); Bt[7] = CK(6, 1); Bt[8] = CK(7, 0); Bt[9] = CK(7, 1);
;             Bt[10] = CK(8, 0); Bt[11] = CK(9, 0); Bt[12] = CK(10, 0); Bt[13] = CK(11, 0); Bt[14] = CK(12, 0); Bt[15] = CK(13, 0);
	v_min_u32_e32 v18, v15, v53
	v_min_u32_e32 v57, v52, v41
	v_min_u32_e32 v58, v54, v22
	v_min_u32_e32 v59, v17, v51
	v_min_u32_e32 v60, v55, v56
	v_min_u32_e32 v61, v23, v34
	v_min_u32_e32 v62, v35, v16
	v_min_u32_e32 v63, v12, v14
	v_max_u32_e32 v33, v33, v63
	v_max3_u32 v12, v44, v12, v14
	v_max_u32_e32 v14, v45, v62
	v_max3_u32 v16, v46, v35, v16
	v_max_u32_e32 v35, v47, v61
	v_max3_u32 v23, v48, v23, v34
	v_max_u32_e32 v34, v43, v60
	v_max3_u32 v42, v42, v55, v56
	v_max_u32_e32 v43, v49, v59
	v_max3_u32 v17, v50, v17, v51
	v_max_u32_e32 v36, v36, v58
	v_max3_u32 v22, v37, v54, v22
	v_max_u32_e32 v37, v38, v57
	v_max3_u32 v38, v39, v52, v41
	v_max_u32_e32 v18, v20, v18
	v_max3_u32 v15, v40, v15, v53
	v_max_u32_e32 v20, v33, v43
	v_min_u32_e32 v33, v33, v43
	v_max_u32_e32 v39, v12, v17
	v_min_u32_e32 v12, v12, v17
	v_max_u32_e32 v17, v14, v36
	v_min_u32_e32 v14, v14, v36
	v_max_u32_e32 v36, v16, v22
	v_min_u32_e32 v16, v16, v22
	v_max_u32_e32 v22, v35, v37
	v_min_u32_e32 v35, v35, v37
	v_max_u32_e32 v37, v23, v38
	v_min_u32_e32 v23, v23, v38
	v_max_u32_e32 v38, v34, v18
	v_min_u32_e32 v18, v34, v18
	v_max_u32_e32 v34, v42, v15
	v_min_u32_e32 v15, v42, v15
	v_max_u32_e32 v40, v20, v22
	v_min_u32_e32 v20, v20, v22
	v_max_u32_e32 v22, v39, v37
	v_min_u32_e32 v37, v39, v37
	v_max_u32_e32 v39, v17, v38
	v_min_u32_e32 v17, v17, v38
	v_max_u32_e32 v38, v36, v34
	v_min_u32_e32 v34, v36, v34
	v_max_u32_e32 v36, v33, v35
	v_min_u32_e32 v33, v33, v35
	v_max_u32_e32 v35, v12, v23
	v_min_u32_e32 v12, v12, v23
	v_max_u32_e32 v23, v14, v18
	v_min_u32_e32 v14, v14, v18
	v_max_u32_e32 v18, v16, v15
	v_min_u32_e32 v15, v16, v15
	v_max_u32_e32 v16, v40, v39
	v_min_u32_e32 v39, v40, v39
	v_max_u32_e32 v40, v22, v38
	v_min_u32_e32 v22, v22, v38
	v_max_u32_e32 v38, v20, v17
	v_min_u32_e32 v17, v20, v17
	v_max_u32_e32 v20, v37, v34
	v_min_u32_e32 v34, v37, v34
	v_max_u32_e32 v37, v36, v23
	v_min_u32_e32 v23, v36, v23
	v_max_u32_e32 v36, v35, v18
	v_min_u32_e32 v18, v35, v18
	v_max_u32_e32 v35, v33, v14
	v_min_u32_e32 v33, v33, v14
	v_max_u32_e32 v41, v12, v15
	v_min_u32_e32 v12, v12, v15
	v_pk_add_f32 v[14:15], v[4:5], v[0:1] op_sel_hi:[0,1]
	v_not_b32_e32 v50, v15
	v_or_b32_e32 v51, 0x80000000, v15
	v_cmp_gt_i32_e32 vcc, 0, v15
	v_not_b32_e32 v4, v3
	v_min_u32_e32 v42, v16, v40
	v_cndmask_b32_e32 v15, v51, v50, vcc
	v_not_b32_e32 v50, v14
	v_or_b32_e32 v51, 0x80000000, v14
	v_cmp_gt_i32_e32 vcc, 0, v14
	v_and_b32_e32 v15, 0xffffff00, v15
	v_or_b32_e32 v15, 0xcf, v15
	v_cndmask_b32_e32 v14, v51, v50, vcc
	v_or_b32_e32 v50, 0x80000000, v3
	v_cmp_gt_i32_e32 vcc, 0, v3
	v_and_b32_e32 v14, 0xffffff00, v14
	v_or_b32_e32 v14, 0xce, v14
	v_cndmask_b32_e32 v3, v50, v4, vcc
	v_and_b32_e32 v3, 0xffffff00, v3
	v_or_b32_e32 v4, 0xcd, v3
	v_not_b32_e32 v3, v2
	v_or_b32_e32 v50, 0x80000000, v2
	v_cmp_gt_i32_e32 vcc, 0, v2
	v_min_u32_e32 v43, v39, v22
	v_min_u32_e32 v44, v38, v20
	v_cndmask_b32_e32 v2, v50, v3, vcc
	v_and_b32_e32 v2, 0xffffff00, v2
	v_or_b32_e32 v50, 0xcc, v2
	v_pk_add_f32 v[2:3], v[10:11], v[0:1] op_sel_hi:[0,1]
	v_not_b32_e32 v10, v3
	v_or_b32_e32 v51, 0x80000000, v3
	v_cmp_gt_i32_e32 vcc, 0, v3
	v_min_u32_e32 v45, v17, v34
	v_min_u32_e32 v46, v37, v36
	v_cndmask_b32_e32 v3, v51, v10, vcc
	v_and_b32_e32 v3, 0xffffff00, v3
	v_or_b32_e32 v10, 0xaf, v3
	v_not_b32_e32 v3, v2
	v_or_b32_e32 v51, 0x80000000, v2
	v_cmp_gt_i32_e32 vcc, 0, v2
	v_min_u32_e32 v47, v23, v18
	v_min_u32_e32 v48, v35, v41
	v_cndmask_b32_e32 v2, v51, v3, vcc
	v_and_b32_e32 v2, 0xffffff00, v2
	v_or_b32_e32 v51, 0xae, v2
	v_pk_add_f32 v[2:3], v[8:9], v[0:1] op_sel_hi:[0,1]
	v_not_b32_e32 v8, v3
	v_or_b32_e32 v52, 0x80000000, v3
	v_cmp_gt_i32_e32 vcc, 0, v3
	v_min_u32_e32 v49, v33, v12
	v_lshlrev_b32_e32 v11, 9, v11
	v_cndmask_b32_e32 v3, v52, v8, vcc
	v_and_b32_e32 v3, 0xffffff00, v3
	v_or_b32_e32 v8, 0x9f, v3
	v_not_b32_e32 v3, v2
	v_or_b32_e32 v52, 0x80000000, v2
	v_cmp_gt_i32_e32 vcc, 0, v2
	s_nop 1
	v_cndmask_b32_e32 v2, v52, v3, vcc
	v_and_b32_e32 v2, 0xffffff00, v2
	v_or_b32_e32 v52, 0x9e, v2
	v_pk_add_f32 v[2:3], v[6:7], v[0:1] op_sel_hi:[0,1]
	v_not_b32_e32 v0, v3
	v_or_b32_e32 v6, 0x80000000, v3
	v_cmp_gt_i32_e32 vcc, 0, v3
	v_not_b32_e32 v3, v2
	s_nop 0
	v_cndmask_b32_e32 v0, v6, v0, vcc
	v_or_b32_e32 v6, 0x80000000, v2
	v_cmp_gt_i32_e32 vcc, 0, v2
	v_and_b32_e32 v0, 0xffffff00, v0
	v_or_b32_e32 v0, 0x8f, v0
	v_cndmask_b32_e32 v2, v6, v3, vcc
	v_add_f32_e32 v3, v27, v1
	v_not_b32_e32 v6, v3
	v_or_b32_e32 v27, 0x80000000, v3
	v_cmp_gt_i32_e32 vcc, 0, v3
	v_and_b32_e32 v2, 0xffffff00, v2
	v_or_b32_e32 v2, 0x8e, v2
	v_cndmask_b32_e32 v3, v27, v6, vcc
	v_add_f32_e32 v6, v28, v1
	v_not_b32_e32 v27, v6
	v_or_b32_e32 v28, 0x80000000, v6
	v_cmp_gt_i32_e32 vcc, 0, v6
	v_and_b32_e32 v3, 0xffffff00, v3
	v_or_b32_e32 v3, 0x7f, v3
	v_cndmask_b32_e32 v6, v28, v27, vcc
	v_add_f32_e32 v27, v29, v1
	v_not_b32_e32 v28, v27
	v_or_b32_e32 v29, 0x80000000, v27
	v_cmp_gt_i32_e32 vcc, 0, v27
	v_and_b32_e32 v6, 0xffffff00, v6
	v_or_b32_e32 v6, 0x6f, v6
	v_cndmask_b32_e32 v27, v29, v28, vcc
	v_add_f32_e32 v28, v30, v1
	v_not_b32_e32 v29, v28
	v_or_b32_e32 v30, 0x80000000, v28
	v_cmp_gt_i32_e32 vcc, 0, v28
	v_and_b32_e32 v27, 0xffffff00, v27
	v_or_b32_e32 v27, 0x5f, v27
	v_cndmask_b32_e32 v28, v30, v29, vcc
	v_add_f32_e32 v29, v31, v1
	v_not_b32_e32 v30, v29
	v_or_b32_e32 v31, 0x80000000, v29
	v_cmp_gt_i32_e32 vcc, 0, v29
	v_and_b32_e32 v28, 0xffffff00, v28
	v_or_b32_e32 v28, 0x4f, v28
	v_cndmask_b32_e32 v29, v31, v30, vcc
	v_add_f32_e32 v30, v32, v1
	v_not_b32_e32 v31, v30
	v_or_b32_e32 v32, 0x80000000, v30
	v_cmp_gt_i32_e32 vcc, 0, v30
	v_and_or_b32 v29, v29, s34, 63
	s_nop 0
	v_cndmask_b32_e32 v30, v32, v31, vcc
; __device__ __forceinline__ void peer_tile(const Args& A, LAS unsigned char* lds, int tile) {
;     ...
;             sort16_desc(Bt); merge16(Lf, Bt);
	v_and_or_b32 v30, v30, s34, 47
	v_max_u32_e32 v31, v15, v14
	v_min_u32_e32 v14, v15, v14
	v_max_u32_e32 v15, v50, v4
	v_min_u32_e32 v4, v50, v4
	v_max_u32_e32 v32, v10, v51
	v_min_u32_e32 v10, v10, v51
	v_max_u32_e32 v50, v52, v8
	v_min_u32_e32 v8, v52, v8
	v_max_u32_e32 v51, v0, v2
	v_min_u32_e32 v0, v0, v2
	v_max_u32_e32 v2, v6, v3
	v_min_u32_e32 v3, v6, v3
	v_max_u32_e32 v6, v27, v28
	v_min_u32_e32 v27, v27, v28
	v_max_u32_e32 v28, v30, v29
	v_min_u32_e32 v29, v30, v29
	v_max_u32_e32 v30, v31, v4
	v_min_u32_e32 v4, v31, v4
	v_max_u32_e32 v31, v14, v15
	v_min_u32_e32 v14, v14, v15
	v_max_u32_e32 v15, v8, v32
	v_min_u32_e32 v8, v8, v32
	v_max_u32_e32 v32, v50, v10
	v_min_u32_e32 v10, v50, v10
	v_max_u32_e32 v50, v51, v3
	v_min_u32_e32 v3, v51, v3
	v_max_u32_e32 v51, v0, v2
	v_min_u32_e32 v0, v0, v2
	v_max_u32_e32 v2, v29, v6
	v_min_u32_e32 v6, v29, v6
	v_max_u32_e32 v29, v28, v27
	v_min_u32_e32 v27, v28, v27
	v_max_u32_e32 v28, v30, v31
	v_min_u32_e32 v30, v30, v31
	v_max_u32_e32 v31, v4, v14
	v_min_u32_e32 v4, v4, v14
	v_max_u32_e32 v14, v10, v8
	v_min_u32_e32 v8, v10, v8
	v_max_u32_e32 v10, v32, v15
	v_min_u32_e32 v15, v32, v15
	v_max_u32_e32 v32, v50, v51
	v_min_u32_e32 v50, v50, v51
	v_max_u32_e32 v51, v3, v0
	v_min_u32_e32 v0, v3, v0
	v_max_u32_e32 v3, v27, v6
	v_min_u32_e32 v6, v27, v6
	v_max_u32_e32 v27, v29, v2
	v_min_u32_e32 v2, v29, v2
	v_max_u32_e32 v29, v28, v8
	v_min_u32_e32 v8, v28, v8
	v_max_u32_e32 v28, v30, v14
	v_min_u32_e32 v14, v30, v14
	v_max_u32_e32 v30, v31, v15
	v_min_u32_e32 v15, v31, v15
	v_max_u32_e32 v31, v4, v10
	v_min_u32_e32 v4, v4, v10
	v_max_u32_e32 v10, v6, v32
	v_min_u32_e32 v6, v6, v32
	v_max_u32_e32 v32, v3, v50
	v_min_u32_e32 v3, v3, v50
	v_max_u32_e32 v50, v2, v51
	v_min_u32_e32 v2, v2, v51
	v_max_u32_e32 v51, v27, v0
	v_min_u32_e32 v0, v27, v0
	v_max_u32_e32 v27, v29, v30
	v_min_u32_e32 v29, v29, v30
	v_max_u32_e32 v30, v28, v31
	v_min_u32_e32 v28, v28, v31
	v_max_u32_e32 v31, v8, v15
	v_min_u32_e32 v8, v8, v15
	v_max_u32_e32 v15, v14, v4
	v_min_u32_e32 v4, v14, v4
	v_max_u32_e32 v14, v2, v6
	v_min_u32_e32 v2, v2, v6
	v_max_u32_e32 v6, v0, v3
	v_min_u32_e32 v0, v0, v3
	v_max_u32_e32 v3, v50, v10
	v_min_u32_e32 v10, v50, v10
	v_max_u32_e32 v50, v51, v32
	v_min_u32_e32 v32, v51, v32
	v_max_u32_e32 v51, v27, v30
	v_min_u32_e32 v27, v27, v30
	v_max_u32_e32 v30, v29, v28
	v_min_u32_e32 v28, v29, v28
	v_max_u32_e32 v29, v31, v15
	v_min_u32_e32 v15, v31, v15
	v_max_u32_e32 v31, v8, v4
	v_min_u32_e32 v4, v8, v4
	v_max_u32_e32 v8, v0, v2
	v_min_u32_e32 v0, v0, v2
	v_max_u32_e32 v2, v6, v14
	v_min_u32_e32 v6, v6, v14
	v_max_u32_e32 v14, v32, v10
	v_min_u32_e32 v10, v32, v10
	v_max_u32_e32 v32, v50, v3
	v_min_u32_e32 v3, v50, v3
	v_max_u32_e32 v50, v51, v0
	v_min_u32_e32 v0, v51, v0
	v_max_u32_e32 v51, v27, v8
	v_min_u32_e32 v8, v27, v8
	v_max_u32_e32 v27, v30, v6
	v_min_u32_e32 v6, v30, v6
	v_max_u32_e32 v30, v28, v2
	v_min_u32_e32 v2, v28, v2
	v_max_u32_e32 v28, v29, v10
	v_min_u32_e32 v10, v29, v10
	v_max_u32_e32 v29, v15, v14
	v_min_u32_e32 v14, v15, v14
	v_max_u32_e32 v15, v31, v3
	v_min_u32_e32 v3, v31, v3
	v_max_u32_e32 v31, v4, v32
	v_min_u32_e32 v4, v4, v32
	v_max_u32_e32 v32, v50, v28
	v_min_u32_e32 v28, v50, v28
	v_max_u32_e32 v50, v51, v29
	v_min_u32_e32 v29, v51, v29
	v_max_u32_e32 v51, v27, v15
	v_min_u32_e32 v15, v27, v15
	v_max_u32_e32 v27, v30, v31
	v_min_u32_e32 v30, v30, v31
	v_max_u32_e32 v31, v0, v10
	v_min_u32_e32 v0, v0, v10
	v_max_u32_e32 v10, v8, v14
	v_min_u32_e32 v8, v8, v14
	v_max_u32_e32 v14, v6, v3
	v_min_u32_e32 v3, v6, v3
	v_max_u32_e32 v6, v2, v4
	v_min_u32_e32 v2, v2, v4
	v_max_u32_e32 v4, v32, v51
	v_min_u32_e32 v32, v32, v51
	v_max_u32_e32 v51, v50, v27
	v_min_u32_e32 v27, v50, v27
	v_max_u32_e32 v50, v28, v15
	v_min_u32_e32 v15, v28, v15
	v_max_u32_e32 v28, v29, v30
	v_min_u32_e32 v29, v29, v30
	v_max_u32_e32 v30, v31, v14
	v_min_u32_e32 v14, v31, v14
	v_max_u32_e32 v31, v10, v6
	v_min_u32_e32 v6, v10, v6
	v_max_u32_e32 v10, v0, v3
	v_min_u32_e32 v0, v0, v3
	v_max_u32_e32 v3, v8, v2
	v_min_u32_e32 v2, v8, v2
	v_min_u32_e32 v8, v4, v51
	v_min_u32_e32 v52, v32, v27
	v_min_u32_e32 v53, v50, v28
	v_min_u32_e32 v54, v15, v29
	v_min_u32_e32 v55, v30, v31
	v_min_u32_e32 v56, v14, v6
	v_min_u32_e32 v57, v10, v3
	v_min_u32_e32 v58, v0, v2
	v_max3_u32 v16, v16, v40, v58
	v_max3_u32 v0, v42, v0, v2
	v_max3_u32 v2, v39, v22, v57
	v_max3_u32 v3, v43, v10, v3
	v_max3_u32 v10, v38, v20, v56
	v_max3_u32 v6, v44, v14, v6
	v_max3_u32 v14, v17, v34, v55
	v_max3_u32 v17, v45, v30, v31
	v_max3_u32 v20, v37, v36, v54
	v_max3_u32 v15, v46, v15, v29
	v_max3_u32 v18, v23, v18, v53
	v_max3_u32 v22, v47, v50, v28
	v_max3_u32 v23, v35, v41, v52
	v_max3_u32 v27, v48, v32, v27
	v_max3_u32 v8, v33, v12, v8
	v_max3_u32 v4, v49, v4, v51
	v_max_u32_e32 v12, v16, v20
	v_min_u32_e32 v16, v16, v20
	v_max_u32_e32 v20, v0, v15
	v_min_u32_e32 v0, v0, v15
	v_max_u32_e32 v15, v2, v18
	v_min_u32_e32 v2, v2, v18
	v_max_u32_e32 v18, v3, v22
	v_min_u32_e32 v3, v3, v22
	v_max_u32_e32 v22, v10, v23
	v_min_u32_e32 v10, v10, v23
	v_max_u32_e32 v23, v6, v27
	v_min_u32_e32 v6, v6, v27
	v_max_u32_e32 v27, v14, v8
	v_min_u32_e32 v8, v14, v8
	v_max_u32_e32 v14, v17, v4
	v_min_u32_e32 v4, v17, v4
	v_max_u32_e32 v17, v12, v22
	v_min_u32_e32 v12, v12, v22
	v_max_u32_e32 v22, v20, v23
	v_min_u32_e32 v20, v20, v23
	v_max_u32_e32 v23, v15, v27
	v_min_u32_e32 v15, v15, v27
	v_max_u32_e32 v27, v18, v14
	v_min_u32_e32 v14, v18, v14
	v_max_u32_e32 v18, v16, v10
	v_min_u32_e32 v10, v16, v10
	v_max_u32_e32 v16, v0, v6
	v_min_u32_e32 v0, v0, v6
	v_max_u32_e32 v6, v2, v8
	v_min_u32_e32 v2, v2, v8
	v_max_u32_e32 v8, v3, v4
; __device__ __forceinline__ float key2f(unsigned k) { const unsigned u = (k & 0x80000000u) ? (k & 0x7fffffffu) : ~k; return __uint_as_float(u); }
; #define CE_DESC(a, b) do { const unsigned _mx = (a) > (b) ? (a) : (b), _mn = (a) > (b) ? (b) : (a); (a) = _mx; (b) = _mn; } while (0)
; #define CK(i, j) ((f2key(va[i] + vb[j]) & ~255u) | (unsigned)(255 - (16 * (i) + (j))))
; __device__ __forceinline__ void peer_tile(const Args& A, LAS unsigned char* lds, int tile) {
;     ...
;             { unsigned x0 = CK(14, 0), x1 = CK(15, 0);
; #pragma unroll
;               for (int i = 0; i < 16; ++i) CE_DESC(Lf[i], x0);
; #pragma unroll
;               for (int i = 0; i < 16; ++i) CE_DESC(Lf[i], x1); }
;     ...
;             float fv[16], den = 0.f; const float f0 = key2f(Lf[0] & ~255u);
; #pragma unroll
;             for (int k = 0; k < 16; ++k) { fv[k] = __expf(key2f(Lf[k] & ~255u) - f0); den += fv[k]; }
	v_min_u32_e32 v3, v3, v4
	v_max_u32_e32 v4, v17, v23
	v_min_u32_e32 v17, v17, v23
	v_max_u32_e32 v23, v22, v27
	v_min_u32_e32 v22, v22, v27
	v_max_u32_e32 v27, v12, v15
	v_min_u32_e32 v12, v12, v15
	v_max_u32_e32 v15, v20, v14
	v_min_u32_e32 v14, v20, v14
	v_max_u32_e32 v20, v18, v6
	v_min_u32_e32 v6, v18, v6
	v_max_u32_e32 v18, v16, v8
	v_min_u32_e32 v8, v16, v8
	v_max_u32_e32 v16, v10, v2
	v_min_u32_e32 v2, v10, v2
	v_max_u32_e32 v10, v0, v3
	v_min_u32_e32 v0, v0, v3
	v_max_u32_e32 v41, v2, v0
	v_min_u32_e32 v0, v2, v0
	v_add_f32_e32 v2, v25, v1
	v_not_b32_e32 v25, v2
	v_or_b32_e32 v42, 0x80000000, v2
	v_cmp_gt_i32_e32 vcc, 0, v2
	v_add_f32_e32 v1, v26, v1
	v_max_u32_e32 v3, v4, v23
	v_cndmask_b32_e32 v2, v42, v25, vcc
	v_and_or_b32 v2, v2, s34, 31
	v_not_b32_e32 v25, v1
	v_or_b32_e32 v26, 0x80000000, v1
	v_cmp_gt_i32_e32 vcc, 0, v1
	v_min_u32_e32 v28, v4, v23
	v_max_u32_e32 v29, v17, v22
	v_cndmask_b32_e32 v1, v26, v25, vcc
	v_max_u32_e32 v25, v3, v2
	v_min_u32_e32 v3, v3, v2
	v_min_u32_e32 v3, v28, v3
	v_min_u32_e32 v30, v17, v22
	v_med3_u32 v2, v4, v23, v2
	v_min_u32_e32 v23, v29, v3
	v_max_u32_e32 v31, v27, v15
	v_max_u32_e32 v4, v29, v3
	v_med3_u32 v3, v17, v22, v3
	v_min_u32_e32 v17, v30, v23
	v_min_u32_e32 v32, v27, v15
	v_min_u32_e32 v23, v31, v17
	v_max_u32_e32 v33, v12, v14
	v_max_u32_e32 v22, v31, v17
	v_med3_u32 v15, v27, v15, v17
	v_min_u32_e32 v17, v32, v23
	v_min_u32_e32 v34, v12, v14
	v_min_u32_e32 v26, v33, v17
	v_max_u32_e32 v35, v20, v18
	v_med3_u32 v12, v12, v14, v17
	v_min_u32_e32 v14, v34, v26
	v_min_u32_e32 v36, v20, v18
	v_min_u32_e32 v26, v35, v14
	v_max_u32_e32 v37, v6, v8
	v_max_u32_e32 v23, v33, v17
	v_max_u32_e32 v17, v35, v14
	v_med3_u32 v14, v20, v18, v14
	v_min_u32_e32 v18, v36, v26
	v_min_u32_e32 v38, v6, v8
	v_min_u32_e32 v26, v37, v18
	v_max_u32_e32 v39, v16, v10
	v_med3_u32 v6, v6, v8, v18
	v_min_u32_e32 v8, v38, v26
	v_min_u32_e32 v40, v16, v10
	v_min_u32_e32 v26, v39, v8
	v_and_or_b32 v1, v1, s34, 15
	v_max_u32_e32 v20, v37, v18
	v_max_u32_e32 v18, v39, v8
	v_med3_u32 v8, v16, v10, v8
	v_min_u32_e32 v10, v40, v26
	v_max_u32_e32 v26, v25, v1
	v_min_u32_e32 v1, v25, v1
	v_max_u32_e32 v25, v2, v1
	v_min_u32_e32 v1, v2, v1
	v_max_u32_e32 v2, v4, v1
	v_min_u32_e32 v1, v4, v1
	v_max_u32_e32 v4, v3, v1
	v_min_u32_e32 v1, v3, v1
	v_max_u32_e32 v3, v22, v1
	v_min_u32_e32 v1, v22, v1
	v_max_u32_e32 v22, v15, v1
	v_min_u32_e32 v1, v15, v1
	v_max_u32_e32 v15, v23, v1
	v_min_u32_e32 v1, v23, v1
	v_max_u32_e32 v23, v12, v1
	v_min_u32_e32 v1, v12, v1
	v_max_u32_e32 v12, v17, v1
	v_min_u32_e32 v1, v17, v1
	v_max_u32_e32 v17, v14, v1
	v_min_u32_e32 v1, v14, v1
	v_max_u32_e32 v14, v20, v1
	v_min_u32_e32 v1, v20, v1
	v_max_u32_e32 v20, v6, v1
	v_min_u32_e32 v1, v6, v1
	v_max_u32_e32 v6, v18, v1
	v_min_u32_e32 v1, v18, v1
	v_max_u32_e32 v16, v41, v10
	v_max_u32_e32 v18, v8, v1
	v_min_u32_e32 v1, v8, v1
	v_min_u32_e32 v10, v41, v10
	v_max_u32_e32 v8, v16, v1
	v_min_u32_e32 v1, v16, v1
	v_max3_u32 v10, v0, v10, v1
	v_and_b32_e32 v0, 0x7fffff00, v26
	v_bitop3_b32 v1, v26, s33, v26 bitop3:0xcf
	v_cmp_gt_i32_e32 vcc, 0, v26
	v_and_b32_e32 v16, 0x7fffff00, v25
	v_bitop3_b32 v27, v25, s33, v25 bitop3:0xcf
	v_cndmask_b32_e32 v0, v1, v0, vcc
	v_cmp_gt_i32_e32 vcc, 0, v25
	v_sub_f32_e32 v1, v0, v0
	v_bitop3_b32 v28, v2, s33, v2 bitop3:0xcf
	v_cndmask_b32_e32 v16, v27, v16, vcc
	v_and_b32_e32 v27, 0x7fffff00, v2
	v_cmp_gt_i32_e32 vcc, 0, v2
	v_mul_f32_e32 v1, 0x3fb8aa3b, v1
	v_sub_f32_e32 v16, v16, v0
	v_cndmask_b32_e32 v27, v28, v27, vcc
	v_and_b32_e32 v28, 0x7fffff00, v4
	v_bitop3_b32 v29, v4, s33, v4 bitop3:0xcf
	v_cmp_gt_i32_e32 vcc, 0, v4
	v_exp_f32_e32 v1, v1
	v_mul_f32_e32 v16, 0x3fb8aa3b, v16
	v_sub_f32_e32 v27, v27, v0
	v_cndmask_b32_e32 v28, v29, v28, vcc
	v_and_b32_e32 v30, 0x7fffff00, v3
	v_bitop3_b32 v31, v3, s33, v3 bitop3:0xcf
	v_cmp_gt_i32_e32 vcc, 0, v3
	v_exp_f32_e32 v16, v16
	v_mul_f32_e32 v27, 0x3fb8aa3b, v27
	v_sub_f32_e32 v28, v28, v0
	v_cndmask_b32_e32 v30, v31, v30, vcc
	v_and_b32_e32 v31, 0x7fffff00, v22
	v_bitop3_b32 v32, v22, s33, v22 bitop3:0xcf
	v_cmp_gt_i32_e32 vcc, 0, v22
	v_exp_f32_e32 v27, v27
	v_mul_f32_e32 v28, 0x3fb8aa3b, v28
	v_sub_f32_e32 v30, v30, v0
	v_cndmask_b32_e32 v31, v32, v31, vcc
	v_and_b32_e32 v32, 0x7fffff00, v15
	v_bitop3_b32 v33, v15, s33, v15 bitop3:0xcf
	v_cmp_gt_i32_e32 vcc, 0, v15
	v_exp_f32_e32 v28, v28
	v_mul_f32_e32 v30, 0x3fb8aa3b, v30
	v_sub_f32_e32 v31, v31, v0
	v_cndmask_b32_e32 v32, v33, v32, vcc
	v_and_b32_e32 v33, 0x7fffff00, v23
	v_bitop3_b32 v34, v23, s33, v23 bitop3:0xcf
	v_cmp_gt_i32_e32 vcc, 0, v23
	v_add_f32_e32 v29, 0, v1
	v_exp_f32_e32 v30, v30
	v_mul_f32_e32 v31, 0x3fb8aa3b, v31
	v_sub_f32_e32 v32, v32, v0
	v_cndmask_b32_e32 v33, v34, v33, vcc
	v_and_b32_e32 v34, 0x7fffff00, v12
	v_bitop3_b32 v35, v12, s33, v12 bitop3:0xcf
	v_cmp_gt_i32_e32 vcc, 0, v12
	v_add_f32_e32 v29, v29, v16
	v_exp_f32_e32 v31, v31
	v_mul_f32_e32 v32, 0x3fb8aa3b, v32
	v_sub_f32_e32 v33, v33, v0
	v_cndmask_b32_e32 v34, v35, v34, vcc
	v_and_b32_e32 v35, 0x7fffff00, v17
	v_bitop3_b32 v36, v17, s33, v17 bitop3:0xcf
	v_cmp_gt_i32_e32 vcc, 0, v17
	v_add_f32_e32 v29, v29, v27
	v_exp_f32_e32 v32, v32
	v_mul_f32_e32 v33, 0x3fb8aa3b, v33
	v_sub_f32_e32 v34, v34, v0
	v_cndmask_b32_e32 v35, v36, v35, vcc
	v_and_b32_e32 v36, 0x7fffff00, v14
	v_bitop3_b32 v37, v14, s33, v14 bitop3:0xcf
	v_cmp_gt_i32_e32 vcc, 0, v14
	v_add_f32_e32 v29, v29, v28
	v_exp_f32_e32 v33, v33
	v_mul_f32_e32 v34, 0x3fb8aa3b, v34
	v_sub_f32_e32 v35, v35, v0
	v_cndmask_b32_e32 v36, v37, v36, vcc
	v_and_b32_e32 v37, 0x7fffff00, v20
	v_bitop3_b32 v38, v20, s33, v20 bitop3:0xcf
	v_cmp_gt_i32_e32 vcc, 0, v20
	v_add_f32_e32 v29, v29, v30
; #define LDS_WAIT() asm volatile("s_waitcnt lgkmcnt(0)" ::: "memory")
; __device__ __forceinline__ float key2f(unsigned k) { const unsigned u = (k & 0x80000000u) ? (k & 0x7fffffffu) : ~k; return __uint_as_float(u); }
; __device__ __forceinline__ void peer_tile(const Args& A, LAS unsigned char* lds, int tile) {
;     ...
;             for (int k = 0; k < 16; ++k) { fv[k] = __expf(key2f(Lf[k] & ~255u) - f0); den += fv[k]; }
;             const float rden = 1.f / den;
;             LDS_WAIT();
; #pragma unroll
;             for (int k = 0; k < 16; ++k) { const unsigned code = 255u - (Lf[k] & 255u); const unsigned e = idx[code >> 4] * 128u + idx[16 + (code & 15u)];
;                 u32x2 sv; sv.x = e; sv.y = __float_as_uint(fv[k] * rden); SEL[(tl * 8 + h) * 16 + k] = sv; }
	v_exp_f32_e32 v34, v34
	v_mul_f32_e32 v35, 0x3fb8aa3b, v35
	v_sub_f32_e32 v36, v36, v0
	v_cndmask_b32_e32 v37, v38, v37, vcc
	v_and_b32_e32 v38, 0x7fffff00, v6
	v_bitop3_b32 v39, v6, s33, v6 bitop3:0xcf
	v_cmp_gt_i32_e32 vcc, 0, v6
	v_add_f32_e32 v29, v29, v31
	v_exp_f32_e32 v35, v35
	v_mul_f32_e32 v36, 0x3fb8aa3b, v36
	v_sub_f32_e32 v37, v37, v0
	v_cndmask_b32_e32 v38, v39, v38, vcc
	v_and_b32_e32 v39, 0x7fffff00, v18
	v_bitop3_b32 v40, v18, s33, v18 bitop3:0xcf
	v_cmp_gt_i32_e32 vcc, 0, v18
	v_add_f32_e32 v29, v29, v32
	v_exp_f32_e32 v36, v36
	v_mul_f32_e32 v37, 0x3fb8aa3b, v37
	v_sub_f32_e32 v38, v38, v0
	v_cndmask_b32_e32 v39, v40, v39, vcc
	v_and_b32_e32 v40, 0x7fffff00, v8
	v_bitop3_b32 v41, v8, s33, v8 bitop3:0xcf
	v_cmp_gt_i32_e32 vcc, 0, v8
	v_add_f32_e32 v29, v29, v33
	v_exp_f32_e32 v37, v37
	v_mul_f32_e32 v38, 0x3fb8aa3b, v38
	v_sub_f32_e32 v39, v39, v0
	v_cndmask_b32_e32 v40, v41, v40, vcc
	v_and_b32_e32 v41, 0x7fffff00, v10
	v_bitop3_b32 v42, v10, s33, v10 bitop3:0xcf
	v_cmp_gt_i32_e32 vcc, 0, v10
	v_add_f32_e32 v29, v29, v34
	v_exp_f32_e32 v38, v38
	v_mul_f32_e32 v39, 0x3fb8aa3b, v39
	v_sub_f32_e32 v40, v40, v0
	v_cndmask_b32_e32 v41, v42, v41, vcc
	v_add_f32_e32 v29, v29, v35
	v_exp_f32_e32 v39, v39
	v_mul_f32_e32 v40, 0x3fb8aa3b, v40
	v_sub_f32_e32 v0, v41, v0
	v_add_f32_e32 v29, v29, v36
	v_exp_f32_e32 v40, v40
	v_mul_f32_e32 v0, 0x3fb8aa3b, v0
	v_add_f32_e32 v29, v29, v37
	v_exp_f32_e32 v41, v0
	v_add_f32_e32 v0, v29, v38
	v_add_f32_e32 v0, v0, v39
	v_add_f32_e32 v0, v0, v40
	v_add_f32_e32 v0, v0, v41
	v_div_scale_f32 v29, s[0:1], v0, v0, 1.0
	v_rcp_f32_e32 v42, v29
	v_not_b32_e32 v21, v26
	v_not_b32_e32 v24, v25
	v_fma_f32 v43, -v29, v42, 1.0
	v_fmac_f32_e32 v42, v43, v42
	v_div_scale_f32 v43, vcc, 1.0, v0, 1.0
	v_mul_f32_e32 v44, v43, v42
	v_fma_f32 v45, -v29, v44, v43
	v_fmac_f32_e32 v44, v45, v42
	v_fma_f32 v29, -v29, v44, v43
	v_div_fmas_f32 v29, v29, v42, v44
	v_div_fixup_f32 v29, v29, v0, 1.0
	v_and_b32_e32 v0, 48, v19
	v_lshrrev_b32_e32 v19, 2, v21
	v_and_b32_e32 v19, 60, v19
	v_bitop3_b32 v21, v26, 15, v26 bitop3:0xc
	v_add_u32_e32 v19, v5, v19
	v_lshl_add_u32 v21, v21, 2, v5
	ds_read_b32 v19, v19
	ds_read_b32 v21, v21 offset:64
	v_lshlrev_b32_e32 v0, 3, v0
	v_add3_u32 v11, v13, v11, v0
	v_mul_f32_e32 v1, v1, v29
	v_not_b32_e32 v13, v2
	s_waitcnt lgkmcnt(0)
	v_lshl_add_u32 v0, v19, 7, v21
	ds_write_b64 v11, v[0:1]
	v_lshrrev_b32_e32 v0, 2, v24
	v_and_b32_e32 v0, 60, v0
	v_bitop3_b32 v1, v25, 15, v25 bitop3:0xc
	v_add_u32_e32 v0, v5, v0
	v_lshl_add_u32 v1, v1, 2, v5
	ds_read_b32 v0, v0
	ds_read_b32 v1, v1 offset:64
	v_cmp_eq_u32_e32 vcc, 0, v9
	s_waitcnt lgkmcnt(0)
	v_lshl_add_u32 v0, v0, 7, v1
	v_mul_f32_e32 v1, v16, v29
	ds_write_b64 v11, v[0:1] offset:8
	v_lshrrev_b32_e32 v0, 2, v13
	v_and_b32_e32 v0, 60, v0
	v_bitop3_b32 v1, v2, 15, v2 bitop3:0xc
	v_add_u32_e32 v0, v5, v0
	v_lshl_add_u32 v1, v1, 2, v5
	ds_read_b32 v0, v0
	ds_read_b32 v1, v1 offset:64
	v_not_b32_e32 v2, v4
	s_waitcnt lgkmcnt(0)
	v_lshl_add_u32 v0, v0, 7, v1
	v_mul_f32_e32 v1, v27, v29
	ds_write_b64 v11, v[0:1] offset:16
	v_lshrrev_b32_e32 v0, 2, v2
	v_and_b32_e32 v0, 60, v0
	v_bitop3_b32 v1, v4, 15, v4 bitop3:0xc
	v_add_u32_e32 v0, v5, v0
	v_lshl_add_u32 v1, v1, 2, v5
	ds_read_b32 v0, v0
	ds_read_b32 v1, v1 offset:64
	v_not_b32_e32 v2, v3
	v_mul_lo_u32 v4, v7, s36
	s_waitcnt lgkmcnt(0)
	v_lshl_add_u32 v0, v0, 7, v1
	v_mul_f32_e32 v1, v28, v29
	ds_write_b64 v11, v[0:1] offset:24
	v_lshrrev_b32_e32 v0, 2, v2
	v_and_b32_e32 v0, 60, v0
	v_bitop3_b32 v1, v3, 15, v3 bitop3:0xc
	v_add_u32_e32 v0, v5, v0
	v_lshl_add_u32 v1, v1, 2, v5
	ds_read_b32 v0, v0
	ds_read_b32 v1, v1 offset:64
	v_not_b32_e32 v2, v22
	s_waitcnt lgkmcnt(0)
	v_lshl_add_u32 v0, v0, 7, v1
	v_mul_f32_e32 v1, v30, v29
	ds_write_b64 v11, v[0:1] offset:32
	v_lshrrev_b32_e32 v0, 2, v2
	v_and_b32_e32 v0, 60, v0
	v_bitop3_b32 v1, v22, 15, v22 bitop3:0xc
	v_add_u32_e32 v0, v5, v0
	v_lshl_add_u32 v1, v1, 2, v5
	ds_read_b32 v0, v0
	ds_read_b32 v1, v1 offset:64
	v_not_b32_e32 v2, v15
	s_waitcnt lgkmcnt(0)
	v_lshl_add_u32 v0, v0, 7, v1
	v_mul_f32_e32 v1, v31, v29
	ds_write_b64 v11, v[0:1] offset:40
	v_lshrrev_b32_e32 v0, 2, v2
	v_and_b32_e32 v0, 60, v0
	v_bitop3_b32 v1, v15, 15, v15 bitop3:0xc
	v_add_u32_e32 v0, v5, v0
	v_lshl_add_u32 v1, v1, 2, v5
	ds_read_b32 v0, v0
	ds_read_b32 v1, v1 offset:64
	v_not_b32_e32 v2, v23
	s_waitcnt lgkmcnt(0)
	v_lshl_add_u32 v0, v0, 7, v1
	v_mul_f32_e32 v1, v32, v29
	ds_write_b64 v11, v[0:1] offset:48
	v_lshrrev_b32_e32 v0, 2, v2
	v_and_b32_e32 v0, 60, v0
	v_bitop3_b32 v1, v23, 15, v23 bitop3:0xc
	v_add_u32_e32 v0, v5, v0
	v_lshl_add_u32 v1, v1, 2, v5
	ds_read_b32 v0, v0
	ds_read_b32 v1, v1 offset:64
	v_not_b32_e32 v2, v12
	s_waitcnt lgkmcnt(0)
	v_lshl_add_u32 v0, v0, 7, v1
	v_mul_f32_e32 v1, v33, v29
	ds_write_b64 v11, v[0:1] offset:56
	v_lshrrev_b32_e32 v0, 2, v2
	v_and_b32_e32 v0, 60, v0
	v_bitop3_b32 v1, v12, 15, v12 bitop3:0xc
	v_add_u32_e32 v0, v5, v0
	v_lshl_add_u32 v1, v1, 2, v5
	ds_read_b32 v0, v0
	ds_read_b32 v1, v1 offset:64
	v_not_b32_e32 v2, v17
	s_waitcnt lgkmcnt(0)
	v_lshl_add_u32 v0, v0, 7, v1
	v_mul_f32_e32 v1, v34, v29
	ds_write_b64 v11, v[0:1] offset:64
	v_lshrrev_b32_e32 v0, 2, v2
	v_and_b32_e32 v0, 60, v0
	v_bitop3_b32 v1, v17, 15, v17 bitop3:0xc
	v_add_u32_e32 v0, v5, v0
	v_lshl_add_u32 v1, v1, 2, v5
	ds_read_b32 v0, v0
	ds_read_b32 v1, v1 offset:64
	v_not_b32_e32 v2, v14
	s_waitcnt lgkmcnt(0)
	v_lshl_add_u32 v0, v0, 7, v1
	v_mul_f32_e32 v1, v35, v29
	ds_write_b64 v11, v[0:1] offset:72
	v_lshrrev_b32_e32 v0, 2, v2
	v_and_b32_e32 v0, 60, v0
	v_bitop3_b32 v1, v14, 15, v14 bitop3:0xc
	v_add_u32_e32 v0, v5, v0
	v_lshl_add_u32 v1, v1, 2, v5
	ds_read_b32 v0, v0
	ds_read_b32 v1, v1 offset:64
	v_not_b32_e32 v2, v20
	s_waitcnt lgkmcnt(0)
; __device__ __forceinline__ unsigned pk2(float lo, float hi) { const f32x2 v = {lo, hi}; const bf16x2_t b = __builtin_convertvector(v, bf16x2_t); return __builtin_bit_cast(unsigned, b); }
; __device__ __forceinline__ float bflo(unsigned u) { return __uint_as_float(u << 16); }
; __device__ __forceinline__ float bfhi(unsigned u) { return __uint_as_float(u & 0xffff0000u); }
; __device__ __forceinline__ void peer_tile(const Args& A, LAS unsigned char* lds, int tile) {
;     ...
;             for (int k = 0; k < 16; ++k) { const unsigned code = 255u - (Lf[k] & 255u); const unsigned e = idx[code >> 4] * 128u + idx[16 + (code & 15u)];
;                 u32x2 sv; sv.x = e; sv.y = __float_as_uint(fv[k] * rden); SEL[(tl * 8 + h) * 16 + k] = sv; }
;         }
;     }
;     __syncthreads();
;     ...
;     const bf16_t* A3 = (const bf16_t*)(A.ws + WS_A3); const float* RSq = (const float*)(A.ws + WS_RS);
;     for (int pass = 0; pass < 2; ++pass) {
;         const int tb = 8 * w + 4 * pass;
;         u32x4 xpa[4], xpb[4]; f32x2 oacc[4][8];
; #pragma unroll
;         for (int tk = 0; tk < 4; ++tk) { const size_t m = (size_t)tile * 64 + tb + tk;
;             { const u32x4 ra = *(const u32x4*)(A3 + m * 1024 + 16 * lane), rb = *(const u32x4*)(A3 + m * 1024 + 16 * lane + 8);
;               float xr_; { const f32x4 p0 = *(const f32x4*)(RSq + m * 16), p1 = *(const f32x4*)(RSq + m * 16 + 4), p2 = *(const f32x4*)(RSq + m * 16 + 8), p3 = *(const f32x4*)(RSq + m * 16 + 12);
;                 const f32x4 ps = (p0 + p1) + (p2 + p3); xr_ = rsqrtf(((ps[0] + ps[1]) + (ps[2] + ps[3])) * (1.f / 1024.f) + 1e-6f); }
;               const unsigned rr[8] = {ra.x, ra.y, ra.z, ra.w, rb.x, rb.y, rb.z, rb.w}; unsigned hh[8];
;               const float* sp = MOD + (int)(m >> 11) * 6144 + 3072 + 16 * lane;
; #pragma unroll
;               for (int q = 0; q < 8; ++q) { const f32x2 sh = *(const f32x2*)(sp + 2 * q); hh[q] = pk2(bflo(rr[q]) * xr_ + sh[0], bfhi(rr[q]) * xr_ + sh[1]); }
;               xpa[tk] = (u32x4){hh[0], hh[1], hh[2], hh[3]}; xpb[tk] = (u32x4){hh[4], hh[5], hh[6], hh[7]}; }
; #pragma unroll
;             for (int q = 0; q < 8; ++q) oacc[tk][q] = (f32x2){0.f, 0.f}; }
	v_lshl_add_u32 v0, v0, 7, v1
	v_mul_f32_e32 v1, v36, v29
	ds_write_b64 v11, v[0:1] offset:80
	v_lshrrev_b32_e32 v0, 2, v2
	v_and_b32_e32 v0, 60, v0
	v_bitop3_b32 v1, v20, 15, v20 bitop3:0xc
	v_add_u32_e32 v0, v5, v0
	v_lshl_add_u32 v1, v1, 2, v5
	ds_read_b32 v0, v0
	ds_read_b32 v1, v1 offset:64
	v_not_b32_e32 v2, v6
	s_waitcnt lgkmcnt(0)
	v_lshl_add_u32 v0, v0, 7, v1
	v_mul_f32_e32 v1, v37, v29
	ds_write_b64 v11, v[0:1] offset:88
	v_lshrrev_b32_e32 v0, 2, v2
	v_and_b32_e32 v0, 60, v0
	v_bitop3_b32 v1, v6, 15, v6 bitop3:0xc
	v_add_u32_e32 v0, v5, v0
	v_lshl_add_u32 v1, v1, 2, v5
	ds_read_b32 v0, v0
	ds_read_b32 v1, v1 offset:64
	v_not_b32_e32 v2, v18
	s_waitcnt lgkmcnt(0)
	v_lshl_add_u32 v0, v0, 7, v1
	v_mul_f32_e32 v1, v38, v29
	ds_write_b64 v11, v[0:1] offset:96
	v_lshrrev_b32_e32 v0, 2, v2
	v_and_b32_e32 v0, 60, v0
	v_bitop3_b32 v1, v18, 15, v18 bitop3:0xc
	v_add_u32_e32 v0, v5, v0
	v_lshl_add_u32 v1, v1, 2, v5
	ds_read_b32 v0, v0
	ds_read_b32 v1, v1 offset:64
	v_not_b32_e32 v2, v8
	s_waitcnt lgkmcnt(0)
	v_lshl_add_u32 v0, v0, 7, v1
	v_mul_f32_e32 v1, v39, v29
	ds_write_b64 v11, v[0:1] offset:104
	v_lshrrev_b32_e32 v0, 2, v2
	v_and_b32_e32 v0, 60, v0
	v_bitop3_b32 v1, v8, 15, v8 bitop3:0xc
	v_add_u32_e32 v0, v5, v0
	v_lshl_add_u32 v1, v1, 2, v5
	ds_read_b32 v0, v0
	ds_read_b32 v1, v1 offset:64
	v_not_b32_e32 v2, v10
	s_waitcnt lgkmcnt(0)
	v_lshl_add_u32 v0, v0, 7, v1
	v_mul_f32_e32 v1, v40, v29
	ds_write_b64 v11, v[0:1] offset:112
	v_lshrrev_b32_e32 v0, 2, v2
	v_and_b32_e32 v0, 60, v0
	v_bitop3_b32 v1, v10, 15, v10 bitop3:0xc
	v_add_u32_e32 v0, v5, v0
	v_lshl_add_u32 v1, v1, 2, v5
	ds_read_b32 v0, v0
	ds_read_b32 v1, v1 offset:64
	v_lshlrev_b32_e32 v5, 13, v7
	v_lshl_or_b32 v6, v9, 3, v5
	s_waitcnt lgkmcnt(0)
	v_lshl_add_u32 v0, v0, 7, v1
	v_mul_f32_e32 v1, v41, v29
	ds_write_b64 v11, v[0:1] offset:120
	s_waitcnt lgkmcnt(0)
	s_barrier
	s_mov_b64 exec, -1
	v_and_b32_e32 v240, 63, v214
	v_lshrrev_b32_e32 v242, 6, v214
	v_lshlrev_b32_e32 v240, 4, v240
	v_readfirstlane_b32 s16, v242
	v_lshlrev_b32_e32 v245, 1, v240
	v_lshlrev_b32_e32 v246, 2, v240
	v_lshrrev_b32_e32 v247, 4, v240
	v_and_b32_e32 v247, 48, v247
	v_mov_b32_e32 v244, 0
	v_mov_b32_e32 v243, 0x358637bd
	v_mov_b32_e32 v242, 0xbf3a00e3
	s_add_u32 s4, s50, 0x1000000
	s_addc_u32 s5, s51, 0
	s_add_u32 s6, s50, 0x2000000
	s_addc_u32 s7, s51, 0
	s_add_u32 s8, s50, 0x3000000
	s_addc_u32 s9, s51, 0
	s_add_u32 s52, s50, 0x3010000
	s_addc_u32 s53, s51, 0
	s_add_u32 s12, s50, 0xb000000
	s_addc_u32 s13, s51, 0
	s_add_u32 s14, s50, 0xd000000
	s_addc_u32 s15, s51, 0
	s_lshr_b32 s0, s2, 5
	s_mul_i32 s0, s0, 0x6000
	s_add_u32 s10, s50, s0
	s_addc_u32 s11, s51, 0
	s_add_u32 s80, s10, 0x4000
	s_addc_u32 s81, s11, 0
	s_add_u32 s82, s10, 0x6000
	s_addc_u32 s83, s11, 0
	s_mul_i32 s22, s16, 8704
	s_mov_b32 s72, 0x3e6d3388
	s_lshl_b32 s76, s16, 3
	s_lshl_b32 s0, s2, 6
	s_add_i32 s77, s0, s76
	global_load_dwordx4 v[192:195], v246, s[80:81] offset:0
	global_load_dwordx4 v[196:199], v246, s[80:81] offset:16
	global_load_dwordx4 v[200:203], v246, s[80:81] offset:32
	global_load_dwordx4 v[204:207], v246, s[80:81] offset:48
	s_add_i32 s0, s77, 0
	s_lshl_b32 s1, s0, 11
	s_add_u32 s78, s12, s1
	s_addc_u32 s79, s13, 0
	global_load_dwordx4 v[128:131], v245, s[78:79]
	global_load_dwordx4 v[132:135], v245, s[78:79] offset:16
	global_load_dwordx4 v[136:139], v245, s[78:79] offset:2048
	global_load_dwordx4 v[140:143], v245, s[78:79] offset:2064
	s_lshl_b32 s1, s0, 6
	s_add_u32 s78, s14, s1
	s_addc_u32 s79, s15, 0
	global_load_dwordx4 v[144:147], v244, s[78:79] offset:0
	global_load_dwordx4 v[148:151], v244, s[78:79] offset:16
	global_load_dwordx4 v[152:155], v244, s[78:79] offset:32
	global_load_dwordx4 v[156:159], v244, s[78:79] offset:48
	global_load_dwordx4 v[160:163], v244, s[78:79] offset:64
	global_load_dwordx4 v[164:167], v244, s[78:79] offset:80
	global_load_dwordx4 v[168:171], v244, s[78:79] offset:96
	global_load_dwordx4 v[172:175], v244, s[78:79] offset:112
	s_waitcnt vmcnt(0)
	v_pk_add_f32 v[144:145], v[144:145], v[148:149]
	v_pk_add_f32 v[146:147], v[146:147], v[150:151]
	v_pk_add_f32 v[152:153], v[152:153], v[156:157]
	v_pk_add_f32 v[154:155], v[154:155], v[158:159]
	v_pk_add_f32 v[144:145], v[144:145], v[152:153]
	v_pk_add_f32 v[146:147], v[146:147], v[154:155]
	v_add_f32_e32 v144, v144, v145
	v_add_f32_e32 v146, v146, v147
	v_add_f32_e32 v144, v144, v146
	v_fmamk_f32 v144, v144, 0x3a800000, v243
	v_rsq_f32_e32 v144, v144
	v_pk_add_f32 v[160:161], v[160:161], v[164:165]
	v_pk_add_f32 v[162:163], v[162:163], v[166:167]
	v_pk_add_f32 v[168:169], v[168:169], v[172:173]
	v_pk_add_f32 v[170:171], v[170:171], v[174:175]
	v_pk_add_f32 v[160:161], v[160:161], v[168:169]
	v_pk_add_f32 v[162:163], v[162:163], v[170:171]
	v_add_f32_e32 v160, v160, v161
	v_add_f32_e32 v162, v162, v163
	v_add_f32_e32 v160, v160, v162
	v_fmamk_f32 v160, v160, 0x3a800000, v243
	v_rsq_f32_e32 v160, v160
	v_lshlrev_b32_e32 v253, 16, v128
	v_and_b32_e32 v254, 0xffff0000, v128
	v_fma_f32 v253, v253, v144, v192
	v_fma_f32 v254, v254, v144, v193
	v_cvt_pk_bf16_f32 v255, v253, v254
	v_lshlrev_b32_e32 v0, 16, v255
	v_and_b32_e32 v1, 0xffff0000, v255
	v_lshlrev_b32_e32 v253, 16, v129
	v_and_b32_e32 v254, 0xffff0000, v129
	v_fma_f32 v253, v253, v144, v194
	v_fma_f32 v254, v254, v144, v195
	v_cvt_pk_bf16_f32 v255, v253, v254
	v_lshlrev_b32_e32 v2, 16, v255
	v_and_b32_e32 v3, 0xffff0000, v255
	v_lshlrev_b32_e32 v253, 16, v130
	v_and_b32_e32 v254, 0xffff0000, v130
	v_fma_f32 v253, v253, v144, v196
	v_fma_f32 v254, v254, v144, v197
	v_cvt_pk_bf16_f32 v255, v253, v254
	v_lshlrev_b32_e32 v4, 16, v255
	v_and_b32_e32 v5, 0xffff0000, v255
; __device__ __forceinline__ unsigned pk2(float lo, float hi) { const f32x2 v = {lo, hi}; const bf16x2_t b = __builtin_convertvector(v, bf16x2_t); return __builtin_bit_cast(unsigned, b); }
; __device__ __forceinline__ float bflo(unsigned u) { return __uint_as_float(u << 16); }
; __device__ __forceinline__ float bfhi(unsigned u) { return __uint_as_float(u & 0xffff0000u); }
; __device__ __forceinline__ void peer_tile(const Args& A, LAS unsigned char* lds, int tile) {
;     ...
;         for (int tk = 0; tk < 4; ++tk) { const size_t m = (size_t)tile * 64 + tb + tk;
;             { const u32x4 ra = *(const u32x4*)(A3 + m * 1024 + 16 * lane), rb = *(const u32x4*)(A3 + m * 1024 + 16 * lane + 8);
;               float xr_; { const f32x4 p0 = *(const f32x4*)(RSq + m * 16), p1 = *(const f32x4*)(RSq + m * 16 + 4), p2 = *(const f32x4*)(RSq + m * 16 + 8), p3 = *(const f32x4*)(RSq + m * 16 + 12);
;                 const f32x4 ps = (p0 + p1) + (p2 + p3); xr_ = rsqrtf(((ps[0] + ps[1]) + (ps[2] + ps[3])) * (1.f / 1024.f) + 1e-6f); }
;               const unsigned rr[8] = {ra.x, ra.y, ra.z, ra.w, rb.x, rb.y, rb.z, rb.w}; unsigned hh[8];
;               const float* sp = MOD + (int)(m >> 11) * 6144 + 3072 + 16 * lane;
; #pragma unroll
;               for (int q = 0; q < 8; ++q) { const f32x2 sh = *(const f32x2*)(sp + 2 * q); hh[q] = pk2(bflo(rr[q]) * xr_ + sh[0], bfhi(rr[q]) * xr_ + sh[1]); }
;               xpa[tk] = (u32x4){hh[0], hh[1], hh[2], hh[3]}; xpb[tk] = (u32x4){hh[4], hh[5], hh[6], hh[7]}; }
;     ...
;                 { const unsigned xx[8] = {xpa[tk].x, xpa[tk].y, xpa[tk].z, xpa[tk].w, xpb[tk].x, xpb[tk].y, xpb[tk].z, xpb[tk].w};
; #pragma unroll
;                   for (int q = 0; q < 8; ++q) xf[q] = (f32x2){bflo(xx[q]), bfhi(xx[q])}; }
	v_lshlrev_b32_e32 v253, 16, v131
	v_and_b32_e32 v254, 0xffff0000, v131
	v_fma_f32 v253, v253, v144, v198
	v_fma_f32 v254, v254, v144, v199
	v_cvt_pk_bf16_f32 v255, v253, v254
	v_lshlrev_b32_e32 v6, 16, v255
	v_and_b32_e32 v7, 0xffff0000, v255
	v_lshlrev_b32_e32 v253, 16, v132
	v_and_b32_e32 v254, 0xffff0000, v132
	v_fma_f32 v253, v253, v144, v200
	v_fma_f32 v254, v254, v144, v201
	v_cvt_pk_bf16_f32 v255, v253, v254
	v_lshlrev_b32_e32 v8, 16, v255
	v_and_b32_e32 v9, 0xffff0000, v255
	v_lshlrev_b32_e32 v253, 16, v133
	v_and_b32_e32 v254, 0xffff0000, v133
	v_fma_f32 v253, v253, v144, v202
	v_fma_f32 v254, v254, v144, v203
	v_cvt_pk_bf16_f32 v255, v253, v254
	v_lshlrev_b32_e32 v10, 16, v255
	v_and_b32_e32 v11, 0xffff0000, v255
	v_lshlrev_b32_e32 v253, 16, v134
	v_and_b32_e32 v254, 0xffff0000, v134
	v_fma_f32 v253, v253, v144, v204
	v_fma_f32 v254, v254, v144, v205
	v_cvt_pk_bf16_f32 v255, v253, v254
	v_lshlrev_b32_e32 v12, 16, v255
	v_and_b32_e32 v13, 0xffff0000, v255
	v_lshlrev_b32_e32 v253, 16, v135
	v_and_b32_e32 v254, 0xffff0000, v135
	v_fma_f32 v253, v253, v144, v206
	v_fma_f32 v254, v254, v144, v207
	v_cvt_pk_bf16_f32 v255, v253, v254
	v_lshlrev_b32_e32 v14, 16, v255
	v_and_b32_e32 v15, 0xffff0000, v255
	v_lshlrev_b32_e32 v253, 16, v136
	v_and_b32_e32 v254, 0xffff0000, v136
	v_fma_f32 v253, v253, v160, v192
	v_fma_f32 v254, v254, v160, v193
	v_cvt_pk_bf16_f32 v255, v253, v254
	v_lshlrev_b32_e32 v16, 16, v255
	v_and_b32_e32 v17, 0xffff0000, v255
	v_lshlrev_b32_e32 v253, 16, v137
	v_and_b32_e32 v254, 0xffff0000, v137
	v_fma_f32 v253, v253, v160, v194
	v_fma_f32 v254, v254, v160, v195
	v_cvt_pk_bf16_f32 v255, v253, v254
	v_lshlrev_b32_e32 v18, 16, v255
	v_and_b32_e32 v19, 0xffff0000, v255
	v_lshlrev_b32_e32 v253, 16, v138
	v_and_b32_e32 v254, 0xffff0000, v138
	v_fma_f32 v253, v253, v160, v196
	v_fma_f32 v254, v254, v160, v197
	v_cvt_pk_bf16_f32 v255, v253, v254
	v_lshlrev_b32_e32 v20, 16, v255
	v_and_b32_e32 v21, 0xffff0000, v255
	v_lshlrev_b32_e32 v253, 16, v139
	v_and_b32_e32 v254, 0xffff0000, v139
	v_fma_f32 v253, v253, v160, v198
	v_fma_f32 v254, v254, v160, v199
	v_cvt_pk_bf16_f32 v255, v253, v254
	v_lshlrev_b32_e32 v22, 16, v255
	v_and_b32_e32 v23, 0xffff0000, v255
	v_lshlrev_b32_e32 v253, 16, v140
	v_and_b32_e32 v254, 0xffff0000, v140
	v_fma_f32 v253, v253, v160, v200
	v_fma_f32 v254, v254, v160, v201
	v_cvt_pk_bf16_f32 v255, v253, v254
	v_lshlrev_b32_e32 v24, 16, v255
	v_and_b32_e32 v25, 0xffff0000, v255
	v_lshlrev_b32_e32 v253, 16, v141
	v_and_b32_e32 v254, 0xffff0000, v141
	v_fma_f32 v253, v253, v160, v202
	v_fma_f32 v254, v254, v160, v203
	v_cvt_pk_bf16_f32 v255, v253, v254
	v_lshlrev_b32_e32 v26, 16, v255
	v_and_b32_e32 v27, 0xffff0000, v255
	v_lshlrev_b32_e32 v253, 16, v142
	v_and_b32_e32 v254, 0xffff0000, v142
	v_fma_f32 v253, v253, v160, v204
	v_fma_f32 v254, v254, v160, v205
	v_cvt_pk_bf16_f32 v255, v253, v254
	v_lshlrev_b32_e32 v28, 16, v255
	v_and_b32_e32 v29, 0xffff0000, v255
	v_lshlrev_b32_e32 v253, 16, v143
	v_and_b32_e32 v254, 0xffff0000, v143
	v_fma_f32 v253, v253, v160, v206
	v_fma_f32 v254, v254, v160, v207
	v_cvt_pk_bf16_f32 v255, v253, v254
	v_lshlrev_b32_e32 v30, 16, v255
	v_and_b32_e32 v31, 0xffff0000, v255
	s_add_i32 s0, s77, 2
	s_lshl_b32 s1, s0, 11
	s_add_u32 s78, s12, s1
	s_addc_u32 s79, s13, 0
	global_load_dwordx4 v[128:131], v245, s[78:79]
	global_load_dwordx4 v[132:135], v245, s[78:79] offset:16
	global_load_dwordx4 v[136:139], v245, s[78:79] offset:2048
	global_load_dwordx4 v[140:143], v245, s[78:79] offset:2064
	s_lshl_b32 s1, s0, 6
	s_add_u32 s78, s14, s1
	s_addc_u32 s79, s15, 0
	global_load_dwordx4 v[144:147], v244, s[78:79] offset:0
	global_load_dwordx4 v[148:151], v244, s[78:79] offset:16
	global_load_dwordx4 v[152:155], v244, s[78:79] offset:32
	global_load_dwordx4 v[156:159], v244, s[78:79] offset:48
	global_load_dwordx4 v[160:163], v244, s[78:79] offset:64
	global_load_dwordx4 v[164:167], v244, s[78:79] offset:80
	global_load_dwordx4 v[168:171], v244, s[78:79] offset:96
	global_load_dwordx4 v[172:175], v244, s[78:79] offset:112
	s_waitcnt vmcnt(0)
	v_pk_add_f32 v[144:145], v[144:145], v[148:149]
	v_pk_add_f32 v[146:147], v[146:147], v[150:151]
	v_pk_add_f32 v[152:153], v[152:153], v[156:157]
	v_pk_add_f32 v[154:155], v[154:155], v[158:159]
	v_pk_add_f32 v[144:145], v[144:145], v[152:153]
	v_pk_add_f32 v[146:147], v[146:147], v[154:155]
	v_add_f32_e32 v144, v144, v145
	v_add_f32_e32 v146, v146, v147
	v_add_f32_e32 v144, v144, v146
	v_fmamk_f32 v144, v144, 0x3a800000, v243
	v_rsq_f32_e32 v144, v144
	v_pk_add_f32 v[160:161], v[160:161], v[164:165]
	v_pk_add_f32 v[162:163], v[162:163], v[166:167]
	v_pk_add_f32 v[168:169], v[168:169], v[172:173]
	v_pk_add_f32 v[170:171], v[170:171], v[174:175]
	v_pk_add_f32 v[160:161], v[160:161], v[168:169]
	v_pk_add_f32 v[162:163], v[162:163], v[170:171]
	v_add_f32_e32 v160, v160, v161
	v_add_f32_e32 v162, v162, v163
	v_add_f32_e32 v160, v160, v162
	v_fmamk_f32 v160, v160, 0x3a800000, v243
	v_rsq_f32_e32 v160, v160
	v_lshlrev_b32_e32 v253, 16, v128
	v_and_b32_e32 v254, 0xffff0000, v128
	v_fma_f32 v253, v253, v144, v192
	v_fma_f32 v254, v254, v144, v193
	v_cvt_pk_bf16_f32 v255, v253, v254
	v_lshlrev_b32_e32 v32, 16, v255
	v_and_b32_e32 v33, 0xffff0000, v255
	v_lshlrev_b32_e32 v253, 16, v129
	v_and_b32_e32 v254, 0xffff0000, v129
	v_fma_f32 v253, v253, v144, v194
	v_fma_f32 v254, v254, v144, v195
	v_cvt_pk_bf16_f32 v255, v253, v254
	v_lshlrev_b32_e32 v34, 16, v255
	v_and_b32_e32 v35, 0xffff0000, v255
	v_lshlrev_b32_e32 v253, 16, v130
	v_and_b32_e32 v254, 0xffff0000, v130
	v_fma_f32 v253, v253, v144, v196
	v_fma_f32 v254, v254, v144, v197
	v_cvt_pk_bf16_f32 v255, v253, v254
; __device__ __forceinline__ unsigned pk2(float lo, float hi) { const f32x2 v = {lo, hi}; const bf16x2_t b = __builtin_convertvector(v, bf16x2_t); return __builtin_bit_cast(unsigned, b); }
; __device__ __forceinline__ float bflo(unsigned u) { return __uint_as_float(u << 16); }
; __device__ __forceinline__ float bfhi(unsigned u) { return __uint_as_float(u & 0xffff0000u); }
; __device__ __forceinline__ void peer_tile(const Args& A, LAS unsigned char* lds, int tile) {
;     ...
;         for (int tk = 0; tk < 4; ++tk) { const size_t m = (size_t)tile * 64 + tb + tk;
;             { const u32x4 ra = *(const u32x4*)(A3 + m * 1024 + 16 * lane), rb = *(const u32x4*)(A3 + m * 1024 + 16 * lane + 8);
;               float xr_; { const f32x4 p0 = *(const f32x4*)(RSq + m * 16), p1 = *(const f32x4*)(RSq + m * 16 + 4), p2 = *(const f32x4*)(RSq + m * 16 + 8), p3 = *(const f32x4*)(RSq + m * 16 + 12);
;                 const f32x4 ps = (p0 + p1) + (p2 + p3); xr_ = rsqrtf(((ps[0] + ps[1]) + (ps[2] + ps[3])) * (1.f / 1024.f) + 1e-6f); }
;               const unsigned rr[8] = {ra.x, ra.y, ra.z, ra.w, rb.x, rb.y, rb.z, rb.w}; unsigned hh[8];
;               const float* sp = MOD + (int)(m >> 11) * 6144 + 3072 + 16 * lane;
; #pragma unroll
;               for (int q = 0; q < 8; ++q) { const f32x2 sh = *(const f32x2*)(sp + 2 * q); hh[q] = pk2(bflo(rr[q]) * xr_ + sh[0], bfhi(rr[q]) * xr_ + sh[1]); }
;               xpa[tk] = (u32x4){hh[0], hh[1], hh[2], hh[3]}; xpb[tk] = (u32x4){hh[4], hh[5], hh[6], hh[7]}; }
;     ...
;                 { const unsigned xx[8] = {xpa[tk].x, xpa[tk].y, xpa[tk].z, xpa[tk].w, xpb[tk].x, xpb[tk].y, xpb[tk].z, xpb[tk].w};
; #pragma unroll
;                   for (int q = 0; q < 8; ++q) xf[q] = (f32x2){bflo(xx[q]), bfhi(xx[q])}; }
	v_lshlrev_b32_e32 v36, 16, v255
	v_and_b32_e32 v37, 0xffff0000, v255
	v_lshlrev_b32_e32 v253, 16, v131
	v_and_b32_e32 v254, 0xffff0000, v131
	v_fma_f32 v253, v253, v144, v198
	v_fma_f32 v254, v254, v144, v199
	v_cvt_pk_bf16_f32 v255, v253, v254
	v_lshlrev_b32_e32 v38, 16, v255
	v_and_b32_e32 v39, 0xffff0000, v255
	v_lshlrev_b32_e32 v253, 16, v132
	v_and_b32_e32 v254, 0xffff0000, v132
	v_fma_f32 v253, v253, v144, v200
	v_fma_f32 v254, v254, v144, v201
	v_cvt_pk_bf16_f32 v255, v253, v254
	v_lshlrev_b32_e32 v40, 16, v255
	v_and_b32_e32 v41, 0xffff0000, v255
	v_lshlrev_b32_e32 v253, 16, v133
	v_and_b32_e32 v254, 0xffff0000, v133
	v_fma_f32 v253, v253, v144, v202
	v_fma_f32 v254, v254, v144, v203
	v_cvt_pk_bf16_f32 v255, v253, v254
	v_lshlrev_b32_e32 v42, 16, v255
	v_and_b32_e32 v43, 0xffff0000, v255
	v_lshlrev_b32_e32 v253, 16, v134
	v_and_b32_e32 v254, 0xffff0000, v134
	v_fma_f32 v253, v253, v144, v204
	v_fma_f32 v254, v254, v144, v205
	v_cvt_pk_bf16_f32 v255, v253, v254
	v_lshlrev_b32_e32 v44, 16, v255
	v_and_b32_e32 v45, 0xffff0000, v255
	v_lshlrev_b32_e32 v253, 16, v135
	v_and_b32_e32 v254, 0xffff0000, v135
	v_fma_f32 v253, v253, v144, v206
	v_fma_f32 v254, v254, v144, v207
	v_cvt_pk_bf16_f32 v255, v253, v254
	v_lshlrev_b32_e32 v46, 16, v255
	v_and_b32_e32 v47, 0xffff0000, v255
	v_lshlrev_b32_e32 v253, 16, v136
	v_and_b32_e32 v254, 0xffff0000, v136
	v_fma_f32 v253, v253, v160, v192
	v_fma_f32 v254, v254, v160, v193
	v_cvt_pk_bf16_f32 v255, v253, v254
	v_lshlrev_b32_e32 v48, 16, v255
	v_and_b32_e32 v49, 0xffff0000, v255
	v_lshlrev_b32_e32 v253, 16, v137
	v_and_b32_e32 v254, 0xffff0000, v137
	v_fma_f32 v253, v253, v160, v194
	v_fma_f32 v254, v254, v160, v195
	v_cvt_pk_bf16_f32 v255, v253, v254
	v_lshlrev_b32_e32 v50, 16, v255
	v_and_b32_e32 v51, 0xffff0000, v255
	v_lshlrev_b32_e32 v253, 16, v138
	v_and_b32_e32 v254, 0xffff0000, v138
	v_fma_f32 v253, v253, v160, v196
	v_fma_f32 v254, v254, v160, v197
	v_cvt_pk_bf16_f32 v255, v253, v254
	v_lshlrev_b32_e32 v52, 16, v255
	v_and_b32_e32 v53, 0xffff0000, v255
	v_lshlrev_b32_e32 v253, 16, v139
	v_and_b32_e32 v254, 0xffff0000, v139
	v_fma_f32 v253, v253, v160, v198
	v_fma_f32 v254, v254, v160, v199
	v_cvt_pk_bf16_f32 v255, v253, v254
	v_lshlrev_b32_e32 v54, 16, v255
	v_and_b32_e32 v55, 0xffff0000, v255
	v_lshlrev_b32_e32 v253, 16, v140
	v_and_b32_e32 v254, 0xffff0000, v140
	v_fma_f32 v253, v253, v160, v200
	v_fma_f32 v254, v254, v160, v201
	v_cvt_pk_bf16_f32 v255, v253, v254
	v_lshlrev_b32_e32 v56, 16, v255
	v_and_b32_e32 v57, 0xffff0000, v255
	v_lshlrev_b32_e32 v253, 16, v141
	v_and_b32_e32 v254, 0xffff0000, v141
	v_fma_f32 v253, v253, v160, v202
	v_fma_f32 v254, v254, v160, v203
	v_cvt_pk_bf16_f32 v255, v253, v254
	v_lshlrev_b32_e32 v58, 16, v255
	v_and_b32_e32 v59, 0xffff0000, v255
	v_lshlrev_b32_e32 v253, 16, v142
	v_and_b32_e32 v254, 0xffff0000, v142
	v_fma_f32 v253, v253, v160, v204
	v_fma_f32 v254, v254, v160, v205
	v_cvt_pk_bf16_f32 v255, v253, v254
	v_lshlrev_b32_e32 v60, 16, v255
	v_and_b32_e32 v61, 0xffff0000, v255
	v_lshlrev_b32_e32 v253, 16, v143
	v_and_b32_e32 v254, 0xffff0000, v143
	v_fma_f32 v253, v253, v160, v206
	v_fma_f32 v254, v254, v160, v207
	v_cvt_pk_bf16_f32 v255, v253, v254
	v_lshlrev_b32_e32 v62, 16, v255
	v_and_b32_e32 v63, 0xffff0000, v255
	s_add_i32 s0, s77, 4
	s_lshl_b32 s1, s0, 11
	s_add_u32 s78, s12, s1
	s_addc_u32 s79, s13, 0
	global_load_dwordx4 v[128:131], v245, s[78:79]
	global_load_dwordx4 v[132:135], v245, s[78:79] offset:16
	global_load_dwordx4 v[136:139], v245, s[78:79] offset:2048
	global_load_dwordx4 v[140:143], v245, s[78:79] offset:2064
	s_lshl_b32 s1, s0, 6
	s_add_u32 s78, s14, s1
	s_addc_u32 s79, s15, 0
	global_load_dwordx4 v[144:147], v244, s[78:79] offset:0
	global_load_dwordx4 v[148:151], v244, s[78:79] offset:16
	global_load_dwordx4 v[152:155], v244, s[78:79] offset:32
	global_load_dwordx4 v[156:159], v244, s[78:79] offset:48
	global_load_dwordx4 v[160:163], v244, s[78:79] offset:64
	global_load_dwordx4 v[164:167], v244, s[78:79] offset:80
	global_load_dwordx4 v[168:171], v244, s[78:79] offset:96
	global_load_dwordx4 v[172:175], v244, s[78:79] offset:112
	s_waitcnt vmcnt(0)
	v_pk_add_f32 v[144:145], v[144:145], v[148:149]
	v_pk_add_f32 v[146:147], v[146:147], v[150:151]
	v_pk_add_f32 v[152:153], v[152:153], v[156:157]
	v_pk_add_f32 v[154:155], v[154:155], v[158:159]
	v_pk_add_f32 v[144:145], v[144:145], v[152:153]
	v_pk_add_f32 v[146:147], v[146:147], v[154:155]
	v_add_f32_e32 v144, v144, v145
	v_add_f32_e32 v146, v146, v147
	v_add_f32_e32 v144, v144, v146
	v_fmamk_f32 v144, v144, 0x3a800000, v243
	v_rsq_f32_e32 v144, v144
	v_pk_add_f32 v[160:161], v[160:161], v[164:165]
	v_pk_add_f32 v[162:163], v[162:163], v[166:167]
	v_pk_add_f32 v[168:169], v[168:169], v[172:173]
	v_pk_add_f32 v[170:171], v[170:171], v[174:175]
	v_pk_add_f32 v[160:161], v[160:161], v[168:169]
	v_pk_add_f32 v[162:163], v[162:163], v[170:171]
	v_add_f32_e32 v160, v160, v161
	v_add_f32_e32 v162, v162, v163
	v_add_f32_e32 v160, v160, v162
	v_fmamk_f32 v160, v160, 0x3a800000, v243
	v_rsq_f32_e32 v160, v160
	v_lshlrev_b32_e32 v253, 16, v128
	v_and_b32_e32 v254, 0xffff0000, v128
	v_fma_f32 v253, v253, v144, v192
	v_fma_f32 v254, v254, v144, v193
	v_cvt_pk_bf16_f32 v255, v253, v254
	v_lshlrev_b32_e32 v64, 16, v255
	v_and_b32_e32 v65, 0xffff0000, v255
	v_lshlrev_b32_e32 v253, 16, v129
	v_and_b32_e32 v254, 0xffff0000, v129
	v_fma_f32 v253, v253, v144, v194
	v_fma_f32 v254, v254, v144, v195
	v_cvt_pk_bf16_f32 v255, v253, v254
	v_lshlrev_b32_e32 v66, 16, v255
	v_and_b32_e32 v67, 0xffff0000, v255
	v_lshlrev_b32_e32 v253, 16, v130
	v_and_b32_e32 v254, 0xffff0000, v130
	v_fma_f32 v253, v253, v144, v196
; __device__ __forceinline__ unsigned pk2(float lo, float hi) { const f32x2 v = {lo, hi}; const bf16x2_t b = __builtin_convertvector(v, bf16x2_t); return __builtin_bit_cast(unsigned, b); }
; __device__ __forceinline__ float bflo(unsigned u) { return __uint_as_float(u << 16); }
; __device__ __forceinline__ float bfhi(unsigned u) { return __uint_as_float(u & 0xffff0000u); }
; __device__ __forceinline__ void peer_tile(const Args& A, LAS unsigned char* lds, int tile) {
;     ...
;         for (int tk = 0; tk < 4; ++tk) { const size_t m = (size_t)tile * 64 + tb + tk;
;             { const u32x4 ra = *(const u32x4*)(A3 + m * 1024 + 16 * lane), rb = *(const u32x4*)(A3 + m * 1024 + 16 * lane + 8);
;               float xr_; { const f32x4 p0 = *(const f32x4*)(RSq + m * 16), p1 = *(const f32x4*)(RSq + m * 16 + 4), p2 = *(const f32x4*)(RSq + m * 16 + 8), p3 = *(const f32x4*)(RSq + m * 16 + 12);
;                 const f32x4 ps = (p0 + p1) + (p2 + p3); xr_ = rsqrtf(((ps[0] + ps[1]) + (ps[2] + ps[3])) * (1.f / 1024.f) + 1e-6f); }
;               const unsigned rr[8] = {ra.x, ra.y, ra.z, ra.w, rb.x, rb.y, rb.z, rb.w}; unsigned hh[8];
;               const float* sp = MOD + (int)(m >> 11) * 6144 + 3072 + 16 * lane;
; #pragma unroll
;               for (int q = 0; q < 8; ++q) { const f32x2 sh = *(const f32x2*)(sp + 2 * q); hh[q] = pk2(bflo(rr[q]) * xr_ + sh[0], bfhi(rr[q]) * xr_ + sh[1]); }
;               xpa[tk] = (u32x4){hh[0], hh[1], hh[2], hh[3]}; xpb[tk] = (u32x4){hh[4], hh[5], hh[6], hh[7]}; }
;     ...
;                 { const unsigned xx[8] = {xpa[tk].x, xpa[tk].y, xpa[tk].z, xpa[tk].w, xpb[tk].x, xpb[tk].y, xpb[tk].z, xpb[tk].w};
; #pragma unroll
;                   for (int q = 0; q < 8; ++q) xf[q] = (f32x2){bflo(xx[q]), bfhi(xx[q])}; }
	v_fma_f32 v254, v254, v144, v197
	v_cvt_pk_bf16_f32 v255, v253, v254
	v_lshlrev_b32_e32 v68, 16, v255
	v_and_b32_e32 v69, 0xffff0000, v255
	v_lshlrev_b32_e32 v253, 16, v131
	v_and_b32_e32 v254, 0xffff0000, v131
	v_fma_f32 v253, v253, v144, v198
	v_fma_f32 v254, v254, v144, v199
	v_cvt_pk_bf16_f32 v255, v253, v254
	v_lshlrev_b32_e32 v70, 16, v255
	v_and_b32_e32 v71, 0xffff0000, v255
	v_lshlrev_b32_e32 v253, 16, v132
	v_and_b32_e32 v254, 0xffff0000, v132
	v_fma_f32 v253, v253, v144, v200
	v_fma_f32 v254, v254, v144, v201
	v_cvt_pk_bf16_f32 v255, v253, v254
	v_lshlrev_b32_e32 v72, 16, v255
	v_and_b32_e32 v73, 0xffff0000, v255
	v_lshlrev_b32_e32 v253, 16, v133
	v_and_b32_e32 v254, 0xffff0000, v133
	v_fma_f32 v253, v253, v144, v202
	v_fma_f32 v254, v254, v144, v203
	v_cvt_pk_bf16_f32 v255, v253, v254
	v_lshlrev_b32_e32 v74, 16, v255
	v_and_b32_e32 v75, 0xffff0000, v255
	v_lshlrev_b32_e32 v253, 16, v134
	v_and_b32_e32 v254, 0xffff0000, v134
	v_fma_f32 v253, v253, v144, v204
	v_fma_f32 v254, v254, v144, v205
	v_cvt_pk_bf16_f32 v255, v253, v254
	v_lshlrev_b32_e32 v76, 16, v255
	v_and_b32_e32 v77, 0xffff0000, v255
	v_lshlrev_b32_e32 v253, 16, v135
	v_and_b32_e32 v254, 0xffff0000, v135
	v_fma_f32 v253, v253, v144, v206
	v_fma_f32 v254, v254, v144, v207
	v_cvt_pk_bf16_f32 v255, v253, v254
	v_lshlrev_b32_e32 v78, 16, v255
	v_and_b32_e32 v79, 0xffff0000, v255
	v_lshlrev_b32_e32 v253, 16, v136
	v_and_b32_e32 v254, 0xffff0000, v136
	v_fma_f32 v253, v253, v160, v192
	v_fma_f32 v254, v254, v160, v193
	v_cvt_pk_bf16_f32 v255, v253, v254
	v_lshlrev_b32_e32 v80, 16, v255
	v_and_b32_e32 v81, 0xffff0000, v255
	v_lshlrev_b32_e32 v253, 16, v137
	v_and_b32_e32 v254, 0xffff0000, v137
	v_fma_f32 v253, v253, v160, v194
	v_fma_f32 v254, v254, v160, v195
	v_cvt_pk_bf16_f32 v255, v253, v254
	v_lshlrev_b32_e32 v82, 16, v255
	v_and_b32_e32 v83, 0xffff0000, v255
	v_lshlrev_b32_e32 v253, 16, v138
	v_and_b32_e32 v254, 0xffff0000, v138
	v_fma_f32 v253, v253, v160, v196
	v_fma_f32 v254, v254, v160, v197
	v_cvt_pk_bf16_f32 v255, v253, v254
	v_lshlrev_b32_e32 v84, 16, v255
	v_and_b32_e32 v85, 0xffff0000, v255
	v_lshlrev_b32_e32 v253, 16, v139
	v_and_b32_e32 v254, 0xffff0000, v139
	v_fma_f32 v253, v253, v160, v198
	v_fma_f32 v254, v254, v160, v199
	v_cvt_pk_bf16_f32 v255, v253, v254
	v_lshlrev_b32_e32 v86, 16, v255
	v_and_b32_e32 v87, 0xffff0000, v255
	v_lshlrev_b32_e32 v253, 16, v140
	v_and_b32_e32 v254, 0xffff0000, v140
	v_fma_f32 v253, v253, v160, v200
	v_fma_f32 v254, v254, v160, v201
	v_cvt_pk_bf16_f32 v255, v253, v254
	v_lshlrev_b32_e32 v88, 16, v255
	v_and_b32_e32 v89, 0xffff0000, v255
	v_lshlrev_b32_e32 v253, 16, v141
	v_and_b32_e32 v254, 0xffff0000, v141
	v_fma_f32 v253, v253, v160, v202
	v_fma_f32 v254, v254, v160, v203
	v_cvt_pk_bf16_f32 v255, v253, v254
	v_lshlrev_b32_e32 v90, 16, v255
	v_and_b32_e32 v91, 0xffff0000, v255
	v_lshlrev_b32_e32 v253, 16, v142
	v_and_b32_e32 v254, 0xffff0000, v142
	v_fma_f32 v253, v253, v160, v204
	v_fma_f32 v254, v254, v160, v205
	v_cvt_pk_bf16_f32 v255, v253, v254
	v_lshlrev_b32_e32 v92, 16, v255
	v_and_b32_e32 v93, 0xffff0000, v255
	v_lshlrev_b32_e32 v253, 16, v143
	v_and_b32_e32 v254, 0xffff0000, v143
	v_fma_f32 v253, v253, v160, v206
	v_fma_f32 v254, v254, v160, v207
	v_cvt_pk_bf16_f32 v255, v253, v254
	v_lshlrev_b32_e32 v94, 16, v255
	v_and_b32_e32 v95, 0xffff0000, v255
	s_add_i32 s0, s77, 6
	s_lshl_b32 s1, s0, 11
	s_add_u32 s78, s12, s1
	s_addc_u32 s79, s13, 0
	global_load_dwordx4 v[128:131], v245, s[78:79]
	global_load_dwordx4 v[132:135], v245, s[78:79] offset:16
	global_load_dwordx4 v[136:139], v245, s[78:79] offset:2048
	global_load_dwordx4 v[140:143], v245, s[78:79] offset:2064
	s_lshl_b32 s1, s0, 6
	s_add_u32 s78, s14, s1
	s_addc_u32 s79, s15, 0
	global_load_dwordx4 v[144:147], v244, s[78:79] offset:0
	global_load_dwordx4 v[148:151], v244, s[78:79] offset:16
	global_load_dwordx4 v[152:155], v244, s[78:79] offset:32
	global_load_dwordx4 v[156:159], v244, s[78:79] offset:48
	global_load_dwordx4 v[160:163], v244, s[78:79] offset:64
	global_load_dwordx4 v[164:167], v244, s[78:79] offset:80
	global_load_dwordx4 v[168:171], v244, s[78:79] offset:96
	global_load_dwordx4 v[172:175], v244, s[78:79] offset:112
	s_waitcnt vmcnt(0)
	v_pk_add_f32 v[144:145], v[144:145], v[148:149]
	v_pk_add_f32 v[146:147], v[146:147], v[150:151]
	v_pk_add_f32 v[152:153], v[152:153], v[156:157]
	v_pk_add_f32 v[154:155], v[154:155], v[158:159]
	v_pk_add_f32 v[144:145], v[144:145], v[152:153]
	v_pk_add_f32 v[146:147], v[146:147], v[154:155]
	v_add_f32_e32 v144, v144, v145
	v_add_f32_e32 v146, v146, v147
	v_add_f32_e32 v144, v144, v146
	v_fmamk_f32 v144, v144, 0x3a800000, v243
	v_rsq_f32_e32 v144, v144
	v_pk_add_f32 v[160:161], v[160:161], v[164:165]
	v_pk_add_f32 v[162:163], v[162:163], v[166:167]
	v_pk_add_f32 v[168:169], v[168:169], v[172:173]
	v_pk_add_f32 v[170:171], v[170:171], v[174:175]
	v_pk_add_f32 v[160:161], v[160:161], v[168:169]
	v_pk_add_f32 v[162:163], v[162:163], v[170:171]
	v_add_f32_e32 v160, v160, v161
	v_add_f32_e32 v162, v162, v163
	v_add_f32_e32 v160, v160, v162
	v_fmamk_f32 v160, v160, 0x3a800000, v243
	v_rsq_f32_e32 v160, v160
	v_lshlrev_b32_e32 v253, 16, v128
	v_and_b32_e32 v254, 0xffff0000, v128
	v_fma_f32 v253, v253, v144, v192
	v_fma_f32 v254, v254, v144, v193
	v_cvt_pk_bf16_f32 v255, v253, v254
	v_lshlrev_b32_e32 v96, 16, v255
	v_and_b32_e32 v97, 0xffff0000, v255
	v_lshlrev_b32_e32 v253, 16, v129
	v_and_b32_e32 v254, 0xffff0000, v129
	v_fma_f32 v253, v253, v144, v194
	v_fma_f32 v254, v254, v144, v195
	v_cvt_pk_bf16_f32 v255, v253, v254
	v_lshlrev_b32_e32 v98, 16, v255
	v_and_b32_e32 v99, 0xffff0000, v255
	v_lshlrev_b32_e32 v253, 16, v130
; __device__ __forceinline__ unsigned pk2(float lo, float hi) { const f32x2 v = {lo, hi}; const bf16x2_t b = __builtin_convertvector(v, bf16x2_t); return __builtin_bit_cast(unsigned, b); }
; __device__ __forceinline__ float bflo(unsigned u) { return __uint_as_float(u << 16); }
; __device__ __forceinline__ void peer_tile(const Args& A, LAS unsigned char* lds, int tile) {
;     ...
;     for (int ti = 0; ti < 8; ++ti) {
;         const int tl = 8 * w + ti;
;         const u32x2 e0 = SEL[tl * 128 + lane], e1 = SEL[tl * 128 + 64 + lane];
;         const int p0 = (int)(e0.x >> 10), p1 = (int)(e1.x >> 10);
;         int off = 0;
;         for (int p = 0; p < 16; ++p) {
;             const unsigned long long m0 = __ballot(p0 == p), m1 = __ballot(p1 == p);
;             const int c0 = __popcll(m0), c1 = __popcll(m1);
;             const int r0 = __builtin_amdgcn_mbcnt_hi((unsigned)(m0 >> 32), __builtin_amdgcn_mbcnt_lo((unsigned)m0, 0u));
;             const int r1 = __builtin_amdgcn_mbcnt_hi((unsigned)(m1 >> 32), __builtin_amdgcn_mbcnt_lo((unsigned)m1, 0u));
;             if (p0 == p) SORT[tl * 128 + off + r0] = e0;
;             if (p1 == p) SORT[tl * 128 + off + c0 + r1] = e1;
;             if (lane == 0) OFFS[tl * 17 + p] = off;
;             off += c0 + c1;
;         }
;         if (lane == 0) OFFS[tl * 17 + 16] = off;
;     }
;     ...
;         for (int tk = 0; tk < 4; ++tk) { const size_t m = (size_t)tile * 64 + tb + tk;
;             { const u32x4 ra = *(const u32x4*)(A3 + m * 1024 + 16 * lane), rb = *(const u32x4*)(A3 + m * 1024 + 16 * lane + 8);
;               float xr_; { const f32x4 p0 = *(const f32x4*)(RSq + m * 16), p1 = *(const f32x4*)(RSq + m * 16 + 4), p2 = *(const f32x4*)(RSq + m * 16 + 8), p3 = *(const f32x4*)(RSq + m * 16 + 12);
;                 const f32x4 ps = (p0 + p1) + (p2 + p3); xr_ = rsqrtf(((ps[0] + ps[1]) + (ps[2] + ps[3])) * (1.f / 1024.f) + 1e-6f); }
;               const unsigned rr[8] = {ra.x, ra.y, ra.z, ra.w, rb.x, rb.y, rb.z, rb.w}; unsigned hh[8];
;               const float* sp = MOD + (int)(m >> 11) * 6144 + 3072 + 16 * lane;
; #pragma unroll
;               for (int q = 0; q < 8; ++q) { const f32x2 sh = *(const f32x2*)(sp + 2 * q); hh[q] = pk2(bflo(rr[q]) * xr_ + sh[0], bfhi(rr[q]) * xr_ + sh[1]); }
;               xpa[tk] = (u32x4){hh[0], hh[1], hh[2], hh[3]}; xpb[tk] = (u32x4){hh[4], hh[5], hh[6], hh[7]}; }
	v_and_b32_e32 v254, 0xffff0000, v130
	v_fma_f32 v253, v253, v144, v196
	v_fma_f32 v254, v254, v144, v197
	v_cvt_pk_bf16_f32 v255, v253, v254
	v_lshlrev_b32_e32 v100, 16, v255
	v_and_b32_e32 v101, 0xffff0000, v255
	v_lshlrev_b32_e32 v253, 16, v131
	v_and_b32_e32 v254, 0xffff0000, v131
	v_fma_f32 v253, v253, v144, v198
	v_fma_f32 v254, v254, v144, v199
	v_cvt_pk_bf16_f32 v255, v253, v254
	v_lshlrev_b32_e32 v102, 16, v255
	v_and_b32_e32 v103, 0xffff0000, v255
	v_lshlrev_b32_e32 v253, 16, v132
	v_and_b32_e32 v254, 0xffff0000, v132
	v_fma_f32 v253, v253, v144, v200
	v_fma_f32 v254, v254, v144, v201
	v_cvt_pk_bf16_f32 v255, v253, v254
	v_lshlrev_b32_e32 v104, 16, v255
	v_and_b32_e32 v105, 0xffff0000, v255
	v_lshlrev_b32_e32 v253, 16, v133
	v_and_b32_e32 v254, 0xffff0000, v133
	v_fma_f32 v253, v253, v144, v202
	v_fma_f32 v254, v254, v144, v203
	v_cvt_pk_bf16_f32 v255, v253, v254
	v_lshlrev_b32_e32 v106, 16, v255
	v_and_b32_e32 v107, 0xffff0000, v255
	v_lshlrev_b32_e32 v253, 16, v134
	v_and_b32_e32 v254, 0xffff0000, v134
	v_fma_f32 v253, v253, v144, v204
	v_fma_f32 v254, v254, v144, v205
	v_cvt_pk_bf16_f32 v255, v253, v254
	v_lshlrev_b32_e32 v108, 16, v255
	v_and_b32_e32 v109, 0xffff0000, v255
	v_lshlrev_b32_e32 v253, 16, v135
	v_and_b32_e32 v254, 0xffff0000, v135
	v_fma_f32 v253, v253, v144, v206
	v_fma_f32 v254, v254, v144, v207
	v_cvt_pk_bf16_f32 v255, v253, v254
	v_lshlrev_b32_e32 v110, 16, v255
	v_and_b32_e32 v111, 0xffff0000, v255
	v_lshlrev_b32_e32 v253, 16, v136
	v_and_b32_e32 v254, 0xffff0000, v136
	v_fma_f32 v253, v253, v160, v192
	v_fma_f32 v254, v254, v160, v193
	v_cvt_pk_bf16_f32 v255, v253, v254
	v_lshlrev_b32_e32 v112, 16, v255
	v_and_b32_e32 v113, 0xffff0000, v255
	v_lshlrev_b32_e32 v253, 16, v137
	v_and_b32_e32 v254, 0xffff0000, v137
	v_fma_f32 v253, v253, v160, v194
	v_fma_f32 v254, v254, v160, v195
	v_cvt_pk_bf16_f32 v255, v253, v254
	v_lshlrev_b32_e32 v114, 16, v255
	v_and_b32_e32 v115, 0xffff0000, v255
	v_lshlrev_b32_e32 v253, 16, v138
	v_and_b32_e32 v254, 0xffff0000, v138
	v_fma_f32 v253, v253, v160, v196
	v_fma_f32 v254, v254, v160, v197
	v_cvt_pk_bf16_f32 v255, v253, v254
	v_lshlrev_b32_e32 v116, 16, v255
	v_and_b32_e32 v117, 0xffff0000, v255
	v_lshlrev_b32_e32 v253, 16, v139
	v_and_b32_e32 v254, 0xffff0000, v139
	v_fma_f32 v253, v253, v160, v198
	v_fma_f32 v254, v254, v160, v199
	v_cvt_pk_bf16_f32 v255, v253, v254
	v_lshlrev_b32_e32 v118, 16, v255
	v_and_b32_e32 v119, 0xffff0000, v255
	v_lshlrev_b32_e32 v253, 16, v140
	v_and_b32_e32 v254, 0xffff0000, v140
	v_fma_f32 v253, v253, v160, v200
	v_fma_f32 v254, v254, v160, v201
	v_cvt_pk_bf16_f32 v255, v253, v254
	v_lshlrev_b32_e32 v120, 16, v255
	v_and_b32_e32 v121, 0xffff0000, v255
	v_lshlrev_b32_e32 v253, 16, v141
	v_and_b32_e32 v254, 0xffff0000, v141
	v_fma_f32 v253, v253, v160, v202
	v_fma_f32 v254, v254, v160, v203
	v_cvt_pk_bf16_f32 v255, v253, v254
	v_lshlrev_b32_e32 v122, 16, v255
	v_and_b32_e32 v123, 0xffff0000, v255
	v_lshlrev_b32_e32 v253, 16, v142
	v_and_b32_e32 v254, 0xffff0000, v142
	v_fma_f32 v253, v253, v160, v204
	v_fma_f32 v254, v254, v160, v205
	v_cvt_pk_bf16_f32 v255, v253, v254
	v_lshlrev_b32_e32 v124, 16, v255
	v_and_b32_e32 v125, 0xffff0000, v255
	v_lshlrev_b32_e32 v253, 16, v143
	v_and_b32_e32 v254, 0xffff0000, v143
	v_fma_f32 v253, v253, v160, v206
	v_fma_f32 v254, v254, v160, v207
	v_cvt_pk_bf16_f32 v255, v253, v254
	v_lshlrev_b32_e32 v126, 16, v255
	v_and_b32_e32 v127, 0xffff0000, v255
	s_mov_b32 s89, 0
.LU_chunk:
	s_mov_b32 s90, 0
.LU_win:
	v_mov_b32_e32 v216, 0
	v_mov_b32_e32 v217, 0
	v_mov_b32_e32 v218, 0x11fe80
	v_mov_b32_e32 v219, 0
	v_add_u32_e32 v220, s22, v240
	ds_write_b128 v220, v[216:219] offset:0
	ds_write_b128 v220, v[216:219] offset:1024
	ds_write_b128 v220, v[216:219] offset:2048
	ds_write_b128 v220, v[216:219] offset:3072
	ds_write_b128 v220, v[216:219] offset:4096
	ds_write_b128 v220, v[216:219] offset:5120
	ds_write_b128 v220, v[216:219] offset:6144
	ds_write_b128 v220, v[216:219] offset:7168
	s_mov_b32 exec_hi, 0
	ds_write_b128 v220, v[216:219] offset:8192
	s_mov_b64 exec, -1
	s_lshl_b32 s0, s76, 10
	s_add_i32 s0, s0, 0x11000
	v_lshrrev_b32_e32 v221, 1, v240
	v_add_u32_e32 v221, s0, v221
	ds_read_b64 v[128:129], v221 offset:0
	ds_read_b64 v[132:133], v221 offset:512
	ds_read_b64 v[136:137], v221 offset:1024
	ds_read_b64 v[140:141], v221 offset:1536
	ds_read_b64 v[144:145], v221 offset:2048
	ds_read_b64 v[148:149], v221 offset:2560
	ds_read_b64 v[152:153], v221 offset:3072
	ds_read_b64 v[156:157], v221 offset:3584
	ds_read_b64 v[160:161], v221 offset:4096
	ds_read_b64 v[164:165], v221 offset:4608
	ds_read_b64 v[168:169], v221 offset:5120
	ds_read_b64 v[172:173], v221 offset:5632
	ds_read_b64 v[176:177], v221 offset:6144
	ds_read_b64 v[180:181], v221 offset:6656
	ds_read_b64 v[184:185], v221 offset:7168
	ds_read_b64 v[188:189], v221 offset:7680
	s_waitcnt lgkmcnt(0)
; __device__ __forceinline__ void peer_tile(const Args& A, LAS unsigned char* lds, int tile) {
;     ...
;     for (int ti = 0; ti < 8; ++ti) {
;         const int tl = 8 * w + ti;
;         const u32x2 e0 = SEL[tl * 128 + lane], e1 = SEL[tl * 128 + 64 + lane];
;         const int p0 = (int)(e0.x >> 10), p1 = (int)(e1.x >> 10);
;         int off = 0;
;         for (int p = 0; p < 16; ++p) {
;             const unsigned long long m0 = __ballot(p0 == p), m1 = __ballot(p1 == p);
;             const int c0 = __popcll(m0), c1 = __popcll(m1);
;             const int r0 = __builtin_amdgcn_mbcnt_hi((unsigned)(m0 >> 32), __builtin_amdgcn_mbcnt_lo((unsigned)m0, 0u));
;             const int r1 = __builtin_amdgcn_mbcnt_hi((unsigned)(m1 >> 32), __builtin_amdgcn_mbcnt_lo((unsigned)m1, 0u));
;             if (p0 == p) SORT[tl * 128 + off + r0] = e0;
;             if (p1 == p) SORT[tl * 128 + off + c0 + r1] = e1;
;             if (lane == 0) OFFS[tl * 17 + p] = off;
;             off += c0 + c1;
;         }
;         if (lane == 0) OFFS[tl * 17 + 16] = off;
;     }
	v_lshrrev_b32_e32 v192, 10, v128
	v_lshlrev_b32_e32 v128, 10, v128
	v_add_u32_e32 v130, 4, v221
	v_lshl_or_b32 v130, v130, 3, 0
	v_mov_b32_e32 v131, 0
	v_lshrrev_b32_e32 v193, 10, v132
	v_lshlrev_b32_e32 v132, 10, v132
	v_add_u32_e32 v134, 516, v221
	v_lshl_or_b32 v134, v134, 3, 0
	v_mov_b32_e32 v135, 0
	v_lshrrev_b32_e32 v194, 10, v136
	v_lshlrev_b32_e32 v136, 10, v136
	v_add_u32_e32 v138, 1028, v221
	v_lshl_or_b32 v138, v138, 3, 1
	v_mov_b32_e32 v139, 0
	v_lshrrev_b32_e32 v195, 10, v140
	v_lshlrev_b32_e32 v140, 10, v140
	v_add_u32_e32 v142, 1540, v221
	v_lshl_or_b32 v142, v142, 3, 1
	v_mov_b32_e32 v143, 0
	v_lshrrev_b32_e32 v196, 10, v144
	v_lshlrev_b32_e32 v144, 10, v144
	v_add_u32_e32 v146, 2052, v221
	v_lshl_or_b32 v146, v146, 3, 2
	v_mov_b32_e32 v147, 0
	v_lshrrev_b32_e32 v197, 10, v148
	v_lshlrev_b32_e32 v148, 10, v148
	v_add_u32_e32 v150, 2564, v221
	v_lshl_or_b32 v150, v150, 3, 2
	v_mov_b32_e32 v151, 0
	v_lshrrev_b32_e32 v198, 10, v152
	v_lshlrev_b32_e32 v152, 10, v152
	v_add_u32_e32 v154, 3076, v221
	v_lshl_or_b32 v154, v154, 3, 3
	v_mov_b32_e32 v155, 0
	v_lshrrev_b32_e32 v199, 10, v156
	v_lshlrev_b32_e32 v156, 10, v156
	v_add_u32_e32 v158, 3588, v221
	v_lshl_or_b32 v158, v158, 3, 3
	v_mov_b32_e32 v159, 0
	v_lshrrev_b32_e32 v200, 10, v160
	v_lshlrev_b32_e32 v160, 10, v160
	v_add_u32_e32 v162, 4100, v221
	v_lshl_or_b32 v162, v162, 3, 4
	v_mov_b32_e32 v163, 0
	v_lshrrev_b32_e32 v201, 10, v164
	v_lshlrev_b32_e32 v164, 10, v164
	v_add_u32_e32 v166, 4612, v221
	v_lshl_or_b32 v166, v166, 3, 4
	v_mov_b32_e32 v167, 0
	v_lshrrev_b32_e32 v202, 10, v168
	v_lshlrev_b32_e32 v168, 10, v168
	v_add_u32_e32 v170, 5124, v221
	v_lshl_or_b32 v170, v170, 3, 5
	v_mov_b32_e32 v171, 0
	v_lshrrev_b32_e32 v203, 10, v172
	v_lshlrev_b32_e32 v172, 10, v172
	v_add_u32_e32 v174, 5636, v221
	v_lshl_or_b32 v174, v174, 3, 5
	v_mov_b32_e32 v175, 0
	v_lshrrev_b32_e32 v204, 10, v176
	v_lshlrev_b32_e32 v176, 10, v176
	v_add_u32_e32 v178, 6148, v221
	v_lshl_or_b32 v178, v178, 3, 6
	v_mov_b32_e32 v179, 0
	v_lshrrev_b32_e32 v205, 10, v180
	v_lshlrev_b32_e32 v180, 10, v180
	v_add_u32_e32 v182, 6660, v221
	v_lshl_or_b32 v182, v182, 3, 6
	v_mov_b32_e32 v183, 0
	v_lshrrev_b32_e32 v206, 10, v184
	v_lshlrev_b32_e32 v184, 10, v184
	v_add_u32_e32 v186, 7172, v221
	v_lshl_or_b32 v186, v186, 3, 7
	v_mov_b32_e32 v187, 0
	v_lshrrev_b32_e32 v207, 10, v188
	v_lshlrev_b32_e32 v188, 10, v188
	v_add_u32_e32 v190, 7684, v221
	v_lshl_or_b32 v190, v190, 3, 7
	v_mov_b32_e32 v191, 0
	s_mul_i32 s74, s89, 4
	s_add_i32 s93, s74, 4
	s_mov_b32 s75, 0
	s_lshl_b32 s37, s90, 2
	s_mov_b32 s42, 512
.LU_bp:
	v_cmp_eq_u32_e64 s[68:69], s74, v192
	v_cmp_eq_u32_e64 s[70:71], s74, v193
	s_nop 0
	s_lshl_b32 s3, s75, 2
	s_sub_i32 s3, s3, s37
	s_bcnt1_i32_b64 s0, s[68:69]
	s_bcnt1_i32_b64 s1, s[70:71]
	v_mbcnt_lo_u32_b32 v222, s68, 0
	v_mbcnt_hi_u32_b32 v222, s69, v222
	v_mbcnt_lo_u32_b32 v223, s70, 0
	v_mbcnt_hi_u32_b32 v223, s71, v223
	v_add_u32_e32 v222, s3, v222
	v_add_u32_e32 v223, s0, v223
	v_add_u32_e32 v223, s3, v223
	v_cmp_gt_u32_e64 s[38:39], s42, v222
	v_cmp_gt_u32_e64 s[40:41], s42, v223
	v_lshl_add_u32 v222, v222, 4, s22
	v_lshl_add_u32 v223, v223, 4, s22
	s_and_b64 exec, s[68:69], s[38:39]
	ds_write_b128 v222, v[128:131]
	s_and_b64 exec, s[70:71], s[40:41]
	ds_write_b128 v223, v[132:135]
	s_mov_b64 exec, -1
	s_add_i32 s0, s0, s1
	s_add_i32 s0, s0, 3
	s_lshr_b32 s0, s0, 2
	s_add_i32 s75, s75, s0
	v_cmp_eq_u32_e64 s[68:69], s74, v194
	v_cmp_eq_u32_e64 s[70:71], s74, v195
	s_nop 0
	s_lshl_b32 s3, s75, 2
	s_sub_i32 s3, s3, s37
	s_bcnt1_i32_b64 s0, s[68:69]
	s_bcnt1_i32_b64 s1, s[70:71]
	v_mbcnt_lo_u32_b32 v222, s68, 0
	v_mbcnt_hi_u32_b32 v222, s69, v222
	v_mbcnt_lo_u32_b32 v223, s70, 0
	v_mbcnt_hi_u32_b32 v223, s71, v223
	v_add_u32_e32 v222, s3, v222
	v_add_u32_e32 v223, s0, v223
	v_add_u32_e32 v223, s3, v223
	v_cmp_gt_u32_e64 s[38:39], s42, v222
	v_cmp_gt_u32_e64 s[40:41], s42, v223
	v_lshl_add_u32 v222, v222, 4, s22
	v_lshl_add_u32 v223, v223, 4, s22
	s_and_b64 exec, s[68:69], s[38:39]
	ds_write_b128 v222, v[136:139]
	s_and_b64 exec, s[70:71], s[40:41]
	ds_write_b128 v223, v[140:143]
	s_mov_b64 exec, -1
	s_add_i32 s0, s0, s1
	s_add_i32 s0, s0, 3
	s_lshr_b32 s0, s0, 2
	s_add_i32 s75, s75, s0
	v_cmp_eq_u32_e64 s[68:69], s74, v196
	v_cmp_eq_u32_e64 s[70:71], s74, v197
	s_nop 0
	s_lshl_b32 s3, s75, 2
	s_sub_i32 s3, s3, s37
	s_bcnt1_i32_b64 s0, s[68:69]
	s_bcnt1_i32_b64 s1, s[70:71]
	v_mbcnt_lo_u32_b32 v222, s68, 0
	v_mbcnt_hi_u32_b32 v222, s69, v222
	v_mbcnt_lo_u32_b32 v223, s70, 0
	v_mbcnt_hi_u32_b32 v223, s71, v223
	v_add_u32_e32 v222, s3, v222
	v_add_u32_e32 v223, s0, v223
	v_add_u32_e32 v223, s3, v223
	v_cmp_gt_u32_e64 s[38:39], s42, v222
	v_cmp_gt_u32_e64 s[40:41], s42, v223
	v_lshl_add_u32 v222, v222, 4, s22
	v_lshl_add_u32 v223, v223, 4, s22
	s_and_b64 exec, s[68:69], s[38:39]
	ds_write_b128 v222, v[144:147]
	s_and_b64 exec, s[70:71], s[40:41]
	ds_write_b128 v223, v[148:151]
	s_mov_b64 exec, -1
	s_add_i32 s0, s0, s1
	s_add_i32 s0, s0, 3
	s_lshr_b32 s0, s0, 2
	s_add_i32 s75, s75, s0
	v_cmp_eq_u32_e64 s[68:69], s74, v198
	v_cmp_eq_u32_e64 s[70:71], s74, v199
	s_nop 0
	s_lshl_b32 s3, s75, 2
	s_sub_i32 s3, s3, s37
	s_bcnt1_i32_b64 s0, s[68:69]
	s_bcnt1_i32_b64 s1, s[70:71]
	v_mbcnt_lo_u32_b32 v222, s68, 0
	v_mbcnt_hi_u32_b32 v222, s69, v222
	v_mbcnt_lo_u32_b32 v223, s70, 0
	v_mbcnt_hi_u32_b32 v223, s71, v223
	v_add_u32_e32 v222, s3, v222
	v_add_u32_e32 v223, s0, v223
	v_add_u32_e32 v223, s3, v223
	v_cmp_gt_u32_e64 s[38:39], s42, v222
	v_cmp_gt_u32_e64 s[40:41], s42, v223
	v_lshl_add_u32 v222, v222, 4, s22
	v_lshl_add_u32 v223, v223, 4, s22
	s_and_b64 exec, s[68:69], s[38:39]
	ds_write_b128 v222, v[152:155]
; __device__ __forceinline__ void peer_tile(const Args& A, LAS unsigned char* lds, int tile) {
;     ...
;         for (int p = 0; p < 16; ++p) {
;             const unsigned long long m0 = __ballot(p0 == p), m1 = __ballot(p1 == p);
;             const int c0 = __popcll(m0), c1 = __popcll(m1);
;             const int r0 = __builtin_amdgcn_mbcnt_hi((unsigned)(m0 >> 32), __builtin_amdgcn_mbcnt_lo((unsigned)m0, 0u));
;             const int r1 = __builtin_amdgcn_mbcnt_hi((unsigned)(m1 >> 32), __builtin_amdgcn_mbcnt_lo((unsigned)m1, 0u));
;             if (p0 == p) SORT[tl * 128 + off + r0] = e0;
;             if (p1 == p) SORT[tl * 128 + off + c0 + r1] = e1;
;             if (lane == 0) OFFS[tl * 17 + p] = off;
;             off += c0 + c1;
;         }
;         if (lane == 0) OFFS[tl * 17 + 16] = off;
	s_and_b64 exec, s[70:71], s[40:41]
	ds_write_b128 v223, v[156:159]
	s_mov_b64 exec, -1
	s_add_i32 s0, s0, s1
	s_add_i32 s0, s0, 3
	s_lshr_b32 s0, s0, 2
	s_add_i32 s75, s75, s0
	v_cmp_eq_u32_e64 s[68:69], s74, v200
	v_cmp_eq_u32_e64 s[70:71], s74, v201
	s_nop 0
	s_lshl_b32 s3, s75, 2
	s_sub_i32 s3, s3, s37
	s_bcnt1_i32_b64 s0, s[68:69]
	s_bcnt1_i32_b64 s1, s[70:71]
	v_mbcnt_lo_u32_b32 v222, s68, 0
	v_mbcnt_hi_u32_b32 v222, s69, v222
	v_mbcnt_lo_u32_b32 v223, s70, 0
	v_mbcnt_hi_u32_b32 v223, s71, v223
	v_add_u32_e32 v222, s3, v222
	v_add_u32_e32 v223, s0, v223
	v_add_u32_e32 v223, s3, v223
	v_cmp_gt_u32_e64 s[38:39], s42, v222
	v_cmp_gt_u32_e64 s[40:41], s42, v223
	v_lshl_add_u32 v222, v222, 4, s22
	v_lshl_add_u32 v223, v223, 4, s22
	s_and_b64 exec, s[68:69], s[38:39]
	ds_write_b128 v222, v[160:163]
	s_and_b64 exec, s[70:71], s[40:41]
	ds_write_b128 v223, v[164:167]
	s_mov_b64 exec, -1
	s_add_i32 s0, s0, s1
	s_add_i32 s0, s0, 3
	s_lshr_b32 s0, s0, 2
	s_add_i32 s75, s75, s0
	v_cmp_eq_u32_e64 s[68:69], s74, v202
	v_cmp_eq_u32_e64 s[70:71], s74, v203
	s_nop 0
	s_lshl_b32 s3, s75, 2
	s_sub_i32 s3, s3, s37
	s_bcnt1_i32_b64 s0, s[68:69]
	s_bcnt1_i32_b64 s1, s[70:71]
	v_mbcnt_lo_u32_b32 v222, s68, 0
	v_mbcnt_hi_u32_b32 v222, s69, v222
	v_mbcnt_lo_u32_b32 v223, s70, 0
	v_mbcnt_hi_u32_b32 v223, s71, v223
	v_add_u32_e32 v222, s3, v222
	v_add_u32_e32 v223, s0, v223
	v_add_u32_e32 v223, s3, v223
	v_cmp_gt_u32_e64 s[38:39], s42, v222
	v_cmp_gt_u32_e64 s[40:41], s42, v223
	v_lshl_add_u32 v222, v222, 4, s22
	v_lshl_add_u32 v223, v223, 4, s22
	s_and_b64 exec, s[68:69], s[38:39]
	ds_write_b128 v222, v[168:171]
	s_and_b64 exec, s[70:71], s[40:41]
	ds_write_b128 v223, v[172:175]
	s_mov_b64 exec, -1
	s_add_i32 s0, s0, s1
	s_add_i32 s0, s0, 3
	s_lshr_b32 s0, s0, 2
	s_add_i32 s75, s75, s0
	v_cmp_eq_u32_e64 s[68:69], s74, v204
	v_cmp_eq_u32_e64 s[70:71], s74, v205
	s_nop 0
	s_lshl_b32 s3, s75, 2
	s_sub_i32 s3, s3, s37
	s_bcnt1_i32_b64 s0, s[68:69]
	s_bcnt1_i32_b64 s1, s[70:71]
	v_mbcnt_lo_u32_b32 v222, s68, 0
	v_mbcnt_hi_u32_b32 v222, s69, v222
	v_mbcnt_lo_u32_b32 v223, s70, 0
	v_mbcnt_hi_u32_b32 v223, s71, v223
	v_add_u32_e32 v222, s3, v222
	v_add_u32_e32 v223, s0, v223
	v_add_u32_e32 v223, s3, v223
	v_cmp_gt_u32_e64 s[38:39], s42, v222
	v_cmp_gt_u32_e64 s[40:41], s42, v223
	v_lshl_add_u32 v222, v222, 4, s22
	v_lshl_add_u32 v223, v223, 4, s22
	s_and_b64 exec, s[68:69], s[38:39]
	ds_write_b128 v222, v[176:179]
	s_and_b64 exec, s[70:71], s[40:41]
	ds_write_b128 v223, v[180:183]
	s_mov_b64 exec, -1
	s_add_i32 s0, s0, s1
	s_add_i32 s0, s0, 3
	s_lshr_b32 s0, s0, 2
	s_add_i32 s75, s75, s0
	v_cmp_eq_u32_e64 s[68:69], s74, v206
	v_cmp_eq_u32_e64 s[70:71], s74, v207
	s_nop 0
	s_lshl_b32 s3, s75, 2
	s_sub_i32 s3, s3, s37
	s_bcnt1_i32_b64 s0, s[68:69]
	s_bcnt1_i32_b64 s1, s[70:71]
	v_mbcnt_lo_u32_b32 v222, s68, 0
	v_mbcnt_hi_u32_b32 v222, s69, v222
	v_mbcnt_lo_u32_b32 v223, s70, 0
	v_mbcnt_hi_u32_b32 v223, s71, v223
	v_add_u32_e32 v222, s3, v222
	v_add_u32_e32 v223, s0, v223
	v_add_u32_e32 v223, s3, v223
	v_cmp_gt_u32_e64 s[38:39], s42, v222
	v_cmp_gt_u32_e64 s[40:41], s42, v223
	v_lshl_add_u32 v222, v222, 4, s22
	v_lshl_add_u32 v223, v223, 4, s22
	s_and_b64 exec, s[68:69], s[38:39]
	ds_write_b128 v222, v[184:187]
	s_and_b64 exec, s[70:71], s[40:41]
	ds_write_b128 v223, v[188:191]
	s_mov_b64 exec, -1
	s_add_i32 s0, s0, s1
	s_add_i32 s0, s0, 3
	s_lshr_b32 s0, s0, 2
	s_add_i32 s75, s75, s0
	s_add_i32 s74, s74, 1
	s_cmp_lt_u32 s74, s93
	s_cbranch_scc1 .LU_bp
	s_mov_b32 s91, s75
	s_sub_i32 s20, s91, s90
	s_min_u32 s20, s20, 128
	s_waitcnt vmcnt(0) lgkmcnt(0)
	v_add_u32_e32 v241, s22, v247
	ds_read_b128 v[232:235], v241 offset:0
	s_waitcnt lgkmcnt(0)
	v_readlane_b32 s64, v232, 0
	v_readlane_b32 s65, v232, 16
	v_readlane_b32 s66, v232, 32
	v_readlane_b32 s67, v232, 48
	v_lshrrev_b32_e32 v253, 8, v232
	s_add_u32 s24, s4, s64
	s_addc_u32 s25, s5, 0
	s_add_u32 s26, s4, s65
	s_addc_u32 s27, s5, 0
	s_add_u32 s28, s4, s66
	s_addc_u32 s29, s5, 0
	s_add_u32 s30, s4, s67
	s_addc_u32 s31, s5, 0
	global_load_dwordx4 v[128:131], v240, s[24:25]
	global_load_dwordx4 v[132:135], v240, s[26:27]
	global_load_dwordx4 v[136:139], v240, s[28:29]
	global_load_dwordx4 v[140:143], v240, s[30:31]
	global_load_dword v248, v253, s[8:9]
	global_load_dword v208, v253, s[52:53]
	ds_read_b128 v[232:235], v241 offset:64
	s_waitcnt lgkmcnt(0)
	v_readlane_b32 s64, v232, 0
	v_readlane_b32 s65, v232, 16
	v_readlane_b32 s66, v232, 32
	v_readlane_b32 s67, v232, 48
	v_lshrrev_b32_e32 v253, 8, v232
	s_add_u32 s24, s4, s64
	s_addc_u32 s25, s5, 0
	s_add_u32 s26, s4, s65
	s_addc_u32 s27, s5, 0
	s_add_u32 s28, s4, s66
	s_addc_u32 s29, s5, 0
	s_add_u32 s30, s4, s67
	s_addc_u32 s31, s5, 0
	global_load_dwordx4 v[144:147], v240, s[24:25]
	global_load_dwordx4 v[148:151], v240, s[26:27]
	global_load_dwordx4 v[152:155], v240, s[28:29]
	global_load_dwordx4 v[156:159], v240, s[30:31]
	global_load_dword v249, v253, s[8:9]
	global_load_dword v209, v253, s[52:53]
	ds_read_b128 v[232:235], v241 offset:128
	s_waitcnt lgkmcnt(0)
	v_readlane_b32 s64, v232, 0
	v_readlane_b32 s65, v232, 16
	v_readlane_b32 s66, v232, 32
	v_readlane_b32 s67, v232, 48
	v_lshrrev_b32_e32 v253, 8, v232
	s_add_u32 s24, s4, s64
	s_addc_u32 s25, s5, 0
	s_add_u32 s26, s4, s65
	s_addc_u32 s27, s5, 0
	s_add_u32 s28, s4, s66
	s_addc_u32 s29, s5, 0
	s_add_u32 s30, s4, s67
	s_addc_u32 s31, s5, 0
	global_load_dwordx4 v[160:163], v240, s[24:25]
	global_load_dwordx4 v[164:167], v240, s[26:27]
	global_load_dwordx4 v[168:171], v240, s[28:29]
	global_load_dwordx4 v[172:175], v240, s[30:31]
	global_load_dword v250, v253, s[8:9]
	global_load_dword v210, v253, s[52:53]
	ds_read_b128 v[232:235], v241 offset:192
	s_waitcnt lgkmcnt(0)
	v_readlane_b32 s64, v232, 0
	v_readlane_b32 s65, v232, 16
	v_readlane_b32 s66, v232, 32
	v_readlane_b32 s67, v232, 48
	v_lshrrev_b32_e32 v253, 8, v232
	s_add_u32 s24, s4, s64
	s_addc_u32 s25, s5, 0
	s_add_u32 s26, s4, s65
	s_addc_u32 s27, s5, 0
	s_add_u32 s28, s4, s66
	s_addc_u32 s29, s5, 0
	s_add_u32 s30, s4, s67
	s_addc_u32 s31, s5, 0
	global_load_dwordx4 v[176:179], v240, s[24:25]
	global_load_dwordx4 v[180:183], v240, s[26:27]
	global_load_dwordx4 v[184:187], v240, s[28:29]
	global_load_dwordx4 v[188:191], v240, s[30:31]
	global_load_dword v251, v253, s[8:9]
	global_load_dword v211, v253, s[52:53]
	ds_read_b128 v[236:239], v241 offset:0
	ds_read_b128 v[232:235], v241 offset:256
	s_mov_b32 s21, 0
.LU_s0:
	s_cmp_ge_u32 s21, s20
	s_cbranch_scc1 .LU_done
	s_waitcnt lgkmcnt(0)
	v_readlane_b32 s64, v232, 0
	v_readlane_b32 s65, v232, 16
	v_readlane_b32 s66, v232, 32
	v_readlane_b32 s67, v232, 48
	v_lshrrev_b32_e32 v253, 8, v232
	s_add_u32 s24, s4, s64
	s_addc_u32 s25, s5, 0
	s_add_u32 s26, s4, s65
	s_addc_u32 s27, s5, 0
	s_add_u32 s28, s4, s66
	s_addc_u32 s29, s5, 0
	s_add_u32 s30, s4, s67
	s_addc_u32 s31, s5, 0
	global_load_dwordx4 v[192:195], v240, s[24:25]
	global_load_dwordx4 v[196:199], v240, s[26:27]
	global_load_dwordx4 v[200:203], v240, s[28:29]
	global_load_dwordx4 v[204:207], v240, s[30:31]
	global_load_dword v252, v253, s[8:9]
	global_load_dword v212, v253, s[52:53]
	v_readfirstlane_b32 s23, v238
	s_and_b32 s23, s23, 7
	s_waitcnt vmcnt(24)
	s_cmp_ge_u32 s23, 4
	s_cbranch_scc1 .LU_s0_h
	s_cmp_ge_u32 s23, 2
	s_cbranch_scc1 .LU_s0_23
	s_cmp_eq_u32 s23, 0
	s_cbranch_scc1 .LU_s0_t0
	s_branch .LU_s0_t1
.LU_s0_23:
	s_cmp_eq_u32 s23, 2
	s_cbranch_scc1 .LU_s0_t2
	s_branch .LU_s0_t3
.LU_s0_h:
	s_cmp_ge_u32 s23, 6
	s_cbranch_scc1 .LU_s0_67
	s_cmp_eq_u32 s23, 4
	s_cbranch_scc1 .LU_s0_t4
	s_branch .LU_s0_t5
.LU_s0_67:
	s_cmp_eq_u32 s23, 6
	s_cbranch_scc1 .LU_s0_t6
	s_branch .LU_s0_t7
.LU_s0_t0:
	v_cvt_pk_f32_fp8_e32 v[224:225], v128
	v_cvt_pk_f32_fp8_e32 v[226:227], v132
	v_cvt_pk_f32_fp8_e32 v[228:229], v136
	v_cvt_pk_f32_fp8_e32 v[230:231], v140
	v_pk_mul_f32 v[216:217], v[224:225], v[0:1]
	v_pk_mul_f32 v[218:219], v[226:227], v[0:1]
	v_pk_mul_f32 v[220:221], v[228:229], v[0:1]
	v_pk_mul_f32 v[222:223], v[230:231], v[0:1]
	v_cvt_pk_f32_fp8_sdwa v[224:225], v128 src0_sel:WORD_1
	v_cvt_pk_f32_fp8_sdwa v[226:227], v132 src0_sel:WORD_1
	v_cvt_pk_f32_fp8_sdwa v[228:229], v136 src0_sel:WORD_1
	v_cvt_pk_f32_fp8_sdwa v[230:231], v140 src0_sel:WORD_1
	v_pk_fma_f32 v[216:217], v[224:225], v[2:3], v[216:217]
	v_pk_fma_f32 v[218:219], v[226:227], v[2:3], v[218:219]
	v_pk_fma_f32 v[220:221], v[228:229], v[2:3], v[220:221]
	v_pk_fma_f32 v[222:223], v[230:231], v[2:3], v[222:223]
	v_cvt_pk_f32_fp8_e32 v[224:225], v129
	v_cvt_pk_f32_fp8_e32 v[226:227], v133
	v_cvt_pk_f32_fp8_e32 v[228:229], v137
	v_cvt_pk_f32_fp8_e32 v[230:231], v141
	v_pk_fma_f32 v[216:217], v[224:225], v[4:5], v[216:217]
	v_pk_fma_f32 v[218:219], v[226:227], v[4:5], v[218:219]
	v_pk_fma_f32 v[220:221], v[228:229], v[4:5], v[220:221]
	v_pk_fma_f32 v[222:223], v[230:231], v[4:5], v[222:223]
	v_cvt_pk_f32_fp8_sdwa v[224:225], v129 src0_sel:WORD_1
	v_cvt_pk_f32_fp8_sdwa v[226:227], v133 src0_sel:WORD_1
	v_cvt_pk_f32_fp8_sdwa v[228:229], v137 src0_sel:WORD_1
	v_cvt_pk_f32_fp8_sdwa v[230:231], v141 src0_sel:WORD_1
	v_pk_fma_f32 v[216:217], v[224:225], v[6:7], v[216:217]
	v_pk_fma_f32 v[218:219], v[226:227], v[6:7], v[218:219]
	v_pk_fma_f32 v[220:221], v[228:229], v[6:7], v[220:221]
	v_pk_fma_f32 v[222:223], v[230:231], v[6:7], v[222:223]
	v_cvt_pk_f32_fp8_e32 v[224:225], v130
	v_cvt_pk_f32_fp8_e32 v[226:227], v134
	v_cvt_pk_f32_fp8_e32 v[228:229], v138
	v_cvt_pk_f32_fp8_e32 v[230:231], v142
	v_pk_fma_f32 v[216:217], v[224:225], v[8:9], v[216:217]
	v_pk_fma_f32 v[218:219], v[226:227], v[8:9], v[218:219]
	v_pk_fma_f32 v[220:221], v[228:229], v[8:9], v[220:221]
	v_pk_fma_f32 v[222:223], v[230:231], v[8:9], v[222:223]
	v_cvt_pk_f32_fp8_sdwa v[224:225], v130 src0_sel:WORD_1
	v_cvt_pk_f32_fp8_sdwa v[226:227], v134 src0_sel:WORD_1
	v_cvt_pk_f32_fp8_sdwa v[228:229], v138 src0_sel:WORD_1
	v_cvt_pk_f32_fp8_sdwa v[230:231], v142 src0_sel:WORD_1
	v_pk_fma_f32 v[216:217], v[224:225], v[10:11], v[216:217]
	v_pk_fma_f32 v[218:219], v[226:227], v[10:11], v[218:219]
	v_pk_fma_f32 v[220:221], v[228:229], v[10:11], v[220:221]
	v_pk_fma_f32 v[222:223], v[230:231], v[10:11], v[222:223]
	v_cvt_pk_f32_fp8_e32 v[224:225], v131
	v_cvt_pk_f32_fp8_e32 v[226:227], v135
	v_cvt_pk_f32_fp8_e32 v[228:229], v139
	v_cvt_pk_f32_fp8_e32 v[230:231], v143
	v_pk_fma_f32 v[216:217], v[224:225], v[12:13], v[216:217]
	v_pk_fma_f32 v[218:219], v[226:227], v[12:13], v[218:219]
	v_pk_fma_f32 v[220:221], v[228:229], v[12:13], v[220:221]
	v_pk_fma_f32 v[222:223], v[230:231], v[12:13], v[222:223]
	v_cvt_pk_f32_fp8_sdwa v[224:225], v131 src0_sel:WORD_1
	v_cvt_pk_f32_fp8_sdwa v[226:227], v135 src0_sel:WORD_1
	v_cvt_pk_f32_fp8_sdwa v[228:229], v139 src0_sel:WORD_1
	v_cvt_pk_f32_fp8_sdwa v[230:231], v143 src0_sel:WORD_1
	v_pk_fma_f32 v[216:217], v[224:225], v[14:15], v[216:217]
	v_pk_fma_f32 v[218:219], v[226:227], v[14:15], v[218:219]
	v_pk_fma_f32 v[220:221], v[228:229], v[14:15], v[220:221]
	v_pk_fma_f32 v[222:223], v[230:231], v[14:15], v[222:223]
	s_branch .LU_s0_tail
.LU_s0_t1:
	v_cvt_pk_f32_fp8_e32 v[224:225], v128
	v_cvt_pk_f32_fp8_e32 v[226:227], v132
	v_cvt_pk_f32_fp8_e32 v[228:229], v136
	v_cvt_pk_f32_fp8_e32 v[230:231], v140
	v_pk_mul_f32 v[216:217], v[224:225], v[16:17]
	v_pk_mul_f32 v[218:219], v[226:227], v[16:17]
	v_pk_mul_f32 v[220:221], v[228:229], v[16:17]
	v_pk_mul_f32 v[222:223], v[230:231], v[16:17]
	v_cvt_pk_f32_fp8_sdwa v[224:225], v128 src0_sel:WORD_1
	v_cvt_pk_f32_fp8_sdwa v[226:227], v132 src0_sel:WORD_1
	v_cvt_pk_f32_fp8_sdwa v[228:229], v136 src0_sel:WORD_1
	v_cvt_pk_f32_fp8_sdwa v[230:231], v140 src0_sel:WORD_1
	v_pk_fma_f32 v[216:217], v[224:225], v[18:19], v[216:217]
	v_pk_fma_f32 v[218:219], v[226:227], v[18:19], v[218:219]
	v_pk_fma_f32 v[220:221], v[228:229], v[18:19], v[220:221]
	v_pk_fma_f32 v[222:223], v[230:231], v[18:19], v[222:223]
	v_cvt_pk_f32_fp8_e32 v[224:225], v129
	v_cvt_pk_f32_fp8_e32 v[226:227], v133
	v_cvt_pk_f32_fp8_e32 v[228:229], v137
	v_cvt_pk_f32_fp8_e32 v[230:231], v141
	v_pk_fma_f32 v[216:217], v[224:225], v[20:21], v[216:217]
	v_pk_fma_f32 v[218:219], v[226:227], v[20:21], v[218:219]
	v_pk_fma_f32 v[220:221], v[228:229], v[20:21], v[220:221]
	v_pk_fma_f32 v[222:223], v[230:231], v[20:21], v[222:223]
	v_cvt_pk_f32_fp8_sdwa v[224:225], v129 src0_sel:WORD_1
	v_cvt_pk_f32_fp8_sdwa v[226:227], v133 src0_sel:WORD_1
	v_cvt_pk_f32_fp8_sdwa v[228:229], v137 src0_sel:WORD_1
	v_cvt_pk_f32_fp8_sdwa v[230:231], v141 src0_sel:WORD_1
	v_pk_fma_f32 v[216:217], v[224:225], v[22:23], v[216:217]
	v_pk_fma_f32 v[218:219], v[226:227], v[22:23], v[218:219]
	v_pk_fma_f32 v[220:221], v[228:229], v[22:23], v[220:221]
	v_pk_fma_f32 v[222:223], v[230:231], v[22:23], v[222:223]
	v_cvt_pk_f32_fp8_e32 v[224:225], v130
	v_cvt_pk_f32_fp8_e32 v[226:227], v134
	v_cvt_pk_f32_fp8_e32 v[228:229], v138
	v_cvt_pk_f32_fp8_e32 v[230:231], v142
	v_pk_fma_f32 v[216:217], v[224:225], v[24:25], v[216:217]
	v_pk_fma_f32 v[218:219], v[226:227], v[24:25], v[218:219]
	v_pk_fma_f32 v[220:221], v[228:229], v[24:25], v[220:221]
	v_pk_fma_f32 v[222:223], v[230:231], v[24:25], v[222:223]
	v_cvt_pk_f32_fp8_sdwa v[224:225], v130 src0_sel:WORD_1
	v_cvt_pk_f32_fp8_sdwa v[226:227], v134 src0_sel:WORD_1
	v_cvt_pk_f32_fp8_sdwa v[228:229], v138 src0_sel:WORD_1
	v_cvt_pk_f32_fp8_sdwa v[230:231], v142 src0_sel:WORD_1
	v_pk_fma_f32 v[216:217], v[224:225], v[26:27], v[216:217]
	v_pk_fma_f32 v[218:219], v[226:227], v[26:27], v[218:219]
	v_pk_fma_f32 v[220:221], v[228:229], v[26:27], v[220:221]
	v_pk_fma_f32 v[222:223], v[230:231], v[26:27], v[222:223]
	v_cvt_pk_f32_fp8_e32 v[224:225], v131
	v_cvt_pk_f32_fp8_e32 v[226:227], v135
	v_cvt_pk_f32_fp8_e32 v[228:229], v139
	v_cvt_pk_f32_fp8_e32 v[230:231], v143
	v_pk_fma_f32 v[216:217], v[224:225], v[28:29], v[216:217]
	v_pk_fma_f32 v[218:219], v[226:227], v[28:29], v[218:219]
	v_pk_fma_f32 v[220:221], v[228:229], v[28:29], v[220:221]
	v_pk_fma_f32 v[222:223], v[230:231], v[28:29], v[222:223]
	v_cvt_pk_f32_fp8_sdwa v[224:225], v131 src0_sel:WORD_1
	v_cvt_pk_f32_fp8_sdwa v[226:227], v135 src0_sel:WORD_1
	v_cvt_pk_f32_fp8_sdwa v[228:229], v139 src0_sel:WORD_1
	v_cvt_pk_f32_fp8_sdwa v[230:231], v143 src0_sel:WORD_1
	v_pk_fma_f32 v[216:217], v[224:225], v[30:31], v[216:217]
	v_pk_fma_f32 v[218:219], v[226:227], v[30:31], v[218:219]
	v_pk_fma_f32 v[220:221], v[228:229], v[30:31], v[220:221]
	v_pk_fma_f32 v[222:223], v[230:231], v[30:31], v[222:223]
	s_branch .LU_s0_tail
.LU_s0_t2:
	v_cvt_pk_f32_fp8_e32 v[224:225], v128
	v_cvt_pk_f32_fp8_e32 v[226:227], v132
	v_cvt_pk_f32_fp8_e32 v[228:229], v136
	v_cvt_pk_f32_fp8_e32 v[230:231], v140
	v_pk_mul_f32 v[216:217], v[224:225], v[32:33]
	v_pk_mul_f32 v[218:219], v[226:227], v[32:33]
	v_pk_mul_f32 v[220:221], v[228:229], v[32:33]
	v_pk_mul_f32 v[222:223], v[230:231], v[32:33]
	v_cvt_pk_f32_fp8_sdwa v[224:225], v128 src0_sel:WORD_1
	v_cvt_pk_f32_fp8_sdwa v[226:227], v132 src0_sel:WORD_1
	v_cvt_pk_f32_fp8_sdwa v[228:229], v136 src0_sel:WORD_1
	v_cvt_pk_f32_fp8_sdwa v[230:231], v140 src0_sel:WORD_1
	v_pk_fma_f32 v[216:217], v[224:225], v[34:35], v[216:217]
	v_pk_fma_f32 v[218:219], v[226:227], v[34:35], v[218:219]
	v_pk_fma_f32 v[220:221], v[228:229], v[34:35], v[220:221]
	v_pk_fma_f32 v[222:223], v[230:231], v[34:35], v[222:223]
	v_cvt_pk_f32_fp8_e32 v[224:225], v129
	v_cvt_pk_f32_fp8_e32 v[226:227], v133
	v_cvt_pk_f32_fp8_e32 v[228:229], v137
	v_cvt_pk_f32_fp8_e32 v[230:231], v141
	v_pk_fma_f32 v[216:217], v[224:225], v[36:37], v[216:217]
	v_pk_fma_f32 v[218:219], v[226:227], v[36:37], v[218:219]
	v_pk_fma_f32 v[220:221], v[228:229], v[36:37], v[220:221]
	v_pk_fma_f32 v[222:223], v[230:231], v[36:37], v[222:223]
	v_cvt_pk_f32_fp8_sdwa v[224:225], v129 src0_sel:WORD_1
	v_cvt_pk_f32_fp8_sdwa v[226:227], v133 src0_sel:WORD_1
	v_cvt_pk_f32_fp8_sdwa v[228:229], v137 src0_sel:WORD_1
	v_cvt_pk_f32_fp8_sdwa v[230:231], v141 src0_sel:WORD_1
	v_pk_fma_f32 v[216:217], v[224:225], v[38:39], v[216:217]
	v_pk_fma_f32 v[218:219], v[226:227], v[38:39], v[218:219]
	v_pk_fma_f32 v[220:221], v[228:229], v[38:39], v[220:221]
	v_pk_fma_f32 v[222:223], v[230:231], v[38:39], v[222:223]
	v_cvt_pk_f32_fp8_e32 v[224:225], v130
	v_cvt_pk_f32_fp8_e32 v[226:227], v134
	v_cvt_pk_f32_fp8_e32 v[228:229], v138
	v_cvt_pk_f32_fp8_e32 v[230:231], v142
	v_pk_fma_f32 v[216:217], v[224:225], v[40:41], v[216:217]
	v_pk_fma_f32 v[218:219], v[226:227], v[40:41], v[218:219]
	v_pk_fma_f32 v[220:221], v[228:229], v[40:41], v[220:221]
	v_pk_fma_f32 v[222:223], v[230:231], v[40:41], v[222:223]
	v_cvt_pk_f32_fp8_sdwa v[224:225], v130 src0_sel:WORD_1
	v_cvt_pk_f32_fp8_sdwa v[226:227], v134 src0_sel:WORD_1
	v_cvt_pk_f32_fp8_sdwa v[228:229], v138 src0_sel:WORD_1
	v_cvt_pk_f32_fp8_sdwa v[230:231], v142 src0_sel:WORD_1
	v_pk_fma_f32 v[216:217], v[224:225], v[42:43], v[216:217]
	v_pk_fma_f32 v[218:219], v[226:227], v[42:43], v[218:219]
	v_pk_fma_f32 v[220:221], v[228:229], v[42:43], v[220:221]
	v_pk_fma_f32 v[222:223], v[230:231], v[42:43], v[222:223]
	v_cvt_pk_f32_fp8_e32 v[224:225], v131
	v_cvt_pk_f32_fp8_e32 v[226:227], v135
	v_cvt_pk_f32_fp8_e32 v[228:229], v139
	v_cvt_pk_f32_fp8_e32 v[230:231], v143
	v_pk_fma_f32 v[216:217], v[224:225], v[44:45], v[216:217]
	v_pk_fma_f32 v[218:219], v[226:227], v[44:45], v[218:219]
	v_pk_fma_f32 v[220:221], v[228:229], v[44:45], v[220:221]
	v_pk_fma_f32 v[222:223], v[230:231], v[44:45], v[222:223]
	v_cvt_pk_f32_fp8_sdwa v[224:225], v131 src0_sel:WORD_1
	v_cvt_pk_f32_fp8_sdwa v[226:227], v135 src0_sel:WORD_1
	v_cvt_pk_f32_fp8_sdwa v[228:229], v139 src0_sel:WORD_1
	v_cvt_pk_f32_fp8_sdwa v[230:231], v143 src0_sel:WORD_1
	v_pk_fma_f32 v[216:217], v[224:225], v[46:47], v[216:217]
	v_pk_fma_f32 v[218:219], v[226:227], v[46:47], v[218:219]
	v_pk_fma_f32 v[220:221], v[228:229], v[46:47], v[220:221]
	v_pk_fma_f32 v[222:223], v[230:231], v[46:47], v[222:223]
	s_branch .LU_s0_tail
.LU_s0_t3:
	v_cvt_pk_f32_fp8_e32 v[224:225], v128
	v_cvt_pk_f32_fp8_e32 v[226:227], v132
	v_cvt_pk_f32_fp8_e32 v[228:229], v136
	v_cvt_pk_f32_fp8_e32 v[230:231], v140
	v_pk_mul_f32 v[216:217], v[224:225], v[48:49]
	v_pk_mul_f32 v[218:219], v[226:227], v[48:49]
	v_pk_mul_f32 v[220:221], v[228:229], v[48:49]
	v_pk_mul_f32 v[222:223], v[230:231], v[48:49]
	v_cvt_pk_f32_fp8_sdwa v[224:225], v128 src0_sel:WORD_1
	v_cvt_pk_f32_fp8_sdwa v[226:227], v132 src0_sel:WORD_1
	v_cvt_pk_f32_fp8_sdwa v[228:229], v136 src0_sel:WORD_1
	v_cvt_pk_f32_fp8_sdwa v[230:231], v140 src0_sel:WORD_1
	v_pk_fma_f32 v[216:217], v[224:225], v[50:51], v[216:217]
	v_pk_fma_f32 v[218:219], v[226:227], v[50:51], v[218:219]
	v_pk_fma_f32 v[220:221], v[228:229], v[50:51], v[220:221]
	v_pk_fma_f32 v[222:223], v[230:231], v[50:51], v[222:223]
	v_cvt_pk_f32_fp8_e32 v[224:225], v129
	v_cvt_pk_f32_fp8_e32 v[226:227], v133
	v_cvt_pk_f32_fp8_e32 v[228:229], v137
	v_cvt_pk_f32_fp8_e32 v[230:231], v141
	v_pk_fma_f32 v[216:217], v[224:225], v[52:53], v[216:217]
	v_pk_fma_f32 v[218:219], v[226:227], v[52:53], v[218:219]
	v_pk_fma_f32 v[220:221], v[228:229], v[52:53], v[220:221]
	v_pk_fma_f32 v[222:223], v[230:231], v[52:53], v[222:223]
	v_cvt_pk_f32_fp8_sdwa v[224:225], v129 src0_sel:WORD_1
	v_cvt_pk_f32_fp8_sdwa v[226:227], v133 src0_sel:WORD_1
	v_cvt_pk_f32_fp8_sdwa v[228:229], v137 src0_sel:WORD_1
	v_cvt_pk_f32_fp8_sdwa v[230:231], v141 src0_sel:WORD_1
	v_pk_fma_f32 v[216:217], v[224:225], v[54:55], v[216:217]
	v_pk_fma_f32 v[218:219], v[226:227], v[54:55], v[218:219]
	v_pk_fma_f32 v[220:221], v[228:229], v[54:55], v[220:221]
	v_pk_fma_f32 v[222:223], v[230:231], v[54:55], v[222:223]
	v_cvt_pk_f32_fp8_e32 v[224:225], v130
	v_cvt_pk_f32_fp8_e32 v[226:227], v134
	v_cvt_pk_f32_fp8_e32 v[228:229], v138
	v_cvt_pk_f32_fp8_e32 v[230:231], v142
	v_pk_fma_f32 v[216:217], v[224:225], v[56:57], v[216:217]
	v_pk_fma_f32 v[218:219], v[226:227], v[56:57], v[218:219]
	v_pk_fma_f32 v[220:221], v[228:229], v[56:57], v[220:221]
	v_pk_fma_f32 v[222:223], v[230:231], v[56:57], v[222:223]
	v_cvt_pk_f32_fp8_sdwa v[224:225], v130 src0_sel:WORD_1
	v_cvt_pk_f32_fp8_sdwa v[226:227], v134 src0_sel:WORD_1
	v_cvt_pk_f32_fp8_sdwa v[228:229], v138 src0_sel:WORD_1
	v_cvt_pk_f32_fp8_sdwa v[230:231], v142 src0_sel:WORD_1
	v_pk_fma_f32 v[216:217], v[224:225], v[58:59], v[216:217]
	v_pk_fma_f32 v[218:219], v[226:227], v[58:59], v[218:219]
	v_pk_fma_f32 v[220:221], v[228:229], v[58:59], v[220:221]
	v_pk_fma_f32 v[222:223], v[230:231], v[58:59], v[222:223]
	v_cvt_pk_f32_fp8_e32 v[224:225], v131
	v_cvt_pk_f32_fp8_e32 v[226:227], v135
	v_cvt_pk_f32_fp8_e32 v[228:229], v139
	v_cvt_pk_f32_fp8_e32 v[230:231], v143
	v_pk_fma_f32 v[216:217], v[224:225], v[60:61], v[216:217]
	v_pk_fma_f32 v[218:219], v[226:227], v[60:61], v[218:219]
	v_pk_fma_f32 v[220:221], v[228:229], v[60:61], v[220:221]
	v_pk_fma_f32 v[222:223], v[230:231], v[60:61], v[222:223]
	v_cvt_pk_f32_fp8_sdwa v[224:225], v131 src0_sel:WORD_1
	v_cvt_pk_f32_fp8_sdwa v[226:227], v135 src0_sel:WORD_1
	v_cvt_pk_f32_fp8_sdwa v[228:229], v139 src0_sel:WORD_1
	v_cvt_pk_f32_fp8_sdwa v[230:231], v143 src0_sel:WORD_1
	v_pk_fma_f32 v[216:217], v[224:225], v[62:63], v[216:217]
	v_pk_fma_f32 v[218:219], v[226:227], v[62:63], v[218:219]
	v_pk_fma_f32 v[220:221], v[228:229], v[62:63], v[220:221]
	v_pk_fma_f32 v[222:223], v[230:231], v[62:63], v[222:223]
	s_branch .LU_s0_tail
.LU_s0_t4:
	v_cvt_pk_f32_fp8_e32 v[224:225], v128
	v_cvt_pk_f32_fp8_e32 v[226:227], v132
	v_cvt_pk_f32_fp8_e32 v[228:229], v136
	v_cvt_pk_f32_fp8_e32 v[230:231], v140
	v_pk_mul_f32 v[216:217], v[224:225], v[64:65]
	v_pk_mul_f32 v[218:219], v[226:227], v[64:65]
	v_pk_mul_f32 v[220:221], v[228:229], v[64:65]
	v_pk_mul_f32 v[222:223], v[230:231], v[64:65]
	v_cvt_pk_f32_fp8_sdwa v[224:225], v128 src0_sel:WORD_1
	v_cvt_pk_f32_fp8_sdwa v[226:227], v132 src0_sel:WORD_1
	v_cvt_pk_f32_fp8_sdwa v[228:229], v136 src0_sel:WORD_1
	v_cvt_pk_f32_fp8_sdwa v[230:231], v140 src0_sel:WORD_1
	v_pk_fma_f32 v[216:217], v[224:225], v[66:67], v[216:217]
	v_pk_fma_f32 v[218:219], v[226:227], v[66:67], v[218:219]
	v_pk_fma_f32 v[220:221], v[228:229], v[66:67], v[220:221]
	v_pk_fma_f32 v[222:223], v[230:231], v[66:67], v[222:223]
	v_cvt_pk_f32_fp8_e32 v[224:225], v129
	v_cvt_pk_f32_fp8_e32 v[226:227], v133
	v_cvt_pk_f32_fp8_e32 v[228:229], v137
	v_cvt_pk_f32_fp8_e32 v[230:231], v141
	v_pk_fma_f32 v[216:217], v[224:225], v[68:69], v[216:217]
	v_pk_fma_f32 v[218:219], v[226:227], v[68:69], v[218:219]
	v_pk_fma_f32 v[220:221], v[228:229], v[68:69], v[220:221]
	v_pk_fma_f32 v[222:223], v[230:231], v[68:69], v[222:223]
	v_cvt_pk_f32_fp8_sdwa v[224:225], v129 src0_sel:WORD_1
	v_cvt_pk_f32_fp8_sdwa v[226:227], v133 src0_sel:WORD_1
	v_cvt_pk_f32_fp8_sdwa v[228:229], v137 src0_sel:WORD_1
	v_cvt_pk_f32_fp8_sdwa v[230:231], v141 src0_sel:WORD_1
	v_pk_fma_f32 v[216:217], v[224:225], v[70:71], v[216:217]
	v_pk_fma_f32 v[218:219], v[226:227], v[70:71], v[218:219]
	v_pk_fma_f32 v[220:221], v[228:229], v[70:71], v[220:221]
	v_pk_fma_f32 v[222:223], v[230:231], v[70:71], v[222:223]
	v_cvt_pk_f32_fp8_e32 v[224:225], v130
	v_cvt_pk_f32_fp8_e32 v[226:227], v134
	v_cvt_pk_f32_fp8_e32 v[228:229], v138
	v_cvt_pk_f32_fp8_e32 v[230:231], v142
	v_pk_fma_f32 v[216:217], v[224:225], v[72:73], v[216:217]
	v_pk_fma_f32 v[218:219], v[226:227], v[72:73], v[218:219]
	v_pk_fma_f32 v[220:221], v[228:229], v[72:73], v[220:221]
	v_pk_fma_f32 v[222:223], v[230:231], v[72:73], v[222:223]
	v_cvt_pk_f32_fp8_sdwa v[224:225], v130 src0_sel:WORD_1
	v_cvt_pk_f32_fp8_sdwa v[226:227], v134 src0_sel:WORD_1
	v_cvt_pk_f32_fp8_sdwa v[228:229], v138 src0_sel:WORD_1
	v_cvt_pk_f32_fp8_sdwa v[230:231], v142 src0_sel:WORD_1
	v_pk_fma_f32 v[216:217], v[224:225], v[74:75], v[216:217]
	v_pk_fma_f32 v[218:219], v[226:227], v[74:75], v[218:219]
	v_pk_fma_f32 v[220:221], v[228:229], v[74:75], v[220:221]
	v_pk_fma_f32 v[222:223], v[230:231], v[74:75], v[222:223]
	v_cvt_pk_f32_fp8_e32 v[224:225], v131
	v_cvt_pk_f32_fp8_e32 v[226:227], v135
	v_cvt_pk_f32_fp8_e32 v[228:229], v139
	v_cvt_pk_f32_fp8_e32 v[230:231], v143
	v_pk_fma_f32 v[216:217], v[224:225], v[76:77], v[216:217]
	v_pk_fma_f32 v[218:219], v[226:227], v[76:77], v[218:219]
	v_pk_fma_f32 v[220:221], v[228:229], v[76:77], v[220:221]
	v_pk_fma_f32 v[222:223], v[230:231], v[76:77], v[222:223]
	v_cvt_pk_f32_fp8_sdwa v[224:225], v131 src0_sel:WORD_1
	v_cvt_pk_f32_fp8_sdwa v[226:227], v135 src0_sel:WORD_1
	v_cvt_pk_f32_fp8_sdwa v[228:229], v139 src0_sel:WORD_1
	v_cvt_pk_f32_fp8_sdwa v[230:231], v143 src0_sel:WORD_1
	v_pk_fma_f32 v[216:217], v[224:225], v[78:79], v[216:217]
	v_pk_fma_f32 v[218:219], v[226:227], v[78:79], v[218:219]
	v_pk_fma_f32 v[220:221], v[228:229], v[78:79], v[220:221]
	v_pk_fma_f32 v[222:223], v[230:231], v[78:79], v[222:223]
	s_branch .LU_s0_tail
.LU_s0_t5:
	v_cvt_pk_f32_fp8_e32 v[224:225], v128
	v_cvt_pk_f32_fp8_e32 v[226:227], v132
	v_cvt_pk_f32_fp8_e32 v[228:229], v136
	v_cvt_pk_f32_fp8_e32 v[230:231], v140
	v_pk_mul_f32 v[216:217], v[224:225], v[80:81]
	v_pk_mul_f32 v[218:219], v[226:227], v[80:81]
	v_pk_mul_f32 v[220:221], v[228:229], v[80:81]
	v_pk_mul_f32 v[222:223], v[230:231], v[80:81]
	v_cvt_pk_f32_fp8_sdwa v[224:225], v128 src0_sel:WORD_1
	v_cvt_pk_f32_fp8_sdwa v[226:227], v132 src0_sel:WORD_1
	v_cvt_pk_f32_fp8_sdwa v[228:229], v136 src0_sel:WORD_1
	v_cvt_pk_f32_fp8_sdwa v[230:231], v140 src0_sel:WORD_1
	v_pk_fma_f32 v[216:217], v[224:225], v[82:83], v[216:217]
	v_pk_fma_f32 v[218:219], v[226:227], v[82:83], v[218:219]
	v_pk_fma_f32 v[220:221], v[228:229], v[82:83], v[220:221]
	v_pk_fma_f32 v[222:223], v[230:231], v[82:83], v[222:223]
	v_cvt_pk_f32_fp8_e32 v[224:225], v129
	v_cvt_pk_f32_fp8_e32 v[226:227], v133
	v_cvt_pk_f32_fp8_e32 v[228:229], v137
	v_cvt_pk_f32_fp8_e32 v[230:231], v141
	v_pk_fma_f32 v[216:217], v[224:225], v[84:85], v[216:217]
	v_pk_fma_f32 v[218:219], v[226:227], v[84:85], v[218:219]
	v_pk_fma_f32 v[220:221], v[228:229], v[84:85], v[220:221]
	v_pk_fma_f32 v[222:223], v[230:231], v[84:85], v[222:223]
	v_cvt_pk_f32_fp8_sdwa v[224:225], v129 src0_sel:WORD_1
	v_cvt_pk_f32_fp8_sdwa v[226:227], v133 src0_sel:WORD_1
	v_cvt_pk_f32_fp8_sdwa v[228:229], v137 src0_sel:WORD_1
	v_cvt_pk_f32_fp8_sdwa v[230:231], v141 src0_sel:WORD_1
	v_pk_fma_f32 v[216:217], v[224:225], v[86:87], v[216:217]
	v_pk_fma_f32 v[218:219], v[226:227], v[86:87], v[218:219]
	v_pk_fma_f32 v[220:221], v[228:229], v[86:87], v[220:221]
	v_pk_fma_f32 v[222:223], v[230:231], v[86:87], v[222:223]
	v_cvt_pk_f32_fp8_e32 v[224:225], v130
	v_cvt_pk_f32_fp8_e32 v[226:227], v134
	v_cvt_pk_f32_fp8_e32 v[228:229], v138
	v_cvt_pk_f32_fp8_e32 v[230:231], v142
	v_pk_fma_f32 v[216:217], v[224:225], v[88:89], v[216:217]
	v_pk_fma_f32 v[218:219], v[226:227], v[88:89], v[218:219]
	v_pk_fma_f32 v[220:221], v[228:229], v[88:89], v[220:221]
	v_pk_fma_f32 v[222:223], v[230:231], v[88:89], v[222:223]
	v_cvt_pk_f32_fp8_sdwa v[224:225], v130 src0_sel:WORD_1
	v_cvt_pk_f32_fp8_sdwa v[226:227], v134 src0_sel:WORD_1
	v_cvt_pk_f32_fp8_sdwa v[228:229], v138 src0_sel:WORD_1
	v_cvt_pk_f32_fp8_sdwa v[230:231], v142 src0_sel:WORD_1
	v_pk_fma_f32 v[216:217], v[224:225], v[90:91], v[216:217]
	v_pk_fma_f32 v[218:219], v[226:227], v[90:91], v[218:219]
	v_pk_fma_f32 v[220:221], v[228:229], v[90:91], v[220:221]
	v_pk_fma_f32 v[222:223], v[230:231], v[90:91], v[222:223]
	v_cvt_pk_f32_fp8_e32 v[224:225], v131
	v_cvt_pk_f32_fp8_e32 v[226:227], v135
	v_cvt_pk_f32_fp8_e32 v[228:229], v139
	v_cvt_pk_f32_fp8_e32 v[230:231], v143
	v_pk_fma_f32 v[216:217], v[224:225], v[92:93], v[216:217]
	v_pk_fma_f32 v[218:219], v[226:227], v[92:93], v[218:219]
	v_pk_fma_f32 v[220:221], v[228:229], v[92:93], v[220:221]
	v_pk_fma_f32 v[222:223], v[230:231], v[92:93], v[222:223]
	v_cvt_pk_f32_fp8_sdwa v[224:225], v131 src0_sel:WORD_1
	v_cvt_pk_f32_fp8_sdwa v[226:227], v135 src0_sel:WORD_1
	v_cvt_pk_f32_fp8_sdwa v[228:229], v139 src0_sel:WORD_1
	v_cvt_pk_f32_fp8_sdwa v[230:231], v143 src0_sel:WORD_1
	v_pk_fma_f32 v[216:217], v[224:225], v[94:95], v[216:217]
	v_pk_fma_f32 v[218:219], v[226:227], v[94:95], v[218:219]
	v_pk_fma_f32 v[220:221], v[228:229], v[94:95], v[220:221]
	v_pk_fma_f32 v[222:223], v[230:231], v[94:95], v[222:223]
	s_branch .LU_s0_tail
.LU_s0_t6:
	v_cvt_pk_f32_fp8_e32 v[224:225], v128
	v_cvt_pk_f32_fp8_e32 v[226:227], v132
	v_cvt_pk_f32_fp8_e32 v[228:229], v136
	v_cvt_pk_f32_fp8_e32 v[230:231], v140
	v_pk_mul_f32 v[216:217], v[224:225], v[96:97]
	v_pk_mul_f32 v[218:219], v[226:227], v[96:97]
	v_pk_mul_f32 v[220:221], v[228:229], v[96:97]
	v_pk_mul_f32 v[222:223], v[230:231], v[96:97]
	v_cvt_pk_f32_fp8_sdwa v[224:225], v128 src0_sel:WORD_1
	v_cvt_pk_f32_fp8_sdwa v[226:227], v132 src0_sel:WORD_1
	v_cvt_pk_f32_fp8_sdwa v[228:229], v136 src0_sel:WORD_1
	v_cvt_pk_f32_fp8_sdwa v[230:231], v140 src0_sel:WORD_1
	v_pk_fma_f32 v[216:217], v[224:225], v[98:99], v[216:217]
	v_pk_fma_f32 v[218:219], v[226:227], v[98:99], v[218:219]
	v_pk_fma_f32 v[220:221], v[228:229], v[98:99], v[220:221]
	v_pk_fma_f32 v[222:223], v[230:231], v[98:99], v[222:223]
	v_cvt_pk_f32_fp8_e32 v[224:225], v129
	v_cvt_pk_f32_fp8_e32 v[226:227], v133
	v_cvt_pk_f32_fp8_e32 v[228:229], v137
	v_cvt_pk_f32_fp8_e32 v[230:231], v141
	v_pk_fma_f32 v[216:217], v[224:225], v[100:101], v[216:217]
	v_pk_fma_f32 v[218:219], v[226:227], v[100:101], v[218:219]
	v_pk_fma_f32 v[220:221], v[228:229], v[100:101], v[220:221]
	v_pk_fma_f32 v[222:223], v[230:231], v[100:101], v[222:223]
	v_cvt_pk_f32_fp8_sdwa v[224:225], v129 src0_sel:WORD_1
	v_cvt_pk_f32_fp8_sdwa v[226:227], v133 src0_sel:WORD_1
	v_cvt_pk_f32_fp8_sdwa v[228:229], v137 src0_sel:WORD_1
	v_cvt_pk_f32_fp8_sdwa v[230:231], v141 src0_sel:WORD_1
	v_pk_fma_f32 v[216:217], v[224:225], v[102:103], v[216:217]
	v_pk_fma_f32 v[218:219], v[226:227], v[102:103], v[218:219]
	v_pk_fma_f32 v[220:221], v[228:229], v[102:103], v[220:221]
	v_pk_fma_f32 v[222:223], v[230:231], v[102:103], v[222:223]
	v_cvt_pk_f32_fp8_e32 v[224:225], v130
	v_cvt_pk_f32_fp8_e32 v[226:227], v134
	v_cvt_pk_f32_fp8_e32 v[228:229], v138
	v_cvt_pk_f32_fp8_e32 v[230:231], v142
	v_pk_fma_f32 v[216:217], v[224:225], v[104:105], v[216:217]
	v_pk_fma_f32 v[218:219], v[226:227], v[104:105], v[218:219]
	v_pk_fma_f32 v[220:221], v[228:229], v[104:105], v[220:221]
	v_pk_fma_f32 v[222:223], v[230:231], v[104:105], v[222:223]
	v_cvt_pk_f32_fp8_sdwa v[224:225], v130 src0_sel:WORD_1
	v_cvt_pk_f32_fp8_sdwa v[226:227], v134 src0_sel:WORD_1
	v_cvt_pk_f32_fp8_sdwa v[228:229], v138 src0_sel:WORD_1
	v_cvt_pk_f32_fp8_sdwa v[230:231], v142 src0_sel:WORD_1
	v_pk_fma_f32 v[216:217], v[224:225], v[106:107], v[216:217]
	v_pk_fma_f32 v[218:219], v[226:227], v[106:107], v[218:219]
	v_pk_fma_f32 v[220:221], v[228:229], v[106:107], v[220:221]
	v_pk_fma_f32 v[222:223], v[230:231], v[106:107], v[222:223]
	v_cvt_pk_f32_fp8_e32 v[224:225], v131
	v_cvt_pk_f32_fp8_e32 v[226:227], v135
	v_cvt_pk_f32_fp8_e32 v[228:229], v139
	v_cvt_pk_f32_fp8_e32 v[230:231], v143
	v_pk_fma_f32 v[216:217], v[224:225], v[108:109], v[216:217]
	v_pk_fma_f32 v[218:219], v[226:227], v[108:109], v[218:219]
	v_pk_fma_f32 v[220:221], v[228:229], v[108:109], v[220:221]
	v_pk_fma_f32 v[222:223], v[230:231], v[108:109], v[222:223]
	v_cvt_pk_f32_fp8_sdwa v[224:225], v131 src0_sel:WORD_1
	v_cvt_pk_f32_fp8_sdwa v[226:227], v135 src0_sel:WORD_1
	v_cvt_pk_f32_fp8_sdwa v[228:229], v139 src0_sel:WORD_1
	v_cvt_pk_f32_fp8_sdwa v[230:231], v143 src0_sel:WORD_1
	v_pk_fma_f32 v[216:217], v[224:225], v[110:111], v[216:217]
	v_pk_fma_f32 v[218:219], v[226:227], v[110:111], v[218:219]
	v_pk_fma_f32 v[220:221], v[228:229], v[110:111], v[220:221]
	v_pk_fma_f32 v[222:223], v[230:231], v[110:111], v[222:223]
	s_branch .LU_s0_tail
.LU_s0_t7:
	v_cvt_pk_f32_fp8_e32 v[224:225], v128
	v_cvt_pk_f32_fp8_e32 v[226:227], v132
	v_cvt_pk_f32_fp8_e32 v[228:229], v136
	v_cvt_pk_f32_fp8_e32 v[230:231], v140
	v_pk_mul_f32 v[216:217], v[224:225], v[112:113]
	v_pk_mul_f32 v[218:219], v[226:227], v[112:113]
	v_pk_mul_f32 v[220:221], v[228:229], v[112:113]
	v_pk_mul_f32 v[222:223], v[230:231], v[112:113]
	v_cvt_pk_f32_fp8_sdwa v[224:225], v128 src0_sel:WORD_1
	v_cvt_pk_f32_fp8_sdwa v[226:227], v132 src0_sel:WORD_1
	v_cvt_pk_f32_fp8_sdwa v[228:229], v136 src0_sel:WORD_1
	v_cvt_pk_f32_fp8_sdwa v[230:231], v140 src0_sel:WORD_1
	v_pk_fma_f32 v[216:217], v[224:225], v[114:115], v[216:217]
	v_pk_fma_f32 v[218:219], v[226:227], v[114:115], v[218:219]
	v_pk_fma_f32 v[220:221], v[228:229], v[114:115], v[220:221]
	v_pk_fma_f32 v[222:223], v[230:231], v[114:115], v[222:223]
	v_cvt_pk_f32_fp8_e32 v[224:225], v129
	v_cvt_pk_f32_fp8_e32 v[226:227], v133
	v_cvt_pk_f32_fp8_e32 v[228:229], v137
	v_cvt_pk_f32_fp8_e32 v[230:231], v141
	v_pk_fma_f32 v[216:217], v[224:225], v[116:117], v[216:217]
	v_pk_fma_f32 v[218:219], v[226:227], v[116:117], v[218:219]
	v_pk_fma_f32 v[220:221], v[228:229], v[116:117], v[220:221]
	v_pk_fma_f32 v[222:223], v[230:231], v[116:117], v[222:223]
	v_cvt_pk_f32_fp8_sdwa v[224:225], v129 src0_sel:WORD_1
	v_cvt_pk_f32_fp8_sdwa v[226:227], v133 src0_sel:WORD_1
	v_cvt_pk_f32_fp8_sdwa v[228:229], v137 src0_sel:WORD_1
	v_cvt_pk_f32_fp8_sdwa v[230:231], v141 src0_sel:WORD_1
	v_pk_fma_f32 v[216:217], v[224:225], v[118:119], v[216:217]
	v_pk_fma_f32 v[218:219], v[226:227], v[118:119], v[218:219]
	v_pk_fma_f32 v[220:221], v[228:229], v[118:119], v[220:221]
	v_pk_fma_f32 v[222:223], v[230:231], v[118:119], v[222:223]
	v_cvt_pk_f32_fp8_e32 v[224:225], v130
	v_cvt_pk_f32_fp8_e32 v[226:227], v134
	v_cvt_pk_f32_fp8_e32 v[228:229], v138
	v_cvt_pk_f32_fp8_e32 v[230:231], v142
	v_pk_fma_f32 v[216:217], v[224:225], v[120:121], v[216:217]
	v_pk_fma_f32 v[218:219], v[226:227], v[120:121], v[218:219]
	v_pk_fma_f32 v[220:221], v[228:229], v[120:121], v[220:221]
	v_pk_fma_f32 v[222:223], v[230:231], v[120:121], v[222:223]
	v_cvt_pk_f32_fp8_sdwa v[224:225], v130 src0_sel:WORD_1
	v_cvt_pk_f32_fp8_sdwa v[226:227], v134 src0_sel:WORD_1
	v_cvt_pk_f32_fp8_sdwa v[228:229], v138 src0_sel:WORD_1
	v_cvt_pk_f32_fp8_sdwa v[230:231], v142 src0_sel:WORD_1
	v_pk_fma_f32 v[216:217], v[224:225], v[122:123], v[216:217]
	v_pk_fma_f32 v[218:219], v[226:227], v[122:123], v[218:219]
	v_pk_fma_f32 v[220:221], v[228:229], v[122:123], v[220:221]
	v_pk_fma_f32 v[222:223], v[230:231], v[122:123], v[222:223]
	v_cvt_pk_f32_fp8_e32 v[224:225], v131
	v_cvt_pk_f32_fp8_e32 v[226:227], v135
	v_cvt_pk_f32_fp8_e32 v[228:229], v139
	v_cvt_pk_f32_fp8_e32 v[230:231], v143
	v_pk_fma_f32 v[216:217], v[224:225], v[124:125], v[216:217]
	v_pk_fma_f32 v[218:219], v[226:227], v[124:125], v[218:219]
	v_pk_fma_f32 v[220:221], v[228:229], v[124:125], v[220:221]
	v_pk_fma_f32 v[222:223], v[230:231], v[124:125], v[222:223]
	v_cvt_pk_f32_fp8_sdwa v[224:225], v131 src0_sel:WORD_1
	v_cvt_pk_f32_fp8_sdwa v[226:227], v135 src0_sel:WORD_1
	v_cvt_pk_f32_fp8_sdwa v[228:229], v139 src0_sel:WORD_1
	v_cvt_pk_f32_fp8_sdwa v[230:231], v143 src0_sel:WORD_1
	v_pk_fma_f32 v[216:217], v[224:225], v[126:127], v[216:217]
	v_pk_fma_f32 v[218:219], v[226:227], v[126:127], v[218:219]
	v_pk_fma_f32 v[220:221], v[228:229], v[126:127], v[220:221]
	v_pk_fma_f32 v[222:223], v[230:231], v[126:127], v[222:223]
.LU_s0_tail:
	v_add_f32_e32 v216, v216, v217
	v_add_f32_e32 v220, v220, v221
	v_add_f32_e32 v218, v218, v219
	v_add_f32_e32 v222, v222, v223
	s_nop 0
	v_permlane32_swap_b32_e32 v216, v220
	s_nop 0
	v_permlane32_swap_b32_e32 v218, v222
	v_add_f32_e32 v216, v216, v220
	v_add_f32_e32 v218, v218, v222
	s_nop 1
	v_permlane16_swap_b32_e32 v216, v218
	v_add_f32_e32 v216, v216, v218
	s_nop 1
	v_add_f32_dpp v216, v216, v216 quad_perm:[1,0,3,2] row_mask:0xf bank_mask:0xf bound_ctrl:1
	s_nop 1
	v_add_f32_dpp v216, v216, v216 quad_perm:[2,3,0,1] row_mask:0xf bank_mask:0xf bound_ctrl:1
	s_nop 1
	v_add_f32_dpp v216, v216, v216 row_half_mirror row_mask:0xf bank_mask:0xf bound_ctrl:1
	s_nop 1
	v_add_f32_dpp v216, v216, v216 row_mirror row_mask:0xf bank_mask:0xf bound_ctrl:1
	v_mul_f32_e32 v217, v248, v216
	v_fma_f32 v218, |v217|, s72, 1.0
	v_mul_f32_e32 v219, v217, v217
	v_rcp_f32_e32 v218, v218
	v_mul_f32_e32 v219, 0xbf38aa3b, v219
	v_exp_f32_e32 v219, v219
	v_fmamk_f32 v220, v218, 0x3f07dc22, v242
	v_fmaak_f32 v220, v218, v220, 0x3f35f0e3
	v_fmaak_f32 v220, v218, v220, 0xbe11a98e
	v_fmaak_f32 v220, v218, v220, 0x3e027906
	v_mul_f32_e32 v220, v218, v220
	v_mul_f32_e32 v220, v219, v220
	v_mul_f32_e32 v221, v217, v220
	v_fma_f32 v220, -v217, v220, v217
	v_cmp_gt_f32_e32 vcc, 0, v217
	v_lshrrev_b32_e32 v254, 3, v238
	s_nop 0
	v_cndmask_b32_e32 v220, v220, v221, vcc
	v_mul_f32_e32 v220, v237, v220
	v_mul_f32_e32 v220, v208, v220
	ds_write_b32 v254, v220
	ds_read_b128 v[236:239], v241 offset:64
	ds_read_b128 v[232:235], v241 offset:320
	s_add_i32 s21, s21, 1
.LU_s1:
	s_cmp_ge_u32 s21, s20
	s_cbranch_scc1 .LU_done
	s_waitcnt lgkmcnt(0)
	v_readlane_b32 s64, v232, 0
	v_readlane_b32 s65, v232, 16
	v_readlane_b32 s66, v232, 32
	v_readlane_b32 s67, v232, 48
	v_lshrrev_b32_e32 v253, 8, v232
	s_add_u32 s24, s4, s64
	s_addc_u32 s25, s5, 0
	s_add_u32 s26, s4, s65
	s_addc_u32 s27, s5, 0
	s_add_u32 s28, s4, s66
	s_addc_u32 s29, s5, 0
	s_add_u32 s30, s4, s67
	s_addc_u32 s31, s5, 0
	global_load_dwordx4 v[128:131], v240, s[24:25]
	global_load_dwordx4 v[132:135], v240, s[26:27]
	global_load_dwordx4 v[136:139], v240, s[28:29]
	global_load_dwordx4 v[140:143], v240, s[30:31]
	global_load_dword v248, v253, s[8:9]
	global_load_dword v208, v253, s[52:53]
	v_readfirstlane_b32 s23, v238
	s_and_b32 s23, s23, 7
	s_waitcnt vmcnt(24)
	s_cmp_ge_u32 s23, 4
	s_cbranch_scc1 .LU_s1_h
	s_cmp_ge_u32 s23, 2
	s_cbranch_scc1 .LU_s1_23
	s_cmp_eq_u32 s23, 0
	s_cbranch_scc1 .LU_s1_t0
	s_branch .LU_s1_t1

.LU_s1_t0:
	v_cvt_pk_f32_fp8_e32 v[224:225], v144
	v_cvt_pk_f32_fp8_e32 v[226:227], v148
	v_cvt_pk_f32_fp8_e32 v[228:229], v152
	v_cvt_pk_f32_fp8_e32 v[230:231], v156
	v_pk_mul_f32 v[216:217], v[224:225], v[0:1]
	v_pk_mul_f32 v[218:219], v[226:227], v[0:1]
	v_pk_mul_f32 v[220:221], v[228:229], v[0:1]
	v_pk_mul_f32 v[222:223], v[230:231], v[0:1]
	v_cvt_pk_f32_fp8_sdwa v[224:225], v144 src0_sel:WORD_1
	v_cvt_pk_f32_fp8_sdwa v[226:227], v148 src0_sel:WORD_1
	v_cvt_pk_f32_fp8_sdwa v[228:229], v152 src0_sel:WORD_1
	v_cvt_pk_f32_fp8_sdwa v[230:231], v156 src0_sel:WORD_1
	v_pk_fma_f32 v[216:217], v[224:225], v[2:3], v[216:217]
	v_pk_fma_f32 v[218:219], v[226:227], v[2:3], v[218:219]
	v_pk_fma_f32 v[220:221], v[228:229], v[2:3], v[220:221]
	v_pk_fma_f32 v[222:223], v[230:231], v[2:3], v[222:223]
	v_cvt_pk_f32_fp8_e32 v[224:225], v145
	v_cvt_pk_f32_fp8_e32 v[226:227], v149
	v_cvt_pk_f32_fp8_e32 v[228:229], v153
	v_cvt_pk_f32_fp8_e32 v[230:231], v157
	v_pk_fma_f32 v[216:217], v[224:225], v[4:5], v[216:217]
	v_pk_fma_f32 v[218:219], v[226:227], v[4:5], v[218:219]
	v_pk_fma_f32 v[220:221], v[228:229], v[4:5], v[220:221]
	v_pk_fma_f32 v[222:223], v[230:231], v[4:5], v[222:223]
	v_cvt_pk_f32_fp8_sdwa v[224:225], v145 src0_sel:WORD_1
	v_cvt_pk_f32_fp8_sdwa v[226:227], v149 src0_sel:WORD_1
	v_cvt_pk_f32_fp8_sdwa v[228:229], v153 src0_sel:WORD_1
	v_cvt_pk_f32_fp8_sdwa v[230:231], v157 src0_sel:WORD_1
	v_pk_fma_f32 v[216:217], v[224:225], v[6:7], v[216:217]
	v_pk_fma_f32 v[218:219], v[226:227], v[6:7], v[218:219]
	v_pk_fma_f32 v[220:221], v[228:229], v[6:7], v[220:221]
	v_pk_fma_f32 v[222:223], v[230:231], v[6:7], v[222:223]
	v_cvt_pk_f32_fp8_e32 v[224:225], v146
	v_cvt_pk_f32_fp8_e32 v[226:227], v150
	v_cvt_pk_f32_fp8_e32 v[228:229], v154
	v_cvt_pk_f32_fp8_e32 v[230:231], v158
	v_pk_fma_f32 v[216:217], v[224:225], v[8:9], v[216:217]
	v_pk_fma_f32 v[218:219], v[226:227], v[8:9], v[218:219]
	v_pk_fma_f32 v[220:221], v[228:229], v[8:9], v[220:221]
	v_pk_fma_f32 v[222:223], v[230:231], v[8:9], v[222:223]
	v_cvt_pk_f32_fp8_sdwa v[224:225], v146 src0_sel:WORD_1
	v_cvt_pk_f32_fp8_sdwa v[226:227], v150 src0_sel:WORD_1
	v_cvt_pk_f32_fp8_sdwa v[228:229], v154 src0_sel:WORD_1
	v_cvt_pk_f32_fp8_sdwa v[230:231], v158 src0_sel:WORD_1
	v_pk_fma_f32 v[216:217], v[224:225], v[10:11], v[216:217]
	v_pk_fma_f32 v[218:219], v[226:227], v[10:11], v[218:219]
	v_pk_fma_f32 v[220:221], v[228:229], v[10:11], v[220:221]
	v_pk_fma_f32 v[222:223], v[230:231], v[10:11], v[222:223]
	v_cvt_pk_f32_fp8_e32 v[224:225], v147
	v_cvt_pk_f32_fp8_e32 v[226:227], v151
	v_cvt_pk_f32_fp8_e32 v[228:229], v155
	v_cvt_pk_f32_fp8_e32 v[230:231], v159
	v_pk_fma_f32 v[216:217], v[224:225], v[12:13], v[216:217]
	v_pk_fma_f32 v[218:219], v[226:227], v[12:13], v[218:219]
	v_pk_fma_f32 v[220:221], v[228:229], v[12:13], v[220:221]
	v_pk_fma_f32 v[222:223], v[230:231], v[12:13], v[222:223]
	v_cvt_pk_f32_fp8_sdwa v[224:225], v147 src0_sel:WORD_1
	v_cvt_pk_f32_fp8_sdwa v[226:227], v151 src0_sel:WORD_1
	v_cvt_pk_f32_fp8_sdwa v[228:229], v155 src0_sel:WORD_1
	v_cvt_pk_f32_fp8_sdwa v[230:231], v159 src0_sel:WORD_1
	v_pk_fma_f32 v[216:217], v[224:225], v[14:15], v[216:217]
	v_pk_fma_f32 v[218:219], v[226:227], v[14:15], v[218:219]
	v_pk_fma_f32 v[220:221], v[228:229], v[14:15], v[220:221]
	v_pk_fma_f32 v[222:223], v[230:231], v[14:15], v[222:223]
	s_branch .LU_s1_tail
.LU_s1_t1:
	v_cvt_pk_f32_fp8_e32 v[224:225], v144
	v_cvt_pk_f32_fp8_e32 v[226:227], v148
	v_cvt_pk_f32_fp8_e32 v[228:229], v152
	v_cvt_pk_f32_fp8_e32 v[230:231], v156
	v_pk_mul_f32 v[216:217], v[224:225], v[16:17]
	v_pk_mul_f32 v[218:219], v[226:227], v[16:17]
	v_pk_mul_f32 v[220:221], v[228:229], v[16:17]
	v_pk_mul_f32 v[222:223], v[230:231], v[16:17]
	v_cvt_pk_f32_fp8_sdwa v[224:225], v144 src0_sel:WORD_1
	v_cvt_pk_f32_fp8_sdwa v[226:227], v148 src0_sel:WORD_1
	v_cvt_pk_f32_fp8_sdwa v[228:229], v152 src0_sel:WORD_1
	v_cvt_pk_f32_fp8_sdwa v[230:231], v156 src0_sel:WORD_1
	v_pk_fma_f32 v[216:217], v[224:225], v[18:19], v[216:217]
	v_pk_fma_f32 v[218:219], v[226:227], v[18:19], v[218:219]
	v_pk_fma_f32 v[220:221], v[228:229], v[18:19], v[220:221]
	v_pk_fma_f32 v[222:223], v[230:231], v[18:19], v[222:223]
	v_cvt_pk_f32_fp8_e32 v[224:225], v145
	v_cvt_pk_f32_fp8_e32 v[226:227], v149
	v_cvt_pk_f32_fp8_e32 v[228:229], v153
	v_cvt_pk_f32_fp8_e32 v[230:231], v157
	v_pk_fma_f32 v[216:217], v[224:225], v[20:21], v[216:217]
	v_pk_fma_f32 v[218:219], v[226:227], v[20:21], v[218:219]
	v_pk_fma_f32 v[220:221], v[228:229], v[20:21], v[220:221]
	v_pk_fma_f32 v[222:223], v[230:231], v[20:21], v[222:223]
	v_cvt_pk_f32_fp8_sdwa v[224:225], v145 src0_sel:WORD_1
	v_cvt_pk_f32_fp8_sdwa v[226:227], v149 src0_sel:WORD_1
	v_cvt_pk_f32_fp8_sdwa v[228:229], v153 src0_sel:WORD_1
	v_cvt_pk_f32_fp8_sdwa v[230:231], v157 src0_sel:WORD_1
	v_pk_fma_f32 v[216:217], v[224:225], v[22:23], v[216:217]
	v_pk_fma_f32 v[218:219], v[226:227], v[22:23], v[218:219]
	v_pk_fma_f32 v[220:221], v[228:229], v[22:23], v[220:221]
	v_pk_fma_f32 v[222:223], v[230:231], v[22:23], v[222:223]
	v_cvt_pk_f32_fp8_e32 v[224:225], v146
	v_cvt_pk_f32_fp8_e32 v[226:227], v150
	v_cvt_pk_f32_fp8_e32 v[228:229], v154
	v_cvt_pk_f32_fp8_e32 v[230:231], v158
	v_pk_fma_f32 v[216:217], v[224:225], v[24:25], v[216:217]
	v_pk_fma_f32 v[218:219], v[226:227], v[24:25], v[218:219]
	v_pk_fma_f32 v[220:221], v[228:229], v[24:25], v[220:221]
	v_pk_fma_f32 v[222:223], v[230:231], v[24:25], v[222:223]
	v_cvt_pk_f32_fp8_sdwa v[224:225], v146 src0_sel:WORD_1
	v_cvt_pk_f32_fp8_sdwa v[226:227], v150 src0_sel:WORD_1
	v_cvt_pk_f32_fp8_sdwa v[228:229], v154 src0_sel:WORD_1
	v_cvt_pk_f32_fp8_sdwa v[230:231], v158 src0_sel:WORD_1
	v_pk_fma_f32 v[216:217], v[224:225], v[26:27], v[216:217]
	v_pk_fma_f32 v[218:219], v[226:227], v[26:27], v[218:219]
	v_pk_fma_f32 v[220:221], v[228:229], v[26:27], v[220:221]
	v_pk_fma_f32 v[222:223], v[230:231], v[26:27], v[222:223]
	v_cvt_pk_f32_fp8_e32 v[224:225], v147
	v_cvt_pk_f32_fp8_e32 v[226:227], v151
	v_cvt_pk_f32_fp8_e32 v[228:229], v155
	v_cvt_pk_f32_fp8_e32 v[230:231], v159
	v_pk_fma_f32 v[216:217], v[224:225], v[28:29], v[216:217]
	v_pk_fma_f32 v[218:219], v[226:227], v[28:29], v[218:219]
	v_pk_fma_f32 v[220:221], v[228:229], v[28:29], v[220:221]
	v_pk_fma_f32 v[222:223], v[230:231], v[28:29], v[222:223]
	v_cvt_pk_f32_fp8_sdwa v[224:225], v147 src0_sel:WORD_1
	v_cvt_pk_f32_fp8_sdwa v[226:227], v151 src0_sel:WORD_1
	v_cvt_pk_f32_fp8_sdwa v[228:229], v155 src0_sel:WORD_1
	v_cvt_pk_f32_fp8_sdwa v[230:231], v159 src0_sel:WORD_1
	v_pk_fma_f32 v[216:217], v[224:225], v[30:31], v[216:217]
	v_pk_fma_f32 v[218:219], v[226:227], v[30:31], v[218:219]
	v_pk_fma_f32 v[220:221], v[228:229], v[30:31], v[220:221]
	v_pk_fma_f32 v[222:223], v[230:231], v[30:31], v[222:223]
	s_branch .LU_s1_tail
.LU_s1_t2:
	v_cvt_pk_f32_fp8_e32 v[224:225], v144
	v_cvt_pk_f32_fp8_e32 v[226:227], v148
	v_cvt_pk_f32_fp8_e32 v[228:229], v152
	v_cvt_pk_f32_fp8_e32 v[230:231], v156
	v_pk_mul_f32 v[216:217], v[224:225], v[32:33]
	v_pk_mul_f32 v[218:219], v[226:227], v[32:33]
	v_pk_mul_f32 v[220:221], v[228:229], v[32:33]
	v_pk_mul_f32 v[222:223], v[230:231], v[32:33]
	v_cvt_pk_f32_fp8_sdwa v[224:225], v144 src0_sel:WORD_1
	v_cvt_pk_f32_fp8_sdwa v[226:227], v148 src0_sel:WORD_1
	v_cvt_pk_f32_fp8_sdwa v[228:229], v152 src0_sel:WORD_1
	v_cvt_pk_f32_fp8_sdwa v[230:231], v156 src0_sel:WORD_1
	v_pk_fma_f32 v[216:217], v[224:225], v[34:35], v[216:217]
	v_pk_fma_f32 v[218:219], v[226:227], v[34:35], v[218:219]
	v_pk_fma_f32 v[220:221], v[228:229], v[34:35], v[220:221]
	v_pk_fma_f32 v[222:223], v[230:231], v[34:35], v[222:223]
	v_cvt_pk_f32_fp8_e32 v[224:225], v145
	v_cvt_pk_f32_fp8_e32 v[226:227], v149
	v_cvt_pk_f32_fp8_e32 v[228:229], v153
	v_cvt_pk_f32_fp8_e32 v[230:231], v157
	v_pk_fma_f32 v[216:217], v[224:225], v[36:37], v[216:217]
	v_pk_fma_f32 v[218:219], v[226:227], v[36:37], v[218:219]
	v_pk_fma_f32 v[220:221], v[228:229], v[36:37], v[220:221]
	v_pk_fma_f32 v[222:223], v[230:231], v[36:37], v[222:223]
	v_cvt_pk_f32_fp8_sdwa v[224:225], v145 src0_sel:WORD_1
	v_cvt_pk_f32_fp8_sdwa v[226:227], v149 src0_sel:WORD_1
	v_cvt_pk_f32_fp8_sdwa v[228:229], v153 src0_sel:WORD_1
	v_cvt_pk_f32_fp8_sdwa v[230:231], v157 src0_sel:WORD_1
	v_pk_fma_f32 v[216:217], v[224:225], v[38:39], v[216:217]
	v_pk_fma_f32 v[218:219], v[226:227], v[38:39], v[218:219]
	v_pk_fma_f32 v[220:221], v[228:229], v[38:39], v[220:221]
	v_pk_fma_f32 v[222:223], v[230:231], v[38:39], v[222:223]
	v_cvt_pk_f32_fp8_e32 v[224:225], v146
	v_cvt_pk_f32_fp8_e32 v[226:227], v150
	v_cvt_pk_f32_fp8_e32 v[228:229], v154
	v_cvt_pk_f32_fp8_e32 v[230:231], v158
	v_pk_fma_f32 v[216:217], v[224:225], v[40:41], v[216:217]
	v_pk_fma_f32 v[218:219], v[226:227], v[40:41], v[218:219]
	v_pk_fma_f32 v[220:221], v[228:229], v[40:41], v[220:221]
	v_pk_fma_f32 v[222:223], v[230:231], v[40:41], v[222:223]
	v_cvt_pk_f32_fp8_sdwa v[224:225], v146 src0_sel:WORD_1
	v_cvt_pk_f32_fp8_sdwa v[226:227], v150 src0_sel:WORD_1
	v_cvt_pk_f32_fp8_sdwa v[228:229], v154 src0_sel:WORD_1
	v_cvt_pk_f32_fp8_sdwa v[230:231], v158 src0_sel:WORD_1
	v_pk_fma_f32 v[216:217], v[224:225], v[42:43], v[216:217]
	v_pk_fma_f32 v[218:219], v[226:227], v[42:43], v[218:219]
	v_pk_fma_f32 v[220:221], v[228:229], v[42:43], v[220:221]
	v_pk_fma_f32 v[222:223], v[230:231], v[42:43], v[222:223]
	v_cvt_pk_f32_fp8_e32 v[224:225], v147
	v_cvt_pk_f32_fp8_e32 v[226:227], v151
	v_cvt_pk_f32_fp8_e32 v[228:229], v155
	v_cvt_pk_f32_fp8_e32 v[230:231], v159
	v_pk_fma_f32 v[216:217], v[224:225], v[44:45], v[216:217]
	v_pk_fma_f32 v[218:219], v[226:227], v[44:45], v[218:219]
	v_pk_fma_f32 v[220:221], v[228:229], v[44:45], v[220:221]
	v_pk_fma_f32 v[222:223], v[230:231], v[44:45], v[222:223]
	v_cvt_pk_f32_fp8_sdwa v[224:225], v147 src0_sel:WORD_1
	v_cvt_pk_f32_fp8_sdwa v[226:227], v151 src0_sel:WORD_1
	v_cvt_pk_f32_fp8_sdwa v[228:229], v155 src0_sel:WORD_1
	v_cvt_pk_f32_fp8_sdwa v[230:231], v159 src0_sel:WORD_1
	v_pk_fma_f32 v[216:217], v[224:225], v[46:47], v[216:217]
	v_pk_fma_f32 v[218:219], v[226:227], v[46:47], v[218:219]
	v_pk_fma_f32 v[220:221], v[228:229], v[46:47], v[220:221]
	v_pk_fma_f32 v[222:223], v[230:231], v[46:47], v[222:223]
	s_branch .LU_s1_tail
.LU_s1_t3:
	v_cvt_pk_f32_fp8_e32 v[224:225], v144
	v_cvt_pk_f32_fp8_e32 v[226:227], v148
	v_cvt_pk_f32_fp8_e32 v[228:229], v152
	v_cvt_pk_f32_fp8_e32 v[230:231], v156
	v_pk_mul_f32 v[216:217], v[224:225], v[48:49]
	v_pk_mul_f32 v[218:219], v[226:227], v[48:49]
	v_pk_mul_f32 v[220:221], v[228:229], v[48:49]
	v_pk_mul_f32 v[222:223], v[230:231], v[48:49]
	v_cvt_pk_f32_fp8_sdwa v[224:225], v144 src0_sel:WORD_1
	v_cvt_pk_f32_fp8_sdwa v[226:227], v148 src0_sel:WORD_1
	v_cvt_pk_f32_fp8_sdwa v[228:229], v152 src0_sel:WORD_1
	v_cvt_pk_f32_fp8_sdwa v[230:231], v156 src0_sel:WORD_1
	v_pk_fma_f32 v[216:217], v[224:225], v[50:51], v[216:217]
	v_pk_fma_f32 v[218:219], v[226:227], v[50:51], v[218:219]
	v_pk_fma_f32 v[220:221], v[228:229], v[50:51], v[220:221]
	v_pk_fma_f32 v[222:223], v[230:231], v[50:51], v[222:223]
	v_cvt_pk_f32_fp8_e32 v[224:225], v145
	v_cvt_pk_f32_fp8_e32 v[226:227], v149
	v_cvt_pk_f32_fp8_e32 v[228:229], v153
	v_cvt_pk_f32_fp8_e32 v[230:231], v157
	v_pk_fma_f32 v[216:217], v[224:225], v[52:53], v[216:217]
	v_pk_fma_f32 v[218:219], v[226:227], v[52:53], v[218:219]
	v_pk_fma_f32 v[220:221], v[228:229], v[52:53], v[220:221]
	v_pk_fma_f32 v[222:223], v[230:231], v[52:53], v[222:223]
	v_cvt_pk_f32_fp8_sdwa v[224:225], v145 src0_sel:WORD_1
	v_cvt_pk_f32_fp8_sdwa v[226:227], v149 src0_sel:WORD_1
	v_cvt_pk_f32_fp8_sdwa v[228:229], v153 src0_sel:WORD_1
	v_cvt_pk_f32_fp8_sdwa v[230:231], v157 src0_sel:WORD_1
	v_pk_fma_f32 v[216:217], v[224:225], v[54:55], v[216:217]
	v_pk_fma_f32 v[218:219], v[226:227], v[54:55], v[218:219]
	v_pk_fma_f32 v[220:221], v[228:229], v[54:55], v[220:221]
	v_pk_fma_f32 v[222:223], v[230:231], v[54:55], v[222:223]
	v_cvt_pk_f32_fp8_e32 v[224:225], v146
	v_cvt_pk_f32_fp8_e32 v[226:227], v150
	v_cvt_pk_f32_fp8_e32 v[228:229], v154
	v_cvt_pk_f32_fp8_e32 v[230:231], v158
	v_pk_fma_f32 v[216:217], v[224:225], v[56:57], v[216:217]
	v_pk_fma_f32 v[218:219], v[226:227], v[56:57], v[218:219]
	v_pk_fma_f32 v[220:221], v[228:229], v[56:57], v[220:221]
	v_pk_fma_f32 v[222:223], v[230:231], v[56:57], v[222:223]
	v_cvt_pk_f32_fp8_sdwa v[224:225], v146 src0_sel:WORD_1
	v_cvt_pk_f32_fp8_sdwa v[226:227], v150 src0_sel:WORD_1
	v_cvt_pk_f32_fp8_sdwa v[228:229], v154 src0_sel:WORD_1
	v_cvt_pk_f32_fp8_sdwa v[230:231], v158 src0_sel:WORD_1
	v_pk_fma_f32 v[216:217], v[224:225], v[58:59], v[216:217]
	v_pk_fma_f32 v[218:219], v[226:227], v[58:59], v[218:219]
	v_pk_fma_f32 v[220:221], v[228:229], v[58:59], v[220:221]
	v_pk_fma_f32 v[222:223], v[230:231], v[58:59], v[222:223]
	v_cvt_pk_f32_fp8_e32 v[224:225], v147
	v_cvt_pk_f32_fp8_e32 v[226:227], v151
	v_cvt_pk_f32_fp8_e32 v[228:229], v155
	v_cvt_pk_f32_fp8_e32 v[230:231], v159
	v_pk_fma_f32 v[216:217], v[224:225], v[60:61], v[216:217]
	v_pk_fma_f32 v[218:219], v[226:227], v[60:61], v[218:219]
	v_pk_fma_f32 v[220:221], v[228:229], v[60:61], v[220:221]
	v_pk_fma_f32 v[222:223], v[230:231], v[60:61], v[222:223]
	v_cvt_pk_f32_fp8_sdwa v[224:225], v147 src0_sel:WORD_1
	v_cvt_pk_f32_fp8_sdwa v[226:227], v151 src0_sel:WORD_1
	v_cvt_pk_f32_fp8_sdwa v[228:229], v155 src0_sel:WORD_1
	v_cvt_pk_f32_fp8_sdwa v[230:231], v159 src0_sel:WORD_1
	v_pk_fma_f32 v[216:217], v[224:225], v[62:63], v[216:217]
	v_pk_fma_f32 v[218:219], v[226:227], v[62:63], v[218:219]
	v_pk_fma_f32 v[220:221], v[228:229], v[62:63], v[220:221]
	v_pk_fma_f32 v[222:223], v[230:231], v[62:63], v[222:223]
	s_branch .LU_s1_tail
.LU_s1_t4:
	v_cvt_pk_f32_fp8_e32 v[224:225], v144
	v_cvt_pk_f32_fp8_e32 v[226:227], v148
	v_cvt_pk_f32_fp8_e32 v[228:229], v152
	v_cvt_pk_f32_fp8_e32 v[230:231], v156
	v_pk_mul_f32 v[216:217], v[224:225], v[64:65]
	v_pk_mul_f32 v[218:219], v[226:227], v[64:65]
	v_pk_mul_f32 v[220:221], v[228:229], v[64:65]
	v_pk_mul_f32 v[222:223], v[230:231], v[64:65]
	v_cvt_pk_f32_fp8_sdwa v[224:225], v144 src0_sel:WORD_1
	v_cvt_pk_f32_fp8_sdwa v[226:227], v148 src0_sel:WORD_1
	v_cvt_pk_f32_fp8_sdwa v[228:229], v152 src0_sel:WORD_1
	v_cvt_pk_f32_fp8_sdwa v[230:231], v156 src0_sel:WORD_1
	v_pk_fma_f32 v[216:217], v[224:225], v[66:67], v[216:217]
	v_pk_fma_f32 v[218:219], v[226:227], v[66:67], v[218:219]
	v_pk_fma_f32 v[220:221], v[228:229], v[66:67], v[220:221]
	v_pk_fma_f32 v[222:223], v[230:231], v[66:67], v[222:223]
	v_cvt_pk_f32_fp8_e32 v[224:225], v145
	v_cvt_pk_f32_fp8_e32 v[226:227], v149
	v_cvt_pk_f32_fp8_e32 v[228:229], v153
	v_cvt_pk_f32_fp8_e32 v[230:231], v157
	v_pk_fma_f32 v[216:217], v[224:225], v[68:69], v[216:217]
	v_pk_fma_f32 v[218:219], v[226:227], v[68:69], v[218:219]
	v_pk_fma_f32 v[220:221], v[228:229], v[68:69], v[220:221]
	v_pk_fma_f32 v[222:223], v[230:231], v[68:69], v[222:223]
	v_cvt_pk_f32_fp8_sdwa v[224:225], v145 src0_sel:WORD_1
	v_cvt_pk_f32_fp8_sdwa v[226:227], v149 src0_sel:WORD_1
	v_cvt_pk_f32_fp8_sdwa v[228:229], v153 src0_sel:WORD_1
	v_cvt_pk_f32_fp8_sdwa v[230:231], v157 src0_sel:WORD_1
	v_pk_fma_f32 v[216:217], v[224:225], v[70:71], v[216:217]
	v_pk_fma_f32 v[218:219], v[226:227], v[70:71], v[218:219]
	v_pk_fma_f32 v[220:221], v[228:229], v[70:71], v[220:221]
	v_pk_fma_f32 v[222:223], v[230:231], v[70:71], v[222:223]
	v_cvt_pk_f32_fp8_e32 v[224:225], v146
	v_cvt_pk_f32_fp8_e32 v[226:227], v150
	v_cvt_pk_f32_fp8_e32 v[228:229], v154
	v_cvt_pk_f32_fp8_e32 v[230:231], v158
	v_pk_fma_f32 v[216:217], v[224:225], v[72:73], v[216:217]
	v_pk_fma_f32 v[218:219], v[226:227], v[72:73], v[218:219]
	v_pk_fma_f32 v[220:221], v[228:229], v[72:73], v[220:221]
	v_pk_fma_f32 v[222:223], v[230:231], v[72:73], v[222:223]
	v_cvt_pk_f32_fp8_sdwa v[224:225], v146 src0_sel:WORD_1
	v_cvt_pk_f32_fp8_sdwa v[226:227], v150 src0_sel:WORD_1
	v_cvt_pk_f32_fp8_sdwa v[228:229], v154 src0_sel:WORD_1
	v_cvt_pk_f32_fp8_sdwa v[230:231], v158 src0_sel:WORD_1
	v_pk_fma_f32 v[216:217], v[224:225], v[74:75], v[216:217]
	v_pk_fma_f32 v[218:219], v[226:227], v[74:75], v[218:219]
	v_pk_fma_f32 v[220:221], v[228:229], v[74:75], v[220:221]
	v_pk_fma_f32 v[222:223], v[230:231], v[74:75], v[222:223]
	v_cvt_pk_f32_fp8_e32 v[224:225], v147
	v_cvt_pk_f32_fp8_e32 v[226:227], v151
	v_cvt_pk_f32_fp8_e32 v[228:229], v155
	v_cvt_pk_f32_fp8_e32 v[230:231], v159
	v_pk_fma_f32 v[216:217], v[224:225], v[76:77], v[216:217]
	v_pk_fma_f32 v[218:219], v[226:227], v[76:77], v[218:219]
	v_pk_fma_f32 v[220:221], v[228:229], v[76:77], v[220:221]
	v_pk_fma_f32 v[222:223], v[230:231], v[76:77], v[222:223]
	v_cvt_pk_f32_fp8_sdwa v[224:225], v147 src0_sel:WORD_1
	v_cvt_pk_f32_fp8_sdwa v[226:227], v151 src0_sel:WORD_1
	v_cvt_pk_f32_fp8_sdwa v[228:229], v155 src0_sel:WORD_1
	v_cvt_pk_f32_fp8_sdwa v[230:231], v159 src0_sel:WORD_1
	v_pk_fma_f32 v[216:217], v[224:225], v[78:79], v[216:217]
	v_pk_fma_f32 v[218:219], v[226:227], v[78:79], v[218:219]
	v_pk_fma_f32 v[220:221], v[228:229], v[78:79], v[220:221]
	v_pk_fma_f32 v[222:223], v[230:231], v[78:79], v[222:223]
	s_branch .LU_s1_tail
.LU_s1_t5:
	v_cvt_pk_f32_fp8_e32 v[224:225], v144
	v_cvt_pk_f32_fp8_e32 v[226:227], v148
	v_cvt_pk_f32_fp8_e32 v[228:229], v152
	v_cvt_pk_f32_fp8_e32 v[230:231], v156
	v_pk_mul_f32 v[216:217], v[224:225], v[80:81]
	v_pk_mul_f32 v[218:219], v[226:227], v[80:81]
	v_pk_mul_f32 v[220:221], v[228:229], v[80:81]
	v_pk_mul_f32 v[222:223], v[230:231], v[80:81]
	v_cvt_pk_f32_fp8_sdwa v[224:225], v144 src0_sel:WORD_1
	v_cvt_pk_f32_fp8_sdwa v[226:227], v148 src0_sel:WORD_1
	v_cvt_pk_f32_fp8_sdwa v[228:229], v152 src0_sel:WORD_1
	v_cvt_pk_f32_fp8_sdwa v[230:231], v156 src0_sel:WORD_1
	v_pk_fma_f32 v[216:217], v[224:225], v[82:83], v[216:217]
	v_pk_fma_f32 v[218:219], v[226:227], v[82:83], v[218:219]
	v_pk_fma_f32 v[220:221], v[228:229], v[82:83], v[220:221]
	v_pk_fma_f32 v[222:223], v[230:231], v[82:83], v[222:223]
	v_cvt_pk_f32_fp8_e32 v[224:225], v145
	v_cvt_pk_f32_fp8_e32 v[226:227], v149
	v_cvt_pk_f32_fp8_e32 v[228:229], v153
	v_cvt_pk_f32_fp8_e32 v[230:231], v157
	v_pk_fma_f32 v[216:217], v[224:225], v[84:85], v[216:217]
	v_pk_fma_f32 v[218:219], v[226:227], v[84:85], v[218:219]
	v_pk_fma_f32 v[220:221], v[228:229], v[84:85], v[220:221]
	v_pk_fma_f32 v[222:223], v[230:231], v[84:85], v[222:223]
	v_cvt_pk_f32_fp8_sdwa v[224:225], v145 src0_sel:WORD_1
	v_cvt_pk_f32_fp8_sdwa v[226:227], v149 src0_sel:WORD_1
	v_cvt_pk_f32_fp8_sdwa v[228:229], v153 src0_sel:WORD_1
	v_cvt_pk_f32_fp8_sdwa v[230:231], v157 src0_sel:WORD_1
	v_pk_fma_f32 v[216:217], v[224:225], v[86:87], v[216:217]
	v_pk_fma_f32 v[218:219], v[226:227], v[86:87], v[218:219]
	v_pk_fma_f32 v[220:221], v[228:229], v[86:87], v[220:221]
	v_pk_fma_f32 v[222:223], v[230:231], v[86:87], v[222:223]
	v_cvt_pk_f32_fp8_e32 v[224:225], v146
	v_cvt_pk_f32_fp8_e32 v[226:227], v150
	v_cvt_pk_f32_fp8_e32 v[228:229], v154
	v_cvt_pk_f32_fp8_e32 v[230:231], v158
	v_pk_fma_f32 v[216:217], v[224:225], v[88:89], v[216:217]
	v_pk_fma_f32 v[218:219], v[226:227], v[88:89], v[218:219]
	v_pk_fma_f32 v[220:221], v[228:229], v[88:89], v[220:221]
	v_pk_fma_f32 v[222:223], v[230:231], v[88:89], v[222:223]
	v_cvt_pk_f32_fp8_sdwa v[224:225], v146 src0_sel:WORD_1
	v_cvt_pk_f32_fp8_sdwa v[226:227], v150 src0_sel:WORD_1
	v_cvt_pk_f32_fp8_sdwa v[228:229], v154 src0_sel:WORD_1
	v_cvt_pk_f32_fp8_sdwa v[230:231], v158 src0_sel:WORD_1
	v_pk_fma_f32 v[216:217], v[224:225], v[90:91], v[216:217]
	v_pk_fma_f32 v[218:219], v[226:227], v[90:91], v[218:219]
	v_pk_fma_f32 v[220:221], v[228:229], v[90:91], v[220:221]
	v_pk_fma_f32 v[222:223], v[230:231], v[90:91], v[222:223]
	v_cvt_pk_f32_fp8_e32 v[224:225], v147
	v_cvt_pk_f32_fp8_e32 v[226:227], v151
	v_cvt_pk_f32_fp8_e32 v[228:229], v155
	v_cvt_pk_f32_fp8_e32 v[230:231], v159
	v_pk_fma_f32 v[216:217], v[224:225], v[92:93], v[216:217]
	v_pk_fma_f32 v[218:219], v[226:227], v[92:93], v[218:219]
	v_pk_fma_f32 v[220:221], v[228:229], v[92:93], v[220:221]
	v_pk_fma_f32 v[222:223], v[230:231], v[92:93], v[222:223]
	v_cvt_pk_f32_fp8_sdwa v[224:225], v147 src0_sel:WORD_1
	v_cvt_pk_f32_fp8_sdwa v[226:227], v151 src0_sel:WORD_1
	v_cvt_pk_f32_fp8_sdwa v[228:229], v155 src0_sel:WORD_1
	v_cvt_pk_f32_fp8_sdwa v[230:231], v159 src0_sel:WORD_1
	v_pk_fma_f32 v[216:217], v[224:225], v[94:95], v[216:217]
	v_pk_fma_f32 v[218:219], v[226:227], v[94:95], v[218:219]
	v_pk_fma_f32 v[220:221], v[228:229], v[94:95], v[220:221]
	v_pk_fma_f32 v[222:223], v[230:231], v[94:95], v[222:223]
	s_branch .LU_s1_tail
.LU_s1_t6:
	v_cvt_pk_f32_fp8_e32 v[224:225], v144
	v_cvt_pk_f32_fp8_e32 v[226:227], v148
	v_cvt_pk_f32_fp8_e32 v[228:229], v152
	v_cvt_pk_f32_fp8_e32 v[230:231], v156
	v_pk_mul_f32 v[216:217], v[224:225], v[96:97]
	v_pk_mul_f32 v[218:219], v[226:227], v[96:97]
	v_pk_mul_f32 v[220:221], v[228:229], v[96:97]
	v_pk_mul_f32 v[222:223], v[230:231], v[96:97]
	v_cvt_pk_f32_fp8_sdwa v[224:225], v144 src0_sel:WORD_1
	v_cvt_pk_f32_fp8_sdwa v[226:227], v148 src0_sel:WORD_1
	v_cvt_pk_f32_fp8_sdwa v[228:229], v152 src0_sel:WORD_1
	v_cvt_pk_f32_fp8_sdwa v[230:231], v156 src0_sel:WORD_1
	v_pk_fma_f32 v[216:217], v[224:225], v[98:99], v[216:217]
	v_pk_fma_f32 v[218:219], v[226:227], v[98:99], v[218:219]
	v_pk_fma_f32 v[220:221], v[228:229], v[98:99], v[220:221]
	v_pk_fma_f32 v[222:223], v[230:231], v[98:99], v[222:223]
	v_cvt_pk_f32_fp8_e32 v[224:225], v145
	v_cvt_pk_f32_fp8_e32 v[226:227], v149
	v_cvt_pk_f32_fp8_e32 v[228:229], v153
	v_cvt_pk_f32_fp8_e32 v[230:231], v157
	v_pk_fma_f32 v[216:217], v[224:225], v[100:101], v[216:217]
	v_pk_fma_f32 v[218:219], v[226:227], v[100:101], v[218:219]
	v_pk_fma_f32 v[220:221], v[228:229], v[100:101], v[220:221]
	v_pk_fma_f32 v[222:223], v[230:231], v[100:101], v[222:223]
	v_cvt_pk_f32_fp8_sdwa v[224:225], v145 src0_sel:WORD_1
	v_cvt_pk_f32_fp8_sdwa v[226:227], v149 src0_sel:WORD_1
	v_cvt_pk_f32_fp8_sdwa v[228:229], v153 src0_sel:WORD_1
	v_cvt_pk_f32_fp8_sdwa v[230:231], v157 src0_sel:WORD_1
	v_pk_fma_f32 v[216:217], v[224:225], v[102:103], v[216:217]
	v_pk_fma_f32 v[218:219], v[226:227], v[102:103], v[218:219]
	v_pk_fma_f32 v[220:221], v[228:229], v[102:103], v[220:221]
	v_pk_fma_f32 v[222:223], v[230:231], v[102:103], v[222:223]
	v_cvt_pk_f32_fp8_e32 v[224:225], v146
	v_cvt_pk_f32_fp8_e32 v[226:227], v150
	v_cvt_pk_f32_fp8_e32 v[228:229], v154
	v_cvt_pk_f32_fp8_e32 v[230:231], v158
	v_pk_fma_f32 v[216:217], v[224:225], v[104:105], v[216:217]
	v_pk_fma_f32 v[218:219], v[226:227], v[104:105], v[218:219]
	v_pk_fma_f32 v[220:221], v[228:229], v[104:105], v[220:221]
	v_pk_fma_f32 v[222:223], v[230:231], v[104:105], v[222:223]
	v_cvt_pk_f32_fp8_sdwa v[224:225], v146 src0_sel:WORD_1
	v_cvt_pk_f32_fp8_sdwa v[226:227], v150 src0_sel:WORD_1
	v_cvt_pk_f32_fp8_sdwa v[228:229], v154 src0_sel:WORD_1
	v_cvt_pk_f32_fp8_sdwa v[230:231], v158 src0_sel:WORD_1
	v_pk_fma_f32 v[216:217], v[224:225], v[106:107], v[216:217]
	v_pk_fma_f32 v[218:219], v[226:227], v[106:107], v[218:219]
	v_pk_fma_f32 v[220:221], v[228:229], v[106:107], v[220:221]
	v_pk_fma_f32 v[222:223], v[230:231], v[106:107], v[222:223]
	v_cvt_pk_f32_fp8_e32 v[224:225], v147
	v_cvt_pk_f32_fp8_e32 v[226:227], v151
	v_cvt_pk_f32_fp8_e32 v[228:229], v155
	v_cvt_pk_f32_fp8_e32 v[230:231], v159
	v_pk_fma_f32 v[216:217], v[224:225], v[108:109], v[216:217]
	v_pk_fma_f32 v[218:219], v[226:227], v[108:109], v[218:219]
	v_pk_fma_f32 v[220:221], v[228:229], v[108:109], v[220:221]
	v_pk_fma_f32 v[222:223], v[230:231], v[108:109], v[222:223]
	v_cvt_pk_f32_fp8_sdwa v[224:225], v147 src0_sel:WORD_1
	v_cvt_pk_f32_fp8_sdwa v[226:227], v151 src0_sel:WORD_1
	v_cvt_pk_f32_fp8_sdwa v[228:229], v155 src0_sel:WORD_1
	v_cvt_pk_f32_fp8_sdwa v[230:231], v159 src0_sel:WORD_1
	v_pk_fma_f32 v[216:217], v[224:225], v[110:111], v[216:217]
	v_pk_fma_f32 v[218:219], v[226:227], v[110:111], v[218:219]
	v_pk_fma_f32 v[220:221], v[228:229], v[110:111], v[220:221]
	v_pk_fma_f32 v[222:223], v[230:231], v[110:111], v[222:223]
	s_branch .LU_s1_tail
.LU_s1_t7:
	v_cvt_pk_f32_fp8_e32 v[224:225], v144
	v_cvt_pk_f32_fp8_e32 v[226:227], v148
	v_cvt_pk_f32_fp8_e32 v[228:229], v152
	v_cvt_pk_f32_fp8_e32 v[230:231], v156
	v_pk_mul_f32 v[216:217], v[224:225], v[112:113]
	v_pk_mul_f32 v[218:219], v[226:227], v[112:113]
	v_pk_mul_f32 v[220:221], v[228:229], v[112:113]
	v_pk_mul_f32 v[222:223], v[230:231], v[112:113]
	v_cvt_pk_f32_fp8_sdwa v[224:225], v144 src0_sel:WORD_1
	v_cvt_pk_f32_fp8_sdwa v[226:227], v148 src0_sel:WORD_1
	v_cvt_pk_f32_fp8_sdwa v[228:229], v152 src0_sel:WORD_1
	v_cvt_pk_f32_fp8_sdwa v[230:231], v156 src0_sel:WORD_1
	v_pk_fma_f32 v[216:217], v[224:225], v[114:115], v[216:217]
	v_pk_fma_f32 v[218:219], v[226:227], v[114:115], v[218:219]
	v_pk_fma_f32 v[220:221], v[228:229], v[114:115], v[220:221]
	v_pk_fma_f32 v[222:223], v[230:231], v[114:115], v[222:223]
	v_cvt_pk_f32_fp8_e32 v[224:225], v145
	v_cvt_pk_f32_fp8_e32 v[226:227], v149
	v_cvt_pk_f32_fp8_e32 v[228:229], v153
	v_cvt_pk_f32_fp8_e32 v[230:231], v157
	v_pk_fma_f32 v[216:217], v[224:225], v[116:117], v[216:217]
	v_pk_fma_f32 v[218:219], v[226:227], v[116:117], v[218:219]
	v_pk_fma_f32 v[220:221], v[228:229], v[116:117], v[220:221]
	v_pk_fma_f32 v[222:223], v[230:231], v[116:117], v[222:223]
	v_cvt_pk_f32_fp8_sdwa v[224:225], v145 src0_sel:WORD_1
	v_cvt_pk_f32_fp8_sdwa v[226:227], v149 src0_sel:WORD_1
	v_cvt_pk_f32_fp8_sdwa v[228:229], v153 src0_sel:WORD_1
	v_cvt_pk_f32_fp8_sdwa v[230:231], v157 src0_sel:WORD_1
	v_pk_fma_f32 v[216:217], v[224:225], v[118:119], v[216:217]
	v_pk_fma_f32 v[218:219], v[226:227], v[118:119], v[218:219]
	v_pk_fma_f32 v[220:221], v[228:229], v[118:119], v[220:221]
	v_pk_fma_f32 v[222:223], v[230:231], v[118:119], v[222:223]
	v_cvt_pk_f32_fp8_e32 v[224:225], v146
	v_cvt_pk_f32_fp8_e32 v[226:227], v150
	v_cvt_pk_f32_fp8_e32 v[228:229], v154
	v_cvt_pk_f32_fp8_e32 v[230:231], v158
	v_pk_fma_f32 v[216:217], v[224:225], v[120:121], v[216:217]
	v_pk_fma_f32 v[218:219], v[226:227], v[120:121], v[218:219]
	v_pk_fma_f32 v[220:221], v[228:229], v[120:121], v[220:221]
	v_pk_fma_f32 v[222:223], v[230:231], v[120:121], v[222:223]
	v_cvt_pk_f32_fp8_sdwa v[224:225], v146 src0_sel:WORD_1
	v_cvt_pk_f32_fp8_sdwa v[226:227], v150 src0_sel:WORD_1
	v_cvt_pk_f32_fp8_sdwa v[228:229], v154 src0_sel:WORD_1
	v_cvt_pk_f32_fp8_sdwa v[230:231], v158 src0_sel:WORD_1
	v_pk_fma_f32 v[216:217], v[224:225], v[122:123], v[216:217]
	v_pk_fma_f32 v[218:219], v[226:227], v[122:123], v[218:219]
	v_pk_fma_f32 v[220:221], v[228:229], v[122:123], v[220:221]
	v_pk_fma_f32 v[222:223], v[230:231], v[122:123], v[222:223]
	v_cvt_pk_f32_fp8_e32 v[224:225], v147
	v_cvt_pk_f32_fp8_e32 v[226:227], v151
	v_cvt_pk_f32_fp8_e32 v[228:229], v155
	v_cvt_pk_f32_fp8_e32 v[230:231], v159
	v_pk_fma_f32 v[216:217], v[224:225], v[124:125], v[216:217]
	v_pk_fma_f32 v[218:219], v[226:227], v[124:125], v[218:219]
	v_pk_fma_f32 v[220:221], v[228:229], v[124:125], v[220:221]
	v_pk_fma_f32 v[222:223], v[230:231], v[124:125], v[222:223]
	v_cvt_pk_f32_fp8_sdwa v[224:225], v147 src0_sel:WORD_1
	v_cvt_pk_f32_fp8_sdwa v[226:227], v151 src0_sel:WORD_1
	v_cvt_pk_f32_fp8_sdwa v[228:229], v155 src0_sel:WORD_1
	v_cvt_pk_f32_fp8_sdwa v[230:231], v159 src0_sel:WORD_1
	v_pk_fma_f32 v[216:217], v[224:225], v[126:127], v[216:217]
	v_pk_fma_f32 v[218:219], v[226:227], v[126:127], v[218:219]
	v_pk_fma_f32 v[220:221], v[228:229], v[126:127], v[220:221]
	v_pk_fma_f32 v[222:223], v[230:231], v[126:127], v[222:223]
.LU_s1_tail:
	v_add_f32_e32 v216, v216, v217
	v_add_f32_e32 v220, v220, v221
	v_add_f32_e32 v218, v218, v219
	v_add_f32_e32 v222, v222, v223
	s_nop 0
	v_permlane32_swap_b32_e32 v216, v220
	s_nop 0
	v_permlane32_swap_b32_e32 v218, v222
	v_add_f32_e32 v216, v216, v220
	v_add_f32_e32 v218, v218, v222
	s_nop 1
	v_permlane16_swap_b32_e32 v216, v218
	v_add_f32_e32 v216, v216, v218
	s_nop 1
	v_add_f32_dpp v216, v216, v216 quad_perm:[1,0,3,2] row_mask:0xf bank_mask:0xf bound_ctrl:1
	s_nop 1
	v_add_f32_dpp v216, v216, v216 quad_perm:[2,3,0,1] row_mask:0xf bank_mask:0xf bound_ctrl:1
	s_nop 1
	v_add_f32_dpp v216, v216, v216 row_half_mirror row_mask:0xf bank_mask:0xf bound_ctrl:1
	s_nop 1
	v_add_f32_dpp v216, v216, v216 row_mirror row_mask:0xf bank_mask:0xf bound_ctrl:1
	v_mul_f32_e32 v217, v249, v216
	v_fma_f32 v218, |v217|, s72, 1.0
	v_mul_f32_e32 v219, v217, v217
	v_rcp_f32_e32 v218, v218
	v_mul_f32_e32 v219, 0xbf38aa3b, v219
	v_exp_f32_e32 v219, v219
	v_fmamk_f32 v220, v218, 0x3f07dc22, v242
	v_fmaak_f32 v220, v218, v220, 0x3f35f0e3
	v_fmaak_f32 v220, v218, v220, 0xbe11a98e
	v_fmaak_f32 v220, v218, v220, 0x3e027906
	v_mul_f32_e32 v220, v218, v220
	v_mul_f32_e32 v220, v219, v220
	v_mul_f32_e32 v221, v217, v220
	v_fma_f32 v220, -v217, v220, v217
	v_cmp_gt_f32_e32 vcc, 0, v217
	v_lshrrev_b32_e32 v254, 3, v238
	s_nop 0
	v_cndmask_b32_e32 v220, v220, v221, vcc
	v_mul_f32_e32 v220, v237, v220
	v_mul_f32_e32 v220, v209, v220
	ds_write_b32 v254, v220
	ds_read_b128 v[236:239], v241 offset:128
	ds_read_b128 v[232:235], v241 offset:384
	s_add_i32 s21, s21, 1
.LU_s2:
	s_cmp_ge_u32 s21, s20
	s_cbranch_scc1 .LU_done
	s_waitcnt lgkmcnt(0)
	v_readlane_b32 s64, v232, 0
	v_readlane_b32 s65, v232, 16
	v_readlane_b32 s66, v232, 32
	v_readlane_b32 s67, v232, 48
	v_lshrrev_b32_e32 v253, 8, v232
	s_add_u32 s24, s4, s64
	s_addc_u32 s25, s5, 0
	s_add_u32 s26, s4, s65
	s_addc_u32 s27, s5, 0
	s_add_u32 s28, s4, s66
	s_addc_u32 s29, s5, 0
	s_add_u32 s30, s4, s67
	s_addc_u32 s31, s5, 0
	global_load_dwordx4 v[144:147], v240, s[24:25]
	global_load_dwordx4 v[148:151], v240, s[26:27]
	global_load_dwordx4 v[152:155], v240, s[28:29]
	global_load_dwordx4 v[156:159], v240, s[30:31]
	global_load_dword v249, v253, s[8:9]
	global_load_dword v209, v253, s[52:53]
	v_readfirstlane_b32 s23, v238
	s_and_b32 s23, s23, 7
	s_waitcnt vmcnt(24)
	s_cmp_ge_u32 s23, 4
	s_cbranch_scc1 .LU_s2_h
	s_cmp_ge_u32 s23, 2
	s_cbranch_scc1 .LU_s2_23
	s_cmp_eq_u32 s23, 0
	s_cbranch_scc1 .LU_s2_t0
	s_branch .LU_s2_t1

.LU_s2_t0:
	v_cvt_pk_f32_fp8_e32 v[224:225], v160
	v_cvt_pk_f32_fp8_e32 v[226:227], v164
	v_cvt_pk_f32_fp8_e32 v[228:229], v168
	v_cvt_pk_f32_fp8_e32 v[230:231], v172
	v_pk_mul_f32 v[216:217], v[224:225], v[0:1]
	v_pk_mul_f32 v[218:219], v[226:227], v[0:1]
	v_pk_mul_f32 v[220:221], v[228:229], v[0:1]
	v_pk_mul_f32 v[222:223], v[230:231], v[0:1]
	v_cvt_pk_f32_fp8_sdwa v[224:225], v160 src0_sel:WORD_1
	v_cvt_pk_f32_fp8_sdwa v[226:227], v164 src0_sel:WORD_1
	v_cvt_pk_f32_fp8_sdwa v[228:229], v168 src0_sel:WORD_1
	v_cvt_pk_f32_fp8_sdwa v[230:231], v172 src0_sel:WORD_1
	v_pk_fma_f32 v[216:217], v[224:225], v[2:3], v[216:217]
	v_pk_fma_f32 v[218:219], v[226:227], v[2:3], v[218:219]
	v_pk_fma_f32 v[220:221], v[228:229], v[2:3], v[220:221]
	v_pk_fma_f32 v[222:223], v[230:231], v[2:3], v[222:223]
	v_cvt_pk_f32_fp8_e32 v[224:225], v161
	v_cvt_pk_f32_fp8_e32 v[226:227], v165
	v_cvt_pk_f32_fp8_e32 v[228:229], v169
	v_cvt_pk_f32_fp8_e32 v[230:231], v173
	v_pk_fma_f32 v[216:217], v[224:225], v[4:5], v[216:217]
	v_pk_fma_f32 v[218:219], v[226:227], v[4:5], v[218:219]
	v_pk_fma_f32 v[220:221], v[228:229], v[4:5], v[220:221]
	v_pk_fma_f32 v[222:223], v[230:231], v[4:5], v[222:223]
	v_cvt_pk_f32_fp8_sdwa v[224:225], v161 src0_sel:WORD_1
	v_cvt_pk_f32_fp8_sdwa v[226:227], v165 src0_sel:WORD_1
	v_cvt_pk_f32_fp8_sdwa v[228:229], v169 src0_sel:WORD_1
	v_cvt_pk_f32_fp8_sdwa v[230:231], v173 src0_sel:WORD_1
	v_pk_fma_f32 v[216:217], v[224:225], v[6:7], v[216:217]
	v_pk_fma_f32 v[218:219], v[226:227], v[6:7], v[218:219]
	v_pk_fma_f32 v[220:221], v[228:229], v[6:7], v[220:221]
	v_pk_fma_f32 v[222:223], v[230:231], v[6:7], v[222:223]
	v_cvt_pk_f32_fp8_e32 v[224:225], v162
	v_cvt_pk_f32_fp8_e32 v[226:227], v166
	v_cvt_pk_f32_fp8_e32 v[228:229], v170
	v_cvt_pk_f32_fp8_e32 v[230:231], v174
	v_pk_fma_f32 v[216:217], v[224:225], v[8:9], v[216:217]
	v_pk_fma_f32 v[218:219], v[226:227], v[8:9], v[218:219]
	v_pk_fma_f32 v[220:221], v[228:229], v[8:9], v[220:221]
	v_pk_fma_f32 v[222:223], v[230:231], v[8:9], v[222:223]
	v_cvt_pk_f32_fp8_sdwa v[224:225], v162 src0_sel:WORD_1
	v_cvt_pk_f32_fp8_sdwa v[226:227], v166 src0_sel:WORD_1
	v_cvt_pk_f32_fp8_sdwa v[228:229], v170 src0_sel:WORD_1
	v_cvt_pk_f32_fp8_sdwa v[230:231], v174 src0_sel:WORD_1
	v_pk_fma_f32 v[216:217], v[224:225], v[10:11], v[216:217]
	v_pk_fma_f32 v[218:219], v[226:227], v[10:11], v[218:219]
	v_pk_fma_f32 v[220:221], v[228:229], v[10:11], v[220:221]
	v_pk_fma_f32 v[222:223], v[230:231], v[10:11], v[222:223]
	v_cvt_pk_f32_fp8_e32 v[224:225], v163
	v_cvt_pk_f32_fp8_e32 v[226:227], v167
	v_cvt_pk_f32_fp8_e32 v[228:229], v171
	v_cvt_pk_f32_fp8_e32 v[230:231], v175
	v_pk_fma_f32 v[216:217], v[224:225], v[12:13], v[216:217]
	v_pk_fma_f32 v[218:219], v[226:227], v[12:13], v[218:219]
	v_pk_fma_f32 v[220:221], v[228:229], v[12:13], v[220:221]
	v_pk_fma_f32 v[222:223], v[230:231], v[12:13], v[222:223]
	v_cvt_pk_f32_fp8_sdwa v[224:225], v163 src0_sel:WORD_1
	v_cvt_pk_f32_fp8_sdwa v[226:227], v167 src0_sel:WORD_1
	v_cvt_pk_f32_fp8_sdwa v[228:229], v171 src0_sel:WORD_1
	v_cvt_pk_f32_fp8_sdwa v[230:231], v175 src0_sel:WORD_1
	v_pk_fma_f32 v[216:217], v[224:225], v[14:15], v[216:217]
	v_pk_fma_f32 v[218:219], v[226:227], v[14:15], v[218:219]
	v_pk_fma_f32 v[220:221], v[228:229], v[14:15], v[220:221]
	v_pk_fma_f32 v[222:223], v[230:231], v[14:15], v[222:223]
	s_branch .LU_s2_tail
.LU_s2_t1:
	v_cvt_pk_f32_fp8_e32 v[224:225], v160
	v_cvt_pk_f32_fp8_e32 v[226:227], v164
	v_cvt_pk_f32_fp8_e32 v[228:229], v168
	v_cvt_pk_f32_fp8_e32 v[230:231], v172
	v_pk_mul_f32 v[216:217], v[224:225], v[16:17]
	v_pk_mul_f32 v[218:219], v[226:227], v[16:17]
	v_pk_mul_f32 v[220:221], v[228:229], v[16:17]
	v_pk_mul_f32 v[222:223], v[230:231], v[16:17]
	v_cvt_pk_f32_fp8_sdwa v[224:225], v160 src0_sel:WORD_1
	v_cvt_pk_f32_fp8_sdwa v[226:227], v164 src0_sel:WORD_1
	v_cvt_pk_f32_fp8_sdwa v[228:229], v168 src0_sel:WORD_1
	v_cvt_pk_f32_fp8_sdwa v[230:231], v172 src0_sel:WORD_1
	v_pk_fma_f32 v[216:217], v[224:225], v[18:19], v[216:217]
	v_pk_fma_f32 v[218:219], v[226:227], v[18:19], v[218:219]
	v_pk_fma_f32 v[220:221], v[228:229], v[18:19], v[220:221]
	v_pk_fma_f32 v[222:223], v[230:231], v[18:19], v[222:223]
	v_cvt_pk_f32_fp8_e32 v[224:225], v161
	v_cvt_pk_f32_fp8_e32 v[226:227], v165
	v_cvt_pk_f32_fp8_e32 v[228:229], v169
	v_cvt_pk_f32_fp8_e32 v[230:231], v173
	v_pk_fma_f32 v[216:217], v[224:225], v[20:21], v[216:217]
	v_pk_fma_f32 v[218:219], v[226:227], v[20:21], v[218:219]
	v_pk_fma_f32 v[220:221], v[228:229], v[20:21], v[220:221]
	v_pk_fma_f32 v[222:223], v[230:231], v[20:21], v[222:223]
	v_cvt_pk_f32_fp8_sdwa v[224:225], v161 src0_sel:WORD_1
	v_cvt_pk_f32_fp8_sdwa v[226:227], v165 src0_sel:WORD_1
	v_cvt_pk_f32_fp8_sdwa v[228:229], v169 src0_sel:WORD_1
	v_cvt_pk_f32_fp8_sdwa v[230:231], v173 src0_sel:WORD_1
	v_pk_fma_f32 v[216:217], v[224:225], v[22:23], v[216:217]
	v_pk_fma_f32 v[218:219], v[226:227], v[22:23], v[218:219]
	v_pk_fma_f32 v[220:221], v[228:229], v[22:23], v[220:221]
	v_pk_fma_f32 v[222:223], v[230:231], v[22:23], v[222:223]
	v_cvt_pk_f32_fp8_e32 v[224:225], v162
	v_cvt_pk_f32_fp8_e32 v[226:227], v166
	v_cvt_pk_f32_fp8_e32 v[228:229], v170
	v_cvt_pk_f32_fp8_e32 v[230:231], v174
	v_pk_fma_f32 v[216:217], v[224:225], v[24:25], v[216:217]
	v_pk_fma_f32 v[218:219], v[226:227], v[24:25], v[218:219]
	v_pk_fma_f32 v[220:221], v[228:229], v[24:25], v[220:221]
	v_pk_fma_f32 v[222:223], v[230:231], v[24:25], v[222:223]
	v_cvt_pk_f32_fp8_sdwa v[224:225], v162 src0_sel:WORD_1
	v_cvt_pk_f32_fp8_sdwa v[226:227], v166 src0_sel:WORD_1
	v_cvt_pk_f32_fp8_sdwa v[228:229], v170 src0_sel:WORD_1
	v_cvt_pk_f32_fp8_sdwa v[230:231], v174 src0_sel:WORD_1
	v_pk_fma_f32 v[216:217], v[224:225], v[26:27], v[216:217]
	v_pk_fma_f32 v[218:219], v[226:227], v[26:27], v[218:219]
	v_pk_fma_f32 v[220:221], v[228:229], v[26:27], v[220:221]
	v_pk_fma_f32 v[222:223], v[230:231], v[26:27], v[222:223]
	v_cvt_pk_f32_fp8_e32 v[224:225], v163
	v_cvt_pk_f32_fp8_e32 v[226:227], v167
	v_cvt_pk_f32_fp8_e32 v[228:229], v171
	v_cvt_pk_f32_fp8_e32 v[230:231], v175
	v_pk_fma_f32 v[216:217], v[224:225], v[28:29], v[216:217]
	v_pk_fma_f32 v[218:219], v[226:227], v[28:29], v[218:219]
	v_pk_fma_f32 v[220:221], v[228:229], v[28:29], v[220:221]
	v_pk_fma_f32 v[222:223], v[230:231], v[28:29], v[222:223]
	v_cvt_pk_f32_fp8_sdwa v[224:225], v163 src0_sel:WORD_1
	v_cvt_pk_f32_fp8_sdwa v[226:227], v167 src0_sel:WORD_1
	v_cvt_pk_f32_fp8_sdwa v[228:229], v171 src0_sel:WORD_1
	v_cvt_pk_f32_fp8_sdwa v[230:231], v175 src0_sel:WORD_1
	v_pk_fma_f32 v[216:217], v[224:225], v[30:31], v[216:217]
	v_pk_fma_f32 v[218:219], v[226:227], v[30:31], v[218:219]
	v_pk_fma_f32 v[220:221], v[228:229], v[30:31], v[220:221]
	v_pk_fma_f32 v[222:223], v[230:231], v[30:31], v[222:223]
	s_branch .LU_s2_tail
.LU_s2_t2:
	v_cvt_pk_f32_fp8_e32 v[224:225], v160
	v_cvt_pk_f32_fp8_e32 v[226:227], v164
	v_cvt_pk_f32_fp8_e32 v[228:229], v168
	v_cvt_pk_f32_fp8_e32 v[230:231], v172
	v_pk_mul_f32 v[216:217], v[224:225], v[32:33]
	v_pk_mul_f32 v[218:219], v[226:227], v[32:33]
	v_pk_mul_f32 v[220:221], v[228:229], v[32:33]
	v_pk_mul_f32 v[222:223], v[230:231], v[32:33]
	v_cvt_pk_f32_fp8_sdwa v[224:225], v160 src0_sel:WORD_1
	v_cvt_pk_f32_fp8_sdwa v[226:227], v164 src0_sel:WORD_1
	v_cvt_pk_f32_fp8_sdwa v[228:229], v168 src0_sel:WORD_1
	v_cvt_pk_f32_fp8_sdwa v[230:231], v172 src0_sel:WORD_1
	v_pk_fma_f32 v[216:217], v[224:225], v[34:35], v[216:217]
	v_pk_fma_f32 v[218:219], v[226:227], v[34:35], v[218:219]
	v_pk_fma_f32 v[220:221], v[228:229], v[34:35], v[220:221]
	v_pk_fma_f32 v[222:223], v[230:231], v[34:35], v[222:223]
	v_cvt_pk_f32_fp8_e32 v[224:225], v161
	v_cvt_pk_f32_fp8_e32 v[226:227], v165
	v_cvt_pk_f32_fp8_e32 v[228:229], v169
	v_cvt_pk_f32_fp8_e32 v[230:231], v173
	v_pk_fma_f32 v[216:217], v[224:225], v[36:37], v[216:217]
	v_pk_fma_f32 v[218:219], v[226:227], v[36:37], v[218:219]
	v_pk_fma_f32 v[220:221], v[228:229], v[36:37], v[220:221]
	v_pk_fma_f32 v[222:223], v[230:231], v[36:37], v[222:223]
	v_cvt_pk_f32_fp8_sdwa v[224:225], v161 src0_sel:WORD_1
	v_cvt_pk_f32_fp8_sdwa v[226:227], v165 src0_sel:WORD_1
	v_cvt_pk_f32_fp8_sdwa v[228:229], v169 src0_sel:WORD_1
	v_cvt_pk_f32_fp8_sdwa v[230:231], v173 src0_sel:WORD_1
	v_pk_fma_f32 v[216:217], v[224:225], v[38:39], v[216:217]
	v_pk_fma_f32 v[218:219], v[226:227], v[38:39], v[218:219]
	v_pk_fma_f32 v[220:221], v[228:229], v[38:39], v[220:221]
	v_pk_fma_f32 v[222:223], v[230:231], v[38:39], v[222:223]
	v_cvt_pk_f32_fp8_e32 v[224:225], v162
	v_cvt_pk_f32_fp8_e32 v[226:227], v166
	v_cvt_pk_f32_fp8_e32 v[228:229], v170
	v_cvt_pk_f32_fp8_e32 v[230:231], v174
	v_pk_fma_f32 v[216:217], v[224:225], v[40:41], v[216:217]
	v_pk_fma_f32 v[218:219], v[226:227], v[40:41], v[218:219]
	v_pk_fma_f32 v[220:221], v[228:229], v[40:41], v[220:221]
	v_pk_fma_f32 v[222:223], v[230:231], v[40:41], v[222:223]
	v_cvt_pk_f32_fp8_sdwa v[224:225], v162 src0_sel:WORD_1
	v_cvt_pk_f32_fp8_sdwa v[226:227], v166 src0_sel:WORD_1
	v_cvt_pk_f32_fp8_sdwa v[228:229], v170 src0_sel:WORD_1
	v_cvt_pk_f32_fp8_sdwa v[230:231], v174 src0_sel:WORD_1
	v_pk_fma_f32 v[216:217], v[224:225], v[42:43], v[216:217]
	v_pk_fma_f32 v[218:219], v[226:227], v[42:43], v[218:219]
	v_pk_fma_f32 v[220:221], v[228:229], v[42:43], v[220:221]
	v_pk_fma_f32 v[222:223], v[230:231], v[42:43], v[222:223]
	v_cvt_pk_f32_fp8_e32 v[224:225], v163
	v_cvt_pk_f32_fp8_e32 v[226:227], v167
	v_cvt_pk_f32_fp8_e32 v[228:229], v171
	v_cvt_pk_f32_fp8_e32 v[230:231], v175
	v_pk_fma_f32 v[216:217], v[224:225], v[44:45], v[216:217]
	v_pk_fma_f32 v[218:219], v[226:227], v[44:45], v[218:219]
	v_pk_fma_f32 v[220:221], v[228:229], v[44:45], v[220:221]
	v_pk_fma_f32 v[222:223], v[230:231], v[44:45], v[222:223]
	v_cvt_pk_f32_fp8_sdwa v[224:225], v163 src0_sel:WORD_1
	v_cvt_pk_f32_fp8_sdwa v[226:227], v167 src0_sel:WORD_1
	v_cvt_pk_f32_fp8_sdwa v[228:229], v171 src0_sel:WORD_1
	v_cvt_pk_f32_fp8_sdwa v[230:231], v175 src0_sel:WORD_1
	v_pk_fma_f32 v[216:217], v[224:225], v[46:47], v[216:217]
	v_pk_fma_f32 v[218:219], v[226:227], v[46:47], v[218:219]
	v_pk_fma_f32 v[220:221], v[228:229], v[46:47], v[220:221]
	v_pk_fma_f32 v[222:223], v[230:231], v[46:47], v[222:223]
	s_branch .LU_s2_tail
.LU_s2_t3:
	v_cvt_pk_f32_fp8_e32 v[224:225], v160
	v_cvt_pk_f32_fp8_e32 v[226:227], v164
	v_cvt_pk_f32_fp8_e32 v[228:229], v168
	v_cvt_pk_f32_fp8_e32 v[230:231], v172
	v_pk_mul_f32 v[216:217], v[224:225], v[48:49]
	v_pk_mul_f32 v[218:219], v[226:227], v[48:49]
	v_pk_mul_f32 v[220:221], v[228:229], v[48:49]
	v_pk_mul_f32 v[222:223], v[230:231], v[48:49]
	v_cvt_pk_f32_fp8_sdwa v[224:225], v160 src0_sel:WORD_1
	v_cvt_pk_f32_fp8_sdwa v[226:227], v164 src0_sel:WORD_1
	v_cvt_pk_f32_fp8_sdwa v[228:229], v168 src0_sel:WORD_1
	v_cvt_pk_f32_fp8_sdwa v[230:231], v172 src0_sel:WORD_1
	v_pk_fma_f32 v[216:217], v[224:225], v[50:51], v[216:217]
	v_pk_fma_f32 v[218:219], v[226:227], v[50:51], v[218:219]
	v_pk_fma_f32 v[220:221], v[228:229], v[50:51], v[220:221]
	v_pk_fma_f32 v[222:223], v[230:231], v[50:51], v[222:223]
	v_cvt_pk_f32_fp8_e32 v[224:225], v161
	v_cvt_pk_f32_fp8_e32 v[226:227], v165
	v_cvt_pk_f32_fp8_e32 v[228:229], v169
	v_cvt_pk_f32_fp8_e32 v[230:231], v173
	v_pk_fma_f32 v[216:217], v[224:225], v[52:53], v[216:217]
	v_pk_fma_f32 v[218:219], v[226:227], v[52:53], v[218:219]
	v_pk_fma_f32 v[220:221], v[228:229], v[52:53], v[220:221]
	v_pk_fma_f32 v[222:223], v[230:231], v[52:53], v[222:223]
	v_cvt_pk_f32_fp8_sdwa v[224:225], v161 src0_sel:WORD_1
	v_cvt_pk_f32_fp8_sdwa v[226:227], v165 src0_sel:WORD_1
	v_cvt_pk_f32_fp8_sdwa v[228:229], v169 src0_sel:WORD_1
	v_cvt_pk_f32_fp8_sdwa v[230:231], v173 src0_sel:WORD_1
	v_pk_fma_f32 v[216:217], v[224:225], v[54:55], v[216:217]
	v_pk_fma_f32 v[218:219], v[226:227], v[54:55], v[218:219]
	v_pk_fma_f32 v[220:221], v[228:229], v[54:55], v[220:221]
	v_pk_fma_f32 v[222:223], v[230:231], v[54:55], v[222:223]
	v_cvt_pk_f32_fp8_e32 v[224:225], v162
	v_cvt_pk_f32_fp8_e32 v[226:227], v166
	v_cvt_pk_f32_fp8_e32 v[228:229], v170
	v_cvt_pk_f32_fp8_e32 v[230:231], v174
	v_pk_fma_f32 v[216:217], v[224:225], v[56:57], v[216:217]
	v_pk_fma_f32 v[218:219], v[226:227], v[56:57], v[218:219]
	v_pk_fma_f32 v[220:221], v[228:229], v[56:57], v[220:221]
	v_pk_fma_f32 v[222:223], v[230:231], v[56:57], v[222:223]
	v_cvt_pk_f32_fp8_sdwa v[224:225], v162 src0_sel:WORD_1
	v_cvt_pk_f32_fp8_sdwa v[226:227], v166 src0_sel:WORD_1
	v_cvt_pk_f32_fp8_sdwa v[228:229], v170 src0_sel:WORD_1
	v_cvt_pk_f32_fp8_sdwa v[230:231], v174 src0_sel:WORD_1
	v_pk_fma_f32 v[216:217], v[224:225], v[58:59], v[216:217]
	v_pk_fma_f32 v[218:219], v[226:227], v[58:59], v[218:219]
	v_pk_fma_f32 v[220:221], v[228:229], v[58:59], v[220:221]
	v_pk_fma_f32 v[222:223], v[230:231], v[58:59], v[222:223]
	v_cvt_pk_f32_fp8_e32 v[224:225], v163
	v_cvt_pk_f32_fp8_e32 v[226:227], v167
	v_cvt_pk_f32_fp8_e32 v[228:229], v171
	v_cvt_pk_f32_fp8_e32 v[230:231], v175
	v_pk_fma_f32 v[216:217], v[224:225], v[60:61], v[216:217]
	v_pk_fma_f32 v[218:219], v[226:227], v[60:61], v[218:219]
	v_pk_fma_f32 v[220:221], v[228:229], v[60:61], v[220:221]
	v_pk_fma_f32 v[222:223], v[230:231], v[60:61], v[222:223]
	v_cvt_pk_f32_fp8_sdwa v[224:225], v163 src0_sel:WORD_1
	v_cvt_pk_f32_fp8_sdwa v[226:227], v167 src0_sel:WORD_1
	v_cvt_pk_f32_fp8_sdwa v[228:229], v171 src0_sel:WORD_1
	v_cvt_pk_f32_fp8_sdwa v[230:231], v175 src0_sel:WORD_1
	v_pk_fma_f32 v[216:217], v[224:225], v[62:63], v[216:217]
	v_pk_fma_f32 v[218:219], v[226:227], v[62:63], v[218:219]
	v_pk_fma_f32 v[220:221], v[228:229], v[62:63], v[220:221]
	v_pk_fma_f32 v[222:223], v[230:231], v[62:63], v[222:223]
	s_branch .LU_s2_tail
.LU_s2_t4:
	v_cvt_pk_f32_fp8_e32 v[224:225], v160
	v_cvt_pk_f32_fp8_e32 v[226:227], v164
	v_cvt_pk_f32_fp8_e32 v[228:229], v168
	v_cvt_pk_f32_fp8_e32 v[230:231], v172
	v_pk_mul_f32 v[216:217], v[224:225], v[64:65]
	v_pk_mul_f32 v[218:219], v[226:227], v[64:65]
	v_pk_mul_f32 v[220:221], v[228:229], v[64:65]
	v_pk_mul_f32 v[222:223], v[230:231], v[64:65]
	v_cvt_pk_f32_fp8_sdwa v[224:225], v160 src0_sel:WORD_1
	v_cvt_pk_f32_fp8_sdwa v[226:227], v164 src0_sel:WORD_1
	v_cvt_pk_f32_fp8_sdwa v[228:229], v168 src0_sel:WORD_1
	v_cvt_pk_f32_fp8_sdwa v[230:231], v172 src0_sel:WORD_1
	v_pk_fma_f32 v[216:217], v[224:225], v[66:67], v[216:217]
	v_pk_fma_f32 v[218:219], v[226:227], v[66:67], v[218:219]
	v_pk_fma_f32 v[220:221], v[228:229], v[66:67], v[220:221]
	v_pk_fma_f32 v[222:223], v[230:231], v[66:67], v[222:223]
	v_cvt_pk_f32_fp8_e32 v[224:225], v161
	v_cvt_pk_f32_fp8_e32 v[226:227], v165
	v_cvt_pk_f32_fp8_e32 v[228:229], v169
	v_cvt_pk_f32_fp8_e32 v[230:231], v173
	v_pk_fma_f32 v[216:217], v[224:225], v[68:69], v[216:217]
	v_pk_fma_f32 v[218:219], v[226:227], v[68:69], v[218:219]
	v_pk_fma_f32 v[220:221], v[228:229], v[68:69], v[220:221]
	v_pk_fma_f32 v[222:223], v[230:231], v[68:69], v[222:223]
	v_cvt_pk_f32_fp8_sdwa v[224:225], v161 src0_sel:WORD_1
	v_cvt_pk_f32_fp8_sdwa v[226:227], v165 src0_sel:WORD_1
	v_cvt_pk_f32_fp8_sdwa v[228:229], v169 src0_sel:WORD_1
	v_cvt_pk_f32_fp8_sdwa v[230:231], v173 src0_sel:WORD_1
	v_pk_fma_f32 v[216:217], v[224:225], v[70:71], v[216:217]
	v_pk_fma_f32 v[218:219], v[226:227], v[70:71], v[218:219]
	v_pk_fma_f32 v[220:221], v[228:229], v[70:71], v[220:221]
	v_pk_fma_f32 v[222:223], v[230:231], v[70:71], v[222:223]
	v_cvt_pk_f32_fp8_e32 v[224:225], v162
	v_cvt_pk_f32_fp8_e32 v[226:227], v166
	v_cvt_pk_f32_fp8_e32 v[228:229], v170
	v_cvt_pk_f32_fp8_e32 v[230:231], v174
	v_pk_fma_f32 v[216:217], v[224:225], v[72:73], v[216:217]
	v_pk_fma_f32 v[218:219], v[226:227], v[72:73], v[218:219]
	v_pk_fma_f32 v[220:221], v[228:229], v[72:73], v[220:221]
	v_pk_fma_f32 v[222:223], v[230:231], v[72:73], v[222:223]
	v_cvt_pk_f32_fp8_sdwa v[224:225], v162 src0_sel:WORD_1
	v_cvt_pk_f32_fp8_sdwa v[226:227], v166 src0_sel:WORD_1
	v_cvt_pk_f32_fp8_sdwa v[228:229], v170 src0_sel:WORD_1
	v_cvt_pk_f32_fp8_sdwa v[230:231], v174 src0_sel:WORD_1
	v_pk_fma_f32 v[216:217], v[224:225], v[74:75], v[216:217]
	v_pk_fma_f32 v[218:219], v[226:227], v[74:75], v[218:219]
	v_pk_fma_f32 v[220:221], v[228:229], v[74:75], v[220:221]
	v_pk_fma_f32 v[222:223], v[230:231], v[74:75], v[222:223]
	v_cvt_pk_f32_fp8_e32 v[224:225], v163
	v_cvt_pk_f32_fp8_e32 v[226:227], v167
	v_cvt_pk_f32_fp8_e32 v[228:229], v171
	v_cvt_pk_f32_fp8_e32 v[230:231], v175
	v_pk_fma_f32 v[216:217], v[224:225], v[76:77], v[216:217]
	v_pk_fma_f32 v[218:219], v[226:227], v[76:77], v[218:219]
	v_pk_fma_f32 v[220:221], v[228:229], v[76:77], v[220:221]
	v_pk_fma_f32 v[222:223], v[230:231], v[76:77], v[222:223]
	v_cvt_pk_f32_fp8_sdwa v[224:225], v163 src0_sel:WORD_1
	v_cvt_pk_f32_fp8_sdwa v[226:227], v167 src0_sel:WORD_1
	v_cvt_pk_f32_fp8_sdwa v[228:229], v171 src0_sel:WORD_1
	v_cvt_pk_f32_fp8_sdwa v[230:231], v175 src0_sel:WORD_1
	v_pk_fma_f32 v[216:217], v[224:225], v[78:79], v[216:217]
	v_pk_fma_f32 v[218:219], v[226:227], v[78:79], v[218:219]
	v_pk_fma_f32 v[220:221], v[228:229], v[78:79], v[220:221]
	v_pk_fma_f32 v[222:223], v[230:231], v[78:79], v[222:223]
	s_branch .LU_s2_tail
.LU_s2_t5:
	v_cvt_pk_f32_fp8_e32 v[224:225], v160
	v_cvt_pk_f32_fp8_e32 v[226:227], v164
	v_cvt_pk_f32_fp8_e32 v[228:229], v168
	v_cvt_pk_f32_fp8_e32 v[230:231], v172
	v_pk_mul_f32 v[216:217], v[224:225], v[80:81]
	v_pk_mul_f32 v[218:219], v[226:227], v[80:81]
	v_pk_mul_f32 v[220:221], v[228:229], v[80:81]
	v_pk_mul_f32 v[222:223], v[230:231], v[80:81]
	v_cvt_pk_f32_fp8_sdwa v[224:225], v160 src0_sel:WORD_1
	v_cvt_pk_f32_fp8_sdwa v[226:227], v164 src0_sel:WORD_1
	v_cvt_pk_f32_fp8_sdwa v[228:229], v168 src0_sel:WORD_1
	v_cvt_pk_f32_fp8_sdwa v[230:231], v172 src0_sel:WORD_1
	v_pk_fma_f32 v[216:217], v[224:225], v[82:83], v[216:217]
	v_pk_fma_f32 v[218:219], v[226:227], v[82:83], v[218:219]
	v_pk_fma_f32 v[220:221], v[228:229], v[82:83], v[220:221]
	v_pk_fma_f32 v[222:223], v[230:231], v[82:83], v[222:223]
	v_cvt_pk_f32_fp8_e32 v[224:225], v161
	v_cvt_pk_f32_fp8_e32 v[226:227], v165
	v_cvt_pk_f32_fp8_e32 v[228:229], v169
	v_cvt_pk_f32_fp8_e32 v[230:231], v173
	v_pk_fma_f32 v[216:217], v[224:225], v[84:85], v[216:217]
	v_pk_fma_f32 v[218:219], v[226:227], v[84:85], v[218:219]
	v_pk_fma_f32 v[220:221], v[228:229], v[84:85], v[220:221]
	v_pk_fma_f32 v[222:223], v[230:231], v[84:85], v[222:223]
	v_cvt_pk_f32_fp8_sdwa v[224:225], v161 src0_sel:WORD_1
	v_cvt_pk_f32_fp8_sdwa v[226:227], v165 src0_sel:WORD_1
	v_cvt_pk_f32_fp8_sdwa v[228:229], v169 src0_sel:WORD_1
	v_cvt_pk_f32_fp8_sdwa v[230:231], v173 src0_sel:WORD_1
	v_pk_fma_f32 v[216:217], v[224:225], v[86:87], v[216:217]
	v_pk_fma_f32 v[218:219], v[226:227], v[86:87], v[218:219]
	v_pk_fma_f32 v[220:221], v[228:229], v[86:87], v[220:221]
	v_pk_fma_f32 v[222:223], v[230:231], v[86:87], v[222:223]
	v_cvt_pk_f32_fp8_e32 v[224:225], v162
	v_cvt_pk_f32_fp8_e32 v[226:227], v166
	v_cvt_pk_f32_fp8_e32 v[228:229], v170
	v_cvt_pk_f32_fp8_e32 v[230:231], v174
	v_pk_fma_f32 v[216:217], v[224:225], v[88:89], v[216:217]
	v_pk_fma_f32 v[218:219], v[226:227], v[88:89], v[218:219]
	v_pk_fma_f32 v[220:221], v[228:229], v[88:89], v[220:221]
	v_pk_fma_f32 v[222:223], v[230:231], v[88:89], v[222:223]
	v_cvt_pk_f32_fp8_sdwa v[224:225], v162 src0_sel:WORD_1
	v_cvt_pk_f32_fp8_sdwa v[226:227], v166 src0_sel:WORD_1
	v_cvt_pk_f32_fp8_sdwa v[228:229], v170 src0_sel:WORD_1
	v_cvt_pk_f32_fp8_sdwa v[230:231], v174 src0_sel:WORD_1
	v_pk_fma_f32 v[216:217], v[224:225], v[90:91], v[216:217]
	v_pk_fma_f32 v[218:219], v[226:227], v[90:91], v[218:219]
	v_pk_fma_f32 v[220:221], v[228:229], v[90:91], v[220:221]
	v_pk_fma_f32 v[222:223], v[230:231], v[90:91], v[222:223]
	v_cvt_pk_f32_fp8_e32 v[224:225], v163
	v_cvt_pk_f32_fp8_e32 v[226:227], v167
	v_cvt_pk_f32_fp8_e32 v[228:229], v171
	v_cvt_pk_f32_fp8_e32 v[230:231], v175
	v_pk_fma_f32 v[216:217], v[224:225], v[92:93], v[216:217]
	v_pk_fma_f32 v[218:219], v[226:227], v[92:93], v[218:219]
	v_pk_fma_f32 v[220:221], v[228:229], v[92:93], v[220:221]
	v_pk_fma_f32 v[222:223], v[230:231], v[92:93], v[222:223]
	v_cvt_pk_f32_fp8_sdwa v[224:225], v163 src0_sel:WORD_1
	v_cvt_pk_f32_fp8_sdwa v[226:227], v167 src0_sel:WORD_1
	v_cvt_pk_f32_fp8_sdwa v[228:229], v171 src0_sel:WORD_1
	v_cvt_pk_f32_fp8_sdwa v[230:231], v175 src0_sel:WORD_1
	v_pk_fma_f32 v[216:217], v[224:225], v[94:95], v[216:217]
	v_pk_fma_f32 v[218:219], v[226:227], v[94:95], v[218:219]
	v_pk_fma_f32 v[220:221], v[228:229], v[94:95], v[220:221]
	v_pk_fma_f32 v[222:223], v[230:231], v[94:95], v[222:223]
	s_branch .LU_s2_tail
.LU_s2_t6:
	v_cvt_pk_f32_fp8_e32 v[224:225], v160
	v_cvt_pk_f32_fp8_e32 v[226:227], v164
	v_cvt_pk_f32_fp8_e32 v[228:229], v168
	v_cvt_pk_f32_fp8_e32 v[230:231], v172
	v_pk_mul_f32 v[216:217], v[224:225], v[96:97]
	v_pk_mul_f32 v[218:219], v[226:227], v[96:97]
	v_pk_mul_f32 v[220:221], v[228:229], v[96:97]
	v_pk_mul_f32 v[222:223], v[230:231], v[96:97]
	v_cvt_pk_f32_fp8_sdwa v[224:225], v160 src0_sel:WORD_1
	v_cvt_pk_f32_fp8_sdwa v[226:227], v164 src0_sel:WORD_1
	v_cvt_pk_f32_fp8_sdwa v[228:229], v168 src0_sel:WORD_1
	v_cvt_pk_f32_fp8_sdwa v[230:231], v172 src0_sel:WORD_1
	v_pk_fma_f32 v[216:217], v[224:225], v[98:99], v[216:217]
	v_pk_fma_f32 v[218:219], v[226:227], v[98:99], v[218:219]
	v_pk_fma_f32 v[220:221], v[228:229], v[98:99], v[220:221]
	v_pk_fma_f32 v[222:223], v[230:231], v[98:99], v[222:223]
	v_cvt_pk_f32_fp8_e32 v[224:225], v161
	v_cvt_pk_f32_fp8_e32 v[226:227], v165
	v_cvt_pk_f32_fp8_e32 v[228:229], v169
	v_cvt_pk_f32_fp8_e32 v[230:231], v173
	v_pk_fma_f32 v[216:217], v[224:225], v[100:101], v[216:217]
	v_pk_fma_f32 v[218:219], v[226:227], v[100:101], v[218:219]
	v_pk_fma_f32 v[220:221], v[228:229], v[100:101], v[220:221]
	v_pk_fma_f32 v[222:223], v[230:231], v[100:101], v[222:223]
	v_cvt_pk_f32_fp8_sdwa v[224:225], v161 src0_sel:WORD_1
	v_cvt_pk_f32_fp8_sdwa v[226:227], v165 src0_sel:WORD_1
	v_cvt_pk_f32_fp8_sdwa v[228:229], v169 src0_sel:WORD_1
	v_cvt_pk_f32_fp8_sdwa v[230:231], v173 src0_sel:WORD_1
	v_pk_fma_f32 v[216:217], v[224:225], v[102:103], v[216:217]
	v_pk_fma_f32 v[218:219], v[226:227], v[102:103], v[218:219]
	v_pk_fma_f32 v[220:221], v[228:229], v[102:103], v[220:221]
	v_pk_fma_f32 v[222:223], v[230:231], v[102:103], v[222:223]
	v_cvt_pk_f32_fp8_e32 v[224:225], v162
	v_cvt_pk_f32_fp8_e32 v[226:227], v166
	v_cvt_pk_f32_fp8_e32 v[228:229], v170
	v_cvt_pk_f32_fp8_e32 v[230:231], v174
	v_pk_fma_f32 v[216:217], v[224:225], v[104:105], v[216:217]
	v_pk_fma_f32 v[218:219], v[226:227], v[104:105], v[218:219]
	v_pk_fma_f32 v[220:221], v[228:229], v[104:105], v[220:221]
	v_pk_fma_f32 v[222:223], v[230:231], v[104:105], v[222:223]
	v_cvt_pk_f32_fp8_sdwa v[224:225], v162 src0_sel:WORD_1
	v_cvt_pk_f32_fp8_sdwa v[226:227], v166 src0_sel:WORD_1
	v_cvt_pk_f32_fp8_sdwa v[228:229], v170 src0_sel:WORD_1
	v_cvt_pk_f32_fp8_sdwa v[230:231], v174 src0_sel:WORD_1
	v_pk_fma_f32 v[216:217], v[224:225], v[106:107], v[216:217]
	v_pk_fma_f32 v[218:219], v[226:227], v[106:107], v[218:219]
	v_pk_fma_f32 v[220:221], v[228:229], v[106:107], v[220:221]
	v_pk_fma_f32 v[222:223], v[230:231], v[106:107], v[222:223]
	v_cvt_pk_f32_fp8_e32 v[224:225], v163
	v_cvt_pk_f32_fp8_e32 v[226:227], v167
	v_cvt_pk_f32_fp8_e32 v[228:229], v171
	v_cvt_pk_f32_fp8_e32 v[230:231], v175
	v_pk_fma_f32 v[216:217], v[224:225], v[108:109], v[216:217]
	v_pk_fma_f32 v[218:219], v[226:227], v[108:109], v[218:219]
	v_pk_fma_f32 v[220:221], v[228:229], v[108:109], v[220:221]
	v_pk_fma_f32 v[222:223], v[230:231], v[108:109], v[222:223]
	v_cvt_pk_f32_fp8_sdwa v[224:225], v163 src0_sel:WORD_1
	v_cvt_pk_f32_fp8_sdwa v[226:227], v167 src0_sel:WORD_1
	v_cvt_pk_f32_fp8_sdwa v[228:229], v171 src0_sel:WORD_1
	v_cvt_pk_f32_fp8_sdwa v[230:231], v175 src0_sel:WORD_1
	v_pk_fma_f32 v[216:217], v[224:225], v[110:111], v[216:217]
	v_pk_fma_f32 v[218:219], v[226:227], v[110:111], v[218:219]
	v_pk_fma_f32 v[220:221], v[228:229], v[110:111], v[220:221]
	v_pk_fma_f32 v[222:223], v[230:231], v[110:111], v[222:223]
	s_branch .LU_s2_tail
.LU_s2_t7:
	v_cvt_pk_f32_fp8_e32 v[224:225], v160
	v_cvt_pk_f32_fp8_e32 v[226:227], v164
	v_cvt_pk_f32_fp8_e32 v[228:229], v168
	v_cvt_pk_f32_fp8_e32 v[230:231], v172
	v_pk_mul_f32 v[216:217], v[224:225], v[112:113]
	v_pk_mul_f32 v[218:219], v[226:227], v[112:113]
	v_pk_mul_f32 v[220:221], v[228:229], v[112:113]
	v_pk_mul_f32 v[222:223], v[230:231], v[112:113]
	v_cvt_pk_f32_fp8_sdwa v[224:225], v160 src0_sel:WORD_1
	v_cvt_pk_f32_fp8_sdwa v[226:227], v164 src0_sel:WORD_1
	v_cvt_pk_f32_fp8_sdwa v[228:229], v168 src0_sel:WORD_1
	v_cvt_pk_f32_fp8_sdwa v[230:231], v172 src0_sel:WORD_1
	v_pk_fma_f32 v[216:217], v[224:225], v[114:115], v[216:217]
	v_pk_fma_f32 v[218:219], v[226:227], v[114:115], v[218:219]
	v_pk_fma_f32 v[220:221], v[228:229], v[114:115], v[220:221]
	v_pk_fma_f32 v[222:223], v[230:231], v[114:115], v[222:223]
	v_cvt_pk_f32_fp8_e32 v[224:225], v161
	v_cvt_pk_f32_fp8_e32 v[226:227], v165
	v_cvt_pk_f32_fp8_e32 v[228:229], v169
	v_cvt_pk_f32_fp8_e32 v[230:231], v173
	v_pk_fma_f32 v[216:217], v[224:225], v[116:117], v[216:217]
	v_pk_fma_f32 v[218:219], v[226:227], v[116:117], v[218:219]
	v_pk_fma_f32 v[220:221], v[228:229], v[116:117], v[220:221]
	v_pk_fma_f32 v[222:223], v[230:231], v[116:117], v[222:223]
	v_cvt_pk_f32_fp8_sdwa v[224:225], v161 src0_sel:WORD_1
	v_cvt_pk_f32_fp8_sdwa v[226:227], v165 src0_sel:WORD_1
	v_cvt_pk_f32_fp8_sdwa v[228:229], v169 src0_sel:WORD_1
	v_cvt_pk_f32_fp8_sdwa v[230:231], v173 src0_sel:WORD_1
	v_pk_fma_f32 v[216:217], v[224:225], v[118:119], v[216:217]
	v_pk_fma_f32 v[218:219], v[226:227], v[118:119], v[218:219]
	v_pk_fma_f32 v[220:221], v[228:229], v[118:119], v[220:221]
	v_pk_fma_f32 v[222:223], v[230:231], v[118:119], v[222:223]
	v_cvt_pk_f32_fp8_e32 v[224:225], v162
	v_cvt_pk_f32_fp8_e32 v[226:227], v166
	v_cvt_pk_f32_fp8_e32 v[228:229], v170
	v_cvt_pk_f32_fp8_e32 v[230:231], v174
	v_pk_fma_f32 v[216:217], v[224:225], v[120:121], v[216:217]
	v_pk_fma_f32 v[218:219], v[226:227], v[120:121], v[218:219]
	v_pk_fma_f32 v[220:221], v[228:229], v[120:121], v[220:221]
	v_pk_fma_f32 v[222:223], v[230:231], v[120:121], v[222:223]
	v_cvt_pk_f32_fp8_sdwa v[224:225], v162 src0_sel:WORD_1
	v_cvt_pk_f32_fp8_sdwa v[226:227], v166 src0_sel:WORD_1
	v_cvt_pk_f32_fp8_sdwa v[228:229], v170 src0_sel:WORD_1
	v_cvt_pk_f32_fp8_sdwa v[230:231], v174 src0_sel:WORD_1
	v_pk_fma_f32 v[216:217], v[224:225], v[122:123], v[216:217]
	v_pk_fma_f32 v[218:219], v[226:227], v[122:123], v[218:219]
	v_pk_fma_f32 v[220:221], v[228:229], v[122:123], v[220:221]
	v_pk_fma_f32 v[222:223], v[230:231], v[122:123], v[222:223]
	v_cvt_pk_f32_fp8_e32 v[224:225], v163
	v_cvt_pk_f32_fp8_e32 v[226:227], v167
	v_cvt_pk_f32_fp8_e32 v[228:229], v171
	v_cvt_pk_f32_fp8_e32 v[230:231], v175
	v_pk_fma_f32 v[216:217], v[224:225], v[124:125], v[216:217]
	v_pk_fma_f32 v[218:219], v[226:227], v[124:125], v[218:219]
	v_pk_fma_f32 v[220:221], v[228:229], v[124:125], v[220:221]
	v_pk_fma_f32 v[222:223], v[230:231], v[124:125], v[222:223]
	v_cvt_pk_f32_fp8_sdwa v[224:225], v163 src0_sel:WORD_1
	v_cvt_pk_f32_fp8_sdwa v[226:227], v167 src0_sel:WORD_1
	v_cvt_pk_f32_fp8_sdwa v[228:229], v171 src0_sel:WORD_1
	v_cvt_pk_f32_fp8_sdwa v[230:231], v175 src0_sel:WORD_1
	v_pk_fma_f32 v[216:217], v[224:225], v[126:127], v[216:217]
	v_pk_fma_f32 v[218:219], v[226:227], v[126:127], v[218:219]
	v_pk_fma_f32 v[220:221], v[228:229], v[126:127], v[220:221]
	v_pk_fma_f32 v[222:223], v[230:231], v[126:127], v[222:223]
.LU_s2_tail:
	v_add_f32_e32 v216, v216, v217
	v_add_f32_e32 v220, v220, v221
	v_add_f32_e32 v218, v218, v219
	v_add_f32_e32 v222, v222, v223
	s_nop 0
	v_permlane32_swap_b32_e32 v216, v220
	s_nop 0
	v_permlane32_swap_b32_e32 v218, v222
	v_add_f32_e32 v216, v216, v220
	v_add_f32_e32 v218, v218, v222
	s_nop 1
	v_permlane16_swap_b32_e32 v216, v218
	v_add_f32_e32 v216, v216, v218
	s_nop 1
	v_add_f32_dpp v216, v216, v216 quad_perm:[1,0,3,2] row_mask:0xf bank_mask:0xf bound_ctrl:1
	s_nop 1
	v_add_f32_dpp v216, v216, v216 quad_perm:[2,3,0,1] row_mask:0xf bank_mask:0xf bound_ctrl:1
	s_nop 1
	v_add_f32_dpp v216, v216, v216 row_half_mirror row_mask:0xf bank_mask:0xf bound_ctrl:1
	s_nop 1
	v_add_f32_dpp v216, v216, v216 row_mirror row_mask:0xf bank_mask:0xf bound_ctrl:1
	v_mul_f32_e32 v217, v250, v216
	v_fma_f32 v218, |v217|, s72, 1.0
	v_mul_f32_e32 v219, v217, v217
	v_rcp_f32_e32 v218, v218
	v_mul_f32_e32 v219, 0xbf38aa3b, v219
	v_exp_f32_e32 v219, v219
	v_fmamk_f32 v220, v218, 0x3f07dc22, v242
	v_fmaak_f32 v220, v218, v220, 0x3f35f0e3
	v_fmaak_f32 v220, v218, v220, 0xbe11a98e
	v_fmaak_f32 v220, v218, v220, 0x3e027906
	v_mul_f32_e32 v220, v218, v220
	v_mul_f32_e32 v220, v219, v220
	v_mul_f32_e32 v221, v217, v220
	v_fma_f32 v220, -v217, v220, v217
	v_cmp_gt_f32_e32 vcc, 0, v217
	v_lshrrev_b32_e32 v254, 3, v238
	s_nop 0
	v_cndmask_b32_e32 v220, v220, v221, vcc
	v_mul_f32_e32 v220, v237, v220
	v_mul_f32_e32 v220, v210, v220
	ds_write_b32 v254, v220
	ds_read_b128 v[236:239], v241 offset:192
	ds_read_b128 v[232:235], v241 offset:448
	s_add_i32 s21, s21, 1
.LU_s3:
	s_cmp_ge_u32 s21, s20
	s_cbranch_scc1 .LU_done
	s_waitcnt lgkmcnt(0)
	v_readlane_b32 s64, v232, 0
	v_readlane_b32 s65, v232, 16
	v_readlane_b32 s66, v232, 32
	v_readlane_b32 s67, v232, 48
	v_lshrrev_b32_e32 v253, 8, v232
	s_add_u32 s24, s4, s64
	s_addc_u32 s25, s5, 0
	s_add_u32 s26, s4, s65
	s_addc_u32 s27, s5, 0
	s_add_u32 s28, s4, s66
	s_addc_u32 s29, s5, 0
	s_add_u32 s30, s4, s67
	s_addc_u32 s31, s5, 0
	global_load_dwordx4 v[160:163], v240, s[24:25]
	global_load_dwordx4 v[164:167], v240, s[26:27]
	global_load_dwordx4 v[168:171], v240, s[28:29]
	global_load_dwordx4 v[172:175], v240, s[30:31]
	global_load_dword v250, v253, s[8:9]
	global_load_dword v210, v253, s[52:53]
	v_readfirstlane_b32 s23, v238
	s_and_b32 s23, s23, 7
	s_waitcnt vmcnt(24)
	s_cmp_ge_u32 s23, 4
	s_cbranch_scc1 .LU_s3_h
	s_cmp_ge_u32 s23, 2
	s_cbranch_scc1 .LU_s3_23
	s_cmp_eq_u32 s23, 0
	s_cbranch_scc1 .LU_s3_t0
	s_branch .LU_s3_t1

.LU_s3_t0:
	v_cvt_pk_f32_fp8_e32 v[224:225], v176
	v_cvt_pk_f32_fp8_e32 v[226:227], v180
	v_cvt_pk_f32_fp8_e32 v[228:229], v184
	v_cvt_pk_f32_fp8_e32 v[230:231], v188
	v_pk_mul_f32 v[216:217], v[224:225], v[0:1]
	v_pk_mul_f32 v[218:219], v[226:227], v[0:1]
	v_pk_mul_f32 v[220:221], v[228:229], v[0:1]
	v_pk_mul_f32 v[222:223], v[230:231], v[0:1]
	v_cvt_pk_f32_fp8_sdwa v[224:225], v176 src0_sel:WORD_1
	v_cvt_pk_f32_fp8_sdwa v[226:227], v180 src0_sel:WORD_1
	v_cvt_pk_f32_fp8_sdwa v[228:229], v184 src0_sel:WORD_1
	v_cvt_pk_f32_fp8_sdwa v[230:231], v188 src0_sel:WORD_1
	v_pk_fma_f32 v[216:217], v[224:225], v[2:3], v[216:217]
	v_pk_fma_f32 v[218:219], v[226:227], v[2:3], v[218:219]
	v_pk_fma_f32 v[220:221], v[228:229], v[2:3], v[220:221]
	v_pk_fma_f32 v[222:223], v[230:231], v[2:3], v[222:223]
	v_cvt_pk_f32_fp8_e32 v[224:225], v177
	v_cvt_pk_f32_fp8_e32 v[226:227], v181
	v_cvt_pk_f32_fp8_e32 v[228:229], v185
	v_cvt_pk_f32_fp8_e32 v[230:231], v189
	v_pk_fma_f32 v[216:217], v[224:225], v[4:5], v[216:217]
	v_pk_fma_f32 v[218:219], v[226:227], v[4:5], v[218:219]
	v_pk_fma_f32 v[220:221], v[228:229], v[4:5], v[220:221]
	v_pk_fma_f32 v[222:223], v[230:231], v[4:5], v[222:223]
	v_cvt_pk_f32_fp8_sdwa v[224:225], v177 src0_sel:WORD_1
	v_cvt_pk_f32_fp8_sdwa v[226:227], v181 src0_sel:WORD_1
	v_cvt_pk_f32_fp8_sdwa v[228:229], v185 src0_sel:WORD_1
	v_cvt_pk_f32_fp8_sdwa v[230:231], v189 src0_sel:WORD_1
	v_pk_fma_f32 v[216:217], v[224:225], v[6:7], v[216:217]
	v_pk_fma_f32 v[218:219], v[226:227], v[6:7], v[218:219]
	v_pk_fma_f32 v[220:221], v[228:229], v[6:7], v[220:221]
	v_pk_fma_f32 v[222:223], v[230:231], v[6:7], v[222:223]
	v_cvt_pk_f32_fp8_e32 v[224:225], v178
	v_cvt_pk_f32_fp8_e32 v[226:227], v182
	v_cvt_pk_f32_fp8_e32 v[228:229], v186
	v_cvt_pk_f32_fp8_e32 v[230:231], v190
	v_pk_fma_f32 v[216:217], v[224:225], v[8:9], v[216:217]
	v_pk_fma_f32 v[218:219], v[226:227], v[8:9], v[218:219]
	v_pk_fma_f32 v[220:221], v[228:229], v[8:9], v[220:221]
	v_pk_fma_f32 v[222:223], v[230:231], v[8:9], v[222:223]
	v_cvt_pk_f32_fp8_sdwa v[224:225], v178 src0_sel:WORD_1
	v_cvt_pk_f32_fp8_sdwa v[226:227], v182 src0_sel:WORD_1
	v_cvt_pk_f32_fp8_sdwa v[228:229], v186 src0_sel:WORD_1
	v_cvt_pk_f32_fp8_sdwa v[230:231], v190 src0_sel:WORD_1
	v_pk_fma_f32 v[216:217], v[224:225], v[10:11], v[216:217]
	v_pk_fma_f32 v[218:219], v[226:227], v[10:11], v[218:219]
	v_pk_fma_f32 v[220:221], v[228:229], v[10:11], v[220:221]
	v_pk_fma_f32 v[222:223], v[230:231], v[10:11], v[222:223]
	v_cvt_pk_f32_fp8_e32 v[224:225], v179
	v_cvt_pk_f32_fp8_e32 v[226:227], v183
	v_cvt_pk_f32_fp8_e32 v[228:229], v187
	v_cvt_pk_f32_fp8_e32 v[230:231], v191
	v_pk_fma_f32 v[216:217], v[224:225], v[12:13], v[216:217]
	v_pk_fma_f32 v[218:219], v[226:227], v[12:13], v[218:219]
	v_pk_fma_f32 v[220:221], v[228:229], v[12:13], v[220:221]
	v_pk_fma_f32 v[222:223], v[230:231], v[12:13], v[222:223]
	v_cvt_pk_f32_fp8_sdwa v[224:225], v179 src0_sel:WORD_1
	v_cvt_pk_f32_fp8_sdwa v[226:227], v183 src0_sel:WORD_1
	v_cvt_pk_f32_fp8_sdwa v[228:229], v187 src0_sel:WORD_1
	v_cvt_pk_f32_fp8_sdwa v[230:231], v191 src0_sel:WORD_1
	v_pk_fma_f32 v[216:217], v[224:225], v[14:15], v[216:217]
	v_pk_fma_f32 v[218:219], v[226:227], v[14:15], v[218:219]
	v_pk_fma_f32 v[220:221], v[228:229], v[14:15], v[220:221]
	v_pk_fma_f32 v[222:223], v[230:231], v[14:15], v[222:223]
	s_branch .LU_s3_tail
.LU_s3_t1:
	v_cvt_pk_f32_fp8_e32 v[224:225], v176
	v_cvt_pk_f32_fp8_e32 v[226:227], v180
	v_cvt_pk_f32_fp8_e32 v[228:229], v184
	v_cvt_pk_f32_fp8_e32 v[230:231], v188
	v_pk_mul_f32 v[216:217], v[224:225], v[16:17]
	v_pk_mul_f32 v[218:219], v[226:227], v[16:17]
	v_pk_mul_f32 v[220:221], v[228:229], v[16:17]
	v_pk_mul_f32 v[222:223], v[230:231], v[16:17]
	v_cvt_pk_f32_fp8_sdwa v[224:225], v176 src0_sel:WORD_1
	v_cvt_pk_f32_fp8_sdwa v[226:227], v180 src0_sel:WORD_1
	v_cvt_pk_f32_fp8_sdwa v[228:229], v184 src0_sel:WORD_1
	v_cvt_pk_f32_fp8_sdwa v[230:231], v188 src0_sel:WORD_1
	v_pk_fma_f32 v[216:217], v[224:225], v[18:19], v[216:217]
	v_pk_fma_f32 v[218:219], v[226:227], v[18:19], v[218:219]
	v_pk_fma_f32 v[220:221], v[228:229], v[18:19], v[220:221]
	v_pk_fma_f32 v[222:223], v[230:231], v[18:19], v[222:223]
	v_cvt_pk_f32_fp8_e32 v[224:225], v177
	v_cvt_pk_f32_fp8_e32 v[226:227], v181
	v_cvt_pk_f32_fp8_e32 v[228:229], v185
	v_cvt_pk_f32_fp8_e32 v[230:231], v189
	v_pk_fma_f32 v[216:217], v[224:225], v[20:21], v[216:217]
	v_pk_fma_f32 v[218:219], v[226:227], v[20:21], v[218:219]
	v_pk_fma_f32 v[220:221], v[228:229], v[20:21], v[220:221]
	v_pk_fma_f32 v[222:223], v[230:231], v[20:21], v[222:223]
	v_cvt_pk_f32_fp8_sdwa v[224:225], v177 src0_sel:WORD_1
	v_cvt_pk_f32_fp8_sdwa v[226:227], v181 src0_sel:WORD_1
	v_cvt_pk_f32_fp8_sdwa v[228:229], v185 src0_sel:WORD_1
	v_cvt_pk_f32_fp8_sdwa v[230:231], v189 src0_sel:WORD_1
	v_pk_fma_f32 v[216:217], v[224:225], v[22:23], v[216:217]
	v_pk_fma_f32 v[218:219], v[226:227], v[22:23], v[218:219]
	v_pk_fma_f32 v[220:221], v[228:229], v[22:23], v[220:221]
	v_pk_fma_f32 v[222:223], v[230:231], v[22:23], v[222:223]
	v_cvt_pk_f32_fp8_e32 v[224:225], v178
	v_cvt_pk_f32_fp8_e32 v[226:227], v182
	v_cvt_pk_f32_fp8_e32 v[228:229], v186
	v_cvt_pk_f32_fp8_e32 v[230:231], v190
	v_pk_fma_f32 v[216:217], v[224:225], v[24:25], v[216:217]
	v_pk_fma_f32 v[218:219], v[226:227], v[24:25], v[218:219]
	v_pk_fma_f32 v[220:221], v[228:229], v[24:25], v[220:221]
	v_pk_fma_f32 v[222:223], v[230:231], v[24:25], v[222:223]
	v_cvt_pk_f32_fp8_sdwa v[224:225], v178 src0_sel:WORD_1
	v_cvt_pk_f32_fp8_sdwa v[226:227], v182 src0_sel:WORD_1
	v_cvt_pk_f32_fp8_sdwa v[228:229], v186 src0_sel:WORD_1
	v_cvt_pk_f32_fp8_sdwa v[230:231], v190 src0_sel:WORD_1
	v_pk_fma_f32 v[216:217], v[224:225], v[26:27], v[216:217]
	v_pk_fma_f32 v[218:219], v[226:227], v[26:27], v[218:219]
	v_pk_fma_f32 v[220:221], v[228:229], v[26:27], v[220:221]
	v_pk_fma_f32 v[222:223], v[230:231], v[26:27], v[222:223]
	v_cvt_pk_f32_fp8_e32 v[224:225], v179
	v_cvt_pk_f32_fp8_e32 v[226:227], v183
	v_cvt_pk_f32_fp8_e32 v[228:229], v187
	v_cvt_pk_f32_fp8_e32 v[230:231], v191
	v_pk_fma_f32 v[216:217], v[224:225], v[28:29], v[216:217]
	v_pk_fma_f32 v[218:219], v[226:227], v[28:29], v[218:219]
	v_pk_fma_f32 v[220:221], v[228:229], v[28:29], v[220:221]
	v_pk_fma_f32 v[222:223], v[230:231], v[28:29], v[222:223]
	v_cvt_pk_f32_fp8_sdwa v[224:225], v179 src0_sel:WORD_1
	v_cvt_pk_f32_fp8_sdwa v[226:227], v183 src0_sel:WORD_1
	v_cvt_pk_f32_fp8_sdwa v[228:229], v187 src0_sel:WORD_1
	v_cvt_pk_f32_fp8_sdwa v[230:231], v191 src0_sel:WORD_1
	v_pk_fma_f32 v[216:217], v[224:225], v[30:31], v[216:217]
	v_pk_fma_f32 v[218:219], v[226:227], v[30:31], v[218:219]
	v_pk_fma_f32 v[220:221], v[228:229], v[30:31], v[220:221]
	v_pk_fma_f32 v[222:223], v[230:231], v[30:31], v[222:223]
	s_branch .LU_s3_tail
.LU_s3_t2:
	v_cvt_pk_f32_fp8_e32 v[224:225], v176
	v_cvt_pk_f32_fp8_e32 v[226:227], v180
	v_cvt_pk_f32_fp8_e32 v[228:229], v184
	v_cvt_pk_f32_fp8_e32 v[230:231], v188
	v_pk_mul_f32 v[216:217], v[224:225], v[32:33]
	v_pk_mul_f32 v[218:219], v[226:227], v[32:33]
	v_pk_mul_f32 v[220:221], v[228:229], v[32:33]
	v_pk_mul_f32 v[222:223], v[230:231], v[32:33]
	v_cvt_pk_f32_fp8_sdwa v[224:225], v176 src0_sel:WORD_1
	v_cvt_pk_f32_fp8_sdwa v[226:227], v180 src0_sel:WORD_1
	v_cvt_pk_f32_fp8_sdwa v[228:229], v184 src0_sel:WORD_1
	v_cvt_pk_f32_fp8_sdwa v[230:231], v188 src0_sel:WORD_1
	v_pk_fma_f32 v[216:217], v[224:225], v[34:35], v[216:217]
	v_pk_fma_f32 v[218:219], v[226:227], v[34:35], v[218:219]
	v_pk_fma_f32 v[220:221], v[228:229], v[34:35], v[220:221]
	v_pk_fma_f32 v[222:223], v[230:231], v[34:35], v[222:223]
	v_cvt_pk_f32_fp8_e32 v[224:225], v177
	v_cvt_pk_f32_fp8_e32 v[226:227], v181
	v_cvt_pk_f32_fp8_e32 v[228:229], v185
	v_cvt_pk_f32_fp8_e32 v[230:231], v189
	v_pk_fma_f32 v[216:217], v[224:225], v[36:37], v[216:217]
	v_pk_fma_f32 v[218:219], v[226:227], v[36:37], v[218:219]
	v_pk_fma_f32 v[220:221], v[228:229], v[36:37], v[220:221]
	v_pk_fma_f32 v[222:223], v[230:231], v[36:37], v[222:223]
	v_cvt_pk_f32_fp8_sdwa v[224:225], v177 src0_sel:WORD_1
	v_cvt_pk_f32_fp8_sdwa v[226:227], v181 src0_sel:WORD_1
	v_cvt_pk_f32_fp8_sdwa v[228:229], v185 src0_sel:WORD_1
	v_cvt_pk_f32_fp8_sdwa v[230:231], v189 src0_sel:WORD_1
	v_pk_fma_f32 v[216:217], v[224:225], v[38:39], v[216:217]
	v_pk_fma_f32 v[218:219], v[226:227], v[38:39], v[218:219]
	v_pk_fma_f32 v[220:221], v[228:229], v[38:39], v[220:221]
	v_pk_fma_f32 v[222:223], v[230:231], v[38:39], v[222:223]
	v_cvt_pk_f32_fp8_e32 v[224:225], v178
	v_cvt_pk_f32_fp8_e32 v[226:227], v182
	v_cvt_pk_f32_fp8_e32 v[228:229], v186
	v_cvt_pk_f32_fp8_e32 v[230:231], v190
	v_pk_fma_f32 v[216:217], v[224:225], v[40:41], v[216:217]
	v_pk_fma_f32 v[218:219], v[226:227], v[40:41], v[218:219]
	v_pk_fma_f32 v[220:221], v[228:229], v[40:41], v[220:221]
	v_pk_fma_f32 v[222:223], v[230:231], v[40:41], v[222:223]
	v_cvt_pk_f32_fp8_sdwa v[224:225], v178 src0_sel:WORD_1
	v_cvt_pk_f32_fp8_sdwa v[226:227], v182 src0_sel:WORD_1
	v_cvt_pk_f32_fp8_sdwa v[228:229], v186 src0_sel:WORD_1
	v_cvt_pk_f32_fp8_sdwa v[230:231], v190 src0_sel:WORD_1
	v_pk_fma_f32 v[216:217], v[224:225], v[42:43], v[216:217]
	v_pk_fma_f32 v[218:219], v[226:227], v[42:43], v[218:219]
	v_pk_fma_f32 v[220:221], v[228:229], v[42:43], v[220:221]
	v_pk_fma_f32 v[222:223], v[230:231], v[42:43], v[222:223]
	v_cvt_pk_f32_fp8_e32 v[224:225], v179
	v_cvt_pk_f32_fp8_e32 v[226:227], v183
	v_cvt_pk_f32_fp8_e32 v[228:229], v187
	v_cvt_pk_f32_fp8_e32 v[230:231], v191
	v_pk_fma_f32 v[216:217], v[224:225], v[44:45], v[216:217]
	v_pk_fma_f32 v[218:219], v[226:227], v[44:45], v[218:219]
	v_pk_fma_f32 v[220:221], v[228:229], v[44:45], v[220:221]
	v_pk_fma_f32 v[222:223], v[230:231], v[44:45], v[222:223]
	v_cvt_pk_f32_fp8_sdwa v[224:225], v179 src0_sel:WORD_1
	v_cvt_pk_f32_fp8_sdwa v[226:227], v183 src0_sel:WORD_1
	v_cvt_pk_f32_fp8_sdwa v[228:229], v187 src0_sel:WORD_1
	v_cvt_pk_f32_fp8_sdwa v[230:231], v191 src0_sel:WORD_1
	v_pk_fma_f32 v[216:217], v[224:225], v[46:47], v[216:217]
	v_pk_fma_f32 v[218:219], v[226:227], v[46:47], v[218:219]
	v_pk_fma_f32 v[220:221], v[228:229], v[46:47], v[220:221]
	v_pk_fma_f32 v[222:223], v[230:231], v[46:47], v[222:223]
	s_branch .LU_s3_tail
.LU_s3_t3:
	v_cvt_pk_f32_fp8_e32 v[224:225], v176
	v_cvt_pk_f32_fp8_e32 v[226:227], v180
	v_cvt_pk_f32_fp8_e32 v[228:229], v184
	v_cvt_pk_f32_fp8_e32 v[230:231], v188
	v_pk_mul_f32 v[216:217], v[224:225], v[48:49]
	v_pk_mul_f32 v[218:219], v[226:227], v[48:49]
	v_pk_mul_f32 v[220:221], v[228:229], v[48:49]
	v_pk_mul_f32 v[222:223], v[230:231], v[48:49]
	v_cvt_pk_f32_fp8_sdwa v[224:225], v176 src0_sel:WORD_1
	v_cvt_pk_f32_fp8_sdwa v[226:227], v180 src0_sel:WORD_1
	v_cvt_pk_f32_fp8_sdwa v[228:229], v184 src0_sel:WORD_1
	v_cvt_pk_f32_fp8_sdwa v[230:231], v188 src0_sel:WORD_1
	v_pk_fma_f32 v[216:217], v[224:225], v[50:51], v[216:217]
	v_pk_fma_f32 v[218:219], v[226:227], v[50:51], v[218:219]
	v_pk_fma_f32 v[220:221], v[228:229], v[50:51], v[220:221]
	v_pk_fma_f32 v[222:223], v[230:231], v[50:51], v[222:223]
	v_cvt_pk_f32_fp8_e32 v[224:225], v177
	v_cvt_pk_f32_fp8_e32 v[226:227], v181
	v_cvt_pk_f32_fp8_e32 v[228:229], v185
	v_cvt_pk_f32_fp8_e32 v[230:231], v189
	v_pk_fma_f32 v[216:217], v[224:225], v[52:53], v[216:217]
	v_pk_fma_f32 v[218:219], v[226:227], v[52:53], v[218:219]
	v_pk_fma_f32 v[220:221], v[228:229], v[52:53], v[220:221]
	v_pk_fma_f32 v[222:223], v[230:231], v[52:53], v[222:223]
	v_cvt_pk_f32_fp8_sdwa v[224:225], v177 src0_sel:WORD_1
	v_cvt_pk_f32_fp8_sdwa v[226:227], v181 src0_sel:WORD_1
	v_cvt_pk_f32_fp8_sdwa v[228:229], v185 src0_sel:WORD_1
	v_cvt_pk_f32_fp8_sdwa v[230:231], v189 src0_sel:WORD_1
	v_pk_fma_f32 v[216:217], v[224:225], v[54:55], v[216:217]
	v_pk_fma_f32 v[218:219], v[226:227], v[54:55], v[218:219]
	v_pk_fma_f32 v[220:221], v[228:229], v[54:55], v[220:221]
	v_pk_fma_f32 v[222:223], v[230:231], v[54:55], v[222:223]
	v_cvt_pk_f32_fp8_e32 v[224:225], v178
	v_cvt_pk_f32_fp8_e32 v[226:227], v182
	v_cvt_pk_f32_fp8_e32 v[228:229], v186
	v_cvt_pk_f32_fp8_e32 v[230:231], v190
	v_pk_fma_f32 v[216:217], v[224:225], v[56:57], v[216:217]
	v_pk_fma_f32 v[218:219], v[226:227], v[56:57], v[218:219]
	v_pk_fma_f32 v[220:221], v[228:229], v[56:57], v[220:221]
	v_pk_fma_f32 v[222:223], v[230:231], v[56:57], v[222:223]
	v_cvt_pk_f32_fp8_sdwa v[224:225], v178 src0_sel:WORD_1
	v_cvt_pk_f32_fp8_sdwa v[226:227], v182 src0_sel:WORD_1
	v_cvt_pk_f32_fp8_sdwa v[228:229], v186 src0_sel:WORD_1
	v_cvt_pk_f32_fp8_sdwa v[230:231], v190 src0_sel:WORD_1
	v_pk_fma_f32 v[216:217], v[224:225], v[58:59], v[216:217]
	v_pk_fma_f32 v[218:219], v[226:227], v[58:59], v[218:219]
	v_pk_fma_f32 v[220:221], v[228:229], v[58:59], v[220:221]
	v_pk_fma_f32 v[222:223], v[230:231], v[58:59], v[222:223]
	v_cvt_pk_f32_fp8_e32 v[224:225], v179
	v_cvt_pk_f32_fp8_e32 v[226:227], v183
	v_cvt_pk_f32_fp8_e32 v[228:229], v187
	v_cvt_pk_f32_fp8_e32 v[230:231], v191
	v_pk_fma_f32 v[216:217], v[224:225], v[60:61], v[216:217]
	v_pk_fma_f32 v[218:219], v[226:227], v[60:61], v[218:219]
	v_pk_fma_f32 v[220:221], v[228:229], v[60:61], v[220:221]
	v_pk_fma_f32 v[222:223], v[230:231], v[60:61], v[222:223]
	v_cvt_pk_f32_fp8_sdwa v[224:225], v179 src0_sel:WORD_1
	v_cvt_pk_f32_fp8_sdwa v[226:227], v183 src0_sel:WORD_1
	v_cvt_pk_f32_fp8_sdwa v[228:229], v187 src0_sel:WORD_1
	v_cvt_pk_f32_fp8_sdwa v[230:231], v191 src0_sel:WORD_1
	v_pk_fma_f32 v[216:217], v[224:225], v[62:63], v[216:217]
	v_pk_fma_f32 v[218:219], v[226:227], v[62:63], v[218:219]
	v_pk_fma_f32 v[220:221], v[228:229], v[62:63], v[220:221]
	v_pk_fma_f32 v[222:223], v[230:231], v[62:63], v[222:223]
	s_branch .LU_s3_tail
.LU_s3_t4:
	v_cvt_pk_f32_fp8_e32 v[224:225], v176
	v_cvt_pk_f32_fp8_e32 v[226:227], v180
	v_cvt_pk_f32_fp8_e32 v[228:229], v184
	v_cvt_pk_f32_fp8_e32 v[230:231], v188
	v_pk_mul_f32 v[216:217], v[224:225], v[64:65]
	v_pk_mul_f32 v[218:219], v[226:227], v[64:65]
	v_pk_mul_f32 v[220:221], v[228:229], v[64:65]
	v_pk_mul_f32 v[222:223], v[230:231], v[64:65]
	v_cvt_pk_f32_fp8_sdwa v[224:225], v176 src0_sel:WORD_1
	v_cvt_pk_f32_fp8_sdwa v[226:227], v180 src0_sel:WORD_1
	v_cvt_pk_f32_fp8_sdwa v[228:229], v184 src0_sel:WORD_1
	v_cvt_pk_f32_fp8_sdwa v[230:231], v188 src0_sel:WORD_1
	v_pk_fma_f32 v[216:217], v[224:225], v[66:67], v[216:217]
	v_pk_fma_f32 v[218:219], v[226:227], v[66:67], v[218:219]
	v_pk_fma_f32 v[220:221], v[228:229], v[66:67], v[220:221]
	v_pk_fma_f32 v[222:223], v[230:231], v[66:67], v[222:223]
	v_cvt_pk_f32_fp8_e32 v[224:225], v177
	v_cvt_pk_f32_fp8_e32 v[226:227], v181
	v_cvt_pk_f32_fp8_e32 v[228:229], v185
	v_cvt_pk_f32_fp8_e32 v[230:231], v189
	v_pk_fma_f32 v[216:217], v[224:225], v[68:69], v[216:217]
	v_pk_fma_f32 v[218:219], v[226:227], v[68:69], v[218:219]
	v_pk_fma_f32 v[220:221], v[228:229], v[68:69], v[220:221]
	v_pk_fma_f32 v[222:223], v[230:231], v[68:69], v[222:223]
	v_cvt_pk_f32_fp8_sdwa v[224:225], v177 src0_sel:WORD_1
	v_cvt_pk_f32_fp8_sdwa v[226:227], v181 src0_sel:WORD_1
	v_cvt_pk_f32_fp8_sdwa v[228:229], v185 src0_sel:WORD_1
	v_cvt_pk_f32_fp8_sdwa v[230:231], v189 src0_sel:WORD_1
	v_pk_fma_f32 v[216:217], v[224:225], v[70:71], v[216:217]
	v_pk_fma_f32 v[218:219], v[226:227], v[70:71], v[218:219]
	v_pk_fma_f32 v[220:221], v[228:229], v[70:71], v[220:221]
	v_pk_fma_f32 v[222:223], v[230:231], v[70:71], v[222:223]
	v_cvt_pk_f32_fp8_e32 v[224:225], v178
	v_cvt_pk_f32_fp8_e32 v[226:227], v182
	v_cvt_pk_f32_fp8_e32 v[228:229], v186
	v_cvt_pk_f32_fp8_e32 v[230:231], v190
	v_pk_fma_f32 v[216:217], v[224:225], v[72:73], v[216:217]
	v_pk_fma_f32 v[218:219], v[226:227], v[72:73], v[218:219]
	v_pk_fma_f32 v[220:221], v[228:229], v[72:73], v[220:221]
	v_pk_fma_f32 v[222:223], v[230:231], v[72:73], v[222:223]
	v_cvt_pk_f32_fp8_sdwa v[224:225], v178 src0_sel:WORD_1
	v_cvt_pk_f32_fp8_sdwa v[226:227], v182 src0_sel:WORD_1
	v_cvt_pk_f32_fp8_sdwa v[228:229], v186 src0_sel:WORD_1
	v_cvt_pk_f32_fp8_sdwa v[230:231], v190 src0_sel:WORD_1
	v_pk_fma_f32 v[216:217], v[224:225], v[74:75], v[216:217]
	v_pk_fma_f32 v[218:219], v[226:227], v[74:75], v[218:219]
	v_pk_fma_f32 v[220:221], v[228:229], v[74:75], v[220:221]
	v_pk_fma_f32 v[222:223], v[230:231], v[74:75], v[222:223]
	v_cvt_pk_f32_fp8_e32 v[224:225], v179
	v_cvt_pk_f32_fp8_e32 v[226:227], v183
	v_cvt_pk_f32_fp8_e32 v[228:229], v187
	v_cvt_pk_f32_fp8_e32 v[230:231], v191
	v_pk_fma_f32 v[216:217], v[224:225], v[76:77], v[216:217]
	v_pk_fma_f32 v[218:219], v[226:227], v[76:77], v[218:219]
	v_pk_fma_f32 v[220:221], v[228:229], v[76:77], v[220:221]
	v_pk_fma_f32 v[222:223], v[230:231], v[76:77], v[222:223]
	v_cvt_pk_f32_fp8_sdwa v[224:225], v179 src0_sel:WORD_1
	v_cvt_pk_f32_fp8_sdwa v[226:227], v183 src0_sel:WORD_1
	v_cvt_pk_f32_fp8_sdwa v[228:229], v187 src0_sel:WORD_1
	v_cvt_pk_f32_fp8_sdwa v[230:231], v191 src0_sel:WORD_1
	v_pk_fma_f32 v[216:217], v[224:225], v[78:79], v[216:217]
	v_pk_fma_f32 v[218:219], v[226:227], v[78:79], v[218:219]
	v_pk_fma_f32 v[220:221], v[228:229], v[78:79], v[220:221]
	v_pk_fma_f32 v[222:223], v[230:231], v[78:79], v[222:223]
	s_branch .LU_s3_tail
.LU_s3_t5:
	v_cvt_pk_f32_fp8_e32 v[224:225], v176
	v_cvt_pk_f32_fp8_e32 v[226:227], v180
	v_cvt_pk_f32_fp8_e32 v[228:229], v184
	v_cvt_pk_f32_fp8_e32 v[230:231], v188
	v_pk_mul_f32 v[216:217], v[224:225], v[80:81]
	v_pk_mul_f32 v[218:219], v[226:227], v[80:81]
	v_pk_mul_f32 v[220:221], v[228:229], v[80:81]
	v_pk_mul_f32 v[222:223], v[230:231], v[80:81]
	v_cvt_pk_f32_fp8_sdwa v[224:225], v176 src0_sel:WORD_1
	v_cvt_pk_f32_fp8_sdwa v[226:227], v180 src0_sel:WORD_1
	v_cvt_pk_f32_fp8_sdwa v[228:229], v184 src0_sel:WORD_1
	v_cvt_pk_f32_fp8_sdwa v[230:231], v188 src0_sel:WORD_1
	v_pk_fma_f32 v[216:217], v[224:225], v[82:83], v[216:217]
	v_pk_fma_f32 v[218:219], v[226:227], v[82:83], v[218:219]
	v_pk_fma_f32 v[220:221], v[228:229], v[82:83], v[220:221]
	v_pk_fma_f32 v[222:223], v[230:231], v[82:83], v[222:223]
	v_cvt_pk_f32_fp8_e32 v[224:225], v177
	v_cvt_pk_f32_fp8_e32 v[226:227], v181
	v_cvt_pk_f32_fp8_e32 v[228:229], v185
	v_cvt_pk_f32_fp8_e32 v[230:231], v189
	v_pk_fma_f32 v[216:217], v[224:225], v[84:85], v[216:217]
	v_pk_fma_f32 v[218:219], v[226:227], v[84:85], v[218:219]
	v_pk_fma_f32 v[220:221], v[228:229], v[84:85], v[220:221]
	v_pk_fma_f32 v[222:223], v[230:231], v[84:85], v[222:223]
	v_cvt_pk_f32_fp8_sdwa v[224:225], v177 src0_sel:WORD_1
	v_cvt_pk_f32_fp8_sdwa v[226:227], v181 src0_sel:WORD_1
	v_cvt_pk_f32_fp8_sdwa v[228:229], v185 src0_sel:WORD_1
	v_cvt_pk_f32_fp8_sdwa v[230:231], v189 src0_sel:WORD_1
	v_pk_fma_f32 v[216:217], v[224:225], v[86:87], v[216:217]
	v_pk_fma_f32 v[218:219], v[226:227], v[86:87], v[218:219]
	v_pk_fma_f32 v[220:221], v[228:229], v[86:87], v[220:221]
	v_pk_fma_f32 v[222:223], v[230:231], v[86:87], v[222:223]
	v_cvt_pk_f32_fp8_e32 v[224:225], v178
	v_cvt_pk_f32_fp8_e32 v[226:227], v182
	v_cvt_pk_f32_fp8_e32 v[228:229], v186
	v_cvt_pk_f32_fp8_e32 v[230:231], v190
	v_pk_fma_f32 v[216:217], v[224:225], v[88:89], v[216:217]
	v_pk_fma_f32 v[218:219], v[226:227], v[88:89], v[218:219]
	v_pk_fma_f32 v[220:221], v[228:229], v[88:89], v[220:221]
	v_pk_fma_f32 v[222:223], v[230:231], v[88:89], v[222:223]
	v_cvt_pk_f32_fp8_sdwa v[224:225], v178 src0_sel:WORD_1
	v_cvt_pk_f32_fp8_sdwa v[226:227], v182 src0_sel:WORD_1
	v_cvt_pk_f32_fp8_sdwa v[228:229], v186 src0_sel:WORD_1
	v_cvt_pk_f32_fp8_sdwa v[230:231], v190 src0_sel:WORD_1
	v_pk_fma_f32 v[216:217], v[224:225], v[90:91], v[216:217]
	v_pk_fma_f32 v[218:219], v[226:227], v[90:91], v[218:219]
	v_pk_fma_f32 v[220:221], v[228:229], v[90:91], v[220:221]
	v_pk_fma_f32 v[222:223], v[230:231], v[90:91], v[222:223]
	v_cvt_pk_f32_fp8_e32 v[224:225], v179
	v_cvt_pk_f32_fp8_e32 v[226:227], v183
	v_cvt_pk_f32_fp8_e32 v[228:229], v187
	v_cvt_pk_f32_fp8_e32 v[230:231], v191
	v_pk_fma_f32 v[216:217], v[224:225], v[92:93], v[216:217]
	v_pk_fma_f32 v[218:219], v[226:227], v[92:93], v[218:219]
	v_pk_fma_f32 v[220:221], v[228:229], v[92:93], v[220:221]
	v_pk_fma_f32 v[222:223], v[230:231], v[92:93], v[222:223]
	v_cvt_pk_f32_fp8_sdwa v[224:225], v179 src0_sel:WORD_1
	v_cvt_pk_f32_fp8_sdwa v[226:227], v183 src0_sel:WORD_1
	v_cvt_pk_f32_fp8_sdwa v[228:229], v187 src0_sel:WORD_1
	v_cvt_pk_f32_fp8_sdwa v[230:231], v191 src0_sel:WORD_1
	v_pk_fma_f32 v[216:217], v[224:225], v[94:95], v[216:217]
	v_pk_fma_f32 v[218:219], v[226:227], v[94:95], v[218:219]
	v_pk_fma_f32 v[220:221], v[228:229], v[94:95], v[220:221]
	v_pk_fma_f32 v[222:223], v[230:231], v[94:95], v[222:223]
	s_branch .LU_s3_tail
.LU_s3_t6:
	v_cvt_pk_f32_fp8_e32 v[224:225], v176
	v_cvt_pk_f32_fp8_e32 v[226:227], v180
	v_cvt_pk_f32_fp8_e32 v[228:229], v184
	v_cvt_pk_f32_fp8_e32 v[230:231], v188
	v_pk_mul_f32 v[216:217], v[224:225], v[96:97]
	v_pk_mul_f32 v[218:219], v[226:227], v[96:97]
	v_pk_mul_f32 v[220:221], v[228:229], v[96:97]
	v_pk_mul_f32 v[222:223], v[230:231], v[96:97]
	v_cvt_pk_f32_fp8_sdwa v[224:225], v176 src0_sel:WORD_1
	v_cvt_pk_f32_fp8_sdwa v[226:227], v180 src0_sel:WORD_1
	v_cvt_pk_f32_fp8_sdwa v[228:229], v184 src0_sel:WORD_1
	v_cvt_pk_f32_fp8_sdwa v[230:231], v188 src0_sel:WORD_1
	v_pk_fma_f32 v[216:217], v[224:225], v[98:99], v[216:217]
	v_pk_fma_f32 v[218:219], v[226:227], v[98:99], v[218:219]
	v_pk_fma_f32 v[220:221], v[228:229], v[98:99], v[220:221]
	v_pk_fma_f32 v[222:223], v[230:231], v[98:99], v[222:223]
	v_cvt_pk_f32_fp8_e32 v[224:225], v177
	v_cvt_pk_f32_fp8_e32 v[226:227], v181
	v_cvt_pk_f32_fp8_e32 v[228:229], v185
	v_cvt_pk_f32_fp8_e32 v[230:231], v189
	v_pk_fma_f32 v[216:217], v[224:225], v[100:101], v[216:217]
	v_pk_fma_f32 v[218:219], v[226:227], v[100:101], v[218:219]
	v_pk_fma_f32 v[220:221], v[228:229], v[100:101], v[220:221]
	v_pk_fma_f32 v[222:223], v[230:231], v[100:101], v[222:223]
	v_cvt_pk_f32_fp8_sdwa v[224:225], v177 src0_sel:WORD_1
	v_cvt_pk_f32_fp8_sdwa v[226:227], v181 src0_sel:WORD_1
	v_cvt_pk_f32_fp8_sdwa v[228:229], v185 src0_sel:WORD_1
	v_cvt_pk_f32_fp8_sdwa v[230:231], v189 src0_sel:WORD_1
	v_pk_fma_f32 v[216:217], v[224:225], v[102:103], v[216:217]
	v_pk_fma_f32 v[218:219], v[226:227], v[102:103], v[218:219]
	v_pk_fma_f32 v[220:221], v[228:229], v[102:103], v[220:221]
	v_pk_fma_f32 v[222:223], v[230:231], v[102:103], v[222:223]
	v_cvt_pk_f32_fp8_e32 v[224:225], v178
	v_cvt_pk_f32_fp8_e32 v[226:227], v182
	v_cvt_pk_f32_fp8_e32 v[228:229], v186
	v_cvt_pk_f32_fp8_e32 v[230:231], v190
	v_pk_fma_f32 v[216:217], v[224:225], v[104:105], v[216:217]
	v_pk_fma_f32 v[218:219], v[226:227], v[104:105], v[218:219]
	v_pk_fma_f32 v[220:221], v[228:229], v[104:105], v[220:221]
	v_pk_fma_f32 v[222:223], v[230:231], v[104:105], v[222:223]
	v_cvt_pk_f32_fp8_sdwa v[224:225], v178 src0_sel:WORD_1
	v_cvt_pk_f32_fp8_sdwa v[226:227], v182 src0_sel:WORD_1
	v_cvt_pk_f32_fp8_sdwa v[228:229], v186 src0_sel:WORD_1
	v_cvt_pk_f32_fp8_sdwa v[230:231], v190 src0_sel:WORD_1
	v_pk_fma_f32 v[216:217], v[224:225], v[106:107], v[216:217]
	v_pk_fma_f32 v[218:219], v[226:227], v[106:107], v[218:219]
	v_pk_fma_f32 v[220:221], v[228:229], v[106:107], v[220:221]
	v_pk_fma_f32 v[222:223], v[230:231], v[106:107], v[222:223]
	v_cvt_pk_f32_fp8_e32 v[224:225], v179
	v_cvt_pk_f32_fp8_e32 v[226:227], v183
	v_cvt_pk_f32_fp8_e32 v[228:229], v187
	v_cvt_pk_f32_fp8_e32 v[230:231], v191
	v_pk_fma_f32 v[216:217], v[224:225], v[108:109], v[216:217]
	v_pk_fma_f32 v[218:219], v[226:227], v[108:109], v[218:219]
	v_pk_fma_f32 v[220:221], v[228:229], v[108:109], v[220:221]
	v_pk_fma_f32 v[222:223], v[230:231], v[108:109], v[222:223]
	v_cvt_pk_f32_fp8_sdwa v[224:225], v179 src0_sel:WORD_1
	v_cvt_pk_f32_fp8_sdwa v[226:227], v183 src0_sel:WORD_1
	v_cvt_pk_f32_fp8_sdwa v[228:229], v187 src0_sel:WORD_1
	v_cvt_pk_f32_fp8_sdwa v[230:231], v191 src0_sel:WORD_1
	v_pk_fma_f32 v[216:217], v[224:225], v[110:111], v[216:217]
	v_pk_fma_f32 v[218:219], v[226:227], v[110:111], v[218:219]
	v_pk_fma_f32 v[220:221], v[228:229], v[110:111], v[220:221]
	v_pk_fma_f32 v[222:223], v[230:231], v[110:111], v[222:223]
	s_branch .LU_s3_tail
.LU_s3_t7:
	v_cvt_pk_f32_fp8_e32 v[224:225], v176
	v_cvt_pk_f32_fp8_e32 v[226:227], v180
	v_cvt_pk_f32_fp8_e32 v[228:229], v184
	v_cvt_pk_f32_fp8_e32 v[230:231], v188
	v_pk_mul_f32 v[216:217], v[224:225], v[112:113]
	v_pk_mul_f32 v[218:219], v[226:227], v[112:113]
	v_pk_mul_f32 v[220:221], v[228:229], v[112:113]
	v_pk_mul_f32 v[222:223], v[230:231], v[112:113]
	v_cvt_pk_f32_fp8_sdwa v[224:225], v176 src0_sel:WORD_1
	v_cvt_pk_f32_fp8_sdwa v[226:227], v180 src0_sel:WORD_1
	v_cvt_pk_f32_fp8_sdwa v[228:229], v184 src0_sel:WORD_1
	v_cvt_pk_f32_fp8_sdwa v[230:231], v188 src0_sel:WORD_1
	v_pk_fma_f32 v[216:217], v[224:225], v[114:115], v[216:217]
	v_pk_fma_f32 v[218:219], v[226:227], v[114:115], v[218:219]
	v_pk_fma_f32 v[220:221], v[228:229], v[114:115], v[220:221]
	v_pk_fma_f32 v[222:223], v[230:231], v[114:115], v[222:223]
	v_cvt_pk_f32_fp8_e32 v[224:225], v177
	v_cvt_pk_f32_fp8_e32 v[226:227], v181
	v_cvt_pk_f32_fp8_e32 v[228:229], v185
	v_cvt_pk_f32_fp8_e32 v[230:231], v189
	v_pk_fma_f32 v[216:217], v[224:225], v[116:117], v[216:217]
	v_pk_fma_f32 v[218:219], v[226:227], v[116:117], v[218:219]
	v_pk_fma_f32 v[220:221], v[228:229], v[116:117], v[220:221]
	v_pk_fma_f32 v[222:223], v[230:231], v[116:117], v[222:223]
	v_cvt_pk_f32_fp8_sdwa v[224:225], v177 src0_sel:WORD_1
	v_cvt_pk_f32_fp8_sdwa v[226:227], v181 src0_sel:WORD_1
	v_cvt_pk_f32_fp8_sdwa v[228:229], v185 src0_sel:WORD_1
	v_cvt_pk_f32_fp8_sdwa v[230:231], v189 src0_sel:WORD_1
	v_pk_fma_f32 v[216:217], v[224:225], v[118:119], v[216:217]
	v_pk_fma_f32 v[218:219], v[226:227], v[118:119], v[218:219]
	v_pk_fma_f32 v[220:221], v[228:229], v[118:119], v[220:221]
	v_pk_fma_f32 v[222:223], v[230:231], v[118:119], v[222:223]
	v_cvt_pk_f32_fp8_e32 v[224:225], v178
	v_cvt_pk_f32_fp8_e32 v[226:227], v182
	v_cvt_pk_f32_fp8_e32 v[228:229], v186
	v_cvt_pk_f32_fp8_e32 v[230:231], v190
	v_pk_fma_f32 v[216:217], v[224:225], v[120:121], v[216:217]
	v_pk_fma_f32 v[218:219], v[226:227], v[120:121], v[218:219]
	v_pk_fma_f32 v[220:221], v[228:229], v[120:121], v[220:221]
	v_pk_fma_f32 v[222:223], v[230:231], v[120:121], v[222:223]
	v_cvt_pk_f32_fp8_sdwa v[224:225], v178 src0_sel:WORD_1
	v_cvt_pk_f32_fp8_sdwa v[226:227], v182 src0_sel:WORD_1
	v_cvt_pk_f32_fp8_sdwa v[228:229], v186 src0_sel:WORD_1
	v_cvt_pk_f32_fp8_sdwa v[230:231], v190 src0_sel:WORD_1
	v_pk_fma_f32 v[216:217], v[224:225], v[122:123], v[216:217]
	v_pk_fma_f32 v[218:219], v[226:227], v[122:123], v[218:219]
	v_pk_fma_f32 v[220:221], v[228:229], v[122:123], v[220:221]
	v_pk_fma_f32 v[222:223], v[230:231], v[122:123], v[222:223]
	v_cvt_pk_f32_fp8_e32 v[224:225], v179
	v_cvt_pk_f32_fp8_e32 v[226:227], v183
	v_cvt_pk_f32_fp8_e32 v[228:229], v187
	v_cvt_pk_f32_fp8_e32 v[230:231], v191
	v_pk_fma_f32 v[216:217], v[224:225], v[124:125], v[216:217]
	v_pk_fma_f32 v[218:219], v[226:227], v[124:125], v[218:219]
	v_pk_fma_f32 v[220:221], v[228:229], v[124:125], v[220:221]
	v_pk_fma_f32 v[222:223], v[230:231], v[124:125], v[222:223]
	v_cvt_pk_f32_fp8_sdwa v[224:225], v179 src0_sel:WORD_1
	v_cvt_pk_f32_fp8_sdwa v[226:227], v183 src0_sel:WORD_1
	v_cvt_pk_f32_fp8_sdwa v[228:229], v187 src0_sel:WORD_1
	v_cvt_pk_f32_fp8_sdwa v[230:231], v191 src0_sel:WORD_1
	v_pk_fma_f32 v[216:217], v[224:225], v[126:127], v[216:217]
	v_pk_fma_f32 v[218:219], v[226:227], v[126:127], v[218:219]
	v_pk_fma_f32 v[220:221], v[228:229], v[126:127], v[220:221]
	v_pk_fma_f32 v[222:223], v[230:231], v[126:127], v[222:223]
.LU_s3_tail:
	v_add_f32_e32 v216, v216, v217
	v_add_f32_e32 v220, v220, v221
	v_add_f32_e32 v218, v218, v219
	v_add_f32_e32 v222, v222, v223
	s_nop 0
	v_permlane32_swap_b32_e32 v216, v220
	s_nop 0
	v_permlane32_swap_b32_e32 v218, v222
	v_add_f32_e32 v216, v216, v220
	v_add_f32_e32 v218, v218, v222
	s_nop 1
	v_permlane16_swap_b32_e32 v216, v218
	v_add_f32_e32 v216, v216, v218
	s_nop 1
	v_add_f32_dpp v216, v216, v216 quad_perm:[1,0,3,2] row_mask:0xf bank_mask:0xf bound_ctrl:1
	s_nop 1
	v_add_f32_dpp v216, v216, v216 quad_perm:[2,3,0,1] row_mask:0xf bank_mask:0xf bound_ctrl:1
	s_nop 1
	v_add_f32_dpp v216, v216, v216 row_half_mirror row_mask:0xf bank_mask:0xf bound_ctrl:1
	s_nop 1
	v_add_f32_dpp v216, v216, v216 row_mirror row_mask:0xf bank_mask:0xf bound_ctrl:1
	v_mul_f32_e32 v217, v251, v216
	v_fma_f32 v218, |v217|, s72, 1.0
	v_mul_f32_e32 v219, v217, v217
	v_rcp_f32_e32 v218, v218
	v_mul_f32_e32 v219, 0xbf38aa3b, v219
	v_exp_f32_e32 v219, v219
	v_fmamk_f32 v220, v218, 0x3f07dc22, v242
	v_fmaak_f32 v220, v218, v220, 0x3f35f0e3
	v_fmaak_f32 v220, v218, v220, 0xbe11a98e
	v_fmaak_f32 v220, v218, v220, 0x3e027906
	v_mul_f32_e32 v220, v218, v220
	v_mul_f32_e32 v220, v219, v220
	v_mul_f32_e32 v221, v217, v220
	v_fma_f32 v220, -v217, v220, v217
	v_cmp_gt_f32_e32 vcc, 0, v217
	v_lshrrev_b32_e32 v254, 3, v238
	s_nop 0
	v_cndmask_b32_e32 v220, v220, v221, vcc
	v_mul_f32_e32 v220, v237, v220
	v_mul_f32_e32 v220, v211, v220
	ds_write_b32 v254, v220
	ds_read_b128 v[236:239], v241 offset:256
	ds_read_b128 v[232:235], v241 offset:512
	s_add_i32 s21, s21, 1
.LU_s4:
	s_cmp_ge_u32 s21, s20
	s_cbranch_scc1 .LU_done
	s_waitcnt lgkmcnt(0)
	v_readlane_b32 s64, v232, 0
	v_readlane_b32 s65, v232, 16
	v_readlane_b32 s66, v232, 32
	v_readlane_b32 s67, v232, 48
	v_lshrrev_b32_e32 v253, 8, v232
	s_add_u32 s24, s4, s64
	s_addc_u32 s25, s5, 0
	s_add_u32 s26, s4, s65
	s_addc_u32 s27, s5, 0
	s_add_u32 s28, s4, s66
	s_addc_u32 s29, s5, 0
	s_add_u32 s30, s4, s67
	s_addc_u32 s31, s5, 0
	global_load_dwordx4 v[176:179], v240, s[24:25]
	global_load_dwordx4 v[180:183], v240, s[26:27]
	global_load_dwordx4 v[184:187], v240, s[28:29]
	global_load_dwordx4 v[188:191], v240, s[30:31]
	global_load_dword v251, v253, s[8:9]
	global_load_dword v211, v253, s[52:53]
	v_readfirstlane_b32 s23, v238
	s_and_b32 s23, s23, 7
	s_waitcnt vmcnt(24)
	s_cmp_ge_u32 s23, 4
	s_cbranch_scc1 .LU_s4_h
	s_cmp_ge_u32 s23, 2
	s_cbranch_scc1 .LU_s4_23
	s_cmp_eq_u32 s23, 0
	s_cbranch_scc1 .LU_s4_t0
	s_branch .LU_s4_t1

.LU_s4_t0:
	v_cvt_pk_f32_fp8_e32 v[224:225], v192
	v_cvt_pk_f32_fp8_e32 v[226:227], v196
	v_cvt_pk_f32_fp8_e32 v[228:229], v200
	v_cvt_pk_f32_fp8_e32 v[230:231], v204
	v_pk_mul_f32 v[216:217], v[224:225], v[0:1]
	v_pk_mul_f32 v[218:219], v[226:227], v[0:1]
	v_pk_mul_f32 v[220:221], v[228:229], v[0:1]
	v_pk_mul_f32 v[222:223], v[230:231], v[0:1]
	v_cvt_pk_f32_fp8_sdwa v[224:225], v192 src0_sel:WORD_1
	v_cvt_pk_f32_fp8_sdwa v[226:227], v196 src0_sel:WORD_1
	v_cvt_pk_f32_fp8_sdwa v[228:229], v200 src0_sel:WORD_1
	v_cvt_pk_f32_fp8_sdwa v[230:231], v204 src0_sel:WORD_1
	v_pk_fma_f32 v[216:217], v[224:225], v[2:3], v[216:217]
	v_pk_fma_f32 v[218:219], v[226:227], v[2:3], v[218:219]
	v_pk_fma_f32 v[220:221], v[228:229], v[2:3], v[220:221]
	v_pk_fma_f32 v[222:223], v[230:231], v[2:3], v[222:223]
	v_cvt_pk_f32_fp8_e32 v[224:225], v193
	v_cvt_pk_f32_fp8_e32 v[226:227], v197
	v_cvt_pk_f32_fp8_e32 v[228:229], v201
	v_cvt_pk_f32_fp8_e32 v[230:231], v205
	v_pk_fma_f32 v[216:217], v[224:225], v[4:5], v[216:217]
	v_pk_fma_f32 v[218:219], v[226:227], v[4:5], v[218:219]
	v_pk_fma_f32 v[220:221], v[228:229], v[4:5], v[220:221]
	v_pk_fma_f32 v[222:223], v[230:231], v[4:5], v[222:223]
	v_cvt_pk_f32_fp8_sdwa v[224:225], v193 src0_sel:WORD_1
	v_cvt_pk_f32_fp8_sdwa v[226:227], v197 src0_sel:WORD_1
	v_cvt_pk_f32_fp8_sdwa v[228:229], v201 src0_sel:WORD_1
	v_cvt_pk_f32_fp8_sdwa v[230:231], v205 src0_sel:WORD_1
	v_pk_fma_f32 v[216:217], v[224:225], v[6:7], v[216:217]
	v_pk_fma_f32 v[218:219], v[226:227], v[6:7], v[218:219]
	v_pk_fma_f32 v[220:221], v[228:229], v[6:7], v[220:221]
	v_pk_fma_f32 v[222:223], v[230:231], v[6:7], v[222:223]
	v_cvt_pk_f32_fp8_e32 v[224:225], v194
	v_cvt_pk_f32_fp8_e32 v[226:227], v198
	v_cvt_pk_f32_fp8_e32 v[228:229], v202
	v_cvt_pk_f32_fp8_e32 v[230:231], v206
	v_pk_fma_f32 v[216:217], v[224:225], v[8:9], v[216:217]
	v_pk_fma_f32 v[218:219], v[226:227], v[8:9], v[218:219]
	v_pk_fma_f32 v[220:221], v[228:229], v[8:9], v[220:221]
	v_pk_fma_f32 v[222:223], v[230:231], v[8:9], v[222:223]
	v_cvt_pk_f32_fp8_sdwa v[224:225], v194 src0_sel:WORD_1
	v_cvt_pk_f32_fp8_sdwa v[226:227], v198 src0_sel:WORD_1
	v_cvt_pk_f32_fp8_sdwa v[228:229], v202 src0_sel:WORD_1
	v_cvt_pk_f32_fp8_sdwa v[230:231], v206 src0_sel:WORD_1
	v_pk_fma_f32 v[216:217], v[224:225], v[10:11], v[216:217]
	v_pk_fma_f32 v[218:219], v[226:227], v[10:11], v[218:219]
	v_pk_fma_f32 v[220:221], v[228:229], v[10:11], v[220:221]
	v_pk_fma_f32 v[222:223], v[230:231], v[10:11], v[222:223]
	v_cvt_pk_f32_fp8_e32 v[224:225], v195
	v_cvt_pk_f32_fp8_e32 v[226:227], v199
	v_cvt_pk_f32_fp8_e32 v[228:229], v203
	v_cvt_pk_f32_fp8_e32 v[230:231], v207
	v_pk_fma_f32 v[216:217], v[224:225], v[12:13], v[216:217]
	v_pk_fma_f32 v[218:219], v[226:227], v[12:13], v[218:219]
	v_pk_fma_f32 v[220:221], v[228:229], v[12:13], v[220:221]
	v_pk_fma_f32 v[222:223], v[230:231], v[12:13], v[222:223]
	v_cvt_pk_f32_fp8_sdwa v[224:225], v195 src0_sel:WORD_1
	v_cvt_pk_f32_fp8_sdwa v[226:227], v199 src0_sel:WORD_1
	v_cvt_pk_f32_fp8_sdwa v[228:229], v203 src0_sel:WORD_1
	v_cvt_pk_f32_fp8_sdwa v[230:231], v207 src0_sel:WORD_1
	v_pk_fma_f32 v[216:217], v[224:225], v[14:15], v[216:217]
	v_pk_fma_f32 v[218:219], v[226:227], v[14:15], v[218:219]
	v_pk_fma_f32 v[220:221], v[228:229], v[14:15], v[220:221]
	v_pk_fma_f32 v[222:223], v[230:231], v[14:15], v[222:223]
	s_branch .LU_s4_tail
.LU_s4_t1:
	v_cvt_pk_f32_fp8_e32 v[224:225], v192
	v_cvt_pk_f32_fp8_e32 v[226:227], v196
	v_cvt_pk_f32_fp8_e32 v[228:229], v200
	v_cvt_pk_f32_fp8_e32 v[230:231], v204
	v_pk_mul_f32 v[216:217], v[224:225], v[16:17]
	v_pk_mul_f32 v[218:219], v[226:227], v[16:17]
	v_pk_mul_f32 v[220:221], v[228:229], v[16:17]
	v_pk_mul_f32 v[222:223], v[230:231], v[16:17]
	v_cvt_pk_f32_fp8_sdwa v[224:225], v192 src0_sel:WORD_1
	v_cvt_pk_f32_fp8_sdwa v[226:227], v196 src0_sel:WORD_1
	v_cvt_pk_f32_fp8_sdwa v[228:229], v200 src0_sel:WORD_1
	v_cvt_pk_f32_fp8_sdwa v[230:231], v204 src0_sel:WORD_1
	v_pk_fma_f32 v[216:217], v[224:225], v[18:19], v[216:217]
	v_pk_fma_f32 v[218:219], v[226:227], v[18:19], v[218:219]
	v_pk_fma_f32 v[220:221], v[228:229], v[18:19], v[220:221]
	v_pk_fma_f32 v[222:223], v[230:231], v[18:19], v[222:223]
	v_cvt_pk_f32_fp8_e32 v[224:225], v193
	v_cvt_pk_f32_fp8_e32 v[226:227], v197
	v_cvt_pk_f32_fp8_e32 v[228:229], v201
	v_cvt_pk_f32_fp8_e32 v[230:231], v205
	v_pk_fma_f32 v[216:217], v[224:225], v[20:21], v[216:217]
	v_pk_fma_f32 v[218:219], v[226:227], v[20:21], v[218:219]
	v_pk_fma_f32 v[220:221], v[228:229], v[20:21], v[220:221]
	v_pk_fma_f32 v[222:223], v[230:231], v[20:21], v[222:223]
	v_cvt_pk_f32_fp8_sdwa v[224:225], v193 src0_sel:WORD_1
	v_cvt_pk_f32_fp8_sdwa v[226:227], v197 src0_sel:WORD_1
	v_cvt_pk_f32_fp8_sdwa v[228:229], v201 src0_sel:WORD_1
	v_cvt_pk_f32_fp8_sdwa v[230:231], v205 src0_sel:WORD_1
	v_pk_fma_f32 v[216:217], v[224:225], v[22:23], v[216:217]
	v_pk_fma_f32 v[218:219], v[226:227], v[22:23], v[218:219]
	v_pk_fma_f32 v[220:221], v[228:229], v[22:23], v[220:221]
	v_pk_fma_f32 v[222:223], v[230:231], v[22:23], v[222:223]
	v_cvt_pk_f32_fp8_e32 v[224:225], v194
	v_cvt_pk_f32_fp8_e32 v[226:227], v198
	v_cvt_pk_f32_fp8_e32 v[228:229], v202
	v_cvt_pk_f32_fp8_e32 v[230:231], v206
	v_pk_fma_f32 v[216:217], v[224:225], v[24:25], v[216:217]
	v_pk_fma_f32 v[218:219], v[226:227], v[24:25], v[218:219]
	v_pk_fma_f32 v[220:221], v[228:229], v[24:25], v[220:221]
	v_pk_fma_f32 v[222:223], v[230:231], v[24:25], v[222:223]
	v_cvt_pk_f32_fp8_sdwa v[224:225], v194 src0_sel:WORD_1
	v_cvt_pk_f32_fp8_sdwa v[226:227], v198 src0_sel:WORD_1
	v_cvt_pk_f32_fp8_sdwa v[228:229], v202 src0_sel:WORD_1
	v_cvt_pk_f32_fp8_sdwa v[230:231], v206 src0_sel:WORD_1
	v_pk_fma_f32 v[216:217], v[224:225], v[26:27], v[216:217]
	v_pk_fma_f32 v[218:219], v[226:227], v[26:27], v[218:219]
	v_pk_fma_f32 v[220:221], v[228:229], v[26:27], v[220:221]
	v_pk_fma_f32 v[222:223], v[230:231], v[26:27], v[222:223]
	v_cvt_pk_f32_fp8_e32 v[224:225], v195
	v_cvt_pk_f32_fp8_e32 v[226:227], v199
	v_cvt_pk_f32_fp8_e32 v[228:229], v203
	v_cvt_pk_f32_fp8_e32 v[230:231], v207
	v_pk_fma_f32 v[216:217], v[224:225], v[28:29], v[216:217]
	v_pk_fma_f32 v[218:219], v[226:227], v[28:29], v[218:219]
	v_pk_fma_f32 v[220:221], v[228:229], v[28:29], v[220:221]
	v_pk_fma_f32 v[222:223], v[230:231], v[28:29], v[222:223]
	v_cvt_pk_f32_fp8_sdwa v[224:225], v195 src0_sel:WORD_1
	v_cvt_pk_f32_fp8_sdwa v[226:227], v199 src0_sel:WORD_1
	v_cvt_pk_f32_fp8_sdwa v[228:229], v203 src0_sel:WORD_1
	v_cvt_pk_f32_fp8_sdwa v[230:231], v207 src0_sel:WORD_1
	v_pk_fma_f32 v[216:217], v[224:225], v[30:31], v[216:217]
	v_pk_fma_f32 v[218:219], v[226:227], v[30:31], v[218:219]
	v_pk_fma_f32 v[220:221], v[228:229], v[30:31], v[220:221]
	v_pk_fma_f32 v[222:223], v[230:231], v[30:31], v[222:223]
	s_branch .LU_s4_tail
.LU_s4_t2:
	v_cvt_pk_f32_fp8_e32 v[224:225], v192
	v_cvt_pk_f32_fp8_e32 v[226:227], v196
	v_cvt_pk_f32_fp8_e32 v[228:229], v200
	v_cvt_pk_f32_fp8_e32 v[230:231], v204
	v_pk_mul_f32 v[216:217], v[224:225], v[32:33]
	v_pk_mul_f32 v[218:219], v[226:227], v[32:33]
	v_pk_mul_f32 v[220:221], v[228:229], v[32:33]
	v_pk_mul_f32 v[222:223], v[230:231], v[32:33]
	v_cvt_pk_f32_fp8_sdwa v[224:225], v192 src0_sel:WORD_1
	v_cvt_pk_f32_fp8_sdwa v[226:227], v196 src0_sel:WORD_1
	v_cvt_pk_f32_fp8_sdwa v[228:229], v200 src0_sel:WORD_1
	v_cvt_pk_f32_fp8_sdwa v[230:231], v204 src0_sel:WORD_1
	v_pk_fma_f32 v[216:217], v[224:225], v[34:35], v[216:217]
	v_pk_fma_f32 v[218:219], v[226:227], v[34:35], v[218:219]
	v_pk_fma_f32 v[220:221], v[228:229], v[34:35], v[220:221]
	v_pk_fma_f32 v[222:223], v[230:231], v[34:35], v[222:223]
	v_cvt_pk_f32_fp8_e32 v[224:225], v193
	v_cvt_pk_f32_fp8_e32 v[226:227], v197
	v_cvt_pk_f32_fp8_e32 v[228:229], v201
	v_cvt_pk_f32_fp8_e32 v[230:231], v205
	v_pk_fma_f32 v[216:217], v[224:225], v[36:37], v[216:217]
	v_pk_fma_f32 v[218:219], v[226:227], v[36:37], v[218:219]
	v_pk_fma_f32 v[220:221], v[228:229], v[36:37], v[220:221]
	v_pk_fma_f32 v[222:223], v[230:231], v[36:37], v[222:223]
	v_cvt_pk_f32_fp8_sdwa v[224:225], v193 src0_sel:WORD_1
	v_cvt_pk_f32_fp8_sdwa v[226:227], v197 src0_sel:WORD_1
	v_cvt_pk_f32_fp8_sdwa v[228:229], v201 src0_sel:WORD_1
	v_cvt_pk_f32_fp8_sdwa v[230:231], v205 src0_sel:WORD_1
	v_pk_fma_f32 v[216:217], v[224:225], v[38:39], v[216:217]
	v_pk_fma_f32 v[218:219], v[226:227], v[38:39], v[218:219]
	v_pk_fma_f32 v[220:221], v[228:229], v[38:39], v[220:221]
	v_pk_fma_f32 v[222:223], v[230:231], v[38:39], v[222:223]
	v_cvt_pk_f32_fp8_e32 v[224:225], v194
	v_cvt_pk_f32_fp8_e32 v[226:227], v198
	v_cvt_pk_f32_fp8_e32 v[228:229], v202
	v_cvt_pk_f32_fp8_e32 v[230:231], v206
	v_pk_fma_f32 v[216:217], v[224:225], v[40:41], v[216:217]
	v_pk_fma_f32 v[218:219], v[226:227], v[40:41], v[218:219]
	v_pk_fma_f32 v[220:221], v[228:229], v[40:41], v[220:221]
	v_pk_fma_f32 v[222:223], v[230:231], v[40:41], v[222:223]
	v_cvt_pk_f32_fp8_sdwa v[224:225], v194 src0_sel:WORD_1
	v_cvt_pk_f32_fp8_sdwa v[226:227], v198 src0_sel:WORD_1
	v_cvt_pk_f32_fp8_sdwa v[228:229], v202 src0_sel:WORD_1
	v_cvt_pk_f32_fp8_sdwa v[230:231], v206 src0_sel:WORD_1
	v_pk_fma_f32 v[216:217], v[224:225], v[42:43], v[216:217]
	v_pk_fma_f32 v[218:219], v[226:227], v[42:43], v[218:219]
	v_pk_fma_f32 v[220:221], v[228:229], v[42:43], v[220:221]
	v_pk_fma_f32 v[222:223], v[230:231], v[42:43], v[222:223]
	v_cvt_pk_f32_fp8_e32 v[224:225], v195
	v_cvt_pk_f32_fp8_e32 v[226:227], v199
	v_cvt_pk_f32_fp8_e32 v[228:229], v203
	v_cvt_pk_f32_fp8_e32 v[230:231], v207
	v_pk_fma_f32 v[216:217], v[224:225], v[44:45], v[216:217]
	v_pk_fma_f32 v[218:219], v[226:227], v[44:45], v[218:219]
	v_pk_fma_f32 v[220:221], v[228:229], v[44:45], v[220:221]
	v_pk_fma_f32 v[222:223], v[230:231], v[44:45], v[222:223]
	v_cvt_pk_f32_fp8_sdwa v[224:225], v195 src0_sel:WORD_1
	v_cvt_pk_f32_fp8_sdwa v[226:227], v199 src0_sel:WORD_1
	v_cvt_pk_f32_fp8_sdwa v[228:229], v203 src0_sel:WORD_1
	v_cvt_pk_f32_fp8_sdwa v[230:231], v207 src0_sel:WORD_1
	v_pk_fma_f32 v[216:217], v[224:225], v[46:47], v[216:217]
	v_pk_fma_f32 v[218:219], v[226:227], v[46:47], v[218:219]
	v_pk_fma_f32 v[220:221], v[228:229], v[46:47], v[220:221]
	v_pk_fma_f32 v[222:223], v[230:231], v[46:47], v[222:223]
	s_branch .LU_s4_tail
.LU_s4_t3:
	v_cvt_pk_f32_fp8_e32 v[224:225], v192
	v_cvt_pk_f32_fp8_e32 v[226:227], v196
	v_cvt_pk_f32_fp8_e32 v[228:229], v200
	v_cvt_pk_f32_fp8_e32 v[230:231], v204
	v_pk_mul_f32 v[216:217], v[224:225], v[48:49]
	v_pk_mul_f32 v[218:219], v[226:227], v[48:49]
	v_pk_mul_f32 v[220:221], v[228:229], v[48:49]
	v_pk_mul_f32 v[222:223], v[230:231], v[48:49]
	v_cvt_pk_f32_fp8_sdwa v[224:225], v192 src0_sel:WORD_1
	v_cvt_pk_f32_fp8_sdwa v[226:227], v196 src0_sel:WORD_1
	v_cvt_pk_f32_fp8_sdwa v[228:229], v200 src0_sel:WORD_1
	v_cvt_pk_f32_fp8_sdwa v[230:231], v204 src0_sel:WORD_1
	v_pk_fma_f32 v[216:217], v[224:225], v[50:51], v[216:217]
	v_pk_fma_f32 v[218:219], v[226:227], v[50:51], v[218:219]
	v_pk_fma_f32 v[220:221], v[228:229], v[50:51], v[220:221]
	v_pk_fma_f32 v[222:223], v[230:231], v[50:51], v[222:223]
	v_cvt_pk_f32_fp8_e32 v[224:225], v193
	v_cvt_pk_f32_fp8_e32 v[226:227], v197
	v_cvt_pk_f32_fp8_e32 v[228:229], v201
	v_cvt_pk_f32_fp8_e32 v[230:231], v205
	v_pk_fma_f32 v[216:217], v[224:225], v[52:53], v[216:217]
	v_pk_fma_f32 v[218:219], v[226:227], v[52:53], v[218:219]
	v_pk_fma_f32 v[220:221], v[228:229], v[52:53], v[220:221]
	v_pk_fma_f32 v[222:223], v[230:231], v[52:53], v[222:223]
	v_cvt_pk_f32_fp8_sdwa v[224:225], v193 src0_sel:WORD_1
	v_cvt_pk_f32_fp8_sdwa v[226:227], v197 src0_sel:WORD_1
	v_cvt_pk_f32_fp8_sdwa v[228:229], v201 src0_sel:WORD_1
	v_cvt_pk_f32_fp8_sdwa v[230:231], v205 src0_sel:WORD_1
	v_pk_fma_f32 v[216:217], v[224:225], v[54:55], v[216:217]
	v_pk_fma_f32 v[218:219], v[226:227], v[54:55], v[218:219]
	v_pk_fma_f32 v[220:221], v[228:229], v[54:55], v[220:221]
	v_pk_fma_f32 v[222:223], v[230:231], v[54:55], v[222:223]
	v_cvt_pk_f32_fp8_e32 v[224:225], v194
	v_cvt_pk_f32_fp8_e32 v[226:227], v198
	v_cvt_pk_f32_fp8_e32 v[228:229], v202
	v_cvt_pk_f32_fp8_e32 v[230:231], v206
	v_pk_fma_f32 v[216:217], v[224:225], v[56:57], v[216:217]
	v_pk_fma_f32 v[218:219], v[226:227], v[56:57], v[218:219]
	v_pk_fma_f32 v[220:221], v[228:229], v[56:57], v[220:221]
	v_pk_fma_f32 v[222:223], v[230:231], v[56:57], v[222:223]
	v_cvt_pk_f32_fp8_sdwa v[224:225], v194 src0_sel:WORD_1
	v_cvt_pk_f32_fp8_sdwa v[226:227], v198 src0_sel:WORD_1
	v_cvt_pk_f32_fp8_sdwa v[228:229], v202 src0_sel:WORD_1
	v_cvt_pk_f32_fp8_sdwa v[230:231], v206 src0_sel:WORD_1
	v_pk_fma_f32 v[216:217], v[224:225], v[58:59], v[216:217]
	v_pk_fma_f32 v[218:219], v[226:227], v[58:59], v[218:219]
	v_pk_fma_f32 v[220:221], v[228:229], v[58:59], v[220:221]
	v_pk_fma_f32 v[222:223], v[230:231], v[58:59], v[222:223]
	v_cvt_pk_f32_fp8_e32 v[224:225], v195
	v_cvt_pk_f32_fp8_e32 v[226:227], v199
	v_cvt_pk_f32_fp8_e32 v[228:229], v203
	v_cvt_pk_f32_fp8_e32 v[230:231], v207
	v_pk_fma_f32 v[216:217], v[224:225], v[60:61], v[216:217]
	v_pk_fma_f32 v[218:219], v[226:227], v[60:61], v[218:219]
	v_pk_fma_f32 v[220:221], v[228:229], v[60:61], v[220:221]
	v_pk_fma_f32 v[222:223], v[230:231], v[60:61], v[222:223]
	v_cvt_pk_f32_fp8_sdwa v[224:225], v195 src0_sel:WORD_1
	v_cvt_pk_f32_fp8_sdwa v[226:227], v199 src0_sel:WORD_1
	v_cvt_pk_f32_fp8_sdwa v[228:229], v203 src0_sel:WORD_1
	v_cvt_pk_f32_fp8_sdwa v[230:231], v207 src0_sel:WORD_1
	v_pk_fma_f32 v[216:217], v[224:225], v[62:63], v[216:217]
	v_pk_fma_f32 v[218:219], v[226:227], v[62:63], v[218:219]
	v_pk_fma_f32 v[220:221], v[228:229], v[62:63], v[220:221]
	v_pk_fma_f32 v[222:223], v[230:231], v[62:63], v[222:223]
	s_branch .LU_s4_tail
.LU_s4_t4:
	v_cvt_pk_f32_fp8_e32 v[224:225], v192
	v_cvt_pk_f32_fp8_e32 v[226:227], v196
	v_cvt_pk_f32_fp8_e32 v[228:229], v200
	v_cvt_pk_f32_fp8_e32 v[230:231], v204
	v_pk_mul_f32 v[216:217], v[224:225], v[64:65]
	v_pk_mul_f32 v[218:219], v[226:227], v[64:65]
	v_pk_mul_f32 v[220:221], v[228:229], v[64:65]
	v_pk_mul_f32 v[222:223], v[230:231], v[64:65]
	v_cvt_pk_f32_fp8_sdwa v[224:225], v192 src0_sel:WORD_1
	v_cvt_pk_f32_fp8_sdwa v[226:227], v196 src0_sel:WORD_1
	v_cvt_pk_f32_fp8_sdwa v[228:229], v200 src0_sel:WORD_1
	v_cvt_pk_f32_fp8_sdwa v[230:231], v204 src0_sel:WORD_1
	v_pk_fma_f32 v[216:217], v[224:225], v[66:67], v[216:217]
	v_pk_fma_f32 v[218:219], v[226:227], v[66:67], v[218:219]
	v_pk_fma_f32 v[220:221], v[228:229], v[66:67], v[220:221]
	v_pk_fma_f32 v[222:223], v[230:231], v[66:67], v[222:223]
	v_cvt_pk_f32_fp8_e32 v[224:225], v193
	v_cvt_pk_f32_fp8_e32 v[226:227], v197
	v_cvt_pk_f32_fp8_e32 v[228:229], v201
	v_cvt_pk_f32_fp8_e32 v[230:231], v205
	v_pk_fma_f32 v[216:217], v[224:225], v[68:69], v[216:217]
	v_pk_fma_f32 v[218:219], v[226:227], v[68:69], v[218:219]
	v_pk_fma_f32 v[220:221], v[228:229], v[68:69], v[220:221]
	v_pk_fma_f32 v[222:223], v[230:231], v[68:69], v[222:223]
	v_cvt_pk_f32_fp8_sdwa v[224:225], v193 src0_sel:WORD_1
	v_cvt_pk_f32_fp8_sdwa v[226:227], v197 src0_sel:WORD_1
	v_cvt_pk_f32_fp8_sdwa v[228:229], v201 src0_sel:WORD_1
	v_cvt_pk_f32_fp8_sdwa v[230:231], v205 src0_sel:WORD_1
	v_pk_fma_f32 v[216:217], v[224:225], v[70:71], v[216:217]
	v_pk_fma_f32 v[218:219], v[226:227], v[70:71], v[218:219]
	v_pk_fma_f32 v[220:221], v[228:229], v[70:71], v[220:221]
	v_pk_fma_f32 v[222:223], v[230:231], v[70:71], v[222:223]
	v_cvt_pk_f32_fp8_e32 v[224:225], v194
	v_cvt_pk_f32_fp8_e32 v[226:227], v198
	v_cvt_pk_f32_fp8_e32 v[228:229], v202
	v_cvt_pk_f32_fp8_e32 v[230:231], v206
	v_pk_fma_f32 v[216:217], v[224:225], v[72:73], v[216:217]
	v_pk_fma_f32 v[218:219], v[226:227], v[72:73], v[218:219]
	v_pk_fma_f32 v[220:221], v[228:229], v[72:73], v[220:221]
	v_pk_fma_f32 v[222:223], v[230:231], v[72:73], v[222:223]
	v_cvt_pk_f32_fp8_sdwa v[224:225], v194 src0_sel:WORD_1
	v_cvt_pk_f32_fp8_sdwa v[226:227], v198 src0_sel:WORD_1
	v_cvt_pk_f32_fp8_sdwa v[228:229], v202 src0_sel:WORD_1
	v_cvt_pk_f32_fp8_sdwa v[230:231], v206 src0_sel:WORD_1
	v_pk_fma_f32 v[216:217], v[224:225], v[74:75], v[216:217]
	v_pk_fma_f32 v[218:219], v[226:227], v[74:75], v[218:219]
	v_pk_fma_f32 v[220:221], v[228:229], v[74:75], v[220:221]
	v_pk_fma_f32 v[222:223], v[230:231], v[74:75], v[222:223]
	v_cvt_pk_f32_fp8_e32 v[224:225], v195
	v_cvt_pk_f32_fp8_e32 v[226:227], v199
	v_cvt_pk_f32_fp8_e32 v[228:229], v203
	v_cvt_pk_f32_fp8_e32 v[230:231], v207
	v_pk_fma_f32 v[216:217], v[224:225], v[76:77], v[216:217]
	v_pk_fma_f32 v[218:219], v[226:227], v[76:77], v[218:219]
	v_pk_fma_f32 v[220:221], v[228:229], v[76:77], v[220:221]
	v_pk_fma_f32 v[222:223], v[230:231], v[76:77], v[222:223]
	v_cvt_pk_f32_fp8_sdwa v[224:225], v195 src0_sel:WORD_1
	v_cvt_pk_f32_fp8_sdwa v[226:227], v199 src0_sel:WORD_1
	v_cvt_pk_f32_fp8_sdwa v[228:229], v203 src0_sel:WORD_1
	v_cvt_pk_f32_fp8_sdwa v[230:231], v207 src0_sel:WORD_1
	v_pk_fma_f32 v[216:217], v[224:225], v[78:79], v[216:217]
	v_pk_fma_f32 v[218:219], v[226:227], v[78:79], v[218:219]
	v_pk_fma_f32 v[220:221], v[228:229], v[78:79], v[220:221]
	v_pk_fma_f32 v[222:223], v[230:231], v[78:79], v[222:223]
	s_branch .LU_s4_tail
.LU_s4_t5:
	v_cvt_pk_f32_fp8_e32 v[224:225], v192
	v_cvt_pk_f32_fp8_e32 v[226:227], v196
	v_cvt_pk_f32_fp8_e32 v[228:229], v200
	v_cvt_pk_f32_fp8_e32 v[230:231], v204
	v_pk_mul_f32 v[216:217], v[224:225], v[80:81]
	v_pk_mul_f32 v[218:219], v[226:227], v[80:81]
	v_pk_mul_f32 v[220:221], v[228:229], v[80:81]
	v_pk_mul_f32 v[222:223], v[230:231], v[80:81]
	v_cvt_pk_f32_fp8_sdwa v[224:225], v192 src0_sel:WORD_1
	v_cvt_pk_f32_fp8_sdwa v[226:227], v196 src0_sel:WORD_1
	v_cvt_pk_f32_fp8_sdwa v[228:229], v200 src0_sel:WORD_1
	v_cvt_pk_f32_fp8_sdwa v[230:231], v204 src0_sel:WORD_1
	v_pk_fma_f32 v[216:217], v[224:225], v[82:83], v[216:217]
	v_pk_fma_f32 v[218:219], v[226:227], v[82:83], v[218:219]
	v_pk_fma_f32 v[220:221], v[228:229], v[82:83], v[220:221]
	v_pk_fma_f32 v[222:223], v[230:231], v[82:83], v[222:223]
	v_cvt_pk_f32_fp8_e32 v[224:225], v193
	v_cvt_pk_f32_fp8_e32 v[226:227], v197
	v_cvt_pk_f32_fp8_e32 v[228:229], v201
	v_cvt_pk_f32_fp8_e32 v[230:231], v205
	v_pk_fma_f32 v[216:217], v[224:225], v[84:85], v[216:217]
	v_pk_fma_f32 v[218:219], v[226:227], v[84:85], v[218:219]
	v_pk_fma_f32 v[220:221], v[228:229], v[84:85], v[220:221]
	v_pk_fma_f32 v[222:223], v[230:231], v[84:85], v[222:223]
	v_cvt_pk_f32_fp8_sdwa v[224:225], v193 src0_sel:WORD_1
	v_cvt_pk_f32_fp8_sdwa v[226:227], v197 src0_sel:WORD_1
	v_cvt_pk_f32_fp8_sdwa v[228:229], v201 src0_sel:WORD_1
	v_cvt_pk_f32_fp8_sdwa v[230:231], v205 src0_sel:WORD_1
	v_pk_fma_f32 v[216:217], v[224:225], v[86:87], v[216:217]
	v_pk_fma_f32 v[218:219], v[226:227], v[86:87], v[218:219]
	v_pk_fma_f32 v[220:221], v[228:229], v[86:87], v[220:221]
	v_pk_fma_f32 v[222:223], v[230:231], v[86:87], v[222:223]
	v_cvt_pk_f32_fp8_e32 v[224:225], v194
	v_cvt_pk_f32_fp8_e32 v[226:227], v198
	v_cvt_pk_f32_fp8_e32 v[228:229], v202
	v_cvt_pk_f32_fp8_e32 v[230:231], v206
	v_pk_fma_f32 v[216:217], v[224:225], v[88:89], v[216:217]
	v_pk_fma_f32 v[218:219], v[226:227], v[88:89], v[218:219]
	v_pk_fma_f32 v[220:221], v[228:229], v[88:89], v[220:221]
	v_pk_fma_f32 v[222:223], v[230:231], v[88:89], v[222:223]
	v_cvt_pk_f32_fp8_sdwa v[224:225], v194 src0_sel:WORD_1
	v_cvt_pk_f32_fp8_sdwa v[226:227], v198 src0_sel:WORD_1
	v_cvt_pk_f32_fp8_sdwa v[228:229], v202 src0_sel:WORD_1
	v_cvt_pk_f32_fp8_sdwa v[230:231], v206 src0_sel:WORD_1
	v_pk_fma_f32 v[216:217], v[224:225], v[90:91], v[216:217]
	v_pk_fma_f32 v[218:219], v[226:227], v[90:91], v[218:219]
	v_pk_fma_f32 v[220:221], v[228:229], v[90:91], v[220:221]
	v_pk_fma_f32 v[222:223], v[230:231], v[90:91], v[222:223]
	v_cvt_pk_f32_fp8_e32 v[224:225], v195
	v_cvt_pk_f32_fp8_e32 v[226:227], v199
	v_cvt_pk_f32_fp8_e32 v[228:229], v203
	v_cvt_pk_f32_fp8_e32 v[230:231], v207
	v_pk_fma_f32 v[216:217], v[224:225], v[92:93], v[216:217]
	v_pk_fma_f32 v[218:219], v[226:227], v[92:93], v[218:219]
	v_pk_fma_f32 v[220:221], v[228:229], v[92:93], v[220:221]
	v_pk_fma_f32 v[222:223], v[230:231], v[92:93], v[222:223]
	v_cvt_pk_f32_fp8_sdwa v[224:225], v195 src0_sel:WORD_1
	v_cvt_pk_f32_fp8_sdwa v[226:227], v199 src0_sel:WORD_1
	v_cvt_pk_f32_fp8_sdwa v[228:229], v203 src0_sel:WORD_1
	v_cvt_pk_f32_fp8_sdwa v[230:231], v207 src0_sel:WORD_1
	v_pk_fma_f32 v[216:217], v[224:225], v[94:95], v[216:217]
	v_pk_fma_f32 v[218:219], v[226:227], v[94:95], v[218:219]
	v_pk_fma_f32 v[220:221], v[228:229], v[94:95], v[220:221]
	v_pk_fma_f32 v[222:223], v[230:231], v[94:95], v[222:223]
	s_branch .LU_s4_tail
.LU_s4_t6:
	v_cvt_pk_f32_fp8_e32 v[224:225], v192
	v_cvt_pk_f32_fp8_e32 v[226:227], v196
	v_cvt_pk_f32_fp8_e32 v[228:229], v200
	v_cvt_pk_f32_fp8_e32 v[230:231], v204
	v_pk_mul_f32 v[216:217], v[224:225], v[96:97]
	v_pk_mul_f32 v[218:219], v[226:227], v[96:97]
	v_pk_mul_f32 v[220:221], v[228:229], v[96:97]
	v_pk_mul_f32 v[222:223], v[230:231], v[96:97]
	v_cvt_pk_f32_fp8_sdwa v[224:225], v192 src0_sel:WORD_1
	v_cvt_pk_f32_fp8_sdwa v[226:227], v196 src0_sel:WORD_1
	v_cvt_pk_f32_fp8_sdwa v[228:229], v200 src0_sel:WORD_1
	v_cvt_pk_f32_fp8_sdwa v[230:231], v204 src0_sel:WORD_1
	v_pk_fma_f32 v[216:217], v[224:225], v[98:99], v[216:217]
	v_pk_fma_f32 v[218:219], v[226:227], v[98:99], v[218:219]
	v_pk_fma_f32 v[220:221], v[228:229], v[98:99], v[220:221]
	v_pk_fma_f32 v[222:223], v[230:231], v[98:99], v[222:223]
	v_cvt_pk_f32_fp8_e32 v[224:225], v193
	v_cvt_pk_f32_fp8_e32 v[226:227], v197
	v_cvt_pk_f32_fp8_e32 v[228:229], v201
	v_cvt_pk_f32_fp8_e32 v[230:231], v205
	v_pk_fma_f32 v[216:217], v[224:225], v[100:101], v[216:217]
	v_pk_fma_f32 v[218:219], v[226:227], v[100:101], v[218:219]
	v_pk_fma_f32 v[220:221], v[228:229], v[100:101], v[220:221]
	v_pk_fma_f32 v[222:223], v[230:231], v[100:101], v[222:223]
	v_cvt_pk_f32_fp8_sdwa v[224:225], v193 src0_sel:WORD_1
	v_cvt_pk_f32_fp8_sdwa v[226:227], v197 src0_sel:WORD_1
	v_cvt_pk_f32_fp8_sdwa v[228:229], v201 src0_sel:WORD_1
	v_cvt_pk_f32_fp8_sdwa v[230:231], v205 src0_sel:WORD_1
	v_pk_fma_f32 v[216:217], v[224:225], v[102:103], v[216:217]
	v_pk_fma_f32 v[218:219], v[226:227], v[102:103], v[218:219]
	v_pk_fma_f32 v[220:221], v[228:229], v[102:103], v[220:221]
	v_pk_fma_f32 v[222:223], v[230:231], v[102:103], v[222:223]
	v_cvt_pk_f32_fp8_e32 v[224:225], v194
	v_cvt_pk_f32_fp8_e32 v[226:227], v198
	v_cvt_pk_f32_fp8_e32 v[228:229], v202
	v_cvt_pk_f32_fp8_e32 v[230:231], v206
	v_pk_fma_f32 v[216:217], v[224:225], v[104:105], v[216:217]
	v_pk_fma_f32 v[218:219], v[226:227], v[104:105], v[218:219]
	v_pk_fma_f32 v[220:221], v[228:229], v[104:105], v[220:221]
	v_pk_fma_f32 v[222:223], v[230:231], v[104:105], v[222:223]
	v_cvt_pk_f32_fp8_sdwa v[224:225], v194 src0_sel:WORD_1
	v_cvt_pk_f32_fp8_sdwa v[226:227], v198 src0_sel:WORD_1
	v_cvt_pk_f32_fp8_sdwa v[228:229], v202 src0_sel:WORD_1
	v_cvt_pk_f32_fp8_sdwa v[230:231], v206 src0_sel:WORD_1
	v_pk_fma_f32 v[216:217], v[224:225], v[106:107], v[216:217]
	v_pk_fma_f32 v[218:219], v[226:227], v[106:107], v[218:219]
	v_pk_fma_f32 v[220:221], v[228:229], v[106:107], v[220:221]
	v_pk_fma_f32 v[222:223], v[230:231], v[106:107], v[222:223]
	v_cvt_pk_f32_fp8_e32 v[224:225], v195
	v_cvt_pk_f32_fp8_e32 v[226:227], v199
	v_cvt_pk_f32_fp8_e32 v[228:229], v203
	v_cvt_pk_f32_fp8_e32 v[230:231], v207
	v_pk_fma_f32 v[216:217], v[224:225], v[108:109], v[216:217]
	v_pk_fma_f32 v[218:219], v[226:227], v[108:109], v[218:219]
	v_pk_fma_f32 v[220:221], v[228:229], v[108:109], v[220:221]
	v_pk_fma_f32 v[222:223], v[230:231], v[108:109], v[222:223]
	v_cvt_pk_f32_fp8_sdwa v[224:225], v195 src0_sel:WORD_1
	v_cvt_pk_f32_fp8_sdwa v[226:227], v199 src0_sel:WORD_1
	v_cvt_pk_f32_fp8_sdwa v[228:229], v203 src0_sel:WORD_1
	v_cvt_pk_f32_fp8_sdwa v[230:231], v207 src0_sel:WORD_1
	v_pk_fma_f32 v[216:217], v[224:225], v[110:111], v[216:217]
	v_pk_fma_f32 v[218:219], v[226:227], v[110:111], v[218:219]
	v_pk_fma_f32 v[220:221], v[228:229], v[110:111], v[220:221]
	v_pk_fma_f32 v[222:223], v[230:231], v[110:111], v[222:223]
	s_branch .LU_s4_tail
.LU_s4_t7:
	v_cvt_pk_f32_fp8_e32 v[224:225], v192
	v_cvt_pk_f32_fp8_e32 v[226:227], v196
	v_cvt_pk_f32_fp8_e32 v[228:229], v200
	v_cvt_pk_f32_fp8_e32 v[230:231], v204
	v_pk_mul_f32 v[216:217], v[224:225], v[112:113]
	v_pk_mul_f32 v[218:219], v[226:227], v[112:113]
	v_pk_mul_f32 v[220:221], v[228:229], v[112:113]
	v_pk_mul_f32 v[222:223], v[230:231], v[112:113]
	v_cvt_pk_f32_fp8_sdwa v[224:225], v192 src0_sel:WORD_1
	v_cvt_pk_f32_fp8_sdwa v[226:227], v196 src0_sel:WORD_1
	v_cvt_pk_f32_fp8_sdwa v[228:229], v200 src0_sel:WORD_1
	v_cvt_pk_f32_fp8_sdwa v[230:231], v204 src0_sel:WORD_1
	v_pk_fma_f32 v[216:217], v[224:225], v[114:115], v[216:217]
	v_pk_fma_f32 v[218:219], v[226:227], v[114:115], v[218:219]
	v_pk_fma_f32 v[220:221], v[228:229], v[114:115], v[220:221]
	v_pk_fma_f32 v[222:223], v[230:231], v[114:115], v[222:223]
	v_cvt_pk_f32_fp8_e32 v[224:225], v193
	v_cvt_pk_f32_fp8_e32 v[226:227], v197
	v_cvt_pk_f32_fp8_e32 v[228:229], v201
	v_cvt_pk_f32_fp8_e32 v[230:231], v205
	v_pk_fma_f32 v[216:217], v[224:225], v[116:117], v[216:217]
	v_pk_fma_f32 v[218:219], v[226:227], v[116:117], v[218:219]
	v_pk_fma_f32 v[220:221], v[228:229], v[116:117], v[220:221]
	v_pk_fma_f32 v[222:223], v[230:231], v[116:117], v[222:223]
	v_cvt_pk_f32_fp8_sdwa v[224:225], v193 src0_sel:WORD_1
	v_cvt_pk_f32_fp8_sdwa v[226:227], v197 src0_sel:WORD_1
	v_cvt_pk_f32_fp8_sdwa v[228:229], v201 src0_sel:WORD_1
	v_cvt_pk_f32_fp8_sdwa v[230:231], v205 src0_sel:WORD_1
	v_pk_fma_f32 v[216:217], v[224:225], v[118:119], v[216:217]
	v_pk_fma_f32 v[218:219], v[226:227], v[118:119], v[218:219]
	v_pk_fma_f32 v[220:221], v[228:229], v[118:119], v[220:221]
	v_pk_fma_f32 v[222:223], v[230:231], v[118:119], v[222:223]
	v_cvt_pk_f32_fp8_e32 v[224:225], v194
	v_cvt_pk_f32_fp8_e32 v[226:227], v198
	v_cvt_pk_f32_fp8_e32 v[228:229], v202
	v_cvt_pk_f32_fp8_e32 v[230:231], v206
	v_pk_fma_f32 v[216:217], v[224:225], v[120:121], v[216:217]
	v_pk_fma_f32 v[218:219], v[226:227], v[120:121], v[218:219]
	v_pk_fma_f32 v[220:221], v[228:229], v[120:121], v[220:221]
	v_pk_fma_f32 v[222:223], v[230:231], v[120:121], v[222:223]
	v_cvt_pk_f32_fp8_sdwa v[224:225], v194 src0_sel:WORD_1
	v_cvt_pk_f32_fp8_sdwa v[226:227], v198 src0_sel:WORD_1
	v_cvt_pk_f32_fp8_sdwa v[228:229], v202 src0_sel:WORD_1
	v_cvt_pk_f32_fp8_sdwa v[230:231], v206 src0_sel:WORD_1
	v_pk_fma_f32 v[216:217], v[224:225], v[122:123], v[216:217]
	v_pk_fma_f32 v[218:219], v[226:227], v[122:123], v[218:219]
	v_pk_fma_f32 v[220:221], v[228:229], v[122:123], v[220:221]
	v_pk_fma_f32 v[222:223], v[230:231], v[122:123], v[222:223]
	v_cvt_pk_f32_fp8_e32 v[224:225], v195
	v_cvt_pk_f32_fp8_e32 v[226:227], v199
	v_cvt_pk_f32_fp8_e32 v[228:229], v203
	v_cvt_pk_f32_fp8_e32 v[230:231], v207
	v_pk_fma_f32 v[216:217], v[224:225], v[124:125], v[216:217]
	v_pk_fma_f32 v[218:219], v[226:227], v[124:125], v[218:219]
	v_pk_fma_f32 v[220:221], v[228:229], v[124:125], v[220:221]
	v_pk_fma_f32 v[222:223], v[230:231], v[124:125], v[222:223]
	v_cvt_pk_f32_fp8_sdwa v[224:225], v195 src0_sel:WORD_1
	v_cvt_pk_f32_fp8_sdwa v[226:227], v199 src0_sel:WORD_1
	v_cvt_pk_f32_fp8_sdwa v[228:229], v203 src0_sel:WORD_1
	v_cvt_pk_f32_fp8_sdwa v[230:231], v207 src0_sel:WORD_1
	v_pk_fma_f32 v[216:217], v[224:225], v[126:127], v[216:217]
	v_pk_fma_f32 v[218:219], v[226:227], v[126:127], v[218:219]
	v_pk_fma_f32 v[220:221], v[228:229], v[126:127], v[220:221]
	v_pk_fma_f32 v[222:223], v[230:231], v[126:127], v[222:223]
; __device__ __forceinline__ void peer_tile(const Args& A, LAS unsigned char* lds, int tile) {
;     ...
;             for (int q = 0; q < 8; ++q) oacc[tk][q] = (f32x2){0.f, 0.f}; }
.LU_s4_tail:
	v_add_f32_e32 v216, v216, v217
	v_add_f32_e32 v220, v220, v221
	v_add_f32_e32 v218, v218, v219
	v_add_f32_e32 v222, v222, v223
	s_nop 0
	v_permlane32_swap_b32_e32 v216, v220
	s_nop 0
	v_permlane32_swap_b32_e32 v218, v222
	v_add_f32_e32 v216, v216, v220
	v_add_f32_e32 v218, v218, v222
	s_nop 1
	v_permlane16_swap_b32_e32 v216, v218
	v_add_f32_e32 v216, v216, v218
	s_nop 1
	v_add_f32_dpp v216, v216, v216 quad_perm:[1,0,3,2] row_mask:0xf bank_mask:0xf bound_ctrl:1
	s_nop 1
	v_add_f32_dpp v216, v216, v216 quad_perm:[2,3,0,1] row_mask:0xf bank_mask:0xf bound_ctrl:1
	s_nop 1
	v_add_f32_dpp v216, v216, v216 row_half_mirror row_mask:0xf bank_mask:0xf bound_ctrl:1
	s_nop 1
	v_add_f32_dpp v216, v216, v216 row_mirror row_mask:0xf bank_mask:0xf bound_ctrl:1
	v_mul_f32_e32 v217, v252, v216
	v_fma_f32 v218, |v217|, s72, 1.0
	v_mul_f32_e32 v219, v217, v217
	v_rcp_f32_e32 v218, v218
	v_mul_f32_e32 v219, 0xbf38aa3b, v219
	v_exp_f32_e32 v219, v219
	v_fmamk_f32 v220, v218, 0x3f07dc22, v242
	v_fmaak_f32 v220, v218, v220, 0x3f35f0e3
	v_fmaak_f32 v220, v218, v220, 0xbe11a98e
	v_fmaak_f32 v220, v218, v220, 0x3e027906
	v_mul_f32_e32 v220, v218, v220
	v_mul_f32_e32 v220, v219, v220
	v_mul_f32_e32 v221, v217, v220
	v_fma_f32 v220, -v217, v220, v217
	v_cmp_gt_f32_e32 vcc, 0, v217
	v_lshrrev_b32_e32 v254, 3, v238
	s_nop 0
	v_cndmask_b32_e32 v220, v220, v221, vcc
	v_mul_f32_e32 v220, v237, v220
	v_mul_f32_e32 v220, v212, v220
	ds_write_b32 v254, v220
	ds_read_b128 v[236:239], v241 offset:320
	ds_read_b128 v[232:235], v241 offset:576
	s_add_i32 s21, s21, 1
	v_add_u32_e32 v241, 320, v241
	s_branch .LU_s0
.LU_done:
	s_waitcnt vmcnt(0) lgkmcnt(0)
	s_add_i32 s90, s90, 128
	s_cmp_lt_u32 s90, s91
	s_cbranch_scc1 .LU_win
	s_add_i32 s89, s89, 1
	s_cmp_lt_u32 s89, 4
	s_cbranch_scc1 .LU_chunk
	v_mov_b64_e32 v[0:1], 0
	v_mov_b64_e32 v[2:3], 0
	v_mov_b64_e32 v[4:5], 0
	v_mov_b64_e32 v[6:7], 0
	v_mov_b64_e32 v[8:9], 0
	v_mov_b64_e32 v[10:11], 0
	v_mov_b64_e32 v[12:13], 0
	v_mov_b64_e32 v[14:15], 0
	v_mov_b64_e32 v[16:17], 0
	v_mov_b64_e32 v[18:19], 0
	v_mov_b64_e32 v[20:21], 0
	v_mov_b64_e32 v[22:23], 0
	v_mov_b64_e32 v[24:25], 0
	v_mov_b64_e32 v[26:27], 0
	v_mov_b64_e32 v[28:29], 0
	v_mov_b64_e32 v[30:31], 0
	v_mov_b64_e32 v[32:33], 0
	v_mov_b64_e32 v[34:35], 0
	v_mov_b64_e32 v[36:37], 0
	v_mov_b64_e32 v[38:39], 0
	v_mov_b64_e32 v[40:41], 0
	v_mov_b64_e32 v[42:43], 0
	v_mov_b64_e32 v[44:45], 0
	v_mov_b64_e32 v[46:47], 0
	v_mov_b64_e32 v[48:49], 0
	v_mov_b64_e32 v[50:51], 0
	v_mov_b64_e32 v[52:53], 0
	v_mov_b64_e32 v[54:55], 0
	v_mov_b64_e32 v[56:57], 0
	v_mov_b64_e32 v[58:59], 0
	v_mov_b64_e32 v[60:61], 0
	v_mov_b64_e32 v[62:63], 0
	v_mov_b64_e32 v[64:65], 0
	v_mov_b64_e32 v[66:67], 0
	v_mov_b64_e32 v[68:69], 0
	v_mov_b64_e32 v[70:71], 0
	v_mov_b64_e32 v[72:73], 0
	v_mov_b64_e32 v[74:75], 0
	v_mov_b64_e32 v[76:77], 0
	v_mov_b64_e32 v[78:79], 0
	v_mov_b64_e32 v[80:81], 0
	v_mov_b64_e32 v[82:83], 0
	v_mov_b64_e32 v[84:85], 0
	v_mov_b64_e32 v[86:87], 0
	v_mov_b64_e32 v[88:89], 0
	v_mov_b64_e32 v[90:91], 0
	v_mov_b64_e32 v[92:93], 0
	v_mov_b64_e32 v[94:95], 0
	v_mov_b64_e32 v[96:97], 0
	v_mov_b64_e32 v[98:99], 0
	v_mov_b64_e32 v[100:101], 0
	v_mov_b64_e32 v[102:103], 0
	v_mov_b64_e32 v[104:105], 0
	v_mov_b64_e32 v[106:107], 0
	v_mov_b64_e32 v[108:109], 0
	v_mov_b64_e32 v[110:111], 0
	v_mov_b64_e32 v[112:113], 0
	v_mov_b64_e32 v[114:115], 0
	v_mov_b64_e32 v[116:117], 0
	v_mov_b64_e32 v[118:119], 0
	v_mov_b64_e32 v[120:121], 0
	v_mov_b64_e32 v[122:123], 0
	v_mov_b64_e32 v[124:125], 0
	v_mov_b64_e32 v[126:127], 0
	s_mov_b32 s89, 0

; __device__ __forceinline__ void peer_tile(const Args& A, LAS unsigned char* lds, int tile) {
;     ...
;     for (int ti = 0; ti < 8; ++ti) {
;         const int tl = 8 * w + ti;
;         const u32x2 e0 = SEL[tl * 128 + lane], e1 = SEL[tl * 128 + 64 + lane];
;         const int p0 = (int)(e0.x >> 10), p1 = (int)(e1.x >> 10);
;         int off = 0;
;         for (int p = 0; p < 16; ++p) {
;             const unsigned long long m0 = __ballot(p0 == p), m1 = __ballot(p1 == p);
;             const int c0 = __popcll(m0), c1 = __popcll(m1);
;             const int r0 = __builtin_amdgcn_mbcnt_hi((unsigned)(m0 >> 32), __builtin_amdgcn_mbcnt_lo((unsigned)m0, 0u));
;             const int r1 = __builtin_amdgcn_mbcnt_hi((unsigned)(m1 >> 32), __builtin_amdgcn_mbcnt_lo((unsigned)m1, 0u));
;             if (p0 == p) SORT[tl * 128 + off + r0] = e0;
;             if (p1 == p) SORT[tl * 128 + off + c0 + r1] = e1;
;             if (lane == 0) OFFS[tl * 17 + p] = off;
;             off += c0 + c1;
;         }
;         if (lane == 0) OFFS[tl * 17 + 16] = off;
;     }
.LV_win:
	v_mov_b32_e32 v216, 0
	v_mov_b32_e32 v217, 0
	v_mov_b32_e32 v218, 0x0
	v_mov_b32_e32 v219, 0
	v_add_u32_e32 v220, s22, v240
	ds_write_b128 v220, v[216:219] offset:0
	ds_write_b128 v220, v[216:219] offset:1024
	ds_write_b128 v220, v[216:219] offset:2048
	ds_write_b128 v220, v[216:219] offset:3072
	ds_write_b128 v220, v[216:219] offset:4096
	ds_write_b128 v220, v[216:219] offset:5120
	ds_write_b128 v220, v[216:219] offset:6144
	ds_write_b128 v220, v[216:219] offset:7168
	s_mov_b32 exec_hi, 0
	ds_write_b128 v220, v[216:219] offset:8192
	s_mov_b64 exec, -1
	s_lshl_b32 s0, s76, 10
	s_add_i32 s0, s0, 0x11000
	v_lshrrev_b32_e32 v221, 1, v240
	v_add_u32_e32 v221, s0, v221
	ds_read_b64 v[128:129], v221 offset:0
	ds_read_b64 v[132:133], v221 offset:512
	ds_read_b64 v[136:137], v221 offset:1024
	ds_read_b64 v[140:141], v221 offset:1536
	ds_read_b64 v[144:145], v221 offset:2048
	ds_read_b64 v[148:149], v221 offset:2560
	ds_read_b64 v[152:153], v221 offset:3072
	ds_read_b64 v[156:157], v221 offset:3584
	ds_read_b64 v[160:161], v221 offset:4096
	ds_read_b64 v[164:165], v221 offset:4608
	ds_read_b64 v[168:169], v221 offset:5120
	ds_read_b64 v[172:173], v221 offset:5632
	ds_read_b64 v[176:177], v221 offset:6144
	ds_read_b64 v[180:181], v221 offset:6656
	ds_read_b64 v[184:185], v221 offset:7168
	ds_read_b64 v[188:189], v221 offset:7680
	s_waitcnt lgkmcnt(0)
	v_lshrrev_b32_e32 v192, 10, v128
	v_lshlrev_b32_e32 v128, 10, v128
	v_mov_b32_e32 v130, 0
	v_mov_b32_e32 v131, 0
	v_lshrrev_b32_e32 v193, 10, v132
	v_lshlrev_b32_e32 v132, 10, v132
	v_mov_b32_e32 v134, 0
	v_mov_b32_e32 v135, 0
	v_lshrrev_b32_e32 v194, 10, v136
	v_lshlrev_b32_e32 v136, 10, v136
	v_mov_b32_e32 v138, 1
	v_mov_b32_e32 v139, 0
	v_lshrrev_b32_e32 v195, 10, v140
	v_lshlrev_b32_e32 v140, 10, v140
	v_mov_b32_e32 v142, 1
	v_mov_b32_e32 v143, 0
	v_lshrrev_b32_e32 v196, 10, v144
	v_lshlrev_b32_e32 v144, 10, v144
	v_mov_b32_e32 v146, 2
	v_mov_b32_e32 v147, 0
	v_lshrrev_b32_e32 v197, 10, v148
	v_lshlrev_b32_e32 v148, 10, v148
	v_mov_b32_e32 v150, 2
	v_mov_b32_e32 v151, 0
	v_lshrrev_b32_e32 v198, 10, v152
	v_lshlrev_b32_e32 v152, 10, v152
	v_mov_b32_e32 v154, 3
	v_mov_b32_e32 v155, 0
	v_lshrrev_b32_e32 v199, 10, v156
	v_lshlrev_b32_e32 v156, 10, v156
	v_mov_b32_e32 v158, 3
	v_mov_b32_e32 v159, 0
	v_lshrrev_b32_e32 v200, 10, v160
	v_lshlrev_b32_e32 v160, 10, v160
	v_mov_b32_e32 v162, 4
	v_mov_b32_e32 v163, 0
	v_lshrrev_b32_e32 v201, 10, v164
	v_lshlrev_b32_e32 v164, 10, v164
	v_mov_b32_e32 v166, 4
	v_mov_b32_e32 v167, 0
	v_lshrrev_b32_e32 v202, 10, v168
	v_lshlrev_b32_e32 v168, 10, v168
	v_mov_b32_e32 v170, 5
	v_mov_b32_e32 v171, 0
	v_lshrrev_b32_e32 v203, 10, v172
	v_lshlrev_b32_e32 v172, 10, v172
	v_mov_b32_e32 v174, 5
	v_mov_b32_e32 v175, 0
	v_lshrrev_b32_e32 v204, 10, v176
	v_lshlrev_b32_e32 v176, 10, v176
	v_mov_b32_e32 v178, 6
	v_mov_b32_e32 v179, 0
	v_lshrrev_b32_e32 v205, 10, v180
	v_lshlrev_b32_e32 v180, 10, v180
	v_mov_b32_e32 v182, 6
	v_mov_b32_e32 v183, 0
	v_lshrrev_b32_e32 v206, 10, v184
	v_lshlrev_b32_e32 v184, 10, v184
	v_mov_b32_e32 v186, 7
	v_mov_b32_e32 v187, 0
	v_lshrrev_b32_e32 v207, 10, v188
	v_lshlrev_b32_e32 v188, 10, v188
	v_mov_b32_e32 v190, 7
	v_mov_b32_e32 v191, 0
	s_mul_i32 s74, s89, 4
	s_add_i32 s93, s74, 4
	s_mov_b32 s75, 0
	s_lshl_b32 s37, s90, 2
	s_mov_b32 s42, 512
.LV_bp:
	v_cmp_eq_u32_e64 s[68:69], s74, v192
	v_cmp_eq_u32_e64 s[70:71], s74, v193
	s_nop 0
	s_lshl_b32 s3, s75, 2
	s_sub_i32 s3, s3, s37
	s_bcnt1_i32_b64 s0, s[68:69]
	s_bcnt1_i32_b64 s1, s[70:71]
	v_mbcnt_lo_u32_b32 v222, s68, 0
	v_mbcnt_hi_u32_b32 v222, s69, v222
	v_mbcnt_lo_u32_b32 v223, s70, 0
	v_mbcnt_hi_u32_b32 v223, s71, v223
	v_add_u32_e32 v222, s3, v222
	v_add_u32_e32 v223, s0, v223
	v_add_u32_e32 v223, s3, v223
	v_cmp_gt_u32_e64 s[38:39], s42, v222
	v_cmp_gt_u32_e64 s[40:41], s42, v223
	v_lshl_add_u32 v222, v222, 4, s22
	v_lshl_add_u32 v223, v223, 4, s22
	s_and_b64 exec, s[68:69], s[38:39]
	ds_write_b128 v222, v[128:131]
	s_and_b64 exec, s[70:71], s[40:41]
	ds_write_b128 v223, v[132:135]
	s_mov_b64 exec, -1
	s_add_i32 s0, s0, s1
	s_add_i32 s0, s0, 3
	s_lshr_b32 s0, s0, 2
	s_add_i32 s75, s75, s0
	v_cmp_eq_u32_e64 s[68:69], s74, v194
	v_cmp_eq_u32_e64 s[70:71], s74, v195
	s_nop 0
	s_lshl_b32 s3, s75, 2
	s_sub_i32 s3, s3, s37
	s_bcnt1_i32_b64 s0, s[68:69]
	s_bcnt1_i32_b64 s1, s[70:71]
	v_mbcnt_lo_u32_b32 v222, s68, 0
	v_mbcnt_hi_u32_b32 v222, s69, v222
	v_mbcnt_lo_u32_b32 v223, s70, 0
	v_mbcnt_hi_u32_b32 v223, s71, v223
	v_add_u32_e32 v222, s3, v222
	v_add_u32_e32 v223, s0, v223
	v_add_u32_e32 v223, s3, v223
	v_cmp_gt_u32_e64 s[38:39], s42, v222
	v_cmp_gt_u32_e64 s[40:41], s42, v223
	v_lshl_add_u32 v222, v222, 4, s22
	v_lshl_add_u32 v223, v223, 4, s22
	s_and_b64 exec, s[68:69], s[38:39]
	ds_write_b128 v222, v[136:139]
	s_and_b64 exec, s[70:71], s[40:41]
	ds_write_b128 v223, v[140:143]
	s_mov_b64 exec, -1
	s_add_i32 s0, s0, s1
	s_add_i32 s0, s0, 3
	s_lshr_b32 s0, s0, 2
	s_add_i32 s75, s75, s0
	v_cmp_eq_u32_e64 s[68:69], s74, v196
	v_cmp_eq_u32_e64 s[70:71], s74, v197
	s_nop 0
	s_lshl_b32 s3, s75, 2
	s_sub_i32 s3, s3, s37
	s_bcnt1_i32_b64 s0, s[68:69]
	s_bcnt1_i32_b64 s1, s[70:71]
	v_mbcnt_lo_u32_b32 v222, s68, 0
	v_mbcnt_hi_u32_b32 v222, s69, v222
	v_mbcnt_lo_u32_b32 v223, s70, 0
	v_mbcnt_hi_u32_b32 v223, s71, v223
	v_add_u32_e32 v222, s3, v222
	v_add_u32_e32 v223, s0, v223
	v_add_u32_e32 v223, s3, v223
	v_cmp_gt_u32_e64 s[38:39], s42, v222
	v_cmp_gt_u32_e64 s[40:41], s42, v223
	v_lshl_add_u32 v222, v222, 4, s22
	v_lshl_add_u32 v223, v223, 4, s22
	s_and_b64 exec, s[68:69], s[38:39]
	ds_write_b128 v222, v[144:147]
	s_and_b64 exec, s[70:71], s[40:41]
	ds_write_b128 v223, v[148:151]
; __device__ __forceinline__ void peer_tile(const Args& A, LAS unsigned char* lds, int tile) {
;     ...
;     for (int ti = 0; ti < 8; ++ti) {
;         const int tl = 8 * w + ti;
;         const u32x2 e0 = SEL[tl * 128 + lane], e1 = SEL[tl * 128 + 64 + lane];
;         const int p0 = (int)(e0.x >> 10), p1 = (int)(e1.x >> 10);
;         int off = 0;
;         for (int p = 0; p < 16; ++p) {
;             const unsigned long long m0 = __ballot(p0 == p), m1 = __ballot(p1 == p);
;             const int c0 = __popcll(m0), c1 = __popcll(m1);
;             const int r0 = __builtin_amdgcn_mbcnt_hi((unsigned)(m0 >> 32), __builtin_amdgcn_mbcnt_lo((unsigned)m0, 0u));
;             const int r1 = __builtin_amdgcn_mbcnt_hi((unsigned)(m1 >> 32), __builtin_amdgcn_mbcnt_lo((unsigned)m1, 0u));
;             if (p0 == p) SORT[tl * 128 + off + r0] = e0;
;             if (p1 == p) SORT[tl * 128 + off + c0 + r1] = e1;
;             if (lane == 0) OFFS[tl * 17 + p] = off;
;             off += c0 + c1;
;         }
;         if (lane == 0) OFFS[tl * 17 + 16] = off;
;     }
	s_mov_b64 exec, -1
	s_add_i32 s0, s0, s1
	s_add_i32 s0, s0, 3
	s_lshr_b32 s0, s0, 2
	s_add_i32 s75, s75, s0
	v_cmp_eq_u32_e64 s[68:69], s74, v198
	v_cmp_eq_u32_e64 s[70:71], s74, v199
	s_nop 0
	s_lshl_b32 s3, s75, 2
	s_sub_i32 s3, s3, s37
	s_bcnt1_i32_b64 s0, s[68:69]
	s_bcnt1_i32_b64 s1, s[70:71]
	v_mbcnt_lo_u32_b32 v222, s68, 0
	v_mbcnt_hi_u32_b32 v222, s69, v222
	v_mbcnt_lo_u32_b32 v223, s70, 0
	v_mbcnt_hi_u32_b32 v223, s71, v223
	v_add_u32_e32 v222, s3, v222
	v_add_u32_e32 v223, s0, v223
	v_add_u32_e32 v223, s3, v223
	v_cmp_gt_u32_e64 s[38:39], s42, v222
	v_cmp_gt_u32_e64 s[40:41], s42, v223
	v_lshl_add_u32 v222, v222, 4, s22
	v_lshl_add_u32 v223, v223, 4, s22
	s_and_b64 exec, s[68:69], s[38:39]
	ds_write_b128 v222, v[152:155]
	s_and_b64 exec, s[70:71], s[40:41]
	ds_write_b128 v223, v[156:159]
	s_mov_b64 exec, -1
	s_add_i32 s0, s0, s1
	s_add_i32 s0, s0, 3
	s_lshr_b32 s0, s0, 2
	s_add_i32 s75, s75, s0
	v_cmp_eq_u32_e64 s[68:69], s74, v200
	v_cmp_eq_u32_e64 s[70:71], s74, v201
	s_nop 0
	s_lshl_b32 s3, s75, 2
	s_sub_i32 s3, s3, s37
	s_bcnt1_i32_b64 s0, s[68:69]
	s_bcnt1_i32_b64 s1, s[70:71]
	v_mbcnt_lo_u32_b32 v222, s68, 0
	v_mbcnt_hi_u32_b32 v222, s69, v222
	v_mbcnt_lo_u32_b32 v223, s70, 0
	v_mbcnt_hi_u32_b32 v223, s71, v223
	v_add_u32_e32 v222, s3, v222
	v_add_u32_e32 v223, s0, v223
	v_add_u32_e32 v223, s3, v223
	v_cmp_gt_u32_e64 s[38:39], s42, v222
	v_cmp_gt_u32_e64 s[40:41], s42, v223
	v_lshl_add_u32 v222, v222, 4, s22
	v_lshl_add_u32 v223, v223, 4, s22
	s_and_b64 exec, s[68:69], s[38:39]
	ds_write_b128 v222, v[160:163]
	s_and_b64 exec, s[70:71], s[40:41]
	ds_write_b128 v223, v[164:167]
	s_mov_b64 exec, -1
	s_add_i32 s0, s0, s1
	s_add_i32 s0, s0, 3
	s_lshr_b32 s0, s0, 2
	s_add_i32 s75, s75, s0
	v_cmp_eq_u32_e64 s[68:69], s74, v202
	v_cmp_eq_u32_e64 s[70:71], s74, v203
	s_nop 0
	s_lshl_b32 s3, s75, 2
	s_sub_i32 s3, s3, s37
	s_bcnt1_i32_b64 s0, s[68:69]
	s_bcnt1_i32_b64 s1, s[70:71]
	v_mbcnt_lo_u32_b32 v222, s68, 0
	v_mbcnt_hi_u32_b32 v222, s69, v222
	v_mbcnt_lo_u32_b32 v223, s70, 0
	v_mbcnt_hi_u32_b32 v223, s71, v223
	v_add_u32_e32 v222, s3, v222
	v_add_u32_e32 v223, s0, v223
	v_add_u32_e32 v223, s3, v223
	v_cmp_gt_u32_e64 s[38:39], s42, v222
	v_cmp_gt_u32_e64 s[40:41], s42, v223
	v_lshl_add_u32 v222, v222, 4, s22
	v_lshl_add_u32 v223, v223, 4, s22
	s_and_b64 exec, s[68:69], s[38:39]
	ds_write_b128 v222, v[168:171]
	s_and_b64 exec, s[70:71], s[40:41]
	ds_write_b128 v223, v[172:175]
	s_mov_b64 exec, -1
	s_add_i32 s0, s0, s1
	s_add_i32 s0, s0, 3
	s_lshr_b32 s0, s0, 2
	s_add_i32 s75, s75, s0
	v_cmp_eq_u32_e64 s[68:69], s74, v204
	v_cmp_eq_u32_e64 s[70:71], s74, v205
	s_nop 0
	s_lshl_b32 s3, s75, 2
	s_sub_i32 s3, s3, s37
	s_bcnt1_i32_b64 s0, s[68:69]
	s_bcnt1_i32_b64 s1, s[70:71]
	v_mbcnt_lo_u32_b32 v222, s68, 0
	v_mbcnt_hi_u32_b32 v222, s69, v222
	v_mbcnt_lo_u32_b32 v223, s70, 0
	v_mbcnt_hi_u32_b32 v223, s71, v223
	v_add_u32_e32 v222, s3, v222
	v_add_u32_e32 v223, s0, v223
	v_add_u32_e32 v223, s3, v223
	v_cmp_gt_u32_e64 s[38:39], s42, v222
	v_cmp_gt_u32_e64 s[40:41], s42, v223
	v_lshl_add_u32 v222, v222, 4, s22
	v_lshl_add_u32 v223, v223, 4, s22
	s_and_b64 exec, s[68:69], s[38:39]
	ds_write_b128 v222, v[176:179]
	s_and_b64 exec, s[70:71], s[40:41]
	ds_write_b128 v223, v[180:183]
	s_mov_b64 exec, -1
	s_add_i32 s0, s0, s1
	s_add_i32 s0, s0, 3
	s_lshr_b32 s0, s0, 2
	s_add_i32 s75, s75, s0
	v_cmp_eq_u32_e64 s[68:69], s74, v206
	v_cmp_eq_u32_e64 s[70:71], s74, v207
	s_nop 0
	s_lshl_b32 s3, s75, 2
	s_sub_i32 s3, s3, s37
	s_bcnt1_i32_b64 s0, s[68:69]
	s_bcnt1_i32_b64 s1, s[70:71]
	v_mbcnt_lo_u32_b32 v222, s68, 0
	v_mbcnt_hi_u32_b32 v222, s69, v222
	v_mbcnt_lo_u32_b32 v223, s70, 0
	v_mbcnt_hi_u32_b32 v223, s71, v223
	v_add_u32_e32 v222, s3, v222
	v_add_u32_e32 v223, s0, v223
	v_add_u32_e32 v223, s3, v223
	v_cmp_gt_u32_e64 s[38:39], s42, v222
	v_cmp_gt_u32_e64 s[40:41], s42, v223
	v_lshl_add_u32 v222, v222, 4, s22
	v_lshl_add_u32 v223, v223, 4, s22
	s_and_b64 exec, s[68:69], s[38:39]
	ds_write_b128 v222, v[184:187]
	s_and_b64 exec, s[70:71], s[40:41]
	ds_write_b128 v223, v[188:191]
	s_mov_b64 exec, -1
	s_add_i32 s0, s0, s1
	s_add_i32 s0, s0, 3
	s_lshr_b32 s0, s0, 2
	s_add_i32 s75, s75, s0
	s_add_i32 s74, s74, 1
	s_cmp_lt_u32 s74, s93
	s_cbranch_scc1 .LV_bp
	s_mov_b32 s91, s75
	s_sub_i32 s20, s91, s90
	s_min_u32 s20, s20, 128
	s_waitcnt vmcnt(0) lgkmcnt(0)
	v_add_u32_e32 v241, s22, v247
	ds_read_b128 v[232:235], v241 offset:0
	s_waitcnt lgkmcnt(0)
	v_readlane_b32 s64, v232, 0
	v_readlane_b32 s65, v232, 16
	v_readlane_b32 s66, v232, 32
	v_readlane_b32 s67, v232, 48
	s_add_u32 s24, s6, s64
	s_addc_u32 s25, s7, 0
	s_add_u32 s26, s6, s65
	s_addc_u32 s27, s7, 0
	s_add_u32 s28, s6, s66
	s_addc_u32 s29, s7, 0
	s_add_u32 s30, s6, s67
	s_addc_u32 s31, s7, 0
	global_load_dwordx4 v[128:131], v240, s[24:25]
	global_load_dwordx4 v[132:135], v240, s[26:27]
	global_load_dwordx4 v[136:139], v240, s[28:29]
	global_load_dwordx4 v[140:143], v240, s[30:31]
	ds_read_b128 v[232:235], v241 offset:64
	s_waitcnt lgkmcnt(0)
	v_readlane_b32 s64, v232, 0
	v_readlane_b32 s65, v232, 16
	v_readlane_b32 s66, v232, 32
	v_readlane_b32 s67, v232, 48
	s_add_u32 s24, s6, s64
	s_addc_u32 s25, s7, 0
	s_add_u32 s26, s6, s65
	s_addc_u32 s27, s7, 0
	s_add_u32 s28, s6, s66
	s_addc_u32 s29, s7, 0
	s_add_u32 s30, s6, s67
	s_addc_u32 s31, s7, 0
	global_load_dwordx4 v[144:147], v240, s[24:25]
	global_load_dwordx4 v[148:151], v240, s[26:27]
	global_load_dwordx4 v[152:155], v240, s[28:29]
	global_load_dwordx4 v[156:159], v240, s[30:31]
	ds_read_b128 v[232:235], v241 offset:128
	s_waitcnt lgkmcnt(0)
	v_readlane_b32 s64, v232, 0
	v_readlane_b32 s65, v232, 16
	v_readlane_b32 s66, v232, 32
	v_readlane_b32 s67, v232, 48
	s_add_u32 s24, s6, s64
	s_addc_u32 s25, s7, 0
	s_add_u32 s26, s6, s65
	s_addc_u32 s27, s7, 0
	s_add_u32 s28, s6, s66
	s_addc_u32 s29, s7, 0
	s_add_u32 s30, s6, s67
	s_addc_u32 s31, s7, 0
	global_load_dwordx4 v[160:163], v240, s[24:25]
	global_load_dwordx4 v[164:167], v240, s[26:27]
	global_load_dwordx4 v[168:171], v240, s[28:29]
	global_load_dwordx4 v[172:175], v240, s[30:31]
	ds_read_b128 v[232:235], v241 offset:192
	s_waitcnt lgkmcnt(0)
	v_readlane_b32 s64, v232, 0
	v_readlane_b32 s65, v232, 16
	v_readlane_b32 s66, v232, 32
	v_readlane_b32 s67, v232, 48
	s_add_u32 s24, s6, s64
	s_addc_u32 s25, s7, 0
	s_add_u32 s26, s6, s65
	s_addc_u32 s27, s7, 0
	s_add_u32 s28, s6, s66
	s_addc_u32 s29, s7, 0
	s_add_u32 s30, s6, s67
	s_addc_u32 s31, s7, 0
	global_load_dwordx4 v[176:179], v240, s[24:25]
	global_load_dwordx4 v[180:183], v240, s[26:27]
	global_load_dwordx4 v[184:187], v240, s[28:29]
	global_load_dwordx4 v[188:191], v240, s[30:31]
	ds_read_b128 v[236:239], v241 offset:0
	ds_read_b128 v[232:235], v241 offset:256
	s_mov_b32 s21, 0
.LV_s0:
	s_cmp_ge_u32 s21, s20
	s_cbranch_scc1 .LV_done
	s_waitcnt lgkmcnt(0)
	v_readlane_b32 s64, v232, 0
	v_readlane_b32 s65, v232, 16
	v_readlane_b32 s66, v232, 32
	v_readlane_b32 s67, v232, 48
	s_add_u32 s24, s6, s64
	s_addc_u32 s25, s7, 0
	s_add_u32 s26, s6, s65
	s_addc_u32 s27, s7, 0
	s_add_u32 s28, s6, s66
	s_addc_u32 s29, s7, 0
	s_add_u32 s30, s6, s67
	s_addc_u32 s31, s7, 0
	global_load_dwordx4 v[192:195], v240, s[24:25]
	global_load_dwordx4 v[196:199], v240, s[26:27]
	global_load_dwordx4 v[200:203], v240, s[28:29]
	global_load_dwordx4 v[204:207], v240, s[30:31]
	v_readfirstlane_b32 s23, v238
	v_readlane_b32 s56, v237, 0
	v_readlane_b32 s58, v237, 16
	v_readlane_b32 s60, v237, 32
	v_readlane_b32 s62, v237, 48
	s_and_b32 s23, s23, 7
	s_waitcnt vmcnt(16)
	s_cmp_ge_u32 s23, 4
	s_cbranch_scc1 .LV_s0_h
	s_cmp_ge_u32 s23, 2
	s_cbranch_scc1 .LV_s0_23
	s_cmp_eq_u32 s23, 0
	s_cbranch_scc1 .LV_s0_t0
	s_branch .LV_s0_t1

.LV_s0_t0:
	v_cvt_pk_f32_fp8_e32 v[224:225], v128
	v_cvt_pk_f32_fp8_sdwa v[226:227], v128 src0_sel:WORD_1
	v_cvt_pk_f32_fp8_e32 v[228:229], v129
	v_cvt_pk_f32_fp8_sdwa v[230:231], v129 src0_sel:WORD_1
	v_pk_fma_f32 v[0:1], v[224:225], s[56:57], v[0:1] op_sel_hi:[1,0,1]
	v_pk_fma_f32 v[2:3], v[226:227], s[56:57], v[2:3] op_sel_hi:[1,0,1]
	v_pk_fma_f32 v[4:5], v[228:229], s[56:57], v[4:5] op_sel_hi:[1,0,1]
	v_pk_fma_f32 v[6:7], v[230:231], s[56:57], v[6:7] op_sel_hi:[1,0,1]
	v_cvt_pk_f32_fp8_e32 v[224:225], v130
	v_cvt_pk_f32_fp8_sdwa v[226:227], v130 src0_sel:WORD_1
	v_cvt_pk_f32_fp8_e32 v[228:229], v131
	v_cvt_pk_f32_fp8_sdwa v[230:231], v131 src0_sel:WORD_1
	v_pk_fma_f32 v[8:9], v[224:225], s[56:57], v[8:9] op_sel_hi:[1,0,1]
	v_pk_fma_f32 v[10:11], v[226:227], s[56:57], v[10:11] op_sel_hi:[1,0,1]
	v_pk_fma_f32 v[12:13], v[228:229], s[56:57], v[12:13] op_sel_hi:[1,0,1]
	v_pk_fma_f32 v[14:15], v[230:231], s[56:57], v[14:15] op_sel_hi:[1,0,1]
	v_cvt_pk_f32_fp8_e32 v[224:225], v132
	v_cvt_pk_f32_fp8_sdwa v[226:227], v132 src0_sel:WORD_1
	v_cvt_pk_f32_fp8_e32 v[228:229], v133
	v_cvt_pk_f32_fp8_sdwa v[230:231], v133 src0_sel:WORD_1
	v_pk_fma_f32 v[0:1], v[224:225], s[58:59], v[0:1] op_sel_hi:[1,0,1]
	v_pk_fma_f32 v[2:3], v[226:227], s[58:59], v[2:3] op_sel_hi:[1,0,1]
	v_pk_fma_f32 v[4:5], v[228:229], s[58:59], v[4:5] op_sel_hi:[1,0,1]
	v_pk_fma_f32 v[6:7], v[230:231], s[58:59], v[6:7] op_sel_hi:[1,0,1]
	v_cvt_pk_f32_fp8_e32 v[224:225], v134
	v_cvt_pk_f32_fp8_sdwa v[226:227], v134 src0_sel:WORD_1
	v_cvt_pk_f32_fp8_e32 v[228:229], v135
	v_cvt_pk_f32_fp8_sdwa v[230:231], v135 src0_sel:WORD_1
	v_pk_fma_f32 v[8:9], v[224:225], s[58:59], v[8:9] op_sel_hi:[1,0,1]
	v_pk_fma_f32 v[10:11], v[226:227], s[58:59], v[10:11] op_sel_hi:[1,0,1]
	v_pk_fma_f32 v[12:13], v[228:229], s[58:59], v[12:13] op_sel_hi:[1,0,1]
	v_pk_fma_f32 v[14:15], v[230:231], s[58:59], v[14:15] op_sel_hi:[1,0,1]
	v_cvt_pk_f32_fp8_e32 v[224:225], v136
	v_cvt_pk_f32_fp8_sdwa v[226:227], v136 src0_sel:WORD_1
	v_cvt_pk_f32_fp8_e32 v[228:229], v137
	v_cvt_pk_f32_fp8_sdwa v[230:231], v137 src0_sel:WORD_1
	v_pk_fma_f32 v[0:1], v[224:225], s[60:61], v[0:1] op_sel_hi:[1,0,1]
	v_pk_fma_f32 v[2:3], v[226:227], s[60:61], v[2:3] op_sel_hi:[1,0,1]
	v_pk_fma_f32 v[4:5], v[228:229], s[60:61], v[4:5] op_sel_hi:[1,0,1]
	v_pk_fma_f32 v[6:7], v[230:231], s[60:61], v[6:7] op_sel_hi:[1,0,1]
	v_cvt_pk_f32_fp8_e32 v[224:225], v138
	v_cvt_pk_f32_fp8_sdwa v[226:227], v138 src0_sel:WORD_1
	v_cvt_pk_f32_fp8_e32 v[228:229], v139
	v_cvt_pk_f32_fp8_sdwa v[230:231], v139 src0_sel:WORD_1
	v_pk_fma_f32 v[8:9], v[224:225], s[60:61], v[8:9] op_sel_hi:[1,0,1]
	v_pk_fma_f32 v[10:11], v[226:227], s[60:61], v[10:11] op_sel_hi:[1,0,1]
	v_pk_fma_f32 v[12:13], v[228:229], s[60:61], v[12:13] op_sel_hi:[1,0,1]
	v_pk_fma_f32 v[14:15], v[230:231], s[60:61], v[14:15] op_sel_hi:[1,0,1]
	v_cvt_pk_f32_fp8_e32 v[224:225], v140
	v_cvt_pk_f32_fp8_sdwa v[226:227], v140 src0_sel:WORD_1
	v_cvt_pk_f32_fp8_e32 v[228:229], v141
	v_cvt_pk_f32_fp8_sdwa v[230:231], v141 src0_sel:WORD_1
	v_pk_fma_f32 v[0:1], v[224:225], s[62:63], v[0:1] op_sel_hi:[1,0,1]
	v_pk_fma_f32 v[2:3], v[226:227], s[62:63], v[2:3] op_sel_hi:[1,0,1]
	v_pk_fma_f32 v[4:5], v[228:229], s[62:63], v[4:5] op_sel_hi:[1,0,1]
	v_pk_fma_f32 v[6:7], v[230:231], s[62:63], v[6:7] op_sel_hi:[1,0,1]
	v_cvt_pk_f32_fp8_e32 v[224:225], v142
	v_cvt_pk_f32_fp8_sdwa v[226:227], v142 src0_sel:WORD_1
	v_cvt_pk_f32_fp8_e32 v[228:229], v143
	v_cvt_pk_f32_fp8_sdwa v[230:231], v143 src0_sel:WORD_1
	v_pk_fma_f32 v[8:9], v[224:225], s[62:63], v[8:9] op_sel_hi:[1,0,1]
	v_pk_fma_f32 v[10:11], v[226:227], s[62:63], v[10:11] op_sel_hi:[1,0,1]
	v_pk_fma_f32 v[12:13], v[228:229], s[62:63], v[12:13] op_sel_hi:[1,0,1]
	v_pk_fma_f32 v[14:15], v[230:231], s[62:63], v[14:15] op_sel_hi:[1,0,1]
	s_branch .LV_s0_tail
.LV_s0_t1:
	v_cvt_pk_f32_fp8_e32 v[224:225], v128
	v_cvt_pk_f32_fp8_sdwa v[226:227], v128 src0_sel:WORD_1
	v_cvt_pk_f32_fp8_e32 v[228:229], v129
	v_cvt_pk_f32_fp8_sdwa v[230:231], v129 src0_sel:WORD_1
	v_pk_fma_f32 v[16:17], v[224:225], s[56:57], v[16:17] op_sel_hi:[1,0,1]
	v_pk_fma_f32 v[18:19], v[226:227], s[56:57], v[18:19] op_sel_hi:[1,0,1]
	v_pk_fma_f32 v[20:21], v[228:229], s[56:57], v[20:21] op_sel_hi:[1,0,1]
	v_pk_fma_f32 v[22:23], v[230:231], s[56:57], v[22:23] op_sel_hi:[1,0,1]
	v_cvt_pk_f32_fp8_e32 v[224:225], v130
	v_cvt_pk_f32_fp8_sdwa v[226:227], v130 src0_sel:WORD_1
	v_cvt_pk_f32_fp8_e32 v[228:229], v131
	v_cvt_pk_f32_fp8_sdwa v[230:231], v131 src0_sel:WORD_1
	v_pk_fma_f32 v[24:25], v[224:225], s[56:57], v[24:25] op_sel_hi:[1,0,1]
	v_pk_fma_f32 v[26:27], v[226:227], s[56:57], v[26:27] op_sel_hi:[1,0,1]
	v_pk_fma_f32 v[28:29], v[228:229], s[56:57], v[28:29] op_sel_hi:[1,0,1]
	v_pk_fma_f32 v[30:31], v[230:231], s[56:57], v[30:31] op_sel_hi:[1,0,1]
	v_cvt_pk_f32_fp8_e32 v[224:225], v132
	v_cvt_pk_f32_fp8_sdwa v[226:227], v132 src0_sel:WORD_1
	v_cvt_pk_f32_fp8_e32 v[228:229], v133
	v_cvt_pk_f32_fp8_sdwa v[230:231], v133 src0_sel:WORD_1
	v_pk_fma_f32 v[16:17], v[224:225], s[58:59], v[16:17] op_sel_hi:[1,0,1]
	v_pk_fma_f32 v[18:19], v[226:227], s[58:59], v[18:19] op_sel_hi:[1,0,1]
	v_pk_fma_f32 v[20:21], v[228:229], s[58:59], v[20:21] op_sel_hi:[1,0,1]
	v_pk_fma_f32 v[22:23], v[230:231], s[58:59], v[22:23] op_sel_hi:[1,0,1]
	v_cvt_pk_f32_fp8_e32 v[224:225], v134
	v_cvt_pk_f32_fp8_sdwa v[226:227], v134 src0_sel:WORD_1
	v_cvt_pk_f32_fp8_e32 v[228:229], v135
	v_cvt_pk_f32_fp8_sdwa v[230:231], v135 src0_sel:WORD_1
	v_pk_fma_f32 v[24:25], v[224:225], s[58:59], v[24:25] op_sel_hi:[1,0,1]
	v_pk_fma_f32 v[26:27], v[226:227], s[58:59], v[26:27] op_sel_hi:[1,0,1]
	v_pk_fma_f32 v[28:29], v[228:229], s[58:59], v[28:29] op_sel_hi:[1,0,1]
	v_pk_fma_f32 v[30:31], v[230:231], s[58:59], v[30:31] op_sel_hi:[1,0,1]
	v_cvt_pk_f32_fp8_e32 v[224:225], v136
	v_cvt_pk_f32_fp8_sdwa v[226:227], v136 src0_sel:WORD_1
	v_cvt_pk_f32_fp8_e32 v[228:229], v137
	v_cvt_pk_f32_fp8_sdwa v[230:231], v137 src0_sel:WORD_1
	v_pk_fma_f32 v[16:17], v[224:225], s[60:61], v[16:17] op_sel_hi:[1,0,1]
	v_pk_fma_f32 v[18:19], v[226:227], s[60:61], v[18:19] op_sel_hi:[1,0,1]
	v_pk_fma_f32 v[20:21], v[228:229], s[60:61], v[20:21] op_sel_hi:[1,0,1]
	v_pk_fma_f32 v[22:23], v[230:231], s[60:61], v[22:23] op_sel_hi:[1,0,1]
	v_cvt_pk_f32_fp8_e32 v[224:225], v138
	v_cvt_pk_f32_fp8_sdwa v[226:227], v138 src0_sel:WORD_1
	v_cvt_pk_f32_fp8_e32 v[228:229], v139
	v_cvt_pk_f32_fp8_sdwa v[230:231], v139 src0_sel:WORD_1
	v_pk_fma_f32 v[24:25], v[224:225], s[60:61], v[24:25] op_sel_hi:[1,0,1]
	v_pk_fma_f32 v[26:27], v[226:227], s[60:61], v[26:27] op_sel_hi:[1,0,1]
	v_pk_fma_f32 v[28:29], v[228:229], s[60:61], v[28:29] op_sel_hi:[1,0,1]
	v_pk_fma_f32 v[30:31], v[230:231], s[60:61], v[30:31] op_sel_hi:[1,0,1]
	v_cvt_pk_f32_fp8_e32 v[224:225], v140
	v_cvt_pk_f32_fp8_sdwa v[226:227], v140 src0_sel:WORD_1
	v_cvt_pk_f32_fp8_e32 v[228:229], v141
	v_cvt_pk_f32_fp8_sdwa v[230:231], v141 src0_sel:WORD_1
	v_pk_fma_f32 v[16:17], v[224:225], s[62:63], v[16:17] op_sel_hi:[1,0,1]
	v_pk_fma_f32 v[18:19], v[226:227], s[62:63], v[18:19] op_sel_hi:[1,0,1]
	v_pk_fma_f32 v[20:21], v[228:229], s[62:63], v[20:21] op_sel_hi:[1,0,1]
	v_pk_fma_f32 v[22:23], v[230:231], s[62:63], v[22:23] op_sel_hi:[1,0,1]
	v_cvt_pk_f32_fp8_e32 v[224:225], v142
	v_cvt_pk_f32_fp8_sdwa v[226:227], v142 src0_sel:WORD_1
	v_cvt_pk_f32_fp8_e32 v[228:229], v143
	v_cvt_pk_f32_fp8_sdwa v[230:231], v143 src0_sel:WORD_1
	v_pk_fma_f32 v[24:25], v[224:225], s[62:63], v[24:25] op_sel_hi:[1,0,1]
	v_pk_fma_f32 v[26:27], v[226:227], s[62:63], v[26:27] op_sel_hi:[1,0,1]
	v_pk_fma_f32 v[28:29], v[228:229], s[62:63], v[28:29] op_sel_hi:[1,0,1]
	v_pk_fma_f32 v[30:31], v[230:231], s[62:63], v[30:31] op_sel_hi:[1,0,1]
	s_branch .LV_s0_tail
.LV_s0_t2:
	v_cvt_pk_f32_fp8_e32 v[224:225], v128
	v_cvt_pk_f32_fp8_sdwa v[226:227], v128 src0_sel:WORD_1
	v_cvt_pk_f32_fp8_e32 v[228:229], v129
	v_cvt_pk_f32_fp8_sdwa v[230:231], v129 src0_sel:WORD_1
	v_pk_fma_f32 v[32:33], v[224:225], s[56:57], v[32:33] op_sel_hi:[1,0,1]
	v_pk_fma_f32 v[34:35], v[226:227], s[56:57], v[34:35] op_sel_hi:[1,0,1]
	v_pk_fma_f32 v[36:37], v[228:229], s[56:57], v[36:37] op_sel_hi:[1,0,1]
	v_pk_fma_f32 v[38:39], v[230:231], s[56:57], v[38:39] op_sel_hi:[1,0,1]
	v_cvt_pk_f32_fp8_e32 v[224:225], v130
	v_cvt_pk_f32_fp8_sdwa v[226:227], v130 src0_sel:WORD_1
	v_cvt_pk_f32_fp8_e32 v[228:229], v131
	v_cvt_pk_f32_fp8_sdwa v[230:231], v131 src0_sel:WORD_1
	v_pk_fma_f32 v[40:41], v[224:225], s[56:57], v[40:41] op_sel_hi:[1,0,1]
	v_pk_fma_f32 v[42:43], v[226:227], s[56:57], v[42:43] op_sel_hi:[1,0,1]
	v_pk_fma_f32 v[44:45], v[228:229], s[56:57], v[44:45] op_sel_hi:[1,0,1]
	v_pk_fma_f32 v[46:47], v[230:231], s[56:57], v[46:47] op_sel_hi:[1,0,1]
	v_cvt_pk_f32_fp8_e32 v[224:225], v132
	v_cvt_pk_f32_fp8_sdwa v[226:227], v132 src0_sel:WORD_1
	v_cvt_pk_f32_fp8_e32 v[228:229], v133
	v_cvt_pk_f32_fp8_sdwa v[230:231], v133 src0_sel:WORD_1
	v_pk_fma_f32 v[32:33], v[224:225], s[58:59], v[32:33] op_sel_hi:[1,0,1]
	v_pk_fma_f32 v[34:35], v[226:227], s[58:59], v[34:35] op_sel_hi:[1,0,1]
	v_pk_fma_f32 v[36:37], v[228:229], s[58:59], v[36:37] op_sel_hi:[1,0,1]
	v_pk_fma_f32 v[38:39], v[230:231], s[58:59], v[38:39] op_sel_hi:[1,0,1]
	v_cvt_pk_f32_fp8_e32 v[224:225], v134
	v_cvt_pk_f32_fp8_sdwa v[226:227], v134 src0_sel:WORD_1
	v_cvt_pk_f32_fp8_e32 v[228:229], v135
	v_cvt_pk_f32_fp8_sdwa v[230:231], v135 src0_sel:WORD_1
	v_pk_fma_f32 v[40:41], v[224:225], s[58:59], v[40:41] op_sel_hi:[1,0,1]
	v_pk_fma_f32 v[42:43], v[226:227], s[58:59], v[42:43] op_sel_hi:[1,0,1]
	v_pk_fma_f32 v[44:45], v[228:229], s[58:59], v[44:45] op_sel_hi:[1,0,1]
	v_pk_fma_f32 v[46:47], v[230:231], s[58:59], v[46:47] op_sel_hi:[1,0,1]
	v_cvt_pk_f32_fp8_e32 v[224:225], v136
	v_cvt_pk_f32_fp8_sdwa v[226:227], v136 src0_sel:WORD_1
	v_cvt_pk_f32_fp8_e32 v[228:229], v137
	v_cvt_pk_f32_fp8_sdwa v[230:231], v137 src0_sel:WORD_1
	v_pk_fma_f32 v[32:33], v[224:225], s[60:61], v[32:33] op_sel_hi:[1,0,1]
	v_pk_fma_f32 v[34:35], v[226:227], s[60:61], v[34:35] op_sel_hi:[1,0,1]
	v_pk_fma_f32 v[36:37], v[228:229], s[60:61], v[36:37] op_sel_hi:[1,0,1]
	v_pk_fma_f32 v[38:39], v[230:231], s[60:61], v[38:39] op_sel_hi:[1,0,1]
	v_cvt_pk_f32_fp8_e32 v[224:225], v138
	v_cvt_pk_f32_fp8_sdwa v[226:227], v138 src0_sel:WORD_1
	v_cvt_pk_f32_fp8_e32 v[228:229], v139
	v_cvt_pk_f32_fp8_sdwa v[230:231], v139 src0_sel:WORD_1
	v_pk_fma_f32 v[40:41], v[224:225], s[60:61], v[40:41] op_sel_hi:[1,0,1]
	v_pk_fma_f32 v[42:43], v[226:227], s[60:61], v[42:43] op_sel_hi:[1,0,1]
	v_pk_fma_f32 v[44:45], v[228:229], s[60:61], v[44:45] op_sel_hi:[1,0,1]
	v_pk_fma_f32 v[46:47], v[230:231], s[60:61], v[46:47] op_sel_hi:[1,0,1]
	v_cvt_pk_f32_fp8_e32 v[224:225], v140
	v_cvt_pk_f32_fp8_sdwa v[226:227], v140 src0_sel:WORD_1
	v_cvt_pk_f32_fp8_e32 v[228:229], v141
	v_cvt_pk_f32_fp8_sdwa v[230:231], v141 src0_sel:WORD_1
	v_pk_fma_f32 v[32:33], v[224:225], s[62:63], v[32:33] op_sel_hi:[1,0,1]
	v_pk_fma_f32 v[34:35], v[226:227], s[62:63], v[34:35] op_sel_hi:[1,0,1]
	v_pk_fma_f32 v[36:37], v[228:229], s[62:63], v[36:37] op_sel_hi:[1,0,1]
	v_pk_fma_f32 v[38:39], v[230:231], s[62:63], v[38:39] op_sel_hi:[1,0,1]
	v_cvt_pk_f32_fp8_e32 v[224:225], v142
	v_cvt_pk_f32_fp8_sdwa v[226:227], v142 src0_sel:WORD_1
	v_cvt_pk_f32_fp8_e32 v[228:229], v143
	v_cvt_pk_f32_fp8_sdwa v[230:231], v143 src0_sel:WORD_1
	v_pk_fma_f32 v[40:41], v[224:225], s[62:63], v[40:41] op_sel_hi:[1,0,1]
	v_pk_fma_f32 v[42:43], v[226:227], s[62:63], v[42:43] op_sel_hi:[1,0,1]
	v_pk_fma_f32 v[44:45], v[228:229], s[62:63], v[44:45] op_sel_hi:[1,0,1]
	v_pk_fma_f32 v[46:47], v[230:231], s[62:63], v[46:47] op_sel_hi:[1,0,1]
	s_branch .LV_s0_tail
.LV_s0_t3:
	v_cvt_pk_f32_fp8_e32 v[224:225], v128
	v_cvt_pk_f32_fp8_sdwa v[226:227], v128 src0_sel:WORD_1
	v_cvt_pk_f32_fp8_e32 v[228:229], v129
	v_cvt_pk_f32_fp8_sdwa v[230:231], v129 src0_sel:WORD_1
	v_pk_fma_f32 v[48:49], v[224:225], s[56:57], v[48:49] op_sel_hi:[1,0,1]
	v_pk_fma_f32 v[50:51], v[226:227], s[56:57], v[50:51] op_sel_hi:[1,0,1]
	v_pk_fma_f32 v[52:53], v[228:229], s[56:57], v[52:53] op_sel_hi:[1,0,1]
	v_pk_fma_f32 v[54:55], v[230:231], s[56:57], v[54:55] op_sel_hi:[1,0,1]
	v_cvt_pk_f32_fp8_e32 v[224:225], v130
	v_cvt_pk_f32_fp8_sdwa v[226:227], v130 src0_sel:WORD_1
	v_cvt_pk_f32_fp8_e32 v[228:229], v131
	v_cvt_pk_f32_fp8_sdwa v[230:231], v131 src0_sel:WORD_1
	v_pk_fma_f32 v[56:57], v[224:225], s[56:57], v[56:57] op_sel_hi:[1,0,1]
	v_pk_fma_f32 v[58:59], v[226:227], s[56:57], v[58:59] op_sel_hi:[1,0,1]
	v_pk_fma_f32 v[60:61], v[228:229], s[56:57], v[60:61] op_sel_hi:[1,0,1]
	v_pk_fma_f32 v[62:63], v[230:231], s[56:57], v[62:63] op_sel_hi:[1,0,1]
	v_cvt_pk_f32_fp8_e32 v[224:225], v132
	v_cvt_pk_f32_fp8_sdwa v[226:227], v132 src0_sel:WORD_1
	v_cvt_pk_f32_fp8_e32 v[228:229], v133
	v_cvt_pk_f32_fp8_sdwa v[230:231], v133 src0_sel:WORD_1
	v_pk_fma_f32 v[48:49], v[224:225], s[58:59], v[48:49] op_sel_hi:[1,0,1]
	v_pk_fma_f32 v[50:51], v[226:227], s[58:59], v[50:51] op_sel_hi:[1,0,1]
	v_pk_fma_f32 v[52:53], v[228:229], s[58:59], v[52:53] op_sel_hi:[1,0,1]
	v_pk_fma_f32 v[54:55], v[230:231], s[58:59], v[54:55] op_sel_hi:[1,0,1]
	v_cvt_pk_f32_fp8_e32 v[224:225], v134
	v_cvt_pk_f32_fp8_sdwa v[226:227], v134 src0_sel:WORD_1
	v_cvt_pk_f32_fp8_e32 v[228:229], v135
	v_cvt_pk_f32_fp8_sdwa v[230:231], v135 src0_sel:WORD_1
	v_pk_fma_f32 v[56:57], v[224:225], s[58:59], v[56:57] op_sel_hi:[1,0,1]
	v_pk_fma_f32 v[58:59], v[226:227], s[58:59], v[58:59] op_sel_hi:[1,0,1]
	v_pk_fma_f32 v[60:61], v[228:229], s[58:59], v[60:61] op_sel_hi:[1,0,1]
	v_pk_fma_f32 v[62:63], v[230:231], s[58:59], v[62:63] op_sel_hi:[1,0,1]
	v_cvt_pk_f32_fp8_e32 v[224:225], v136
	v_cvt_pk_f32_fp8_sdwa v[226:227], v136 src0_sel:WORD_1
	v_cvt_pk_f32_fp8_e32 v[228:229], v137
	v_cvt_pk_f32_fp8_sdwa v[230:231], v137 src0_sel:WORD_1
	v_pk_fma_f32 v[48:49], v[224:225], s[60:61], v[48:49] op_sel_hi:[1,0,1]
	v_pk_fma_f32 v[50:51], v[226:227], s[60:61], v[50:51] op_sel_hi:[1,0,1]
	v_pk_fma_f32 v[52:53], v[228:229], s[60:61], v[52:53] op_sel_hi:[1,0,1]
	v_pk_fma_f32 v[54:55], v[230:231], s[60:61], v[54:55] op_sel_hi:[1,0,1]
	v_cvt_pk_f32_fp8_e32 v[224:225], v138
	v_cvt_pk_f32_fp8_sdwa v[226:227], v138 src0_sel:WORD_1
	v_cvt_pk_f32_fp8_e32 v[228:229], v139
	v_cvt_pk_f32_fp8_sdwa v[230:231], v139 src0_sel:WORD_1
	v_pk_fma_f32 v[56:57], v[224:225], s[60:61], v[56:57] op_sel_hi:[1,0,1]
	v_pk_fma_f32 v[58:59], v[226:227], s[60:61], v[58:59] op_sel_hi:[1,0,1]
	v_pk_fma_f32 v[60:61], v[228:229], s[60:61], v[60:61] op_sel_hi:[1,0,1]
	v_pk_fma_f32 v[62:63], v[230:231], s[60:61], v[62:63] op_sel_hi:[1,0,1]
	v_cvt_pk_f32_fp8_e32 v[224:225], v140
	v_cvt_pk_f32_fp8_sdwa v[226:227], v140 src0_sel:WORD_1
	v_cvt_pk_f32_fp8_e32 v[228:229], v141
	v_cvt_pk_f32_fp8_sdwa v[230:231], v141 src0_sel:WORD_1
	v_pk_fma_f32 v[48:49], v[224:225], s[62:63], v[48:49] op_sel_hi:[1,0,1]
	v_pk_fma_f32 v[50:51], v[226:227], s[62:63], v[50:51] op_sel_hi:[1,0,1]
	v_pk_fma_f32 v[52:53], v[228:229], s[62:63], v[52:53] op_sel_hi:[1,0,1]
	v_pk_fma_f32 v[54:55], v[230:231], s[62:63], v[54:55] op_sel_hi:[1,0,1]
	v_cvt_pk_f32_fp8_e32 v[224:225], v142
	v_cvt_pk_f32_fp8_sdwa v[226:227], v142 src0_sel:WORD_1
	v_cvt_pk_f32_fp8_e32 v[228:229], v143
	v_cvt_pk_f32_fp8_sdwa v[230:231], v143 src0_sel:WORD_1
	v_pk_fma_f32 v[56:57], v[224:225], s[62:63], v[56:57] op_sel_hi:[1,0,1]
	v_pk_fma_f32 v[58:59], v[226:227], s[62:63], v[58:59] op_sel_hi:[1,0,1]
	v_pk_fma_f32 v[60:61], v[228:229], s[62:63], v[60:61] op_sel_hi:[1,0,1]
	v_pk_fma_f32 v[62:63], v[230:231], s[62:63], v[62:63] op_sel_hi:[1,0,1]
	s_branch .LV_s0_tail
.LV_s0_t4:
	v_cvt_pk_f32_fp8_e32 v[224:225], v128
	v_cvt_pk_f32_fp8_sdwa v[226:227], v128 src0_sel:WORD_1
	v_cvt_pk_f32_fp8_e32 v[228:229], v129
	v_cvt_pk_f32_fp8_sdwa v[230:231], v129 src0_sel:WORD_1
	v_pk_fma_f32 v[64:65], v[224:225], s[56:57], v[64:65] op_sel_hi:[1,0,1]
	v_pk_fma_f32 v[66:67], v[226:227], s[56:57], v[66:67] op_sel_hi:[1,0,1]
	v_pk_fma_f32 v[68:69], v[228:229], s[56:57], v[68:69] op_sel_hi:[1,0,1]
	v_pk_fma_f32 v[70:71], v[230:231], s[56:57], v[70:71] op_sel_hi:[1,0,1]
	v_cvt_pk_f32_fp8_e32 v[224:225], v130
	v_cvt_pk_f32_fp8_sdwa v[226:227], v130 src0_sel:WORD_1
	v_cvt_pk_f32_fp8_e32 v[228:229], v131
	v_cvt_pk_f32_fp8_sdwa v[230:231], v131 src0_sel:WORD_1
	v_pk_fma_f32 v[72:73], v[224:225], s[56:57], v[72:73] op_sel_hi:[1,0,1]
	v_pk_fma_f32 v[74:75], v[226:227], s[56:57], v[74:75] op_sel_hi:[1,0,1]
	v_pk_fma_f32 v[76:77], v[228:229], s[56:57], v[76:77] op_sel_hi:[1,0,1]
	v_pk_fma_f32 v[78:79], v[230:231], s[56:57], v[78:79] op_sel_hi:[1,0,1]
	v_cvt_pk_f32_fp8_e32 v[224:225], v132
	v_cvt_pk_f32_fp8_sdwa v[226:227], v132 src0_sel:WORD_1
	v_cvt_pk_f32_fp8_e32 v[228:229], v133
	v_cvt_pk_f32_fp8_sdwa v[230:231], v133 src0_sel:WORD_1
	v_pk_fma_f32 v[64:65], v[224:225], s[58:59], v[64:65] op_sel_hi:[1,0,1]
	v_pk_fma_f32 v[66:67], v[226:227], s[58:59], v[66:67] op_sel_hi:[1,0,1]
	v_pk_fma_f32 v[68:69], v[228:229], s[58:59], v[68:69] op_sel_hi:[1,0,1]
	v_pk_fma_f32 v[70:71], v[230:231], s[58:59], v[70:71] op_sel_hi:[1,0,1]
	v_cvt_pk_f32_fp8_e32 v[224:225], v134
	v_cvt_pk_f32_fp8_sdwa v[226:227], v134 src0_sel:WORD_1
	v_cvt_pk_f32_fp8_e32 v[228:229], v135
	v_cvt_pk_f32_fp8_sdwa v[230:231], v135 src0_sel:WORD_1
	v_pk_fma_f32 v[72:73], v[224:225], s[58:59], v[72:73] op_sel_hi:[1,0,1]
	v_pk_fma_f32 v[74:75], v[226:227], s[58:59], v[74:75] op_sel_hi:[1,0,1]
	v_pk_fma_f32 v[76:77], v[228:229], s[58:59], v[76:77] op_sel_hi:[1,0,1]
	v_pk_fma_f32 v[78:79], v[230:231], s[58:59], v[78:79] op_sel_hi:[1,0,1]
	v_cvt_pk_f32_fp8_e32 v[224:225], v136
	v_cvt_pk_f32_fp8_sdwa v[226:227], v136 src0_sel:WORD_1
	v_cvt_pk_f32_fp8_e32 v[228:229], v137
	v_cvt_pk_f32_fp8_sdwa v[230:231], v137 src0_sel:WORD_1
	v_pk_fma_f32 v[64:65], v[224:225], s[60:61], v[64:65] op_sel_hi:[1,0,1]
	v_pk_fma_f32 v[66:67], v[226:227], s[60:61], v[66:67] op_sel_hi:[1,0,1]
	v_pk_fma_f32 v[68:69], v[228:229], s[60:61], v[68:69] op_sel_hi:[1,0,1]
	v_pk_fma_f32 v[70:71], v[230:231], s[60:61], v[70:71] op_sel_hi:[1,0,1]
	v_cvt_pk_f32_fp8_e32 v[224:225], v138
	v_cvt_pk_f32_fp8_sdwa v[226:227], v138 src0_sel:WORD_1
	v_cvt_pk_f32_fp8_e32 v[228:229], v139
	v_cvt_pk_f32_fp8_sdwa v[230:231], v139 src0_sel:WORD_1
	v_pk_fma_f32 v[72:73], v[224:225], s[60:61], v[72:73] op_sel_hi:[1,0,1]
	v_pk_fma_f32 v[74:75], v[226:227], s[60:61], v[74:75] op_sel_hi:[1,0,1]
	v_pk_fma_f32 v[76:77], v[228:229], s[60:61], v[76:77] op_sel_hi:[1,0,1]
	v_pk_fma_f32 v[78:79], v[230:231], s[60:61], v[78:79] op_sel_hi:[1,0,1]
	v_cvt_pk_f32_fp8_e32 v[224:225], v140
	v_cvt_pk_f32_fp8_sdwa v[226:227], v140 src0_sel:WORD_1
	v_cvt_pk_f32_fp8_e32 v[228:229], v141
	v_cvt_pk_f32_fp8_sdwa v[230:231], v141 src0_sel:WORD_1
	v_pk_fma_f32 v[64:65], v[224:225], s[62:63], v[64:65] op_sel_hi:[1,0,1]
	v_pk_fma_f32 v[66:67], v[226:227], s[62:63], v[66:67] op_sel_hi:[1,0,1]
	v_pk_fma_f32 v[68:69], v[228:229], s[62:63], v[68:69] op_sel_hi:[1,0,1]
	v_pk_fma_f32 v[70:71], v[230:231], s[62:63], v[70:71] op_sel_hi:[1,0,1]
	v_cvt_pk_f32_fp8_e32 v[224:225], v142
	v_cvt_pk_f32_fp8_sdwa v[226:227], v142 src0_sel:WORD_1
	v_cvt_pk_f32_fp8_e32 v[228:229], v143
	v_cvt_pk_f32_fp8_sdwa v[230:231], v143 src0_sel:WORD_1
	v_pk_fma_f32 v[72:73], v[224:225], s[62:63], v[72:73] op_sel_hi:[1,0,1]
	v_pk_fma_f32 v[74:75], v[226:227], s[62:63], v[74:75] op_sel_hi:[1,0,1]
	v_pk_fma_f32 v[76:77], v[228:229], s[62:63], v[76:77] op_sel_hi:[1,0,1]
	v_pk_fma_f32 v[78:79], v[230:231], s[62:63], v[78:79] op_sel_hi:[1,0,1]
	s_branch .LV_s0_tail
.LV_s0_t5:
	v_cvt_pk_f32_fp8_e32 v[224:225], v128
	v_cvt_pk_f32_fp8_sdwa v[226:227], v128 src0_sel:WORD_1
	v_cvt_pk_f32_fp8_e32 v[228:229], v129
	v_cvt_pk_f32_fp8_sdwa v[230:231], v129 src0_sel:WORD_1
	v_pk_fma_f32 v[80:81], v[224:225], s[56:57], v[80:81] op_sel_hi:[1,0,1]
	v_pk_fma_f32 v[82:83], v[226:227], s[56:57], v[82:83] op_sel_hi:[1,0,1]
	v_pk_fma_f32 v[84:85], v[228:229], s[56:57], v[84:85] op_sel_hi:[1,0,1]
	v_pk_fma_f32 v[86:87], v[230:231], s[56:57], v[86:87] op_sel_hi:[1,0,1]
	v_cvt_pk_f32_fp8_e32 v[224:225], v130
	v_cvt_pk_f32_fp8_sdwa v[226:227], v130 src0_sel:WORD_1
	v_cvt_pk_f32_fp8_e32 v[228:229], v131
	v_cvt_pk_f32_fp8_sdwa v[230:231], v131 src0_sel:WORD_1
	v_pk_fma_f32 v[88:89], v[224:225], s[56:57], v[88:89] op_sel_hi:[1,0,1]
	v_pk_fma_f32 v[90:91], v[226:227], s[56:57], v[90:91] op_sel_hi:[1,0,1]
	v_pk_fma_f32 v[92:93], v[228:229], s[56:57], v[92:93] op_sel_hi:[1,0,1]
	v_pk_fma_f32 v[94:95], v[230:231], s[56:57], v[94:95] op_sel_hi:[1,0,1]
	v_cvt_pk_f32_fp8_e32 v[224:225], v132
	v_cvt_pk_f32_fp8_sdwa v[226:227], v132 src0_sel:WORD_1
	v_cvt_pk_f32_fp8_e32 v[228:229], v133
	v_cvt_pk_f32_fp8_sdwa v[230:231], v133 src0_sel:WORD_1
	v_pk_fma_f32 v[80:81], v[224:225], s[58:59], v[80:81] op_sel_hi:[1,0,1]
	v_pk_fma_f32 v[82:83], v[226:227], s[58:59], v[82:83] op_sel_hi:[1,0,1]
	v_pk_fma_f32 v[84:85], v[228:229], s[58:59], v[84:85] op_sel_hi:[1,0,1]
	v_pk_fma_f32 v[86:87], v[230:231], s[58:59], v[86:87] op_sel_hi:[1,0,1]
	v_cvt_pk_f32_fp8_e32 v[224:225], v134
	v_cvt_pk_f32_fp8_sdwa v[226:227], v134 src0_sel:WORD_1
	v_cvt_pk_f32_fp8_e32 v[228:229], v135
	v_cvt_pk_f32_fp8_sdwa v[230:231], v135 src0_sel:WORD_1
	v_pk_fma_f32 v[88:89], v[224:225], s[58:59], v[88:89] op_sel_hi:[1,0,1]
	v_pk_fma_f32 v[90:91], v[226:227], s[58:59], v[90:91] op_sel_hi:[1,0,1]
	v_pk_fma_f32 v[92:93], v[228:229], s[58:59], v[92:93] op_sel_hi:[1,0,1]
	v_pk_fma_f32 v[94:95], v[230:231], s[58:59], v[94:95] op_sel_hi:[1,0,1]
	v_cvt_pk_f32_fp8_e32 v[224:225], v136
	v_cvt_pk_f32_fp8_sdwa v[226:227], v136 src0_sel:WORD_1
	v_cvt_pk_f32_fp8_e32 v[228:229], v137
	v_cvt_pk_f32_fp8_sdwa v[230:231], v137 src0_sel:WORD_1
	v_pk_fma_f32 v[80:81], v[224:225], s[60:61], v[80:81] op_sel_hi:[1,0,1]
	v_pk_fma_f32 v[82:83], v[226:227], s[60:61], v[82:83] op_sel_hi:[1,0,1]
	v_pk_fma_f32 v[84:85], v[228:229], s[60:61], v[84:85] op_sel_hi:[1,0,1]
	v_pk_fma_f32 v[86:87], v[230:231], s[60:61], v[86:87] op_sel_hi:[1,0,1]
	v_cvt_pk_f32_fp8_e32 v[224:225], v138
	v_cvt_pk_f32_fp8_sdwa v[226:227], v138 src0_sel:WORD_1
	v_cvt_pk_f32_fp8_e32 v[228:229], v139
	v_cvt_pk_f32_fp8_sdwa v[230:231], v139 src0_sel:WORD_1
	v_pk_fma_f32 v[88:89], v[224:225], s[60:61], v[88:89] op_sel_hi:[1,0,1]
	v_pk_fma_f32 v[90:91], v[226:227], s[60:61], v[90:91] op_sel_hi:[1,0,1]
	v_pk_fma_f32 v[92:93], v[228:229], s[60:61], v[92:93] op_sel_hi:[1,0,1]
	v_pk_fma_f32 v[94:95], v[230:231], s[60:61], v[94:95] op_sel_hi:[1,0,1]
	v_cvt_pk_f32_fp8_e32 v[224:225], v140
	v_cvt_pk_f32_fp8_sdwa v[226:227], v140 src0_sel:WORD_1
	v_cvt_pk_f32_fp8_e32 v[228:229], v141
	v_cvt_pk_f32_fp8_sdwa v[230:231], v141 src0_sel:WORD_1
	v_pk_fma_f32 v[80:81], v[224:225], s[62:63], v[80:81] op_sel_hi:[1,0,1]
	v_pk_fma_f32 v[82:83], v[226:227], s[62:63], v[82:83] op_sel_hi:[1,0,1]
	v_pk_fma_f32 v[84:85], v[228:229], s[62:63], v[84:85] op_sel_hi:[1,0,1]
	v_pk_fma_f32 v[86:87], v[230:231], s[62:63], v[86:87] op_sel_hi:[1,0,1]
	v_cvt_pk_f32_fp8_e32 v[224:225], v142
	v_cvt_pk_f32_fp8_sdwa v[226:227], v142 src0_sel:WORD_1
	v_cvt_pk_f32_fp8_e32 v[228:229], v143
	v_cvt_pk_f32_fp8_sdwa v[230:231], v143 src0_sel:WORD_1
	v_pk_fma_f32 v[88:89], v[224:225], s[62:63], v[88:89] op_sel_hi:[1,0,1]
	v_pk_fma_f32 v[90:91], v[226:227], s[62:63], v[90:91] op_sel_hi:[1,0,1]
	v_pk_fma_f32 v[92:93], v[228:229], s[62:63], v[92:93] op_sel_hi:[1,0,1]
	v_pk_fma_f32 v[94:95], v[230:231], s[62:63], v[94:95] op_sel_hi:[1,0,1]
	s_branch .LV_s0_tail
.LV_s0_t6:
	v_cvt_pk_f32_fp8_e32 v[224:225], v128
	v_cvt_pk_f32_fp8_sdwa v[226:227], v128 src0_sel:WORD_1
	v_cvt_pk_f32_fp8_e32 v[228:229], v129
	v_cvt_pk_f32_fp8_sdwa v[230:231], v129 src0_sel:WORD_1
	v_pk_fma_f32 v[96:97], v[224:225], s[56:57], v[96:97] op_sel_hi:[1,0,1]
	v_pk_fma_f32 v[98:99], v[226:227], s[56:57], v[98:99] op_sel_hi:[1,0,1]
	v_pk_fma_f32 v[100:101], v[228:229], s[56:57], v[100:101] op_sel_hi:[1,0,1]
	v_pk_fma_f32 v[102:103], v[230:231], s[56:57], v[102:103] op_sel_hi:[1,0,1]
	v_cvt_pk_f32_fp8_e32 v[224:225], v130
	v_cvt_pk_f32_fp8_sdwa v[226:227], v130 src0_sel:WORD_1
	v_cvt_pk_f32_fp8_e32 v[228:229], v131
	v_cvt_pk_f32_fp8_sdwa v[230:231], v131 src0_sel:WORD_1
	v_pk_fma_f32 v[104:105], v[224:225], s[56:57], v[104:105] op_sel_hi:[1,0,1]
	v_pk_fma_f32 v[106:107], v[226:227], s[56:57], v[106:107] op_sel_hi:[1,0,1]
	v_pk_fma_f32 v[108:109], v[228:229], s[56:57], v[108:109] op_sel_hi:[1,0,1]
	v_pk_fma_f32 v[110:111], v[230:231], s[56:57], v[110:111] op_sel_hi:[1,0,1]
	v_cvt_pk_f32_fp8_e32 v[224:225], v132
	v_cvt_pk_f32_fp8_sdwa v[226:227], v132 src0_sel:WORD_1
	v_cvt_pk_f32_fp8_e32 v[228:229], v133
	v_cvt_pk_f32_fp8_sdwa v[230:231], v133 src0_sel:WORD_1
	v_pk_fma_f32 v[96:97], v[224:225], s[58:59], v[96:97] op_sel_hi:[1,0,1]
	v_pk_fma_f32 v[98:99], v[226:227], s[58:59], v[98:99] op_sel_hi:[1,0,1]
	v_pk_fma_f32 v[100:101], v[228:229], s[58:59], v[100:101] op_sel_hi:[1,0,1]
	v_pk_fma_f32 v[102:103], v[230:231], s[58:59], v[102:103] op_sel_hi:[1,0,1]
	v_cvt_pk_f32_fp8_e32 v[224:225], v134
	v_cvt_pk_f32_fp8_sdwa v[226:227], v134 src0_sel:WORD_1
	v_cvt_pk_f32_fp8_e32 v[228:229], v135
	v_cvt_pk_f32_fp8_sdwa v[230:231], v135 src0_sel:WORD_1
	v_pk_fma_f32 v[104:105], v[224:225], s[58:59], v[104:105] op_sel_hi:[1,0,1]
	v_pk_fma_f32 v[106:107], v[226:227], s[58:59], v[106:107] op_sel_hi:[1,0,1]
	v_pk_fma_f32 v[108:109], v[228:229], s[58:59], v[108:109] op_sel_hi:[1,0,1]
	v_pk_fma_f32 v[110:111], v[230:231], s[58:59], v[110:111] op_sel_hi:[1,0,1]
	v_cvt_pk_f32_fp8_e32 v[224:225], v136
	v_cvt_pk_f32_fp8_sdwa v[226:227], v136 src0_sel:WORD_1
	v_cvt_pk_f32_fp8_e32 v[228:229], v137
	v_cvt_pk_f32_fp8_sdwa v[230:231], v137 src0_sel:WORD_1
	v_pk_fma_f32 v[96:97], v[224:225], s[60:61], v[96:97] op_sel_hi:[1,0,1]
	v_pk_fma_f32 v[98:99], v[226:227], s[60:61], v[98:99] op_sel_hi:[1,0,1]
	v_pk_fma_f32 v[100:101], v[228:229], s[60:61], v[100:101] op_sel_hi:[1,0,1]
	v_pk_fma_f32 v[102:103], v[230:231], s[60:61], v[102:103] op_sel_hi:[1,0,1]
	v_cvt_pk_f32_fp8_e32 v[224:225], v138
	v_cvt_pk_f32_fp8_sdwa v[226:227], v138 src0_sel:WORD_1
	v_cvt_pk_f32_fp8_e32 v[228:229], v139
	v_cvt_pk_f32_fp8_sdwa v[230:231], v139 src0_sel:WORD_1
	v_pk_fma_f32 v[104:105], v[224:225], s[60:61], v[104:105] op_sel_hi:[1,0,1]
	v_pk_fma_f32 v[106:107], v[226:227], s[60:61], v[106:107] op_sel_hi:[1,0,1]
	v_pk_fma_f32 v[108:109], v[228:229], s[60:61], v[108:109] op_sel_hi:[1,0,1]
	v_pk_fma_f32 v[110:111], v[230:231], s[60:61], v[110:111] op_sel_hi:[1,0,1]
	v_cvt_pk_f32_fp8_e32 v[224:225], v140
	v_cvt_pk_f32_fp8_sdwa v[226:227], v140 src0_sel:WORD_1
	v_cvt_pk_f32_fp8_e32 v[228:229], v141
	v_cvt_pk_f32_fp8_sdwa v[230:231], v141 src0_sel:WORD_1
	v_pk_fma_f32 v[96:97], v[224:225], s[62:63], v[96:97] op_sel_hi:[1,0,1]
	v_pk_fma_f32 v[98:99], v[226:227], s[62:63], v[98:99] op_sel_hi:[1,0,1]
	v_pk_fma_f32 v[100:101], v[228:229], s[62:63], v[100:101] op_sel_hi:[1,0,1]
	v_pk_fma_f32 v[102:103], v[230:231], s[62:63], v[102:103] op_sel_hi:[1,0,1]
	v_cvt_pk_f32_fp8_e32 v[224:225], v142
	v_cvt_pk_f32_fp8_sdwa v[226:227], v142 src0_sel:WORD_1
	v_cvt_pk_f32_fp8_e32 v[228:229], v143
	v_cvt_pk_f32_fp8_sdwa v[230:231], v143 src0_sel:WORD_1
	v_pk_fma_f32 v[104:105], v[224:225], s[62:63], v[104:105] op_sel_hi:[1,0,1]
	v_pk_fma_f32 v[106:107], v[226:227], s[62:63], v[106:107] op_sel_hi:[1,0,1]
	v_pk_fma_f32 v[108:109], v[228:229], s[62:63], v[108:109] op_sel_hi:[1,0,1]
	v_pk_fma_f32 v[110:111], v[230:231], s[62:63], v[110:111] op_sel_hi:[1,0,1]
	s_branch .LV_s0_tail
.LV_s0_t7:
	v_cvt_pk_f32_fp8_e32 v[224:225], v128
	v_cvt_pk_f32_fp8_sdwa v[226:227], v128 src0_sel:WORD_1
	v_cvt_pk_f32_fp8_e32 v[228:229], v129
	v_cvt_pk_f32_fp8_sdwa v[230:231], v129 src0_sel:WORD_1
	v_pk_fma_f32 v[112:113], v[224:225], s[56:57], v[112:113] op_sel_hi:[1,0,1]
	v_pk_fma_f32 v[114:115], v[226:227], s[56:57], v[114:115] op_sel_hi:[1,0,1]
	v_pk_fma_f32 v[116:117], v[228:229], s[56:57], v[116:117] op_sel_hi:[1,0,1]
	v_pk_fma_f32 v[118:119], v[230:231], s[56:57], v[118:119] op_sel_hi:[1,0,1]
	v_cvt_pk_f32_fp8_e32 v[224:225], v130
	v_cvt_pk_f32_fp8_sdwa v[226:227], v130 src0_sel:WORD_1
	v_cvt_pk_f32_fp8_e32 v[228:229], v131
	v_cvt_pk_f32_fp8_sdwa v[230:231], v131 src0_sel:WORD_1
	v_pk_fma_f32 v[120:121], v[224:225], s[56:57], v[120:121] op_sel_hi:[1,0,1]
	v_pk_fma_f32 v[122:123], v[226:227], s[56:57], v[122:123] op_sel_hi:[1,0,1]
	v_pk_fma_f32 v[124:125], v[228:229], s[56:57], v[124:125] op_sel_hi:[1,0,1]
	v_pk_fma_f32 v[126:127], v[230:231], s[56:57], v[126:127] op_sel_hi:[1,0,1]
	v_cvt_pk_f32_fp8_e32 v[224:225], v132
	v_cvt_pk_f32_fp8_sdwa v[226:227], v132 src0_sel:WORD_1
	v_cvt_pk_f32_fp8_e32 v[228:229], v133
	v_cvt_pk_f32_fp8_sdwa v[230:231], v133 src0_sel:WORD_1
	v_pk_fma_f32 v[112:113], v[224:225], s[58:59], v[112:113] op_sel_hi:[1,0,1]
	v_pk_fma_f32 v[114:115], v[226:227], s[58:59], v[114:115] op_sel_hi:[1,0,1]
	v_pk_fma_f32 v[116:117], v[228:229], s[58:59], v[116:117] op_sel_hi:[1,0,1]
	v_pk_fma_f32 v[118:119], v[230:231], s[58:59], v[118:119] op_sel_hi:[1,0,1]
	v_cvt_pk_f32_fp8_e32 v[224:225], v134
	v_cvt_pk_f32_fp8_sdwa v[226:227], v134 src0_sel:WORD_1
	v_cvt_pk_f32_fp8_e32 v[228:229], v135
	v_cvt_pk_f32_fp8_sdwa v[230:231], v135 src0_sel:WORD_1
	v_pk_fma_f32 v[120:121], v[224:225], s[58:59], v[120:121] op_sel_hi:[1,0,1]
	v_pk_fma_f32 v[122:123], v[226:227], s[58:59], v[122:123] op_sel_hi:[1,0,1]
	v_pk_fma_f32 v[124:125], v[228:229], s[58:59], v[124:125] op_sel_hi:[1,0,1]
	v_pk_fma_f32 v[126:127], v[230:231], s[58:59], v[126:127] op_sel_hi:[1,0,1]
	v_cvt_pk_f32_fp8_e32 v[224:225], v136
	v_cvt_pk_f32_fp8_sdwa v[226:227], v136 src0_sel:WORD_1
	v_cvt_pk_f32_fp8_e32 v[228:229], v137
	v_cvt_pk_f32_fp8_sdwa v[230:231], v137 src0_sel:WORD_1
	v_pk_fma_f32 v[112:113], v[224:225], s[60:61], v[112:113] op_sel_hi:[1,0,1]
	v_pk_fma_f32 v[114:115], v[226:227], s[60:61], v[114:115] op_sel_hi:[1,0,1]
	v_pk_fma_f32 v[116:117], v[228:229], s[60:61], v[116:117] op_sel_hi:[1,0,1]
	v_pk_fma_f32 v[118:119], v[230:231], s[60:61], v[118:119] op_sel_hi:[1,0,1]
	v_cvt_pk_f32_fp8_e32 v[224:225], v138
	v_cvt_pk_f32_fp8_sdwa v[226:227], v138 src0_sel:WORD_1
	v_cvt_pk_f32_fp8_e32 v[228:229], v139
	v_cvt_pk_f32_fp8_sdwa v[230:231], v139 src0_sel:WORD_1
	v_pk_fma_f32 v[120:121], v[224:225], s[60:61], v[120:121] op_sel_hi:[1,0,1]
	v_pk_fma_f32 v[122:123], v[226:227], s[60:61], v[122:123] op_sel_hi:[1,0,1]
	v_pk_fma_f32 v[124:125], v[228:229], s[60:61], v[124:125] op_sel_hi:[1,0,1]
	v_pk_fma_f32 v[126:127], v[230:231], s[60:61], v[126:127] op_sel_hi:[1,0,1]
	v_cvt_pk_f32_fp8_e32 v[224:225], v140
	v_cvt_pk_f32_fp8_sdwa v[226:227], v140 src0_sel:WORD_1
	v_cvt_pk_f32_fp8_e32 v[228:229], v141
	v_cvt_pk_f32_fp8_sdwa v[230:231], v141 src0_sel:WORD_1
	v_pk_fma_f32 v[112:113], v[224:225], s[62:63], v[112:113] op_sel_hi:[1,0,1]
	v_pk_fma_f32 v[114:115], v[226:227], s[62:63], v[114:115] op_sel_hi:[1,0,1]
	v_pk_fma_f32 v[116:117], v[228:229], s[62:63], v[116:117] op_sel_hi:[1,0,1]
	v_pk_fma_f32 v[118:119], v[230:231], s[62:63], v[118:119] op_sel_hi:[1,0,1]
	v_cvt_pk_f32_fp8_e32 v[224:225], v142
	v_cvt_pk_f32_fp8_sdwa v[226:227], v142 src0_sel:WORD_1
	v_cvt_pk_f32_fp8_e32 v[228:229], v143
	v_cvt_pk_f32_fp8_sdwa v[230:231], v143 src0_sel:WORD_1
	v_pk_fma_f32 v[120:121], v[224:225], s[62:63], v[120:121] op_sel_hi:[1,0,1]
	v_pk_fma_f32 v[122:123], v[226:227], s[62:63], v[122:123] op_sel_hi:[1,0,1]
	v_pk_fma_f32 v[124:125], v[228:229], s[62:63], v[124:125] op_sel_hi:[1,0,1]
	v_pk_fma_f32 v[126:127], v[230:231], s[62:63], v[126:127] op_sel_hi:[1,0,1]
.LV_s0_tail:
	ds_read_b128 v[236:239], v241 offset:64
	ds_read_b128 v[232:235], v241 offset:320
	s_add_i32 s21, s21, 1
.LV_s1:
	s_cmp_ge_u32 s21, s20
	s_cbranch_scc1 .LV_done
	s_waitcnt lgkmcnt(0)
	v_readlane_b32 s64, v232, 0
	v_readlane_b32 s65, v232, 16
	v_readlane_b32 s66, v232, 32
	v_readlane_b32 s67, v232, 48
	s_add_u32 s24, s6, s64
	s_addc_u32 s25, s7, 0
	s_add_u32 s26, s6, s65
	s_addc_u32 s27, s7, 0
	s_add_u32 s28, s6, s66
	s_addc_u32 s29, s7, 0
	s_add_u32 s30, s6, s67
	s_addc_u32 s31, s7, 0
	global_load_dwordx4 v[128:131], v240, s[24:25]
	global_load_dwordx4 v[132:135], v240, s[26:27]
	global_load_dwordx4 v[136:139], v240, s[28:29]
	global_load_dwordx4 v[140:143], v240, s[30:31]
	v_readfirstlane_b32 s23, v238
	v_readlane_b32 s56, v237, 0
	v_readlane_b32 s58, v237, 16
	v_readlane_b32 s60, v237, 32
	v_readlane_b32 s62, v237, 48
	s_and_b32 s23, s23, 7
	s_waitcnt vmcnt(16)
	s_cmp_ge_u32 s23, 4
	s_cbranch_scc1 .LV_s1_h
	s_cmp_ge_u32 s23, 2
	s_cbranch_scc1 .LV_s1_23
	s_cmp_eq_u32 s23, 0
	s_cbranch_scc1 .LV_s1_t0
	s_branch .LV_s1_t1

.LV_s1_t0:
	v_cvt_pk_f32_fp8_e32 v[224:225], v144
	v_cvt_pk_f32_fp8_sdwa v[226:227], v144 src0_sel:WORD_1
	v_cvt_pk_f32_fp8_e32 v[228:229], v145
	v_cvt_pk_f32_fp8_sdwa v[230:231], v145 src0_sel:WORD_1
	v_pk_fma_f32 v[0:1], v[224:225], s[56:57], v[0:1] op_sel_hi:[1,0,1]
	v_pk_fma_f32 v[2:3], v[226:227], s[56:57], v[2:3] op_sel_hi:[1,0,1]
	v_pk_fma_f32 v[4:5], v[228:229], s[56:57], v[4:5] op_sel_hi:[1,0,1]
	v_pk_fma_f32 v[6:7], v[230:231], s[56:57], v[6:7] op_sel_hi:[1,0,1]
	v_cvt_pk_f32_fp8_e32 v[224:225], v146
	v_cvt_pk_f32_fp8_sdwa v[226:227], v146 src0_sel:WORD_1
	v_cvt_pk_f32_fp8_e32 v[228:229], v147
	v_cvt_pk_f32_fp8_sdwa v[230:231], v147 src0_sel:WORD_1
	v_pk_fma_f32 v[8:9], v[224:225], s[56:57], v[8:9] op_sel_hi:[1,0,1]
	v_pk_fma_f32 v[10:11], v[226:227], s[56:57], v[10:11] op_sel_hi:[1,0,1]
	v_pk_fma_f32 v[12:13], v[228:229], s[56:57], v[12:13] op_sel_hi:[1,0,1]
	v_pk_fma_f32 v[14:15], v[230:231], s[56:57], v[14:15] op_sel_hi:[1,0,1]
	v_cvt_pk_f32_fp8_e32 v[224:225], v148
	v_cvt_pk_f32_fp8_sdwa v[226:227], v148 src0_sel:WORD_1
	v_cvt_pk_f32_fp8_e32 v[228:229], v149
	v_cvt_pk_f32_fp8_sdwa v[230:231], v149 src0_sel:WORD_1
	v_pk_fma_f32 v[0:1], v[224:225], s[58:59], v[0:1] op_sel_hi:[1,0,1]
	v_pk_fma_f32 v[2:3], v[226:227], s[58:59], v[2:3] op_sel_hi:[1,0,1]
	v_pk_fma_f32 v[4:5], v[228:229], s[58:59], v[4:5] op_sel_hi:[1,0,1]
	v_pk_fma_f32 v[6:7], v[230:231], s[58:59], v[6:7] op_sel_hi:[1,0,1]
	v_cvt_pk_f32_fp8_e32 v[224:225], v150
	v_cvt_pk_f32_fp8_sdwa v[226:227], v150 src0_sel:WORD_1
	v_cvt_pk_f32_fp8_e32 v[228:229], v151
	v_cvt_pk_f32_fp8_sdwa v[230:231], v151 src0_sel:WORD_1
	v_pk_fma_f32 v[8:9], v[224:225], s[58:59], v[8:9] op_sel_hi:[1,0,1]
	v_pk_fma_f32 v[10:11], v[226:227], s[58:59], v[10:11] op_sel_hi:[1,0,1]
	v_pk_fma_f32 v[12:13], v[228:229], s[58:59], v[12:13] op_sel_hi:[1,0,1]
	v_pk_fma_f32 v[14:15], v[230:231], s[58:59], v[14:15] op_sel_hi:[1,0,1]
	v_cvt_pk_f32_fp8_e32 v[224:225], v152
	v_cvt_pk_f32_fp8_sdwa v[226:227], v152 src0_sel:WORD_1
	v_cvt_pk_f32_fp8_e32 v[228:229], v153
	v_cvt_pk_f32_fp8_sdwa v[230:231], v153 src0_sel:WORD_1
	v_pk_fma_f32 v[0:1], v[224:225], s[60:61], v[0:1] op_sel_hi:[1,0,1]
	v_pk_fma_f32 v[2:3], v[226:227], s[60:61], v[2:3] op_sel_hi:[1,0,1]
	v_pk_fma_f32 v[4:5], v[228:229], s[60:61], v[4:5] op_sel_hi:[1,0,1]
	v_pk_fma_f32 v[6:7], v[230:231], s[60:61], v[6:7] op_sel_hi:[1,0,1]
	v_cvt_pk_f32_fp8_e32 v[224:225], v154
	v_cvt_pk_f32_fp8_sdwa v[226:227], v154 src0_sel:WORD_1
	v_cvt_pk_f32_fp8_e32 v[228:229], v155
	v_cvt_pk_f32_fp8_sdwa v[230:231], v155 src0_sel:WORD_1
	v_pk_fma_f32 v[8:9], v[224:225], s[60:61], v[8:9] op_sel_hi:[1,0,1]
	v_pk_fma_f32 v[10:11], v[226:227], s[60:61], v[10:11] op_sel_hi:[1,0,1]
	v_pk_fma_f32 v[12:13], v[228:229], s[60:61], v[12:13] op_sel_hi:[1,0,1]
	v_pk_fma_f32 v[14:15], v[230:231], s[60:61], v[14:15] op_sel_hi:[1,0,1]
	v_cvt_pk_f32_fp8_e32 v[224:225], v156
	v_cvt_pk_f32_fp8_sdwa v[226:227], v156 src0_sel:WORD_1
	v_cvt_pk_f32_fp8_e32 v[228:229], v157
	v_cvt_pk_f32_fp8_sdwa v[230:231], v157 src0_sel:WORD_1
	v_pk_fma_f32 v[0:1], v[224:225], s[62:63], v[0:1] op_sel_hi:[1,0,1]
	v_pk_fma_f32 v[2:3], v[226:227], s[62:63], v[2:3] op_sel_hi:[1,0,1]
	v_pk_fma_f32 v[4:5], v[228:229], s[62:63], v[4:5] op_sel_hi:[1,0,1]
	v_pk_fma_f32 v[6:7], v[230:231], s[62:63], v[6:7] op_sel_hi:[1,0,1]
	v_cvt_pk_f32_fp8_e32 v[224:225], v158
	v_cvt_pk_f32_fp8_sdwa v[226:227], v158 src0_sel:WORD_1
	v_cvt_pk_f32_fp8_e32 v[228:229], v159
	v_cvt_pk_f32_fp8_sdwa v[230:231], v159 src0_sel:WORD_1
	v_pk_fma_f32 v[8:9], v[224:225], s[62:63], v[8:9] op_sel_hi:[1,0,1]
	v_pk_fma_f32 v[10:11], v[226:227], s[62:63], v[10:11] op_sel_hi:[1,0,1]
	v_pk_fma_f32 v[12:13], v[228:229], s[62:63], v[12:13] op_sel_hi:[1,0,1]
	v_pk_fma_f32 v[14:15], v[230:231], s[62:63], v[14:15] op_sel_hi:[1,0,1]
	s_branch .LV_s1_tail
.LV_s1_t1:
	v_cvt_pk_f32_fp8_e32 v[224:225], v144
	v_cvt_pk_f32_fp8_sdwa v[226:227], v144 src0_sel:WORD_1
	v_cvt_pk_f32_fp8_e32 v[228:229], v145
	v_cvt_pk_f32_fp8_sdwa v[230:231], v145 src0_sel:WORD_1
	v_pk_fma_f32 v[16:17], v[224:225], s[56:57], v[16:17] op_sel_hi:[1,0,1]
	v_pk_fma_f32 v[18:19], v[226:227], s[56:57], v[18:19] op_sel_hi:[1,0,1]
	v_pk_fma_f32 v[20:21], v[228:229], s[56:57], v[20:21] op_sel_hi:[1,0,1]
	v_pk_fma_f32 v[22:23], v[230:231], s[56:57], v[22:23] op_sel_hi:[1,0,1]
	v_cvt_pk_f32_fp8_e32 v[224:225], v146
	v_cvt_pk_f32_fp8_sdwa v[226:227], v146 src0_sel:WORD_1
	v_cvt_pk_f32_fp8_e32 v[228:229], v147
	v_cvt_pk_f32_fp8_sdwa v[230:231], v147 src0_sel:WORD_1
	v_pk_fma_f32 v[24:25], v[224:225], s[56:57], v[24:25] op_sel_hi:[1,0,1]
	v_pk_fma_f32 v[26:27], v[226:227], s[56:57], v[26:27] op_sel_hi:[1,0,1]
	v_pk_fma_f32 v[28:29], v[228:229], s[56:57], v[28:29] op_sel_hi:[1,0,1]
	v_pk_fma_f32 v[30:31], v[230:231], s[56:57], v[30:31] op_sel_hi:[1,0,1]
	v_cvt_pk_f32_fp8_e32 v[224:225], v148
	v_cvt_pk_f32_fp8_sdwa v[226:227], v148 src0_sel:WORD_1
	v_cvt_pk_f32_fp8_e32 v[228:229], v149
	v_cvt_pk_f32_fp8_sdwa v[230:231], v149 src0_sel:WORD_1
	v_pk_fma_f32 v[16:17], v[224:225], s[58:59], v[16:17] op_sel_hi:[1,0,1]
	v_pk_fma_f32 v[18:19], v[226:227], s[58:59], v[18:19] op_sel_hi:[1,0,1]
	v_pk_fma_f32 v[20:21], v[228:229], s[58:59], v[20:21] op_sel_hi:[1,0,1]
	v_pk_fma_f32 v[22:23], v[230:231], s[58:59], v[22:23] op_sel_hi:[1,0,1]
	v_cvt_pk_f32_fp8_e32 v[224:225], v150
	v_cvt_pk_f32_fp8_sdwa v[226:227], v150 src0_sel:WORD_1
	v_cvt_pk_f32_fp8_e32 v[228:229], v151
	v_cvt_pk_f32_fp8_sdwa v[230:231], v151 src0_sel:WORD_1
	v_pk_fma_f32 v[24:25], v[224:225], s[58:59], v[24:25] op_sel_hi:[1,0,1]
	v_pk_fma_f32 v[26:27], v[226:227], s[58:59], v[26:27] op_sel_hi:[1,0,1]
	v_pk_fma_f32 v[28:29], v[228:229], s[58:59], v[28:29] op_sel_hi:[1,0,1]
	v_pk_fma_f32 v[30:31], v[230:231], s[58:59], v[30:31] op_sel_hi:[1,0,1]
	v_cvt_pk_f32_fp8_e32 v[224:225], v152
	v_cvt_pk_f32_fp8_sdwa v[226:227], v152 src0_sel:WORD_1
	v_cvt_pk_f32_fp8_e32 v[228:229], v153
	v_cvt_pk_f32_fp8_sdwa v[230:231], v153 src0_sel:WORD_1
	v_pk_fma_f32 v[16:17], v[224:225], s[60:61], v[16:17] op_sel_hi:[1,0,1]
	v_pk_fma_f32 v[18:19], v[226:227], s[60:61], v[18:19] op_sel_hi:[1,0,1]
	v_pk_fma_f32 v[20:21], v[228:229], s[60:61], v[20:21] op_sel_hi:[1,0,1]
	v_pk_fma_f32 v[22:23], v[230:231], s[60:61], v[22:23] op_sel_hi:[1,0,1]
	v_cvt_pk_f32_fp8_e32 v[224:225], v154
	v_cvt_pk_f32_fp8_sdwa v[226:227], v154 src0_sel:WORD_1
	v_cvt_pk_f32_fp8_e32 v[228:229], v155
	v_cvt_pk_f32_fp8_sdwa v[230:231], v155 src0_sel:WORD_1
	v_pk_fma_f32 v[24:25], v[224:225], s[60:61], v[24:25] op_sel_hi:[1,0,1]
	v_pk_fma_f32 v[26:27], v[226:227], s[60:61], v[26:27] op_sel_hi:[1,0,1]
	v_pk_fma_f32 v[28:29], v[228:229], s[60:61], v[28:29] op_sel_hi:[1,0,1]
	v_pk_fma_f32 v[30:31], v[230:231], s[60:61], v[30:31] op_sel_hi:[1,0,1]
	v_cvt_pk_f32_fp8_e32 v[224:225], v156
	v_cvt_pk_f32_fp8_sdwa v[226:227], v156 src0_sel:WORD_1
	v_cvt_pk_f32_fp8_e32 v[228:229], v157
	v_cvt_pk_f32_fp8_sdwa v[230:231], v157 src0_sel:WORD_1
	v_pk_fma_f32 v[16:17], v[224:225], s[62:63], v[16:17] op_sel_hi:[1,0,1]
	v_pk_fma_f32 v[18:19], v[226:227], s[62:63], v[18:19] op_sel_hi:[1,0,1]
	v_pk_fma_f32 v[20:21], v[228:229], s[62:63], v[20:21] op_sel_hi:[1,0,1]
	v_pk_fma_f32 v[22:23], v[230:231], s[62:63], v[22:23] op_sel_hi:[1,0,1]
	v_cvt_pk_f32_fp8_e32 v[224:225], v158
	v_cvt_pk_f32_fp8_sdwa v[226:227], v158 src0_sel:WORD_1
	v_cvt_pk_f32_fp8_e32 v[228:229], v159
	v_cvt_pk_f32_fp8_sdwa v[230:231], v159 src0_sel:WORD_1
	v_pk_fma_f32 v[24:25], v[224:225], s[62:63], v[24:25] op_sel_hi:[1,0,1]
	v_pk_fma_f32 v[26:27], v[226:227], s[62:63], v[26:27] op_sel_hi:[1,0,1]
	v_pk_fma_f32 v[28:29], v[228:229], s[62:63], v[28:29] op_sel_hi:[1,0,1]
	v_pk_fma_f32 v[30:31], v[230:231], s[62:63], v[30:31] op_sel_hi:[1,0,1]
	s_branch .LV_s1_tail
.LV_s1_t2:
	v_cvt_pk_f32_fp8_e32 v[224:225], v144
	v_cvt_pk_f32_fp8_sdwa v[226:227], v144 src0_sel:WORD_1
	v_cvt_pk_f32_fp8_e32 v[228:229], v145
	v_cvt_pk_f32_fp8_sdwa v[230:231], v145 src0_sel:WORD_1
	v_pk_fma_f32 v[32:33], v[224:225], s[56:57], v[32:33] op_sel_hi:[1,0,1]
	v_pk_fma_f32 v[34:35], v[226:227], s[56:57], v[34:35] op_sel_hi:[1,0,1]
	v_pk_fma_f32 v[36:37], v[228:229], s[56:57], v[36:37] op_sel_hi:[1,0,1]
	v_pk_fma_f32 v[38:39], v[230:231], s[56:57], v[38:39] op_sel_hi:[1,0,1]
	v_cvt_pk_f32_fp8_e32 v[224:225], v146
	v_cvt_pk_f32_fp8_sdwa v[226:227], v146 src0_sel:WORD_1
	v_cvt_pk_f32_fp8_e32 v[228:229], v147
	v_cvt_pk_f32_fp8_sdwa v[230:231], v147 src0_sel:WORD_1
	v_pk_fma_f32 v[40:41], v[224:225], s[56:57], v[40:41] op_sel_hi:[1,0,1]
	v_pk_fma_f32 v[42:43], v[226:227], s[56:57], v[42:43] op_sel_hi:[1,0,1]
	v_pk_fma_f32 v[44:45], v[228:229], s[56:57], v[44:45] op_sel_hi:[1,0,1]
	v_pk_fma_f32 v[46:47], v[230:231], s[56:57], v[46:47] op_sel_hi:[1,0,1]
	v_cvt_pk_f32_fp8_e32 v[224:225], v148
	v_cvt_pk_f32_fp8_sdwa v[226:227], v148 src0_sel:WORD_1
	v_cvt_pk_f32_fp8_e32 v[228:229], v149
	v_cvt_pk_f32_fp8_sdwa v[230:231], v149 src0_sel:WORD_1
	v_pk_fma_f32 v[32:33], v[224:225], s[58:59], v[32:33] op_sel_hi:[1,0,1]
	v_pk_fma_f32 v[34:35], v[226:227], s[58:59], v[34:35] op_sel_hi:[1,0,1]
	v_pk_fma_f32 v[36:37], v[228:229], s[58:59], v[36:37] op_sel_hi:[1,0,1]
	v_pk_fma_f32 v[38:39], v[230:231], s[58:59], v[38:39] op_sel_hi:[1,0,1]
	v_cvt_pk_f32_fp8_e32 v[224:225], v150
	v_cvt_pk_f32_fp8_sdwa v[226:227], v150 src0_sel:WORD_1
	v_cvt_pk_f32_fp8_e32 v[228:229], v151
	v_cvt_pk_f32_fp8_sdwa v[230:231], v151 src0_sel:WORD_1
	v_pk_fma_f32 v[40:41], v[224:225], s[58:59], v[40:41] op_sel_hi:[1,0,1]
	v_pk_fma_f32 v[42:43], v[226:227], s[58:59], v[42:43] op_sel_hi:[1,0,1]
	v_pk_fma_f32 v[44:45], v[228:229], s[58:59], v[44:45] op_sel_hi:[1,0,1]
	v_pk_fma_f32 v[46:47], v[230:231], s[58:59], v[46:47] op_sel_hi:[1,0,1]
	v_cvt_pk_f32_fp8_e32 v[224:225], v152
	v_cvt_pk_f32_fp8_sdwa v[226:227], v152 src0_sel:WORD_1
	v_cvt_pk_f32_fp8_e32 v[228:229], v153
	v_cvt_pk_f32_fp8_sdwa v[230:231], v153 src0_sel:WORD_1
	v_pk_fma_f32 v[32:33], v[224:225], s[60:61], v[32:33] op_sel_hi:[1,0,1]
	v_pk_fma_f32 v[34:35], v[226:227], s[60:61], v[34:35] op_sel_hi:[1,0,1]
	v_pk_fma_f32 v[36:37], v[228:229], s[60:61], v[36:37] op_sel_hi:[1,0,1]
	v_pk_fma_f32 v[38:39], v[230:231], s[60:61], v[38:39] op_sel_hi:[1,0,1]
	v_cvt_pk_f32_fp8_e32 v[224:225], v154
	v_cvt_pk_f32_fp8_sdwa v[226:227], v154 src0_sel:WORD_1
	v_cvt_pk_f32_fp8_e32 v[228:229], v155
	v_cvt_pk_f32_fp8_sdwa v[230:231], v155 src0_sel:WORD_1
	v_pk_fma_f32 v[40:41], v[224:225], s[60:61], v[40:41] op_sel_hi:[1,0,1]
	v_pk_fma_f32 v[42:43], v[226:227], s[60:61], v[42:43] op_sel_hi:[1,0,1]
	v_pk_fma_f32 v[44:45], v[228:229], s[60:61], v[44:45] op_sel_hi:[1,0,1]
	v_pk_fma_f32 v[46:47], v[230:231], s[60:61], v[46:47] op_sel_hi:[1,0,1]
	v_cvt_pk_f32_fp8_e32 v[224:225], v156
	v_cvt_pk_f32_fp8_sdwa v[226:227], v156 src0_sel:WORD_1
	v_cvt_pk_f32_fp8_e32 v[228:229], v157
	v_cvt_pk_f32_fp8_sdwa v[230:231], v157 src0_sel:WORD_1
	v_pk_fma_f32 v[32:33], v[224:225], s[62:63], v[32:33] op_sel_hi:[1,0,1]
	v_pk_fma_f32 v[34:35], v[226:227], s[62:63], v[34:35] op_sel_hi:[1,0,1]
	v_pk_fma_f32 v[36:37], v[228:229], s[62:63], v[36:37] op_sel_hi:[1,0,1]
	v_pk_fma_f32 v[38:39], v[230:231], s[62:63], v[38:39] op_sel_hi:[1,0,1]
	v_cvt_pk_f32_fp8_e32 v[224:225], v158
	v_cvt_pk_f32_fp8_sdwa v[226:227], v158 src0_sel:WORD_1
	v_cvt_pk_f32_fp8_e32 v[228:229], v159
	v_cvt_pk_f32_fp8_sdwa v[230:231], v159 src0_sel:WORD_1
	v_pk_fma_f32 v[40:41], v[224:225], s[62:63], v[40:41] op_sel_hi:[1,0,1]
	v_pk_fma_f32 v[42:43], v[226:227], s[62:63], v[42:43] op_sel_hi:[1,0,1]
	v_pk_fma_f32 v[44:45], v[228:229], s[62:63], v[44:45] op_sel_hi:[1,0,1]
	v_pk_fma_f32 v[46:47], v[230:231], s[62:63], v[46:47] op_sel_hi:[1,0,1]
	s_branch .LV_s1_tail
.LV_s1_t3:
	v_cvt_pk_f32_fp8_e32 v[224:225], v144
	v_cvt_pk_f32_fp8_sdwa v[226:227], v144 src0_sel:WORD_1
	v_cvt_pk_f32_fp8_e32 v[228:229], v145
	v_cvt_pk_f32_fp8_sdwa v[230:231], v145 src0_sel:WORD_1
	v_pk_fma_f32 v[48:49], v[224:225], s[56:57], v[48:49] op_sel_hi:[1,0,1]
	v_pk_fma_f32 v[50:51], v[226:227], s[56:57], v[50:51] op_sel_hi:[1,0,1]
	v_pk_fma_f32 v[52:53], v[228:229], s[56:57], v[52:53] op_sel_hi:[1,0,1]
	v_pk_fma_f32 v[54:55], v[230:231], s[56:57], v[54:55] op_sel_hi:[1,0,1]
	v_cvt_pk_f32_fp8_e32 v[224:225], v146
	v_cvt_pk_f32_fp8_sdwa v[226:227], v146 src0_sel:WORD_1
	v_cvt_pk_f32_fp8_e32 v[228:229], v147
	v_cvt_pk_f32_fp8_sdwa v[230:231], v147 src0_sel:WORD_1
	v_pk_fma_f32 v[56:57], v[224:225], s[56:57], v[56:57] op_sel_hi:[1,0,1]
	v_pk_fma_f32 v[58:59], v[226:227], s[56:57], v[58:59] op_sel_hi:[1,0,1]
	v_pk_fma_f32 v[60:61], v[228:229], s[56:57], v[60:61] op_sel_hi:[1,0,1]
	v_pk_fma_f32 v[62:63], v[230:231], s[56:57], v[62:63] op_sel_hi:[1,0,1]
	v_cvt_pk_f32_fp8_e32 v[224:225], v148
	v_cvt_pk_f32_fp8_sdwa v[226:227], v148 src0_sel:WORD_1
	v_cvt_pk_f32_fp8_e32 v[228:229], v149
	v_cvt_pk_f32_fp8_sdwa v[230:231], v149 src0_sel:WORD_1
	v_pk_fma_f32 v[48:49], v[224:225], s[58:59], v[48:49] op_sel_hi:[1,0,1]
	v_pk_fma_f32 v[50:51], v[226:227], s[58:59], v[50:51] op_sel_hi:[1,0,1]
	v_pk_fma_f32 v[52:53], v[228:229], s[58:59], v[52:53] op_sel_hi:[1,0,1]
	v_pk_fma_f32 v[54:55], v[230:231], s[58:59], v[54:55] op_sel_hi:[1,0,1]
	v_cvt_pk_f32_fp8_e32 v[224:225], v150
	v_cvt_pk_f32_fp8_sdwa v[226:227], v150 src0_sel:WORD_1
	v_cvt_pk_f32_fp8_e32 v[228:229], v151
	v_cvt_pk_f32_fp8_sdwa v[230:231], v151 src0_sel:WORD_1
	v_pk_fma_f32 v[56:57], v[224:225], s[58:59], v[56:57] op_sel_hi:[1,0,1]
	v_pk_fma_f32 v[58:59], v[226:227], s[58:59], v[58:59] op_sel_hi:[1,0,1]
	v_pk_fma_f32 v[60:61], v[228:229], s[58:59], v[60:61] op_sel_hi:[1,0,1]
	v_pk_fma_f32 v[62:63], v[230:231], s[58:59], v[62:63] op_sel_hi:[1,0,1]
	v_cvt_pk_f32_fp8_e32 v[224:225], v152
	v_cvt_pk_f32_fp8_sdwa v[226:227], v152 src0_sel:WORD_1
	v_cvt_pk_f32_fp8_e32 v[228:229], v153
	v_cvt_pk_f32_fp8_sdwa v[230:231], v153 src0_sel:WORD_1
	v_pk_fma_f32 v[48:49], v[224:225], s[60:61], v[48:49] op_sel_hi:[1,0,1]
	v_pk_fma_f32 v[50:51], v[226:227], s[60:61], v[50:51] op_sel_hi:[1,0,1]
	v_pk_fma_f32 v[52:53], v[228:229], s[60:61], v[52:53] op_sel_hi:[1,0,1]
	v_pk_fma_f32 v[54:55], v[230:231], s[60:61], v[54:55] op_sel_hi:[1,0,1]
	v_cvt_pk_f32_fp8_e32 v[224:225], v154
	v_cvt_pk_f32_fp8_sdwa v[226:227], v154 src0_sel:WORD_1
	v_cvt_pk_f32_fp8_e32 v[228:229], v155
	v_cvt_pk_f32_fp8_sdwa v[230:231], v155 src0_sel:WORD_1
	v_pk_fma_f32 v[56:57], v[224:225], s[60:61], v[56:57] op_sel_hi:[1,0,1]
	v_pk_fma_f32 v[58:59], v[226:227], s[60:61], v[58:59] op_sel_hi:[1,0,1]
	v_pk_fma_f32 v[60:61], v[228:229], s[60:61], v[60:61] op_sel_hi:[1,0,1]
	v_pk_fma_f32 v[62:63], v[230:231], s[60:61], v[62:63] op_sel_hi:[1,0,1]
	v_cvt_pk_f32_fp8_e32 v[224:225], v156
	v_cvt_pk_f32_fp8_sdwa v[226:227], v156 src0_sel:WORD_1
	v_cvt_pk_f32_fp8_e32 v[228:229], v157
	v_cvt_pk_f32_fp8_sdwa v[230:231], v157 src0_sel:WORD_1
	v_pk_fma_f32 v[48:49], v[224:225], s[62:63], v[48:49] op_sel_hi:[1,0,1]
	v_pk_fma_f32 v[50:51], v[226:227], s[62:63], v[50:51] op_sel_hi:[1,0,1]
	v_pk_fma_f32 v[52:53], v[228:229], s[62:63], v[52:53] op_sel_hi:[1,0,1]
	v_pk_fma_f32 v[54:55], v[230:231], s[62:63], v[54:55] op_sel_hi:[1,0,1]
	v_cvt_pk_f32_fp8_e32 v[224:225], v158
	v_cvt_pk_f32_fp8_sdwa v[226:227], v158 src0_sel:WORD_1
	v_cvt_pk_f32_fp8_e32 v[228:229], v159
	v_cvt_pk_f32_fp8_sdwa v[230:231], v159 src0_sel:WORD_1
	v_pk_fma_f32 v[56:57], v[224:225], s[62:63], v[56:57] op_sel_hi:[1,0,1]
	v_pk_fma_f32 v[58:59], v[226:227], s[62:63], v[58:59] op_sel_hi:[1,0,1]
	v_pk_fma_f32 v[60:61], v[228:229], s[62:63], v[60:61] op_sel_hi:[1,0,1]
	v_pk_fma_f32 v[62:63], v[230:231], s[62:63], v[62:63] op_sel_hi:[1,0,1]
	s_branch .LV_s1_tail
.LV_s1_t4:
	v_cvt_pk_f32_fp8_e32 v[224:225], v144
	v_cvt_pk_f32_fp8_sdwa v[226:227], v144 src0_sel:WORD_1
	v_cvt_pk_f32_fp8_e32 v[228:229], v145
	v_cvt_pk_f32_fp8_sdwa v[230:231], v145 src0_sel:WORD_1
	v_pk_fma_f32 v[64:65], v[224:225], s[56:57], v[64:65] op_sel_hi:[1,0,1]
	v_pk_fma_f32 v[66:67], v[226:227], s[56:57], v[66:67] op_sel_hi:[1,0,1]
	v_pk_fma_f32 v[68:69], v[228:229], s[56:57], v[68:69] op_sel_hi:[1,0,1]
	v_pk_fma_f32 v[70:71], v[230:231], s[56:57], v[70:71] op_sel_hi:[1,0,1]
	v_cvt_pk_f32_fp8_e32 v[224:225], v146
	v_cvt_pk_f32_fp8_sdwa v[226:227], v146 src0_sel:WORD_1
	v_cvt_pk_f32_fp8_e32 v[228:229], v147
	v_cvt_pk_f32_fp8_sdwa v[230:231], v147 src0_sel:WORD_1
	v_pk_fma_f32 v[72:73], v[224:225], s[56:57], v[72:73] op_sel_hi:[1,0,1]
	v_pk_fma_f32 v[74:75], v[226:227], s[56:57], v[74:75] op_sel_hi:[1,0,1]
	v_pk_fma_f32 v[76:77], v[228:229], s[56:57], v[76:77] op_sel_hi:[1,0,1]
	v_pk_fma_f32 v[78:79], v[230:231], s[56:57], v[78:79] op_sel_hi:[1,0,1]
	v_cvt_pk_f32_fp8_e32 v[224:225], v148
	v_cvt_pk_f32_fp8_sdwa v[226:227], v148 src0_sel:WORD_1
	v_cvt_pk_f32_fp8_e32 v[228:229], v149
	v_cvt_pk_f32_fp8_sdwa v[230:231], v149 src0_sel:WORD_1
	v_pk_fma_f32 v[64:65], v[224:225], s[58:59], v[64:65] op_sel_hi:[1,0,1]
	v_pk_fma_f32 v[66:67], v[226:227], s[58:59], v[66:67] op_sel_hi:[1,0,1]
	v_pk_fma_f32 v[68:69], v[228:229], s[58:59], v[68:69] op_sel_hi:[1,0,1]
	v_pk_fma_f32 v[70:71], v[230:231], s[58:59], v[70:71] op_sel_hi:[1,0,1]
	v_cvt_pk_f32_fp8_e32 v[224:225], v150
	v_cvt_pk_f32_fp8_sdwa v[226:227], v150 src0_sel:WORD_1
	v_cvt_pk_f32_fp8_e32 v[228:229], v151
	v_cvt_pk_f32_fp8_sdwa v[230:231], v151 src0_sel:WORD_1
	v_pk_fma_f32 v[72:73], v[224:225], s[58:59], v[72:73] op_sel_hi:[1,0,1]
	v_pk_fma_f32 v[74:75], v[226:227], s[58:59], v[74:75] op_sel_hi:[1,0,1]
	v_pk_fma_f32 v[76:77], v[228:229], s[58:59], v[76:77] op_sel_hi:[1,0,1]
	v_pk_fma_f32 v[78:79], v[230:231], s[58:59], v[78:79] op_sel_hi:[1,0,1]
	v_cvt_pk_f32_fp8_e32 v[224:225], v152
	v_cvt_pk_f32_fp8_sdwa v[226:227], v152 src0_sel:WORD_1
	v_cvt_pk_f32_fp8_e32 v[228:229], v153
	v_cvt_pk_f32_fp8_sdwa v[230:231], v153 src0_sel:WORD_1
	v_pk_fma_f32 v[64:65], v[224:225], s[60:61], v[64:65] op_sel_hi:[1,0,1]
	v_pk_fma_f32 v[66:67], v[226:227], s[60:61], v[66:67] op_sel_hi:[1,0,1]
	v_pk_fma_f32 v[68:69], v[228:229], s[60:61], v[68:69] op_sel_hi:[1,0,1]
	v_pk_fma_f32 v[70:71], v[230:231], s[60:61], v[70:71] op_sel_hi:[1,0,1]
	v_cvt_pk_f32_fp8_e32 v[224:225], v154
	v_cvt_pk_f32_fp8_sdwa v[226:227], v154 src0_sel:WORD_1
	v_cvt_pk_f32_fp8_e32 v[228:229], v155
	v_cvt_pk_f32_fp8_sdwa v[230:231], v155 src0_sel:WORD_1
	v_pk_fma_f32 v[72:73], v[224:225], s[60:61], v[72:73] op_sel_hi:[1,0,1]
	v_pk_fma_f32 v[74:75], v[226:227], s[60:61], v[74:75] op_sel_hi:[1,0,1]
	v_pk_fma_f32 v[76:77], v[228:229], s[60:61], v[76:77] op_sel_hi:[1,0,1]
	v_pk_fma_f32 v[78:79], v[230:231], s[60:61], v[78:79] op_sel_hi:[1,0,1]
	v_cvt_pk_f32_fp8_e32 v[224:225], v156
	v_cvt_pk_f32_fp8_sdwa v[226:227], v156 src0_sel:WORD_1
	v_cvt_pk_f32_fp8_e32 v[228:229], v157
	v_cvt_pk_f32_fp8_sdwa v[230:231], v157 src0_sel:WORD_1
	v_pk_fma_f32 v[64:65], v[224:225], s[62:63], v[64:65] op_sel_hi:[1,0,1]
	v_pk_fma_f32 v[66:67], v[226:227], s[62:63], v[66:67] op_sel_hi:[1,0,1]
	v_pk_fma_f32 v[68:69], v[228:229], s[62:63], v[68:69] op_sel_hi:[1,0,1]
	v_pk_fma_f32 v[70:71], v[230:231], s[62:63], v[70:71] op_sel_hi:[1,0,1]
	v_cvt_pk_f32_fp8_e32 v[224:225], v158
	v_cvt_pk_f32_fp8_sdwa v[226:227], v158 src0_sel:WORD_1
	v_cvt_pk_f32_fp8_e32 v[228:229], v159
	v_cvt_pk_f32_fp8_sdwa v[230:231], v159 src0_sel:WORD_1
	v_pk_fma_f32 v[72:73], v[224:225], s[62:63], v[72:73] op_sel_hi:[1,0,1]
	v_pk_fma_f32 v[74:75], v[226:227], s[62:63], v[74:75] op_sel_hi:[1,0,1]
	v_pk_fma_f32 v[76:77], v[228:229], s[62:63], v[76:77] op_sel_hi:[1,0,1]
	v_pk_fma_f32 v[78:79], v[230:231], s[62:63], v[78:79] op_sel_hi:[1,0,1]
	s_branch .LV_s1_tail
.LV_s1_t5:
	v_cvt_pk_f32_fp8_e32 v[224:225], v144
	v_cvt_pk_f32_fp8_sdwa v[226:227], v144 src0_sel:WORD_1
	v_cvt_pk_f32_fp8_e32 v[228:229], v145
	v_cvt_pk_f32_fp8_sdwa v[230:231], v145 src0_sel:WORD_1
	v_pk_fma_f32 v[80:81], v[224:225], s[56:57], v[80:81] op_sel_hi:[1,0,1]
	v_pk_fma_f32 v[82:83], v[226:227], s[56:57], v[82:83] op_sel_hi:[1,0,1]
	v_pk_fma_f32 v[84:85], v[228:229], s[56:57], v[84:85] op_sel_hi:[1,0,1]
	v_pk_fma_f32 v[86:87], v[230:231], s[56:57], v[86:87] op_sel_hi:[1,0,1]
	v_cvt_pk_f32_fp8_e32 v[224:225], v146
	v_cvt_pk_f32_fp8_sdwa v[226:227], v146 src0_sel:WORD_1
	v_cvt_pk_f32_fp8_e32 v[228:229], v147
	v_cvt_pk_f32_fp8_sdwa v[230:231], v147 src0_sel:WORD_1
	v_pk_fma_f32 v[88:89], v[224:225], s[56:57], v[88:89] op_sel_hi:[1,0,1]
	v_pk_fma_f32 v[90:91], v[226:227], s[56:57], v[90:91] op_sel_hi:[1,0,1]
	v_pk_fma_f32 v[92:93], v[228:229], s[56:57], v[92:93] op_sel_hi:[1,0,1]
	v_pk_fma_f32 v[94:95], v[230:231], s[56:57], v[94:95] op_sel_hi:[1,0,1]
	v_cvt_pk_f32_fp8_e32 v[224:225], v148
	v_cvt_pk_f32_fp8_sdwa v[226:227], v148 src0_sel:WORD_1
	v_cvt_pk_f32_fp8_e32 v[228:229], v149
	v_cvt_pk_f32_fp8_sdwa v[230:231], v149 src0_sel:WORD_1
	v_pk_fma_f32 v[80:81], v[224:225], s[58:59], v[80:81] op_sel_hi:[1,0,1]
	v_pk_fma_f32 v[82:83], v[226:227], s[58:59], v[82:83] op_sel_hi:[1,0,1]
	v_pk_fma_f32 v[84:85], v[228:229], s[58:59], v[84:85] op_sel_hi:[1,0,1]
	v_pk_fma_f32 v[86:87], v[230:231], s[58:59], v[86:87] op_sel_hi:[1,0,1]
	v_cvt_pk_f32_fp8_e32 v[224:225], v150
	v_cvt_pk_f32_fp8_sdwa v[226:227], v150 src0_sel:WORD_1
	v_cvt_pk_f32_fp8_e32 v[228:229], v151
	v_cvt_pk_f32_fp8_sdwa v[230:231], v151 src0_sel:WORD_1
	v_pk_fma_f32 v[88:89], v[224:225], s[58:59], v[88:89] op_sel_hi:[1,0,1]
	v_pk_fma_f32 v[90:91], v[226:227], s[58:59], v[90:91] op_sel_hi:[1,0,1]
	v_pk_fma_f32 v[92:93], v[228:229], s[58:59], v[92:93] op_sel_hi:[1,0,1]
	v_pk_fma_f32 v[94:95], v[230:231], s[58:59], v[94:95] op_sel_hi:[1,0,1]
	v_cvt_pk_f32_fp8_e32 v[224:225], v152
	v_cvt_pk_f32_fp8_sdwa v[226:227], v152 src0_sel:WORD_1
	v_cvt_pk_f32_fp8_e32 v[228:229], v153
	v_cvt_pk_f32_fp8_sdwa v[230:231], v153 src0_sel:WORD_1
	v_pk_fma_f32 v[80:81], v[224:225], s[60:61], v[80:81] op_sel_hi:[1,0,1]
	v_pk_fma_f32 v[82:83], v[226:227], s[60:61], v[82:83] op_sel_hi:[1,0,1]
	v_pk_fma_f32 v[84:85], v[228:229], s[60:61], v[84:85] op_sel_hi:[1,0,1]
	v_pk_fma_f32 v[86:87], v[230:231], s[60:61], v[86:87] op_sel_hi:[1,0,1]
	v_cvt_pk_f32_fp8_e32 v[224:225], v154
	v_cvt_pk_f32_fp8_sdwa v[226:227], v154 src0_sel:WORD_1
	v_cvt_pk_f32_fp8_e32 v[228:229], v155
	v_cvt_pk_f32_fp8_sdwa v[230:231], v155 src0_sel:WORD_1
	v_pk_fma_f32 v[88:89], v[224:225], s[60:61], v[88:89] op_sel_hi:[1,0,1]
	v_pk_fma_f32 v[90:91], v[226:227], s[60:61], v[90:91] op_sel_hi:[1,0,1]
	v_pk_fma_f32 v[92:93], v[228:229], s[60:61], v[92:93] op_sel_hi:[1,0,1]
	v_pk_fma_f32 v[94:95], v[230:231], s[60:61], v[94:95] op_sel_hi:[1,0,1]
	v_cvt_pk_f32_fp8_e32 v[224:225], v156
	v_cvt_pk_f32_fp8_sdwa v[226:227], v156 src0_sel:WORD_1
	v_cvt_pk_f32_fp8_e32 v[228:229], v157
	v_cvt_pk_f32_fp8_sdwa v[230:231], v157 src0_sel:WORD_1
	v_pk_fma_f32 v[80:81], v[224:225], s[62:63], v[80:81] op_sel_hi:[1,0,1]
	v_pk_fma_f32 v[82:83], v[226:227], s[62:63], v[82:83] op_sel_hi:[1,0,1]
	v_pk_fma_f32 v[84:85], v[228:229], s[62:63], v[84:85] op_sel_hi:[1,0,1]
	v_pk_fma_f32 v[86:87], v[230:231], s[62:63], v[86:87] op_sel_hi:[1,0,1]
	v_cvt_pk_f32_fp8_e32 v[224:225], v158
	v_cvt_pk_f32_fp8_sdwa v[226:227], v158 src0_sel:WORD_1
	v_cvt_pk_f32_fp8_e32 v[228:229], v159
	v_cvt_pk_f32_fp8_sdwa v[230:231], v159 src0_sel:WORD_1
	v_pk_fma_f32 v[88:89], v[224:225], s[62:63], v[88:89] op_sel_hi:[1,0,1]
	v_pk_fma_f32 v[90:91], v[226:227], s[62:63], v[90:91] op_sel_hi:[1,0,1]
	v_pk_fma_f32 v[92:93], v[228:229], s[62:63], v[92:93] op_sel_hi:[1,0,1]
	v_pk_fma_f32 v[94:95], v[230:231], s[62:63], v[94:95] op_sel_hi:[1,0,1]
	s_branch .LV_s1_tail
.LV_s1_t6:
	v_cvt_pk_f32_fp8_e32 v[224:225], v144
	v_cvt_pk_f32_fp8_sdwa v[226:227], v144 src0_sel:WORD_1
	v_cvt_pk_f32_fp8_e32 v[228:229], v145
	v_cvt_pk_f32_fp8_sdwa v[230:231], v145 src0_sel:WORD_1
	v_pk_fma_f32 v[96:97], v[224:225], s[56:57], v[96:97] op_sel_hi:[1,0,1]
	v_pk_fma_f32 v[98:99], v[226:227], s[56:57], v[98:99] op_sel_hi:[1,0,1]
	v_pk_fma_f32 v[100:101], v[228:229], s[56:57], v[100:101] op_sel_hi:[1,0,1]
	v_pk_fma_f32 v[102:103], v[230:231], s[56:57], v[102:103] op_sel_hi:[1,0,1]
	v_cvt_pk_f32_fp8_e32 v[224:225], v146
	v_cvt_pk_f32_fp8_sdwa v[226:227], v146 src0_sel:WORD_1
	v_cvt_pk_f32_fp8_e32 v[228:229], v147
	v_cvt_pk_f32_fp8_sdwa v[230:231], v147 src0_sel:WORD_1
	v_pk_fma_f32 v[104:105], v[224:225], s[56:57], v[104:105] op_sel_hi:[1,0,1]
	v_pk_fma_f32 v[106:107], v[226:227], s[56:57], v[106:107] op_sel_hi:[1,0,1]
	v_pk_fma_f32 v[108:109], v[228:229], s[56:57], v[108:109] op_sel_hi:[1,0,1]
	v_pk_fma_f32 v[110:111], v[230:231], s[56:57], v[110:111] op_sel_hi:[1,0,1]
	v_cvt_pk_f32_fp8_e32 v[224:225], v148
	v_cvt_pk_f32_fp8_sdwa v[226:227], v148 src0_sel:WORD_1
	v_cvt_pk_f32_fp8_e32 v[228:229], v149
	v_cvt_pk_f32_fp8_sdwa v[230:231], v149 src0_sel:WORD_1
	v_pk_fma_f32 v[96:97], v[224:225], s[58:59], v[96:97] op_sel_hi:[1,0,1]
	v_pk_fma_f32 v[98:99], v[226:227], s[58:59], v[98:99] op_sel_hi:[1,0,1]
	v_pk_fma_f32 v[100:101], v[228:229], s[58:59], v[100:101] op_sel_hi:[1,0,1]
	v_pk_fma_f32 v[102:103], v[230:231], s[58:59], v[102:103] op_sel_hi:[1,0,1]
	v_cvt_pk_f32_fp8_e32 v[224:225], v150
	v_cvt_pk_f32_fp8_sdwa v[226:227], v150 src0_sel:WORD_1
	v_cvt_pk_f32_fp8_e32 v[228:229], v151
	v_cvt_pk_f32_fp8_sdwa v[230:231], v151 src0_sel:WORD_1
	v_pk_fma_f32 v[104:105], v[224:225], s[58:59], v[104:105] op_sel_hi:[1,0,1]
	v_pk_fma_f32 v[106:107], v[226:227], s[58:59], v[106:107] op_sel_hi:[1,0,1]
	v_pk_fma_f32 v[108:109], v[228:229], s[58:59], v[108:109] op_sel_hi:[1,0,1]
	v_pk_fma_f32 v[110:111], v[230:231], s[58:59], v[110:111] op_sel_hi:[1,0,1]
	v_cvt_pk_f32_fp8_e32 v[224:225], v152
	v_cvt_pk_f32_fp8_sdwa v[226:227], v152 src0_sel:WORD_1
	v_cvt_pk_f32_fp8_e32 v[228:229], v153
	v_cvt_pk_f32_fp8_sdwa v[230:231], v153 src0_sel:WORD_1
	v_pk_fma_f32 v[96:97], v[224:225], s[60:61], v[96:97] op_sel_hi:[1,0,1]
	v_pk_fma_f32 v[98:99], v[226:227], s[60:61], v[98:99] op_sel_hi:[1,0,1]
	v_pk_fma_f32 v[100:101], v[228:229], s[60:61], v[100:101] op_sel_hi:[1,0,1]
	v_pk_fma_f32 v[102:103], v[230:231], s[60:61], v[102:103] op_sel_hi:[1,0,1]
	v_cvt_pk_f32_fp8_e32 v[224:225], v154
	v_cvt_pk_f32_fp8_sdwa v[226:227], v154 src0_sel:WORD_1
	v_cvt_pk_f32_fp8_e32 v[228:229], v155
	v_cvt_pk_f32_fp8_sdwa v[230:231], v155 src0_sel:WORD_1
	v_pk_fma_f32 v[104:105], v[224:225], s[60:61], v[104:105] op_sel_hi:[1,0,1]
	v_pk_fma_f32 v[106:107], v[226:227], s[60:61], v[106:107] op_sel_hi:[1,0,1]
	v_pk_fma_f32 v[108:109], v[228:229], s[60:61], v[108:109] op_sel_hi:[1,0,1]
	v_pk_fma_f32 v[110:111], v[230:231], s[60:61], v[110:111] op_sel_hi:[1,0,1]
	v_cvt_pk_f32_fp8_e32 v[224:225], v156
	v_cvt_pk_f32_fp8_sdwa v[226:227], v156 src0_sel:WORD_1
	v_cvt_pk_f32_fp8_e32 v[228:229], v157
	v_cvt_pk_f32_fp8_sdwa v[230:231], v157 src0_sel:WORD_1
	v_pk_fma_f32 v[96:97], v[224:225], s[62:63], v[96:97] op_sel_hi:[1,0,1]
	v_pk_fma_f32 v[98:99], v[226:227], s[62:63], v[98:99] op_sel_hi:[1,0,1]
	v_pk_fma_f32 v[100:101], v[228:229], s[62:63], v[100:101] op_sel_hi:[1,0,1]
	v_pk_fma_f32 v[102:103], v[230:231], s[62:63], v[102:103] op_sel_hi:[1,0,1]
	v_cvt_pk_f32_fp8_e32 v[224:225], v158
	v_cvt_pk_f32_fp8_sdwa v[226:227], v158 src0_sel:WORD_1
	v_cvt_pk_f32_fp8_e32 v[228:229], v159
	v_cvt_pk_f32_fp8_sdwa v[230:231], v159 src0_sel:WORD_1
	v_pk_fma_f32 v[104:105], v[224:225], s[62:63], v[104:105] op_sel_hi:[1,0,1]
	v_pk_fma_f32 v[106:107], v[226:227], s[62:63], v[106:107] op_sel_hi:[1,0,1]
	v_pk_fma_f32 v[108:109], v[228:229], s[62:63], v[108:109] op_sel_hi:[1,0,1]
	v_pk_fma_f32 v[110:111], v[230:231], s[62:63], v[110:111] op_sel_hi:[1,0,1]
	s_branch .LV_s1_tail
.LV_s1_t7:
	v_cvt_pk_f32_fp8_e32 v[224:225], v144
	v_cvt_pk_f32_fp8_sdwa v[226:227], v144 src0_sel:WORD_1
	v_cvt_pk_f32_fp8_e32 v[228:229], v145
	v_cvt_pk_f32_fp8_sdwa v[230:231], v145 src0_sel:WORD_1
	v_pk_fma_f32 v[112:113], v[224:225], s[56:57], v[112:113] op_sel_hi:[1,0,1]
	v_pk_fma_f32 v[114:115], v[226:227], s[56:57], v[114:115] op_sel_hi:[1,0,1]
	v_pk_fma_f32 v[116:117], v[228:229], s[56:57], v[116:117] op_sel_hi:[1,0,1]
	v_pk_fma_f32 v[118:119], v[230:231], s[56:57], v[118:119] op_sel_hi:[1,0,1]
	v_cvt_pk_f32_fp8_e32 v[224:225], v146
	v_cvt_pk_f32_fp8_sdwa v[226:227], v146 src0_sel:WORD_1
	v_cvt_pk_f32_fp8_e32 v[228:229], v147
	v_cvt_pk_f32_fp8_sdwa v[230:231], v147 src0_sel:WORD_1
	v_pk_fma_f32 v[120:121], v[224:225], s[56:57], v[120:121] op_sel_hi:[1,0,1]
	v_pk_fma_f32 v[122:123], v[226:227], s[56:57], v[122:123] op_sel_hi:[1,0,1]
	v_pk_fma_f32 v[124:125], v[228:229], s[56:57], v[124:125] op_sel_hi:[1,0,1]
	v_pk_fma_f32 v[126:127], v[230:231], s[56:57], v[126:127] op_sel_hi:[1,0,1]
	v_cvt_pk_f32_fp8_e32 v[224:225], v148
	v_cvt_pk_f32_fp8_sdwa v[226:227], v148 src0_sel:WORD_1
	v_cvt_pk_f32_fp8_e32 v[228:229], v149
	v_cvt_pk_f32_fp8_sdwa v[230:231], v149 src0_sel:WORD_1
	v_pk_fma_f32 v[112:113], v[224:225], s[58:59], v[112:113] op_sel_hi:[1,0,1]
	v_pk_fma_f32 v[114:115], v[226:227], s[58:59], v[114:115] op_sel_hi:[1,0,1]
	v_pk_fma_f32 v[116:117], v[228:229], s[58:59], v[116:117] op_sel_hi:[1,0,1]
	v_pk_fma_f32 v[118:119], v[230:231], s[58:59], v[118:119] op_sel_hi:[1,0,1]
	v_cvt_pk_f32_fp8_e32 v[224:225], v150
	v_cvt_pk_f32_fp8_sdwa v[226:227], v150 src0_sel:WORD_1
	v_cvt_pk_f32_fp8_e32 v[228:229], v151
	v_cvt_pk_f32_fp8_sdwa v[230:231], v151 src0_sel:WORD_1
	v_pk_fma_f32 v[120:121], v[224:225], s[58:59], v[120:121] op_sel_hi:[1,0,1]
	v_pk_fma_f32 v[122:123], v[226:227], s[58:59], v[122:123] op_sel_hi:[1,0,1]
	v_pk_fma_f32 v[124:125], v[228:229], s[58:59], v[124:125] op_sel_hi:[1,0,1]
	v_pk_fma_f32 v[126:127], v[230:231], s[58:59], v[126:127] op_sel_hi:[1,0,1]
	v_cvt_pk_f32_fp8_e32 v[224:225], v152
	v_cvt_pk_f32_fp8_sdwa v[226:227], v152 src0_sel:WORD_1
	v_cvt_pk_f32_fp8_e32 v[228:229], v153
	v_cvt_pk_f32_fp8_sdwa v[230:231], v153 src0_sel:WORD_1
	v_pk_fma_f32 v[112:113], v[224:225], s[60:61], v[112:113] op_sel_hi:[1,0,1]
	v_pk_fma_f32 v[114:115], v[226:227], s[60:61], v[114:115] op_sel_hi:[1,0,1]
	v_pk_fma_f32 v[116:117], v[228:229], s[60:61], v[116:117] op_sel_hi:[1,0,1]
	v_pk_fma_f32 v[118:119], v[230:231], s[60:61], v[118:119] op_sel_hi:[1,0,1]
	v_cvt_pk_f32_fp8_e32 v[224:225], v154
	v_cvt_pk_f32_fp8_sdwa v[226:227], v154 src0_sel:WORD_1
	v_cvt_pk_f32_fp8_e32 v[228:229], v155
	v_cvt_pk_f32_fp8_sdwa v[230:231], v155 src0_sel:WORD_1
	v_pk_fma_f32 v[120:121], v[224:225], s[60:61], v[120:121] op_sel_hi:[1,0,1]
	v_pk_fma_f32 v[122:123], v[226:227], s[60:61], v[122:123] op_sel_hi:[1,0,1]
	v_pk_fma_f32 v[124:125], v[228:229], s[60:61], v[124:125] op_sel_hi:[1,0,1]
	v_pk_fma_f32 v[126:127], v[230:231], s[60:61], v[126:127] op_sel_hi:[1,0,1]
	v_cvt_pk_f32_fp8_e32 v[224:225], v156
	v_cvt_pk_f32_fp8_sdwa v[226:227], v156 src0_sel:WORD_1
	v_cvt_pk_f32_fp8_e32 v[228:229], v157
	v_cvt_pk_f32_fp8_sdwa v[230:231], v157 src0_sel:WORD_1
	v_pk_fma_f32 v[112:113], v[224:225], s[62:63], v[112:113] op_sel_hi:[1,0,1]
	v_pk_fma_f32 v[114:115], v[226:227], s[62:63], v[114:115] op_sel_hi:[1,0,1]
	v_pk_fma_f32 v[116:117], v[228:229], s[62:63], v[116:117] op_sel_hi:[1,0,1]
	v_pk_fma_f32 v[118:119], v[230:231], s[62:63], v[118:119] op_sel_hi:[1,0,1]
	v_cvt_pk_f32_fp8_e32 v[224:225], v158
	v_cvt_pk_f32_fp8_sdwa v[226:227], v158 src0_sel:WORD_1
	v_cvt_pk_f32_fp8_e32 v[228:229], v159
	v_cvt_pk_f32_fp8_sdwa v[230:231], v159 src0_sel:WORD_1
	v_pk_fma_f32 v[120:121], v[224:225], s[62:63], v[120:121] op_sel_hi:[1,0,1]
	v_pk_fma_f32 v[122:123], v[226:227], s[62:63], v[122:123] op_sel_hi:[1,0,1]
	v_pk_fma_f32 v[124:125], v[228:229], s[62:63], v[124:125] op_sel_hi:[1,0,1]
	v_pk_fma_f32 v[126:127], v[230:231], s[62:63], v[126:127] op_sel_hi:[1,0,1]
.LV_s1_tail:
	ds_read_b128 v[236:239], v241 offset:128
	ds_read_b128 v[232:235], v241 offset:384
	s_add_i32 s21, s21, 1
.LV_s2:
	s_cmp_ge_u32 s21, s20
	s_cbranch_scc1 .LV_done
	s_waitcnt lgkmcnt(0)
	v_readlane_b32 s64, v232, 0
	v_readlane_b32 s65, v232, 16
	v_readlane_b32 s66, v232, 32
	v_readlane_b32 s67, v232, 48
	s_add_u32 s24, s6, s64
	s_addc_u32 s25, s7, 0
	s_add_u32 s26, s6, s65
	s_addc_u32 s27, s7, 0
	s_add_u32 s28, s6, s66
	s_addc_u32 s29, s7, 0
	s_add_u32 s30, s6, s67
	s_addc_u32 s31, s7, 0
	global_load_dwordx4 v[144:147], v240, s[24:25]
	global_load_dwordx4 v[148:151], v240, s[26:27]
	global_load_dwordx4 v[152:155], v240, s[28:29]
	global_load_dwordx4 v[156:159], v240, s[30:31]
	v_readfirstlane_b32 s23, v238
	v_readlane_b32 s56, v237, 0
	v_readlane_b32 s58, v237, 16
	v_readlane_b32 s60, v237, 32
	v_readlane_b32 s62, v237, 48
	s_and_b32 s23, s23, 7
	s_waitcnt vmcnt(16)
	s_cmp_ge_u32 s23, 4
	s_cbranch_scc1 .LV_s2_h
	s_cmp_ge_u32 s23, 2
	s_cbranch_scc1 .LV_s2_23
	s_cmp_eq_u32 s23, 0
	s_cbranch_scc1 .LV_s2_t0
	s_branch .LV_s2_t1

.LV_s2_t0:
	v_cvt_pk_f32_fp8_e32 v[224:225], v160
	v_cvt_pk_f32_fp8_sdwa v[226:227], v160 src0_sel:WORD_1
	v_cvt_pk_f32_fp8_e32 v[228:229], v161
	v_cvt_pk_f32_fp8_sdwa v[230:231], v161 src0_sel:WORD_1
	v_pk_fma_f32 v[0:1], v[224:225], s[56:57], v[0:1] op_sel_hi:[1,0,1]
	v_pk_fma_f32 v[2:3], v[226:227], s[56:57], v[2:3] op_sel_hi:[1,0,1]
	v_pk_fma_f32 v[4:5], v[228:229], s[56:57], v[4:5] op_sel_hi:[1,0,1]
	v_pk_fma_f32 v[6:7], v[230:231], s[56:57], v[6:7] op_sel_hi:[1,0,1]
	v_cvt_pk_f32_fp8_e32 v[224:225], v162
	v_cvt_pk_f32_fp8_sdwa v[226:227], v162 src0_sel:WORD_1
	v_cvt_pk_f32_fp8_e32 v[228:229], v163
	v_cvt_pk_f32_fp8_sdwa v[230:231], v163 src0_sel:WORD_1
	v_pk_fma_f32 v[8:9], v[224:225], s[56:57], v[8:9] op_sel_hi:[1,0,1]
	v_pk_fma_f32 v[10:11], v[226:227], s[56:57], v[10:11] op_sel_hi:[1,0,1]
	v_pk_fma_f32 v[12:13], v[228:229], s[56:57], v[12:13] op_sel_hi:[1,0,1]
	v_pk_fma_f32 v[14:15], v[230:231], s[56:57], v[14:15] op_sel_hi:[1,0,1]
	v_cvt_pk_f32_fp8_e32 v[224:225], v164
	v_cvt_pk_f32_fp8_sdwa v[226:227], v164 src0_sel:WORD_1
	v_cvt_pk_f32_fp8_e32 v[228:229], v165
	v_cvt_pk_f32_fp8_sdwa v[230:231], v165 src0_sel:WORD_1
	v_pk_fma_f32 v[0:1], v[224:225], s[58:59], v[0:1] op_sel_hi:[1,0,1]
	v_pk_fma_f32 v[2:3], v[226:227], s[58:59], v[2:3] op_sel_hi:[1,0,1]
	v_pk_fma_f32 v[4:5], v[228:229], s[58:59], v[4:5] op_sel_hi:[1,0,1]
	v_pk_fma_f32 v[6:7], v[230:231], s[58:59], v[6:7] op_sel_hi:[1,0,1]
	v_cvt_pk_f32_fp8_e32 v[224:225], v166
	v_cvt_pk_f32_fp8_sdwa v[226:227], v166 src0_sel:WORD_1
	v_cvt_pk_f32_fp8_e32 v[228:229], v167
	v_cvt_pk_f32_fp8_sdwa v[230:231], v167 src0_sel:WORD_1
	v_pk_fma_f32 v[8:9], v[224:225], s[58:59], v[8:9] op_sel_hi:[1,0,1]
	v_pk_fma_f32 v[10:11], v[226:227], s[58:59], v[10:11] op_sel_hi:[1,0,1]
	v_pk_fma_f32 v[12:13], v[228:229], s[58:59], v[12:13] op_sel_hi:[1,0,1]
	v_pk_fma_f32 v[14:15], v[230:231], s[58:59], v[14:15] op_sel_hi:[1,0,1]
	v_cvt_pk_f32_fp8_e32 v[224:225], v168
	v_cvt_pk_f32_fp8_sdwa v[226:227], v168 src0_sel:WORD_1
	v_cvt_pk_f32_fp8_e32 v[228:229], v169
	v_cvt_pk_f32_fp8_sdwa v[230:231], v169 src0_sel:WORD_1
	v_pk_fma_f32 v[0:1], v[224:225], s[60:61], v[0:1] op_sel_hi:[1,0,1]
	v_pk_fma_f32 v[2:3], v[226:227], s[60:61], v[2:3] op_sel_hi:[1,0,1]
	v_pk_fma_f32 v[4:5], v[228:229], s[60:61], v[4:5] op_sel_hi:[1,0,1]
	v_pk_fma_f32 v[6:7], v[230:231], s[60:61], v[6:7] op_sel_hi:[1,0,1]
	v_cvt_pk_f32_fp8_e32 v[224:225], v170
	v_cvt_pk_f32_fp8_sdwa v[226:227], v170 src0_sel:WORD_1
	v_cvt_pk_f32_fp8_e32 v[228:229], v171
	v_cvt_pk_f32_fp8_sdwa v[230:231], v171 src0_sel:WORD_1
	v_pk_fma_f32 v[8:9], v[224:225], s[60:61], v[8:9] op_sel_hi:[1,0,1]
	v_pk_fma_f32 v[10:11], v[226:227], s[60:61], v[10:11] op_sel_hi:[1,0,1]
	v_pk_fma_f32 v[12:13], v[228:229], s[60:61], v[12:13] op_sel_hi:[1,0,1]
	v_pk_fma_f32 v[14:15], v[230:231], s[60:61], v[14:15] op_sel_hi:[1,0,1]
	v_cvt_pk_f32_fp8_e32 v[224:225], v172
	v_cvt_pk_f32_fp8_sdwa v[226:227], v172 src0_sel:WORD_1
	v_cvt_pk_f32_fp8_e32 v[228:229], v173
	v_cvt_pk_f32_fp8_sdwa v[230:231], v173 src0_sel:WORD_1
	v_pk_fma_f32 v[0:1], v[224:225], s[62:63], v[0:1] op_sel_hi:[1,0,1]
	v_pk_fma_f32 v[2:3], v[226:227], s[62:63], v[2:3] op_sel_hi:[1,0,1]
	v_pk_fma_f32 v[4:5], v[228:229], s[62:63], v[4:5] op_sel_hi:[1,0,1]
	v_pk_fma_f32 v[6:7], v[230:231], s[62:63], v[6:7] op_sel_hi:[1,0,1]
	v_cvt_pk_f32_fp8_e32 v[224:225], v174
	v_cvt_pk_f32_fp8_sdwa v[226:227], v174 src0_sel:WORD_1
	v_cvt_pk_f32_fp8_e32 v[228:229], v175
	v_cvt_pk_f32_fp8_sdwa v[230:231], v175 src0_sel:WORD_1
	v_pk_fma_f32 v[8:9], v[224:225], s[62:63], v[8:9] op_sel_hi:[1,0,1]
	v_pk_fma_f32 v[10:11], v[226:227], s[62:63], v[10:11] op_sel_hi:[1,0,1]
	v_pk_fma_f32 v[12:13], v[228:229], s[62:63], v[12:13] op_sel_hi:[1,0,1]
	v_pk_fma_f32 v[14:15], v[230:231], s[62:63], v[14:15] op_sel_hi:[1,0,1]
	s_branch .LV_s2_tail
.LV_s2_t1:
	v_cvt_pk_f32_fp8_e32 v[224:225], v160
	v_cvt_pk_f32_fp8_sdwa v[226:227], v160 src0_sel:WORD_1
	v_cvt_pk_f32_fp8_e32 v[228:229], v161
	v_cvt_pk_f32_fp8_sdwa v[230:231], v161 src0_sel:WORD_1
	v_pk_fma_f32 v[16:17], v[224:225], s[56:57], v[16:17] op_sel_hi:[1,0,1]
	v_pk_fma_f32 v[18:19], v[226:227], s[56:57], v[18:19] op_sel_hi:[1,0,1]
	v_pk_fma_f32 v[20:21], v[228:229], s[56:57], v[20:21] op_sel_hi:[1,0,1]
	v_pk_fma_f32 v[22:23], v[230:231], s[56:57], v[22:23] op_sel_hi:[1,0,1]
	v_cvt_pk_f32_fp8_e32 v[224:225], v162
	v_cvt_pk_f32_fp8_sdwa v[226:227], v162 src0_sel:WORD_1
	v_cvt_pk_f32_fp8_e32 v[228:229], v163
	v_cvt_pk_f32_fp8_sdwa v[230:231], v163 src0_sel:WORD_1
	v_pk_fma_f32 v[24:25], v[224:225], s[56:57], v[24:25] op_sel_hi:[1,0,1]
	v_pk_fma_f32 v[26:27], v[226:227], s[56:57], v[26:27] op_sel_hi:[1,0,1]
	v_pk_fma_f32 v[28:29], v[228:229], s[56:57], v[28:29] op_sel_hi:[1,0,1]
	v_pk_fma_f32 v[30:31], v[230:231], s[56:57], v[30:31] op_sel_hi:[1,0,1]
	v_cvt_pk_f32_fp8_e32 v[224:225], v164
	v_cvt_pk_f32_fp8_sdwa v[226:227], v164 src0_sel:WORD_1
	v_cvt_pk_f32_fp8_e32 v[228:229], v165
	v_cvt_pk_f32_fp8_sdwa v[230:231], v165 src0_sel:WORD_1
	v_pk_fma_f32 v[16:17], v[224:225], s[58:59], v[16:17] op_sel_hi:[1,0,1]
	v_pk_fma_f32 v[18:19], v[226:227], s[58:59], v[18:19] op_sel_hi:[1,0,1]
	v_pk_fma_f32 v[20:21], v[228:229], s[58:59], v[20:21] op_sel_hi:[1,0,1]
	v_pk_fma_f32 v[22:23], v[230:231], s[58:59], v[22:23] op_sel_hi:[1,0,1]
	v_cvt_pk_f32_fp8_e32 v[224:225], v166
	v_cvt_pk_f32_fp8_sdwa v[226:227], v166 src0_sel:WORD_1
	v_cvt_pk_f32_fp8_e32 v[228:229], v167
	v_cvt_pk_f32_fp8_sdwa v[230:231], v167 src0_sel:WORD_1
	v_pk_fma_f32 v[24:25], v[224:225], s[58:59], v[24:25] op_sel_hi:[1,0,1]
	v_pk_fma_f32 v[26:27], v[226:227], s[58:59], v[26:27] op_sel_hi:[1,0,1]
	v_pk_fma_f32 v[28:29], v[228:229], s[58:59], v[28:29] op_sel_hi:[1,0,1]
	v_pk_fma_f32 v[30:31], v[230:231], s[58:59], v[30:31] op_sel_hi:[1,0,1]
	v_cvt_pk_f32_fp8_e32 v[224:225], v168
	v_cvt_pk_f32_fp8_sdwa v[226:227], v168 src0_sel:WORD_1
	v_cvt_pk_f32_fp8_e32 v[228:229], v169
	v_cvt_pk_f32_fp8_sdwa v[230:231], v169 src0_sel:WORD_1
	v_pk_fma_f32 v[16:17], v[224:225], s[60:61], v[16:17] op_sel_hi:[1,0,1]
	v_pk_fma_f32 v[18:19], v[226:227], s[60:61], v[18:19] op_sel_hi:[1,0,1]
	v_pk_fma_f32 v[20:21], v[228:229], s[60:61], v[20:21] op_sel_hi:[1,0,1]
	v_pk_fma_f32 v[22:23], v[230:231], s[60:61], v[22:23] op_sel_hi:[1,0,1]
	v_cvt_pk_f32_fp8_e32 v[224:225], v170
	v_cvt_pk_f32_fp8_sdwa v[226:227], v170 src0_sel:WORD_1
	v_cvt_pk_f32_fp8_e32 v[228:229], v171
	v_cvt_pk_f32_fp8_sdwa v[230:231], v171 src0_sel:WORD_1
	v_pk_fma_f32 v[24:25], v[224:225], s[60:61], v[24:25] op_sel_hi:[1,0,1]
	v_pk_fma_f32 v[26:27], v[226:227], s[60:61], v[26:27] op_sel_hi:[1,0,1]
	v_pk_fma_f32 v[28:29], v[228:229], s[60:61], v[28:29] op_sel_hi:[1,0,1]
	v_pk_fma_f32 v[30:31], v[230:231], s[60:61], v[30:31] op_sel_hi:[1,0,1]
	v_cvt_pk_f32_fp8_e32 v[224:225], v172
	v_cvt_pk_f32_fp8_sdwa v[226:227], v172 src0_sel:WORD_1
	v_cvt_pk_f32_fp8_e32 v[228:229], v173
	v_cvt_pk_f32_fp8_sdwa v[230:231], v173 src0_sel:WORD_1
	v_pk_fma_f32 v[16:17], v[224:225], s[62:63], v[16:17] op_sel_hi:[1,0,1]
	v_pk_fma_f32 v[18:19], v[226:227], s[62:63], v[18:19] op_sel_hi:[1,0,1]
	v_pk_fma_f32 v[20:21], v[228:229], s[62:63], v[20:21] op_sel_hi:[1,0,1]
	v_pk_fma_f32 v[22:23], v[230:231], s[62:63], v[22:23] op_sel_hi:[1,0,1]
	v_cvt_pk_f32_fp8_e32 v[224:225], v174
	v_cvt_pk_f32_fp8_sdwa v[226:227], v174 src0_sel:WORD_1
	v_cvt_pk_f32_fp8_e32 v[228:229], v175
	v_cvt_pk_f32_fp8_sdwa v[230:231], v175 src0_sel:WORD_1
	v_pk_fma_f32 v[24:25], v[224:225], s[62:63], v[24:25] op_sel_hi:[1,0,1]
	v_pk_fma_f32 v[26:27], v[226:227], s[62:63], v[26:27] op_sel_hi:[1,0,1]
	v_pk_fma_f32 v[28:29], v[228:229], s[62:63], v[28:29] op_sel_hi:[1,0,1]
	v_pk_fma_f32 v[30:31], v[230:231], s[62:63], v[30:31] op_sel_hi:[1,0,1]
	s_branch .LV_s2_tail
.LV_s2_t2:
	v_cvt_pk_f32_fp8_e32 v[224:225], v160
	v_cvt_pk_f32_fp8_sdwa v[226:227], v160 src0_sel:WORD_1
	v_cvt_pk_f32_fp8_e32 v[228:229], v161
	v_cvt_pk_f32_fp8_sdwa v[230:231], v161 src0_sel:WORD_1
	v_pk_fma_f32 v[32:33], v[224:225], s[56:57], v[32:33] op_sel_hi:[1,0,1]
	v_pk_fma_f32 v[34:35], v[226:227], s[56:57], v[34:35] op_sel_hi:[1,0,1]
	v_pk_fma_f32 v[36:37], v[228:229], s[56:57], v[36:37] op_sel_hi:[1,0,1]
	v_pk_fma_f32 v[38:39], v[230:231], s[56:57], v[38:39] op_sel_hi:[1,0,1]
	v_cvt_pk_f32_fp8_e32 v[224:225], v162
	v_cvt_pk_f32_fp8_sdwa v[226:227], v162 src0_sel:WORD_1
	v_cvt_pk_f32_fp8_e32 v[228:229], v163
	v_cvt_pk_f32_fp8_sdwa v[230:231], v163 src0_sel:WORD_1
	v_pk_fma_f32 v[40:41], v[224:225], s[56:57], v[40:41] op_sel_hi:[1,0,1]
	v_pk_fma_f32 v[42:43], v[226:227], s[56:57], v[42:43] op_sel_hi:[1,0,1]
	v_pk_fma_f32 v[44:45], v[228:229], s[56:57], v[44:45] op_sel_hi:[1,0,1]
	v_pk_fma_f32 v[46:47], v[230:231], s[56:57], v[46:47] op_sel_hi:[1,0,1]
	v_cvt_pk_f32_fp8_e32 v[224:225], v164
	v_cvt_pk_f32_fp8_sdwa v[226:227], v164 src0_sel:WORD_1
	v_cvt_pk_f32_fp8_e32 v[228:229], v165
	v_cvt_pk_f32_fp8_sdwa v[230:231], v165 src0_sel:WORD_1
	v_pk_fma_f32 v[32:33], v[224:225], s[58:59], v[32:33] op_sel_hi:[1,0,1]
	v_pk_fma_f32 v[34:35], v[226:227], s[58:59], v[34:35] op_sel_hi:[1,0,1]
	v_pk_fma_f32 v[36:37], v[228:229], s[58:59], v[36:37] op_sel_hi:[1,0,1]
	v_pk_fma_f32 v[38:39], v[230:231], s[58:59], v[38:39] op_sel_hi:[1,0,1]
	v_cvt_pk_f32_fp8_e32 v[224:225], v166
	v_cvt_pk_f32_fp8_sdwa v[226:227], v166 src0_sel:WORD_1
	v_cvt_pk_f32_fp8_e32 v[228:229], v167
	v_cvt_pk_f32_fp8_sdwa v[230:231], v167 src0_sel:WORD_1
	v_pk_fma_f32 v[40:41], v[224:225], s[58:59], v[40:41] op_sel_hi:[1,0,1]
	v_pk_fma_f32 v[42:43], v[226:227], s[58:59], v[42:43] op_sel_hi:[1,0,1]
	v_pk_fma_f32 v[44:45], v[228:229], s[58:59], v[44:45] op_sel_hi:[1,0,1]
	v_pk_fma_f32 v[46:47], v[230:231], s[58:59], v[46:47] op_sel_hi:[1,0,1]
	v_cvt_pk_f32_fp8_e32 v[224:225], v168
	v_cvt_pk_f32_fp8_sdwa v[226:227], v168 src0_sel:WORD_1
	v_cvt_pk_f32_fp8_e32 v[228:229], v169
	v_cvt_pk_f32_fp8_sdwa v[230:231], v169 src0_sel:WORD_1
	v_pk_fma_f32 v[32:33], v[224:225], s[60:61], v[32:33] op_sel_hi:[1,0,1]
	v_pk_fma_f32 v[34:35], v[226:227], s[60:61], v[34:35] op_sel_hi:[1,0,1]
	v_pk_fma_f32 v[36:37], v[228:229], s[60:61], v[36:37] op_sel_hi:[1,0,1]
	v_pk_fma_f32 v[38:39], v[230:231], s[60:61], v[38:39] op_sel_hi:[1,0,1]
	v_cvt_pk_f32_fp8_e32 v[224:225], v170
	v_cvt_pk_f32_fp8_sdwa v[226:227], v170 src0_sel:WORD_1
	v_cvt_pk_f32_fp8_e32 v[228:229], v171
	v_cvt_pk_f32_fp8_sdwa v[230:231], v171 src0_sel:WORD_1
	v_pk_fma_f32 v[40:41], v[224:225], s[60:61], v[40:41] op_sel_hi:[1,0,1]
	v_pk_fma_f32 v[42:43], v[226:227], s[60:61], v[42:43] op_sel_hi:[1,0,1]
	v_pk_fma_f32 v[44:45], v[228:229], s[60:61], v[44:45] op_sel_hi:[1,0,1]
	v_pk_fma_f32 v[46:47], v[230:231], s[60:61], v[46:47] op_sel_hi:[1,0,1]
	v_cvt_pk_f32_fp8_e32 v[224:225], v172
	v_cvt_pk_f32_fp8_sdwa v[226:227], v172 src0_sel:WORD_1
	v_cvt_pk_f32_fp8_e32 v[228:229], v173
	v_cvt_pk_f32_fp8_sdwa v[230:231], v173 src0_sel:WORD_1
	v_pk_fma_f32 v[32:33], v[224:225], s[62:63], v[32:33] op_sel_hi:[1,0,1]
	v_pk_fma_f32 v[34:35], v[226:227], s[62:63], v[34:35] op_sel_hi:[1,0,1]
	v_pk_fma_f32 v[36:37], v[228:229], s[62:63], v[36:37] op_sel_hi:[1,0,1]
	v_pk_fma_f32 v[38:39], v[230:231], s[62:63], v[38:39] op_sel_hi:[1,0,1]
	v_cvt_pk_f32_fp8_e32 v[224:225], v174
	v_cvt_pk_f32_fp8_sdwa v[226:227], v174 src0_sel:WORD_1
	v_cvt_pk_f32_fp8_e32 v[228:229], v175
	v_cvt_pk_f32_fp8_sdwa v[230:231], v175 src0_sel:WORD_1
	v_pk_fma_f32 v[40:41], v[224:225], s[62:63], v[40:41] op_sel_hi:[1,0,1]
	v_pk_fma_f32 v[42:43], v[226:227], s[62:63], v[42:43] op_sel_hi:[1,0,1]
	v_pk_fma_f32 v[44:45], v[228:229], s[62:63], v[44:45] op_sel_hi:[1,0,1]
	v_pk_fma_f32 v[46:47], v[230:231], s[62:63], v[46:47] op_sel_hi:[1,0,1]
	s_branch .LV_s2_tail
.LV_s2_t3:
	v_cvt_pk_f32_fp8_e32 v[224:225], v160
	v_cvt_pk_f32_fp8_sdwa v[226:227], v160 src0_sel:WORD_1
	v_cvt_pk_f32_fp8_e32 v[228:229], v161
	v_cvt_pk_f32_fp8_sdwa v[230:231], v161 src0_sel:WORD_1
	v_pk_fma_f32 v[48:49], v[224:225], s[56:57], v[48:49] op_sel_hi:[1,0,1]
	v_pk_fma_f32 v[50:51], v[226:227], s[56:57], v[50:51] op_sel_hi:[1,0,1]
	v_pk_fma_f32 v[52:53], v[228:229], s[56:57], v[52:53] op_sel_hi:[1,0,1]
	v_pk_fma_f32 v[54:55], v[230:231], s[56:57], v[54:55] op_sel_hi:[1,0,1]
	v_cvt_pk_f32_fp8_e32 v[224:225], v162
	v_cvt_pk_f32_fp8_sdwa v[226:227], v162 src0_sel:WORD_1
	v_cvt_pk_f32_fp8_e32 v[228:229], v163
	v_cvt_pk_f32_fp8_sdwa v[230:231], v163 src0_sel:WORD_1
	v_pk_fma_f32 v[56:57], v[224:225], s[56:57], v[56:57] op_sel_hi:[1,0,1]
	v_pk_fma_f32 v[58:59], v[226:227], s[56:57], v[58:59] op_sel_hi:[1,0,1]
	v_pk_fma_f32 v[60:61], v[228:229], s[56:57], v[60:61] op_sel_hi:[1,0,1]
	v_pk_fma_f32 v[62:63], v[230:231], s[56:57], v[62:63] op_sel_hi:[1,0,1]
	v_cvt_pk_f32_fp8_e32 v[224:225], v164
	v_cvt_pk_f32_fp8_sdwa v[226:227], v164 src0_sel:WORD_1
	v_cvt_pk_f32_fp8_e32 v[228:229], v165
	v_cvt_pk_f32_fp8_sdwa v[230:231], v165 src0_sel:WORD_1
	v_pk_fma_f32 v[48:49], v[224:225], s[58:59], v[48:49] op_sel_hi:[1,0,1]
	v_pk_fma_f32 v[50:51], v[226:227], s[58:59], v[50:51] op_sel_hi:[1,0,1]
	v_pk_fma_f32 v[52:53], v[228:229], s[58:59], v[52:53] op_sel_hi:[1,0,1]
	v_pk_fma_f32 v[54:55], v[230:231], s[58:59], v[54:55] op_sel_hi:[1,0,1]
	v_cvt_pk_f32_fp8_e32 v[224:225], v166
	v_cvt_pk_f32_fp8_sdwa v[226:227], v166 src0_sel:WORD_1
	v_cvt_pk_f32_fp8_e32 v[228:229], v167
	v_cvt_pk_f32_fp8_sdwa v[230:231], v167 src0_sel:WORD_1
	v_pk_fma_f32 v[56:57], v[224:225], s[58:59], v[56:57] op_sel_hi:[1,0,1]
	v_pk_fma_f32 v[58:59], v[226:227], s[58:59], v[58:59] op_sel_hi:[1,0,1]
	v_pk_fma_f32 v[60:61], v[228:229], s[58:59], v[60:61] op_sel_hi:[1,0,1]
	v_pk_fma_f32 v[62:63], v[230:231], s[58:59], v[62:63] op_sel_hi:[1,0,1]
	v_cvt_pk_f32_fp8_e32 v[224:225], v168
	v_cvt_pk_f32_fp8_sdwa v[226:227], v168 src0_sel:WORD_1
	v_cvt_pk_f32_fp8_e32 v[228:229], v169
	v_cvt_pk_f32_fp8_sdwa v[230:231], v169 src0_sel:WORD_1
	v_pk_fma_f32 v[48:49], v[224:225], s[60:61], v[48:49] op_sel_hi:[1,0,1]
	v_pk_fma_f32 v[50:51], v[226:227], s[60:61], v[50:51] op_sel_hi:[1,0,1]
	v_pk_fma_f32 v[52:53], v[228:229], s[60:61], v[52:53] op_sel_hi:[1,0,1]
	v_pk_fma_f32 v[54:55], v[230:231], s[60:61], v[54:55] op_sel_hi:[1,0,1]
	v_cvt_pk_f32_fp8_e32 v[224:225], v170
	v_cvt_pk_f32_fp8_sdwa v[226:227], v170 src0_sel:WORD_1
	v_cvt_pk_f32_fp8_e32 v[228:229], v171
	v_cvt_pk_f32_fp8_sdwa v[230:231], v171 src0_sel:WORD_1
	v_pk_fma_f32 v[56:57], v[224:225], s[60:61], v[56:57] op_sel_hi:[1,0,1]
	v_pk_fma_f32 v[58:59], v[226:227], s[60:61], v[58:59] op_sel_hi:[1,0,1]
	v_pk_fma_f32 v[60:61], v[228:229], s[60:61], v[60:61] op_sel_hi:[1,0,1]
	v_pk_fma_f32 v[62:63], v[230:231], s[60:61], v[62:63] op_sel_hi:[1,0,1]
	v_cvt_pk_f32_fp8_e32 v[224:225], v172
	v_cvt_pk_f32_fp8_sdwa v[226:227], v172 src0_sel:WORD_1
	v_cvt_pk_f32_fp8_e32 v[228:229], v173
	v_cvt_pk_f32_fp8_sdwa v[230:231], v173 src0_sel:WORD_1
	v_pk_fma_f32 v[48:49], v[224:225], s[62:63], v[48:49] op_sel_hi:[1,0,1]
	v_pk_fma_f32 v[50:51], v[226:227], s[62:63], v[50:51] op_sel_hi:[1,0,1]
	v_pk_fma_f32 v[52:53], v[228:229], s[62:63], v[52:53] op_sel_hi:[1,0,1]
	v_pk_fma_f32 v[54:55], v[230:231], s[62:63], v[54:55] op_sel_hi:[1,0,1]
	v_cvt_pk_f32_fp8_e32 v[224:225], v174
	v_cvt_pk_f32_fp8_sdwa v[226:227], v174 src0_sel:WORD_1
	v_cvt_pk_f32_fp8_e32 v[228:229], v175
	v_cvt_pk_f32_fp8_sdwa v[230:231], v175 src0_sel:WORD_1
	v_pk_fma_f32 v[56:57], v[224:225], s[62:63], v[56:57] op_sel_hi:[1,0,1]
	v_pk_fma_f32 v[58:59], v[226:227], s[62:63], v[58:59] op_sel_hi:[1,0,1]
	v_pk_fma_f32 v[60:61], v[228:229], s[62:63], v[60:61] op_sel_hi:[1,0,1]
	v_pk_fma_f32 v[62:63], v[230:231], s[62:63], v[62:63] op_sel_hi:[1,0,1]
	s_branch .LV_s2_tail
.LV_s2_t4:
	v_cvt_pk_f32_fp8_e32 v[224:225], v160
	v_cvt_pk_f32_fp8_sdwa v[226:227], v160 src0_sel:WORD_1
	v_cvt_pk_f32_fp8_e32 v[228:229], v161
	v_cvt_pk_f32_fp8_sdwa v[230:231], v161 src0_sel:WORD_1
	v_pk_fma_f32 v[64:65], v[224:225], s[56:57], v[64:65] op_sel_hi:[1,0,1]
	v_pk_fma_f32 v[66:67], v[226:227], s[56:57], v[66:67] op_sel_hi:[1,0,1]
	v_pk_fma_f32 v[68:69], v[228:229], s[56:57], v[68:69] op_sel_hi:[1,0,1]
	v_pk_fma_f32 v[70:71], v[230:231], s[56:57], v[70:71] op_sel_hi:[1,0,1]
	v_cvt_pk_f32_fp8_e32 v[224:225], v162
	v_cvt_pk_f32_fp8_sdwa v[226:227], v162 src0_sel:WORD_1
	v_cvt_pk_f32_fp8_e32 v[228:229], v163
	v_cvt_pk_f32_fp8_sdwa v[230:231], v163 src0_sel:WORD_1
	v_pk_fma_f32 v[72:73], v[224:225], s[56:57], v[72:73] op_sel_hi:[1,0,1]
	v_pk_fma_f32 v[74:75], v[226:227], s[56:57], v[74:75] op_sel_hi:[1,0,1]
	v_pk_fma_f32 v[76:77], v[228:229], s[56:57], v[76:77] op_sel_hi:[1,0,1]
	v_pk_fma_f32 v[78:79], v[230:231], s[56:57], v[78:79] op_sel_hi:[1,0,1]
	v_cvt_pk_f32_fp8_e32 v[224:225], v164
	v_cvt_pk_f32_fp8_sdwa v[226:227], v164 src0_sel:WORD_1
	v_cvt_pk_f32_fp8_e32 v[228:229], v165
	v_cvt_pk_f32_fp8_sdwa v[230:231], v165 src0_sel:WORD_1
	v_pk_fma_f32 v[64:65], v[224:225], s[58:59], v[64:65] op_sel_hi:[1,0,1]
	v_pk_fma_f32 v[66:67], v[226:227], s[58:59], v[66:67] op_sel_hi:[1,0,1]
	v_pk_fma_f32 v[68:69], v[228:229], s[58:59], v[68:69] op_sel_hi:[1,0,1]
	v_pk_fma_f32 v[70:71], v[230:231], s[58:59], v[70:71] op_sel_hi:[1,0,1]
	v_cvt_pk_f32_fp8_e32 v[224:225], v166
	v_cvt_pk_f32_fp8_sdwa v[226:227], v166 src0_sel:WORD_1
	v_cvt_pk_f32_fp8_e32 v[228:229], v167
	v_cvt_pk_f32_fp8_sdwa v[230:231], v167 src0_sel:WORD_1
	v_pk_fma_f32 v[72:73], v[224:225], s[58:59], v[72:73] op_sel_hi:[1,0,1]
	v_pk_fma_f32 v[74:75], v[226:227], s[58:59], v[74:75] op_sel_hi:[1,0,1]
	v_pk_fma_f32 v[76:77], v[228:229], s[58:59], v[76:77] op_sel_hi:[1,0,1]
	v_pk_fma_f32 v[78:79], v[230:231], s[58:59], v[78:79] op_sel_hi:[1,0,1]
	v_cvt_pk_f32_fp8_e32 v[224:225], v168
	v_cvt_pk_f32_fp8_sdwa v[226:227], v168 src0_sel:WORD_1
	v_cvt_pk_f32_fp8_e32 v[228:229], v169
	v_cvt_pk_f32_fp8_sdwa v[230:231], v169 src0_sel:WORD_1
	v_pk_fma_f32 v[64:65], v[224:225], s[60:61], v[64:65] op_sel_hi:[1,0,1]
	v_pk_fma_f32 v[66:67], v[226:227], s[60:61], v[66:67] op_sel_hi:[1,0,1]
	v_pk_fma_f32 v[68:69], v[228:229], s[60:61], v[68:69] op_sel_hi:[1,0,1]
	v_pk_fma_f32 v[70:71], v[230:231], s[60:61], v[70:71] op_sel_hi:[1,0,1]
	v_cvt_pk_f32_fp8_e32 v[224:225], v170
	v_cvt_pk_f32_fp8_sdwa v[226:227], v170 src0_sel:WORD_1
	v_cvt_pk_f32_fp8_e32 v[228:229], v171
	v_cvt_pk_f32_fp8_sdwa v[230:231], v171 src0_sel:WORD_1
	v_pk_fma_f32 v[72:73], v[224:225], s[60:61], v[72:73] op_sel_hi:[1,0,1]
	v_pk_fma_f32 v[74:75], v[226:227], s[60:61], v[74:75] op_sel_hi:[1,0,1]
	v_pk_fma_f32 v[76:77], v[228:229], s[60:61], v[76:77] op_sel_hi:[1,0,1]
	v_pk_fma_f32 v[78:79], v[230:231], s[60:61], v[78:79] op_sel_hi:[1,0,1]
	v_cvt_pk_f32_fp8_e32 v[224:225], v172
	v_cvt_pk_f32_fp8_sdwa v[226:227], v172 src0_sel:WORD_1
	v_cvt_pk_f32_fp8_e32 v[228:229], v173
	v_cvt_pk_f32_fp8_sdwa v[230:231], v173 src0_sel:WORD_1
	v_pk_fma_f32 v[64:65], v[224:225], s[62:63], v[64:65] op_sel_hi:[1,0,1]
	v_pk_fma_f32 v[66:67], v[226:227], s[62:63], v[66:67] op_sel_hi:[1,0,1]
	v_pk_fma_f32 v[68:69], v[228:229], s[62:63], v[68:69] op_sel_hi:[1,0,1]
	v_pk_fma_f32 v[70:71], v[230:231], s[62:63], v[70:71] op_sel_hi:[1,0,1]
	v_cvt_pk_f32_fp8_e32 v[224:225], v174
	v_cvt_pk_f32_fp8_sdwa v[226:227], v174 src0_sel:WORD_1
	v_cvt_pk_f32_fp8_e32 v[228:229], v175
	v_cvt_pk_f32_fp8_sdwa v[230:231], v175 src0_sel:WORD_1
	v_pk_fma_f32 v[72:73], v[224:225], s[62:63], v[72:73] op_sel_hi:[1,0,1]
	v_pk_fma_f32 v[74:75], v[226:227], s[62:63], v[74:75] op_sel_hi:[1,0,1]
	v_pk_fma_f32 v[76:77], v[228:229], s[62:63], v[76:77] op_sel_hi:[1,0,1]
	v_pk_fma_f32 v[78:79], v[230:231], s[62:63], v[78:79] op_sel_hi:[1,0,1]
	s_branch .LV_s2_tail
.LV_s2_t5:
	v_cvt_pk_f32_fp8_e32 v[224:225], v160
	v_cvt_pk_f32_fp8_sdwa v[226:227], v160 src0_sel:WORD_1
	v_cvt_pk_f32_fp8_e32 v[228:229], v161
	v_cvt_pk_f32_fp8_sdwa v[230:231], v161 src0_sel:WORD_1
	v_pk_fma_f32 v[80:81], v[224:225], s[56:57], v[80:81] op_sel_hi:[1,0,1]
	v_pk_fma_f32 v[82:83], v[226:227], s[56:57], v[82:83] op_sel_hi:[1,0,1]
	v_pk_fma_f32 v[84:85], v[228:229], s[56:57], v[84:85] op_sel_hi:[1,0,1]
	v_pk_fma_f32 v[86:87], v[230:231], s[56:57], v[86:87] op_sel_hi:[1,0,1]
	v_cvt_pk_f32_fp8_e32 v[224:225], v162
	v_cvt_pk_f32_fp8_sdwa v[226:227], v162 src0_sel:WORD_1
	v_cvt_pk_f32_fp8_e32 v[228:229], v163
	v_cvt_pk_f32_fp8_sdwa v[230:231], v163 src0_sel:WORD_1
	v_pk_fma_f32 v[88:89], v[224:225], s[56:57], v[88:89] op_sel_hi:[1,0,1]
	v_pk_fma_f32 v[90:91], v[226:227], s[56:57], v[90:91] op_sel_hi:[1,0,1]
	v_pk_fma_f32 v[92:93], v[228:229], s[56:57], v[92:93] op_sel_hi:[1,0,1]
	v_pk_fma_f32 v[94:95], v[230:231], s[56:57], v[94:95] op_sel_hi:[1,0,1]
	v_cvt_pk_f32_fp8_e32 v[224:225], v164
	v_cvt_pk_f32_fp8_sdwa v[226:227], v164 src0_sel:WORD_1
	v_cvt_pk_f32_fp8_e32 v[228:229], v165
	v_cvt_pk_f32_fp8_sdwa v[230:231], v165 src0_sel:WORD_1
	v_pk_fma_f32 v[80:81], v[224:225], s[58:59], v[80:81] op_sel_hi:[1,0,1]
	v_pk_fma_f32 v[82:83], v[226:227], s[58:59], v[82:83] op_sel_hi:[1,0,1]
	v_pk_fma_f32 v[84:85], v[228:229], s[58:59], v[84:85] op_sel_hi:[1,0,1]
	v_pk_fma_f32 v[86:87], v[230:231], s[58:59], v[86:87] op_sel_hi:[1,0,1]
	v_cvt_pk_f32_fp8_e32 v[224:225], v166
	v_cvt_pk_f32_fp8_sdwa v[226:227], v166 src0_sel:WORD_1
	v_cvt_pk_f32_fp8_e32 v[228:229], v167
	v_cvt_pk_f32_fp8_sdwa v[230:231], v167 src0_sel:WORD_1
	v_pk_fma_f32 v[88:89], v[224:225], s[58:59], v[88:89] op_sel_hi:[1,0,1]
	v_pk_fma_f32 v[90:91], v[226:227], s[58:59], v[90:91] op_sel_hi:[1,0,1]
	v_pk_fma_f32 v[92:93], v[228:229], s[58:59], v[92:93] op_sel_hi:[1,0,1]
	v_pk_fma_f32 v[94:95], v[230:231], s[58:59], v[94:95] op_sel_hi:[1,0,1]
	v_cvt_pk_f32_fp8_e32 v[224:225], v168
	v_cvt_pk_f32_fp8_sdwa v[226:227], v168 src0_sel:WORD_1
	v_cvt_pk_f32_fp8_e32 v[228:229], v169
	v_cvt_pk_f32_fp8_sdwa v[230:231], v169 src0_sel:WORD_1
	v_pk_fma_f32 v[80:81], v[224:225], s[60:61], v[80:81] op_sel_hi:[1,0,1]
	v_pk_fma_f32 v[82:83], v[226:227], s[60:61], v[82:83] op_sel_hi:[1,0,1]
	v_pk_fma_f32 v[84:85], v[228:229], s[60:61], v[84:85] op_sel_hi:[1,0,1]
	v_pk_fma_f32 v[86:87], v[230:231], s[60:61], v[86:87] op_sel_hi:[1,0,1]
	v_cvt_pk_f32_fp8_e32 v[224:225], v170
	v_cvt_pk_f32_fp8_sdwa v[226:227], v170 src0_sel:WORD_1
	v_cvt_pk_f32_fp8_e32 v[228:229], v171
	v_cvt_pk_f32_fp8_sdwa v[230:231], v171 src0_sel:WORD_1
	v_pk_fma_f32 v[88:89], v[224:225], s[60:61], v[88:89] op_sel_hi:[1,0,1]
	v_pk_fma_f32 v[90:91], v[226:227], s[60:61], v[90:91] op_sel_hi:[1,0,1]
	v_pk_fma_f32 v[92:93], v[228:229], s[60:61], v[92:93] op_sel_hi:[1,0,1]
	v_pk_fma_f32 v[94:95], v[230:231], s[60:61], v[94:95] op_sel_hi:[1,0,1]
	v_cvt_pk_f32_fp8_e32 v[224:225], v172
	v_cvt_pk_f32_fp8_sdwa v[226:227], v172 src0_sel:WORD_1
	v_cvt_pk_f32_fp8_e32 v[228:229], v173
	v_cvt_pk_f32_fp8_sdwa v[230:231], v173 src0_sel:WORD_1
	v_pk_fma_f32 v[80:81], v[224:225], s[62:63], v[80:81] op_sel_hi:[1,0,1]
	v_pk_fma_f32 v[82:83], v[226:227], s[62:63], v[82:83] op_sel_hi:[1,0,1]
	v_pk_fma_f32 v[84:85], v[228:229], s[62:63], v[84:85] op_sel_hi:[1,0,1]
	v_pk_fma_f32 v[86:87], v[230:231], s[62:63], v[86:87] op_sel_hi:[1,0,1]
	v_cvt_pk_f32_fp8_e32 v[224:225], v174
	v_cvt_pk_f32_fp8_sdwa v[226:227], v174 src0_sel:WORD_1
	v_cvt_pk_f32_fp8_e32 v[228:229], v175
	v_cvt_pk_f32_fp8_sdwa v[230:231], v175 src0_sel:WORD_1
	v_pk_fma_f32 v[88:89], v[224:225], s[62:63], v[88:89] op_sel_hi:[1,0,1]
	v_pk_fma_f32 v[90:91], v[226:227], s[62:63], v[90:91] op_sel_hi:[1,0,1]
	v_pk_fma_f32 v[92:93], v[228:229], s[62:63], v[92:93] op_sel_hi:[1,0,1]
	v_pk_fma_f32 v[94:95], v[230:231], s[62:63], v[94:95] op_sel_hi:[1,0,1]
	s_branch .LV_s2_tail
.LV_s2_t6:
	v_cvt_pk_f32_fp8_e32 v[224:225], v160
	v_cvt_pk_f32_fp8_sdwa v[226:227], v160 src0_sel:WORD_1
	v_cvt_pk_f32_fp8_e32 v[228:229], v161
	v_cvt_pk_f32_fp8_sdwa v[230:231], v161 src0_sel:WORD_1
	v_pk_fma_f32 v[96:97], v[224:225], s[56:57], v[96:97] op_sel_hi:[1,0,1]
	v_pk_fma_f32 v[98:99], v[226:227], s[56:57], v[98:99] op_sel_hi:[1,0,1]
	v_pk_fma_f32 v[100:101], v[228:229], s[56:57], v[100:101] op_sel_hi:[1,0,1]
	v_pk_fma_f32 v[102:103], v[230:231], s[56:57], v[102:103] op_sel_hi:[1,0,1]
	v_cvt_pk_f32_fp8_e32 v[224:225], v162
	v_cvt_pk_f32_fp8_sdwa v[226:227], v162 src0_sel:WORD_1
	v_cvt_pk_f32_fp8_e32 v[228:229], v163
	v_cvt_pk_f32_fp8_sdwa v[230:231], v163 src0_sel:WORD_1
	v_pk_fma_f32 v[104:105], v[224:225], s[56:57], v[104:105] op_sel_hi:[1,0,1]
	v_pk_fma_f32 v[106:107], v[226:227], s[56:57], v[106:107] op_sel_hi:[1,0,1]
	v_pk_fma_f32 v[108:109], v[228:229], s[56:57], v[108:109] op_sel_hi:[1,0,1]
	v_pk_fma_f32 v[110:111], v[230:231], s[56:57], v[110:111] op_sel_hi:[1,0,1]
	v_cvt_pk_f32_fp8_e32 v[224:225], v164
	v_cvt_pk_f32_fp8_sdwa v[226:227], v164 src0_sel:WORD_1
	v_cvt_pk_f32_fp8_e32 v[228:229], v165
	v_cvt_pk_f32_fp8_sdwa v[230:231], v165 src0_sel:WORD_1
	v_pk_fma_f32 v[96:97], v[224:225], s[58:59], v[96:97] op_sel_hi:[1,0,1]
	v_pk_fma_f32 v[98:99], v[226:227], s[58:59], v[98:99] op_sel_hi:[1,0,1]
	v_pk_fma_f32 v[100:101], v[228:229], s[58:59], v[100:101] op_sel_hi:[1,0,1]
	v_pk_fma_f32 v[102:103], v[230:231], s[58:59], v[102:103] op_sel_hi:[1,0,1]
	v_cvt_pk_f32_fp8_e32 v[224:225], v166
	v_cvt_pk_f32_fp8_sdwa v[226:227], v166 src0_sel:WORD_1
	v_cvt_pk_f32_fp8_e32 v[228:229], v167
	v_cvt_pk_f32_fp8_sdwa v[230:231], v167 src0_sel:WORD_1
	v_pk_fma_f32 v[104:105], v[224:225], s[58:59], v[104:105] op_sel_hi:[1,0,1]
	v_pk_fma_f32 v[106:107], v[226:227], s[58:59], v[106:107] op_sel_hi:[1,0,1]
	v_pk_fma_f32 v[108:109], v[228:229], s[58:59], v[108:109] op_sel_hi:[1,0,1]
	v_pk_fma_f32 v[110:111], v[230:231], s[58:59], v[110:111] op_sel_hi:[1,0,1]
	v_cvt_pk_f32_fp8_e32 v[224:225], v168
	v_cvt_pk_f32_fp8_sdwa v[226:227], v168 src0_sel:WORD_1
	v_cvt_pk_f32_fp8_e32 v[228:229], v169
	v_cvt_pk_f32_fp8_sdwa v[230:231], v169 src0_sel:WORD_1
	v_pk_fma_f32 v[96:97], v[224:225], s[60:61], v[96:97] op_sel_hi:[1,0,1]
	v_pk_fma_f32 v[98:99], v[226:227], s[60:61], v[98:99] op_sel_hi:[1,0,1]
	v_pk_fma_f32 v[100:101], v[228:229], s[60:61], v[100:101] op_sel_hi:[1,0,1]
	v_pk_fma_f32 v[102:103], v[230:231], s[60:61], v[102:103] op_sel_hi:[1,0,1]
	v_cvt_pk_f32_fp8_e32 v[224:225], v170
	v_cvt_pk_f32_fp8_sdwa v[226:227], v170 src0_sel:WORD_1
	v_cvt_pk_f32_fp8_e32 v[228:229], v171
	v_cvt_pk_f32_fp8_sdwa v[230:231], v171 src0_sel:WORD_1
	v_pk_fma_f32 v[104:105], v[224:225], s[60:61], v[104:105] op_sel_hi:[1,0,1]
	v_pk_fma_f32 v[106:107], v[226:227], s[60:61], v[106:107] op_sel_hi:[1,0,1]
	v_pk_fma_f32 v[108:109], v[228:229], s[60:61], v[108:109] op_sel_hi:[1,0,1]
	v_pk_fma_f32 v[110:111], v[230:231], s[60:61], v[110:111] op_sel_hi:[1,0,1]
	v_cvt_pk_f32_fp8_e32 v[224:225], v172
	v_cvt_pk_f32_fp8_sdwa v[226:227], v172 src0_sel:WORD_1
	v_cvt_pk_f32_fp8_e32 v[228:229], v173
	v_cvt_pk_f32_fp8_sdwa v[230:231], v173 src0_sel:WORD_1
	v_pk_fma_f32 v[96:97], v[224:225], s[62:63], v[96:97] op_sel_hi:[1,0,1]
	v_pk_fma_f32 v[98:99], v[226:227], s[62:63], v[98:99] op_sel_hi:[1,0,1]
	v_pk_fma_f32 v[100:101], v[228:229], s[62:63], v[100:101] op_sel_hi:[1,0,1]
	v_pk_fma_f32 v[102:103], v[230:231], s[62:63], v[102:103] op_sel_hi:[1,0,1]
	v_cvt_pk_f32_fp8_e32 v[224:225], v174
	v_cvt_pk_f32_fp8_sdwa v[226:227], v174 src0_sel:WORD_1
	v_cvt_pk_f32_fp8_e32 v[228:229], v175
	v_cvt_pk_f32_fp8_sdwa v[230:231], v175 src0_sel:WORD_1
	v_pk_fma_f32 v[104:105], v[224:225], s[62:63], v[104:105] op_sel_hi:[1,0,1]
	v_pk_fma_f32 v[106:107], v[226:227], s[62:63], v[106:107] op_sel_hi:[1,0,1]
	v_pk_fma_f32 v[108:109], v[228:229], s[62:63], v[108:109] op_sel_hi:[1,0,1]
	v_pk_fma_f32 v[110:111], v[230:231], s[62:63], v[110:111] op_sel_hi:[1,0,1]
	s_branch .LV_s2_tail
.LV_s2_t7:
	v_cvt_pk_f32_fp8_e32 v[224:225], v160
	v_cvt_pk_f32_fp8_sdwa v[226:227], v160 src0_sel:WORD_1
	v_cvt_pk_f32_fp8_e32 v[228:229], v161
	v_cvt_pk_f32_fp8_sdwa v[230:231], v161 src0_sel:WORD_1
	v_pk_fma_f32 v[112:113], v[224:225], s[56:57], v[112:113] op_sel_hi:[1,0,1]
	v_pk_fma_f32 v[114:115], v[226:227], s[56:57], v[114:115] op_sel_hi:[1,0,1]
	v_pk_fma_f32 v[116:117], v[228:229], s[56:57], v[116:117] op_sel_hi:[1,0,1]
	v_pk_fma_f32 v[118:119], v[230:231], s[56:57], v[118:119] op_sel_hi:[1,0,1]
	v_cvt_pk_f32_fp8_e32 v[224:225], v162
	v_cvt_pk_f32_fp8_sdwa v[226:227], v162 src0_sel:WORD_1
	v_cvt_pk_f32_fp8_e32 v[228:229], v163
	v_cvt_pk_f32_fp8_sdwa v[230:231], v163 src0_sel:WORD_1
	v_pk_fma_f32 v[120:121], v[224:225], s[56:57], v[120:121] op_sel_hi:[1,0,1]
	v_pk_fma_f32 v[122:123], v[226:227], s[56:57], v[122:123] op_sel_hi:[1,0,1]
	v_pk_fma_f32 v[124:125], v[228:229], s[56:57], v[124:125] op_sel_hi:[1,0,1]
	v_pk_fma_f32 v[126:127], v[230:231], s[56:57], v[126:127] op_sel_hi:[1,0,1]
	v_cvt_pk_f32_fp8_e32 v[224:225], v164
	v_cvt_pk_f32_fp8_sdwa v[226:227], v164 src0_sel:WORD_1
	v_cvt_pk_f32_fp8_e32 v[228:229], v165
	v_cvt_pk_f32_fp8_sdwa v[230:231], v165 src0_sel:WORD_1
	v_pk_fma_f32 v[112:113], v[224:225], s[58:59], v[112:113] op_sel_hi:[1,0,1]
	v_pk_fma_f32 v[114:115], v[226:227], s[58:59], v[114:115] op_sel_hi:[1,0,1]
	v_pk_fma_f32 v[116:117], v[228:229], s[58:59], v[116:117] op_sel_hi:[1,0,1]
	v_pk_fma_f32 v[118:119], v[230:231], s[58:59], v[118:119] op_sel_hi:[1,0,1]
	v_cvt_pk_f32_fp8_e32 v[224:225], v166
	v_cvt_pk_f32_fp8_sdwa v[226:227], v166 src0_sel:WORD_1
	v_cvt_pk_f32_fp8_e32 v[228:229], v167
	v_cvt_pk_f32_fp8_sdwa v[230:231], v167 src0_sel:WORD_1
	v_pk_fma_f32 v[120:121], v[224:225], s[58:59], v[120:121] op_sel_hi:[1,0,1]
	v_pk_fma_f32 v[122:123], v[226:227], s[58:59], v[122:123] op_sel_hi:[1,0,1]
	v_pk_fma_f32 v[124:125], v[228:229], s[58:59], v[124:125] op_sel_hi:[1,0,1]
	v_pk_fma_f32 v[126:127], v[230:231], s[58:59], v[126:127] op_sel_hi:[1,0,1]
	v_cvt_pk_f32_fp8_e32 v[224:225], v168
	v_cvt_pk_f32_fp8_sdwa v[226:227], v168 src0_sel:WORD_1
	v_cvt_pk_f32_fp8_e32 v[228:229], v169
	v_cvt_pk_f32_fp8_sdwa v[230:231], v169 src0_sel:WORD_1
	v_pk_fma_f32 v[112:113], v[224:225], s[60:61], v[112:113] op_sel_hi:[1,0,1]
	v_pk_fma_f32 v[114:115], v[226:227], s[60:61], v[114:115] op_sel_hi:[1,0,1]
	v_pk_fma_f32 v[116:117], v[228:229], s[60:61], v[116:117] op_sel_hi:[1,0,1]
	v_pk_fma_f32 v[118:119], v[230:231], s[60:61], v[118:119] op_sel_hi:[1,0,1]
	v_cvt_pk_f32_fp8_e32 v[224:225], v170
	v_cvt_pk_f32_fp8_sdwa v[226:227], v170 src0_sel:WORD_1
	v_cvt_pk_f32_fp8_e32 v[228:229], v171
	v_cvt_pk_f32_fp8_sdwa v[230:231], v171 src0_sel:WORD_1
	v_pk_fma_f32 v[120:121], v[224:225], s[60:61], v[120:121] op_sel_hi:[1,0,1]
	v_pk_fma_f32 v[122:123], v[226:227], s[60:61], v[122:123] op_sel_hi:[1,0,1]
	v_pk_fma_f32 v[124:125], v[228:229], s[60:61], v[124:125] op_sel_hi:[1,0,1]
	v_pk_fma_f32 v[126:127], v[230:231], s[60:61], v[126:127] op_sel_hi:[1,0,1]
	v_cvt_pk_f32_fp8_e32 v[224:225], v172
	v_cvt_pk_f32_fp8_sdwa v[226:227], v172 src0_sel:WORD_1
	v_cvt_pk_f32_fp8_e32 v[228:229], v173
	v_cvt_pk_f32_fp8_sdwa v[230:231], v173 src0_sel:WORD_1
	v_pk_fma_f32 v[112:113], v[224:225], s[62:63], v[112:113] op_sel_hi:[1,0,1]
	v_pk_fma_f32 v[114:115], v[226:227], s[62:63], v[114:115] op_sel_hi:[1,0,1]
	v_pk_fma_f32 v[116:117], v[228:229], s[62:63], v[116:117] op_sel_hi:[1,0,1]
	v_pk_fma_f32 v[118:119], v[230:231], s[62:63], v[118:119] op_sel_hi:[1,0,1]
	v_cvt_pk_f32_fp8_e32 v[224:225], v174
	v_cvt_pk_f32_fp8_sdwa v[226:227], v174 src0_sel:WORD_1
	v_cvt_pk_f32_fp8_e32 v[228:229], v175
	v_cvt_pk_f32_fp8_sdwa v[230:231], v175 src0_sel:WORD_1
	v_pk_fma_f32 v[120:121], v[224:225], s[62:63], v[120:121] op_sel_hi:[1,0,1]
	v_pk_fma_f32 v[122:123], v[226:227], s[62:63], v[122:123] op_sel_hi:[1,0,1]
	v_pk_fma_f32 v[124:125], v[228:229], s[62:63], v[124:125] op_sel_hi:[1,0,1]
	v_pk_fma_f32 v[126:127], v[230:231], s[62:63], v[126:127] op_sel_hi:[1,0,1]
.LV_s2_tail:
	ds_read_b128 v[236:239], v241 offset:192
	ds_read_b128 v[232:235], v241 offset:448
	s_add_i32 s21, s21, 1
.LV_s3:
	s_cmp_ge_u32 s21, s20
	s_cbranch_scc1 .LV_done
	s_waitcnt lgkmcnt(0)
	v_readlane_b32 s64, v232, 0
	v_readlane_b32 s65, v232, 16
	v_readlane_b32 s66, v232, 32
	v_readlane_b32 s67, v232, 48
	s_add_u32 s24, s6, s64
	s_addc_u32 s25, s7, 0
	s_add_u32 s26, s6, s65
	s_addc_u32 s27, s7, 0
	s_add_u32 s28, s6, s66
	s_addc_u32 s29, s7, 0
	s_add_u32 s30, s6, s67
	s_addc_u32 s31, s7, 0
	global_load_dwordx4 v[160:163], v240, s[24:25]
	global_load_dwordx4 v[164:167], v240, s[26:27]
	global_load_dwordx4 v[168:171], v240, s[28:29]
	global_load_dwordx4 v[172:175], v240, s[30:31]
	v_readfirstlane_b32 s23, v238
	v_readlane_b32 s56, v237, 0
	v_readlane_b32 s58, v237, 16
	v_readlane_b32 s60, v237, 32
	v_readlane_b32 s62, v237, 48
	s_and_b32 s23, s23, 7
	s_waitcnt vmcnt(16)
	s_cmp_ge_u32 s23, 4
	s_cbranch_scc1 .LV_s3_h
	s_cmp_ge_u32 s23, 2
	s_cbranch_scc1 .LV_s3_23
	s_cmp_eq_u32 s23, 0
	s_cbranch_scc1 .LV_s3_t0
	s_branch .LV_s3_t1

.LV_s3_t0:
	v_cvt_pk_f32_fp8_e32 v[224:225], v176
	v_cvt_pk_f32_fp8_sdwa v[226:227], v176 src0_sel:WORD_1
	v_cvt_pk_f32_fp8_e32 v[228:229], v177
	v_cvt_pk_f32_fp8_sdwa v[230:231], v177 src0_sel:WORD_1
	v_pk_fma_f32 v[0:1], v[224:225], s[56:57], v[0:1] op_sel_hi:[1,0,1]
	v_pk_fma_f32 v[2:3], v[226:227], s[56:57], v[2:3] op_sel_hi:[1,0,1]
	v_pk_fma_f32 v[4:5], v[228:229], s[56:57], v[4:5] op_sel_hi:[1,0,1]
	v_pk_fma_f32 v[6:7], v[230:231], s[56:57], v[6:7] op_sel_hi:[1,0,1]
	v_cvt_pk_f32_fp8_e32 v[224:225], v178
	v_cvt_pk_f32_fp8_sdwa v[226:227], v178 src0_sel:WORD_1
	v_cvt_pk_f32_fp8_e32 v[228:229], v179
	v_cvt_pk_f32_fp8_sdwa v[230:231], v179 src0_sel:WORD_1
	v_pk_fma_f32 v[8:9], v[224:225], s[56:57], v[8:9] op_sel_hi:[1,0,1]
	v_pk_fma_f32 v[10:11], v[226:227], s[56:57], v[10:11] op_sel_hi:[1,0,1]
	v_pk_fma_f32 v[12:13], v[228:229], s[56:57], v[12:13] op_sel_hi:[1,0,1]
	v_pk_fma_f32 v[14:15], v[230:231], s[56:57], v[14:15] op_sel_hi:[1,0,1]
	v_cvt_pk_f32_fp8_e32 v[224:225], v180
	v_cvt_pk_f32_fp8_sdwa v[226:227], v180 src0_sel:WORD_1
	v_cvt_pk_f32_fp8_e32 v[228:229], v181
	v_cvt_pk_f32_fp8_sdwa v[230:231], v181 src0_sel:WORD_1
	v_pk_fma_f32 v[0:1], v[224:225], s[58:59], v[0:1] op_sel_hi:[1,0,1]
	v_pk_fma_f32 v[2:3], v[226:227], s[58:59], v[2:3] op_sel_hi:[1,0,1]
	v_pk_fma_f32 v[4:5], v[228:229], s[58:59], v[4:5] op_sel_hi:[1,0,1]
	v_pk_fma_f32 v[6:7], v[230:231], s[58:59], v[6:7] op_sel_hi:[1,0,1]
	v_cvt_pk_f32_fp8_e32 v[224:225], v182
	v_cvt_pk_f32_fp8_sdwa v[226:227], v182 src0_sel:WORD_1
	v_cvt_pk_f32_fp8_e32 v[228:229], v183
	v_cvt_pk_f32_fp8_sdwa v[230:231], v183 src0_sel:WORD_1
	v_pk_fma_f32 v[8:9], v[224:225], s[58:59], v[8:9] op_sel_hi:[1,0,1]
	v_pk_fma_f32 v[10:11], v[226:227], s[58:59], v[10:11] op_sel_hi:[1,0,1]
	v_pk_fma_f32 v[12:13], v[228:229], s[58:59], v[12:13] op_sel_hi:[1,0,1]
	v_pk_fma_f32 v[14:15], v[230:231], s[58:59], v[14:15] op_sel_hi:[1,0,1]
	v_cvt_pk_f32_fp8_e32 v[224:225], v184
	v_cvt_pk_f32_fp8_sdwa v[226:227], v184 src0_sel:WORD_1
	v_cvt_pk_f32_fp8_e32 v[228:229], v185
	v_cvt_pk_f32_fp8_sdwa v[230:231], v185 src0_sel:WORD_1
	v_pk_fma_f32 v[0:1], v[224:225], s[60:61], v[0:1] op_sel_hi:[1,0,1]
	v_pk_fma_f32 v[2:3], v[226:227], s[60:61], v[2:3] op_sel_hi:[1,0,1]
	v_pk_fma_f32 v[4:5], v[228:229], s[60:61], v[4:5] op_sel_hi:[1,0,1]
	v_pk_fma_f32 v[6:7], v[230:231], s[60:61], v[6:7] op_sel_hi:[1,0,1]
	v_cvt_pk_f32_fp8_e32 v[224:225], v186
	v_cvt_pk_f32_fp8_sdwa v[226:227], v186 src0_sel:WORD_1
	v_cvt_pk_f32_fp8_e32 v[228:229], v187
	v_cvt_pk_f32_fp8_sdwa v[230:231], v187 src0_sel:WORD_1
	v_pk_fma_f32 v[8:9], v[224:225], s[60:61], v[8:9] op_sel_hi:[1,0,1]
	v_pk_fma_f32 v[10:11], v[226:227], s[60:61], v[10:11] op_sel_hi:[1,0,1]
	v_pk_fma_f32 v[12:13], v[228:229], s[60:61], v[12:13] op_sel_hi:[1,0,1]
	v_pk_fma_f32 v[14:15], v[230:231], s[60:61], v[14:15] op_sel_hi:[1,0,1]
	v_cvt_pk_f32_fp8_e32 v[224:225], v188
	v_cvt_pk_f32_fp8_sdwa v[226:227], v188 src0_sel:WORD_1
	v_cvt_pk_f32_fp8_e32 v[228:229], v189
	v_cvt_pk_f32_fp8_sdwa v[230:231], v189 src0_sel:WORD_1
	v_pk_fma_f32 v[0:1], v[224:225], s[62:63], v[0:1] op_sel_hi:[1,0,1]
	v_pk_fma_f32 v[2:3], v[226:227], s[62:63], v[2:3] op_sel_hi:[1,0,1]
	v_pk_fma_f32 v[4:5], v[228:229], s[62:63], v[4:5] op_sel_hi:[1,0,1]
	v_pk_fma_f32 v[6:7], v[230:231], s[62:63], v[6:7] op_sel_hi:[1,0,1]
	v_cvt_pk_f32_fp8_e32 v[224:225], v190
	v_cvt_pk_f32_fp8_sdwa v[226:227], v190 src0_sel:WORD_1
	v_cvt_pk_f32_fp8_e32 v[228:229], v191
	v_cvt_pk_f32_fp8_sdwa v[230:231], v191 src0_sel:WORD_1
	v_pk_fma_f32 v[8:9], v[224:225], s[62:63], v[8:9] op_sel_hi:[1,0,1]
	v_pk_fma_f32 v[10:11], v[226:227], s[62:63], v[10:11] op_sel_hi:[1,0,1]
	v_pk_fma_f32 v[12:13], v[228:229], s[62:63], v[12:13] op_sel_hi:[1,0,1]
	v_pk_fma_f32 v[14:15], v[230:231], s[62:63], v[14:15] op_sel_hi:[1,0,1]
	s_branch .LV_s3_tail
.LV_s3_t1:
	v_cvt_pk_f32_fp8_e32 v[224:225], v176
	v_cvt_pk_f32_fp8_sdwa v[226:227], v176 src0_sel:WORD_1
	v_cvt_pk_f32_fp8_e32 v[228:229], v177
	v_cvt_pk_f32_fp8_sdwa v[230:231], v177 src0_sel:WORD_1
	v_pk_fma_f32 v[16:17], v[224:225], s[56:57], v[16:17] op_sel_hi:[1,0,1]
	v_pk_fma_f32 v[18:19], v[226:227], s[56:57], v[18:19] op_sel_hi:[1,0,1]
	v_pk_fma_f32 v[20:21], v[228:229], s[56:57], v[20:21] op_sel_hi:[1,0,1]
	v_pk_fma_f32 v[22:23], v[230:231], s[56:57], v[22:23] op_sel_hi:[1,0,1]
	v_cvt_pk_f32_fp8_e32 v[224:225], v178
	v_cvt_pk_f32_fp8_sdwa v[226:227], v178 src0_sel:WORD_1
	v_cvt_pk_f32_fp8_e32 v[228:229], v179
	v_cvt_pk_f32_fp8_sdwa v[230:231], v179 src0_sel:WORD_1
	v_pk_fma_f32 v[24:25], v[224:225], s[56:57], v[24:25] op_sel_hi:[1,0,1]
	v_pk_fma_f32 v[26:27], v[226:227], s[56:57], v[26:27] op_sel_hi:[1,0,1]
	v_pk_fma_f32 v[28:29], v[228:229], s[56:57], v[28:29] op_sel_hi:[1,0,1]
	v_pk_fma_f32 v[30:31], v[230:231], s[56:57], v[30:31] op_sel_hi:[1,0,1]
	v_cvt_pk_f32_fp8_e32 v[224:225], v180
	v_cvt_pk_f32_fp8_sdwa v[226:227], v180 src0_sel:WORD_1
	v_cvt_pk_f32_fp8_e32 v[228:229], v181
	v_cvt_pk_f32_fp8_sdwa v[230:231], v181 src0_sel:WORD_1
	v_pk_fma_f32 v[16:17], v[224:225], s[58:59], v[16:17] op_sel_hi:[1,0,1]
	v_pk_fma_f32 v[18:19], v[226:227], s[58:59], v[18:19] op_sel_hi:[1,0,1]
	v_pk_fma_f32 v[20:21], v[228:229], s[58:59], v[20:21] op_sel_hi:[1,0,1]
	v_pk_fma_f32 v[22:23], v[230:231], s[58:59], v[22:23] op_sel_hi:[1,0,1]
	v_cvt_pk_f32_fp8_e32 v[224:225], v182
	v_cvt_pk_f32_fp8_sdwa v[226:227], v182 src0_sel:WORD_1
	v_cvt_pk_f32_fp8_e32 v[228:229], v183
	v_cvt_pk_f32_fp8_sdwa v[230:231], v183 src0_sel:WORD_1
	v_pk_fma_f32 v[24:25], v[224:225], s[58:59], v[24:25] op_sel_hi:[1,0,1]
	v_pk_fma_f32 v[26:27], v[226:227], s[58:59], v[26:27] op_sel_hi:[1,0,1]
	v_pk_fma_f32 v[28:29], v[228:229], s[58:59], v[28:29] op_sel_hi:[1,0,1]
	v_pk_fma_f32 v[30:31], v[230:231], s[58:59], v[30:31] op_sel_hi:[1,0,1]
	v_cvt_pk_f32_fp8_e32 v[224:225], v184
	v_cvt_pk_f32_fp8_sdwa v[226:227], v184 src0_sel:WORD_1
	v_cvt_pk_f32_fp8_e32 v[228:229], v185
	v_cvt_pk_f32_fp8_sdwa v[230:231], v185 src0_sel:WORD_1
	v_pk_fma_f32 v[16:17], v[224:225], s[60:61], v[16:17] op_sel_hi:[1,0,1]
	v_pk_fma_f32 v[18:19], v[226:227], s[60:61], v[18:19] op_sel_hi:[1,0,1]
	v_pk_fma_f32 v[20:21], v[228:229], s[60:61], v[20:21] op_sel_hi:[1,0,1]
	v_pk_fma_f32 v[22:23], v[230:231], s[60:61], v[22:23] op_sel_hi:[1,0,1]
	v_cvt_pk_f32_fp8_e32 v[224:225], v186
	v_cvt_pk_f32_fp8_sdwa v[226:227], v186 src0_sel:WORD_1
	v_cvt_pk_f32_fp8_e32 v[228:229], v187
	v_cvt_pk_f32_fp8_sdwa v[230:231], v187 src0_sel:WORD_1
	v_pk_fma_f32 v[24:25], v[224:225], s[60:61], v[24:25] op_sel_hi:[1,0,1]
	v_pk_fma_f32 v[26:27], v[226:227], s[60:61], v[26:27] op_sel_hi:[1,0,1]
	v_pk_fma_f32 v[28:29], v[228:229], s[60:61], v[28:29] op_sel_hi:[1,0,1]
	v_pk_fma_f32 v[30:31], v[230:231], s[60:61], v[30:31] op_sel_hi:[1,0,1]
	v_cvt_pk_f32_fp8_e32 v[224:225], v188
	v_cvt_pk_f32_fp8_sdwa v[226:227], v188 src0_sel:WORD_1
	v_cvt_pk_f32_fp8_e32 v[228:229], v189
	v_cvt_pk_f32_fp8_sdwa v[230:231], v189 src0_sel:WORD_1
	v_pk_fma_f32 v[16:17], v[224:225], s[62:63], v[16:17] op_sel_hi:[1,0,1]
	v_pk_fma_f32 v[18:19], v[226:227], s[62:63], v[18:19] op_sel_hi:[1,0,1]
	v_pk_fma_f32 v[20:21], v[228:229], s[62:63], v[20:21] op_sel_hi:[1,0,1]
	v_pk_fma_f32 v[22:23], v[230:231], s[62:63], v[22:23] op_sel_hi:[1,0,1]
	v_cvt_pk_f32_fp8_e32 v[224:225], v190
	v_cvt_pk_f32_fp8_sdwa v[226:227], v190 src0_sel:WORD_1
	v_cvt_pk_f32_fp8_e32 v[228:229], v191
	v_cvt_pk_f32_fp8_sdwa v[230:231], v191 src0_sel:WORD_1
	v_pk_fma_f32 v[24:25], v[224:225], s[62:63], v[24:25] op_sel_hi:[1,0,1]
	v_pk_fma_f32 v[26:27], v[226:227], s[62:63], v[26:27] op_sel_hi:[1,0,1]
	v_pk_fma_f32 v[28:29], v[228:229], s[62:63], v[28:29] op_sel_hi:[1,0,1]
	v_pk_fma_f32 v[30:31], v[230:231], s[62:63], v[30:31] op_sel_hi:[1,0,1]
	s_branch .LV_s3_tail
.LV_s3_t2:
	v_cvt_pk_f32_fp8_e32 v[224:225], v176
	v_cvt_pk_f32_fp8_sdwa v[226:227], v176 src0_sel:WORD_1
	v_cvt_pk_f32_fp8_e32 v[228:229], v177
	v_cvt_pk_f32_fp8_sdwa v[230:231], v177 src0_sel:WORD_1
	v_pk_fma_f32 v[32:33], v[224:225], s[56:57], v[32:33] op_sel_hi:[1,0,1]
	v_pk_fma_f32 v[34:35], v[226:227], s[56:57], v[34:35] op_sel_hi:[1,0,1]
	v_pk_fma_f32 v[36:37], v[228:229], s[56:57], v[36:37] op_sel_hi:[1,0,1]
	v_pk_fma_f32 v[38:39], v[230:231], s[56:57], v[38:39] op_sel_hi:[1,0,1]
	v_cvt_pk_f32_fp8_e32 v[224:225], v178
	v_cvt_pk_f32_fp8_sdwa v[226:227], v178 src0_sel:WORD_1
	v_cvt_pk_f32_fp8_e32 v[228:229], v179
	v_cvt_pk_f32_fp8_sdwa v[230:231], v179 src0_sel:WORD_1
	v_pk_fma_f32 v[40:41], v[224:225], s[56:57], v[40:41] op_sel_hi:[1,0,1]
	v_pk_fma_f32 v[42:43], v[226:227], s[56:57], v[42:43] op_sel_hi:[1,0,1]
	v_pk_fma_f32 v[44:45], v[228:229], s[56:57], v[44:45] op_sel_hi:[1,0,1]
	v_pk_fma_f32 v[46:47], v[230:231], s[56:57], v[46:47] op_sel_hi:[1,0,1]
	v_cvt_pk_f32_fp8_e32 v[224:225], v180
	v_cvt_pk_f32_fp8_sdwa v[226:227], v180 src0_sel:WORD_1
	v_cvt_pk_f32_fp8_e32 v[228:229], v181
	v_cvt_pk_f32_fp8_sdwa v[230:231], v181 src0_sel:WORD_1
	v_pk_fma_f32 v[32:33], v[224:225], s[58:59], v[32:33] op_sel_hi:[1,0,1]
	v_pk_fma_f32 v[34:35], v[226:227], s[58:59], v[34:35] op_sel_hi:[1,0,1]
	v_pk_fma_f32 v[36:37], v[228:229], s[58:59], v[36:37] op_sel_hi:[1,0,1]
	v_pk_fma_f32 v[38:39], v[230:231], s[58:59], v[38:39] op_sel_hi:[1,0,1]
	v_cvt_pk_f32_fp8_e32 v[224:225], v182
	v_cvt_pk_f32_fp8_sdwa v[226:227], v182 src0_sel:WORD_1
	v_cvt_pk_f32_fp8_e32 v[228:229], v183
	v_cvt_pk_f32_fp8_sdwa v[230:231], v183 src0_sel:WORD_1
	v_pk_fma_f32 v[40:41], v[224:225], s[58:59], v[40:41] op_sel_hi:[1,0,1]
	v_pk_fma_f32 v[42:43], v[226:227], s[58:59], v[42:43] op_sel_hi:[1,0,1]
	v_pk_fma_f32 v[44:45], v[228:229], s[58:59], v[44:45] op_sel_hi:[1,0,1]
	v_pk_fma_f32 v[46:47], v[230:231], s[58:59], v[46:47] op_sel_hi:[1,0,1]
	v_cvt_pk_f32_fp8_e32 v[224:225], v184
	v_cvt_pk_f32_fp8_sdwa v[226:227], v184 src0_sel:WORD_1
	v_cvt_pk_f32_fp8_e32 v[228:229], v185
	v_cvt_pk_f32_fp8_sdwa v[230:231], v185 src0_sel:WORD_1
	v_pk_fma_f32 v[32:33], v[224:225], s[60:61], v[32:33] op_sel_hi:[1,0,1]
	v_pk_fma_f32 v[34:35], v[226:227], s[60:61], v[34:35] op_sel_hi:[1,0,1]
	v_pk_fma_f32 v[36:37], v[228:229], s[60:61], v[36:37] op_sel_hi:[1,0,1]
	v_pk_fma_f32 v[38:39], v[230:231], s[60:61], v[38:39] op_sel_hi:[1,0,1]
	v_cvt_pk_f32_fp8_e32 v[224:225], v186
	v_cvt_pk_f32_fp8_sdwa v[226:227], v186 src0_sel:WORD_1
	v_cvt_pk_f32_fp8_e32 v[228:229], v187
	v_cvt_pk_f32_fp8_sdwa v[230:231], v187 src0_sel:WORD_1
	v_pk_fma_f32 v[40:41], v[224:225], s[60:61], v[40:41] op_sel_hi:[1,0,1]
	v_pk_fma_f32 v[42:43], v[226:227], s[60:61], v[42:43] op_sel_hi:[1,0,1]
	v_pk_fma_f32 v[44:45], v[228:229], s[60:61], v[44:45] op_sel_hi:[1,0,1]
	v_pk_fma_f32 v[46:47], v[230:231], s[60:61], v[46:47] op_sel_hi:[1,0,1]
	v_cvt_pk_f32_fp8_e32 v[224:225], v188
	v_cvt_pk_f32_fp8_sdwa v[226:227], v188 src0_sel:WORD_1
	v_cvt_pk_f32_fp8_e32 v[228:229], v189
	v_cvt_pk_f32_fp8_sdwa v[230:231], v189 src0_sel:WORD_1
	v_pk_fma_f32 v[32:33], v[224:225], s[62:63], v[32:33] op_sel_hi:[1,0,1]
	v_pk_fma_f32 v[34:35], v[226:227], s[62:63], v[34:35] op_sel_hi:[1,0,1]
	v_pk_fma_f32 v[36:37], v[228:229], s[62:63], v[36:37] op_sel_hi:[1,0,1]
	v_pk_fma_f32 v[38:39], v[230:231], s[62:63], v[38:39] op_sel_hi:[1,0,1]
	v_cvt_pk_f32_fp8_e32 v[224:225], v190
	v_cvt_pk_f32_fp8_sdwa v[226:227], v190 src0_sel:WORD_1
	v_cvt_pk_f32_fp8_e32 v[228:229], v191
	v_cvt_pk_f32_fp8_sdwa v[230:231], v191 src0_sel:WORD_1
	v_pk_fma_f32 v[40:41], v[224:225], s[62:63], v[40:41] op_sel_hi:[1,0,1]
	v_pk_fma_f32 v[42:43], v[226:227], s[62:63], v[42:43] op_sel_hi:[1,0,1]
	v_pk_fma_f32 v[44:45], v[228:229], s[62:63], v[44:45] op_sel_hi:[1,0,1]
	v_pk_fma_f32 v[46:47], v[230:231], s[62:63], v[46:47] op_sel_hi:[1,0,1]
	s_branch .LV_s3_tail
.LV_s3_t3:
	v_cvt_pk_f32_fp8_e32 v[224:225], v176
	v_cvt_pk_f32_fp8_sdwa v[226:227], v176 src0_sel:WORD_1
	v_cvt_pk_f32_fp8_e32 v[228:229], v177
	v_cvt_pk_f32_fp8_sdwa v[230:231], v177 src0_sel:WORD_1
	v_pk_fma_f32 v[48:49], v[224:225], s[56:57], v[48:49] op_sel_hi:[1,0,1]
	v_pk_fma_f32 v[50:51], v[226:227], s[56:57], v[50:51] op_sel_hi:[1,0,1]
	v_pk_fma_f32 v[52:53], v[228:229], s[56:57], v[52:53] op_sel_hi:[1,0,1]
	v_pk_fma_f32 v[54:55], v[230:231], s[56:57], v[54:55] op_sel_hi:[1,0,1]
	v_cvt_pk_f32_fp8_e32 v[224:225], v178
	v_cvt_pk_f32_fp8_sdwa v[226:227], v178 src0_sel:WORD_1
	v_cvt_pk_f32_fp8_e32 v[228:229], v179
	v_cvt_pk_f32_fp8_sdwa v[230:231], v179 src0_sel:WORD_1
	v_pk_fma_f32 v[56:57], v[224:225], s[56:57], v[56:57] op_sel_hi:[1,0,1]
	v_pk_fma_f32 v[58:59], v[226:227], s[56:57], v[58:59] op_sel_hi:[1,0,1]
	v_pk_fma_f32 v[60:61], v[228:229], s[56:57], v[60:61] op_sel_hi:[1,0,1]
	v_pk_fma_f32 v[62:63], v[230:231], s[56:57], v[62:63] op_sel_hi:[1,0,1]
	v_cvt_pk_f32_fp8_e32 v[224:225], v180
	v_cvt_pk_f32_fp8_sdwa v[226:227], v180 src0_sel:WORD_1
	v_cvt_pk_f32_fp8_e32 v[228:229], v181
	v_cvt_pk_f32_fp8_sdwa v[230:231], v181 src0_sel:WORD_1
	v_pk_fma_f32 v[48:49], v[224:225], s[58:59], v[48:49] op_sel_hi:[1,0,1]
	v_pk_fma_f32 v[50:51], v[226:227], s[58:59], v[50:51] op_sel_hi:[1,0,1]
	v_pk_fma_f32 v[52:53], v[228:229], s[58:59], v[52:53] op_sel_hi:[1,0,1]
	v_pk_fma_f32 v[54:55], v[230:231], s[58:59], v[54:55] op_sel_hi:[1,0,1]
	v_cvt_pk_f32_fp8_e32 v[224:225], v182
	v_cvt_pk_f32_fp8_sdwa v[226:227], v182 src0_sel:WORD_1
	v_cvt_pk_f32_fp8_e32 v[228:229], v183
	v_cvt_pk_f32_fp8_sdwa v[230:231], v183 src0_sel:WORD_1
	v_pk_fma_f32 v[56:57], v[224:225], s[58:59], v[56:57] op_sel_hi:[1,0,1]
	v_pk_fma_f32 v[58:59], v[226:227], s[58:59], v[58:59] op_sel_hi:[1,0,1]
	v_pk_fma_f32 v[60:61], v[228:229], s[58:59], v[60:61] op_sel_hi:[1,0,1]
	v_pk_fma_f32 v[62:63], v[230:231], s[58:59], v[62:63] op_sel_hi:[1,0,1]
	v_cvt_pk_f32_fp8_e32 v[224:225], v184
	v_cvt_pk_f32_fp8_sdwa v[226:227], v184 src0_sel:WORD_1
	v_cvt_pk_f32_fp8_e32 v[228:229], v185
	v_cvt_pk_f32_fp8_sdwa v[230:231], v185 src0_sel:WORD_1
	v_pk_fma_f32 v[48:49], v[224:225], s[60:61], v[48:49] op_sel_hi:[1,0,1]
	v_pk_fma_f32 v[50:51], v[226:227], s[60:61], v[50:51] op_sel_hi:[1,0,1]
	v_pk_fma_f32 v[52:53], v[228:229], s[60:61], v[52:53] op_sel_hi:[1,0,1]
	v_pk_fma_f32 v[54:55], v[230:231], s[60:61], v[54:55] op_sel_hi:[1,0,1]
	v_cvt_pk_f32_fp8_e32 v[224:225], v186
	v_cvt_pk_f32_fp8_sdwa v[226:227], v186 src0_sel:WORD_1
	v_cvt_pk_f32_fp8_e32 v[228:229], v187
	v_cvt_pk_f32_fp8_sdwa v[230:231], v187 src0_sel:WORD_1
	v_pk_fma_f32 v[56:57], v[224:225], s[60:61], v[56:57] op_sel_hi:[1,0,1]
	v_pk_fma_f32 v[58:59], v[226:227], s[60:61], v[58:59] op_sel_hi:[1,0,1]
	v_pk_fma_f32 v[60:61], v[228:229], s[60:61], v[60:61] op_sel_hi:[1,0,1]
	v_pk_fma_f32 v[62:63], v[230:231], s[60:61], v[62:63] op_sel_hi:[1,0,1]
	v_cvt_pk_f32_fp8_e32 v[224:225], v188
	v_cvt_pk_f32_fp8_sdwa v[226:227], v188 src0_sel:WORD_1
	v_cvt_pk_f32_fp8_e32 v[228:229], v189
	v_cvt_pk_f32_fp8_sdwa v[230:231], v189 src0_sel:WORD_1
	v_pk_fma_f32 v[48:49], v[224:225], s[62:63], v[48:49] op_sel_hi:[1,0,1]
	v_pk_fma_f32 v[50:51], v[226:227], s[62:63], v[50:51] op_sel_hi:[1,0,1]
	v_pk_fma_f32 v[52:53], v[228:229], s[62:63], v[52:53] op_sel_hi:[1,0,1]
	v_pk_fma_f32 v[54:55], v[230:231], s[62:63], v[54:55] op_sel_hi:[1,0,1]
	v_cvt_pk_f32_fp8_e32 v[224:225], v190
	v_cvt_pk_f32_fp8_sdwa v[226:227], v190 src0_sel:WORD_1
	v_cvt_pk_f32_fp8_e32 v[228:229], v191
	v_cvt_pk_f32_fp8_sdwa v[230:231], v191 src0_sel:WORD_1
	v_pk_fma_f32 v[56:57], v[224:225], s[62:63], v[56:57] op_sel_hi:[1,0,1]
	v_pk_fma_f32 v[58:59], v[226:227], s[62:63], v[58:59] op_sel_hi:[1,0,1]
	v_pk_fma_f32 v[60:61], v[228:229], s[62:63], v[60:61] op_sel_hi:[1,0,1]
	v_pk_fma_f32 v[62:63], v[230:231], s[62:63], v[62:63] op_sel_hi:[1,0,1]
	s_branch .LV_s3_tail
.LV_s3_t4:
	v_cvt_pk_f32_fp8_e32 v[224:225], v176
	v_cvt_pk_f32_fp8_sdwa v[226:227], v176 src0_sel:WORD_1
	v_cvt_pk_f32_fp8_e32 v[228:229], v177
	v_cvt_pk_f32_fp8_sdwa v[230:231], v177 src0_sel:WORD_1
	v_pk_fma_f32 v[64:65], v[224:225], s[56:57], v[64:65] op_sel_hi:[1,0,1]
	v_pk_fma_f32 v[66:67], v[226:227], s[56:57], v[66:67] op_sel_hi:[1,0,1]
	v_pk_fma_f32 v[68:69], v[228:229], s[56:57], v[68:69] op_sel_hi:[1,0,1]
	v_pk_fma_f32 v[70:71], v[230:231], s[56:57], v[70:71] op_sel_hi:[1,0,1]
	v_cvt_pk_f32_fp8_e32 v[224:225], v178
	v_cvt_pk_f32_fp8_sdwa v[226:227], v178 src0_sel:WORD_1
	v_cvt_pk_f32_fp8_e32 v[228:229], v179
	v_cvt_pk_f32_fp8_sdwa v[230:231], v179 src0_sel:WORD_1
	v_pk_fma_f32 v[72:73], v[224:225], s[56:57], v[72:73] op_sel_hi:[1,0,1]
	v_pk_fma_f32 v[74:75], v[226:227], s[56:57], v[74:75] op_sel_hi:[1,0,1]
	v_pk_fma_f32 v[76:77], v[228:229], s[56:57], v[76:77] op_sel_hi:[1,0,1]
	v_pk_fma_f32 v[78:79], v[230:231], s[56:57], v[78:79] op_sel_hi:[1,0,1]
	v_cvt_pk_f32_fp8_e32 v[224:225], v180
	v_cvt_pk_f32_fp8_sdwa v[226:227], v180 src0_sel:WORD_1
	v_cvt_pk_f32_fp8_e32 v[228:229], v181
	v_cvt_pk_f32_fp8_sdwa v[230:231], v181 src0_sel:WORD_1
	v_pk_fma_f32 v[64:65], v[224:225], s[58:59], v[64:65] op_sel_hi:[1,0,1]
	v_pk_fma_f32 v[66:67], v[226:227], s[58:59], v[66:67] op_sel_hi:[1,0,1]
	v_pk_fma_f32 v[68:69], v[228:229], s[58:59], v[68:69] op_sel_hi:[1,0,1]
	v_pk_fma_f32 v[70:71], v[230:231], s[58:59], v[70:71] op_sel_hi:[1,0,1]
	v_cvt_pk_f32_fp8_e32 v[224:225], v182
	v_cvt_pk_f32_fp8_sdwa v[226:227], v182 src0_sel:WORD_1
	v_cvt_pk_f32_fp8_e32 v[228:229], v183
	v_cvt_pk_f32_fp8_sdwa v[230:231], v183 src0_sel:WORD_1
	v_pk_fma_f32 v[72:73], v[224:225], s[58:59], v[72:73] op_sel_hi:[1,0,1]
	v_pk_fma_f32 v[74:75], v[226:227], s[58:59], v[74:75] op_sel_hi:[1,0,1]
	v_pk_fma_f32 v[76:77], v[228:229], s[58:59], v[76:77] op_sel_hi:[1,0,1]
	v_pk_fma_f32 v[78:79], v[230:231], s[58:59], v[78:79] op_sel_hi:[1,0,1]
	v_cvt_pk_f32_fp8_e32 v[224:225], v184
	v_cvt_pk_f32_fp8_sdwa v[226:227], v184 src0_sel:WORD_1
	v_cvt_pk_f32_fp8_e32 v[228:229], v185
	v_cvt_pk_f32_fp8_sdwa v[230:231], v185 src0_sel:WORD_1
	v_pk_fma_f32 v[64:65], v[224:225], s[60:61], v[64:65] op_sel_hi:[1,0,1]
	v_pk_fma_f32 v[66:67], v[226:227], s[60:61], v[66:67] op_sel_hi:[1,0,1]
	v_pk_fma_f32 v[68:69], v[228:229], s[60:61], v[68:69] op_sel_hi:[1,0,1]
	v_pk_fma_f32 v[70:71], v[230:231], s[60:61], v[70:71] op_sel_hi:[1,0,1]
	v_cvt_pk_f32_fp8_e32 v[224:225], v186
	v_cvt_pk_f32_fp8_sdwa v[226:227], v186 src0_sel:WORD_1
	v_cvt_pk_f32_fp8_e32 v[228:229], v187
	v_cvt_pk_f32_fp8_sdwa v[230:231], v187 src0_sel:WORD_1
	v_pk_fma_f32 v[72:73], v[224:225], s[60:61], v[72:73] op_sel_hi:[1,0,1]
	v_pk_fma_f32 v[74:75], v[226:227], s[60:61], v[74:75] op_sel_hi:[1,0,1]
	v_pk_fma_f32 v[76:77], v[228:229], s[60:61], v[76:77] op_sel_hi:[1,0,1]
	v_pk_fma_f32 v[78:79], v[230:231], s[60:61], v[78:79] op_sel_hi:[1,0,1]
	v_cvt_pk_f32_fp8_e32 v[224:225], v188
	v_cvt_pk_f32_fp8_sdwa v[226:227], v188 src0_sel:WORD_1
	v_cvt_pk_f32_fp8_e32 v[228:229], v189
	v_cvt_pk_f32_fp8_sdwa v[230:231], v189 src0_sel:WORD_1
	v_pk_fma_f32 v[64:65], v[224:225], s[62:63], v[64:65] op_sel_hi:[1,0,1]
	v_pk_fma_f32 v[66:67], v[226:227], s[62:63], v[66:67] op_sel_hi:[1,0,1]
	v_pk_fma_f32 v[68:69], v[228:229], s[62:63], v[68:69] op_sel_hi:[1,0,1]
	v_pk_fma_f32 v[70:71], v[230:231], s[62:63], v[70:71] op_sel_hi:[1,0,1]
	v_cvt_pk_f32_fp8_e32 v[224:225], v190
	v_cvt_pk_f32_fp8_sdwa v[226:227], v190 src0_sel:WORD_1
	v_cvt_pk_f32_fp8_e32 v[228:229], v191
	v_cvt_pk_f32_fp8_sdwa v[230:231], v191 src0_sel:WORD_1
	v_pk_fma_f32 v[72:73], v[224:225], s[62:63], v[72:73] op_sel_hi:[1,0,1]
	v_pk_fma_f32 v[74:75], v[226:227], s[62:63], v[74:75] op_sel_hi:[1,0,1]
	v_pk_fma_f32 v[76:77], v[228:229], s[62:63], v[76:77] op_sel_hi:[1,0,1]
	v_pk_fma_f32 v[78:79], v[230:231], s[62:63], v[78:79] op_sel_hi:[1,0,1]
	s_branch .LV_s3_tail
.LV_s3_t5:
	v_cvt_pk_f32_fp8_e32 v[224:225], v176
	v_cvt_pk_f32_fp8_sdwa v[226:227], v176 src0_sel:WORD_1
	v_cvt_pk_f32_fp8_e32 v[228:229], v177
	v_cvt_pk_f32_fp8_sdwa v[230:231], v177 src0_sel:WORD_1
	v_pk_fma_f32 v[80:81], v[224:225], s[56:57], v[80:81] op_sel_hi:[1,0,1]
	v_pk_fma_f32 v[82:83], v[226:227], s[56:57], v[82:83] op_sel_hi:[1,0,1]
	v_pk_fma_f32 v[84:85], v[228:229], s[56:57], v[84:85] op_sel_hi:[1,0,1]
	v_pk_fma_f32 v[86:87], v[230:231], s[56:57], v[86:87] op_sel_hi:[1,0,1]
	v_cvt_pk_f32_fp8_e32 v[224:225], v178
	v_cvt_pk_f32_fp8_sdwa v[226:227], v178 src0_sel:WORD_1
	v_cvt_pk_f32_fp8_e32 v[228:229], v179
	v_cvt_pk_f32_fp8_sdwa v[230:231], v179 src0_sel:WORD_1
	v_pk_fma_f32 v[88:89], v[224:225], s[56:57], v[88:89] op_sel_hi:[1,0,1]
	v_pk_fma_f32 v[90:91], v[226:227], s[56:57], v[90:91] op_sel_hi:[1,0,1]
	v_pk_fma_f32 v[92:93], v[228:229], s[56:57], v[92:93] op_sel_hi:[1,0,1]
	v_pk_fma_f32 v[94:95], v[230:231], s[56:57], v[94:95] op_sel_hi:[1,0,1]
	v_cvt_pk_f32_fp8_e32 v[224:225], v180
	v_cvt_pk_f32_fp8_sdwa v[226:227], v180 src0_sel:WORD_1
	v_cvt_pk_f32_fp8_e32 v[228:229], v181
	v_cvt_pk_f32_fp8_sdwa v[230:231], v181 src0_sel:WORD_1
	v_pk_fma_f32 v[80:81], v[224:225], s[58:59], v[80:81] op_sel_hi:[1,0,1]
	v_pk_fma_f32 v[82:83], v[226:227], s[58:59], v[82:83] op_sel_hi:[1,0,1]
	v_pk_fma_f32 v[84:85], v[228:229], s[58:59], v[84:85] op_sel_hi:[1,0,1]
	v_pk_fma_f32 v[86:87], v[230:231], s[58:59], v[86:87] op_sel_hi:[1,0,1]
	v_cvt_pk_f32_fp8_e32 v[224:225], v182
	v_cvt_pk_f32_fp8_sdwa v[226:227], v182 src0_sel:WORD_1
	v_cvt_pk_f32_fp8_e32 v[228:229], v183
	v_cvt_pk_f32_fp8_sdwa v[230:231], v183 src0_sel:WORD_1
	v_pk_fma_f32 v[88:89], v[224:225], s[58:59], v[88:89] op_sel_hi:[1,0,1]
	v_pk_fma_f32 v[90:91], v[226:227], s[58:59], v[90:91] op_sel_hi:[1,0,1]
	v_pk_fma_f32 v[92:93], v[228:229], s[58:59], v[92:93] op_sel_hi:[1,0,1]
	v_pk_fma_f32 v[94:95], v[230:231], s[58:59], v[94:95] op_sel_hi:[1,0,1]
	v_cvt_pk_f32_fp8_e32 v[224:225], v184
	v_cvt_pk_f32_fp8_sdwa v[226:227], v184 src0_sel:WORD_1
	v_cvt_pk_f32_fp8_e32 v[228:229], v185
	v_cvt_pk_f32_fp8_sdwa v[230:231], v185 src0_sel:WORD_1
	v_pk_fma_f32 v[80:81], v[224:225], s[60:61], v[80:81] op_sel_hi:[1,0,1]
	v_pk_fma_f32 v[82:83], v[226:227], s[60:61], v[82:83] op_sel_hi:[1,0,1]
	v_pk_fma_f32 v[84:85], v[228:229], s[60:61], v[84:85] op_sel_hi:[1,0,1]
	v_pk_fma_f32 v[86:87], v[230:231], s[60:61], v[86:87] op_sel_hi:[1,0,1]
	v_cvt_pk_f32_fp8_e32 v[224:225], v186
	v_cvt_pk_f32_fp8_sdwa v[226:227], v186 src0_sel:WORD_1
	v_cvt_pk_f32_fp8_e32 v[228:229], v187
	v_cvt_pk_f32_fp8_sdwa v[230:231], v187 src0_sel:WORD_1
	v_pk_fma_f32 v[88:89], v[224:225], s[60:61], v[88:89] op_sel_hi:[1,0,1]
	v_pk_fma_f32 v[90:91], v[226:227], s[60:61], v[90:91] op_sel_hi:[1,0,1]
	v_pk_fma_f32 v[92:93], v[228:229], s[60:61], v[92:93] op_sel_hi:[1,0,1]
	v_pk_fma_f32 v[94:95], v[230:231], s[60:61], v[94:95] op_sel_hi:[1,0,1]
	v_cvt_pk_f32_fp8_e32 v[224:225], v188
	v_cvt_pk_f32_fp8_sdwa v[226:227], v188 src0_sel:WORD_1
	v_cvt_pk_f32_fp8_e32 v[228:229], v189
	v_cvt_pk_f32_fp8_sdwa v[230:231], v189 src0_sel:WORD_1
	v_pk_fma_f32 v[80:81], v[224:225], s[62:63], v[80:81] op_sel_hi:[1,0,1]
	v_pk_fma_f32 v[82:83], v[226:227], s[62:63], v[82:83] op_sel_hi:[1,0,1]
	v_pk_fma_f32 v[84:85], v[228:229], s[62:63], v[84:85] op_sel_hi:[1,0,1]
	v_pk_fma_f32 v[86:87], v[230:231], s[62:63], v[86:87] op_sel_hi:[1,0,1]
	v_cvt_pk_f32_fp8_e32 v[224:225], v190
	v_cvt_pk_f32_fp8_sdwa v[226:227], v190 src0_sel:WORD_1
	v_cvt_pk_f32_fp8_e32 v[228:229], v191
	v_cvt_pk_f32_fp8_sdwa v[230:231], v191 src0_sel:WORD_1
	v_pk_fma_f32 v[88:89], v[224:225], s[62:63], v[88:89] op_sel_hi:[1,0,1]
	v_pk_fma_f32 v[90:91], v[226:227], s[62:63], v[90:91] op_sel_hi:[1,0,1]
	v_pk_fma_f32 v[92:93], v[228:229], s[62:63], v[92:93] op_sel_hi:[1,0,1]
	v_pk_fma_f32 v[94:95], v[230:231], s[62:63], v[94:95] op_sel_hi:[1,0,1]
	s_branch .LV_s3_tail
.LV_s3_t6:
	v_cvt_pk_f32_fp8_e32 v[224:225], v176
	v_cvt_pk_f32_fp8_sdwa v[226:227], v176 src0_sel:WORD_1
	v_cvt_pk_f32_fp8_e32 v[228:229], v177
	v_cvt_pk_f32_fp8_sdwa v[230:231], v177 src0_sel:WORD_1
	v_pk_fma_f32 v[96:97], v[224:225], s[56:57], v[96:97] op_sel_hi:[1,0,1]
	v_pk_fma_f32 v[98:99], v[226:227], s[56:57], v[98:99] op_sel_hi:[1,0,1]
	v_pk_fma_f32 v[100:101], v[228:229], s[56:57], v[100:101] op_sel_hi:[1,0,1]
	v_pk_fma_f32 v[102:103], v[230:231], s[56:57], v[102:103] op_sel_hi:[1,0,1]
	v_cvt_pk_f32_fp8_e32 v[224:225], v178
	v_cvt_pk_f32_fp8_sdwa v[226:227], v178 src0_sel:WORD_1
	v_cvt_pk_f32_fp8_e32 v[228:229], v179
	v_cvt_pk_f32_fp8_sdwa v[230:231], v179 src0_sel:WORD_1
	v_pk_fma_f32 v[104:105], v[224:225], s[56:57], v[104:105] op_sel_hi:[1,0,1]
	v_pk_fma_f32 v[106:107], v[226:227], s[56:57], v[106:107] op_sel_hi:[1,0,1]
	v_pk_fma_f32 v[108:109], v[228:229], s[56:57], v[108:109] op_sel_hi:[1,0,1]
	v_pk_fma_f32 v[110:111], v[230:231], s[56:57], v[110:111] op_sel_hi:[1,0,1]
	v_cvt_pk_f32_fp8_e32 v[224:225], v180
	v_cvt_pk_f32_fp8_sdwa v[226:227], v180 src0_sel:WORD_1
	v_cvt_pk_f32_fp8_e32 v[228:229], v181
	v_cvt_pk_f32_fp8_sdwa v[230:231], v181 src0_sel:WORD_1
	v_pk_fma_f32 v[96:97], v[224:225], s[58:59], v[96:97] op_sel_hi:[1,0,1]
	v_pk_fma_f32 v[98:99], v[226:227], s[58:59], v[98:99] op_sel_hi:[1,0,1]
	v_pk_fma_f32 v[100:101], v[228:229], s[58:59], v[100:101] op_sel_hi:[1,0,1]
	v_pk_fma_f32 v[102:103], v[230:231], s[58:59], v[102:103] op_sel_hi:[1,0,1]
	v_cvt_pk_f32_fp8_e32 v[224:225], v182
	v_cvt_pk_f32_fp8_sdwa v[226:227], v182 src0_sel:WORD_1
	v_cvt_pk_f32_fp8_e32 v[228:229], v183
	v_cvt_pk_f32_fp8_sdwa v[230:231], v183 src0_sel:WORD_1
	v_pk_fma_f32 v[104:105], v[224:225], s[58:59], v[104:105] op_sel_hi:[1,0,1]
	v_pk_fma_f32 v[106:107], v[226:227], s[58:59], v[106:107] op_sel_hi:[1,0,1]
	v_pk_fma_f32 v[108:109], v[228:229], s[58:59], v[108:109] op_sel_hi:[1,0,1]
	v_pk_fma_f32 v[110:111], v[230:231], s[58:59], v[110:111] op_sel_hi:[1,0,1]
	v_cvt_pk_f32_fp8_e32 v[224:225], v184
	v_cvt_pk_f32_fp8_sdwa v[226:227], v184 src0_sel:WORD_1
	v_cvt_pk_f32_fp8_e32 v[228:229], v185
	v_cvt_pk_f32_fp8_sdwa v[230:231], v185 src0_sel:WORD_1
	v_pk_fma_f32 v[96:97], v[224:225], s[60:61], v[96:97] op_sel_hi:[1,0,1]
	v_pk_fma_f32 v[98:99], v[226:227], s[60:61], v[98:99] op_sel_hi:[1,0,1]
	v_pk_fma_f32 v[100:101], v[228:229], s[60:61], v[100:101] op_sel_hi:[1,0,1]
	v_pk_fma_f32 v[102:103], v[230:231], s[60:61], v[102:103] op_sel_hi:[1,0,1]
	v_cvt_pk_f32_fp8_e32 v[224:225], v186
	v_cvt_pk_f32_fp8_sdwa v[226:227], v186 src0_sel:WORD_1
	v_cvt_pk_f32_fp8_e32 v[228:229], v187
	v_cvt_pk_f32_fp8_sdwa v[230:231], v187 src0_sel:WORD_1
	v_pk_fma_f32 v[104:105], v[224:225], s[60:61], v[104:105] op_sel_hi:[1,0,1]
	v_pk_fma_f32 v[106:107], v[226:227], s[60:61], v[106:107] op_sel_hi:[1,0,1]
	v_pk_fma_f32 v[108:109], v[228:229], s[60:61], v[108:109] op_sel_hi:[1,0,1]
	v_pk_fma_f32 v[110:111], v[230:231], s[60:61], v[110:111] op_sel_hi:[1,0,1]
	v_cvt_pk_f32_fp8_e32 v[224:225], v188
	v_cvt_pk_f32_fp8_sdwa v[226:227], v188 src0_sel:WORD_1
	v_cvt_pk_f32_fp8_e32 v[228:229], v189
	v_cvt_pk_f32_fp8_sdwa v[230:231], v189 src0_sel:WORD_1
	v_pk_fma_f32 v[96:97], v[224:225], s[62:63], v[96:97] op_sel_hi:[1,0,1]
	v_pk_fma_f32 v[98:99], v[226:227], s[62:63], v[98:99] op_sel_hi:[1,0,1]
	v_pk_fma_f32 v[100:101], v[228:229], s[62:63], v[100:101] op_sel_hi:[1,0,1]
	v_pk_fma_f32 v[102:103], v[230:231], s[62:63], v[102:103] op_sel_hi:[1,0,1]
	v_cvt_pk_f32_fp8_e32 v[224:225], v190
	v_cvt_pk_f32_fp8_sdwa v[226:227], v190 src0_sel:WORD_1
	v_cvt_pk_f32_fp8_e32 v[228:229], v191
	v_cvt_pk_f32_fp8_sdwa v[230:231], v191 src0_sel:WORD_1
	v_pk_fma_f32 v[104:105], v[224:225], s[62:63], v[104:105] op_sel_hi:[1,0,1]
	v_pk_fma_f32 v[106:107], v[226:227], s[62:63], v[106:107] op_sel_hi:[1,0,1]
	v_pk_fma_f32 v[108:109], v[228:229], s[62:63], v[108:109] op_sel_hi:[1,0,1]
	v_pk_fma_f32 v[110:111], v[230:231], s[62:63], v[110:111] op_sel_hi:[1,0,1]
	s_branch .LV_s3_tail
.LV_s3_t7:
	v_cvt_pk_f32_fp8_e32 v[224:225], v176
	v_cvt_pk_f32_fp8_sdwa v[226:227], v176 src0_sel:WORD_1
	v_cvt_pk_f32_fp8_e32 v[228:229], v177
	v_cvt_pk_f32_fp8_sdwa v[230:231], v177 src0_sel:WORD_1
	v_pk_fma_f32 v[112:113], v[224:225], s[56:57], v[112:113] op_sel_hi:[1,0,1]
	v_pk_fma_f32 v[114:115], v[226:227], s[56:57], v[114:115] op_sel_hi:[1,0,1]
	v_pk_fma_f32 v[116:117], v[228:229], s[56:57], v[116:117] op_sel_hi:[1,0,1]
	v_pk_fma_f32 v[118:119], v[230:231], s[56:57], v[118:119] op_sel_hi:[1,0,1]
	v_cvt_pk_f32_fp8_e32 v[224:225], v178
	v_cvt_pk_f32_fp8_sdwa v[226:227], v178 src0_sel:WORD_1
	v_cvt_pk_f32_fp8_e32 v[228:229], v179
	v_cvt_pk_f32_fp8_sdwa v[230:231], v179 src0_sel:WORD_1
	v_pk_fma_f32 v[120:121], v[224:225], s[56:57], v[120:121] op_sel_hi:[1,0,1]
	v_pk_fma_f32 v[122:123], v[226:227], s[56:57], v[122:123] op_sel_hi:[1,0,1]
	v_pk_fma_f32 v[124:125], v[228:229], s[56:57], v[124:125] op_sel_hi:[1,0,1]
	v_pk_fma_f32 v[126:127], v[230:231], s[56:57], v[126:127] op_sel_hi:[1,0,1]
	v_cvt_pk_f32_fp8_e32 v[224:225], v180
	v_cvt_pk_f32_fp8_sdwa v[226:227], v180 src0_sel:WORD_1
	v_cvt_pk_f32_fp8_e32 v[228:229], v181
	v_cvt_pk_f32_fp8_sdwa v[230:231], v181 src0_sel:WORD_1
	v_pk_fma_f32 v[112:113], v[224:225], s[58:59], v[112:113] op_sel_hi:[1,0,1]
	v_pk_fma_f32 v[114:115], v[226:227], s[58:59], v[114:115] op_sel_hi:[1,0,1]
	v_pk_fma_f32 v[116:117], v[228:229], s[58:59], v[116:117] op_sel_hi:[1,0,1]
	v_pk_fma_f32 v[118:119], v[230:231], s[58:59], v[118:119] op_sel_hi:[1,0,1]
	v_cvt_pk_f32_fp8_e32 v[224:225], v182
	v_cvt_pk_f32_fp8_sdwa v[226:227], v182 src0_sel:WORD_1
	v_cvt_pk_f32_fp8_e32 v[228:229], v183
	v_cvt_pk_f32_fp8_sdwa v[230:231], v183 src0_sel:WORD_1
	v_pk_fma_f32 v[120:121], v[224:225], s[58:59], v[120:121] op_sel_hi:[1,0,1]
	v_pk_fma_f32 v[122:123], v[226:227], s[58:59], v[122:123] op_sel_hi:[1,0,1]
	v_pk_fma_f32 v[124:125], v[228:229], s[58:59], v[124:125] op_sel_hi:[1,0,1]
	v_pk_fma_f32 v[126:127], v[230:231], s[58:59], v[126:127] op_sel_hi:[1,0,1]
	v_cvt_pk_f32_fp8_e32 v[224:225], v184
	v_cvt_pk_f32_fp8_sdwa v[226:227], v184 src0_sel:WORD_1
	v_cvt_pk_f32_fp8_e32 v[228:229], v185
	v_cvt_pk_f32_fp8_sdwa v[230:231], v185 src0_sel:WORD_1
	v_pk_fma_f32 v[112:113], v[224:225], s[60:61], v[112:113] op_sel_hi:[1,0,1]
	v_pk_fma_f32 v[114:115], v[226:227], s[60:61], v[114:115] op_sel_hi:[1,0,1]
	v_pk_fma_f32 v[116:117], v[228:229], s[60:61], v[116:117] op_sel_hi:[1,0,1]
	v_pk_fma_f32 v[118:119], v[230:231], s[60:61], v[118:119] op_sel_hi:[1,0,1]
	v_cvt_pk_f32_fp8_e32 v[224:225], v186
	v_cvt_pk_f32_fp8_sdwa v[226:227], v186 src0_sel:WORD_1
	v_cvt_pk_f32_fp8_e32 v[228:229], v187
	v_cvt_pk_f32_fp8_sdwa v[230:231], v187 src0_sel:WORD_1
	v_pk_fma_f32 v[120:121], v[224:225], s[60:61], v[120:121] op_sel_hi:[1,0,1]
	v_pk_fma_f32 v[122:123], v[226:227], s[60:61], v[122:123] op_sel_hi:[1,0,1]
	v_pk_fma_f32 v[124:125], v[228:229], s[60:61], v[124:125] op_sel_hi:[1,0,1]
	v_pk_fma_f32 v[126:127], v[230:231], s[60:61], v[126:127] op_sel_hi:[1,0,1]
	v_cvt_pk_f32_fp8_e32 v[224:225], v188
	v_cvt_pk_f32_fp8_sdwa v[226:227], v188 src0_sel:WORD_1
	v_cvt_pk_f32_fp8_e32 v[228:229], v189
	v_cvt_pk_f32_fp8_sdwa v[230:231], v189 src0_sel:WORD_1
	v_pk_fma_f32 v[112:113], v[224:225], s[62:63], v[112:113] op_sel_hi:[1,0,1]
	v_pk_fma_f32 v[114:115], v[226:227], s[62:63], v[114:115] op_sel_hi:[1,0,1]
	v_pk_fma_f32 v[116:117], v[228:229], s[62:63], v[116:117] op_sel_hi:[1,0,1]
	v_pk_fma_f32 v[118:119], v[230:231], s[62:63], v[118:119] op_sel_hi:[1,0,1]
	v_cvt_pk_f32_fp8_e32 v[224:225], v190
	v_cvt_pk_f32_fp8_sdwa v[226:227], v190 src0_sel:WORD_1
	v_cvt_pk_f32_fp8_e32 v[228:229], v191
	v_cvt_pk_f32_fp8_sdwa v[230:231], v191 src0_sel:WORD_1
	v_pk_fma_f32 v[120:121], v[224:225], s[62:63], v[120:121] op_sel_hi:[1,0,1]
	v_pk_fma_f32 v[122:123], v[226:227], s[62:63], v[122:123] op_sel_hi:[1,0,1]
	v_pk_fma_f32 v[124:125], v[228:229], s[62:63], v[124:125] op_sel_hi:[1,0,1]
	v_pk_fma_f32 v[126:127], v[230:231], s[62:63], v[126:127] op_sel_hi:[1,0,1]
.LV_s3_tail:
	ds_read_b128 v[236:239], v241 offset:256
	ds_read_b128 v[232:235], v241 offset:512
	s_add_i32 s21, s21, 1
.LV_s4:
	s_cmp_ge_u32 s21, s20
	s_cbranch_scc1 .LV_done
	s_waitcnt lgkmcnt(0)
	v_readlane_b32 s64, v232, 0
	v_readlane_b32 s65, v232, 16
	v_readlane_b32 s66, v232, 32
	v_readlane_b32 s67, v232, 48
	s_add_u32 s24, s6, s64
	s_addc_u32 s25, s7, 0
	s_add_u32 s26, s6, s65
	s_addc_u32 s27, s7, 0
	s_add_u32 s28, s6, s66
	s_addc_u32 s29, s7, 0
	s_add_u32 s30, s6, s67
	s_addc_u32 s31, s7, 0
	global_load_dwordx4 v[176:179], v240, s[24:25]
	global_load_dwordx4 v[180:183], v240, s[26:27]
	global_load_dwordx4 v[184:187], v240, s[28:29]
	global_load_dwordx4 v[188:191], v240, s[30:31]
	v_readfirstlane_b32 s23, v238
	v_readlane_b32 s56, v237, 0
	v_readlane_b32 s58, v237, 16
	v_readlane_b32 s60, v237, 32
	v_readlane_b32 s62, v237, 48
	s_and_b32 s23, s23, 7
	s_waitcnt vmcnt(16)
	s_cmp_ge_u32 s23, 4
	s_cbranch_scc1 .LV_s4_h
	s_cmp_ge_u32 s23, 2
	s_cbranch_scc1 .LV_s4_23
	s_cmp_eq_u32 s23, 0
	s_cbranch_scc1 .LV_s4_t0
	s_branch .LV_s4_t1

.LV_s4_t0:
	v_cvt_pk_f32_fp8_e32 v[224:225], v192
	v_cvt_pk_f32_fp8_sdwa v[226:227], v192 src0_sel:WORD_1
	v_cvt_pk_f32_fp8_e32 v[228:229], v193
	v_cvt_pk_f32_fp8_sdwa v[230:231], v193 src0_sel:WORD_1
	v_pk_fma_f32 v[0:1], v[224:225], s[56:57], v[0:1] op_sel_hi:[1,0,1]
	v_pk_fma_f32 v[2:3], v[226:227], s[56:57], v[2:3] op_sel_hi:[1,0,1]
	v_pk_fma_f32 v[4:5], v[228:229], s[56:57], v[4:5] op_sel_hi:[1,0,1]
	v_pk_fma_f32 v[6:7], v[230:231], s[56:57], v[6:7] op_sel_hi:[1,0,1]
	v_cvt_pk_f32_fp8_e32 v[224:225], v194
	v_cvt_pk_f32_fp8_sdwa v[226:227], v194 src0_sel:WORD_1
	v_cvt_pk_f32_fp8_e32 v[228:229], v195
	v_cvt_pk_f32_fp8_sdwa v[230:231], v195 src0_sel:WORD_1
	v_pk_fma_f32 v[8:9], v[224:225], s[56:57], v[8:9] op_sel_hi:[1,0,1]
	v_pk_fma_f32 v[10:11], v[226:227], s[56:57], v[10:11] op_sel_hi:[1,0,1]
	v_pk_fma_f32 v[12:13], v[228:229], s[56:57], v[12:13] op_sel_hi:[1,0,1]
	v_pk_fma_f32 v[14:15], v[230:231], s[56:57], v[14:15] op_sel_hi:[1,0,1]
	v_cvt_pk_f32_fp8_e32 v[224:225], v196
	v_cvt_pk_f32_fp8_sdwa v[226:227], v196 src0_sel:WORD_1
	v_cvt_pk_f32_fp8_e32 v[228:229], v197
	v_cvt_pk_f32_fp8_sdwa v[230:231], v197 src0_sel:WORD_1
	v_pk_fma_f32 v[0:1], v[224:225], s[58:59], v[0:1] op_sel_hi:[1,0,1]
	v_pk_fma_f32 v[2:3], v[226:227], s[58:59], v[2:3] op_sel_hi:[1,0,1]
	v_pk_fma_f32 v[4:5], v[228:229], s[58:59], v[4:5] op_sel_hi:[1,0,1]
	v_pk_fma_f32 v[6:7], v[230:231], s[58:59], v[6:7] op_sel_hi:[1,0,1]
	v_cvt_pk_f32_fp8_e32 v[224:225], v198
	v_cvt_pk_f32_fp8_sdwa v[226:227], v198 src0_sel:WORD_1
	v_cvt_pk_f32_fp8_e32 v[228:229], v199
	v_cvt_pk_f32_fp8_sdwa v[230:231], v199 src0_sel:WORD_1
	v_pk_fma_f32 v[8:9], v[224:225], s[58:59], v[8:9] op_sel_hi:[1,0,1]
	v_pk_fma_f32 v[10:11], v[226:227], s[58:59], v[10:11] op_sel_hi:[1,0,1]
	v_pk_fma_f32 v[12:13], v[228:229], s[58:59], v[12:13] op_sel_hi:[1,0,1]
	v_pk_fma_f32 v[14:15], v[230:231], s[58:59], v[14:15] op_sel_hi:[1,0,1]
	v_cvt_pk_f32_fp8_e32 v[224:225], v200
	v_cvt_pk_f32_fp8_sdwa v[226:227], v200 src0_sel:WORD_1
	v_cvt_pk_f32_fp8_e32 v[228:229], v201
	v_cvt_pk_f32_fp8_sdwa v[230:231], v201 src0_sel:WORD_1
	v_pk_fma_f32 v[0:1], v[224:225], s[60:61], v[0:1] op_sel_hi:[1,0,1]
	v_pk_fma_f32 v[2:3], v[226:227], s[60:61], v[2:3] op_sel_hi:[1,0,1]
	v_pk_fma_f32 v[4:5], v[228:229], s[60:61], v[4:5] op_sel_hi:[1,0,1]
	v_pk_fma_f32 v[6:7], v[230:231], s[60:61], v[6:7] op_sel_hi:[1,0,1]
	v_cvt_pk_f32_fp8_e32 v[224:225], v202
	v_cvt_pk_f32_fp8_sdwa v[226:227], v202 src0_sel:WORD_1
	v_cvt_pk_f32_fp8_e32 v[228:229], v203
	v_cvt_pk_f32_fp8_sdwa v[230:231], v203 src0_sel:WORD_1
	v_pk_fma_f32 v[8:9], v[224:225], s[60:61], v[8:9] op_sel_hi:[1,0,1]
	v_pk_fma_f32 v[10:11], v[226:227], s[60:61], v[10:11] op_sel_hi:[1,0,1]
	v_pk_fma_f32 v[12:13], v[228:229], s[60:61], v[12:13] op_sel_hi:[1,0,1]
	v_pk_fma_f32 v[14:15], v[230:231], s[60:61], v[14:15] op_sel_hi:[1,0,1]
	v_cvt_pk_f32_fp8_e32 v[224:225], v204
	v_cvt_pk_f32_fp8_sdwa v[226:227], v204 src0_sel:WORD_1
	v_cvt_pk_f32_fp8_e32 v[228:229], v205
	v_cvt_pk_f32_fp8_sdwa v[230:231], v205 src0_sel:WORD_1
	v_pk_fma_f32 v[0:1], v[224:225], s[62:63], v[0:1] op_sel_hi:[1,0,1]
	v_pk_fma_f32 v[2:3], v[226:227], s[62:63], v[2:3] op_sel_hi:[1,0,1]
	v_pk_fma_f32 v[4:5], v[228:229], s[62:63], v[4:5] op_sel_hi:[1,0,1]
	v_pk_fma_f32 v[6:7], v[230:231], s[62:63], v[6:7] op_sel_hi:[1,0,1]
	v_cvt_pk_f32_fp8_e32 v[224:225], v206
	v_cvt_pk_f32_fp8_sdwa v[226:227], v206 src0_sel:WORD_1
	v_cvt_pk_f32_fp8_e32 v[228:229], v207
	v_cvt_pk_f32_fp8_sdwa v[230:231], v207 src0_sel:WORD_1
	v_pk_fma_f32 v[8:9], v[224:225], s[62:63], v[8:9] op_sel_hi:[1,0,1]
	v_pk_fma_f32 v[10:11], v[226:227], s[62:63], v[10:11] op_sel_hi:[1,0,1]
	v_pk_fma_f32 v[12:13], v[228:229], s[62:63], v[12:13] op_sel_hi:[1,0,1]
	v_pk_fma_f32 v[14:15], v[230:231], s[62:63], v[14:15] op_sel_hi:[1,0,1]
	s_branch .LV_s4_tail
.LV_s4_t1:
	v_cvt_pk_f32_fp8_e32 v[224:225], v192
	v_cvt_pk_f32_fp8_sdwa v[226:227], v192 src0_sel:WORD_1
	v_cvt_pk_f32_fp8_e32 v[228:229], v193
	v_cvt_pk_f32_fp8_sdwa v[230:231], v193 src0_sel:WORD_1
	v_pk_fma_f32 v[16:17], v[224:225], s[56:57], v[16:17] op_sel_hi:[1,0,1]
	v_pk_fma_f32 v[18:19], v[226:227], s[56:57], v[18:19] op_sel_hi:[1,0,1]
	v_pk_fma_f32 v[20:21], v[228:229], s[56:57], v[20:21] op_sel_hi:[1,0,1]
	v_pk_fma_f32 v[22:23], v[230:231], s[56:57], v[22:23] op_sel_hi:[1,0,1]
	v_cvt_pk_f32_fp8_e32 v[224:225], v194
	v_cvt_pk_f32_fp8_sdwa v[226:227], v194 src0_sel:WORD_1
	v_cvt_pk_f32_fp8_e32 v[228:229], v195
	v_cvt_pk_f32_fp8_sdwa v[230:231], v195 src0_sel:WORD_1
	v_pk_fma_f32 v[24:25], v[224:225], s[56:57], v[24:25] op_sel_hi:[1,0,1]
	v_pk_fma_f32 v[26:27], v[226:227], s[56:57], v[26:27] op_sel_hi:[1,0,1]
	v_pk_fma_f32 v[28:29], v[228:229], s[56:57], v[28:29] op_sel_hi:[1,0,1]
	v_pk_fma_f32 v[30:31], v[230:231], s[56:57], v[30:31] op_sel_hi:[1,0,1]
	v_cvt_pk_f32_fp8_e32 v[224:225], v196
	v_cvt_pk_f32_fp8_sdwa v[226:227], v196 src0_sel:WORD_1
	v_cvt_pk_f32_fp8_e32 v[228:229], v197
	v_cvt_pk_f32_fp8_sdwa v[230:231], v197 src0_sel:WORD_1
	v_pk_fma_f32 v[16:17], v[224:225], s[58:59], v[16:17] op_sel_hi:[1,0,1]
	v_pk_fma_f32 v[18:19], v[226:227], s[58:59], v[18:19] op_sel_hi:[1,0,1]
	v_pk_fma_f32 v[20:21], v[228:229], s[58:59], v[20:21] op_sel_hi:[1,0,1]
	v_pk_fma_f32 v[22:23], v[230:231], s[58:59], v[22:23] op_sel_hi:[1,0,1]
	v_cvt_pk_f32_fp8_e32 v[224:225], v198
	v_cvt_pk_f32_fp8_sdwa v[226:227], v198 src0_sel:WORD_1
	v_cvt_pk_f32_fp8_e32 v[228:229], v199
	v_cvt_pk_f32_fp8_sdwa v[230:231], v199 src0_sel:WORD_1
	v_pk_fma_f32 v[24:25], v[224:225], s[58:59], v[24:25] op_sel_hi:[1,0,1]
	v_pk_fma_f32 v[26:27], v[226:227], s[58:59], v[26:27] op_sel_hi:[1,0,1]
	v_pk_fma_f32 v[28:29], v[228:229], s[58:59], v[28:29] op_sel_hi:[1,0,1]
	v_pk_fma_f32 v[30:31], v[230:231], s[58:59], v[30:31] op_sel_hi:[1,0,1]
	v_cvt_pk_f32_fp8_e32 v[224:225], v200
	v_cvt_pk_f32_fp8_sdwa v[226:227], v200 src0_sel:WORD_1
	v_cvt_pk_f32_fp8_e32 v[228:229], v201
	v_cvt_pk_f32_fp8_sdwa v[230:231], v201 src0_sel:WORD_1
	v_pk_fma_f32 v[16:17], v[224:225], s[60:61], v[16:17] op_sel_hi:[1,0,1]
	v_pk_fma_f32 v[18:19], v[226:227], s[60:61], v[18:19] op_sel_hi:[1,0,1]
	v_pk_fma_f32 v[20:21], v[228:229], s[60:61], v[20:21] op_sel_hi:[1,0,1]
	v_pk_fma_f32 v[22:23], v[230:231], s[60:61], v[22:23] op_sel_hi:[1,0,1]
	v_cvt_pk_f32_fp8_e32 v[224:225], v202
	v_cvt_pk_f32_fp8_sdwa v[226:227], v202 src0_sel:WORD_1
	v_cvt_pk_f32_fp8_e32 v[228:229], v203
	v_cvt_pk_f32_fp8_sdwa v[230:231], v203 src0_sel:WORD_1
	v_pk_fma_f32 v[24:25], v[224:225], s[60:61], v[24:25] op_sel_hi:[1,0,1]
	v_pk_fma_f32 v[26:27], v[226:227], s[60:61], v[26:27] op_sel_hi:[1,0,1]
	v_pk_fma_f32 v[28:29], v[228:229], s[60:61], v[28:29] op_sel_hi:[1,0,1]
	v_pk_fma_f32 v[30:31], v[230:231], s[60:61], v[30:31] op_sel_hi:[1,0,1]
	v_cvt_pk_f32_fp8_e32 v[224:225], v204
	v_cvt_pk_f32_fp8_sdwa v[226:227], v204 src0_sel:WORD_1
	v_cvt_pk_f32_fp8_e32 v[228:229], v205
	v_cvt_pk_f32_fp8_sdwa v[230:231], v205 src0_sel:WORD_1
	v_pk_fma_f32 v[16:17], v[224:225], s[62:63], v[16:17] op_sel_hi:[1,0,1]
	v_pk_fma_f32 v[18:19], v[226:227], s[62:63], v[18:19] op_sel_hi:[1,0,1]
	v_pk_fma_f32 v[20:21], v[228:229], s[62:63], v[20:21] op_sel_hi:[1,0,1]
	v_pk_fma_f32 v[22:23], v[230:231], s[62:63], v[22:23] op_sel_hi:[1,0,1]
	v_cvt_pk_f32_fp8_e32 v[224:225], v206
	v_cvt_pk_f32_fp8_sdwa v[226:227], v206 src0_sel:WORD_1
	v_cvt_pk_f32_fp8_e32 v[228:229], v207
	v_cvt_pk_f32_fp8_sdwa v[230:231], v207 src0_sel:WORD_1
	v_pk_fma_f32 v[24:25], v[224:225], s[62:63], v[24:25] op_sel_hi:[1,0,1]
	v_pk_fma_f32 v[26:27], v[226:227], s[62:63], v[26:27] op_sel_hi:[1,0,1]
	v_pk_fma_f32 v[28:29], v[228:229], s[62:63], v[28:29] op_sel_hi:[1,0,1]
	v_pk_fma_f32 v[30:31], v[230:231], s[62:63], v[30:31] op_sel_hi:[1,0,1]
	s_branch .LV_s4_tail
.LV_s4_t2:
	v_cvt_pk_f32_fp8_e32 v[224:225], v192
	v_cvt_pk_f32_fp8_sdwa v[226:227], v192 src0_sel:WORD_1
	v_cvt_pk_f32_fp8_e32 v[228:229], v193
	v_cvt_pk_f32_fp8_sdwa v[230:231], v193 src0_sel:WORD_1
	v_pk_fma_f32 v[32:33], v[224:225], s[56:57], v[32:33] op_sel_hi:[1,0,1]
	v_pk_fma_f32 v[34:35], v[226:227], s[56:57], v[34:35] op_sel_hi:[1,0,1]
	v_pk_fma_f32 v[36:37], v[228:229], s[56:57], v[36:37] op_sel_hi:[1,0,1]
	v_pk_fma_f32 v[38:39], v[230:231], s[56:57], v[38:39] op_sel_hi:[1,0,1]
	v_cvt_pk_f32_fp8_e32 v[224:225], v194
	v_cvt_pk_f32_fp8_sdwa v[226:227], v194 src0_sel:WORD_1
	v_cvt_pk_f32_fp8_e32 v[228:229], v195
	v_cvt_pk_f32_fp8_sdwa v[230:231], v195 src0_sel:WORD_1
	v_pk_fma_f32 v[40:41], v[224:225], s[56:57], v[40:41] op_sel_hi:[1,0,1]
	v_pk_fma_f32 v[42:43], v[226:227], s[56:57], v[42:43] op_sel_hi:[1,0,1]
	v_pk_fma_f32 v[44:45], v[228:229], s[56:57], v[44:45] op_sel_hi:[1,0,1]
	v_pk_fma_f32 v[46:47], v[230:231], s[56:57], v[46:47] op_sel_hi:[1,0,1]
	v_cvt_pk_f32_fp8_e32 v[224:225], v196
	v_cvt_pk_f32_fp8_sdwa v[226:227], v196 src0_sel:WORD_1
	v_cvt_pk_f32_fp8_e32 v[228:229], v197
	v_cvt_pk_f32_fp8_sdwa v[230:231], v197 src0_sel:WORD_1
	v_pk_fma_f32 v[32:33], v[224:225], s[58:59], v[32:33] op_sel_hi:[1,0,1]
	v_pk_fma_f32 v[34:35], v[226:227], s[58:59], v[34:35] op_sel_hi:[1,0,1]
	v_pk_fma_f32 v[36:37], v[228:229], s[58:59], v[36:37] op_sel_hi:[1,0,1]
	v_pk_fma_f32 v[38:39], v[230:231], s[58:59], v[38:39] op_sel_hi:[1,0,1]
	v_cvt_pk_f32_fp8_e32 v[224:225], v198
	v_cvt_pk_f32_fp8_sdwa v[226:227], v198 src0_sel:WORD_1
	v_cvt_pk_f32_fp8_e32 v[228:229], v199
	v_cvt_pk_f32_fp8_sdwa v[230:231], v199 src0_sel:WORD_1
	v_pk_fma_f32 v[40:41], v[224:225], s[58:59], v[40:41] op_sel_hi:[1,0,1]
	v_pk_fma_f32 v[42:43], v[226:227], s[58:59], v[42:43] op_sel_hi:[1,0,1]
	v_pk_fma_f32 v[44:45], v[228:229], s[58:59], v[44:45] op_sel_hi:[1,0,1]
	v_pk_fma_f32 v[46:47], v[230:231], s[58:59], v[46:47] op_sel_hi:[1,0,1]
	v_cvt_pk_f32_fp8_e32 v[224:225], v200
	v_cvt_pk_f32_fp8_sdwa v[226:227], v200 src0_sel:WORD_1
	v_cvt_pk_f32_fp8_e32 v[228:229], v201
	v_cvt_pk_f32_fp8_sdwa v[230:231], v201 src0_sel:WORD_1
	v_pk_fma_f32 v[32:33], v[224:225], s[60:61], v[32:33] op_sel_hi:[1,0,1]
	v_pk_fma_f32 v[34:35], v[226:227], s[60:61], v[34:35] op_sel_hi:[1,0,1]
	v_pk_fma_f32 v[36:37], v[228:229], s[60:61], v[36:37] op_sel_hi:[1,0,1]
	v_pk_fma_f32 v[38:39], v[230:231], s[60:61], v[38:39] op_sel_hi:[1,0,1]
	v_cvt_pk_f32_fp8_e32 v[224:225], v202
	v_cvt_pk_f32_fp8_sdwa v[226:227], v202 src0_sel:WORD_1
	v_cvt_pk_f32_fp8_e32 v[228:229], v203
	v_cvt_pk_f32_fp8_sdwa v[230:231], v203 src0_sel:WORD_1
	v_pk_fma_f32 v[40:41], v[224:225], s[60:61], v[40:41] op_sel_hi:[1,0,1]
	v_pk_fma_f32 v[42:43], v[226:227], s[60:61], v[42:43] op_sel_hi:[1,0,1]
	v_pk_fma_f32 v[44:45], v[228:229], s[60:61], v[44:45] op_sel_hi:[1,0,1]
	v_pk_fma_f32 v[46:47], v[230:231], s[60:61], v[46:47] op_sel_hi:[1,0,1]
	v_cvt_pk_f32_fp8_e32 v[224:225], v204
	v_cvt_pk_f32_fp8_sdwa v[226:227], v204 src0_sel:WORD_1
	v_cvt_pk_f32_fp8_e32 v[228:229], v205
	v_cvt_pk_f32_fp8_sdwa v[230:231], v205 src0_sel:WORD_1
	v_pk_fma_f32 v[32:33], v[224:225], s[62:63], v[32:33] op_sel_hi:[1,0,1]
	v_pk_fma_f32 v[34:35], v[226:227], s[62:63], v[34:35] op_sel_hi:[1,0,1]
	v_pk_fma_f32 v[36:37], v[228:229], s[62:63], v[36:37] op_sel_hi:[1,0,1]
	v_pk_fma_f32 v[38:39], v[230:231], s[62:63], v[38:39] op_sel_hi:[1,0,1]
	v_cvt_pk_f32_fp8_e32 v[224:225], v206
	v_cvt_pk_f32_fp8_sdwa v[226:227], v206 src0_sel:WORD_1
	v_cvt_pk_f32_fp8_e32 v[228:229], v207
	v_cvt_pk_f32_fp8_sdwa v[230:231], v207 src0_sel:WORD_1
	v_pk_fma_f32 v[40:41], v[224:225], s[62:63], v[40:41] op_sel_hi:[1,0,1]
	v_pk_fma_f32 v[42:43], v[226:227], s[62:63], v[42:43] op_sel_hi:[1,0,1]
	v_pk_fma_f32 v[44:45], v[228:229], s[62:63], v[44:45] op_sel_hi:[1,0,1]
	v_pk_fma_f32 v[46:47], v[230:231], s[62:63], v[46:47] op_sel_hi:[1,0,1]
	s_branch .LV_s4_tail
.LV_s4_t3:
	v_cvt_pk_f32_fp8_e32 v[224:225], v192
	v_cvt_pk_f32_fp8_sdwa v[226:227], v192 src0_sel:WORD_1
	v_cvt_pk_f32_fp8_e32 v[228:229], v193
	v_cvt_pk_f32_fp8_sdwa v[230:231], v193 src0_sel:WORD_1
	v_pk_fma_f32 v[48:49], v[224:225], s[56:57], v[48:49] op_sel_hi:[1,0,1]
	v_pk_fma_f32 v[50:51], v[226:227], s[56:57], v[50:51] op_sel_hi:[1,0,1]
	v_pk_fma_f32 v[52:53], v[228:229], s[56:57], v[52:53] op_sel_hi:[1,0,1]
	v_pk_fma_f32 v[54:55], v[230:231], s[56:57], v[54:55] op_sel_hi:[1,0,1]
	v_cvt_pk_f32_fp8_e32 v[224:225], v194
	v_cvt_pk_f32_fp8_sdwa v[226:227], v194 src0_sel:WORD_1
	v_cvt_pk_f32_fp8_e32 v[228:229], v195
	v_cvt_pk_f32_fp8_sdwa v[230:231], v195 src0_sel:WORD_1
	v_pk_fma_f32 v[56:57], v[224:225], s[56:57], v[56:57] op_sel_hi:[1,0,1]
	v_pk_fma_f32 v[58:59], v[226:227], s[56:57], v[58:59] op_sel_hi:[1,0,1]
	v_pk_fma_f32 v[60:61], v[228:229], s[56:57], v[60:61] op_sel_hi:[1,0,1]
	v_pk_fma_f32 v[62:63], v[230:231], s[56:57], v[62:63] op_sel_hi:[1,0,1]
	v_cvt_pk_f32_fp8_e32 v[224:225], v196
	v_cvt_pk_f32_fp8_sdwa v[226:227], v196 src0_sel:WORD_1
	v_cvt_pk_f32_fp8_e32 v[228:229], v197
	v_cvt_pk_f32_fp8_sdwa v[230:231], v197 src0_sel:WORD_1
	v_pk_fma_f32 v[48:49], v[224:225], s[58:59], v[48:49] op_sel_hi:[1,0,1]
	v_pk_fma_f32 v[50:51], v[226:227], s[58:59], v[50:51] op_sel_hi:[1,0,1]
	v_pk_fma_f32 v[52:53], v[228:229], s[58:59], v[52:53] op_sel_hi:[1,0,1]
	v_pk_fma_f32 v[54:55], v[230:231], s[58:59], v[54:55] op_sel_hi:[1,0,1]
	v_cvt_pk_f32_fp8_e32 v[224:225], v198
	v_cvt_pk_f32_fp8_sdwa v[226:227], v198 src0_sel:WORD_1
	v_cvt_pk_f32_fp8_e32 v[228:229], v199
	v_cvt_pk_f32_fp8_sdwa v[230:231], v199 src0_sel:WORD_1
	v_pk_fma_f32 v[56:57], v[224:225], s[58:59], v[56:57] op_sel_hi:[1,0,1]
	v_pk_fma_f32 v[58:59], v[226:227], s[58:59], v[58:59] op_sel_hi:[1,0,1]
	v_pk_fma_f32 v[60:61], v[228:229], s[58:59], v[60:61] op_sel_hi:[1,0,1]
	v_pk_fma_f32 v[62:63], v[230:231], s[58:59], v[62:63] op_sel_hi:[1,0,1]
	v_cvt_pk_f32_fp8_e32 v[224:225], v200
	v_cvt_pk_f32_fp8_sdwa v[226:227], v200 src0_sel:WORD_1
	v_cvt_pk_f32_fp8_e32 v[228:229], v201
	v_cvt_pk_f32_fp8_sdwa v[230:231], v201 src0_sel:WORD_1
	v_pk_fma_f32 v[48:49], v[224:225], s[60:61], v[48:49] op_sel_hi:[1,0,1]
	v_pk_fma_f32 v[50:51], v[226:227], s[60:61], v[50:51] op_sel_hi:[1,0,1]
	v_pk_fma_f32 v[52:53], v[228:229], s[60:61], v[52:53] op_sel_hi:[1,0,1]
	v_pk_fma_f32 v[54:55], v[230:231], s[60:61], v[54:55] op_sel_hi:[1,0,1]
	v_cvt_pk_f32_fp8_e32 v[224:225], v202
	v_cvt_pk_f32_fp8_sdwa v[226:227], v202 src0_sel:WORD_1
	v_cvt_pk_f32_fp8_e32 v[228:229], v203
	v_cvt_pk_f32_fp8_sdwa v[230:231], v203 src0_sel:WORD_1
	v_pk_fma_f32 v[56:57], v[224:225], s[60:61], v[56:57] op_sel_hi:[1,0,1]
	v_pk_fma_f32 v[58:59], v[226:227], s[60:61], v[58:59] op_sel_hi:[1,0,1]
	v_pk_fma_f32 v[60:61], v[228:229], s[60:61], v[60:61] op_sel_hi:[1,0,1]
	v_pk_fma_f32 v[62:63], v[230:231], s[60:61], v[62:63] op_sel_hi:[1,0,1]
	v_cvt_pk_f32_fp8_e32 v[224:225], v204
	v_cvt_pk_f32_fp8_sdwa v[226:227], v204 src0_sel:WORD_1
	v_cvt_pk_f32_fp8_e32 v[228:229], v205
	v_cvt_pk_f32_fp8_sdwa v[230:231], v205 src0_sel:WORD_1
	v_pk_fma_f32 v[48:49], v[224:225], s[62:63], v[48:49] op_sel_hi:[1,0,1]
	v_pk_fma_f32 v[50:51], v[226:227], s[62:63], v[50:51] op_sel_hi:[1,0,1]
	v_pk_fma_f32 v[52:53], v[228:229], s[62:63], v[52:53] op_sel_hi:[1,0,1]
	v_pk_fma_f32 v[54:55], v[230:231], s[62:63], v[54:55] op_sel_hi:[1,0,1]
	v_cvt_pk_f32_fp8_e32 v[224:225], v206
	v_cvt_pk_f32_fp8_sdwa v[226:227], v206 src0_sel:WORD_1
	v_cvt_pk_f32_fp8_e32 v[228:229], v207
	v_cvt_pk_f32_fp8_sdwa v[230:231], v207 src0_sel:WORD_1
	v_pk_fma_f32 v[56:57], v[224:225], s[62:63], v[56:57] op_sel_hi:[1,0,1]
	v_pk_fma_f32 v[58:59], v[226:227], s[62:63], v[58:59] op_sel_hi:[1,0,1]
	v_pk_fma_f32 v[60:61], v[228:229], s[62:63], v[60:61] op_sel_hi:[1,0,1]
	v_pk_fma_f32 v[62:63], v[230:231], s[62:63], v[62:63] op_sel_hi:[1,0,1]
	s_branch .LV_s4_tail
.LV_s4_t4:
	v_cvt_pk_f32_fp8_e32 v[224:225], v192
	v_cvt_pk_f32_fp8_sdwa v[226:227], v192 src0_sel:WORD_1
	v_cvt_pk_f32_fp8_e32 v[228:229], v193
	v_cvt_pk_f32_fp8_sdwa v[230:231], v193 src0_sel:WORD_1
	v_pk_fma_f32 v[64:65], v[224:225], s[56:57], v[64:65] op_sel_hi:[1,0,1]
	v_pk_fma_f32 v[66:67], v[226:227], s[56:57], v[66:67] op_sel_hi:[1,0,1]
	v_pk_fma_f32 v[68:69], v[228:229], s[56:57], v[68:69] op_sel_hi:[1,0,1]
	v_pk_fma_f32 v[70:71], v[230:231], s[56:57], v[70:71] op_sel_hi:[1,0,1]
	v_cvt_pk_f32_fp8_e32 v[224:225], v194
	v_cvt_pk_f32_fp8_sdwa v[226:227], v194 src0_sel:WORD_1
	v_cvt_pk_f32_fp8_e32 v[228:229], v195
	v_cvt_pk_f32_fp8_sdwa v[230:231], v195 src0_sel:WORD_1
	v_pk_fma_f32 v[72:73], v[224:225], s[56:57], v[72:73] op_sel_hi:[1,0,1]
	v_pk_fma_f32 v[74:75], v[226:227], s[56:57], v[74:75] op_sel_hi:[1,0,1]
	v_pk_fma_f32 v[76:77], v[228:229], s[56:57], v[76:77] op_sel_hi:[1,0,1]
	v_pk_fma_f32 v[78:79], v[230:231], s[56:57], v[78:79] op_sel_hi:[1,0,1]
	v_cvt_pk_f32_fp8_e32 v[224:225], v196
	v_cvt_pk_f32_fp8_sdwa v[226:227], v196 src0_sel:WORD_1
	v_cvt_pk_f32_fp8_e32 v[228:229], v197
	v_cvt_pk_f32_fp8_sdwa v[230:231], v197 src0_sel:WORD_1
	v_pk_fma_f32 v[64:65], v[224:225], s[58:59], v[64:65] op_sel_hi:[1,0,1]
	v_pk_fma_f32 v[66:67], v[226:227], s[58:59], v[66:67] op_sel_hi:[1,0,1]
	v_pk_fma_f32 v[68:69], v[228:229], s[58:59], v[68:69] op_sel_hi:[1,0,1]
	v_pk_fma_f32 v[70:71], v[230:231], s[58:59], v[70:71] op_sel_hi:[1,0,1]
	v_cvt_pk_f32_fp8_e32 v[224:225], v198
	v_cvt_pk_f32_fp8_sdwa v[226:227], v198 src0_sel:WORD_1
	v_cvt_pk_f32_fp8_e32 v[228:229], v199
	v_cvt_pk_f32_fp8_sdwa v[230:231], v199 src0_sel:WORD_1
	v_pk_fma_f32 v[72:73], v[224:225], s[58:59], v[72:73] op_sel_hi:[1,0,1]
	v_pk_fma_f32 v[74:75], v[226:227], s[58:59], v[74:75] op_sel_hi:[1,0,1]
	v_pk_fma_f32 v[76:77], v[228:229], s[58:59], v[76:77] op_sel_hi:[1,0,1]
	v_pk_fma_f32 v[78:79], v[230:231], s[58:59], v[78:79] op_sel_hi:[1,0,1]
	v_cvt_pk_f32_fp8_e32 v[224:225], v200
	v_cvt_pk_f32_fp8_sdwa v[226:227], v200 src0_sel:WORD_1
	v_cvt_pk_f32_fp8_e32 v[228:229], v201
	v_cvt_pk_f32_fp8_sdwa v[230:231], v201 src0_sel:WORD_1
	v_pk_fma_f32 v[64:65], v[224:225], s[60:61], v[64:65] op_sel_hi:[1,0,1]
	v_pk_fma_f32 v[66:67], v[226:227], s[60:61], v[66:67] op_sel_hi:[1,0,1]
	v_pk_fma_f32 v[68:69], v[228:229], s[60:61], v[68:69] op_sel_hi:[1,0,1]
	v_pk_fma_f32 v[70:71], v[230:231], s[60:61], v[70:71] op_sel_hi:[1,0,1]
	v_cvt_pk_f32_fp8_e32 v[224:225], v202
	v_cvt_pk_f32_fp8_sdwa v[226:227], v202 src0_sel:WORD_1
	v_cvt_pk_f32_fp8_e32 v[228:229], v203
	v_cvt_pk_f32_fp8_sdwa v[230:231], v203 src0_sel:WORD_1
	v_pk_fma_f32 v[72:73], v[224:225], s[60:61], v[72:73] op_sel_hi:[1,0,1]
	v_pk_fma_f32 v[74:75], v[226:227], s[60:61], v[74:75] op_sel_hi:[1,0,1]
	v_pk_fma_f32 v[76:77], v[228:229], s[60:61], v[76:77] op_sel_hi:[1,0,1]
	v_pk_fma_f32 v[78:79], v[230:231], s[60:61], v[78:79] op_sel_hi:[1,0,1]
	v_cvt_pk_f32_fp8_e32 v[224:225], v204
	v_cvt_pk_f32_fp8_sdwa v[226:227], v204 src0_sel:WORD_1
	v_cvt_pk_f32_fp8_e32 v[228:229], v205
	v_cvt_pk_f32_fp8_sdwa v[230:231], v205 src0_sel:WORD_1
	v_pk_fma_f32 v[64:65], v[224:225], s[62:63], v[64:65] op_sel_hi:[1,0,1]
	v_pk_fma_f32 v[66:67], v[226:227], s[62:63], v[66:67] op_sel_hi:[1,0,1]
	v_pk_fma_f32 v[68:69], v[228:229], s[62:63], v[68:69] op_sel_hi:[1,0,1]
	v_pk_fma_f32 v[70:71], v[230:231], s[62:63], v[70:71] op_sel_hi:[1,0,1]
	v_cvt_pk_f32_fp8_e32 v[224:225], v206
	v_cvt_pk_f32_fp8_sdwa v[226:227], v206 src0_sel:WORD_1
	v_cvt_pk_f32_fp8_e32 v[228:229], v207
	v_cvt_pk_f32_fp8_sdwa v[230:231], v207 src0_sel:WORD_1
	v_pk_fma_f32 v[72:73], v[224:225], s[62:63], v[72:73] op_sel_hi:[1,0,1]
	v_pk_fma_f32 v[74:75], v[226:227], s[62:63], v[74:75] op_sel_hi:[1,0,1]
	v_pk_fma_f32 v[76:77], v[228:229], s[62:63], v[76:77] op_sel_hi:[1,0,1]
	v_pk_fma_f32 v[78:79], v[230:231], s[62:63], v[78:79] op_sel_hi:[1,0,1]
	s_branch .LV_s4_tail
.LV_s4_t5:
	v_cvt_pk_f32_fp8_e32 v[224:225], v192
	v_cvt_pk_f32_fp8_sdwa v[226:227], v192 src0_sel:WORD_1
	v_cvt_pk_f32_fp8_e32 v[228:229], v193
	v_cvt_pk_f32_fp8_sdwa v[230:231], v193 src0_sel:WORD_1
	v_pk_fma_f32 v[80:81], v[224:225], s[56:57], v[80:81] op_sel_hi:[1,0,1]
	v_pk_fma_f32 v[82:83], v[226:227], s[56:57], v[82:83] op_sel_hi:[1,0,1]
	v_pk_fma_f32 v[84:85], v[228:229], s[56:57], v[84:85] op_sel_hi:[1,0,1]
	v_pk_fma_f32 v[86:87], v[230:231], s[56:57], v[86:87] op_sel_hi:[1,0,1]
	v_cvt_pk_f32_fp8_e32 v[224:225], v194
	v_cvt_pk_f32_fp8_sdwa v[226:227], v194 src0_sel:WORD_1
	v_cvt_pk_f32_fp8_e32 v[228:229], v195
	v_cvt_pk_f32_fp8_sdwa v[230:231], v195 src0_sel:WORD_1
	v_pk_fma_f32 v[88:89], v[224:225], s[56:57], v[88:89] op_sel_hi:[1,0,1]
	v_pk_fma_f32 v[90:91], v[226:227], s[56:57], v[90:91] op_sel_hi:[1,0,1]
	v_pk_fma_f32 v[92:93], v[228:229], s[56:57], v[92:93] op_sel_hi:[1,0,1]
	v_pk_fma_f32 v[94:95], v[230:231], s[56:57], v[94:95] op_sel_hi:[1,0,1]
	v_cvt_pk_f32_fp8_e32 v[224:225], v196
	v_cvt_pk_f32_fp8_sdwa v[226:227], v196 src0_sel:WORD_1
	v_cvt_pk_f32_fp8_e32 v[228:229], v197
	v_cvt_pk_f32_fp8_sdwa v[230:231], v197 src0_sel:WORD_1
	v_pk_fma_f32 v[80:81], v[224:225], s[58:59], v[80:81] op_sel_hi:[1,0,1]
	v_pk_fma_f32 v[82:83], v[226:227], s[58:59], v[82:83] op_sel_hi:[1,0,1]
	v_pk_fma_f32 v[84:85], v[228:229], s[58:59], v[84:85] op_sel_hi:[1,0,1]
	v_pk_fma_f32 v[86:87], v[230:231], s[58:59], v[86:87] op_sel_hi:[1,0,1]
	v_cvt_pk_f32_fp8_e32 v[224:225], v198
	v_cvt_pk_f32_fp8_sdwa v[226:227], v198 src0_sel:WORD_1
	v_cvt_pk_f32_fp8_e32 v[228:229], v199
	v_cvt_pk_f32_fp8_sdwa v[230:231], v199 src0_sel:WORD_1
	v_pk_fma_f32 v[88:89], v[224:225], s[58:59], v[88:89] op_sel_hi:[1,0,1]
	v_pk_fma_f32 v[90:91], v[226:227], s[58:59], v[90:91] op_sel_hi:[1,0,1]
	v_pk_fma_f32 v[92:93], v[228:229], s[58:59], v[92:93] op_sel_hi:[1,0,1]
	v_pk_fma_f32 v[94:95], v[230:231], s[58:59], v[94:95] op_sel_hi:[1,0,1]
	v_cvt_pk_f32_fp8_e32 v[224:225], v200
	v_cvt_pk_f32_fp8_sdwa v[226:227], v200 src0_sel:WORD_1
	v_cvt_pk_f32_fp8_e32 v[228:229], v201
	v_cvt_pk_f32_fp8_sdwa v[230:231], v201 src0_sel:WORD_1
	v_pk_fma_f32 v[80:81], v[224:225], s[60:61], v[80:81] op_sel_hi:[1,0,1]
	v_pk_fma_f32 v[82:83], v[226:227], s[60:61], v[82:83] op_sel_hi:[1,0,1]
	v_pk_fma_f32 v[84:85], v[228:229], s[60:61], v[84:85] op_sel_hi:[1,0,1]
	v_pk_fma_f32 v[86:87], v[230:231], s[60:61], v[86:87] op_sel_hi:[1,0,1]
	v_cvt_pk_f32_fp8_e32 v[224:225], v202
	v_cvt_pk_f32_fp8_sdwa v[226:227], v202 src0_sel:WORD_1
	v_cvt_pk_f32_fp8_e32 v[228:229], v203
	v_cvt_pk_f32_fp8_sdwa v[230:231], v203 src0_sel:WORD_1
	v_pk_fma_f32 v[88:89], v[224:225], s[60:61], v[88:89] op_sel_hi:[1,0,1]
	v_pk_fma_f32 v[90:91], v[226:227], s[60:61], v[90:91] op_sel_hi:[1,0,1]
	v_pk_fma_f32 v[92:93], v[228:229], s[60:61], v[92:93] op_sel_hi:[1,0,1]
	v_pk_fma_f32 v[94:95], v[230:231], s[60:61], v[94:95] op_sel_hi:[1,0,1]
	v_cvt_pk_f32_fp8_e32 v[224:225], v204
	v_cvt_pk_f32_fp8_sdwa v[226:227], v204 src0_sel:WORD_1
	v_cvt_pk_f32_fp8_e32 v[228:229], v205
	v_cvt_pk_f32_fp8_sdwa v[230:231], v205 src0_sel:WORD_1
	v_pk_fma_f32 v[80:81], v[224:225], s[62:63], v[80:81] op_sel_hi:[1,0,1]
	v_pk_fma_f32 v[82:83], v[226:227], s[62:63], v[82:83] op_sel_hi:[1,0,1]
	v_pk_fma_f32 v[84:85], v[228:229], s[62:63], v[84:85] op_sel_hi:[1,0,1]
	v_pk_fma_f32 v[86:87], v[230:231], s[62:63], v[86:87] op_sel_hi:[1,0,1]
	v_cvt_pk_f32_fp8_e32 v[224:225], v206
	v_cvt_pk_f32_fp8_sdwa v[226:227], v206 src0_sel:WORD_1
	v_cvt_pk_f32_fp8_e32 v[228:229], v207
	v_cvt_pk_f32_fp8_sdwa v[230:231], v207 src0_sel:WORD_1
	v_pk_fma_f32 v[88:89], v[224:225], s[62:63], v[88:89] op_sel_hi:[1,0,1]
	v_pk_fma_f32 v[90:91], v[226:227], s[62:63], v[90:91] op_sel_hi:[1,0,1]
	v_pk_fma_f32 v[92:93], v[228:229], s[62:63], v[92:93] op_sel_hi:[1,0,1]
	v_pk_fma_f32 v[94:95], v[230:231], s[62:63], v[94:95] op_sel_hi:[1,0,1]
	s_branch .LV_s4_tail
.LV_s4_t6:
	v_cvt_pk_f32_fp8_e32 v[224:225], v192
	v_cvt_pk_f32_fp8_sdwa v[226:227], v192 src0_sel:WORD_1
	v_cvt_pk_f32_fp8_e32 v[228:229], v193
	v_cvt_pk_f32_fp8_sdwa v[230:231], v193 src0_sel:WORD_1
	v_pk_fma_f32 v[96:97], v[224:225], s[56:57], v[96:97] op_sel_hi:[1,0,1]
	v_pk_fma_f32 v[98:99], v[226:227], s[56:57], v[98:99] op_sel_hi:[1,0,1]
	v_pk_fma_f32 v[100:101], v[228:229], s[56:57], v[100:101] op_sel_hi:[1,0,1]
	v_pk_fma_f32 v[102:103], v[230:231], s[56:57], v[102:103] op_sel_hi:[1,0,1]
	v_cvt_pk_f32_fp8_e32 v[224:225], v194
	v_cvt_pk_f32_fp8_sdwa v[226:227], v194 src0_sel:WORD_1
	v_cvt_pk_f32_fp8_e32 v[228:229], v195
	v_cvt_pk_f32_fp8_sdwa v[230:231], v195 src0_sel:WORD_1
	v_pk_fma_f32 v[104:105], v[224:225], s[56:57], v[104:105] op_sel_hi:[1,0,1]
	v_pk_fma_f32 v[106:107], v[226:227], s[56:57], v[106:107] op_sel_hi:[1,0,1]
	v_pk_fma_f32 v[108:109], v[228:229], s[56:57], v[108:109] op_sel_hi:[1,0,1]
	v_pk_fma_f32 v[110:111], v[230:231], s[56:57], v[110:111] op_sel_hi:[1,0,1]
	v_cvt_pk_f32_fp8_e32 v[224:225], v196
	v_cvt_pk_f32_fp8_sdwa v[226:227], v196 src0_sel:WORD_1
	v_cvt_pk_f32_fp8_e32 v[228:229], v197
	v_cvt_pk_f32_fp8_sdwa v[230:231], v197 src0_sel:WORD_1
	v_pk_fma_f32 v[96:97], v[224:225], s[58:59], v[96:97] op_sel_hi:[1,0,1]
	v_pk_fma_f32 v[98:99], v[226:227], s[58:59], v[98:99] op_sel_hi:[1,0,1]
	v_pk_fma_f32 v[100:101], v[228:229], s[58:59], v[100:101] op_sel_hi:[1,0,1]
	v_pk_fma_f32 v[102:103], v[230:231], s[58:59], v[102:103] op_sel_hi:[1,0,1]
	v_cvt_pk_f32_fp8_e32 v[224:225], v198
	v_cvt_pk_f32_fp8_sdwa v[226:227], v198 src0_sel:WORD_1
	v_cvt_pk_f32_fp8_e32 v[228:229], v199
	v_cvt_pk_f32_fp8_sdwa v[230:231], v199 src0_sel:WORD_1
	v_pk_fma_f32 v[104:105], v[224:225], s[58:59], v[104:105] op_sel_hi:[1,0,1]
	v_pk_fma_f32 v[106:107], v[226:227], s[58:59], v[106:107] op_sel_hi:[1,0,1]
	v_pk_fma_f32 v[108:109], v[228:229], s[58:59], v[108:109] op_sel_hi:[1,0,1]
	v_pk_fma_f32 v[110:111], v[230:231], s[58:59], v[110:111] op_sel_hi:[1,0,1]
	v_cvt_pk_f32_fp8_e32 v[224:225], v200
	v_cvt_pk_f32_fp8_sdwa v[226:227], v200 src0_sel:WORD_1
	v_cvt_pk_f32_fp8_e32 v[228:229], v201
	v_cvt_pk_f32_fp8_sdwa v[230:231], v201 src0_sel:WORD_1
	v_pk_fma_f32 v[96:97], v[224:225], s[60:61], v[96:97] op_sel_hi:[1,0,1]
	v_pk_fma_f32 v[98:99], v[226:227], s[60:61], v[98:99] op_sel_hi:[1,0,1]
	v_pk_fma_f32 v[100:101], v[228:229], s[60:61], v[100:101] op_sel_hi:[1,0,1]
	v_pk_fma_f32 v[102:103], v[230:231], s[60:61], v[102:103] op_sel_hi:[1,0,1]
	v_cvt_pk_f32_fp8_e32 v[224:225], v202
	v_cvt_pk_f32_fp8_sdwa v[226:227], v202 src0_sel:WORD_1
	v_cvt_pk_f32_fp8_e32 v[228:229], v203
	v_cvt_pk_f32_fp8_sdwa v[230:231], v203 src0_sel:WORD_1
	v_pk_fma_f32 v[104:105], v[224:225], s[60:61], v[104:105] op_sel_hi:[1,0,1]
	v_pk_fma_f32 v[106:107], v[226:227], s[60:61], v[106:107] op_sel_hi:[1,0,1]
	v_pk_fma_f32 v[108:109], v[228:229], s[60:61], v[108:109] op_sel_hi:[1,0,1]
	v_pk_fma_f32 v[110:111], v[230:231], s[60:61], v[110:111] op_sel_hi:[1,0,1]
	v_cvt_pk_f32_fp8_e32 v[224:225], v204
	v_cvt_pk_f32_fp8_sdwa v[226:227], v204 src0_sel:WORD_1
	v_cvt_pk_f32_fp8_e32 v[228:229], v205
	v_cvt_pk_f32_fp8_sdwa v[230:231], v205 src0_sel:WORD_1
	v_pk_fma_f32 v[96:97], v[224:225], s[62:63], v[96:97] op_sel_hi:[1,0,1]
	v_pk_fma_f32 v[98:99], v[226:227], s[62:63], v[98:99] op_sel_hi:[1,0,1]
	v_pk_fma_f32 v[100:101], v[228:229], s[62:63], v[100:101] op_sel_hi:[1,0,1]
	v_pk_fma_f32 v[102:103], v[230:231], s[62:63], v[102:103] op_sel_hi:[1,0,1]
	v_cvt_pk_f32_fp8_e32 v[224:225], v206
	v_cvt_pk_f32_fp8_sdwa v[226:227], v206 src0_sel:WORD_1
	v_cvt_pk_f32_fp8_e32 v[228:229], v207
	v_cvt_pk_f32_fp8_sdwa v[230:231], v207 src0_sel:WORD_1
	v_pk_fma_f32 v[104:105], v[224:225], s[62:63], v[104:105] op_sel_hi:[1,0,1]
	v_pk_fma_f32 v[106:107], v[226:227], s[62:63], v[106:107] op_sel_hi:[1,0,1]
	v_pk_fma_f32 v[108:109], v[228:229], s[62:63], v[108:109] op_sel_hi:[1,0,1]
	v_pk_fma_f32 v[110:111], v[230:231], s[62:63], v[110:111] op_sel_hi:[1,0,1]
	s_branch .LV_s4_tail
.LV_s4_t7:
	v_cvt_pk_f32_fp8_e32 v[224:225], v192
	v_cvt_pk_f32_fp8_sdwa v[226:227], v192 src0_sel:WORD_1
	v_cvt_pk_f32_fp8_e32 v[228:229], v193
	v_cvt_pk_f32_fp8_sdwa v[230:231], v193 src0_sel:WORD_1
	v_pk_fma_f32 v[112:113], v[224:225], s[56:57], v[112:113] op_sel_hi:[1,0,1]
	v_pk_fma_f32 v[114:115], v[226:227], s[56:57], v[114:115] op_sel_hi:[1,0,1]
	v_pk_fma_f32 v[116:117], v[228:229], s[56:57], v[116:117] op_sel_hi:[1,0,1]
	v_pk_fma_f32 v[118:119], v[230:231], s[56:57], v[118:119] op_sel_hi:[1,0,1]
	v_cvt_pk_f32_fp8_e32 v[224:225], v194
	v_cvt_pk_f32_fp8_sdwa v[226:227], v194 src0_sel:WORD_1
	v_cvt_pk_f32_fp8_e32 v[228:229], v195
	v_cvt_pk_f32_fp8_sdwa v[230:231], v195 src0_sel:WORD_1
	v_pk_fma_f32 v[120:121], v[224:225], s[56:57], v[120:121] op_sel_hi:[1,0,1]
	v_pk_fma_f32 v[122:123], v[226:227], s[56:57], v[122:123] op_sel_hi:[1,0,1]
	v_pk_fma_f32 v[124:125], v[228:229], s[56:57], v[124:125] op_sel_hi:[1,0,1]
	v_pk_fma_f32 v[126:127], v[230:231], s[56:57], v[126:127] op_sel_hi:[1,0,1]
	v_cvt_pk_f32_fp8_e32 v[224:225], v196
	v_cvt_pk_f32_fp8_sdwa v[226:227], v196 src0_sel:WORD_1
	v_cvt_pk_f32_fp8_e32 v[228:229], v197
	v_cvt_pk_f32_fp8_sdwa v[230:231], v197 src0_sel:WORD_1
	v_pk_fma_f32 v[112:113], v[224:225], s[58:59], v[112:113] op_sel_hi:[1,0,1]
	v_pk_fma_f32 v[114:115], v[226:227], s[58:59], v[114:115] op_sel_hi:[1,0,1]
	v_pk_fma_f32 v[116:117], v[228:229], s[58:59], v[116:117] op_sel_hi:[1,0,1]
	v_pk_fma_f32 v[118:119], v[230:231], s[58:59], v[118:119] op_sel_hi:[1,0,1]
	v_cvt_pk_f32_fp8_e32 v[224:225], v198
	v_cvt_pk_f32_fp8_sdwa v[226:227], v198 src0_sel:WORD_1
	v_cvt_pk_f32_fp8_e32 v[228:229], v199
; __device__ __forceinline__ void peer_tile(const Args& A, LAS unsigned char* lds, int tile) {
;     ...
;         for (int tk = 0; tk < 4; ++tk) {
;             const size_t m = (size_t)tile * 64 + tb + tk; const int b = (int)(m >> 11);
;             float* orow = A.out + m * 1024 + 16 * lane;
;             const float* g2 = MOD + b * 6144 + 5120 + 16 * lane;
;             f32x4 xv[4]; float ss = 0.f;
; #pragma unroll
;             for (int j = 0; j < 4; ++j) { const f32x4 x1 = *(const f32x4*)(orow + 4 * j), gg = *(const f32x4*)(g2 + 4 * j);
	v_cvt_pk_f32_fp8_sdwa v[230:231], v199 src0_sel:WORD_1
	v_pk_fma_f32 v[120:121], v[224:225], s[58:59], v[120:121] op_sel_hi:[1,0,1]
	v_pk_fma_f32 v[122:123], v[226:227], s[58:59], v[122:123] op_sel_hi:[1,0,1]
	v_pk_fma_f32 v[124:125], v[228:229], s[58:59], v[124:125] op_sel_hi:[1,0,1]
	v_pk_fma_f32 v[126:127], v[230:231], s[58:59], v[126:127] op_sel_hi:[1,0,1]
	v_cvt_pk_f32_fp8_e32 v[224:225], v200
	v_cvt_pk_f32_fp8_sdwa v[226:227], v200 src0_sel:WORD_1
	v_cvt_pk_f32_fp8_e32 v[228:229], v201
	v_cvt_pk_f32_fp8_sdwa v[230:231], v201 src0_sel:WORD_1
	v_pk_fma_f32 v[112:113], v[224:225], s[60:61], v[112:113] op_sel_hi:[1,0,1]
	v_pk_fma_f32 v[114:115], v[226:227], s[60:61], v[114:115] op_sel_hi:[1,0,1]
	v_pk_fma_f32 v[116:117], v[228:229], s[60:61], v[116:117] op_sel_hi:[1,0,1]
	v_pk_fma_f32 v[118:119], v[230:231], s[60:61], v[118:119] op_sel_hi:[1,0,1]
	v_cvt_pk_f32_fp8_e32 v[224:225], v202
	v_cvt_pk_f32_fp8_sdwa v[226:227], v202 src0_sel:WORD_1
	v_cvt_pk_f32_fp8_e32 v[228:229], v203
	v_cvt_pk_f32_fp8_sdwa v[230:231], v203 src0_sel:WORD_1
	v_pk_fma_f32 v[120:121], v[224:225], s[60:61], v[120:121] op_sel_hi:[1,0,1]
	v_pk_fma_f32 v[122:123], v[226:227], s[60:61], v[122:123] op_sel_hi:[1,0,1]
	v_pk_fma_f32 v[124:125], v[228:229], s[60:61], v[124:125] op_sel_hi:[1,0,1]
	v_pk_fma_f32 v[126:127], v[230:231], s[60:61], v[126:127] op_sel_hi:[1,0,1]
	v_cvt_pk_f32_fp8_e32 v[224:225], v204
	v_cvt_pk_f32_fp8_sdwa v[226:227], v204 src0_sel:WORD_1
	v_cvt_pk_f32_fp8_e32 v[228:229], v205
	v_cvt_pk_f32_fp8_sdwa v[230:231], v205 src0_sel:WORD_1
	v_pk_fma_f32 v[112:113], v[224:225], s[62:63], v[112:113] op_sel_hi:[1,0,1]
	v_pk_fma_f32 v[114:115], v[226:227], s[62:63], v[114:115] op_sel_hi:[1,0,1]
	v_pk_fma_f32 v[116:117], v[228:229], s[62:63], v[116:117] op_sel_hi:[1,0,1]
	v_pk_fma_f32 v[118:119], v[230:231], s[62:63], v[118:119] op_sel_hi:[1,0,1]
	v_cvt_pk_f32_fp8_e32 v[224:225], v206
	v_cvt_pk_f32_fp8_sdwa v[226:227], v206 src0_sel:WORD_1
	v_cvt_pk_f32_fp8_e32 v[228:229], v207
	v_cvt_pk_f32_fp8_sdwa v[230:231], v207 src0_sel:WORD_1
	v_pk_fma_f32 v[120:121], v[224:225], s[62:63], v[120:121] op_sel_hi:[1,0,1]
	v_pk_fma_f32 v[122:123], v[226:227], s[62:63], v[122:123] op_sel_hi:[1,0,1]
	v_pk_fma_f32 v[124:125], v[228:229], s[62:63], v[124:125] op_sel_hi:[1,0,1]
	v_pk_fma_f32 v[126:127], v[230:231], s[62:63], v[126:127] op_sel_hi:[1,0,1]
.LV_s4_tail:
	ds_read_b128 v[236:239], v241 offset:320
	ds_read_b128 v[232:235], v241 offset:576
	s_add_i32 s21, s21, 1
	v_add_u32_e32 v241, 320, v241
	s_branch .LV_s0
.LV_done:
	s_waitcnt vmcnt(0) lgkmcnt(0)
	s_add_i32 s90, s90, 128
	s_cmp_lt_u32 s90, s91
	s_cbranch_scc1 .LV_win
	s_add_i32 s89, s89, 1
	s_cmp_lt_u32 s89, 4
	s_cbranch_scc1 .LV_chunk
	global_load_dwordx4 v[192:195], v246, s[82:83]
	global_load_dwordx4 v[196:199], v246, s[82:83] offset:16
	global_load_dwordx4 v[200:203], v246, s[82:83] offset:32
	global_load_dwordx4 v[204:207], v246, s[82:83] offset:48
	global_load_dwordx4 v[216:219], v246, s[46:47]
	global_load_dwordx4 v[220:223], v246, s[46:47] offset:16
	global_load_dwordx4 v[224:227], v246, s[46:47] offset:32
	global_load_dwordx4 v[228:231], v246, s[46:47] offset:48
	s_add_i32 s0, s77, 0
	s_lshl_b32 s0, s0, 12
	s_add_u32 s24, s48, s0
	s_addc_u32 s25, s49, 0
	s_add_i32 s0, s77, 1
	s_lshl_b32 s0, s0, 12
	s_add_u32 s26, s48, s0
	s_addc_u32 s27, s49, 0
	s_add_i32 s0, s77, 2
	s_lshl_b32 s0, s0, 12
	s_add_u32 s28, s48, s0
	s_addc_u32 s29, s49, 0
	s_add_i32 s0, s77, 3
	s_lshl_b32 s0, s0, 12
	s_add_u32 s30, s48, s0
	s_addc_u32 s31, s49, 0
	global_load_dwordx4 v[128:131], v246, s[24:25]
	global_load_dwordx4 v[132:135], v246, s[24:25] offset:16
	global_load_dwordx4 v[136:139], v246, s[24:25] offset:32
	global_load_dwordx4 v[140:143], v246, s[24:25] offset:48
	global_load_dwordx4 v[144:147], v246, s[26:27]
	global_load_dwordx4 v[148:151], v246, s[26:27] offset:16
	global_load_dwordx4 v[152:155], v246, s[26:27] offset:32
	global_load_dwordx4 v[156:159], v246, s[26:27] offset:48
	global_load_dwordx4 v[160:163], v246, s[28:29]
	global_load_dwordx4 v[164:167], v246, s[28:29] offset:16
	global_load_dwordx4 v[168:171], v246, s[28:29] offset:32
	global_load_dwordx4 v[172:175], v246, s[28:29] offset:48
	global_load_dwordx4 v[176:179], v246, s[30:31]
	global_load_dwordx4 v[180:183], v246, s[30:31] offset:16
	global_load_dwordx4 v[184:187], v246, s[30:31] offset:32
	global_load_dwordx4 v[188:191], v246, s[30:31] offset:48
	s_waitcnt vmcnt(0)
; __device__ __forceinline__ void peer_tile(const Args& A, LAS unsigned char* lds, int tile) {
;     ...
;         for (int tk = 0; tk < 4; ++tk) {
;             const size_t m = (size_t)tile * 64 + tb + tk; const int b = (int)(m >> 11);
;             float* orow = A.out + m * 1024 + 16 * lane;
;             const float* g2 = MOD + b * 6144 + 5120 + 16 * lane;
;             f32x4 xv[4]; float ss = 0.f;
; #pragma unroll
;             for (int j = 0; j < 4; ++j) { const f32x4 x1 = *(const f32x4*)(orow + 4 * j), gg = *(const f32x4*)(g2 + 4 * j);
;                 const f32x4 pe = (f32x4){oacc[tk][2 * j][0], oacc[tk][2 * j][1], oacc[tk][2 * j + 1][0], oacc[tk][2 * j + 1][1]};
;                 xv[j] = x1 + gg * pe; ss += (xv[j][0] * xv[j][0] + xv[j][1] * xv[j][1]) + (xv[j][2] * xv[j][2] + xv[j][3] * xv[j][3]); }
;             const float rstd = rsqrtf(wave_sum(ss) * (1.f / 1024.f) + 1e-6f);
	v_pk_fma_f32 v[128:129], v[0:1], v[192:193], v[128:129]
	v_pk_fma_f32 v[130:131], v[2:3], v[194:195], v[130:131]
	v_pk_fma_f32 v[132:133], v[4:5], v[196:197], v[132:133]
	v_pk_fma_f32 v[134:135], v[6:7], v[198:199], v[134:135]
	v_pk_fma_f32 v[136:137], v[8:9], v[200:201], v[136:137]
	v_pk_fma_f32 v[138:139], v[10:11], v[202:203], v[138:139]
	v_pk_fma_f32 v[140:141], v[12:13], v[204:205], v[140:141]
	v_pk_fma_f32 v[142:143], v[14:15], v[206:207], v[142:143]
	v_pk_mul_f32 v[248:249], v[128:129], v[128:129]
	v_pk_fma_f32 v[248:249], v[130:131], v[130:131], v[248:249]
	v_pk_fma_f32 v[248:249], v[132:133], v[132:133], v[248:249]
	v_pk_fma_f32 v[248:249], v[134:135], v[134:135], v[248:249]
	v_pk_fma_f32 v[248:249], v[136:137], v[136:137], v[248:249]
	v_pk_fma_f32 v[248:249], v[138:139], v[138:139], v[248:249]
	v_pk_fma_f32 v[248:249], v[140:141], v[140:141], v[248:249]
	v_pk_fma_f32 v[248:249], v[142:143], v[142:143], v[248:249]
	v_pk_fma_f32 v[144:145], v[16:17], v[192:193], v[144:145]
	v_pk_fma_f32 v[146:147], v[18:19], v[194:195], v[146:147]
	v_pk_fma_f32 v[148:149], v[20:21], v[196:197], v[148:149]
	v_pk_fma_f32 v[150:151], v[22:23], v[198:199], v[150:151]
	v_pk_fma_f32 v[152:153], v[24:25], v[200:201], v[152:153]
	v_pk_fma_f32 v[154:155], v[26:27], v[202:203], v[154:155]
	v_pk_fma_f32 v[156:157], v[28:29], v[204:205], v[156:157]
	v_pk_fma_f32 v[158:159], v[30:31], v[206:207], v[158:159]
	v_pk_mul_f32 v[250:251], v[144:145], v[144:145]
	v_pk_fma_f32 v[250:251], v[146:147], v[146:147], v[250:251]
	v_pk_fma_f32 v[250:251], v[148:149], v[148:149], v[250:251]
	v_pk_fma_f32 v[250:251], v[150:151], v[150:151], v[250:251]
	v_pk_fma_f32 v[250:251], v[152:153], v[152:153], v[250:251]
	v_pk_fma_f32 v[250:251], v[154:155], v[154:155], v[250:251]
	v_pk_fma_f32 v[250:251], v[156:157], v[156:157], v[250:251]
	v_pk_fma_f32 v[250:251], v[158:159], v[158:159], v[250:251]
	v_pk_fma_f32 v[160:161], v[32:33], v[192:193], v[160:161]
	v_pk_fma_f32 v[162:163], v[34:35], v[194:195], v[162:163]
	v_pk_fma_f32 v[164:165], v[36:37], v[196:197], v[164:165]
	v_pk_fma_f32 v[166:167], v[38:39], v[198:199], v[166:167]
	v_pk_fma_f32 v[168:169], v[40:41], v[200:201], v[168:169]
	v_pk_fma_f32 v[170:171], v[42:43], v[202:203], v[170:171]
	v_pk_fma_f32 v[172:173], v[44:45], v[204:205], v[172:173]
	v_pk_fma_f32 v[174:175], v[46:47], v[206:207], v[174:175]
	v_pk_mul_f32 v[252:253], v[160:161], v[160:161]
	v_pk_fma_f32 v[252:253], v[162:163], v[162:163], v[252:253]
	v_pk_fma_f32 v[252:253], v[164:165], v[164:165], v[252:253]
	v_pk_fma_f32 v[252:253], v[166:167], v[166:167], v[252:253]
	v_pk_fma_f32 v[252:253], v[168:169], v[168:169], v[252:253]
	v_pk_fma_f32 v[252:253], v[170:171], v[170:171], v[252:253]
	v_pk_fma_f32 v[252:253], v[172:173], v[172:173], v[252:253]
	v_pk_fma_f32 v[252:253], v[174:175], v[174:175], v[252:253]
	v_pk_fma_f32 v[176:177], v[48:49], v[192:193], v[176:177]
	v_pk_fma_f32 v[178:179], v[50:51], v[194:195], v[178:179]
	v_pk_fma_f32 v[180:181], v[52:53], v[196:197], v[180:181]
	v_pk_fma_f32 v[182:183], v[54:55], v[198:199], v[182:183]
	v_pk_fma_f32 v[184:185], v[56:57], v[200:201], v[184:185]
	v_pk_fma_f32 v[186:187], v[58:59], v[202:203], v[186:187]
	v_pk_fma_f32 v[188:189], v[60:61], v[204:205], v[188:189]
	v_pk_fma_f32 v[190:191], v[62:63], v[206:207], v[190:191]
	v_pk_mul_f32 v[254:255], v[176:177], v[176:177]
	v_pk_fma_f32 v[254:255], v[178:179], v[178:179], v[254:255]
	v_pk_fma_f32 v[254:255], v[180:181], v[180:181], v[254:255]
	v_pk_fma_f32 v[254:255], v[182:183], v[182:183], v[254:255]
	v_pk_fma_f32 v[254:255], v[184:185], v[184:185], v[254:255]
	v_pk_fma_f32 v[254:255], v[186:187], v[186:187], v[254:255]
	v_pk_fma_f32 v[254:255], v[188:189], v[188:189], v[254:255]
	v_pk_fma_f32 v[254:255], v[190:191], v[190:191], v[254:255]
	v_add_f32_e32 v248, v248, v249
	v_add_f32_e32 v250, v250, v251
	v_add_f32_e32 v252, v252, v253
	v_add_f32_e32 v254, v254, v255
	v_mov_b32_e32 v249, v248
	v_mov_b32_e32 v251, v250
	v_mov_b32_e32 v253, v252
	v_mov_b32_e32 v255, v254
	v_permlane32_swap_b32_e32 v248, v249
	v_permlane32_swap_b32_e32 v250, v251
	v_permlane32_swap_b32_e32 v252, v253
	v_permlane32_swap_b32_e32 v254, v255
	v_add_f32_e32 v248, v248, v249
	v_add_f32_e32 v250, v250, v251
	v_add_f32_e32 v252, v252, v253
	v_add_f32_e32 v254, v254, v255
	v_mov_b32_e32 v249, v248
	v_mov_b32_e32 v251, v250
	v_mov_b32_e32 v253, v252
	v_mov_b32_e32 v255, v254
	v_permlane16_swap_b32_e32 v248, v249
	v_permlane16_swap_b32_e32 v250, v251
	v_permlane16_swap_b32_e32 v252, v253
	v_permlane16_swap_b32_e32 v254, v255
	v_add_f32_e32 v248, v248, v249
	v_add_f32_e32 v250, v250, v251
	v_add_f32_e32 v252, v252, v253
	v_add_f32_e32 v254, v254, v255
	v_add_f32_dpp v248, v248, v248 quad_perm:[1,0,3,2] row_mask:0xf bank_mask:0xf bound_ctrl:1
	v_add_f32_dpp v250, v250, v250 quad_perm:[1,0,3,2] row_mask:0xf bank_mask:0xf bound_ctrl:1
	v_add_f32_dpp v252, v252, v252 quad_perm:[1,0,3,2] row_mask:0xf bank_mask:0xf bound_ctrl:1
	v_add_f32_dpp v254, v254, v254 quad_perm:[1,0,3,2] row_mask:0xf bank_mask:0xf bound_ctrl:1
	v_add_f32_dpp v248, v248, v248 quad_perm:[2,3,0,1] row_mask:0xf bank_mask:0xf bound_ctrl:1
	v_add_f32_dpp v250, v250, v250 quad_perm:[2,3,0,1] row_mask:0xf bank_mask:0xf bound_ctrl:1
	v_add_f32_dpp v252, v252, v252 quad_perm:[2,3,0,1] row_mask:0xf bank_mask:0xf bound_ctrl:1
	v_add_f32_dpp v254, v254, v254 quad_perm:[2,3,0,1] row_mask:0xf bank_mask:0xf bound_ctrl:1
	v_add_f32_dpp v248, v248, v248 row_half_mirror row_mask:0xf bank_mask:0xf bound_ctrl:1
	v_add_f32_dpp v250, v250, v250 row_half_mirror row_mask:0xf bank_mask:0xf bound_ctrl:1
	v_add_f32_dpp v252, v252, v252 row_half_mirror row_mask:0xf bank_mask:0xf bound_ctrl:1
; __device__ __forceinline__ void peer_tile(const Args& A, LAS unsigned char* lds, int tile) {
;     ...
;             const float rstd = rsqrtf(wave_sum(ss) * (1.f / 1024.f) + 1e-6f);
; #pragma unroll
;             for (int j = 0; j < 4; ++j) { const f32x4 fg = *(const f32x4*)(A.final_g + 16 * lane + 4 * j); *(f32x4*)(orow + 4 * j) = xv[j] * rstd * fg; }
	v_add_f32_dpp v254, v254, v254 row_half_mirror row_mask:0xf bank_mask:0xf bound_ctrl:1
	v_add_f32_dpp v248, v248, v248 row_mirror row_mask:0xf bank_mask:0xf bound_ctrl:1
	v_add_f32_dpp v250, v250, v250 row_mirror row_mask:0xf bank_mask:0xf bound_ctrl:1
	v_add_f32_dpp v252, v252, v252 row_mirror row_mask:0xf bank_mask:0xf bound_ctrl:1
	v_add_f32_dpp v254, v254, v254 row_mirror row_mask:0xf bank_mask:0xf bound_ctrl:1
	v_fmamk_f32 v248, v248, 0x3a800000, v243
	v_fmamk_f32 v250, v250, 0x3a800000, v243
	v_fmamk_f32 v252, v252, 0x3a800000, v243
	v_fmamk_f32 v254, v254, 0x3a800000, v243
	v_rsq_f32_e32 v248, v248
	v_rsq_f32_e32 v250, v250
	v_rsq_f32_e32 v252, v252
	v_rsq_f32_e32 v254, v254
	s_nop 0
	v_pk_mul_f32 v[128:129], v[128:129], v[248:249] op_sel_hi:[1,0]
	v_pk_mul_f32 v[130:131], v[130:131], v[248:249] op_sel_hi:[1,0]
	v_pk_mul_f32 v[132:133], v[132:133], v[248:249] op_sel_hi:[1,0]
	v_pk_mul_f32 v[134:135], v[134:135], v[248:249] op_sel_hi:[1,0]
	v_pk_mul_f32 v[136:137], v[136:137], v[248:249] op_sel_hi:[1,0]
	v_pk_mul_f32 v[138:139], v[138:139], v[248:249] op_sel_hi:[1,0]
	v_pk_mul_f32 v[140:141], v[140:141], v[248:249] op_sel_hi:[1,0]
	v_pk_mul_f32 v[142:143], v[142:143], v[248:249] op_sel_hi:[1,0]
	v_pk_mul_f32 v[128:129], v[216:217], v[128:129]
	v_pk_mul_f32 v[130:131], v[218:219], v[130:131]
	v_pk_mul_f32 v[132:133], v[220:221], v[132:133]
	v_pk_mul_f32 v[134:135], v[222:223], v[134:135]
	v_pk_mul_f32 v[136:137], v[224:225], v[136:137]
	v_pk_mul_f32 v[138:139], v[226:227], v[138:139]
	v_pk_mul_f32 v[140:141], v[228:229], v[140:141]
	v_pk_mul_f32 v[142:143], v[230:231], v[142:143]
	global_store_dwordx4 v246, v[128:131], s[24:25]
	global_store_dwordx4 v246, v[132:135], s[24:25] offset:16
	global_store_dwordx4 v246, v[136:139], s[24:25] offset:32
	global_store_dwordx4 v246, v[140:143], s[24:25] offset:48
	v_pk_mul_f32 v[144:145], v[144:145], v[250:251] op_sel_hi:[1,0]
	v_pk_mul_f32 v[146:147], v[146:147], v[250:251] op_sel_hi:[1,0]
	v_pk_mul_f32 v[148:149], v[148:149], v[250:251] op_sel_hi:[1,0]
	v_pk_mul_f32 v[150:151], v[150:151], v[250:251] op_sel_hi:[1,0]
	v_pk_mul_f32 v[152:153], v[152:153], v[250:251] op_sel_hi:[1,0]
	v_pk_mul_f32 v[154:155], v[154:155], v[250:251] op_sel_hi:[1,0]
	v_pk_mul_f32 v[156:157], v[156:157], v[250:251] op_sel_hi:[1,0]
	v_pk_mul_f32 v[158:159], v[158:159], v[250:251] op_sel_hi:[1,0]
	v_pk_mul_f32 v[144:145], v[216:217], v[144:145]
	v_pk_mul_f32 v[146:147], v[218:219], v[146:147]
	v_pk_mul_f32 v[148:149], v[220:221], v[148:149]
	v_pk_mul_f32 v[150:151], v[222:223], v[150:151]
	v_pk_mul_f32 v[152:153], v[224:225], v[152:153]
	v_pk_mul_f32 v[154:155], v[226:227], v[154:155]
	v_pk_mul_f32 v[156:157], v[228:229], v[156:157]
	v_pk_mul_f32 v[158:159], v[230:231], v[158:159]
	global_store_dwordx4 v246, v[144:147], s[26:27]
	global_store_dwordx4 v246, v[148:151], s[26:27] offset:16
	global_store_dwordx4 v246, v[152:155], s[26:27] offset:32
	global_store_dwordx4 v246, v[156:159], s[26:27] offset:48
	v_pk_mul_f32 v[160:161], v[160:161], v[252:253] op_sel_hi:[1,0]
	v_pk_mul_f32 v[162:163], v[162:163], v[252:253] op_sel_hi:[1,0]
	v_pk_mul_f32 v[164:165], v[164:165], v[252:253] op_sel_hi:[1,0]
	v_pk_mul_f32 v[166:167], v[166:167], v[252:253] op_sel_hi:[1,0]
	v_pk_mul_f32 v[168:169], v[168:169], v[252:253] op_sel_hi:[1,0]
	v_pk_mul_f32 v[170:171], v[170:171], v[252:253] op_sel_hi:[1,0]
	v_pk_mul_f32 v[172:173], v[172:173], v[252:253] op_sel_hi:[1,0]
	v_pk_mul_f32 v[174:175], v[174:175], v[252:253] op_sel_hi:[1,0]
	v_pk_mul_f32 v[160:161], v[216:217], v[160:161]
	v_pk_mul_f32 v[162:163], v[218:219], v[162:163]
	v_pk_mul_f32 v[164:165], v[220:221], v[164:165]
	v_pk_mul_f32 v[166:167], v[222:223], v[166:167]
	v_pk_mul_f32 v[168:169], v[224:225], v[168:169]
	v_pk_mul_f32 v[170:171], v[226:227], v[170:171]
	v_pk_mul_f32 v[172:173], v[228:229], v[172:173]
	v_pk_mul_f32 v[174:175], v[230:231], v[174:175]
	global_store_dwordx4 v246, v[160:163], s[28:29]
	global_store_dwordx4 v246, v[164:167], s[28:29] offset:16
	global_store_dwordx4 v246, v[168:171], s[28:29] offset:32
	global_store_dwordx4 v246, v[172:175], s[28:29] offset:48
	v_pk_mul_f32 v[176:177], v[176:177], v[254:255] op_sel_hi:[1,0]
	v_pk_mul_f32 v[178:179], v[178:179], v[254:255] op_sel_hi:[1,0]
	v_pk_mul_f32 v[180:181], v[180:181], v[254:255] op_sel_hi:[1,0]
	v_pk_mul_f32 v[182:183], v[182:183], v[254:255] op_sel_hi:[1,0]
	v_pk_mul_f32 v[184:185], v[184:185], v[254:255] op_sel_hi:[1,0]
	v_pk_mul_f32 v[186:187], v[186:187], v[254:255] op_sel_hi:[1,0]
	v_pk_mul_f32 v[188:189], v[188:189], v[254:255] op_sel_hi:[1,0]
	v_pk_mul_f32 v[190:191], v[190:191], v[254:255] op_sel_hi:[1,0]
	v_pk_mul_f32 v[176:177], v[216:217], v[176:177]
	v_pk_mul_f32 v[178:179], v[218:219], v[178:179]
	v_pk_mul_f32 v[180:181], v[220:221], v[180:181]
	v_pk_mul_f32 v[182:183], v[222:223], v[182:183]
	v_pk_mul_f32 v[184:185], v[224:225], v[184:185]
	v_pk_mul_f32 v[186:187], v[226:227], v[186:187]
	v_pk_mul_f32 v[188:189], v[228:229], v[188:189]
	v_pk_mul_f32 v[190:191], v[230:231], v[190:191]
	global_store_dwordx4 v246, v[176:179], s[30:31]
	global_store_dwordx4 v246, v[180:183], s[30:31] offset:16
	global_store_dwordx4 v246, v[184:187], s[30:31] offset:32
	global_store_dwordx4 v246, v[188:191], s[30:31] offset:48
	s_nop 1
	s_add_i32 s0, s77, 4
	s_lshl_b32 s0, s0, 12
	s_add_u32 s24, s48, s0
	s_addc_u32 s25, s49, 0
	s_add_i32 s0, s77, 5
	s_lshl_b32 s0, s0, 12
	s_add_u32 s26, s48, s0
	s_addc_u32 s27, s49, 0
	s_add_i32 s0, s77, 6
	s_lshl_b32 s0, s0, 12
	s_add_u32 s28, s48, s0
	s_addc_u32 s29, s49, 0
	s_add_i32 s0, s77, 7
	s_lshl_b32 s0, s0, 12
	s_add_u32 s30, s48, s0
	s_addc_u32 s31, s49, 0
	global_load_dwordx4 v[128:131], v246, s[24:25]
	global_load_dwordx4 v[132:135], v246, s[24:25] offset:16
	global_load_dwordx4 v[136:139], v246, s[24:25] offset:32
	global_load_dwordx4 v[140:143], v246, s[24:25] offset:48
	global_load_dwordx4 v[144:147], v246, s[26:27]
	global_load_dwordx4 v[148:151], v246, s[26:27] offset:16
	global_load_dwordx4 v[152:155], v246, s[26:27] offset:32
	global_load_dwordx4 v[156:159], v246, s[26:27] offset:48
	global_load_dwordx4 v[160:163], v246, s[28:29]
	global_load_dwordx4 v[164:167], v246, s[28:29] offset:16
	global_load_dwordx4 v[168:171], v246, s[28:29] offset:32
	global_load_dwordx4 v[172:175], v246, s[28:29] offset:48
	global_load_dwordx4 v[176:179], v246, s[30:31]
	global_load_dwordx4 v[180:183], v246, s[30:31] offset:16
	global_load_dwordx4 v[184:187], v246, s[30:31] offset:32
	global_load_dwordx4 v[188:191], v246, s[30:31] offset:48
	s_waitcnt vmcnt(0)
; __device__ __forceinline__ void peer_tile(const Args& A, LAS unsigned char* lds, int tile) {
;     ...
;         for (int tk = 0; tk < 4; ++tk) {
;             const size_t m = (size_t)tile * 64 + tb + tk; const int b = (int)(m >> 11);
;             float* orow = A.out + m * 1024 + 16 * lane;
;             const float* g2 = MOD + b * 6144 + 5120 + 16 * lane;
;             f32x4 xv[4]; float ss = 0.f;
; #pragma unroll
;             for (int j = 0; j < 4; ++j) { const f32x4 x1 = *(const f32x4*)(orow + 4 * j), gg = *(const f32x4*)(g2 + 4 * j);
;                 const f32x4 pe = (f32x4){oacc[tk][2 * j][0], oacc[tk][2 * j][1], oacc[tk][2 * j + 1][0], oacc[tk][2 * j + 1][1]};
;                 xv[j] = x1 + gg * pe; ss += (xv[j][0] * xv[j][0] + xv[j][1] * xv[j][1]) + (xv[j][2] * xv[j][2] + xv[j][3] * xv[j][3]); }
;             const float rstd = rsqrtf(wave_sum(ss) * (1.f / 1024.f) + 1e-6f);
	v_pk_fma_f32 v[128:129], v[64:65], v[192:193], v[128:129]
	v_pk_fma_f32 v[130:131], v[66:67], v[194:195], v[130:131]
	v_pk_fma_f32 v[132:133], v[68:69], v[196:197], v[132:133]
	v_pk_fma_f32 v[134:135], v[70:71], v[198:199], v[134:135]
	v_pk_fma_f32 v[136:137], v[72:73], v[200:201], v[136:137]
	v_pk_fma_f32 v[138:139], v[74:75], v[202:203], v[138:139]
	v_pk_fma_f32 v[140:141], v[76:77], v[204:205], v[140:141]
	v_pk_fma_f32 v[142:143], v[78:79], v[206:207], v[142:143]
	v_pk_mul_f32 v[248:249], v[128:129], v[128:129]
	v_pk_fma_f32 v[248:249], v[130:131], v[130:131], v[248:249]
	v_pk_fma_f32 v[248:249], v[132:133], v[132:133], v[248:249]
	v_pk_fma_f32 v[248:249], v[134:135], v[134:135], v[248:249]
	v_pk_fma_f32 v[248:249], v[136:137], v[136:137], v[248:249]
	v_pk_fma_f32 v[248:249], v[138:139], v[138:139], v[248:249]
	v_pk_fma_f32 v[248:249], v[140:141], v[140:141], v[248:249]
	v_pk_fma_f32 v[248:249], v[142:143], v[142:143], v[248:249]
	v_pk_fma_f32 v[144:145], v[80:81], v[192:193], v[144:145]
	v_pk_fma_f32 v[146:147], v[82:83], v[194:195], v[146:147]
	v_pk_fma_f32 v[148:149], v[84:85], v[196:197], v[148:149]
	v_pk_fma_f32 v[150:151], v[86:87], v[198:199], v[150:151]
	v_pk_fma_f32 v[152:153], v[88:89], v[200:201], v[152:153]
	v_pk_fma_f32 v[154:155], v[90:91], v[202:203], v[154:155]
	v_pk_fma_f32 v[156:157], v[92:93], v[204:205], v[156:157]
	v_pk_fma_f32 v[158:159], v[94:95], v[206:207], v[158:159]
	v_pk_mul_f32 v[250:251], v[144:145], v[144:145]
	v_pk_fma_f32 v[250:251], v[146:147], v[146:147], v[250:251]
	v_pk_fma_f32 v[250:251], v[148:149], v[148:149], v[250:251]
	v_pk_fma_f32 v[250:251], v[150:151], v[150:151], v[250:251]
	v_pk_fma_f32 v[250:251], v[152:153], v[152:153], v[250:251]
	v_pk_fma_f32 v[250:251], v[154:155], v[154:155], v[250:251]
	v_pk_fma_f32 v[250:251], v[156:157], v[156:157], v[250:251]
	v_pk_fma_f32 v[250:251], v[158:159], v[158:159], v[250:251]
	v_pk_fma_f32 v[160:161], v[96:97], v[192:193], v[160:161]
	v_pk_fma_f32 v[162:163], v[98:99], v[194:195], v[162:163]
	v_pk_fma_f32 v[164:165], v[100:101], v[196:197], v[164:165]
	v_pk_fma_f32 v[166:167], v[102:103], v[198:199], v[166:167]
	v_pk_fma_f32 v[168:169], v[104:105], v[200:201], v[168:169]
	v_pk_fma_f32 v[170:171], v[106:107], v[202:203], v[170:171]
	v_pk_fma_f32 v[172:173], v[108:109], v[204:205], v[172:173]
	v_pk_fma_f32 v[174:175], v[110:111], v[206:207], v[174:175]
	v_pk_mul_f32 v[252:253], v[160:161], v[160:161]
	v_pk_fma_f32 v[252:253], v[162:163], v[162:163], v[252:253]
	v_pk_fma_f32 v[252:253], v[164:165], v[164:165], v[252:253]
	v_pk_fma_f32 v[252:253], v[166:167], v[166:167], v[252:253]
	v_pk_fma_f32 v[252:253], v[168:169], v[168:169], v[252:253]
	v_pk_fma_f32 v[252:253], v[170:171], v[170:171], v[252:253]
	v_pk_fma_f32 v[252:253], v[172:173], v[172:173], v[252:253]
	v_pk_fma_f32 v[252:253], v[174:175], v[174:175], v[252:253]
	v_pk_fma_f32 v[176:177], v[112:113], v[192:193], v[176:177]
	v_pk_fma_f32 v[178:179], v[114:115], v[194:195], v[178:179]
	v_pk_fma_f32 v[180:181], v[116:117], v[196:197], v[180:181]
	v_pk_fma_f32 v[182:183], v[118:119], v[198:199], v[182:183]
	v_pk_fma_f32 v[184:185], v[120:121], v[200:201], v[184:185]
	v_pk_fma_f32 v[186:187], v[122:123], v[202:203], v[186:187]
	v_pk_fma_f32 v[188:189], v[124:125], v[204:205], v[188:189]
	v_pk_fma_f32 v[190:191], v[126:127], v[206:207], v[190:191]
	v_pk_mul_f32 v[254:255], v[176:177], v[176:177]
	v_pk_fma_f32 v[254:255], v[178:179], v[178:179], v[254:255]
	v_pk_fma_f32 v[254:255], v[180:181], v[180:181], v[254:255]
	v_pk_fma_f32 v[254:255], v[182:183], v[182:183], v[254:255]
	v_pk_fma_f32 v[254:255], v[184:185], v[184:185], v[254:255]
	v_pk_fma_f32 v[254:255], v[186:187], v[186:187], v[254:255]
	v_pk_fma_f32 v[254:255], v[188:189], v[188:189], v[254:255]
	v_pk_fma_f32 v[254:255], v[190:191], v[190:191], v[254:255]
	v_add_f32_e32 v248, v248, v249
	v_add_f32_e32 v250, v250, v251
	v_add_f32_e32 v252, v252, v253
	v_add_f32_e32 v254, v254, v255
	v_mov_b32_e32 v249, v248
	v_mov_b32_e32 v251, v250
	v_mov_b32_e32 v253, v252
	v_mov_b32_e32 v255, v254
	v_permlane32_swap_b32_e32 v248, v249
	v_permlane32_swap_b32_e32 v250, v251
	v_permlane32_swap_b32_e32 v252, v253
	v_permlane32_swap_b32_e32 v254, v255
	v_add_f32_e32 v248, v248, v249
	v_add_f32_e32 v250, v250, v251
	v_add_f32_e32 v252, v252, v253
	v_add_f32_e32 v254, v254, v255
	v_mov_b32_e32 v249, v248
	v_mov_b32_e32 v251, v250
	v_mov_b32_e32 v253, v252
	v_mov_b32_e32 v255, v254
	v_permlane16_swap_b32_e32 v248, v249
	v_permlane16_swap_b32_e32 v250, v251
	v_permlane16_swap_b32_e32 v252, v253
	v_permlane16_swap_b32_e32 v254, v255
	v_add_f32_e32 v248, v248, v249
	v_add_f32_e32 v250, v250, v251
	v_add_f32_e32 v252, v252, v253
	v_add_f32_e32 v254, v254, v255
	v_add_f32_dpp v248, v248, v248 quad_perm:[1,0,3,2] row_mask:0xf bank_mask:0xf bound_ctrl:1
	v_add_f32_dpp v250, v250, v250 quad_perm:[1,0,3,2] row_mask:0xf bank_mask:0xf bound_ctrl:1
	v_add_f32_dpp v252, v252, v252 quad_perm:[1,0,3,2] row_mask:0xf bank_mask:0xf bound_ctrl:1
	v_add_f32_dpp v254, v254, v254 quad_perm:[1,0,3,2] row_mask:0xf bank_mask:0xf bound_ctrl:1
	v_add_f32_dpp v248, v248, v248 quad_perm:[2,3,0,1] row_mask:0xf bank_mask:0xf bound_ctrl:1
	v_add_f32_dpp v250, v250, v250 quad_perm:[2,3,0,1] row_mask:0xf bank_mask:0xf bound_ctrl:1
	v_add_f32_dpp v252, v252, v252 quad_perm:[2,3,0,1] row_mask:0xf bank_mask:0xf bound_ctrl:1
	v_add_f32_dpp v254, v254, v254 quad_perm:[2,3,0,1] row_mask:0xf bank_mask:0xf bound_ctrl:1
	v_add_f32_dpp v248, v248, v248 row_half_mirror row_mask:0xf bank_mask:0xf bound_ctrl:1
	v_add_f32_dpp v250, v250, v250 row_half_mirror row_mask:0xf bank_mask:0xf bound_ctrl:1
; __device__ __forceinline__ void peer_tile(const Args& A, LAS unsigned char* lds, int tile) {
;     ...
;             const float rstd = rsqrtf(wave_sum(ss) * (1.f / 1024.f) + 1e-6f);
; #pragma unroll
;             for (int j = 0; j < 4; ++j) { const f32x4 fg = *(const f32x4*)(A.final_g + 16 * lane + 4 * j); *(f32x4*)(orow + 4 * j) = xv[j] * rstd * fg; }
	v_add_f32_dpp v252, v252, v252 row_half_mirror row_mask:0xf bank_mask:0xf bound_ctrl:1
	v_add_f32_dpp v254, v254, v254 row_half_mirror row_mask:0xf bank_mask:0xf bound_ctrl:1
	v_add_f32_dpp v248, v248, v248 row_mirror row_mask:0xf bank_mask:0xf bound_ctrl:1
	v_add_f32_dpp v250, v250, v250 row_mirror row_mask:0xf bank_mask:0xf bound_ctrl:1
	v_add_f32_dpp v252, v252, v252 row_mirror row_mask:0xf bank_mask:0xf bound_ctrl:1
	v_add_f32_dpp v254, v254, v254 row_mirror row_mask:0xf bank_mask:0xf bound_ctrl:1
	v_fmamk_f32 v248, v248, 0x3a800000, v243
	v_fmamk_f32 v250, v250, 0x3a800000, v243
	v_fmamk_f32 v252, v252, 0x3a800000, v243
	v_fmamk_f32 v254, v254, 0x3a800000, v243
	v_rsq_f32_e32 v248, v248
	v_rsq_f32_e32 v250, v250
	v_rsq_f32_e32 v252, v252
	v_rsq_f32_e32 v254, v254
	s_nop 0
	v_pk_mul_f32 v[128:129], v[128:129], v[248:249] op_sel_hi:[1,0]
	v_pk_mul_f32 v[130:131], v[130:131], v[248:249] op_sel_hi:[1,0]
	v_pk_mul_f32 v[132:133], v[132:133], v[248:249] op_sel_hi:[1,0]
	v_pk_mul_f32 v[134:135], v[134:135], v[248:249] op_sel_hi:[1,0]
	v_pk_mul_f32 v[136:137], v[136:137], v[248:249] op_sel_hi:[1,0]
	v_pk_mul_f32 v[138:139], v[138:139], v[248:249] op_sel_hi:[1,0]
	v_pk_mul_f32 v[140:141], v[140:141], v[248:249] op_sel_hi:[1,0]
	v_pk_mul_f32 v[142:143], v[142:143], v[248:249] op_sel_hi:[1,0]
	v_pk_mul_f32 v[128:129], v[216:217], v[128:129]
	v_pk_mul_f32 v[130:131], v[218:219], v[130:131]
	v_pk_mul_f32 v[132:133], v[220:221], v[132:133]
	v_pk_mul_f32 v[134:135], v[222:223], v[134:135]
	v_pk_mul_f32 v[136:137], v[224:225], v[136:137]
	v_pk_mul_f32 v[138:139], v[226:227], v[138:139]
	v_pk_mul_f32 v[140:141], v[228:229], v[140:141]
	v_pk_mul_f32 v[142:143], v[230:231], v[142:143]
	global_store_dwordx4 v246, v[128:131], s[24:25]
	global_store_dwordx4 v246, v[132:135], s[24:25] offset:16
	global_store_dwordx4 v246, v[136:139], s[24:25] offset:32
	global_store_dwordx4 v246, v[140:143], s[24:25] offset:48
	v_pk_mul_f32 v[144:145], v[144:145], v[250:251] op_sel_hi:[1,0]
	v_pk_mul_f32 v[146:147], v[146:147], v[250:251] op_sel_hi:[1,0]
	v_pk_mul_f32 v[148:149], v[148:149], v[250:251] op_sel_hi:[1,0]
	v_pk_mul_f32 v[150:151], v[150:151], v[250:251] op_sel_hi:[1,0]
	v_pk_mul_f32 v[152:153], v[152:153], v[250:251] op_sel_hi:[1,0]
	v_pk_mul_f32 v[154:155], v[154:155], v[250:251] op_sel_hi:[1,0]
	v_pk_mul_f32 v[156:157], v[156:157], v[250:251] op_sel_hi:[1,0]
	v_pk_mul_f32 v[158:159], v[158:159], v[250:251] op_sel_hi:[1,0]
	v_pk_mul_f32 v[144:145], v[216:217], v[144:145]
	v_pk_mul_f32 v[146:147], v[218:219], v[146:147]
	v_pk_mul_f32 v[148:149], v[220:221], v[148:149]
	v_pk_mul_f32 v[150:151], v[222:223], v[150:151]
	v_pk_mul_f32 v[152:153], v[224:225], v[152:153]
	v_pk_mul_f32 v[154:155], v[226:227], v[154:155]
	v_pk_mul_f32 v[156:157], v[228:229], v[156:157]
	v_pk_mul_f32 v[158:159], v[230:231], v[158:159]
	global_store_dwordx4 v246, v[144:147], s[26:27]
	global_store_dwordx4 v246, v[148:151], s[26:27] offset:16
	global_store_dwordx4 v246, v[152:155], s[26:27] offset:32
	global_store_dwordx4 v246, v[156:159], s[26:27] offset:48
	v_pk_mul_f32 v[160:161], v[160:161], v[252:253] op_sel_hi:[1,0]
	v_pk_mul_f32 v[162:163], v[162:163], v[252:253] op_sel_hi:[1,0]
	v_pk_mul_f32 v[164:165], v[164:165], v[252:253] op_sel_hi:[1,0]
	v_pk_mul_f32 v[166:167], v[166:167], v[252:253] op_sel_hi:[1,0]
	v_pk_mul_f32 v[168:169], v[168:169], v[252:253] op_sel_hi:[1,0]
	v_pk_mul_f32 v[170:171], v[170:171], v[252:253] op_sel_hi:[1,0]
	v_pk_mul_f32 v[172:173], v[172:173], v[252:253] op_sel_hi:[1,0]
	v_pk_mul_f32 v[174:175], v[174:175], v[252:253] op_sel_hi:[1,0]
	v_pk_mul_f32 v[160:161], v[216:217], v[160:161]
	v_pk_mul_f32 v[162:163], v[218:219], v[162:163]
	v_pk_mul_f32 v[164:165], v[220:221], v[164:165]
	v_pk_mul_f32 v[166:167], v[222:223], v[166:167]
	v_pk_mul_f32 v[168:169], v[224:225], v[168:169]
	v_pk_mul_f32 v[170:171], v[226:227], v[170:171]
	v_pk_mul_f32 v[172:173], v[228:229], v[172:173]
	v_pk_mul_f32 v[174:175], v[230:231], v[174:175]
	global_store_dwordx4 v246, v[160:163], s[28:29]
	global_store_dwordx4 v246, v[164:167], s[28:29] offset:16
	global_store_dwordx4 v246, v[168:171], s[28:29] offset:32
	global_store_dwordx4 v246, v[172:175], s[28:29] offset:48
	v_pk_mul_f32 v[176:177], v[176:177], v[254:255] op_sel_hi:[1,0]
	v_pk_mul_f32 v[178:179], v[178:179], v[254:255] op_sel_hi:[1,0]
	v_pk_mul_f32 v[180:181], v[180:181], v[254:255] op_sel_hi:[1,0]
	v_pk_mul_f32 v[182:183], v[182:183], v[254:255] op_sel_hi:[1,0]
	v_pk_mul_f32 v[184:185], v[184:185], v[254:255] op_sel_hi:[1,0]
	v_pk_mul_f32 v[186:187], v[186:187], v[254:255] op_sel_hi:[1,0]
	v_pk_mul_f32 v[188:189], v[188:189], v[254:255] op_sel_hi:[1,0]
	v_pk_mul_f32 v[190:191], v[190:191], v[254:255] op_sel_hi:[1,0]
	v_pk_mul_f32 v[176:177], v[216:217], v[176:177]
	v_pk_mul_f32 v[178:179], v[218:219], v[178:179]
	v_pk_mul_f32 v[180:181], v[220:221], v[180:181]
	v_pk_mul_f32 v[182:183], v[222:223], v[182:183]
	v_pk_mul_f32 v[184:185], v[224:225], v[184:185]
	v_pk_mul_f32 v[186:187], v[226:227], v[186:187]
	v_pk_mul_f32 v[188:189], v[228:229], v[188:189]
	v_pk_mul_f32 v[190:191], v[230:231], v[190:191]
	global_store_dwordx4 v246, v[176:179], s[30:31]
	global_store_dwordx4 v246, v[180:183], s[30:31] offset:16
	global_store_dwordx4 v246, v[184:187], s[30:31] offset:32
	global_store_dwordx4 v246, v[188:191], s[30:31] offset:48
	s_nop 1
	v_mov_b32_e32 v113, 0
	v_mbcnt_lo_u32_b32 v215, -1, 0
	v_mbcnt_hi_u32_b32 v215, -1, v215
	v_and_b32_e32 v216, 64, v215
	v_add_u32_e32 v216, 64, v216
	v_xor_b32_e32 v217, 16, v215
	v_xor_b32_e32 v218, 32, v215
	s_branch .LBB0_698

